# all global stores write-through (sc1) and the grid barrier's L2 write-back dropped (stores are already at device scope)
# baseline (speedup 1.0000x reference)
.LBB0_21:
	s_add_i32 s5, s42, s30
	s_cmp_lt_i32 s5, 0x8000
	s_cselect_b32 s6, s5, s42
	s_ashr_i32 s7, s6, 31
	s_lshl_b64 s[6:7], s[6:7], 11
	s_waitcnt vmcnt(0)
	v_lshlrev_b32_e32 v26, 16, v22
	v_and_b32_e32 v53, 0xffff0000, v22
	v_lshlrev_b32_e32 v30, 16, v23
	v_and_b32_e32 v31, 0xffff0000, v23
	v_lshl_add_u64 v[22:23], v[18:19], 0, s[6:7]
	v_lshlrev_b32_e32 v28, 16, v24
	v_and_b32_e32 v29, 0xffff0000, v24
	v_lshlrev_b32_e32 v41, 16, v35
	v_lshlrev_b32_e32 v40, 16, v34
	v_and_b32_e32 v37, 0xffff0000, v35
	v_and_b32_e32 v36, 0xffff0000, v34
	v_lshlrev_b32_e32 v43, 16, v33
	v_lshlrev_b32_e32 v42, 16, v32
	v_and_b32_e32 v39, 0xffff0000, v33
	v_and_b32_e32 v38, 0xffff0000, v32
	global_load_dwordx2 v[34:35], v[22:23], off
	global_load_dwordx2 v[32:33], v[22:23], off offset:512
	global_load_dwordx2 v[24:25], v[22:23], off offset:1024
	s_nop 0
	global_load_dwordx2 v[22:23], v[22:23], off offset:1536
	v_lshlrev_b32_e32 v44, 16, v1
	v_pk_mul_f32 v[46:47], v[36:37], v[36:37]
	v_pk_mul_f32 v[48:49], v[38:39], v[38:39]
	v_and_b32_e32 v45, 0xffff0000, v1
	v_mul_f32_e32 v27, v28, v28
	v_mul_f32_e32 v51, v29, v29
	v_mul_f32_e32 v52, v44, v44
	v_mov_b32_e32 v50, v26
	v_mov_b32_e32 v56, v40
	v_mov_b32_e32 v57, v36
	v_mov_b32_e32 v36, v41
	v_mov_b32_e32 v58, v42
	v_mov_b32_e32 v59, v38
	v_mov_b32_e32 v38, v43
	v_pk_fma_f32 v[40:41], v[40:41], v[40:41], v[46:47]
	v_pk_fma_f32 v[42:43], v[42:43], v[42:43], v[48:49]
	v_pk_fma_f32 v[46:47], v[44:45], v[44:45], v[52:53] op_sel_hi:[1,1,0]
	v_pk_add_f32 v[48:49], v[26:27], v[50:51]
	v_pk_add_f32 v[40:41], v[40:41], v[40:41] op_sel_hi:[0,1]
	v_pk_add_f32 v[42:43], v[42:43], v[42:43] op_sel_hi:[0,1]
	v_mul_f32_e32 v54, v26, v26
	v_mul_f32_e32 v46, v53, v53
	v_mov_b32_e32 v55, v49
	v_mul_f32_e32 v40, v30, v30
	v_mul_f32_e32 v42, v31, v31
	v_pk_add_f32 v[46:47], v[54:55], v[46:47]
	v_pk_add_f32 v[40:41], v[40:41], v[42:43]
	v_mov_b32_e32 v1, 0
	v_pk_add_f32 v[40:41], v[46:47], v[40:41]
	v_mov_b32_e32 v60, 0
	v_add_f32_e32 v40, v40, v41
	s_mov_b32 s42, s5
	s_cmpk_gt_i32 s5, 0x7fff
	v_add_f32_dpp v40, v40, v40 quad_perm:[1,0,3,2] row_mask:0xf bank_mask:0xf bound_ctrl:1
	v_mov_b32_e32 v27, v53
	s_nop 0
	v_add_f32_dpp v40, v40, v40 quad_perm:[2,3,0,1] row_mask:0xf bank_mask:0xf bound_ctrl:1
	s_nop 1
	v_add_f32_dpp v40, v40, v40 row_half_mirror row_mask:0xf bank_mask:0xf bound_ctrl:1
	s_nop 1
	v_add_f32_dpp v40, v40, v40 row_mirror row_mask:0xf bank_mask:0xf bound_ctrl:1
	s_nop 1
	v_mov_b32_dpp v1, v40 row_bcast:15 row_mask:0xa bank_mask:0xf
	v_add_f32_e32 v1, v40, v1
	s_nop 1
	v_mov_b32_dpp v60, v1 row_bcast:31 row_mask:0xc bank_mask:0xf
	v_add_f32_e32 v1, v1, v60
	s_nop 0
	v_readlane_b32 s5, v1, 63
	v_mov_b32_e32 v1, 0x3a800000
	s_nop 0
	v_fma_f32 v1, s5, v1, v225
	v_rsq_f32_e32 v40, v1
	s_waitcnt vmcnt(1)
	v_mov_b32_e32 v1, v25
	v_pk_mul_f32 v[42:43], v[40:41], v[56:57] op_sel_hi:[0,1]
	v_pk_mul_f32 v[36:37], v[40:41], v[36:37] op_sel_hi:[0,1]
	v_pk_mul_f32 v[46:47], v[40:41], v[58:59] op_sel_hi:[0,1]
	v_pk_mul_f32 v[38:39], v[40:41], v[38:39] op_sel_hi:[0,1]
	v_pk_mul_f32 v[48:49], v[28:29], v[40:41] op_sel_hi:[1,0]
	v_pk_mul_f32 v[44:45], v[44:45], v[40:41] op_sel_hi:[1,0]
	v_pk_mul_f32 v[50:51], v[26:27], v[40:41] op_sel_hi:[1,0]
	v_pk_mul_f32 v[30:31], v[30:31], v[40:41] op_sel_hi:[1,0]
	v_pk_mul_f32 v[28:29], v[4:5], v[36:37]
	v_pk_mul_f32 v[26:27], v[2:3], v[42:43]
	v_pk_mul_f32 v[38:39], v[8:9], v[38:39]
	v_pk_mul_f32 v[36:37], v[6:7], v[46:47]
	v_pk_mul_f32 v[42:43], v[12:13], v[44:45]
	v_pk_mul_f32 v[40:41], v[10:11], v[48:49]
	v_pk_mul_f32 v[46:47], v[16:17], v[30:31]
	v_pk_mul_f32 v[44:45], v[14:15], v[50:51]
	global_store_dwordx4 v[20:21], v[26:29], off sc1
	global_store_dwordx4 v[20:21], v[36:39], off offset:1024 sc1
	global_store_dwordx4 v[20:21], v[40:43], off offset:2048 sc1
	global_store_dwordx4 v[20:21], v[44:47], off offset:3072 sc1
	v_lshl_add_u64 v[20:21], v[20:21], 0, s[40:41]
	s_cbranch_scc0 .LBB0_21

.LBB0_103:
	v_mov_b32_e32 v28, v242
	s_and_b32 s42, s40, 0xfffff000
	v_readfirstlane_b32 s7, v28
	s_ashr_i32 s6, s7, 6
	s_add_i32 s8, s34, s45
	s_cmpk_lt_i32 s8, 0x800
	s_cselect_b32 s8, s8, s45
	s_lshl_b32 s9, s8, 4
	s_lshl_b32 s10, s8, 6
	s_and_b32 s9, s9, 0xfffff000
	s_and_b32 s10, s10, 0xfc0
	s_or_b32 s43, s9, s10
	s_ashr_i32 s9, s8, 31
	s_lshl_b64 s[10:11], s[8:9], 14
	v_lshl_add_u64 v[6:7], v[36:37], 0, s[10:11]
	s_add_i32 s10, s43, s5
	s_mul_i32 s11, s10, 0x1800
	s_mul_hi_i32 s9, s10, 0x1800
	s_add_u32 s11, s80, s11
	s_addc_u32 s9, s81, s9
	s_lshl_b32 s8, s8, 2
	s_and_b32 s43, s8, 0x300
	s_add_u32 s8, s11, s43
	s_addc_u32 s9, s9, 0
	v_lshl_add_u64 v[26:27], s[8:9], 0, v[130:131]
	s_or_b32 s8, s10, 1
	s_mul_hi_i32 s9, s8, 0x1800
	s_mulk_i32 s8, 0x1800
	s_add_u32 s8, s80, s8
	s_addc_u32 s9, s81, s9
	v_add_co_u32_e32 v26, vcc, s90, v26
	s_add_u32 s8, s8, s43
	s_nop 0
	v_addc_co_u32_e32 v27, vcc, 0, v27, vcc
	s_addc_u32 s9, s9, 0
	s_waitcnt vmcnt(0)
	v_mov_b32_e32 v60, v44
	global_load_dwordx4 v[2:5], v[6:7], off
	s_nop 0
	global_load_dwordx4 v[6:9], v[6:7], off offset:1024
	v_mov_b32_e32 v59, v43
	global_load_dword v44, v[26:27], off offset:1024
	v_lshl_add_u64 v[26:27], s[8:9], 0, v[130:131]
	s_or_b32 s8, s10, 2
	s_mul_hi_i32 s9, s8, 0x1800
	s_mulk_i32 s8, 0x1800
	s_add_u32 s8, s80, s8
	s_addc_u32 s9, s81, s9
	v_add_co_u32_e32 v26, vcc, s90, v26
	s_add_u32 s8, s8, s43
	s_nop 0
	v_addc_co_u32_e32 v27, vcc, 0, v27, vcc
	s_addc_u32 s9, s9, 0
	global_load_dword v43, v[26:27], off offset:1024
	v_lshl_add_u64 v[26:27], s[8:9], 0, v[130:131]
	s_or_b32 s8, s10, 3
	s_mul_hi_i32 s9, s8, 0x1800
	s_mulk_i32 s8, 0x1800
	s_add_u32 s8, s80, s8
	s_addc_u32 s9, s81, s9
	v_add_co_u32_e32 v26, vcc, s90, v26
	s_add_u32 s8, s8, s43
	s_nop 0
	v_addc_co_u32_e32 v27, vcc, 0, v27, vcc
	s_addc_u32 s9, s9, 0
	v_mov_b32_e32 v58, v42
	global_load_dword v42, v[26:27], off offset:1024
	v_lshl_add_u64 v[26:27], s[8:9], 0, v[130:131]
	s_or_b32 s8, s10, 4
	s_mul_hi_i32 s9, s8, 0x1800
	s_mulk_i32 s8, 0x1800
	s_add_u32 s8, s80, s8
	s_addc_u32 s9, s81, s9
	v_add_co_u32_e32 v26, vcc, s90, v26
	s_add_u32 s8, s8, s43
	s_nop 0
	v_addc_co_u32_e32 v27, vcc, 0, v27, vcc
	s_addc_u32 s9, s9, 0
	v_mov_b32_e32 v57, v41
	global_load_dword v41, v[26:27], off offset:1024
	v_lshl_add_u64 v[26:27], s[8:9], 0, v[130:131]
	s_or_b32 s8, s10, 5
	s_mul_hi_i32 s9, s8, 0x1800
	s_mulk_i32 s8, 0x1800
	s_add_u32 s8, s80, s8
	s_addc_u32 s9, s81, s9
	v_add_co_u32_e32 v26, vcc, s90, v26
	s_add_u32 s8, s8, s43
	s_nop 0
	v_addc_co_u32_e32 v27, vcc, 0, v27, vcc
	s_addc_u32 s9, s9, 0
	v_mov_b32_e32 v56, v40
	global_load_dword v40, v[26:27], off offset:1024
	v_lshl_add_u64 v[26:27], s[8:9], 0, v[130:131]
	s_or_b32 s8, s10, 6
	s_mul_hi_i32 s9, s8, 0x1800
	s_mulk_i32 s8, 0x1800
	s_add_u32 s8, s80, s8
	s_addc_u32 s9, s81, s9
	v_add_co_u32_e32 v26, vcc, s90, v26
	s_add_u32 s8, s8, s43
	s_nop 0
	v_addc_co_u32_e32 v27, vcc, 0, v27, vcc
	s_addc_u32 s9, s9, 0
	v_mov_b32_e32 v55, v39
	global_load_dword v39, v[26:27], off offset:1024
	v_lshl_add_u64 v[26:27], s[8:9], 0, v[130:131]
	s_or_b32 s8, s10, 7
	s_mul_hi_i32 s9, s8, 0x1800
	s_mulk_i32 s8, 0x1800
	s_add_u32 s8, s80, s8
	s_addc_u32 s9, s81, s9
	v_add_co_u32_e32 v26, vcc, s90, v26
	s_add_u32 s8, s8, s43
	s_nop 0
	v_addc_co_u32_e32 v27, vcc, 0, v27, vcc
	s_addc_u32 s9, s9, 0
	v_mov_b32_e32 v54, v38
	global_load_dword v38, v[26:27], off offset:1024
	v_lshl_add_u64 v[26:27], s[8:9], 0, v[130:131]
	v_add_co_u32_e32 v26, vcc, s90, v26
	v_mov_b32_e32 v53, v1
	s_nop 0
	v_addc_co_u32_e32 v27, vcc, 0, v27, vcc
	global_load_dword v1, v[26:27], off offset:1024
	v_lshrrev_b32_e32 v27, 3, v28
	s_lshl_b32 s8, s6, 5
	v_and_b32_e32 v27, 4, v27
	v_and_b32_e32 v26, 31, v28
	v_and_or_b32 v27, s8, 32, v27
	s_and_b32 s7, s7, 0xffffff80
	s_add_i32 s7, s7, 0
	v_lshlrev_b32_e32 v26, 2, v26
	v_mul_u32_u24_e32 v27, 0x210, v27
	v_and_b32_e32 v61, 63, v28
	v_lshlrev_b32_e32 v28, 16, v22
	v_add3_u32 v26, s7, v26, v27
	v_and_b32_e32 v22, 0xffff0000, v22
	ds_write2_b32 v26, v28, v22 offset1:132
	v_lshlrev_b32_e32 v22, 16, v23
	v_and_b32_e32 v23, 0xffff0000, v23
	v_add_u32_e32 v27, 0x400, v26
	ds_write2_b32 v27, v22, v23 offset0:8 offset1:140
	v_lshlrev_b32_e32 v22, 16, v24
	v_and_b32_e32 v23, 0xffff0000, v24
	v_add_u32_e32 v24, 0x1000, v26
	ds_write2_b32 v24, v22, v23 offset0:32 offset1:164
	v_lshlrev_b32_e32 v22, 16, v25
	v_and_b32_e32 v23, 0xffff0000, v25
	v_add_u32_e32 v24, 0x1400, v26
	ds_write2_b32 v24, v22, v23 offset0:40 offset1:172
	v_lshlrev_b32_e32 v22, 16, v18
	v_and_b32_e32 v18, 0xffff0000, v18
	v_add_u32_e32 v23, 0x2000, v26
	ds_write2_b32 v23, v22, v18 offset0:64 offset1:196
	v_lshlrev_b32_e32 v18, 16, v19
	v_and_b32_e32 v19, 0xffff0000, v19
	v_add_u32_e32 v22, 0x2400, v26
	ds_write2_b32 v22, v18, v19 offset0:72 offset1:204
	v_lshlrev_b32_e32 v18, 16, v20
	v_and_b32_e32 v19, 0xffff0000, v20
	v_add_u32_e32 v20, 0x3000, v26
	s_lshl_b32 s43, s6, 3
	s_mulk_i32 s6, 0x1080
	ds_write2_b32 v20, v18, v19 offset0:96 offset1:228
	v_lshlrev_b32_e32 v18, 16, v21
	v_and_b32_e32 v19, 0xffff0000, v21
	v_add_u32_e32 v20, 0x3400, v26
	s_add_i32 s6, s6, 0
	ds_write2_b32 v20, v18, v19 offset0:104 offset1:236
	v_lshl_add_u32 v20, v61, 3, s6
	s_waitcnt lgkmcnt(0)
	s_barrier
	ds_read2_b64 v[30:33], v20 offset1:66
	ds_read2_b64 v[26:29], v20 offset0:132 offset1:198
	v_add_u32_e32 v20, 0x800, v20
	ds_read2_b64 v[22:25], v20 offset0:8 offset1:74
	s_and_b32 s8, s41, 0xfc0
	s_waitcnt lgkmcnt(2)
	v_pk_mul_f32 v[18:19], v[30:31], v[30:31]
	s_or_b32 s8, s42, s8
	v_add_f32_e32 v64, v18, v19
	v_pk_mul_f32 v[18:19], v[32:33], v[32:33]
	s_add_i32 s42, s43, s8
	v_add_f32_e32 v65, v18, v19
	s_waitcnt lgkmcnt(1)
	v_pk_mul_f32 v[18:19], v[26:27], v[26:27]
	s_ashr_i32 s43, s42, 31
	v_add_f32_e32 v66, v18, v19
	v_pk_mul_f32 v[18:19], v[28:29], v[28:29]
	s_and_b32 s11, s44, 0x180
	v_add_f32_e32 v67, v18, v19
	s_waitcnt lgkmcnt(0)
	v_pk_mul_f32 v[18:19], v[22:23], v[22:23]
	s_lshl_b64 s[8:9], s[42:43], 11
	v_add_f32_e32 v68, v18, v19
	v_pk_mul_f32 v[18:19], v[24:25], v[24:25]
	s_add_u32 s8, s76, s8
	v_add_f32_e32 v69, v18, v19
	ds_read2_b64 v[18:21], v20 offset0:140 offset1:206
	s_addc_u32 s9, s77, s9
	s_waitcnt lgkmcnt(0)
	v_pk_mul_f32 v[62:63], v[18:19], v[18:19]
	v_add_f32_e32 v70, v62, v63
	v_pk_mul_f32 v[62:63], v[20:21], v[20:21]
	v_add_f32_e32 v62, v62, v63
	v_add_f32_dpp v63, v64, v64 quad_perm:[1,0,3,2] row_mask:0xf bank_mask:0xf bound_ctrl:1
	v_add_f32_dpp v64, v65, v65 quad_perm:[1,0,3,2] row_mask:0xf bank_mask:0xf bound_ctrl:1
	v_add_f32_dpp v65, v66, v66 quad_perm:[1,0,3,2] row_mask:0xf bank_mask:0xf bound_ctrl:1
	v_add_f32_dpp v63, v63, v63 quad_perm:[2,3,0,1] row_mask:0xf bank_mask:0xf bound_ctrl:1
	v_add_f32_dpp v66, v67, v67 quad_perm:[1,0,3,2] row_mask:0xf bank_mask:0xf bound_ctrl:1
	v_add_f32_dpp v67, v68, v68 quad_perm:[1,0,3,2] row_mask:0xf bank_mask:0xf bound_ctrl:1
	v_add_f32_dpp v63, v63, v63 row_half_mirror row_mask:0xf bank_mask:0xf bound_ctrl:1
	v_add_f32_dpp v68, v69, v69 quad_perm:[1,0,3,2] row_mask:0xf bank_mask:0xf bound_ctrl:1
	v_add_f32_dpp v69, v70, v70 quad_perm:[1,0,3,2] row_mask:0xf bank_mask:0xf bound_ctrl:1
	v_add_f32_dpp v64, v64, v64 quad_perm:[2,3,0,1] row_mask:0xf bank_mask:0xf bound_ctrl:1
	v_add_f32_dpp v63, v63, v63 row_mirror row_mask:0xf bank_mask:0xf bound_ctrl:1
	s_nop 0
	v_add_f32_dpp v64, v64, v64 row_half_mirror row_mask:0xf bank_mask:0xf bound_ctrl:1
	v_add_f32_dpp v65, v65, v65 quad_perm:[2,3,0,1] row_mask:0xf bank_mask:0xf bound_ctrl:1
	v_add_f32_dpp v63, v63, v63 row_bcast:15 row_mask:0xa bank_mask:0xf
	v_add_f32_dpp v64, v64, v64 row_mirror row_mask:0xf bank_mask:0xf bound_ctrl:1
	v_add_f32_dpp v65, v65, v65 row_half_mirror row_mask:0xf bank_mask:0xf bound_ctrl:1
	v_add_f32_dpp v66, v66, v66 quad_perm:[2,3,0,1] row_mask:0xf bank_mask:0xf bound_ctrl:1
	v_add_f32_dpp v64, v64, v64 row_bcast:15 row_mask:0xa bank_mask:0xf
	v_add_f32_dpp v65, v65, v65 row_mirror row_mask:0xf bank_mask:0xf bound_ctrl:1
	v_add_f32_dpp v66, v66, v66 row_half_mirror row_mask:0xf bank_mask:0xf bound_ctrl:1
	v_add_f32_dpp v67, v67, v67 quad_perm:[2,3,0,1] row_mask:0xf bank_mask:0xf bound_ctrl:1
	v_add_f32_dpp v65, v65, v65 row_bcast:15 row_mask:0xa bank_mask:0xf
	v_add_f32_dpp v66, v66, v66 row_mirror row_mask:0xf bank_mask:0xf bound_ctrl:1
	v_add_f32_dpp v67, v67, v67 row_half_mirror row_mask:0xf bank_mask:0xf bound_ctrl:1
	v_add_f32_dpp v68, v68, v68 quad_perm:[2,3,0,1] row_mask:0xf bank_mask:0xf bound_ctrl:1
	v_add_f32_dpp v66, v66, v66 row_bcast:15 row_mask:0xa bank_mask:0xf
	v_add_f32_dpp v67, v67, v67 row_mirror row_mask:0xf bank_mask:0xf bound_ctrl:1
	v_add_f32_dpp v68, v68, v68 row_half_mirror row_mask:0xf bank_mask:0xf bound_ctrl:1
	v_add_f32_dpp v69, v69, v69 quad_perm:[2,3,0,1] row_mask:0xf bank_mask:0xf bound_ctrl:1
	v_add_f32_dpp v67, v67, v67 row_bcast:15 row_mask:0xa bank_mask:0xf
	v_add_f32_dpp v68, v68, v68 row_mirror row_mask:0xf bank_mask:0xf bound_ctrl:1
	v_add_f32_dpp v62, v62, v62 quad_perm:[1,0,3,2] row_mask:0xf bank_mask:0xf bound_ctrl:1
	v_add_f32_dpp v69, v69, v69 row_half_mirror row_mask:0xf bank_mask:0xf bound_ctrl:1
	v_add_f32_dpp v68, v68, v68 row_bcast:15 row_mask:0xa bank_mask:0xf
	v_add_f32_dpp v62, v62, v62 quad_perm:[2,3,0,1] row_mask:0xf bank_mask:0xf bound_ctrl:1
	v_add_f32_dpp v69, v69, v69 row_mirror row_mask:0xf bank_mask:0xf bound_ctrl:1
	s_nop 0
	v_add_f32_dpp v62, v62, v62 row_half_mirror row_mask:0xf bank_mask:0xf bound_ctrl:1
	s_nop 0
	v_add_f32_dpp v69, v69, v69 row_bcast:15 row_mask:0xa bank_mask:0xf
	v_add_f32_dpp v62, v62, v62 row_mirror row_mask:0xf bank_mask:0xf bound_ctrl:1
	s_nop 1
	v_add_f32_dpp v62, v62, v62 row_bcast:15 row_mask:0xa bank_mask:0xf
	s_nop 1
	v_add_f32_dpp v63, v63, v63 row_bcast:31 row_mask:0xc bank_mask:0xf
	s_nop 0
	v_readlane_b32 s6, v63, 63
	s_nop 0
	v_add_f32_dpp v64, v64, v64 row_bcast:31 row_mask:0xc bank_mask:0xf
	s_nop 0
	v_readlane_b32 s10, v64, 63
	v_lshlrev_b32_e32 v64, 16, v52
	v_add_f32_dpp v65, v65, v65 row_bcast:31 row_mask:0xc bank_mask:0xf
	s_nop 0
	v_readlane_b32 s50, v65, 63
	v_and_b32_e32 v65, 0xffff0000, v52
	v_add_f32_dpp v66, v66, v66 row_bcast:31 row_mask:0xc bank_mask:0xf
	v_mul_f32_e32 v52, 0xbfb8aa3b, v64
	v_exp_f32_e32 v52, v52
	v_readlane_b32 s49, v66, 63
	v_add_f32_dpp v67, v67, v67 row_bcast:31 row_mask:0xc bank_mask:0xf
	v_add_f32_e32 v52, 1.0, v52
	v_rcp_f32_e32 v66, v52
	v_add_f32_dpp v68, v68, v68 row_bcast:31 row_mask:0xc bank_mask:0xf
	v_mul_f32_e32 v52, 0xbfb8aa3b, v65
	v_exp_f32_e32 v52, v52
	v_add_f32_dpp v69, v69, v69 row_bcast:31 row_mask:0xc bank_mask:0xf
	v_mov_b32_e32 v70, v131
	v_add_f32_e32 v52, 1.0, v52
	v_readlane_b32 s48, v67, 63
	v_mov_b32_dpp v70, v62 row_bcast:31 row_mask:0xc bank_mask:0xf
	v_add_f32_e32 v62, v62, v70
	v_rcp_f32_e32 v67, v52
	v_readlane_b32 s7, v62, 63
	v_fma_f32 v62, s6, v233, v225
	v_rsq_f32_e32 v62, v62
	s_lshl_b32 s6, s11, 1
	s_add_u32 s8, s8, s6
	s_addc_u32 s9, s9, 0
	v_pk_mul_f32 v[30:31], v[30:31], v[62:63] op_sel_hi:[1,0]
	v_pk_mul_f32 v[62:63], v[66:67], v[64:65]
	v_pk_mul_f32 v[30:31], v[34:35], v[30:31]
	v_readlane_b32 s47, v68, 63
	v_pk_mul_f32 v[30:31], v[62:63], v[30:31]
	v_lshlrev_b32_e32 v62, 16, v51
	v_cvt_pk_bf16_f32 v31, v30, v31
	v_lshlrev_b32_e32 v30, 2, v61
	global_store_dword v30, v31, s[8:9] offset:1024 sc1
	v_fma_f32 v31, s10, v233, v225
	v_rsq_f32_e32 v52, v31
	v_mul_f32_e32 v31, 0xbfb8aa3b, v62
	v_exp_f32_e32 v31, v31
	v_and_b32_e32 v63, 0xffff0000, v51
	s_or_b32 s8, s42, 1
	s_ashr_i32 s9, s8, 31
	v_add_f32_e32 v31, 1.0, v31
	v_rcp_f32_e32 v64, v31
	v_mul_f32_e32 v31, 0xbfb8aa3b, v63
	v_exp_f32_e32 v31, v31
	s_lshl_b64 s[8:9], s[8:9], 11
	v_pk_mul_f32 v[32:33], v[32:33], v[52:53] op_sel_hi:[1,0]
	s_add_u32 s8, s76, s8
	v_add_f32_e32 v31, 1.0, v31
	v_rcp_f32_e32 v65, v31
	v_pk_mul_f32 v[32:33], v[34:35], v[32:33]
	s_addc_u32 s9, s77, s9
	s_add_u32 s8, s8, s6
	v_pk_mul_f32 v[62:63], v[64:65], v[62:63]
	s_addc_u32 s9, s9, 0
	v_pk_mul_f32 v[32:33], v[62:63], v[32:33]
	v_lshlrev_b32_e32 v62, 16, v50
	v_cvt_pk_bf16_f32 v31, v32, v33
	global_store_dword v30, v31, s[8:9] offset:1024 sc1
	v_fma_f32 v31, s50, v233, v225
	v_rsq_f32_e32 v32, v31
	v_mul_f32_e32 v31, 0xbfb8aa3b, v62
	v_exp_f32_e32 v31, v31
	v_and_b32_e32 v63, 0xffff0000, v50
	s_or_b32 s8, s42, 2
	s_ashr_i32 s9, s8, 31
	v_add_f32_e32 v31, 1.0, v31
	v_rcp_f32_e32 v50, v31
	v_mul_f32_e32 v31, 0xbfb8aa3b, v63
	v_exp_f32_e32 v31, v31
	v_pk_mul_f32 v[26:27], v[26:27], v[32:33] op_sel_hi:[1,0]
	s_lshl_b64 s[8:9], s[8:9], 11
	v_pk_mul_f32 v[26:27], v[34:35], v[26:27]
	v_add_f32_e32 v31, 1.0, v31
	v_rcp_f32_e32 v51, v31
	s_add_u32 s8, s76, s8
	s_addc_u32 s9, s77, s9
	s_add_u32 s8, s8, s6
	v_pk_mul_f32 v[32:33], v[50:51], v[62:63]
	s_addc_u32 s9, s9, 0
	v_pk_mul_f32 v[26:27], v[32:33], v[26:27]
	v_lshlrev_b32_e32 v32, 16, v49
	v_cvt_pk_bf16_f32 v26, v26, v27
	v_mul_f32_e32 v27, 0xbfb8aa3b, v32
	v_exp_f32_e32 v27, v27
	global_store_dword v30, v26, s[8:9] offset:1024 sc1
	v_fma_f32 v26, s49, v233, v225
	v_rsq_f32_e32 v26, v26
	v_add_f32_e32 v27, 1.0, v27
	v_and_b32_e32 v33, 0xffff0000, v49
	v_rcp_f32_e32 v50, v27
	s_or_b32 s8, s42, 3
	v_pk_mul_f32 v[26:27], v[28:29], v[26:27] op_sel_hi:[1,0]
	v_mul_f32_e32 v28, 0xbfb8aa3b, v33
	v_exp_f32_e32 v28, v28
	s_ashr_i32 s9, s8, 31
	s_lshl_b64 s[8:9], s[8:9], 11
	s_add_u32 s8, s76, s8
	v_add_f32_e32 v28, 1.0, v28
	v_rcp_f32_e32 v51, v28
	v_pk_mul_f32 v[26:27], v[34:35], v[26:27]
	s_addc_u32 s9, s77, s9
	s_add_u32 s8, s8, s6
	v_pk_mul_f32 v[28:29], v[50:51], v[32:33]
	s_addc_u32 s9, s9, 0
	v_pk_mul_f32 v[26:27], v[28:29], v[26:27]
	v_lshlrev_b32_e32 v28, 16, v48
	v_cvt_pk_bf16_f32 v26, v26, v27
	v_mul_f32_e32 v27, 0xbfb8aa3b, v28
	global_store_dword v30, v26, s[8:9] offset:1024 sc1
	v_fma_f32 v26, s48, v233, v225
	v_exp_f32_e32 v27, v27
	v_rsq_f32_e32 v26, v26
	v_and_b32_e32 v29, 0xffff0000, v48
	s_or_b32 s8, s42, 4
	v_add_f32_e32 v27, 1.0, v27
	v_rcp_f32_e32 v32, v27
	v_pk_mul_f32 v[22:23], v[22:23], v[26:27] op_sel_hi:[1,0]
	v_mul_f32_e32 v26, 0xbfb8aa3b, v29
	v_exp_f32_e32 v26, v26
	s_ashr_i32 s9, s8, 31
	s_lshl_b64 s[8:9], s[8:9], 11
	v_pk_mul_f32 v[22:23], v[34:35], v[22:23]
	v_add_f32_e32 v26, 1.0, v26
	v_rcp_f32_e32 v33, v26
	s_add_u32 s8, s76, s8
	s_addc_u32 s9, s77, s9
	s_add_u32 s8, s8, s6
	v_pk_mul_f32 v[26:27], v[32:33], v[28:29]
	s_addc_u32 s9, s9, 0
	v_pk_mul_f32 v[22:23], v[26:27], v[22:23]
	v_lshlrev_b32_e32 v26, 16, v47
	v_cvt_pk_bf16_f32 v22, v22, v23
	v_mul_f32_e32 v23, 0xbfb8aa3b, v26
	v_exp_f32_e32 v23, v23
	global_store_dword v30, v22, s[8:9] offset:1024 sc1
	v_fma_f32 v22, s47, v233, v225
	v_rsq_f32_e32 v22, v22
	v_add_f32_e32 v23, 1.0, v23
	v_and_b32_e32 v27, 0xffff0000, v47
	v_rcp_f32_e32 v28, v23
	s_or_b32 s8, s42, 5
	v_pk_mul_f32 v[22:23], v[24:25], v[22:23] op_sel_hi:[1,0]
	v_mul_f32_e32 v24, 0xbfb8aa3b, v27
	v_exp_f32_e32 v24, v24
	s_ashr_i32 s9, s8, 31
	s_lshl_b64 s[8:9], s[8:9], 11
	s_add_u32 s8, s76, s8
	v_add_f32_e32 v24, 1.0, v24
	v_rcp_f32_e32 v29, v24
	v_pk_mul_f32 v[22:23], v[34:35], v[22:23]
	s_addc_u32 s9, s77, s9
	s_add_u32 s8, s8, s6
	v_pk_mul_f32 v[24:25], v[28:29], v[26:27]
	v_readlane_b32 s46, v69, 63
	v_pk_mul_f32 v[22:23], v[24:25], v[22:23]
	v_lshlrev_b32_e32 v24, 16, v46
	v_cvt_pk_bf16_f32 v22, v22, v23
	s_addc_u32 s9, s9, 0
	v_mul_f32_e32 v23, 0xbfb8aa3b, v24
	global_store_dword v30, v22, s[8:9] offset:1024 sc1
	v_fma_f32 v22, s46, v233, v225
	v_exp_f32_e32 v23, v23
	v_rsq_f32_e32 v22, v22
	v_and_b32_e32 v25, 0xffff0000, v46
	s_or_b32 s8, s42, 6
	v_add_f32_e32 v23, 1.0, v23
	v_rcp_f32_e32 v26, v23
	v_pk_mul_f32 v[18:19], v[18:19], v[22:23] op_sel_hi:[1,0]
	v_mul_f32_e32 v22, 0xbfb8aa3b, v25
	v_exp_f32_e32 v22, v22
	s_ashr_i32 s9, s8, 31
	s_lshl_b64 s[8:9], s[8:9], 11
	v_pk_mul_f32 v[18:19], v[34:35], v[18:19]
	v_add_f32_e32 v22, 1.0, v22
	v_rcp_f32_e32 v27, v22
	s_add_u32 s8, s76, s8
	s_addc_u32 s9, s77, s9
	s_add_u32 s8, s8, s6
	v_pk_mul_f32 v[22:23], v[26:27], v[24:25]
	s_addc_u32 s9, s9, 0
	v_pk_mul_f32 v[18:19], v[22:23], v[18:19]
	v_lshlrev_b32_e32 v22, 16, v45
	v_cvt_pk_bf16_f32 v18, v18, v19
	v_mul_f32_e32 v19, 0xbfb8aa3b, v22
	v_exp_f32_e32 v19, v19
	global_store_dword v30, v18, s[8:9] offset:1024 sc1
	v_fma_f32 v18, s7, v233, v225
	v_rsq_f32_e32 v18, v18
	v_add_f32_e32 v19, 1.0, v19
	v_and_b32_e32 v23, 0xffff0000, v45
	v_rcp_f32_e32 v24, v19
	s_or_b32 s8, s42, 7
	v_pk_mul_f32 v[18:19], v[20:21], v[18:19] op_sel_hi:[1,0]
	v_mul_f32_e32 v20, 0xbfb8aa3b, v23
	v_exp_f32_e32 v20, v20
	s_ashr_i32 s9, s8, 31
	s_lshl_b64 s[8:9], s[8:9], 11
	s_add_u32 s7, s76, s8
	v_add_f32_e32 v20, 1.0, v20
	v_rcp_f32_e32 v25, v20
	v_pk_mul_f32 v[18:19], v[34:35], v[18:19]
	s_addc_u32 s8, s77, s9
	s_add_u32 s6, s7, s6
	v_pk_mul_f32 v[20:21], v[24:25], v[22:23]
	s_addc_u32 s7, s8, 0
	v_pk_mul_f32 v[18:19], v[20:21], v[18:19]
	v_mov_b64_e32 v[24:25], v[16:17]
	v_cvt_pk_bf16_f32 v18, v18, v19
	global_store_dword v30, v18, s[6:7] offset:1024 sc1
	v_mov_b64_e32 v[20:21], v[12:13]
	s_add_i32 s45, s45, s4
	s_add_i32 s44, s44, s34
	s_add_i32 s41, s41, s28
	s_add_i32 s40, s40, s29
	v_mov_b64_e32 v[22:23], v[14:15]
	v_mov_b64_e32 v[18:19], v[10:11]
	s_waitcnt vmcnt(17)
	v_mov_b64_e32 v[16:17], v[4:5]
	s_waitcnt vmcnt(16)
	v_mov_b64_e32 v[12:13], v[8:9]
	s_cmpk_gt_i32 s45, 0x7ff
	v_mov_b32_e32 v52, v60
	v_mov_b32_e32 v51, v59
	v_mov_b32_e32 v50, v58
	v_mov_b32_e32 v49, v57
	v_mov_b32_e32 v48, v56
	v_mov_b32_e32 v47, v55
	v_mov_b32_e32 v46, v54
	v_mov_b32_e32 v45, v53
	v_mov_b64_e32 v[14:15], v[2:3]
	v_mov_b64_e32 v[10:11], v[6:7]
	s_barrier
	s_cbranch_scc0 .LBB0_103

.LBB0_254:
	v_mov_b32_e32 v3, v242
	s_nop 0
	v_writelane_b32 v254, s6, 27
	s_load_dwordx4 s[8:11], s[0:1], 0x18
	s_load_dwordx2 s[6:7], s[0:1], 0x30
	s_waitcnt lgkmcnt(0)
	v_add_u32_e32 v4, s66, v3
	v_ashrrev_i32_e32 v5, 31, v4
	v_and_b32_e32 v1, 63, v3
	v_readfirstlane_b32 s5, v3
	v_lshl_add_u64 v[4:5], v[4:5], 2, s[6:7]
	global_load_dword v2, v[4:5], off
	v_lshl_add_u32 v4, v3, 2, s40
	s_ashr_i32 s34, s5, 6
	s_lshl_b32 s6, s34, 4
	s_add_i32 s6, s17, s6
	s_add_i32 s7, s6, -1
	s_mul_hi_i32 s7, s7, 0x1800
	v_lshlrev_b32_e32 v7, 1, v1
	s_mov_b32 s19, s60
	s_mov_b32 s13, s66
	v_lshlrev_b32_e32 v130, 4, v1
	s_waitcnt vmcnt(0)
	ds_write_b32 v4, v2
	v_or_b32_e32 v4, s84, v1
	v_ashrrev_i32_e32 v5, 31, v4
	v_lshlrev_b64 v[4:5], 2, v[4:5]
	v_lshl_add_u64 v[18:19], s[8:9], 0, v[4:5]
	s_mul_i32 s8, s6, 0x1800
	s_add_i32 s9, s8, 0xffffe800
	s_add_u32 s28, s80, s9
	s_addc_u32 s29, s81, s7
	s_mul_hi_i32 s7, s6, 0x1800
	s_add_u32 s88, s80, s8
	s_addc_u32 s89, s81, s7
	s_add_i32 s7, s6, 1
	s_add_i32 s9, s8, 0x1800
	v_lshl_add_u64 v[4:5], s[10:11], 0, v[4:5]
	s_mul_hi_i32 s7, s7, 0x1800
	s_mov_b64 s[10:11], s[84:85]
	s_add_u32 s84, s80, s9
	s_addc_u32 s85, s81, s7
	s_add_i32 s7, s6, 2
	s_add_i32 s9, s8, 0x3000
	s_mul_hi_i32 s7, s7, 0x1800
	s_add_u32 s40, s80, s9
	global_load_dword v14, v[18:19], off
	global_load_dword v16, v[4:5], off
	global_load_dword v10, v[18:19], off offset:256
	global_load_dword v12, v[4:5], off offset:256
	global_load_dword v6, v[18:19], off offset:512
	global_load_dword v8, v[4:5], off offset:512
	global_load_dword v2, v[18:19], off offset:768
	s_nop 0
	global_load_dword v4, v[4:5], off offset:768
	s_addc_u32 s41, s81, s7
	global_load_ushort v9, v7, s[28:29] offset:512
	global_load_ushort v11, v7, s[88:89] offset:512
	global_load_ushort v13, v7, s[84:85] offset:512
	global_load_ushort v15, v7, s[40:41] offset:512
	s_add_i32 s7, s6, 3
	s_add_i32 s9, s8, 0x4800
	s_mul_hi_i32 s7, s7, 0x1800
	s_add_u32 s58, s80, s9
	s_addc_u32 s59, s81, s7
	s_add_i32 s7, s6, 4
	s_add_i32 s9, s8, 0x6000
	s_mul_hi_i32 s7, s7, 0x1800
	s_add_u32 s60, s80, s9
	s_addc_u32 s61, s81, s7
	s_add_i32 s7, s6, 5
	s_add_i32 s9, s8, 0x7800
	s_mul_hi_i32 s7, s7, 0x1800
	s_add_u32 s56, s80, s9
	s_addc_u32 s57, s81, s7
	s_add_i32 s7, s6, 6
	s_add_i32 s9, s8, 0x9000
	s_mul_hi_i32 s7, s7, 0x1800
	s_add_u32 s94, s80, s9
	s_addc_u32 s95, s81, s7
	s_add_i32 s7, s6, 7
	s_add_i32 s9, s8, 0xa800
	s_mul_hi_i32 s7, s7, 0x1800
	s_add_u32 s48, s80, s9
	s_addc_u32 s49, s81, s7
	s_add_i32 s7, s6, 8
	s_add_i32 s9, s8, 0xc000
	s_mul_hi_i32 s7, s7, 0x1800
	s_add_u32 s50, s80, s9
	s_addc_u32 s51, s81, s7
	s_add_i32 s7, s6, 9
	s_add_i32 s9, s8, 0xd800
	s_mul_hi_i32 s7, s7, 0x1800
	s_add_u32 s54, s80, s9
	s_addc_u32 s55, s81, s7
	s_add_i32 s7, s6, 10
	s_add_i32 s9, s8, 0xf000
	s_mul_hi_i32 s7, s7, 0x1800
	s_add_u32 s66, s80, s9
	s_addc_u32 s67, s81, s7
	s_add_i32 s7, s6, 11
	s_add_i32 s9, s8, 0x10800
	s_mul_hi_i32 s7, s7, 0x1800
	s_add_u32 s52, s80, s9
	v_mov_b64_e32 v[18:19], s[44:45]
	s_addc_u32 s53, s81, s7
	s_add_i32 s7, s6, 12
	s_add_i32 s9, s8, 0x12000
	s_mul_hi_i32 s7, s7, 0x1800
	s_add_u32 s64, s80, s9
	s_addc_u32 s65, s81, s7
	s_add_i32 s7, s6, 13
	s_add_i32 s9, s8, 0x13800
	s_mul_hi_i32 s7, s7, 0x1800
	s_add_u32 s68, s80, s9
	s_addc_u32 s69, s81, s7
	s_add_i32 s6, s6, 14
	s_add_i32 s8, s8, 0x15000
	s_mul_hi_i32 s6, s6, 0x1800
	s_add_u32 s72, s80, s8
	s_addc_u32 s73, s81, s6
	s_lshl_b32 s34, s34, 5
	s_add_i32 s6, s34, 0
	v_mov_b32_e32 v5, s6
	v_mad_u32_u24 v5, v1, s42, v5
	s_ashr_i32 s5, s5, 7
	s_waitcnt vmcnt(3)
	v_lshlrev_b32_e32 v22, 16, v9
	v_fma_f32 v9, |v22|, s92, 1.0
	v_rcp_f32_e32 v26, v9
	v_mul_f32_e32 v9, v22, v22
	s_waitcnt vmcnt(2)
	v_lshlrev_b32_e32 v23, 16, v11
	v_mul_f32_e32 v9, 0xbf38aa3b, v9
	v_exp_f32_e32 v24, v9
	v_fma_f32 v9, |v23|, s92, 1.0
	v_rcp_f32_e32 v27, v9
	v_mul_f32_e32 v9, v23, v23
	s_waitcnt vmcnt(1)
	v_lshlrev_b32_e32 v20, 16, v13
	v_mul_f32_e32 v9, 0xbf38aa3b, v9
	v_exp_f32_e32 v25, v9
	v_fma_f32 v9, |v20|, s92, 1.0
	v_rcp_f32_e32 v30, v9
	v_mul_f32_e32 v9, v20, v20
	s_waitcnt vmcnt(0)
	v_lshlrev_b32_e32 v21, 16, v15
	v_mul_f32_e32 v9, 0xbf38aa3b, v9
	v_exp_f32_e32 v28, v9
	v_fma_f32 v9, |v21|, s92, 1.0
	v_rcp_f32_e32 v31, v9
	v_mul_f32_e32 v9, v21, v21
	v_mul_f32_e32 v9, 0xbf38aa3b, v9
	v_exp_f32_e32 v29, v9
	global_load_ushort v9, v7, s[28:29] offset:640
	global_load_ushort v11, v7, s[88:89] offset:640
	global_load_ushort v13, v7, s[84:85] offset:640
	global_load_ushort v15, v7, s[40:41] offset:640
	v_pk_fma_f32 v[32:33], v[26:27], s[12:13], v[18:19] op_sel_hi:[1,0,0]
	v_pk_fma_f32 v[34:35], v[30:31], s[12:13], v[18:19] op_sel_hi:[1,0,0]
	v_pk_fma_f32 v[32:33], v[26:27], v[32:33], s[14:15] op_sel_hi:[1,1,0]
	v_pk_fma_f32 v[34:35], v[30:31], v[34:35], s[14:15] op_sel_hi:[1,1,0]
	v_pk_fma_f32 v[32:33], v[26:27], v[32:33], s[16:17] op_sel_hi:[1,1,0]
	v_pk_fma_f32 v[34:35], v[30:31], v[34:35], s[16:17] op_sel_hi:[1,1,0]
	v_pk_fma_f32 v[32:33], v[26:27], v[32:33], s[18:19] op_sel_hi:[1,1,0]
	v_pk_fma_f32 v[34:35], v[30:31], v[34:35], s[18:19] op_sel_hi:[1,1,0]
	v_pk_mul_f32 v[26:27], v[26:27], v[32:33]
	v_cmp_gt_f32_e32 vcc, 0, v22
	v_pk_mul_f32 v[24:25], v[24:25], v[26:27]
	v_pk_mul_f32 v[30:31], v[30:31], v[34:35]
	v_pk_mul_f32 v[26:27], v[24:25], v[22:23]
	v_pk_fma_f32 v[32:33], v[24:25], v[22:23], v[22:23] neg_lo:[1,0,0] neg_hi:[1,0,0]
	v_pk_mul_f32 v[28:29], v[28:29], v[30:31]
	v_cndmask_b32_e32 v22, v32, v26, vcc
	v_pk_mul_f32 v[30:31], v[28:29], v[20:21]
	v_pk_fma_f32 v[24:25], v[28:29], v[20:21], v[20:21] neg_lo:[1,0,0] neg_hi:[1,0,0]
	v_cmp_gt_f32_e64 s[42:43], 0, v23
	v_cmp_gt_f32_e64 s[44:45], 0, v20
	v_cmp_gt_f32_e64 s[46:47], 0, v21
	v_cndmask_b32_e64 v23, v33, v27, s[42:43]
	v_cndmask_b32_e64 v24, v24, v30, s[44:45]
	v_cndmask_b32_e64 v25, v25, v31, s[46:47]
	s_waitcnt vmcnt(3)
	v_lshlrev_b32_e32 v26, 16, v9
	v_fma_f32 v9, |v26|, s92, 1.0
	v_rcp_f32_e32 v28, v9
	v_mul_f32_e32 v9, v26, v26
	s_waitcnt vmcnt(2)
	v_lshlrev_b32_e32 v27, 16, v11
	v_mul_f32_e32 v9, 0xbf38aa3b, v9
	v_exp_f32_e32 v30, v9
	v_fma_f32 v9, |v27|, s92, 1.0
	v_rcp_f32_e32 v29, v9
	v_mul_f32_e32 v9, v27, v27
	s_waitcnt vmcnt(1)
	v_lshlrev_b32_e32 v20, 16, v13
	v_mul_f32_e32 v9, 0xbf38aa3b, v9
	v_exp_f32_e32 v31, v9
	v_fma_f32 v9, |v20|, s92, 1.0
	v_rcp_f32_e32 v32, v9
	v_mul_f32_e32 v9, v20, v20
	s_waitcnt vmcnt(0)
	v_lshlrev_b32_e32 v21, 16, v15
	v_mul_f32_e32 v9, 0xbf38aa3b, v9
	v_exp_f32_e32 v34, v9
	v_fma_f32 v9, |v21|, s92, 1.0
	v_rcp_f32_e32 v33, v9
	v_mul_f32_e32 v9, v21, v21
	v_mul_f32_e32 v9, 0xbf38aa3b, v9
	v_exp_f32_e32 v35, v9
	global_load_ushort v9, v7, s[28:29] offset:768
	global_load_ushort v11, v7, s[88:89] offset:768
	global_load_ushort v13, v7, s[84:85] offset:768
	global_load_ushort v15, v7, s[40:41] offset:768
	v_pk_fma_f32 v[36:37], v[28:29], s[12:13], v[18:19] op_sel_hi:[1,0,0]
	v_pk_fma_f32 v[38:39], v[32:33], s[12:13], v[18:19] op_sel_hi:[1,0,0]
	v_pk_fma_f32 v[36:37], v[28:29], v[36:37], s[14:15] op_sel_hi:[1,1,0]
	v_pk_fma_f32 v[38:39], v[32:33], v[38:39], s[14:15] op_sel_hi:[1,1,0]
	v_pk_fma_f32 v[36:37], v[28:29], v[36:37], s[16:17] op_sel_hi:[1,1,0]
	v_pk_fma_f32 v[38:39], v[32:33], v[38:39], s[16:17] op_sel_hi:[1,1,0]
	v_pk_fma_f32 v[36:37], v[28:29], v[36:37], s[18:19] op_sel_hi:[1,1,0]
	v_pk_fma_f32 v[38:39], v[32:33], v[38:39], s[18:19] op_sel_hi:[1,1,0]
	v_pk_mul_f32 v[28:29], v[28:29], v[36:37]
	v_pk_mul_f32 v[32:33], v[32:33], v[38:39]
	v_pk_mul_f32 v[28:29], v[30:31], v[28:29]
	v_cmp_gt_f32_e32 vcc, 0, v26
	v_pk_mul_f32 v[30:31], v[28:29], v[26:27]
	v_pk_fma_f32 v[28:29], v[28:29], v[26:27], v[26:27] neg_lo:[1,0,0] neg_hi:[1,0,0]
	v_pk_mul_f32 v[32:33], v[34:35], v[32:33]
	v_cndmask_b32_e32 v28, v28, v30, vcc
	v_pk_mul_f32 v[34:35], v[32:33], v[20:21]
	v_pk_fma_f32 v[32:33], v[32:33], v[20:21], v[20:21] neg_lo:[1,0,0] neg_hi:[1,0,0]
	v_cmp_gt_f32_e64 s[44:45], 0, v20
	v_cmp_gt_f32_e64 s[42:43], 0, v27
	v_cmp_gt_f32_e64 s[46:47], 0, v21
	v_cndmask_b32_e64 v26, v32, v34, s[44:45]
	v_cndmask_b32_e64 v29, v29, v31, s[42:43]
	v_cndmask_b32_e64 v27, v33, v35, s[46:47]
	s_waitcnt vmcnt(3)
	v_lshlrev_b32_e32 v30, 16, v9
	v_fma_f32 v9, |v30|, s92, 1.0
	v_rcp_f32_e32 v32, v9
	v_mul_f32_e32 v9, v30, v30
	s_waitcnt vmcnt(2)
	v_lshlrev_b32_e32 v31, 16, v11
	v_mul_f32_e32 v9, 0xbf38aa3b, v9
	v_exp_f32_e32 v34, v9
	v_fma_f32 v9, |v31|, s92, 1.0
	v_rcp_f32_e32 v33, v9
	v_mul_f32_e32 v9, v31, v31
	s_waitcnt vmcnt(1)
	v_lshlrev_b32_e32 v20, 16, v13
	v_mul_f32_e32 v9, 0xbf38aa3b, v9
	v_exp_f32_e32 v35, v9
	v_fma_f32 v9, |v20|, s92, 1.0
	v_rcp_f32_e32 v36, v9
	v_mul_f32_e32 v9, v20, v20
	s_waitcnt vmcnt(0)
	v_lshlrev_b32_e32 v21, 16, v15
	v_mul_f32_e32 v9, 0xbf38aa3b, v9
	v_exp_f32_e32 v38, v9
	v_fma_f32 v9, |v21|, s92, 1.0
	v_rcp_f32_e32 v37, v9
	v_mul_f32_e32 v9, v21, v21
	v_mul_f32_e32 v9, 0xbf38aa3b, v9
	v_exp_f32_e32 v39, v9
	global_load_ushort v9, v7, s[28:29] offset:896
	global_load_ushort v11, v7, s[88:89] offset:896
	global_load_ushort v13, v7, s[84:85] offset:896
	global_load_ushort v15, v7, s[40:41] offset:896
	v_pk_fma_f32 v[40:41], v[32:33], s[12:13], v[18:19] op_sel_hi:[1,0,0]
	v_pk_fma_f32 v[42:43], v[36:37], s[12:13], v[18:19] op_sel_hi:[1,0,0]
	v_pk_fma_f32 v[40:41], v[32:33], v[40:41], s[14:15] op_sel_hi:[1,1,0]
	v_pk_fma_f32 v[42:43], v[36:37], v[42:43], s[14:15] op_sel_hi:[1,1,0]
	v_pk_fma_f32 v[40:41], v[32:33], v[40:41], s[16:17] op_sel_hi:[1,1,0]
	v_pk_fma_f32 v[42:43], v[36:37], v[42:43], s[16:17] op_sel_hi:[1,1,0]
	v_pk_fma_f32 v[40:41], v[32:33], v[40:41], s[18:19] op_sel_hi:[1,1,0]
	v_pk_fma_f32 v[42:43], v[36:37], v[42:43], s[18:19] op_sel_hi:[1,1,0]
	v_pk_mul_f32 v[32:33], v[32:33], v[40:41]
	v_pk_mul_f32 v[36:37], v[36:37], v[42:43]
	v_pk_mul_f32 v[32:33], v[34:35], v[32:33]
	v_cmp_gt_f32_e32 vcc, 0, v30
	v_pk_mul_f32 v[34:35], v[32:33], v[30:31]
	v_pk_fma_f32 v[32:33], v[32:33], v[30:31], v[30:31] neg_lo:[1,0,0] neg_hi:[1,0,0]
	v_pk_mul_f32 v[36:37], v[38:39], v[36:37]
	v_cndmask_b32_e32 v32, v32, v34, vcc
	v_pk_mul_f32 v[38:39], v[36:37], v[20:21]
	v_pk_fma_f32 v[36:37], v[36:37], v[20:21], v[20:21] neg_lo:[1,0,0] neg_hi:[1,0,0]
	v_cmp_gt_f32_e64 s[44:45], 0, v20
	v_cmp_gt_f32_e64 s[42:43], 0, v31
	v_cmp_gt_f32_e64 s[46:47], 0, v21
	v_cndmask_b32_e64 v30, v36, v38, s[44:45]
	v_cndmask_b32_e64 v33, v33, v35, s[42:43]
	v_cndmask_b32_e64 v31, v37, v39, s[46:47]
	s_mov_b64 s[84:85], s[10:11]
	s_mov_b32 s10, 0x3b800000
	v_readlane_b32 s40, v253, 54
	s_waitcnt vmcnt(3)
	v_lshlrev_b32_e32 v34, 16, v9
	v_fma_f32 v9, |v34|, s92, 1.0
	v_rcp_f32_e32 v36, v9
	v_mul_f32_e32 v9, v34, v34
	s_waitcnt vmcnt(2)
	v_lshlrev_b32_e32 v35, 16, v11
	v_mul_f32_e32 v9, 0xbf38aa3b, v9
	v_exp_f32_e32 v38, v9
	v_fma_f32 v9, |v35|, s92, 1.0
	v_rcp_f32_e32 v37, v9
	v_mul_f32_e32 v9, v35, v35
	s_waitcnt vmcnt(1)
	v_lshlrev_b32_e32 v20, 16, v13
	v_mul_f32_e32 v9, 0xbf38aa3b, v9
	v_exp_f32_e32 v39, v9
	v_fma_f32 v9, |v20|, s92, 1.0
	v_rcp_f32_e32 v40, v9
	v_mul_f32_e32 v9, v20, v20
	s_waitcnt vmcnt(0)
	v_lshlrev_b32_e32 v21, 16, v15
	v_mul_f32_e32 v9, 0xbf38aa3b, v9
	v_exp_f32_e32 v42, v9
	v_fma_f32 v9, |v21|, s92, 1.0
	v_rcp_f32_e32 v41, v9
	v_pk_fma_f32 v[44:45], v[36:37], s[12:13], v[18:19] op_sel_hi:[1,0,0]
	v_mul_f32_e32 v9, v21, v21
	v_pk_fma_f32 v[44:45], v[36:37], v[44:45], s[14:15] op_sel_hi:[1,1,0]
	v_pk_fma_f32 v[46:47], v[40:41], s[12:13], v[18:19] op_sel_hi:[1,0,0]
	v_pk_fma_f32 v[44:45], v[36:37], v[44:45], s[16:17] op_sel_hi:[1,1,0]
	v_mul_f32_e32 v9, 0xbf38aa3b, v9
	v_pk_fma_f32 v[46:47], v[40:41], v[46:47], s[14:15] op_sel_hi:[1,1,0]
	v_pk_fma_f32 v[44:45], v[36:37], v[44:45], s[18:19] op_sel_hi:[1,1,0]
	v_exp_f32_e32 v43, v9
	v_pk_fma_f32 v[46:47], v[40:41], v[46:47], s[16:17] op_sel_hi:[1,1,0]
	v_pk_mul_f32 v[36:37], v[36:37], v[44:45]
	v_pk_fma_f32 v[46:47], v[40:41], v[46:47], s[18:19] op_sel_hi:[1,1,0]
	v_pk_mul_f32 v[36:37], v[38:39], v[36:37]
	v_pk_mul_f32 v[40:41], v[40:41], v[46:47]
	v_pk_mul_f32 v[38:39], v[36:37], v[34:35]
	v_pk_fma_f32 v[36:37], v[36:37], v[34:35], v[34:35] neg_lo:[1,0,0] neg_hi:[1,0,0]
	v_cmp_gt_f32_e32 vcc, 0, v34
	v_pk_mul_f32 v[40:41], v[42:43], v[40:41]
	v_cmp_gt_f32_e64 s[42:43], 0, v35
	v_cndmask_b32_e32 v36, v36, v38, vcc
	v_pk_mul_f32 v[42:43], v[40:41], v[20:21]
	v_pk_fma_f32 v[40:41], v[40:41], v[20:21], v[20:21] neg_lo:[1,0,0] neg_hi:[1,0,0]
	v_cmp_gt_f32_e64 s[44:45], 0, v20
	v_cmp_gt_f32_e64 s[46:47], 0, v21
	v_cndmask_b32_e64 v37, v37, v39, s[42:43]
	v_mov_b32_e32 v20, v22
	v_mov_b32_e32 v21, v32
	v_mov_b32_e32 v38, v28
	v_mov_b32_e32 v39, v36
	v_cndmask_b32_e64 v35, v41, v43, s[46:47]
	v_cndmask_b32_e64 v34, v40, v42, s[44:45]
	v_pk_add_f32 v[42:43], v[20:21], v[38:39]
	v_mov_b32_e32 v11, v131
	v_add_f32_e32 v9, v42, v43
	v_mov_b32_e32 v20, v23
	v_mov_b32_e32 v21, v33
	v_add_f32_dpp v9, v9, v9 quad_perm:[1,0,3,2] row_mask:0xf bank_mask:0xf bound_ctrl:1
	v_mov_b32_e32 v38, v29
	v_mov_b32_e32 v39, v37
	v_add_f32_dpp v9, v9, v9 quad_perm:[2,3,0,1] row_mask:0xf bank_mask:0xf bound_ctrl:1
	v_pk_add_f32 v[40:41], v[20:21], v[38:39]
	v_mov_b32_e32 v20, v24
	v_add_f32_dpp v9, v9, v9 row_half_mirror row_mask:0xf bank_mask:0xf bound_ctrl:1
	v_mov_b32_e32 v21, v30
	v_mov_b32_e32 v38, v26
	v_add_f32_dpp v9, v9, v9 row_mirror row_mask:0xf bank_mask:0xf bound_ctrl:1
	v_mov_b32_e32 v39, v34
	v_pk_add_f32 v[38:39], v[20:21], v[38:39]
	v_mov_b32_dpp v11, v9 row_bcast:15 row_mask:0xa bank_mask:0xf
	v_add_f32_e32 v9, v9, v11
	v_mov_b32_e32 v20, v25
	v_mov_b32_e32 v21, v31
	v_add_f32_dpp v9, v9, v9 row_bcast:31 row_mask:0xc bank_mask:0xf
	s_nop 0
	v_readlane_b32 s6, v9, 63
	v_add_f32_e32 v9, v40, v41
	v_mov_b32_e32 v44, v27
	v_mov_b32_e32 v45, v35
	v_add_f32_dpp v9, v9, v9 quad_perm:[1,0,3,2] row_mask:0xf bank_mask:0xf bound_ctrl:1
	v_pk_add_f32 v[20:21], v[20:21], v[44:45]
	s_xor_b32 s6, s6, 0x80000000
	v_add_f32_dpp v9, v9, v9 quad_perm:[2,3,0,1] row_mask:0xf bank_mask:0xf bound_ctrl:1
	s_nop 1
	v_add_f32_dpp v9, v9, v9 row_half_mirror row_mask:0xf bank_mask:0xf bound_ctrl:1
	s_nop 1
	v_add_f32_dpp v9, v9, v9 row_mirror row_mask:0xf bank_mask:0xf bound_ctrl:1
	s_nop 1
	v_add_f32_dpp v9, v9, v9 row_bcast:15 row_mask:0xa bank_mask:0xf
	s_nop 1
	v_add_f32_dpp v9, v9, v9 row_bcast:31 row_mask:0xc bank_mask:0xf
	s_nop 0
	v_readlane_b32 s7, v9, 63
	v_add_f32_e32 v9, v38, v39
	s_xor_b32 s7, s7, 0x80000000
	s_nop 0
	v_add_f32_dpp v9, v9, v9 quad_perm:[1,0,3,2] row_mask:0xf bank_mask:0xf bound_ctrl:1
	s_nop 1
	v_add_f32_dpp v9, v9, v9 quad_perm:[2,3,0,1] row_mask:0xf bank_mask:0xf bound_ctrl:1
	s_nop 1
	v_add_f32_dpp v9, v9, v9 row_half_mirror row_mask:0xf bank_mask:0xf bound_ctrl:1
	s_nop 1
	v_add_f32_dpp v9, v9, v9 row_mirror row_mask:0xf bank_mask:0xf bound_ctrl:1
	s_nop 1
	v_add_f32_dpp v9, v9, v9 row_bcast:15 row_mask:0xa bank_mask:0xf
	s_nop 1
	v_add_f32_dpp v9, v9, v9 row_bcast:31 row_mask:0xc bank_mask:0xf
	v_mov_b32_e32 v11, v131
	v_readlane_b32 s8, v9, 63
	v_add_f32_e32 v9, v20, v21
	v_mov_b64_e32 v[20:21], s[10:11]
	v_pk_fma_f32 v[42:43], s[6:7], v[20:21], v[28:29] op_sel_hi:[1,0,1]
	v_add_f32_dpp v9, v9, v9 quad_perm:[1,0,3,2] row_mask:0xf bank_mask:0xf bound_ctrl:1
	v_pk_fma_f32 v[38:39], s[6:7], v[20:21], v[36:37] op_sel_hi:[1,0,1]
	s_xor_b32 s8, s8, 0x80000000
	v_add_f32_dpp v9, v9, v9 quad_perm:[2,3,0,1] row_mask:0xf bank_mask:0xf bound_ctrl:1
	v_pk_fma_f32 v[44:45], s[6:7], v[20:21], v[22:23] op_sel_hi:[1,0,1]
	v_pk_fma_f32 v[28:29], s[6:7], v[20:21], v[32:33] op_sel_hi:[1,0,1]
	v_add_f32_dpp v9, v9, v9 row_half_mirror row_mask:0xf bank_mask:0xf bound_ctrl:1
	v_mov_b32_e32 v32, v42
	v_mov_b32_e32 v33, v38
	v_add_f32_dpp v9, v9, v9 row_mirror row_mask:0xf bank_mask:0xf bound_ctrl:1
	v_pk_mul_f32 v[32:33], v[32:33], v[32:33]
	s_nop 0
	v_mov_b32_dpp v11, v9 row_bcast:15 row_mask:0xa bank_mask:0xf
	v_add_f32_e32 v9, v9, v11
	s_nop 1
	v_add_f32_dpp v9, v9, v9 row_bcast:31 row_mask:0xc bank_mask:0xf
	v_mov_b32_e32 v11, v131
	v_readlane_b32 s9, v9, 63
	s_xor_b32 s9, s9, 0x80000000
	s_nop 0
	v_pk_fma_f32 v[40:41], s[8:9], v[20:21], v[24:25] op_sel_hi:[1,0,1]
	v_pk_fma_f32 v[24:25], s[8:9], v[20:21], v[30:31] op_sel_hi:[1,0,1]
	v_mov_b32_e32 v30, v44
	v_mov_b32_e32 v31, v28
	v_pk_fma_f32 v[30:31], v[30:31], v[30:31], v[32:33]
	v_mov_b32_e32 v32, v43
	v_add_f32_e32 v9, v30, v31
	v_mov_b32_e32 v33, v39
	v_mov_b32_e32 v30, v45
	v_add_f32_dpp v9, v9, v9 quad_perm:[1,0,3,2] row_mask:0xf bank_mask:0xf bound_ctrl:1
	v_mov_b32_e32 v31, v29
	v_pk_mul_f32 v[32:33], v[32:33], v[32:33]
	v_add_f32_dpp v9, v9, v9 quad_perm:[2,3,0,1] row_mask:0xf bank_mask:0xf bound_ctrl:1
	v_pk_fma_f32 v[30:31], v[30:31], v[30:31], v[32:33]
	v_pk_fma_f32 v[26:27], s[8:9], v[20:21], v[26:27] op_sel_hi:[1,0,1]
	v_add_f32_dpp v9, v9, v9 row_half_mirror row_mask:0xf bank_mask:0xf bound_ctrl:1
	v_pk_fma_f32 v[22:23], s[8:9], v[20:21], v[34:35] op_sel_hi:[1,0,1]
	v_mov_b32_e32 v32, v26
	v_add_f32_dpp v9, v9, v9 row_mirror row_mask:0xf bank_mask:0xf bound_ctrl:1
	v_mov_b32_e32 v33, v22
	v_pk_mul_f32 v[32:33], v[32:33], v[32:33]
	v_mov_b32_dpp v11, v9 row_bcast:15 row_mask:0xa bank_mask:0xf
	v_add_f32_e32 v9, v9, v11
	s_nop 1
	v_add_f32_dpp v9, v9, v9 row_bcast:31 row_mask:0xc bank_mask:0xf
	v_mov_b32_e32 v11, v131
	v_readlane_b32 s6, v9, 63
	s_nop 1
	v_fma_f32 v9, s6, v235, v225
	v_rsq_f32_e32 v46, v9
	v_add_f32_e32 v9, v30, v31
	v_mov_b32_e32 v30, v40
	v_mov_b32_e32 v31, v24
	v_add_f32_dpp v9, v9, v9 quad_perm:[1,0,3,2] row_mask:0xf bank_mask:0xf bound_ctrl:1
	v_pk_fma_f32 v[30:31], v[30:31], v[30:31], v[32:33]
	v_mov_b32_e32 v32, v27
	v_add_f32_dpp v9, v9, v9 quad_perm:[2,3,0,1] row_mask:0xf bank_mask:0xf bound_ctrl:1
	v_mov_b32_e32 v33, v23
	v_pk_mul_f32 v[32:33], v[32:33], v[32:33]
	v_add_f32_dpp v9, v9, v9 row_half_mirror row_mask:0xf bank_mask:0xf bound_ctrl:1
	s_nop 1
	v_add_f32_dpp v9, v9, v9 row_mirror row_mask:0xf bank_mask:0xf bound_ctrl:1
	s_nop 1
	v_mov_b32_dpp v11, v9 row_bcast:15 row_mask:0xa bank_mask:0xf
	v_add_f32_e32 v9, v9, v11
	s_nop 1
	v_add_f32_dpp v9, v9, v9 row_bcast:31 row_mask:0xc bank_mask:0xf
	v_mov_b32_e32 v11, v131
	v_readlane_b32 s6, v9, 63
	s_nop 1
	v_fma_f32 v9, s6, v235, v225
	v_rsq_f32_e32 v47, v9
	v_add_f32_e32 v9, v30, v31
	v_mov_b32_e32 v30, v41
	v_mov_b32_e32 v31, v25
	v_add_f32_dpp v9, v9, v9 quad_perm:[1,0,3,2] row_mask:0xf bank_mask:0xf bound_ctrl:1
	v_pk_fma_f32 v[30:31], v[30:31], v[30:31], v[32:33]
	v_pk_mul_f32 v[28:29], v[28:29], v[46:47]
	v_add_f32_dpp v9, v9, v9 quad_perm:[2,3,0,1] row_mask:0xf bank_mask:0xf bound_ctrl:1
	s_nop 1
	v_add_f32_dpp v9, v9, v9 row_half_mirror row_mask:0xf bank_mask:0xf bound_ctrl:1
	s_nop 1
	v_add_f32_dpp v9, v9, v9 row_mirror row_mask:0xf bank_mask:0xf bound_ctrl:1
	s_nop 1
	v_mov_b32_dpp v11, v9 row_bcast:15 row_mask:0xa bank_mask:0xf
	v_add_f32_e32 v9, v9, v11
	s_nop 1
	v_add_f32_dpp v9, v9, v9 row_bcast:31 row_mask:0xc bank_mask:0xf
	v_mov_b32_e32 v11, v131
	v_readlane_b32 s6, v9, 63
	s_nop 1
	v_fma_f32 v9, s6, v235, v225
	v_rsq_f32_e32 v48, v9
	v_add_f32_e32 v9, v30, v31
	v_pk_mul_f32 v[30:31], v[44:45], v[46:47]
	s_nop 0
	v_add_f32_dpp v9, v9, v9 quad_perm:[1,0,3,2] row_mask:0xf bank_mask:0xf bound_ctrl:1
	v_pk_fma_f32 v[36:37], v[14:15], v[30:31], v[16:17] op_sel_hi:[0,1,0]
	s_nop 0
	v_add_f32_dpp v9, v9, v9 quad_perm:[2,3,0,1] row_mask:0xf bank_mask:0xf bound_ctrl:1
	s_nop 1
	v_add_f32_dpp v9, v9, v9 row_half_mirror row_mask:0xf bank_mask:0xf bound_ctrl:1
	s_nop 1
	v_add_f32_dpp v9, v9, v9 row_mirror row_mask:0xf bank_mask:0xf bound_ctrl:1
	s_nop 1
	v_mov_b32_dpp v11, v9 row_bcast:15 row_mask:0xa bank_mask:0xf
	v_add_f32_e32 v9, v9, v11
	v_mov_b32_e32 v11, v131
	s_nop 1
	v_mov_b32_dpp v11, v9 row_bcast:31 row_mask:0xc bank_mask:0xf
	v_add_f32_e32 v9, v9, v11
	s_nop 0
	v_readlane_b32 s6, v9, 63
	s_nop 1
	v_fma_f32 v9, s6, v235, v225
	v_rsq_f32_e32 v49, v9
	v_pk_fma_f32 v[28:29], v[6:7], v[28:29], v[8:9] op_sel_hi:[0,1,0]
	v_pk_mul_f32 v[32:33], v[40:41], v[48:49]
	v_pk_fma_f32 v[34:35], v[14:15], v[32:33], v[16:17] op_sel_hi:[0,1,0]
	v_pk_mul_f32 v[32:33], v[42:43], v[46:47]
	v_pk_mul_f32 v[26:27], v[26:27], v[48:49]
	v_pk_mul_f32 v[24:25], v[24:25], v[48:49]
	v_pk_fma_f32 v[30:31], v[10:11], v[26:27], v[12:13] op_sel_hi:[0,1,0]
	v_pk_fma_f32 v[32:33], v[10:11], v[32:33], v[12:13] op_sel_hi:[0,1,0]
	v_pk_fma_f32 v[26:27], v[6:7], v[24:25], v[8:9] op_sel_hi:[0,1,0]
	global_load_ushort v9, v7, s[58:59] offset:512
	global_load_ushort v11, v7, s[60:61] offset:512
	global_load_ushort v13, v7, s[56:57] offset:512
	global_load_ushort v15, v7, s[94:95] offset:512
	v_pk_mul_f32 v[24:25], v[38:39], v[46:47]
	v_pk_mul_f32 v[22:23], v[22:23], v[48:49]
	v_pk_fma_f32 v[24:25], v[2:3], v[24:25], v[4:5] op_sel_hi:[0,1,0]
	v_pk_fma_f32 v[22:23], v[2:3], v[22:23], v[4:5] op_sel_hi:[0,1,0]
	s_waitcnt vmcnt(3)
	v_lshlrev_b32_e32 v40, 16, v9
	v_fma_f32 v9, |v40|, s92, 1.0
	v_rcp_f32_e32 v42, v9
	v_mul_f32_e32 v9, v40, v40
	s_waitcnt vmcnt(2)
	v_lshlrev_b32_e32 v41, 16, v11
	v_mul_f32_e32 v9, 0xbf38aa3b, v9
	v_exp_f32_e32 v44, v9
	v_fma_f32 v9, |v41|, s92, 1.0
	v_rcp_f32_e32 v43, v9
	v_mul_f32_e32 v9, v41, v41
	s_waitcnt vmcnt(1)
	v_lshlrev_b32_e32 v38, 16, v13
	v_mul_f32_e32 v9, 0xbf38aa3b, v9
	v_exp_f32_e32 v45, v9
	v_fma_f32 v9, |v38|, s92, 1.0
	v_rcp_f32_e32 v46, v9
	v_mul_f32_e32 v9, v38, v38
	s_waitcnt vmcnt(0)
	v_lshlrev_b32_e32 v39, 16, v15
	v_mul_f32_e32 v9, 0xbf38aa3b, v9
	v_exp_f32_e32 v48, v9
	v_fma_f32 v9, |v39|, s92, 1.0
	v_rcp_f32_e32 v47, v9
	v_mul_f32_e32 v9, v39, v39
	v_mul_f32_e32 v9, 0xbf38aa3b, v9
	v_exp_f32_e32 v49, v9
	global_load_ushort v9, v7, s[58:59] offset:640
	global_load_ushort v11, v7, s[60:61] offset:640
	global_load_ushort v13, v7, s[56:57] offset:640
	global_load_ushort v15, v7, s[94:95] offset:640
	v_pk_fma_f32 v[50:51], v[42:43], s[12:13], v[18:19] op_sel_hi:[1,0,0]
	v_pk_fma_f32 v[52:53], v[46:47], s[12:13], v[18:19] op_sel_hi:[1,0,0]
	v_pk_fma_f32 v[50:51], v[42:43], v[50:51], s[14:15] op_sel_hi:[1,1,0]
	v_pk_fma_f32 v[52:53], v[46:47], v[52:53], s[14:15] op_sel_hi:[1,1,0]
	v_pk_fma_f32 v[50:51], v[42:43], v[50:51], s[16:17] op_sel_hi:[1,1,0]
	v_pk_fma_f32 v[52:53], v[46:47], v[52:53], s[16:17] op_sel_hi:[1,1,0]
	v_pk_fma_f32 v[50:51], v[42:43], v[50:51], s[18:19] op_sel_hi:[1,1,0]
	v_pk_fma_f32 v[52:53], v[46:47], v[52:53], s[18:19] op_sel_hi:[1,1,0]
	v_pk_mul_f32 v[42:43], v[42:43], v[50:51]
	v_pk_mul_f32 v[46:47], v[46:47], v[52:53]
	v_pk_mul_f32 v[42:43], v[44:45], v[42:43]
	v_pk_mul_f32 v[46:47], v[48:49], v[46:47]
	v_pk_mul_f32 v[44:45], v[42:43], v[40:41]
	v_pk_fma_f32 v[42:43], v[42:43], v[40:41], v[40:41] neg_lo:[1,0,0] neg_hi:[1,0,0]
	v_cmp_gt_f32_e32 vcc, 0, v40
	v_pk_mul_f32 v[48:49], v[46:47], v[38:39]
	v_pk_fma_f32 v[46:47], v[46:47], v[38:39], v[38:39] neg_lo:[1,0,0] neg_hi:[1,0,0]
	v_cmp_gt_f32_e64 s[44:45], 0, v38
	v_cndmask_b32_e32 v38, v42, v44, vcc
	v_cmp_gt_f32_e64 s[42:43], 0, v41
	v_cndmask_b32_e64 v40, v46, v48, s[44:45]
	v_cmp_gt_f32_e64 s[46:47], 0, v39
	v_cndmask_b32_e64 v39, v43, v45, s[42:43]
	s_waitcnt vmcnt(3)
	v_lshlrev_b32_e32 v44, 16, v9
	v_fma_f32 v9, |v44|, s92, 1.0
	v_rcp_f32_e32 v46, v9
	v_mul_f32_e32 v9, v44, v44
	s_waitcnt vmcnt(2)
	v_lshlrev_b32_e32 v45, 16, v11
	v_mul_f32_e32 v9, 0xbf38aa3b, v9
	v_exp_f32_e32 v48, v9
	v_fma_f32 v9, |v45|, s92, 1.0
	v_cndmask_b32_e64 v41, v47, v49, s[46:47]
	v_rcp_f32_e32 v47, v9
	v_mul_f32_e32 v9, v45, v45
	s_waitcnt vmcnt(1)
	v_lshlrev_b32_e32 v42, 16, v13
	v_mul_f32_e32 v9, 0xbf38aa3b, v9
	v_exp_f32_e32 v49, v9
	v_fma_f32 v9, |v42|, s92, 1.0
	v_rcp_f32_e32 v50, v9
	v_mul_f32_e32 v9, v42, v42
	s_waitcnt vmcnt(0)
	v_lshlrev_b32_e32 v43, 16, v15
	v_mul_f32_e32 v9, 0xbf38aa3b, v9
	v_exp_f32_e32 v52, v9
	v_fma_f32 v9, |v43|, s92, 1.0
	v_rcp_f32_e32 v51, v9
	v_mul_f32_e32 v9, v43, v43
	v_mul_f32_e32 v9, 0xbf38aa3b, v9
	v_exp_f32_e32 v53, v9
	global_load_ushort v9, v7, s[58:59] offset:768
	global_load_ushort v11, v7, s[60:61] offset:768
	global_load_ushort v13, v7, s[56:57] offset:768
	global_load_ushort v15, v7, s[94:95] offset:768
	v_pk_fma_f32 v[54:55], v[46:47], s[12:13], v[18:19] op_sel_hi:[1,0,0]
	v_pk_fma_f32 v[56:57], v[50:51], s[12:13], v[18:19] op_sel_hi:[1,0,0]
	v_pk_fma_f32 v[54:55], v[46:47], v[54:55], s[14:15] op_sel_hi:[1,1,0]
	v_pk_fma_f32 v[56:57], v[50:51], v[56:57], s[14:15] op_sel_hi:[1,1,0]
	v_pk_fma_f32 v[54:55], v[46:47], v[54:55], s[16:17] op_sel_hi:[1,1,0]
	v_pk_fma_f32 v[56:57], v[50:51], v[56:57], s[16:17] op_sel_hi:[1,1,0]
	v_pk_fma_f32 v[54:55], v[46:47], v[54:55], s[18:19] op_sel_hi:[1,1,0]
	v_pk_fma_f32 v[56:57], v[50:51], v[56:57], s[18:19] op_sel_hi:[1,1,0]
	v_pk_mul_f32 v[46:47], v[46:47], v[54:55]
	v_pk_mul_f32 v[50:51], v[50:51], v[56:57]
	v_pk_mul_f32 v[46:47], v[48:49], v[46:47]
	v_cmp_gt_f32_e32 vcc, 0, v44
	v_pk_mul_f32 v[48:49], v[46:47], v[44:45]
	v_pk_fma_f32 v[46:47], v[46:47], v[44:45], v[44:45] neg_lo:[1,0,0] neg_hi:[1,0,0]
	v_pk_mul_f32 v[50:51], v[52:53], v[50:51]
	v_cndmask_b32_e32 v44, v46, v48, vcc
	v_pk_mul_f32 v[52:53], v[50:51], v[42:43]
	v_pk_fma_f32 v[50:51], v[50:51], v[42:43], v[42:43] neg_lo:[1,0,0] neg_hi:[1,0,0]
	v_cmp_gt_f32_e64 s[44:45], 0, v42
	v_cmp_gt_f32_e64 s[42:43], 0, v45
	v_cmp_gt_f32_e64 s[46:47], 0, v43
	v_cndmask_b32_e64 v42, v50, v52, s[44:45]
	v_cndmask_b32_e64 v45, v47, v49, s[42:43]
	v_cndmask_b32_e64 v43, v51, v53, s[46:47]
	s_waitcnt vmcnt(3)
	v_lshlrev_b32_e32 v48, 16, v9
	v_fma_f32 v9, |v48|, s92, 1.0
	v_rcp_f32_e32 v50, v9
	v_mul_f32_e32 v9, v48, v48
	s_waitcnt vmcnt(2)
	v_lshlrev_b32_e32 v49, 16, v11
	v_mul_f32_e32 v9, 0xbf38aa3b, v9
	v_exp_f32_e32 v52, v9
	v_fma_f32 v9, |v49|, s92, 1.0
	v_rcp_f32_e32 v51, v9
	v_mul_f32_e32 v9, v49, v49
	s_waitcnt vmcnt(1)
	v_lshlrev_b32_e32 v46, 16, v13
	v_mul_f32_e32 v9, 0xbf38aa3b, v9
	v_exp_f32_e32 v53, v9
	v_fma_f32 v9, |v46|, s92, 1.0
	v_rcp_f32_e32 v54, v9
	v_mul_f32_e32 v9, v46, v46
	s_waitcnt vmcnt(0)
	v_lshlrev_b32_e32 v47, 16, v15
	v_mul_f32_e32 v9, 0xbf38aa3b, v9
	v_exp_f32_e32 v56, v9
	v_fma_f32 v9, |v47|, s92, 1.0
	v_rcp_f32_e32 v55, v9
	v_mul_f32_e32 v9, v47, v47
	v_mul_f32_e32 v9, 0xbf38aa3b, v9
	v_exp_f32_e32 v57, v9
	global_load_ushort v9, v7, s[58:59] offset:896
	global_load_ushort v11, v7, s[60:61] offset:896
	global_load_ushort v13, v7, s[56:57] offset:896
	global_load_ushort v15, v7, s[94:95] offset:896
	v_pk_fma_f32 v[58:59], v[50:51], s[12:13], v[18:19] op_sel_hi:[1,0,0]
	v_pk_fma_f32 v[60:61], v[54:55], s[12:13], v[18:19] op_sel_hi:[1,0,0]
	v_pk_fma_f32 v[58:59], v[50:51], v[58:59], s[14:15] op_sel_hi:[1,1,0]
	v_pk_fma_f32 v[60:61], v[54:55], v[60:61], s[14:15] op_sel_hi:[1,1,0]
	v_pk_fma_f32 v[58:59], v[50:51], v[58:59], s[16:17] op_sel_hi:[1,1,0]
	v_pk_fma_f32 v[60:61], v[54:55], v[60:61], s[16:17] op_sel_hi:[1,1,0]
	v_pk_fma_f32 v[58:59], v[50:51], v[58:59], s[18:19] op_sel_hi:[1,1,0]
	v_pk_fma_f32 v[60:61], v[54:55], v[60:61], s[18:19] op_sel_hi:[1,1,0]
	v_pk_mul_f32 v[50:51], v[50:51], v[58:59]
	v_pk_mul_f32 v[54:55], v[54:55], v[60:61]
	v_pk_mul_f32 v[50:51], v[52:53], v[50:51]
	v_cmp_gt_f32_e32 vcc, 0, v48
	v_pk_mul_f32 v[52:53], v[50:51], v[48:49]
	v_pk_fma_f32 v[50:51], v[50:51], v[48:49], v[48:49] neg_lo:[1,0,0] neg_hi:[1,0,0]
	v_pk_mul_f32 v[54:55], v[56:57], v[54:55]
	v_cndmask_b32_e32 v48, v50, v52, vcc
	v_pk_mul_f32 v[56:57], v[54:55], v[46:47]
	v_pk_fma_f32 v[54:55], v[54:55], v[46:47], v[46:47] neg_lo:[1,0,0] neg_hi:[1,0,0]
	v_cmp_gt_f32_e64 s[44:45], 0, v46
	v_cmp_gt_f32_e64 s[42:43], 0, v49
	v_cmp_gt_f32_e64 s[46:47], 0, v47
	v_cndmask_b32_e64 v46, v54, v56, s[44:45]
	v_cndmask_b32_e64 v49, v51, v53, s[42:43]
	v_cndmask_b32_e64 v47, v55, v57, s[46:47]
	global_load_ushort v68, v7, s[48:49] offset:512
	global_load_ushort v69, v7, s[50:51] offset:512
	global_load_ushort v70, v7, s[54:55] offset:512
	global_load_ushort v71, v7, s[66:67] offset:512
	global_load_ushort v72, v7, s[48:49] offset:640
	global_load_ushort v73, v7, s[50:51] offset:640
	global_load_ushort v74, v7, s[54:55] offset:640
	global_load_ushort v75, v7, s[66:67] offset:640
	global_load_ushort v76, v7, s[48:49] offset:768
	global_load_ushort v77, v7, s[50:51] offset:768
	global_load_ushort v78, v7, s[54:55] offset:768
	global_load_ushort v79, v7, s[66:67] offset:768
	global_load_ushort v80, v7, s[48:49] offset:896
	global_load_ushort v81, v7, s[50:51] offset:896
	global_load_ushort v82, v7, s[54:55] offset:896
	global_load_ushort v83, v7, s[66:67] offset:896
	s_mov_b32 s60, s19
	s_mov_b32 s66, s13
	s_waitcnt vmcnt(19)
	v_lshlrev_b32_e32 v52, 16, v9
	v_fma_f32 v9, |v52|, s92, 1.0
	v_rcp_f32_e32 v54, v9
	v_mul_f32_e32 v9, v52, v52
	s_waitcnt vmcnt(18)
	v_lshlrev_b32_e32 v53, 16, v11
	v_mul_f32_e32 v9, 0xbf38aa3b, v9
	v_exp_f32_e32 v56, v9
	v_fma_f32 v9, |v53|, s92, 1.0
	v_rcp_f32_e32 v55, v9
	v_mul_f32_e32 v9, v53, v53
	s_waitcnt vmcnt(17)
	v_lshlrev_b32_e32 v50, 16, v13
	v_mul_f32_e32 v9, 0xbf38aa3b, v9
	v_exp_f32_e32 v57, v9
	v_fma_f32 v9, |v50|, s92, 1.0
	v_rcp_f32_e32 v58, v9
	v_mul_f32_e32 v9, v50, v50
	s_waitcnt vmcnt(16)
	v_lshlrev_b32_e32 v51, 16, v15
	v_mul_f32_e32 v9, 0xbf38aa3b, v9
	v_exp_f32_e32 v60, v9
	v_fma_f32 v9, |v51|, s92, 1.0
	v_rcp_f32_e32 v59, v9
	v_pk_fma_f32 v[62:63], v[54:55], s[12:13], v[18:19] op_sel_hi:[1,0,0]
	v_mul_f32_e32 v9, v51, v51
	v_pk_fma_f32 v[62:63], v[54:55], v[62:63], s[14:15] op_sel_hi:[1,1,0]
	v_pk_fma_f32 v[64:65], v[58:59], s[12:13], v[18:19] op_sel_hi:[1,0,0]
	v_pk_fma_f32 v[62:63], v[54:55], v[62:63], s[16:17] op_sel_hi:[1,1,0]
	v_mul_f32_e32 v9, 0xbf38aa3b, v9
	v_pk_fma_f32 v[64:65], v[58:59], v[64:65], s[14:15] op_sel_hi:[1,1,0]
	v_pk_fma_f32 v[62:63], v[54:55], v[62:63], s[18:19] op_sel_hi:[1,1,0]
	v_exp_f32_e32 v61, v9
	v_pk_fma_f32 v[64:65], v[58:59], v[64:65], s[16:17] op_sel_hi:[1,1,0]
	v_pk_mul_f32 v[54:55], v[54:55], v[62:63]
	v_pk_fma_f32 v[64:65], v[58:59], v[64:65], s[18:19] op_sel_hi:[1,1,0]
	v_pk_mul_f32 v[54:55], v[56:57], v[54:55]
	v_pk_mul_f32 v[58:59], v[58:59], v[64:65]
	v_pk_mul_f32 v[56:57], v[54:55], v[52:53]
	v_pk_fma_f32 v[54:55], v[54:55], v[52:53], v[52:53] neg_lo:[1,0,0] neg_hi:[1,0,0]
	v_cmp_gt_f32_e32 vcc, 0, v52
	v_pk_mul_f32 v[58:59], v[60:61], v[58:59]
	v_cmp_gt_f32_e64 s[42:43], 0, v53
	v_cndmask_b32_e32 v52, v54, v56, vcc
	v_pk_mul_f32 v[60:61], v[58:59], v[50:51]
	v_pk_fma_f32 v[58:59], v[58:59], v[50:51], v[50:51] neg_lo:[1,0,0] neg_hi:[1,0,0]
	v_cmp_gt_f32_e64 s[44:45], 0, v50
	v_cmp_gt_f32_e64 s[46:47], 0, v51
	v_cndmask_b32_e64 v53, v55, v57, s[42:43]
	v_mov_b32_e32 v54, v38
	v_mov_b32_e32 v55, v48
	v_mov_b32_e32 v56, v44
	v_mov_b32_e32 v57, v52
	v_cndmask_b32_e64 v51, v59, v61, s[46:47]
	v_cndmask_b32_e64 v50, v58, v60, s[44:45]
	v_pk_add_f32 v[60:61], v[54:55], v[56:57]
	v_mov_b32_e32 v11, v131
	v_add_f32_e32 v9, v60, v61
	v_mov_b32_e32 v54, v39
	v_mov_b32_e32 v55, v49
	v_add_f32_dpp v9, v9, v9 quad_perm:[1,0,3,2] row_mask:0xf bank_mask:0xf bound_ctrl:1
	v_mov_b32_e32 v56, v45
	v_mov_b32_e32 v57, v53
	v_add_f32_dpp v9, v9, v9 quad_perm:[2,3,0,1] row_mask:0xf bank_mask:0xf bound_ctrl:1
	v_pk_add_f32 v[58:59], v[54:55], v[56:57]
	v_mov_b32_e32 v54, v40
	v_add_f32_dpp v9, v9, v9 row_half_mirror row_mask:0xf bank_mask:0xf bound_ctrl:1
	v_mov_b32_e32 v55, v46
	v_mov_b32_e32 v56, v42
	v_add_f32_dpp v9, v9, v9 row_mirror row_mask:0xf bank_mask:0xf bound_ctrl:1
	v_mov_b32_e32 v57, v50
	v_pk_add_f32 v[56:57], v[54:55], v[56:57]
	v_mov_b32_dpp v11, v9 row_bcast:15 row_mask:0xa bank_mask:0xf
	v_add_f32_e32 v9, v9, v11
	v_mov_b32_e32 v54, v41
	v_mov_b32_e32 v55, v47
	v_add_f32_dpp v9, v9, v9 row_bcast:31 row_mask:0xc bank_mask:0xf
	s_nop 0
	v_readlane_b32 s6, v9, 63
	v_add_f32_e32 v9, v58, v59
	v_mov_b32_e32 v62, v43
	v_mov_b32_e32 v63, v51
	v_add_f32_dpp v9, v9, v9 quad_perm:[1,0,3,2] row_mask:0xf bank_mask:0xf bound_ctrl:1
	v_pk_add_f32 v[54:55], v[54:55], v[62:63]
	s_xor_b32 s6, s6, 0x80000000
	v_add_f32_dpp v9, v9, v9 quad_perm:[2,3,0,1] row_mask:0xf bank_mask:0xf bound_ctrl:1
	v_cvt_pk_bf16_f32 v63, v34, v35
	v_cvt_pk_bf16_f32 v62, v36, v37
	v_add_f32_dpp v9, v9, v9 row_half_mirror row_mask:0xf bank_mask:0xf bound_ctrl:1
	s_nop 1
	v_add_f32_dpp v9, v9, v9 row_mirror row_mask:0xf bank_mask:0xf bound_ctrl:1
	s_nop 1
	v_add_f32_dpp v9, v9, v9 row_bcast:15 row_mask:0xa bank_mask:0xf
	s_nop 1
	v_add_f32_dpp v9, v9, v9 row_bcast:31 row_mask:0xc bank_mask:0xf
	s_nop 0
	v_readlane_b32 s7, v9, 63
	v_add_f32_e32 v9, v56, v57
	s_xor_b32 s7, s7, 0x80000000
	v_pk_fma_f32 v[56:57], s[6:7], v[20:21], v[44:45] op_sel_hi:[1,0,1]
	v_add_f32_dpp v9, v9, v9 quad_perm:[1,0,3,2] row_mask:0xf bank_mask:0xf bound_ctrl:1
	v_pk_fma_f32 v[60:61], s[6:7], v[20:21], v[38:39] op_sel_hi:[1,0,1]
	v_pk_fma_f32 v[44:45], s[6:7], v[20:21], v[48:49] op_sel_hi:[1,0,1]
	v_add_f32_dpp v9, v9, v9 quad_perm:[2,3,0,1] row_mask:0xf bank_mask:0xf bound_ctrl:1
	v_mov_b32_e32 v48, v56
	s_nop 0
	v_add_f32_dpp v9, v9, v9 row_half_mirror row_mask:0xf bank_mask:0xf bound_ctrl:1
	s_nop 1
	v_add_f32_dpp v9, v9, v9 row_mirror row_mask:0xf bank_mask:0xf bound_ctrl:1
	s_nop 1
	v_add_f32_dpp v9, v9, v9 row_bcast:15 row_mask:0xa bank_mask:0xf
	s_nop 1
	v_add_f32_dpp v9, v9, v9 row_bcast:31 row_mask:0xc bank_mask:0xf
	s_nop 0
	v_readlane_b32 s8, v9, 63
	v_add_f32_e32 v9, v54, v55
	s_xor_b32 s8, s8, 0x80000000
	s_nop 0
	v_add_f32_dpp v9, v9, v9 quad_perm:[1,0,3,2] row_mask:0xf bank_mask:0xf bound_ctrl:1
	s_nop 1
	v_add_f32_dpp v9, v9, v9 quad_perm:[2,3,0,1] row_mask:0xf bank_mask:0xf bound_ctrl:1
	s_nop 1
	v_add_f32_dpp v9, v9, v9 row_half_mirror row_mask:0xf bank_mask:0xf bound_ctrl:1
	s_nop 1
	v_add_f32_dpp v9, v9, v9 row_mirror row_mask:0xf bank_mask:0xf bound_ctrl:1
	s_nop 1
	v_add_f32_dpp v9, v9, v9 row_bcast:15 row_mask:0xa bank_mask:0xf
	s_nop 1
	v_add_f32_dpp v9, v9, v9 row_bcast:31 row_mask:0xc bank_mask:0xf
	v_mov_b32_e32 v11, v131
	v_readlane_b32 s9, v9, 63
	s_xor_b32 s9, s9, 0x80000000
	s_nop 0
	v_pk_fma_f32 v[58:59], s[8:9], v[20:21], v[40:41] op_sel_hi:[1,0,1]
	v_pk_fma_f32 v[40:41], s[6:7], v[20:21], v[52:53] op_sel_hi:[1,0,1]
	v_pk_fma_f32 v[54:55], s[8:9], v[20:21], v[42:43] op_sel_hi:[1,0,1]
	v_mov_b32_e32 v49, v40
	v_pk_fma_f32 v[42:43], s[8:9], v[20:21], v[46:47] op_sel_hi:[1,0,1]
	v_mov_b32_e32 v46, v60
	v_mov_b32_e32 v47, v44
	v_pk_mul_f32 v[48:49], v[48:49], v[48:49]
	v_pk_fma_f32 v[38:39], s[8:9], v[20:21], v[50:51] op_sel_hi:[1,0,1]
	v_pk_fma_f32 v[46:47], v[46:47], v[46:47], v[48:49]
	v_mov_b32_e32 v50, v57
	v_add_f32_e32 v9, v46, v47
	v_mov_b32_e32 v51, v41
	v_mov_b32_e32 v48, v61
	v_add_f32_dpp v9, v9, v9 quad_perm:[1,0,3,2] row_mask:0xf bank_mask:0xf bound_ctrl:1
	v_mov_b32_e32 v49, v45
	v_pk_mul_f32 v[50:51], v[50:51], v[50:51]
	v_add_f32_dpp v9, v9, v9 quad_perm:[2,3,0,1] row_mask:0xf bank_mask:0xf bound_ctrl:1
	v_pk_fma_f32 v[48:49], v[48:49], v[48:49], v[50:51]
	v_mov_b32_e32 v50, v54
	v_add_f32_dpp v9, v9, v9 row_half_mirror row_mask:0xf bank_mask:0xf bound_ctrl:1
	v_mov_b32_e32 v51, v38
	v_pk_mul_f32 v[50:51], v[50:51], v[50:51]
	v_add_f32_dpp v9, v9, v9 row_mirror row_mask:0xf bank_mask:0xf bound_ctrl:1
	s_nop 1
	v_mov_b32_dpp v11, v9 row_bcast:15 row_mask:0xa bank_mask:0xf
	v_add_f32_e32 v9, v9, v11
	s_nop 1
	v_add_f32_dpp v9, v9, v9 row_bcast:31 row_mask:0xc bank_mask:0xf
	v_mov_b32_e32 v11, v131
	v_readlane_b32 s6, v9, 63
	s_nop 1
	v_fma_f32 v9, s6, v235, v225
	v_rsq_f32_e32 v46, v9
	v_add_f32_e32 v9, v48, v49
	v_mov_b32_e32 v48, v58
	v_mov_b32_e32 v49, v42
	v_add_f32_dpp v9, v9, v9 quad_perm:[1,0,3,2] row_mask:0xf bank_mask:0xf bound_ctrl:1
	v_pk_fma_f32 v[48:49], v[48:49], v[48:49], v[50:51]
	v_mov_b32_e32 v50, v55
	v_add_f32_dpp v9, v9, v9 quad_perm:[2,3,0,1] row_mask:0xf bank_mask:0xf bound_ctrl:1
	v_mov_b32_e32 v51, v39
	v_pk_mul_f32 v[50:51], v[50:51], v[50:51]
	v_add_f32_dpp v9, v9, v9 row_half_mirror row_mask:0xf bank_mask:0xf bound_ctrl:1
	s_nop 1
	v_add_f32_dpp v9, v9, v9 row_mirror row_mask:0xf bank_mask:0xf bound_ctrl:1
	s_nop 1
	v_mov_b32_dpp v11, v9 row_bcast:15 row_mask:0xa bank_mask:0xf
	v_add_f32_e32 v9, v9, v11
	s_nop 1
	v_add_f32_dpp v9, v9, v9 row_bcast:31 row_mask:0xc bank_mask:0xf
	v_mov_b32_e32 v11, v131
	v_readlane_b32 s6, v9, 63
	s_nop 1
	v_fma_f32 v9, s6, v235, v225
	v_rsq_f32_e32 v47, v9
	v_add_f32_e32 v9, v48, v49
	v_mov_b32_e32 v48, v59
	v_mov_b32_e32 v49, v43
	v_add_f32_dpp v9, v9, v9 quad_perm:[1,0,3,2] row_mask:0xf bank_mask:0xf bound_ctrl:1
	v_pk_fma_f32 v[48:49], v[48:49], v[48:49], v[50:51]
	v_pk_mul_f32 v[34:35], v[56:57], v[46:47]
	v_add_f32_dpp v9, v9, v9 quad_perm:[2,3,0,1] row_mask:0xf bank_mask:0xf bound_ctrl:1
	s_nop 1
	v_add_f32_dpp v9, v9, v9 row_half_mirror row_mask:0xf bank_mask:0xf bound_ctrl:1
	s_nop 1
	v_add_f32_dpp v9, v9, v9 row_mirror row_mask:0xf bank_mask:0xf bound_ctrl:1
	s_nop 1
	v_mov_b32_dpp v11, v9 row_bcast:15 row_mask:0xa bank_mask:0xf
	v_add_f32_e32 v9, v9, v11
	s_nop 1
	v_add_f32_dpp v9, v9, v9 row_bcast:31 row_mask:0xc bank_mask:0xf
	v_mov_b32_e32 v11, v131
	v_readlane_b32 s6, v9, 63
	s_nop 1
	v_fma_f32 v9, s6, v235, v225
	v_rsq_f32_e32 v66, v9
	v_add_f32_e32 v9, v48, v49
	v_pk_mul_f32 v[48:49], v[60:61], v[46:47]
	s_nop 0
	v_add_f32_dpp v9, v9, v9 quad_perm:[1,0,3,2] row_mask:0xf bank_mask:0xf bound_ctrl:1
	v_pk_fma_f32 v[48:49], v[14:15], v[48:49], v[16:17] op_sel_hi:[0,1,0]
	v_cvt_pk_bf16_f32 v64, v48, v49
	v_add_f32_dpp v9, v9, v9 quad_perm:[2,3,0,1] row_mask:0xf bank_mask:0xf bound_ctrl:1
	s_nop 1
	v_add_f32_dpp v9, v9, v9 row_half_mirror row_mask:0xf bank_mask:0xf bound_ctrl:1
	s_nop 1
	v_add_f32_dpp v9, v9, v9 row_mirror row_mask:0xf bank_mask:0xf bound_ctrl:1
	s_nop 1
	v_mov_b32_dpp v11, v9 row_bcast:15 row_mask:0xa bank_mask:0xf
	v_add_f32_e32 v9, v9, v11
	s_nop 1
	v_add_f32_dpp v9, v9, v9 row_bcast:31 row_mask:0xc bank_mask:0xf
	s_nop 0
	v_readlane_b32 s6, v9, 63
	s_nop 1
	v_fma_f32 v9, s6, v235, v225
	v_rsq_f32_e32 v67, v9
	s_nop 0
	v_pk_mul_f32 v[50:51], v[58:59], v[66:67]
	v_pk_fma_f32 v[50:51], v[14:15], v[50:51], v[16:17] op_sel_hi:[0,1,0]
	v_cvt_pk_bf16_f32 v65, v50, v51
	global_load_ushort v58, v7, s[52:53] offset:512
	global_load_ushort v59, v7, s[64:65] offset:512
	global_load_ushort v60, v7, s[68:69] offset:512
	global_load_ushort v61, v7, s[72:73] offset:512
	global_load_ushort v50, v7, s[52:53] offset:640
	global_load_ushort v51, v7, s[64:65] offset:640
	global_load_ushort v52, v7, s[68:69] offset:640
	global_load_ushort v53, v7, s[72:73] offset:640
	global_load_ushort v15, v7, s[52:53] offset:768
	global_load_ushort v17, v7, s[64:65] offset:768
	global_load_ushort v48, v7, s[68:69] offset:768
	global_load_ushort v49, v7, s[72:73] offset:768
	global_load_ushort v9, v7, s[52:53] offset:896
	global_load_ushort v11, v7, s[64:65] offset:896
	global_load_ushort v13, v7, s[68:69] offset:896
	s_nop 0
	global_load_ushort v7, v7, s[72:73] offset:896
	v_pk_mul_f32 v[36:37], v[54:55], v[66:67]
	ds_write_b128 v5, v[62:65]
	s_waitcnt vmcnt(1)
	v_pk_fma_f32 v[36:37], v[10:11], v[36:37], v[12:13] op_sel_hi:[0,1,0]
	v_pk_fma_f32 v[34:35], v[10:11], v[34:35], v[12:13] op_sel_hi:[0,1,0]
	v_cvt_pk_bf16_f32 v37, v36, v37
	v_cvt_pk_bf16_f32 v36, v34, v35
	v_cvt_pk_bf16_f32 v35, v30, v31
	v_cvt_pk_bf16_f32 v34, v32, v33
	v_pk_mul_f32 v[30:31], v[44:45], v[46:47]
	v_pk_mul_f32 v[32:33], v[42:43], v[66:67]
	s_waitcnt vmcnt(0)
	v_pk_fma_f32 v[30:31], v[6:7], v[30:31], v[8:9] op_sel_hi:[0,1,0]
	v_pk_fma_f32 v[32:33], v[6:7], v[32:33], v[8:9] op_sel_hi:[0,1,0]
	v_cvt_pk_bf16_f32 v33, v32, v33
	v_cvt_pk_bf16_f32 v32, v30, v31
	v_cvt_pk_bf16_f32 v31, v26, v27
	v_cvt_pk_bf16_f32 v30, v28, v29
	v_pk_mul_f32 v[26:27], v[40:41], v[46:47]
	v_pk_mul_f32 v[28:29], v[38:39], v[66:67]
	v_pk_fma_f32 v[26:27], v[2:3], v[26:27], v[4:5] op_sel_hi:[0,1,0]
	v_pk_fma_f32 v[28:29], v[2:3], v[28:29], v[4:5] op_sel_hi:[0,1,0]
	v_cvt_pk_bf16_f32 v29, v28, v29
	v_cvt_pk_bf16_f32 v28, v26, v27
	v_cvt_pk_bf16_f32 v27, v22, v23
	v_cvt_pk_bf16_f32 v26, v24, v25
	v_lshlrev_b32_e32 v24, 16, v68
	ds_write_b128 v5, v[26:29] offset:52224
	v_lshlrev_b32_e32 v22, 16, v70
	v_mul_f32_e32 v27, v24, v24
	ds_write_b128 v5, v[30:33] offset:34816
	v_lshlrev_b32_e32 v25, 16, v69
	v_mul_f32_e32 v27, 0xbf38aa3b, v27
	v_mul_f32_e32 v31, v22, v22
	v_lshlrev_b32_e32 v23, 16, v71
	v_fma_f32 v26, |v24|, s92, 1.0
	v_exp_f32_e32 v28, v27
	v_fma_f32 v27, |v25|, s92, 1.0
	v_mul_f32_e32 v31, 0xbf38aa3b, v31
	v_rcp_f32_e32 v26, v26
	v_rcp_f32_e32 v27, v27
	v_fma_f32 v30, |v22|, s92, 1.0
	v_exp_f32_e32 v32, v31
	v_fma_f32 v31, |v23|, s92, 1.0
	v_rcp_f32_e32 v30, v30
	v_rcp_f32_e32 v31, v31
	v_mul_f32_e32 v29, v25, v25
	ds_write_b128 v5, v[34:37] offset:17408
	v_mul_f32_e32 v29, 0xbf38aa3b, v29
	v_pk_fma_f32 v[34:35], v[26:27], s[12:13], v[18:19] op_sel_hi:[1,0,0]
	v_mul_f32_e32 v33, v23, v23
	v_exp_f32_e32 v29, v29
	v_pk_fma_f32 v[36:37], v[30:31], s[12:13], v[18:19] op_sel_hi:[1,0,0]
	v_pk_fma_f32 v[34:35], v[26:27], v[34:35], s[14:15] op_sel_hi:[1,1,0]
	v_mul_f32_e32 v33, 0xbf38aa3b, v33
	v_pk_fma_f32 v[36:37], v[30:31], v[36:37], s[14:15] op_sel_hi:[1,1,0]
	v_pk_fma_f32 v[34:35], v[26:27], v[34:35], s[16:17] op_sel_hi:[1,1,0]
	v_exp_f32_e32 v33, v33
	v_pk_fma_f32 v[36:37], v[30:31], v[36:37], s[16:17] op_sel_hi:[1,1,0]
	v_pk_fma_f32 v[34:35], v[26:27], v[34:35], s[18:19] op_sel_hi:[1,1,0]
	v_pk_fma_f32 v[36:37], v[30:31], v[36:37], s[18:19] op_sel_hi:[1,1,0]
	v_pk_mul_f32 v[26:27], v[26:27], v[34:35]
	v_pk_mul_f32 v[30:31], v[30:31], v[36:37]
	v_pk_mul_f32 v[26:27], v[28:29], v[26:27]
	v_pk_mul_f32 v[30:31], v[32:33], v[30:31]
	v_pk_mul_f32 v[28:29], v[26:27], v[24:25]
	v_pk_fma_f32 v[26:27], v[26:27], v[24:25], v[24:25] neg_lo:[1,0,0] neg_hi:[1,0,0]
	v_cmp_gt_f32_e32 vcc, 0, v24
	v_pk_mul_f32 v[32:33], v[30:31], v[22:23]
	v_pk_fma_f32 v[30:31], v[30:31], v[22:23], v[22:23] neg_lo:[1,0,0] neg_hi:[1,0,0]
	v_cmp_gt_f32_e64 s[44:45], 0, v22
	v_cmp_gt_f32_e64 s[46:47], 0, v23
	v_cndmask_b32_e32 v22, v26, v28, vcc
	v_lshlrev_b32_e32 v28, 16, v72
	v_cmp_gt_f32_e64 s[42:43], 0, v25
	v_cndmask_b32_e64 v25, v31, v33, s[46:47]
	v_lshlrev_b32_e32 v26, 16, v74
	v_mul_f32_e32 v31, v28, v28
	v_cndmask_b32_e64 v23, v27, v29, s[42:43]
	v_lshlrev_b32_e32 v29, 16, v73
	v_mul_f32_e32 v31, 0xbf38aa3b, v31
	v_mul_f32_e32 v35, v26, v26
	v_cndmask_b32_e64 v24, v30, v32, s[44:45]
	v_lshlrev_b32_e32 v27, 16, v75
	v_fma_f32 v30, |v28|, s92, 1.0
	v_exp_f32_e32 v32, v31
	v_fma_f32 v31, |v29|, s92, 1.0
	v_mul_f32_e32 v35, 0xbf38aa3b, v35
	v_rcp_f32_e32 v30, v30
	v_rcp_f32_e32 v31, v31
	v_fma_f32 v34, |v26|, s92, 1.0
	v_exp_f32_e32 v36, v35
	v_fma_f32 v35, |v27|, s92, 1.0
	v_rcp_f32_e32 v34, v34
	v_rcp_f32_e32 v35, v35
	v_mul_f32_e32 v33, v29, v29
	v_mul_f32_e32 v33, 0xbf38aa3b, v33
	v_pk_fma_f32 v[38:39], v[30:31], s[12:13], v[18:19] op_sel_hi:[1,0,0]
	v_mul_f32_e32 v37, v27, v27
	v_exp_f32_e32 v33, v33
	v_pk_fma_f32 v[40:41], v[34:35], s[12:13], v[18:19] op_sel_hi:[1,0,0]
	v_pk_fma_f32 v[38:39], v[30:31], v[38:39], s[14:15] op_sel_hi:[1,1,0]
	v_mul_f32_e32 v37, 0xbf38aa3b, v37
	v_pk_fma_f32 v[40:41], v[34:35], v[40:41], s[14:15] op_sel_hi:[1,1,0]
	v_pk_fma_f32 v[38:39], v[30:31], v[38:39], s[16:17] op_sel_hi:[1,1,0]
	v_exp_f32_e32 v37, v37
	v_pk_fma_f32 v[40:41], v[34:35], v[40:41], s[16:17] op_sel_hi:[1,1,0]
	v_pk_fma_f32 v[38:39], v[30:31], v[38:39], s[18:19] op_sel_hi:[1,1,0]
	v_pk_fma_f32 v[40:41], v[34:35], v[40:41], s[18:19] op_sel_hi:[1,1,0]
	v_pk_mul_f32 v[30:31], v[30:31], v[38:39]
	v_pk_mul_f32 v[34:35], v[34:35], v[40:41]
	v_pk_mul_f32 v[30:31], v[32:33], v[30:31]
	v_pk_mul_f32 v[34:35], v[36:37], v[34:35]
	v_pk_mul_f32 v[32:33], v[30:31], v[28:29]
	v_pk_fma_f32 v[30:31], v[30:31], v[28:29], v[28:29] neg_lo:[1,0,0] neg_hi:[1,0,0]
	v_cmp_gt_f32_e32 vcc, 0, v28
	v_pk_mul_f32 v[36:37], v[34:35], v[26:27]
	v_pk_fma_f32 v[34:35], v[34:35], v[26:27], v[26:27] neg_lo:[1,0,0] neg_hi:[1,0,0]
	v_cmp_gt_f32_e64 s[46:47], 0, v27
	v_cndmask_b32_e32 v28, v30, v32, vcc
	v_lshlrev_b32_e32 v32, 16, v76
	v_cmp_gt_f32_e64 s[42:43], 0, v29
	v_cndmask_b32_e64 v27, v35, v37, s[46:47]
	v_lshlrev_b32_e32 v30, 16, v78
	v_mul_f32_e32 v35, v32, v32
	v_cmp_gt_f32_e64 s[44:45], 0, v26
	v_cndmask_b32_e64 v29, v31, v33, s[42:43]
	v_lshlrev_b32_e32 v33, 16, v77
	v_mul_f32_e32 v35, 0xbf38aa3b, v35
	v_mul_f32_e32 v39, v30, v30
	v_cndmask_b32_e64 v26, v34, v36, s[44:45]
	v_lshlrev_b32_e32 v31, 16, v79
	v_fma_f32 v34, |v32|, s92, 1.0
	v_exp_f32_e32 v36, v35
	v_fma_f32 v35, |v33|, s92, 1.0
	v_mul_f32_e32 v39, 0xbf38aa3b, v39
	v_rcp_f32_e32 v34, v34
	v_rcp_f32_e32 v35, v35
	v_fma_f32 v38, |v30|, s92, 1.0
	v_exp_f32_e32 v40, v39
	v_fma_f32 v39, |v31|, s92, 1.0
	v_rcp_f32_e32 v38, v38
	v_rcp_f32_e32 v39, v39
	v_mul_f32_e32 v37, v33, v33
	v_mul_f32_e32 v37, 0xbf38aa3b, v37
	v_pk_fma_f32 v[42:43], v[34:35], s[12:13], v[18:19] op_sel_hi:[1,0,0]
	v_mul_f32_e32 v41, v31, v31
	v_exp_f32_e32 v37, v37
	v_pk_fma_f32 v[44:45], v[38:39], s[12:13], v[18:19] op_sel_hi:[1,0,0]
	v_pk_fma_f32 v[42:43], v[34:35], v[42:43], s[14:15] op_sel_hi:[1,1,0]
	v_mul_f32_e32 v41, 0xbf38aa3b, v41
	v_pk_fma_f32 v[44:45], v[38:39], v[44:45], s[14:15] op_sel_hi:[1,1,0]
	v_pk_fma_f32 v[42:43], v[34:35], v[42:43], s[16:17] op_sel_hi:[1,1,0]
	v_exp_f32_e32 v41, v41
	v_pk_fma_f32 v[44:45], v[38:39], v[44:45], s[16:17] op_sel_hi:[1,1,0]
	v_pk_fma_f32 v[42:43], v[34:35], v[42:43], s[18:19] op_sel_hi:[1,1,0]
	v_pk_fma_f32 v[44:45], v[38:39], v[44:45], s[18:19] op_sel_hi:[1,1,0]
	v_pk_mul_f32 v[34:35], v[34:35], v[42:43]
	v_pk_mul_f32 v[38:39], v[38:39], v[44:45]
	v_pk_mul_f32 v[34:35], v[36:37], v[34:35]
	v_pk_mul_f32 v[38:39], v[40:41], v[38:39]
	v_pk_mul_f32 v[36:37], v[34:35], v[32:33]
	v_pk_fma_f32 v[34:35], v[34:35], v[32:33], v[32:33] neg_lo:[1,0,0] neg_hi:[1,0,0]
	v_cmp_gt_f32_e32 vcc, 0, v32
	v_pk_mul_f32 v[40:41], v[38:39], v[30:31]
	v_pk_fma_f32 v[38:39], v[38:39], v[30:31], v[30:31] neg_lo:[1,0,0] neg_hi:[1,0,0]
	v_cmp_gt_f32_e64 s[46:47], 0, v31
	v_cndmask_b32_e32 v32, v34, v36, vcc
	v_lshlrev_b32_e32 v36, 16, v80
	v_cmp_gt_f32_e64 s[42:43], 0, v33
	v_cndmask_b32_e64 v31, v39, v41, s[46:47]
	v_mul_f32_e32 v39, v36, v36
	v_cmp_gt_f32_e64 s[44:45], 0, v30
	v_cndmask_b32_e64 v33, v35, v37, s[42:43]
	v_lshlrev_b32_e32 v34, 16, v82
	v_lshlrev_b32_e32 v37, 16, v81
	v_mul_f32_e32 v39, 0xbf38aa3b, v39
	v_cndmask_b32_e64 v30, v38, v40, s[44:45]
	v_fma_f32 v38, |v36|, s92, 1.0
	v_exp_f32_e32 v40, v39
	v_fma_f32 v39, |v37|, s92, 1.0
	v_mul_f32_e32 v43, v34, v34
	v_lshlrev_b32_e32 v35, 16, v83
	v_rcp_f32_e32 v38, v38
	v_rcp_f32_e32 v39, v39
	v_mul_f32_e32 v43, 0xbf38aa3b, v43
	v_fma_f32 v42, |v34|, s92, 1.0
	v_exp_f32_e32 v44, v43
	v_fma_f32 v43, |v35|, s92, 1.0
	v_rcp_f32_e32 v42, v42
	v_rcp_f32_e32 v43, v43
	v_mul_f32_e32 v41, v37, v37
	v_mul_f32_e32 v41, 0xbf38aa3b, v41
	v_pk_fma_f32 v[46:47], v[38:39], s[12:13], v[18:19] op_sel_hi:[1,0,0]
	v_exp_f32_e32 v41, v41
	v_pk_fma_f32 v[46:47], v[38:39], v[46:47], s[14:15] op_sel_hi:[1,1,0]
	v_mul_f32_e32 v45, v35, v35
	v_pk_fma_f32 v[54:55], v[42:43], s[12:13], v[18:19] op_sel_hi:[1,0,0]
	v_pk_fma_f32 v[46:47], v[38:39], v[46:47], s[16:17] op_sel_hi:[1,1,0]
	v_mul_f32_e32 v45, 0xbf38aa3b, v45
	v_pk_fma_f32 v[54:55], v[42:43], v[54:55], s[14:15] op_sel_hi:[1,1,0]
	v_pk_fma_f32 v[46:47], v[38:39], v[46:47], s[18:19] op_sel_hi:[1,1,0]
	v_exp_f32_e32 v45, v45
	v_pk_fma_f32 v[54:55], v[42:43], v[54:55], s[16:17] op_sel_hi:[1,1,0]
	v_pk_mul_f32 v[38:39], v[38:39], v[46:47]
	v_pk_fma_f32 v[54:55], v[42:43], v[54:55], s[18:19] op_sel_hi:[1,1,0]
	v_pk_mul_f32 v[38:39], v[40:41], v[38:39]
	v_pk_mul_f32 v[42:43], v[42:43], v[54:55]
	v_pk_mul_f32 v[40:41], v[38:39], v[36:37]
	v_pk_fma_f32 v[38:39], v[38:39], v[36:37], v[36:37] neg_lo:[1,0,0] neg_hi:[1,0,0]
	v_cmp_gt_f32_e32 vcc, 0, v36
	v_pk_mul_f32 v[42:43], v[44:45], v[42:43]
	v_cmp_gt_f32_e64 s[42:43], 0, v37
	v_cndmask_b32_e32 v36, v38, v40, vcc
	v_pk_mul_f32 v[44:45], v[42:43], v[34:35]
	v_pk_fma_f32 v[42:43], v[42:43], v[34:35], v[34:35] neg_lo:[1,0,0] neg_hi:[1,0,0]
	v_cmp_gt_f32_e64 s[44:45], 0, v34
	v_cmp_gt_f32_e64 s[46:47], 0, v35
	v_cndmask_b32_e64 v37, v39, v41, s[42:43]
	v_mov_b32_e32 v38, v22
	v_mov_b32_e32 v39, v32
	v_mov_b32_e32 v40, v28
	v_mov_b32_e32 v41, v36
	v_cndmask_b32_e64 v35, v43, v45, s[46:47]
	v_cndmask_b32_e64 v34, v42, v44, s[44:45]
	v_pk_add_f32 v[44:45], v[38:39], v[40:41]
	v_mov_b32_e32 v38, v23
	v_mov_b32_e32 v39, v33
	v_mov_b32_e32 v40, v29
	v_mov_b32_e32 v41, v37
	v_pk_add_f32 v[42:43], v[38:39], v[40:41]
	v_mov_b32_e32 v38, v24
	v_mov_b32_e32 v39, v30
	v_mov_b32_e32 v40, v26
	v_mov_b32_e32 v41, v34
	v_pk_add_f32 v[40:41], v[38:39], v[40:41]
	v_mov_b32_e32 v38, v25
	v_mov_b32_e32 v39, v31
	v_mov_b32_e32 v46, v27
	v_mov_b32_e32 v47, v35
	v_add_f32_e32 v44, v44, v45
	v_add_f32_e32 v42, v42, v43
	v_pk_add_f32 v[38:39], v[38:39], v[46:47]
	v_add_f32_dpp v44, v44, v44 quad_perm:[1,0,3,2] row_mask:0xf bank_mask:0xf bound_ctrl:1
	v_add_f32_dpp v42, v42, v42 quad_perm:[1,0,3,2] row_mask:0xf bank_mask:0xf bound_ctrl:1
	v_add_f32_e32 v40, v40, v41
	v_add_f32_dpp v44, v44, v44 quad_perm:[2,3,0,1] row_mask:0xf bank_mask:0xf bound_ctrl:1
	v_add_f32_dpp v42, v42, v42 quad_perm:[2,3,0,1] row_mask:0xf bank_mask:0xf bound_ctrl:1
	v_add_f32_e32 v38, v38, v39
	v_add_f32_dpp v44, v44, v44 row_half_mirror row_mask:0xf bank_mask:0xf bound_ctrl:1
	v_add_f32_dpp v42, v42, v42 row_half_mirror row_mask:0xf bank_mask:0xf bound_ctrl:1
	v_add_f32_dpp v40, v40, v40 quad_perm:[1,0,3,2] row_mask:0xf bank_mask:0xf bound_ctrl:1
	v_add_f32_dpp v38, v38, v38 quad_perm:[1,0,3,2] row_mask:0xf bank_mask:0xf bound_ctrl:1
	v_add_f32_dpp v44, v44, v44 row_mirror row_mask:0xf bank_mask:0xf bound_ctrl:1
	v_add_f32_dpp v42, v42, v42 row_mirror row_mask:0xf bank_mask:0xf bound_ctrl:1
	v_add_f32_dpp v40, v40, v40 quad_perm:[2,3,0,1] row_mask:0xf bank_mask:0xf bound_ctrl:1
	v_add_f32_dpp v38, v38, v38 quad_perm:[2,3,0,1] row_mask:0xf bank_mask:0xf bound_ctrl:1
	v_add_f32_dpp v44, v44, v44 row_bcast:15 row_mask:0xa bank_mask:0xf
	v_add_f32_dpp v42, v42, v42 row_bcast:15 row_mask:0xa bank_mask:0xf
	v_add_f32_dpp v40, v40, v40 row_half_mirror row_mask:0xf bank_mask:0xf bound_ctrl:1
	v_add_f32_dpp v38, v38, v38 row_half_mirror row_mask:0xf bank_mask:0xf bound_ctrl:1
	s_nop 0
	v_add_f32_dpp v40, v40, v40 row_mirror row_mask:0xf bank_mask:0xf bound_ctrl:1
	s_nop 0
	v_add_f32_dpp v38, v38, v38 row_mirror row_mask:0xf bank_mask:0xf bound_ctrl:1
	v_add_f32_dpp v44, v44, v44 row_bcast:31 row_mask:0xc bank_mask:0xf
	v_add_f32_dpp v42, v42, v42 row_bcast:31 row_mask:0xc bank_mask:0xf
	v_add_f32_dpp v40, v40, v40 row_bcast:15 row_mask:0xa bank_mask:0xf
	v_add_f32_dpp v38, v38, v38 row_bcast:15 row_mask:0xa bank_mask:0xf
	v_readlane_b32 s6, v44, 63
	v_readlane_b32 s7, v42, 63
	v_add_f32_dpp v40, v40, v40 row_bcast:31 row_mask:0xc bank_mask:0xf
	v_add_f32_dpp v38, v38, v38 row_bcast:31 row_mask:0xc bank_mask:0xf
	s_xor_b32 s7, s7, 0x80000000
	s_xor_b32 s6, s6, 0x80000000
	v_readlane_b32 s8, v40, 63
	v_readlane_b32 s9, v38, 63
	v_pk_fma_f32 v[42:43], s[6:7], v[20:21], v[28:29] op_sel_hi:[1,0,1]
	v_pk_fma_f32 v[38:39], s[6:7], v[20:21], v[36:37] op_sel_hi:[1,0,1]
	s_xor_b32 s9, s9, 0x80000000
	s_xor_b32 s8, s8, 0x80000000
	v_pk_fma_f32 v[44:45], s[6:7], v[20:21], v[22:23] op_sel_hi:[1,0,1]
	v_pk_fma_f32 v[28:29], s[6:7], v[20:21], v[32:33] op_sel_hi:[1,0,1]
	v_mov_b32_e32 v32, v42
	v_mov_b32_e32 v33, v38
	v_pk_fma_f32 v[40:41], s[8:9], v[20:21], v[24:25] op_sel_hi:[1,0,1]
	v_pk_fma_f32 v[24:25], s[8:9], v[20:21], v[30:31] op_sel_hi:[1,0,1]
	v_mov_b32_e32 v30, v44
	v_mov_b32_e32 v31, v28
	v_pk_mul_f32 v[32:33], v[32:33], v[32:33]
	v_pk_fma_f32 v[26:27], s[8:9], v[20:21], v[26:27] op_sel_hi:[1,0,1]
	v_pk_fma_f32 v[30:31], v[30:31], v[30:31], v[32:33]
	v_mov_b32_e32 v32, v43
	v_add_f32_e32 v30, v30, v31
	v_mov_b32_e32 v33, v39
	s_nop 0
	v_add_f32_dpp v30, v30, v30 quad_perm:[1,0,3,2] row_mask:0xf bank_mask:0xf bound_ctrl:1
	v_pk_mul_f32 v[32:33], v[32:33], v[32:33]
	v_pk_fma_f32 v[22:23], s[8:9], v[20:21], v[34:35] op_sel_hi:[1,0,1]
	v_add_f32_dpp v30, v30, v30 quad_perm:[2,3,0,1] row_mask:0xf bank_mask:0xf bound_ctrl:1
	s_nop 1
	v_add_f32_dpp v30, v30, v30 row_half_mirror row_mask:0xf bank_mask:0xf bound_ctrl:1
	s_nop 1
	v_add_f32_dpp v30, v30, v30 row_mirror row_mask:0xf bank_mask:0xf bound_ctrl:1
	s_nop 1
	v_add_f32_dpp v30, v30, v30 row_bcast:15 row_mask:0xa bank_mask:0xf
	s_nop 1
	v_add_f32_dpp v30, v30, v30 row_bcast:31 row_mask:0xc bank_mask:0xf
	v_mov_b32_e32 v31, v29
	v_readlane_b32 s6, v30, 63
	s_nop 1
	v_fma_f32 v30, s6, v235, v225
	v_rsq_f32_e32 v46, v30
	v_mov_b32_e32 v30, v45
	v_pk_fma_f32 v[30:31], v[30:31], v[30:31], v[32:33]
	v_mov_b32_e32 v32, v26
	v_add_f32_e32 v30, v30, v31
	v_mov_b32_e32 v33, v22
	s_nop 0
	v_add_f32_dpp v30, v30, v30 quad_perm:[1,0,3,2] row_mask:0xf bank_mask:0xf bound_ctrl:1
	v_pk_mul_f32 v[32:33], v[32:33], v[32:33]
	s_nop 0
	v_add_f32_dpp v30, v30, v30 quad_perm:[2,3,0,1] row_mask:0xf bank_mask:0xf bound_ctrl:1
	s_nop 1
	v_add_f32_dpp v30, v30, v30 row_half_mirror row_mask:0xf bank_mask:0xf bound_ctrl:1
	s_nop 1
	v_add_f32_dpp v30, v30, v30 row_mirror row_mask:0xf bank_mask:0xf bound_ctrl:1
	s_nop 1
	v_add_f32_dpp v30, v30, v30 row_bcast:15 row_mask:0xa bank_mask:0xf
	s_nop 1
	v_add_f32_dpp v30, v30, v30 row_bcast:31 row_mask:0xc bank_mask:0xf
	v_mov_b32_e32 v31, v24
	v_readlane_b32 s6, v30, 63
	s_nop 1
	v_fma_f32 v30, s6, v235, v225
	v_rsq_f32_e32 v47, v30
	v_mov_b32_e32 v30, v40
	v_pk_fma_f32 v[30:31], v[30:31], v[30:31], v[32:33]
	v_mov_b32_e32 v32, v27
	v_add_f32_e32 v30, v30, v31
	v_mov_b32_e32 v33, v23
	s_nop 0
	v_add_f32_dpp v30, v30, v30 quad_perm:[1,0,3,2] row_mask:0xf bank_mask:0xf bound_ctrl:1
	v_pk_mul_f32 v[32:33], v[32:33], v[32:33]
	v_pk_mul_f32 v[28:29], v[28:29], v[46:47]
	v_add_f32_dpp v30, v30, v30 quad_perm:[2,3,0,1] row_mask:0xf bank_mask:0xf bound_ctrl:1
	v_pk_fma_f32 v[28:29], v[6:7], v[28:29], v[8:9] op_sel_hi:[0,1,0]
	s_nop 0
	v_add_f32_dpp v30, v30, v30 row_half_mirror row_mask:0xf bank_mask:0xf bound_ctrl:1
	s_nop 1
	v_add_f32_dpp v30, v30, v30 row_mirror row_mask:0xf bank_mask:0xf bound_ctrl:1
	s_nop 1
	v_add_f32_dpp v30, v30, v30 row_bcast:15 row_mask:0xa bank_mask:0xf
	s_nop 1
	v_add_f32_dpp v30, v30, v30 row_bcast:31 row_mask:0xc bank_mask:0xf
	v_mov_b32_e32 v31, v25
	v_readlane_b32 s6, v30, 63
	s_nop 1
	v_fma_f32 v30, s6, v235, v225
	v_rsq_f32_e32 v54, v30
	v_mov_b32_e32 v30, v41
	v_pk_fma_f32 v[30:31], v[30:31], v[30:31], v[32:33]
	v_add_f32_e32 v30, v30, v31
	s_nop 0
	s_nop 0
	v_add_f32_dpp v30, v30, v30 quad_perm:[1,0,3,2] row_mask:0xf bank_mask:0xf bound_ctrl:1
	s_nop 1
	v_add_f32_dpp v30, v30, v30 quad_perm:[2,3,0,1] row_mask:0xf bank_mask:0xf bound_ctrl:1
	s_nop 1
	v_add_f32_dpp v30, v30, v30 row_half_mirror row_mask:0xf bank_mask:0xf bound_ctrl:1
	s_nop 1
	v_add_f32_dpp v30, v30, v30 row_mirror row_mask:0xf bank_mask:0xf bound_ctrl:1
	s_nop 1
	v_add_f32_dpp v30, v30, v30 row_bcast:15 row_mask:0xa bank_mask:0xf
	s_nop 1
	v_add_f32_dpp v30, v30, v30 row_bcast:31 row_mask:0xc bank_mask:0xf
	s_nop 0
	v_readlane_b32 s6, v30, 63
	s_nop 1
	v_fma_f32 v30, s6, v235, v225
	v_rsq_f32_e32 v55, v30
	v_pk_mul_f32 v[30:31], v[44:45], v[46:47]
	v_pk_mul_f32 v[32:33], v[40:41], v[54:55]
	v_pk_mul_f32 v[26:27], v[26:27], v[54:55]
	v_pk_mul_f32 v[24:25], v[24:25], v[54:55]
	v_lshlrev_b32_e32 v40, 16, v58
	v_pk_fma_f32 v[34:35], v[14:15], v[32:33], v[16:17] op_sel_hi:[0,1,0]
	v_pk_fma_f32 v[36:37], v[14:15], v[30:31], v[16:17] op_sel_hi:[0,1,0]
	v_pk_mul_f32 v[32:33], v[42:43], v[46:47]
	v_pk_fma_f32 v[30:31], v[10:11], v[26:27], v[12:13] op_sel_hi:[0,1,0]
	v_pk_fma_f32 v[26:27], v[6:7], v[24:25], v[8:9] op_sel_hi:[0,1,0]
	v_pk_mul_f32 v[24:25], v[38:39], v[46:47]
	v_lshlrev_b32_e32 v38, 16, v60
	v_mul_f32_e32 v43, v40, v40
	v_lshlrev_b32_e32 v41, 16, v59
	v_mul_f32_e32 v43, 0xbf38aa3b, v43
	v_mul_f32_e32 v47, v38, v38
	v_lshlrev_b32_e32 v39, 16, v61
	v_fma_f32 v42, |v40|, s92, 1.0
	v_exp_f32_e32 v44, v43
	v_fma_f32 v43, |v41|, s92, 1.0
	v_mul_f32_e32 v47, 0xbf38aa3b, v47
	v_pk_mul_f32 v[22:23], v[22:23], v[54:55]
	v_rcp_f32_e32 v42, v42
	v_rcp_f32_e32 v43, v43
	v_fma_f32 v46, |v38|, s92, 1.0
	v_exp_f32_e32 v54, v47
	v_fma_f32 v47, |v39|, s92, 1.0
	v_rcp_f32_e32 v46, v46
	v_rcp_f32_e32 v47, v47
	v_mul_f32_e32 v45, v41, v41
	v_mul_f32_e32 v45, 0xbf38aa3b, v45
	v_pk_fma_f32 v[56:57], v[42:43], s[12:13], v[18:19] op_sel_hi:[1,0,0]
	v_mul_f32_e32 v55, v39, v39
	v_exp_f32_e32 v45, v45
	v_pk_fma_f32 v[58:59], v[46:47], s[12:13], v[18:19] op_sel_hi:[1,0,0]
	v_pk_fma_f32 v[56:57], v[42:43], v[56:57], s[14:15] op_sel_hi:[1,1,0]
	v_mul_f32_e32 v55, 0xbf38aa3b, v55
	v_pk_fma_f32 v[58:59], v[46:47], v[58:59], s[14:15] op_sel_hi:[1,1,0]
	v_pk_fma_f32 v[56:57], v[42:43], v[56:57], s[16:17] op_sel_hi:[1,1,0]
	v_exp_f32_e32 v55, v55
	v_pk_fma_f32 v[58:59], v[46:47], v[58:59], s[16:17] op_sel_hi:[1,1,0]
	v_pk_fma_f32 v[56:57], v[42:43], v[56:57], s[18:19] op_sel_hi:[1,1,0]
	v_pk_fma_f32 v[58:59], v[46:47], v[58:59], s[18:19] op_sel_hi:[1,1,0]
	v_pk_mul_f32 v[42:43], v[42:43], v[56:57]
	v_pk_mul_f32 v[46:47], v[46:47], v[58:59]
	v_pk_mul_f32 v[42:43], v[44:45], v[42:43]
	v_pk_mul_f32 v[46:47], v[54:55], v[46:47]
	v_pk_mul_f32 v[44:45], v[42:43], v[40:41]
	v_pk_fma_f32 v[42:43], v[42:43], v[40:41], v[40:41] neg_lo:[1,0,0] neg_hi:[1,0,0]
	v_cmp_gt_f32_e32 vcc, 0, v40
	v_pk_mul_f32 v[54:55], v[46:47], v[38:39]
	v_pk_fma_f32 v[46:47], v[46:47], v[38:39], v[38:39] neg_lo:[1,0,0] neg_hi:[1,0,0]
	v_cmp_gt_f32_e64 s[44:45], 0, v38
	v_cmp_gt_f32_e64 s[46:47], 0, v39
	v_cndmask_b32_e32 v38, v42, v44, vcc
	v_lshlrev_b32_e32 v44, 16, v50
	v_cmp_gt_f32_e64 s[42:43], 0, v41
	v_cndmask_b32_e64 v41, v47, v55, s[46:47]
	v_mul_f32_e32 v47, v44, v44
	v_cndmask_b32_e64 v39, v43, v45, s[42:43]
	v_lshlrev_b32_e32 v45, 16, v51
	v_mul_f32_e32 v47, 0xbf38aa3b, v47
	v_cndmask_b32_e64 v40, v46, v54, s[44:45]
	v_fma_f32 v46, |v44|, s92, 1.0
	v_exp_f32_e32 v50, v47
	v_fma_f32 v47, |v45|, s92, 1.0
	v_lshlrev_b32_e32 v42, 16, v52
	v_rcp_f32_e32 v46, v46
	v_rcp_f32_e32 v47, v47
	v_lshlrev_b32_e32 v43, 16, v53
	v_mul_f32_e32 v53, v42, v42
	v_mul_f32_e32 v53, 0xbf38aa3b, v53
	v_mul_f32_e32 v51, v45, v45
	v_fma_f32 v52, |v42|, s92, 1.0
	v_exp_f32_e32 v54, v53
	v_fma_f32 v53, |v43|, s92, 1.0
	v_mul_f32_e32 v51, 0xbf38aa3b, v51
	v_rcp_f32_e32 v52, v52
	v_rcp_f32_e32 v53, v53
	v_pk_fma_f32 v[56:57], v[46:47], s[12:13], v[18:19] op_sel_hi:[1,0,0]
	v_exp_f32_e32 v51, v51
	v_pk_fma_f32 v[56:57], v[46:47], v[56:57], s[14:15] op_sel_hi:[1,1,0]
	v_mul_f32_e32 v55, v43, v43
	v_pk_fma_f32 v[56:57], v[46:47], v[56:57], s[16:17] op_sel_hi:[1,1,0]
	v_pk_fma_f32 v[58:59], v[52:53], s[12:13], v[18:19] op_sel_hi:[1,0,0]
	v_pk_fma_f32 v[56:57], v[46:47], v[56:57], s[18:19] op_sel_hi:[1,1,0]
	v_mul_f32_e32 v55, 0xbf38aa3b, v55
	v_pk_mul_f32 v[46:47], v[46:47], v[56:57]
	v_pk_fma_f32 v[58:59], v[52:53], v[58:59], s[14:15] op_sel_hi:[1,1,0]
	v_exp_f32_e32 v55, v55
	v_pk_mul_f32 v[46:47], v[50:51], v[46:47]
	v_pk_fma_f32 v[58:59], v[52:53], v[58:59], s[16:17] op_sel_hi:[1,1,0]
	v_pk_mul_f32 v[50:51], v[46:47], v[44:45]
	v_pk_fma_f32 v[46:47], v[46:47], v[44:45], v[44:45] neg_lo:[1,0,0] neg_hi:[1,0,0]
	v_cmp_gt_f32_e32 vcc, 0, v44
	v_pk_fma_f32 v[58:59], v[52:53], v[58:59], s[18:19] op_sel_hi:[1,1,0]
	v_cmp_gt_f32_e64 s[42:43], 0, v45
	v_cndmask_b32_e32 v44, v46, v50, vcc
	v_lshlrev_b32_e32 v46, 16, v48
	v_lshlrev_b32_e32 v48, 16, v15
	v_pk_mul_f32 v[52:53], v[52:53], v[58:59]
	v_fma_f32 v15, |v48|, s92, 1.0
	v_pk_mul_f32 v[52:53], v[54:55], v[52:53]
	v_rcp_f32_e32 v50, v15
	v_mul_f32_e32 v15, v48, v48
	v_pk_mul_f32 v[54:55], v[52:53], v[42:43]
	v_pk_fma_f32 v[52:53], v[52:53], v[42:43], v[42:43] neg_lo:[1,0,0] neg_hi:[1,0,0]
	v_cmp_gt_f32_e64 s[44:45], 0, v42
	v_cndmask_b32_e64 v45, v47, v51, s[42:43]
	v_lshlrev_b32_e32 v47, 16, v49
	v_lshlrev_b32_e32 v49, 16, v17
	v_mul_f32_e32 v15, 0xbf38aa3b, v15
	v_cndmask_b32_e64 v42, v52, v54, s[44:45]
	v_exp_f32_e32 v52, v15
	v_fma_f32 v15, |v49|, s92, 1.0
	v_rcp_f32_e32 v51, v15
	v_mul_f32_e32 v15, v49, v49
	v_cmp_gt_f32_e64 s[46:47], 0, v43
	v_mul_f32_e32 v15, 0xbf38aa3b, v15
	v_pk_fma_f32 v[58:59], v[50:51], s[12:13], v[18:19] op_sel_hi:[1,0,0]
	v_cndmask_b32_e64 v43, v53, v55, s[46:47]
	v_exp_f32_e32 v53, v15
	v_fma_f32 v15, |v46|, s92, 1.0
	v_rcp_f32_e32 v54, v15
	v_mul_f32_e32 v15, v46, v46
	v_mul_f32_e32 v15, 0xbf38aa3b, v15
	v_exp_f32_e32 v56, v15
	v_fma_f32 v15, |v47|, s92, 1.0
	v_rcp_f32_e32 v55, v15
	v_pk_fma_f32 v[58:59], v[50:51], v[58:59], s[14:15] op_sel_hi:[1,1,0]
	v_mul_f32_e32 v15, v47, v47
	v_pk_fma_f32 v[58:59], v[50:51], v[58:59], s[16:17] op_sel_hi:[1,1,0]
	v_pk_fma_f32 v[60:61], v[54:55], s[12:13], v[18:19] op_sel_hi:[1,0,0]
	v_mul_f32_e32 v15, 0xbf38aa3b, v15
	v_pk_fma_f32 v[60:61], v[54:55], v[60:61], s[14:15] op_sel_hi:[1,1,0]
	v_pk_fma_f32 v[58:59], v[50:51], v[58:59], s[18:19] op_sel_hi:[1,1,0]
	v_exp_f32_e32 v57, v15
	v_pk_fma_f32 v[60:61], v[54:55], v[60:61], s[16:17] op_sel_hi:[1,1,0]
	v_pk_mul_f32 v[50:51], v[50:51], v[58:59]
	v_pk_fma_f32 v[60:61], v[54:55], v[60:61], s[18:19] op_sel_hi:[1,1,0]
	v_pk_mul_f32 v[50:51], v[52:53], v[50:51]
	v_pk_mul_f32 v[54:55], v[54:55], v[60:61]
	v_pk_mul_f32 v[52:53], v[50:51], v[48:49]
	v_pk_fma_f32 v[50:51], v[50:51], v[48:49], v[48:49] neg_lo:[1,0,0] neg_hi:[1,0,0]
	v_cmp_gt_f32_e32 vcc, 0, v48
	v_pk_mul_f32 v[54:55], v[56:57], v[54:55]
	v_cmp_gt_f32_e64 s[42:43], 0, v49
	v_cndmask_b32_e32 v48, v50, v52, vcc
	v_lshlrev_b32_e32 v52, 16, v9
	v_pk_mul_f32 v[56:57], v[54:55], v[46:47]
	v_pk_fma_f32 v[54:55], v[54:55], v[46:47], v[46:47] neg_lo:[1,0,0] neg_hi:[1,0,0]
	v_cmp_gt_f32_e64 s[44:45], 0, v46
	v_cndmask_b32_e64 v49, v51, v53, s[42:43]
	v_lshlrev_b32_e32 v51, 16, v7
	v_fma_f32 v7, |v52|, s92, 1.0
	v_cndmask_b32_e64 v46, v54, v56, s[44:45]
	v_rcp_f32_e32 v54, v7
	v_mul_f32_e32 v7, v52, v52
	v_lshlrev_b32_e32 v53, 16, v11
	v_mul_f32_e32 v7, 0xbf38aa3b, v7
	v_cmp_gt_f32_e64 s[46:47], 0, v47
	v_exp_f32_e32 v56, v7
	v_fma_f32 v7, |v53|, s92, 1.0
	v_cndmask_b32_e64 v47, v55, v57, s[46:47]
	v_rcp_f32_e32 v55, v7
	v_mul_f32_e32 v7, v53, v53
	v_lshlrev_b32_e32 v50, 16, v13
	v_mul_f32_e32 v7, 0xbf38aa3b, v7
	v_exp_f32_e32 v57, v7
	v_fma_f32 v7, |v50|, s92, 1.0
	v_rcp_f32_e32 v58, v7
	v_mul_f32_e32 v7, v50, v50
	v_mul_f32_e32 v7, 0xbf38aa3b, v7
	v_exp_f32_e32 v60, v7
	v_fma_f32 v7, |v51|, s92, 1.0
	v_rcp_f32_e32 v59, v7
	v_pk_fma_f32 v[62:63], v[54:55], s[12:13], v[18:19] op_sel_hi:[1,0,0]
	v_mul_f32_e32 v7, v51, v51
	v_pk_fma_f32 v[62:63], v[54:55], v[62:63], s[14:15] op_sel_hi:[1,1,0]
	v_pk_fma_f32 v[18:19], v[58:59], s[12:13], v[18:19] op_sel_hi:[1,0,0]
	v_mul_f32_e32 v7, 0xbf38aa3b, v7
	v_pk_fma_f32 v[18:19], v[58:59], v[18:19], s[14:15] op_sel_hi:[1,1,0]
	v_pk_fma_f32 v[62:63], v[54:55], v[62:63], s[16:17] op_sel_hi:[1,1,0]
	v_exp_f32_e32 v61, v7
	v_pk_fma_f32 v[18:19], v[58:59], v[18:19], s[16:17] op_sel_hi:[1,1,0]
	v_pk_fma_f32 v[62:63], v[54:55], v[62:63], s[18:19] op_sel_hi:[1,1,0]
	v_pk_fma_f32 v[18:19], v[58:59], v[18:19], s[18:19] op_sel_hi:[1,1,0]
	v_pk_mul_f32 v[54:55], v[54:55], v[62:63]
	v_pk_mul_f32 v[18:19], v[58:59], v[18:19]
	v_pk_mul_f32 v[54:55], v[56:57], v[54:55]
	v_pk_mul_f32 v[18:19], v[60:61], v[18:19]
	v_pk_mul_f32 v[56:57], v[54:55], v[52:53]
	v_pk_fma_f32 v[54:55], v[54:55], v[52:53], v[52:53] neg_lo:[1,0,0] neg_hi:[1,0,0]
	v_cmp_gt_f32_e32 vcc, 0, v52
	v_pk_mul_f32 v[58:59], v[18:19], v[50:51]
	v_pk_fma_f32 v[18:19], v[18:19], v[50:51], v[50:51] neg_lo:[1,0,0] neg_hi:[1,0,0]
	v_cmp_gt_f32_e64 s[42:43], 0, v53
	v_cmp_gt_f32_e64 s[44:45], 0, v50
	v_cndmask_b32_e32 v50, v54, v56, vcc
	v_cmp_gt_f32_e64 s[46:47], 0, v51
	v_cndmask_b32_e64 v51, v55, v57, s[42:43]
	v_mov_b32_e32 v52, v38
	v_mov_b32_e32 v53, v48
	v_mov_b32_e32 v54, v44
	v_mov_b32_e32 v55, v50
	v_cndmask_b32_e64 v19, v19, v59, s[46:47]
	v_cndmask_b32_e64 v18, v18, v58, s[44:45]
	v_pk_add_f32 v[58:59], v[52:53], v[54:55]
	v_mov_b32_e32 v9, v131
	v_add_f32_e32 v7, v58, v59
	v_mov_b32_e32 v52, v39
	v_mov_b32_e32 v53, v49
	v_add_f32_dpp v7, v7, v7 quad_perm:[1,0,3,2] row_mask:0xf bank_mask:0xf bound_ctrl:1
	v_mov_b32_e32 v54, v45
	v_mov_b32_e32 v55, v51
	v_add_f32_dpp v7, v7, v7 quad_perm:[2,3,0,1] row_mask:0xf bank_mask:0xf bound_ctrl:1
	v_pk_add_f32 v[56:57], v[52:53], v[54:55]
	v_mov_b32_e32 v52, v40
	v_add_f32_dpp v7, v7, v7 row_half_mirror row_mask:0xf bank_mask:0xf bound_ctrl:1
	v_mov_b32_e32 v53, v46
	v_mov_b32_e32 v54, v42
	v_add_f32_dpp v7, v7, v7 row_mirror row_mask:0xf bank_mask:0xf bound_ctrl:1
	v_mov_b32_e32 v55, v18
	v_pk_add_f32 v[54:55], v[52:53], v[54:55]
	v_mov_b32_dpp v9, v7 row_bcast:15 row_mask:0xa bank_mask:0xf
	v_add_f32_e32 v7, v7, v9
	v_mov_b32_e32 v52, v41
	v_mov_b32_e32 v53, v47
	v_add_f32_dpp v7, v7, v7 row_bcast:31 row_mask:0xc bank_mask:0xf
	v_mov_b32_e32 v9, v131
	v_readlane_b32 s6, v7, 63
	v_add_f32_e32 v7, v56, v57
	v_mov_b32_e32 v60, v43
	v_mov_b32_e32 v61, v19
	v_add_f32_dpp v7, v7, v7 quad_perm:[1,0,3,2] row_mask:0xf bank_mask:0xf bound_ctrl:1
	v_pk_add_f32 v[52:53], v[52:53], v[60:61]
	s_xor_b32 s6, s6, 0x80000000
	v_add_f32_dpp v7, v7, v7 quad_perm:[2,3,0,1] row_mask:0xf bank_mask:0xf bound_ctrl:1
	v_pk_fma_f32 v[32:33], v[10:11], v[32:33], v[12:13] op_sel_hi:[0,1,0]
	v_pk_fma_f32 v[22:23], v[2:3], v[22:23], v[4:5] op_sel_hi:[0,1,0]
	v_add_f32_dpp v7, v7, v7 row_half_mirror row_mask:0xf bank_mask:0xf bound_ctrl:1
	v_pk_fma_f32 v[24:25], v[2:3], v[24:25], v[4:5] op_sel_hi:[0,1,0]
	s_movk_i32 s42, 0x110
	v_add_f32_dpp v7, v7, v7 row_mirror row_mask:0xf bank_mask:0xf bound_ctrl:1
	s_mov_b32 s44, 0xbf3a00e3
	s_nop 0
	v_mov_b32_dpp v9, v7 row_bcast:15 row_mask:0xa bank_mask:0xf
	v_add_f32_e32 v7, v7, v9
	s_nop 1
	v_add_f32_dpp v7, v7, v7 row_bcast:31 row_mask:0xc bank_mask:0xf
	s_nop 0
	v_readlane_b32 s7, v7, 63
	v_add_f32_e32 v7, v54, v55
	s_xor_b32 s7, s7, 0x80000000
	v_pk_fma_f32 v[54:55], s[6:7], v[20:21], v[38:39] op_sel_hi:[1,0,1]
	v_add_f32_dpp v7, v7, v7 quad_perm:[1,0,3,2] row_mask:0xf bank_mask:0xf bound_ctrl:1
	v_pk_fma_f32 v[44:45], s[6:7], v[20:21], v[44:45] op_sel_hi:[1,0,1]
	s_nop 0
	v_add_f32_dpp v7, v7, v7 quad_perm:[2,3,0,1] row_mask:0xf bank_mask:0xf bound_ctrl:1
	s_nop 1
	v_add_f32_dpp v7, v7, v7 row_half_mirror row_mask:0xf bank_mask:0xf bound_ctrl:1
	s_nop 1
	v_add_f32_dpp v7, v7, v7 row_mirror row_mask:0xf bank_mask:0xf bound_ctrl:1
	s_nop 1
	v_add_f32_dpp v7, v7, v7 row_bcast:15 row_mask:0xa bank_mask:0xf
	s_nop 1
	v_add_f32_dpp v7, v7, v7 row_bcast:31 row_mask:0xc bank_mask:0xf
	s_nop 0
	v_readlane_b32 s8, v7, 63
	v_add_f32_e32 v7, v52, v53
	s_xor_b32 s8, s8, 0x80000000
	s_nop 0
	v_add_f32_dpp v7, v7, v7 quad_perm:[1,0,3,2] row_mask:0xf bank_mask:0xf bound_ctrl:1
	s_nop 1
	v_add_f32_dpp v7, v7, v7 quad_perm:[2,3,0,1] row_mask:0xf bank_mask:0xf bound_ctrl:1
	s_nop 1
	v_add_f32_dpp v7, v7, v7 row_half_mirror row_mask:0xf bank_mask:0xf bound_ctrl:1
	s_nop 1
	v_add_f32_dpp v7, v7, v7 row_mirror row_mask:0xf bank_mask:0xf bound_ctrl:1
	s_nop 1
	v_add_f32_dpp v7, v7, v7 row_bcast:15 row_mask:0xa bank_mask:0xf
	s_nop 1
	v_add_f32_dpp v7, v7, v7 row_bcast:31 row_mask:0xc bank_mask:0xf
	v_mov_b32_e32 v9, v131
	v_readlane_b32 s9, v7, 63
	s_xor_b32 s9, s9, 0x80000000
	s_nop 0
	v_pk_fma_f32 v[52:53], s[8:9], v[20:21], v[40:41] op_sel_hi:[1,0,1]
	v_pk_fma_f32 v[42:43], s[8:9], v[20:21], v[42:43] op_sel_hi:[1,0,1]
	v_pk_fma_f32 v[38:39], s[8:9], v[20:21], v[46:47] op_sel_hi:[1,0,1]
	v_pk_fma_f32 v[40:41], s[6:7], v[20:21], v[48:49] op_sel_hi:[1,0,1]
	v_pk_fma_f32 v[18:19], s[8:9], v[20:21], v[18:19] op_sel_hi:[1,0,1]
	v_pk_fma_f32 v[20:21], s[6:7], v[20:21], v[50:51] op_sel_hi:[1,0,1]
	v_mov_b32_e32 v48, v44
	v_mov_b32_e32 v49, v20
	v_mov_b32_e32 v46, v54
	v_mov_b32_e32 v47, v40
	v_pk_mul_f32 v[48:49], v[48:49], v[48:49]
	v_mov_b32_e32 v50, v45
	v_pk_fma_f32 v[46:47], v[46:47], v[46:47], v[48:49]
	v_mov_b32_e32 v51, v21
	v_add_f32_e32 v7, v46, v47
	v_mov_b32_e32 v48, v55
	v_mov_b32_e32 v49, v41
	v_add_f32_dpp v7, v7, v7 quad_perm:[1,0,3,2] row_mask:0xf bank_mask:0xf bound_ctrl:1
	v_pk_mul_f32 v[50:51], v[50:51], v[50:51]
	v_mov_b32_e32 v56, v43
	v_add_f32_dpp v7, v7, v7 quad_perm:[2,3,0,1] row_mask:0xf bank_mask:0xf bound_ctrl:1
	v_pk_fma_f32 v[48:49], v[48:49], v[48:49], v[50:51]
	v_mov_b32_e32 v50, v42
	v_add_f32_dpp v7, v7, v7 row_half_mirror row_mask:0xf bank_mask:0xf bound_ctrl:1
	v_mov_b32_e32 v51, v18
	v_pk_mul_f32 v[50:51], v[50:51], v[50:51]
	v_add_f32_dpp v7, v7, v7 row_mirror row_mask:0xf bank_mask:0xf bound_ctrl:1
	v_mov_b32_e32 v57, v19
	v_pk_mul_f32 v[56:57], v[56:57], v[56:57]
	v_mov_b32_dpp v9, v7 row_bcast:15 row_mask:0xa bank_mask:0xf
	v_add_f32_e32 v7, v7, v9
	v_readlane_b32 s9, v254, 29
	s_movk_i32 s8, 0x2000
	v_add_f32_dpp v7, v7, v7 row_bcast:31 row_mask:0xc bank_mask:0xf
	v_mov_b32_e32 v9, v131
	v_readlane_b32 s6, v7, 63
	s_nop 1
	v_fma_f32 v7, s6, v235, v225
	v_rsq_f32_e32 v46, v7
	v_add_f32_e32 v7, v48, v49
	v_mov_b32_e32 v48, v52
	v_mov_b32_e32 v49, v38
	v_add_f32_dpp v7, v7, v7 quad_perm:[1,0,3,2] row_mask:0xf bank_mask:0xf bound_ctrl:1
	v_pk_fma_f32 v[48:49], v[48:49], v[48:49], v[50:51]
	v_mov_b32_e32 v50, v53
	v_add_f32_dpp v7, v7, v7 quad_perm:[2,3,0,1] row_mask:0xf bank_mask:0xf bound_ctrl:1
	v_mov_b32_e32 v51, v39
	v_pk_fma_f32 v[50:51], v[50:51], v[50:51], v[56:57]
	v_add_f32_dpp v7, v7, v7 row_half_mirror row_mask:0xf bank_mask:0xf bound_ctrl:1
	s_nop 1
	v_add_f32_dpp v7, v7, v7 row_mirror row_mask:0xf bank_mask:0xf bound_ctrl:1
	s_nop 1
	v_mov_b32_dpp v9, v7 row_bcast:15 row_mask:0xa bank_mask:0xf
	v_add_f32_e32 v7, v7, v9
	s_nop 1
	v_add_f32_dpp v7, v7, v7 row_bcast:31 row_mask:0xc bank_mask:0xf
	s_nop 0
	v_readlane_b32 s6, v7, 63
	s_nop 1
	v_fma_f32 v7, s6, v235, v225
	v_rsq_f32_e32 v47, v7
	v_add_f32_e32 v7, v48, v49
	s_nop 1
	v_add_f32_dpp v7, v7, v7 quad_perm:[1,0,3,2] row_mask:0xf bank_mask:0xf bound_ctrl:1
	s_nop 1
	v_add_f32_dpp v7, v7, v7 quad_perm:[2,3,0,1] row_mask:0xf bank_mask:0xf bound_ctrl:1
	s_nop 1
	v_add_f32_dpp v7, v7, v7 row_half_mirror row_mask:0xf bank_mask:0xf bound_ctrl:1
	s_nop 1
	v_add_f32_dpp v7, v7, v7 row_mirror row_mask:0xf bank_mask:0xf bound_ctrl:1
	s_nop 1
	v_add_f32_dpp v7, v7, v7 row_bcast:15 row_mask:0xa bank_mask:0xf
	s_nop 1
	v_add_f32_dpp v7, v7, v7 row_bcast:31 row_mask:0xc bank_mask:0xf
	v_mov_b32_e32 v9, v131
	v_readlane_b32 s6, v7, 63
	s_nop 1
	v_fma_f32 v7, s6, v235, v225
	v_rsq_f32_e32 v48, v7
	v_add_f32_e32 v7, v50, v51
	v_pk_mul_f32 v[50:51], v[54:55], v[46:47]
	s_nop 0
	v_add_f32_dpp v7, v7, v7 quad_perm:[1,0,3,2] row_mask:0xf bank_mask:0xf bound_ctrl:1
	s_nop 1
	v_add_f32_dpp v7, v7, v7 quad_perm:[2,3,0,1] row_mask:0xf bank_mask:0xf bound_ctrl:1
	s_nop 1
	v_add_f32_dpp v7, v7, v7 row_half_mirror row_mask:0xf bank_mask:0xf bound_ctrl:1
	s_nop 1
	v_add_f32_dpp v7, v7, v7 row_mirror row_mask:0xf bank_mask:0xf bound_ctrl:1
	s_nop 1
	v_mov_b32_dpp v9, v7 row_bcast:15 row_mask:0xa bank_mask:0xf
	v_add_f32_e32 v7, v7, v9
	v_mov_b32_e32 v9, v131
	s_nop 1
	v_mov_b32_dpp v9, v7 row_bcast:31 row_mask:0xc bank_mask:0xf
	v_add_f32_e32 v7, v7, v9
	s_nop 0
	v_readlane_b32 s6, v7, 63
	s_nop 1
	v_fma_f32 v7, s6, v235, v225
	v_rsq_f32_e32 v49, v7
	s_add_i32 s6, s5, s15
	s_mul_hi_i32 s7, s6, 0x5000
	s_mulk_i32 s6, 0x5000
	v_pk_mul_f32 v[52:53], v[52:53], v[48:49]
	s_lshl_b32 s5, s5, 9
	v_pk_fma_f32 v[52:53], v[14:15], v[52:53], v[16:17] op_sel_hi:[0,1,0]
	v_pk_fma_f32 v[14:15], v[14:15], v[50:51], v[16:17] op_sel_hi:[0,1,0]
	v_cvt_pk_bf16_f32 v17, v52, v53
	v_cvt_pk_bf16_f32 v16, v14, v15
	v_cvt_pk_bf16_f32 v15, v34, v35
	v_cvt_pk_bf16_f32 v14, v36, v37
	ds_write_b128 v5, v[14:17] offset:16
	v_pk_mul_f32 v[14:15], v[44:45], v[46:47]
	v_pk_mul_f32 v[16:17], v[42:43], v[48:49]
	s_add_u32 s28, s9, s6
	v_pk_fma_f32 v[16:17], v[10:11], v[16:17], v[12:13] op_sel_hi:[0,1,0]
	v_pk_fma_f32 v[10:11], v[10:11], v[14:15], v[12:13] op_sel_hi:[0,1,0]
	v_cvt_pk_bf16_f32 v13, v16, v17
	v_cvt_pk_bf16_f32 v12, v10, v11
	v_cvt_pk_bf16_f32 v11, v30, v31
	v_cvt_pk_bf16_f32 v10, v32, v33
	ds_write_b128 v5, v[10:13] offset:17424
	v_pk_mul_f32 v[10:11], v[40:41], v[46:47]
	v_pk_mul_f32 v[12:13], v[38:39], v[48:49]
	v_readlane_b32 s6, v254, 31
	v_pk_fma_f32 v[12:13], v[6:7], v[12:13], v[8:9] op_sel_hi:[0,1,0]
	v_pk_fma_f32 v[6:7], v[6:7], v[10:11], v[8:9] op_sel_hi:[0,1,0]
	v_cvt_pk_bf16_f32 v9, v12, v13
	v_cvt_pk_bf16_f32 v8, v6, v7
	v_cvt_pk_bf16_f32 v7, v26, v27
	v_cvt_pk_bf16_f32 v6, v28, v29
	ds_write_b128 v5, v[6:9] offset:34832
	v_pk_mul_f32 v[6:7], v[20:21], v[46:47]
	v_pk_mul_f32 v[8:9], v[18:19], v[48:49]
	v_pk_fma_f32 v[6:7], v[2:3], v[6:7], v[4:5] op_sel_hi:[0,1,0]
	v_pk_fma_f32 v[8:9], v[2:3], v[8:9], v[4:5] op_sel_hi:[0,1,0]
	v_bfe_u32 v4, v3, 5, 1
	v_and_or_b32 v2, v3, 31, s34
	v_mul_lo_u32 v3, v2, s42
	v_lshlrev_b32_e32 v164, 4, v4
	v_cvt_pk_bf16_f32 v9, v8, v9
	v_cvt_pk_bf16_f32 v8, v6, v7
	v_cvt_pk_bf16_f32 v7, v22, v23
	v_cvt_pk_bf16_f32 v6, v24, v25
	v_add3_u32 v3, 0, v3, v164
	ds_write_b128 v5, v[6:9] offset:52240
	s_waitcnt lgkmcnt(0)
	s_barrier
	ds_read_b128 v[18:21], v3
	ds_read_b128 v[22:25], v3 offset:32
	ds_read_b128 v[26:29], v3 offset:64
	ds_read_b128 v[30:33], v3 offset:96
	ds_read_b128 v[34:37], v3 offset:128
	ds_read_b128 v[38:41], v3 offset:160
	ds_read_b128 v[42:45], v3 offset:192
	ds_read_b128 v[46:49], v3 offset:224
	s_addc_u32 s29, s6, s7
	v_ashrrev_i32_e32 v3, 31, v2
	v_lshl_add_u32 v94, v4, 2, s17
	v_lshlrev_b64 v[106:107], 1, v[2:3]
	global_load_dwordx4 v[2:5], v130, s[28:29]
	global_load_dwordx4 v[50:53], v130, s[28:29] offset:1024
	v_lshl_add_u64 v[90:91], s[28:29], 0, v[130:131]
	v_add_co_u32_e32 v54, vcc, s90, v90
	v_lshl_add_u64 v[92:93], s[80:81], 0, v[106:107]
	s_nop 0
	v_addc_co_u32_e32 v55, vcc, 0, v91, vcc
	v_add_u32_e32 v72, 15, v94
	v_add_u32_e32 v68, 16, v94
	v_add_u32_e32 v66, 17, v94
	v_add_u32_e32 v64, 18, v94
	v_add_u32_e32 v158, 33, v94
	v_add_u32_e32 v156, 34, v94
	v_add_u32_e32 v154, 39, v94
	v_add_u32_e32 v152, 40, v94
	v_add_u32_e32 v150, 41, v94
	v_add_co_u32_e32 v70, vcc, s8, v90
	v_add_u32_e32 v120, -1, v94
	v_add_u32_e32 v118, 1, v94
	v_add_u32_e32 v116, 2, v94
	v_add_u32_e32 v114, 7, v94
	v_add_u32_e32 v112, 8, v94
	v_add_u32_e32 v110, 9, v94
	v_add_u32_e32 v108, 10, v94
	v_mad_i64_i32 v[126:127], s[6:7], v72, s87, v[92:93]
	v_mad_i64_i32 v[128:129], s[6:7], v68, s87, v[92:93]
	v_mad_i64_i32 v[132:133], s[6:7], v66, s87, v[92:93]
	v_mad_i64_i32 v[134:135], s[6:7], v64, s87, v[92:93]
	v_add_u32_e32 v62, 23, v94
	v_add_u32_e32 v60, 24, v94
	v_add_u32_e32 v58, 25, v94
	v_add_u32_e32 v56, 26, v94
	v_add_u32_e32 v162, 31, v94
	v_add_u32_e32 v160, 32, v94
	v_mad_i64_i32 v[172:173], s[6:7], v158, s87, v[92:93]
	v_mad_i64_i32 v[174:175], s[6:7], v156, s87, v[92:93]
	v_mad_i64_i32 v[176:177], s[6:7], v154, s87, v[92:93]
	v_mad_i64_i32 v[178:179], s[6:7], v152, s87, v[92:93]
	v_mad_i64_i32 v[180:181], s[6:7], v150, s87, v[92:93]
	v_add_u32_e32 v148, 42, v94
	v_add_u32_e32 v146, 47, v94
	v_add_u32_e32 v144, 48, v94
	v_add_u32_e32 v142, 49, v94
	v_add_u32_e32 v104, 50, v94
	v_add_u32_e32 v102, 55, v94
	v_add_u32_e32 v100, 56, v94
	v_add_u32_e32 v98, 57, v94
	v_add_u32_e32 v96, 58, v94
	v_addc_co_u32_e32 v71, vcc, 0, v91, vcc
	v_mad_i64_i32 v[6:7], s[6:7], v120, s87, v[92:93]
	v_mad_i64_i32 v[8:9], s[6:7], v94, s87, v[92:93]
	v_mad_i64_i32 v[10:11], s[6:7], v118, s87, v[92:93]
	v_mad_i64_i32 v[12:13], s[6:7], v116, s87, v[92:93]
	v_mad_i64_i32 v[14:15], s[6:7], v114, s87, v[92:93]
	v_mad_i64_i32 v[16:17], s[6:7], v112, s87, v[92:93]
	v_mad_i64_i32 v[122:123], s[6:7], v110, s87, v[92:93]
	v_mad_i64_i32 v[124:125], s[6:7], v108, s87, v[92:93]
	v_mad_i64_i32 v[136:137], s[6:7], v62, s87, v[92:93]
	v_mad_i64_i32 v[138:139], s[6:7], v60, s87, v[92:93]
	v_mad_i64_i32 v[140:141], s[6:7], v58, s87, v[92:93]
	v_mad_i64_i32 v[166:167], s[6:7], v56, s87, v[92:93]
	v_mad_i64_i32 v[168:169], s[6:7], v162, s87, v[92:93]
	v_mad_i64_i32 v[170:171], s[6:7], v160, s87, v[92:93]
	v_mad_i64_i32 v[188:189], s[6:7], v148, s87, v[92:93]
	v_mad_i64_i32 v[190:191], s[6:7], v146, s87, v[92:93]
	v_mad_i64_i32 v[192:193], s[6:7], v144, s87, v[92:93]
	v_mad_i64_i32 v[194:195], s[6:7], v142, s87, v[92:93]
	v_mad_i64_i32 v[196:197], s[6:7], v104, s87, v[92:93]
	v_mad_i64_i32 v[198:199], s[6:7], v102, s87, v[92:93]
	v_mad_i64_i32 v[200:201], s[6:7], v100, s87, v[92:93]
	v_mad_i64_i32 v[202:203], s[6:7], v98, s87, v[92:93]
	v_mad_i64_i32 v[204:205], s[6:7], v96, s87, v[92:93]
	global_load_dwordx4 v[74:77], v130, s[28:29] offset:2048
	global_load_dwordx4 v[78:81], v130, s[28:29] offset:3072
	global_load_dwordx4 v[82:85], v[70:71], off offset:-4096
	global_load_dwordx4 v[86:89], v[54:55], off offset:1024
	global_load_ushort v1, v[6:7], off
	s_nop 0
	global_load_ushort v130, v[8:9], off
	global_load_ushort v165, v[10:11], off
	global_load_ushort v206, v[12:13], off
	global_load_ushort v207, v[14:15], off
	global_load_ushort v208, v[16:17], off
	global_load_ushort v209, v[122:123], off
	global_load_ushort v210, v[124:125], off
	s_nop 0
	global_load_ushort v126, v[126:127], off
	s_nop 0
	global_load_ushort v127, v[128:129], off
	s_nop 0
	global_load_ushort v128, v[132:133], off
	global_load_ushort v129, v[134:135], off
	s_nop 0
	global_load_ushort v132, v[136:137], off
	global_load_ushort v133, v[138:139], off
	global_load_ushort v134, v[140:141], off
	global_load_ushort v135, v[166:167], off
	global_load_ushort v187, v[168:169], off
	global_load_ushort v186, v[170:171], off
	global_load_ushort v185, v[172:173], off
	global_load_ushort v184, v[174:175], off
	global_load_ushort v183, v[176:177], off
	global_load_ushort v182, v[178:179], off
	s_nop 0
	global_load_ushort v181, v[180:181], off
	s_nop 0
	global_load_ushort v180, v[188:189], off
	global_load_ushort v179, v[190:191], off
	global_load_ushort v178, v[192:193], off
	global_load_ushort v177, v[194:195], off
	global_load_ushort v176, v[196:197], off
	global_load_ushort v175, v[198:199], off
	global_load_ushort v174, v[200:201], off
	global_load_ushort v173, v[202:203], off
	global_load_ushort v172, v[204:205], off
	s_waitcnt vmcnt(37) lgkmcnt(7)
	v_mfma_f32_32x32x16_bf16 v[2:17], v[2:5], v[18:21], 0
	s_add_i32 s5, s40, s5
	v_ashrrev_i32_e32 v121, 31, v120
	v_lshl_add_u64 v[106:107], s[76:77], 0, v[106:107]
	v_lshlrev_b64 v[120:121], 11, v[120:121]
	v_lshl_add_u64 v[120:121], v[106:107], 0, v[120:121]
	v_ashrrev_i32_e32 v95, 31, v94
	s_waitcnt vmcnt(36) lgkmcnt(6)
	v_mfma_f32_32x32x16_bf16 v[2:17], v[50:53], v[22:25], v[2:17]
	v_ashrrev_i32_e32 v119, 31, v118
	v_ashrrev_i32_e32 v117, 31, v116
	v_ashrrev_i32_e32 v115, 31, v114
	v_ashrrev_i32_e32 v113, 31, v112
	v_ashrrev_i32_e32 v111, 31, v110
	v_ashrrev_i32_e32 v109, 31, v108
	v_ashrrev_i32_e32 v73, 31, v72
	v_ashrrev_i32_e32 v69, 31, v68
	v_ashrrev_i32_e32 v67, 31, v66
	v_ashrrev_i32_e32 v65, 31, v64
	v_ashrrev_i32_e32 v63, 31, v62
	v_ashrrev_i32_e32 v61, 31, v60
	v_ashrrev_i32_e32 v59, 31, v58
	v_ashrrev_i32_e32 v57, 31, v56
	v_add_u32_e32 v140, 63, v94
	v_add_u32_e32 v138, 64, v94
	v_ashrrev_i32_e32 v163, 31, v162
	v_ashrrev_i32_e32 v161, 31, v160
	v_ashrrev_i32_e32 v159, 31, v158
	v_ashrrev_i32_e32 v157, 31, v156
	v_ashrrev_i32_e32 v155, 31, v154
	v_ashrrev_i32_e32 v153, 31, v152
	v_ashrrev_i32_e32 v151, 31, v150
	v_ashrrev_i32_e32 v149, 31, v148
	v_ashrrev_i32_e32 v147, 31, v146
	v_ashrrev_i32_e32 v145, 31, v144
	v_ashrrev_i32_e32 v143, 31, v142
	v_ashrrev_i32_e32 v105, 31, v104
	v_ashrrev_i32_e32 v103, 31, v102
	v_ashrrev_i32_e32 v101, 31, v100
	v_ashrrev_i32_e32 v99, 31, v98
	v_ashrrev_i32_e32 v97, 31, v96
	v_ashrrev_i32_e32 v141, 31, v140
	v_ashrrev_i32_e32 v139, 31, v138
	s_waitcnt vmcnt(31)
	v_lshlrev_b32_e32 v1, 16, v1
	v_fma_f32 v50, |v1|, s92, 1.0
	v_rcp_f32_e32 v50, v50
	v_cmp_gt_f32_e32 vcc, 0, v1
	v_fmamk_f32 v51, v50, 0x3f07dc22, v236
	v_fmaak_f32 v51, v50, v51, 0x3f35f0e3
	v_fmaak_f32 v51, v50, v51, 0xbe11a98e
	v_fmaak_f32 v51, v50, v51, 0x3e027906
	v_mul_f32_e32 v50, v50, v51
	v_mul_f32_e32 v51, v1, v1
	v_mul_f32_e32 v51, 0xbf38aa3b, v51
	v_exp_f32_e32 v51, v51
	s_nop 0
	v_mul_f32_e32 v50, v51, v50
	v_mul_f32_e32 v51, v50, v1
	v_fma_f32 v50, -v50, v1, v1
	v_add_u32_e32 v1, s5, v164
	v_cndmask_b32_e32 v136, v50, v51, vcc
	ds_read_b128 v[50:53], v1
	ds_read_b128 v[122:125], v1 offset:32
	s_movk_i32 s5, 0x3000
	s_waitcnt lgkmcnt(1)
	v_add_f32_e32 v2, v2, v50
	v_mul_f32_e32 v2, v136, v2
	v_cvt_pk_bf16_f32 v2, v2, s0
	global_store_short v[120:121], v2, off sc1
	s_waitcnt vmcnt(31)
	v_lshlrev_b32_e32 v2, 16, v130
	v_fma_f32 v50, |v2|, s92, 1.0
	v_rcp_f32_e32 v50, v50
	v_cmp_gt_f32_e32 vcc, 0, v2
	v_add_f32_e32 v3, v3, v51
	v_add_u32_e32 v136, 0x41, v94
	v_fmamk_f32 v120, v50, 0x3f07dc22, v236
	v_fmaak_f32 v120, v50, v120, 0x3f35f0e3
	v_fmaak_f32 v120, v50, v120, 0xbe11a98e
	v_fmaak_f32 v120, v50, v120, 0x3e027906
	v_mul_f32_e32 v50, v50, v120
	v_mul_f32_e32 v120, v2, v2
	v_mul_f32_e32 v120, 0xbf38aa3b, v120
	v_exp_f32_e32 v120, v120
	v_ashrrev_i32_e32 v137, 31, v136
	v_mul_f32_e32 v50, v120, v50
	v_mul_f32_e32 v120, v50, v2
	v_fma_f32 v50, -v50, v2, v2
	v_cndmask_b32_e32 v2, v50, v120, vcc
	v_mul_f32_e32 v2, v2, v3
	v_cvt_pk_bf16_f32 v50, v2, s0
	v_lshlrev_b64 v[2:3], 11, v[94:95]
	v_lshl_add_u64 v[2:3], v[106:107], 0, v[2:3]
	global_store_short v[2:3], v50, off sc1
	s_waitcnt vmcnt(31)
	v_lshlrev_b32_e32 v2, 16, v165
	v_fma_f32 v3, |v2|, s92, 1.0
	v_rcp_f32_e32 v3, v3
	v_cmp_gt_f32_e32 vcc, 0, v2
	v_add_u32_e32 v120, 0x59, v94
	v_ashrrev_i32_e32 v121, 31, v120
	v_fmamk_f32 v50, v3, 0x3f07dc22, v236
	v_fmaak_f32 v50, v3, v50, 0x3f35f0e3
	v_fmaak_f32 v50, v3, v50, 0xbe11a98e
	v_fmaak_f32 v50, v3, v50, 0x3e027906
	v_mul_f32_e32 v3, v3, v50
	v_mul_f32_e32 v50, v2, v2
	v_mul_f32_e32 v50, 0xbf38aa3b, v50
	v_exp_f32_e32 v50, v50
	s_nop 0
	v_mul_f32_e32 v3, v50, v3
	v_mul_f32_e32 v50, v3, v2
	v_fma_f32 v3, -v3, v2, v2
	v_cndmask_b32_e32 v2, v3, v50, vcc
	v_add_f32_e32 v3, v4, v52
	v_mul_f32_e32 v2, v2, v3
	v_cvt_pk_bf16_f32 v4, v2, s0
	v_lshlrev_b64 v[2:3], 11, v[118:119]
	v_lshl_add_u64 v[2:3], v[106:107], 0, v[2:3]
	global_store_short v[2:3], v4, off sc1
	s_waitcnt vmcnt(31)
	v_lshlrev_b32_e32 v2, 16, v206
	v_fma_f32 v3, |v2|, s92, 1.0
	v_rcp_f32_e32 v3, v3
	v_cmp_gt_f32_e32 vcc, 0, v2
	v_add_u32_e32 v118, 0x4a, v94
	v_ashrrev_i32_e32 v119, 31, v118
	v_fmamk_f32 v4, v3, 0x3f07dc22, v236
	v_fmaak_f32 v4, v3, v4, 0x3f35f0e3
	v_fmaak_f32 v4, v3, v4, 0xbe11a98e
	v_fmaak_f32 v4, v3, v4, 0x3e027906
	v_mul_f32_e32 v3, v3, v4
	v_mul_f32_e32 v4, v2, v2
	v_mul_f32_e32 v4, 0xbf38aa3b, v4
	v_exp_f32_e32 v4, v4
	s_nop 0
	v_mul_f32_e32 v3, v4, v3
	v_mul_f32_e32 v4, v3, v2
	v_fma_f32 v3, -v3, v2, v2
	v_cndmask_b32_e32 v2, v3, v4, vcc
	v_add_f32_e32 v3, v5, v53
	v_mul_f32_e32 v2, v2, v3
	v_cvt_pk_bf16_f32 v4, v2, s0
	v_lshlrev_b64 v[2:3], 11, v[116:117]
	v_lshl_add_u64 v[2:3], v[106:107], 0, v[2:3]
	global_store_short v[2:3], v4, off sc1
	s_waitcnt vmcnt(31)
	v_lshlrev_b32_e32 v2, 16, v207
	v_fma_f32 v3, |v2|, s92, 1.0
	v_rcp_f32_e32 v3, v3
	v_cmp_gt_f32_e32 vcc, 0, v2
	v_add_u32_e32 v116, 0x4f, v94
	v_mad_i64_i32 v[164:165], s[6:7], v116, s87, v[92:93]
	v_fmamk_f32 v4, v3, 0x3f07dc22, v236
	v_fmaak_f32 v4, v3, v4, 0x3f35f0e3
	v_fmaak_f32 v4, v3, v4, 0xbe11a98e
	v_fmaak_f32 v4, v3, v4, 0x3e027906
	v_mul_f32_e32 v3, v3, v4
	v_mul_f32_e32 v4, v2, v2
	v_mul_f32_e32 v4, 0xbf38aa3b, v4
	v_exp_f32_e32 v4, v4
	v_mad_i64_i32 v[206:207], s[6:7], v120, s87, v[92:93]
	v_ashrrev_i32_e32 v117, 31, v116
	v_mul_f32_e32 v3, v4, v3
	v_mul_f32_e32 v4, v3, v2
	v_fma_f32 v3, -v3, v2, v2
	v_cndmask_b32_e32 v2, v3, v4, vcc
	s_waitcnt lgkmcnt(0)
	v_add_f32_e32 v3, v6, v122
	v_mul_f32_e32 v2, v2, v3
	v_cvt_pk_bf16_f32 v4, v2, s0
	v_lshlrev_b64 v[2:3], 11, v[114:115]
	v_lshl_add_u64 v[2:3], v[106:107], 0, v[2:3]
	global_store_short v[2:3], v4, off sc1
	s_waitcnt vmcnt(31)
	v_lshlrev_b32_e32 v2, 16, v208
	v_fma_f32 v3, |v2|, s92, 1.0
	v_rcp_f32_e32 v3, v3
	v_cmp_gt_f32_e32 vcc, 0, v2
	v_add_u32_e32 v122, 0x49, v94
	v_add_u32_e32 v114, 0x5a, v94
	v_fmamk_f32 v4, v3, 0x3f07dc22, v236
	v_fmaak_f32 v4, v3, v4, 0x3f35f0e3
	v_fmaak_f32 v4, v3, v4, 0xbe11a98e
	v_fmaak_f32 v4, v3, v4, 0x3e027906
	v_mul_f32_e32 v3, v3, v4
	v_mul_f32_e32 v4, v2, v2
	v_mul_f32_e32 v4, 0xbf38aa3b, v4
	v_exp_f32_e32 v4, v4
	v_ashrrev_i32_e32 v115, 31, v114
	v_mul_f32_e32 v3, v4, v3
	v_mul_f32_e32 v4, v3, v2
	v_fma_f32 v3, -v3, v2, v2
	v_cndmask_b32_e32 v2, v3, v4, vcc
	v_add_f32_e32 v3, v7, v123
	v_mul_f32_e32 v2, v2, v3
	v_cvt_pk_bf16_f32 v4, v2, s0
	v_lshlrev_b64 v[2:3], 11, v[112:113]
	v_lshl_add_u64 v[2:3], v[106:107], 0, v[2:3]
	global_store_short v[2:3], v4, off sc1
	s_waitcnt vmcnt(31)
	v_lshlrev_b32_e32 v2, 16, v209
	v_fma_f32 v3, |v2|, s92, 1.0
	v_rcp_f32_e32 v3, v3
	v_cmp_gt_f32_e32 vcc, 0, v2
	v_add_u32_e32 v112, 0x50, v94
	v_mad_i64_i32 v[166:167], s[6:7], v112, s87, v[92:93]
	v_fmamk_f32 v4, v3, 0x3f07dc22, v236
	v_fmaak_f32 v4, v3, v4, 0x3f35f0e3
	v_fmaak_f32 v4, v3, v4, 0xbe11a98e
	v_fmaak_f32 v4, v3, v4, 0x3e027906
	v_mul_f32_e32 v3, v3, v4
	v_mul_f32_e32 v4, v2, v2
	v_mul_f32_e32 v4, 0xbf38aa3b, v4
	v_exp_f32_e32 v4, v4
	v_mad_i64_i32 v[208:209], s[6:7], v114, s87, v[92:93]
	v_ashrrev_i32_e32 v123, 31, v122
	v_mul_f32_e32 v3, v4, v3
	v_mul_f32_e32 v4, v3, v2
	v_fma_f32 v3, -v3, v2, v2
	v_cndmask_b32_e32 v2, v3, v4, vcc
	v_add_f32_e32 v3, v8, v124
	v_mul_f32_e32 v2, v2, v3
	v_cvt_pk_bf16_f32 v4, v2, s0
	v_lshlrev_b64 v[2:3], 11, v[110:111]
	v_lshl_add_u64 v[2:3], v[106:107], 0, v[2:3]
	global_store_short v[2:3], v4, off sc1
	s_waitcnt vmcnt(31)
	v_lshlrev_b32_e32 v2, 16, v210
	v_fma_f32 v3, |v2|, s92, 1.0
	v_rcp_f32_e32 v3, v3
	v_cmp_gt_f32_e32 vcc, 0, v2
	v_add_u32_e32 v110, 0x51, v94
	v_add_u32_e32 v124, 0x58, v94
	v_fmamk_f32 v4, v3, 0x3f07dc22, v236
	v_fmaak_f32 v4, v3, v4, 0x3f35f0e3
	v_fmaak_f32 v4, v3, v4, 0xbe11a98e
	v_fmaak_f32 v4, v3, v4, 0x3e027906
	v_mul_f32_e32 v3, v3, v4
	v_mul_f32_e32 v4, v2, v2
	v_mul_f32_e32 v4, 0xbf38aa3b, v4
	v_exp_f32_e32 v4, v4
	v_mad_i64_i32 v[168:169], s[6:7], v110, s87, v[92:93]
	v_mad_i64_i32 v[204:205], s[6:7], v124, s87, v[92:93]
	v_mul_f32_e32 v3, v4, v3
	v_mul_f32_e32 v4, v3, v2
	v_fma_f32 v3, -v3, v2, v2
	v_cndmask_b32_e32 v2, v3, v4, vcc
	v_add_f32_e32 v3, v9, v125
	v_mul_f32_e32 v2, v2, v3
	v_cvt_pk_bf16_f32 v4, v2, s0
	v_lshlrev_b64 v[2:3], 11, v[108:109]
	v_lshl_add_u64 v[2:3], v[106:107], 0, v[2:3]
	global_store_short v[2:3], v4, off sc1
	s_waitcnt vmcnt(31)
	v_lshlrev_b32_e32 v2, 16, v126
	v_fma_f32 v3, |v2|, s92, 1.0
	v_rcp_f32_e32 v3, v3
	v_cmp_gt_f32_e32 vcc, 0, v2
	v_add_u32_e32 v126, 0x48, v94
	v_add_u32_e32 v108, 0x52, v94
	v_fmamk_f32 v4, v3, 0x3f07dc22, v236
	v_fmaak_f32 v4, v3, v4, 0x3f35f0e3
	v_fmaak_f32 v4, v3, v4, 0xbe11a98e
	v_fmaak_f32 v4, v3, v4, 0x3e027906
	v_mul_f32_e32 v3, v3, v4
	v_mul_f32_e32 v4, v2, v2
	v_mul_f32_e32 v4, 0xbf38aa3b, v4
	v_exp_f32_e32 v4, v4
	v_mad_i64_i32 v[170:171], s[6:7], v108, s87, v[92:93]
	v_ashrrev_i32_e32 v113, 31, v112
	v_mul_f32_e32 v3, v4, v3
	v_mul_f32_e32 v4, v3, v2
	v_fma_f32 v3, -v3, v2, v2
	v_cndmask_b32_e32 v6, v3, v4, vcc
	ds_read_b128 v[2:5], v1 offset:64
	v_ashrrev_i32_e32 v111, 31, v110
	v_ashrrev_i32_e32 v109, 31, v108
	v_ashrrev_i32_e32 v125, 31, v124
	s_waitcnt lgkmcnt(0)
	v_add_f32_e32 v2, v10, v2
	v_mul_f32_e32 v2, v6, v2
	v_lshlrev_b64 v[6:7], 11, v[72:73]
	v_cvt_pk_bf16_f32 v2, v2, s0
	v_lshl_add_u64 v[6:7], v[106:107], 0, v[6:7]
	global_store_short v[6:7], v2, off sc1
	s_waitcnt vmcnt(31)
	v_lshlrev_b32_e32 v2, 16, v127
	v_fma_f32 v6, |v2|, s92, 1.0
	v_rcp_f32_e32 v6, v6
	v_cmp_gt_f32_e32 vcc, 0, v2
	v_add_f32_e32 v3, v11, v3
	v_ashrrev_i32_e32 v127, 31, v126
	v_fmamk_f32 v7, v6, 0x3f07dc22, v236
	v_fmaak_f32 v7, v6, v7, 0x3f35f0e3
	v_fmaak_f32 v7, v6, v7, 0xbe11a98e
	v_fmaak_f32 v7, v6, v7, 0x3e027906
	v_mul_f32_e32 v6, v6, v7
	v_mul_f32_e32 v7, v2, v2
	v_mul_f32_e32 v7, 0xbf38aa3b, v7
	v_exp_f32_e32 v7, v7
	s_nop 0
	v_mul_f32_e32 v6, v7, v6
	v_mul_f32_e32 v7, v6, v2
	v_fma_f32 v6, -v6, v2, v2
	v_cndmask_b32_e32 v2, v6, v7, vcc
	v_mul_f32_e32 v2, v2, v3
	v_cvt_pk_bf16_f32 v6, v2, s0
	v_lshlrev_b64 v[2:3], 11, v[68:69]
	v_lshl_add_u64 v[2:3], v[106:107], 0, v[2:3]
	global_store_short v[2:3], v6, off sc1
	s_waitcnt vmcnt(31)
	v_lshlrev_b32_e32 v2, 16, v128
	v_fma_f32 v3, |v2|, s92, 1.0
	v_rcp_f32_e32 v3, v3
	v_cmp_gt_f32_e32 vcc, 0, v2
	v_add_u32_e32 v128, 0x57, v94
	v_mad_i64_i32 v[188:189], s[6:7], v128, s87, v[92:93]
	v_fmamk_f32 v6, v3, 0x3f07dc22, v236
	v_fmaak_f32 v6, v3, v6, 0x3f35f0e3
	v_fmaak_f32 v6, v3, v6, 0xbe11a98e
	v_fmaak_f32 v6, v3, v6, 0x3e027906
	v_mul_f32_e32 v3, v3, v6
	v_mul_f32_e32 v6, v2, v2
	v_mul_f32_e32 v6, 0xbf38aa3b, v6
	v_exp_f32_e32 v6, v6
	s_nop 0
	v_mul_f32_e32 v3, v6, v3
	v_mul_f32_e32 v6, v3, v2
	v_fma_f32 v3, -v3, v2, v2
	v_cndmask_b32_e32 v2, v3, v6, vcc
	v_add_f32_e32 v3, v12, v4
	v_mul_f32_e32 v2, v2, v3
	v_cvt_pk_bf16_f32 v4, v2, s0
	v_lshlrev_b64 v[2:3], 11, v[66:67]
	v_lshl_add_u64 v[2:3], v[106:107], 0, v[2:3]
	global_store_short v[2:3], v4, off sc1
	s_waitcnt vmcnt(31)
	v_lshlrev_b32_e32 v2, 16, v129
	v_fma_f32 v3, |v2|, s92, 1.0
	v_rcp_f32_e32 v3, v3
	v_cmp_gt_f32_e32 vcc, 0, v2
	v_ashrrev_i32_e32 v129, 31, v128
	v_fmamk_f32 v4, v3, 0x3f07dc22, v236
	v_fmaak_f32 v4, v3, v4, 0x3f35f0e3
	v_fmaak_f32 v4, v3, v4, 0xbe11a98e
	v_fmaak_f32 v4, v3, v4, 0x3e027906
	v_mul_f32_e32 v3, v3, v4
	v_mul_f32_e32 v4, v2, v2
	v_mul_f32_e32 v4, 0xbf38aa3b, v4
	v_exp_f32_e32 v4, v4
	s_nop 0
	v_mul_f32_e32 v3, v4, v3
	v_mul_f32_e32 v4, v3, v2
	v_fma_f32 v3, -v3, v2, v2
	v_cndmask_b32_e32 v2, v3, v4, vcc
	v_add_f32_e32 v3, v13, v5
	v_mul_f32_e32 v2, v2, v3
	v_cvt_pk_bf16_f32 v4, v2, s0
	v_lshlrev_b64 v[2:3], 11, v[64:65]
	v_lshl_add_u64 v[2:3], v[106:107], 0, v[2:3]
	global_store_short v[2:3], v4, off sc1
	s_waitcnt vmcnt(31)
	v_lshlrev_b32_e32 v2, 16, v132
	v_fma_f32 v3, |v2|, s92, 1.0
	v_rcp_f32_e32 v3, v3
	v_cmp_gt_f32_e32 vcc, 0, v2
	v_add_u32_e32 v132, 0x47, v94
	v_mad_i64_i32 v[10:11], s[6:7], v132, s87, v[92:93]
	v_fmamk_f32 v4, v3, 0x3f07dc22, v236
	v_fmaak_f32 v4, v3, v4, 0x3f35f0e3
	v_fmaak_f32 v4, v3, v4, 0xbe11a98e
	v_fmaak_f32 v4, v3, v4, 0x3e027906
	v_mul_f32_e32 v3, v3, v4
	v_mul_f32_e32 v4, v2, v2
	v_mul_f32_e32 v4, 0xbf38aa3b, v4
	v_exp_f32_e32 v4, v4
	v_mad_i64_i32 v[12:13], s[6:7], v126, s87, v[92:93]
	v_mul_f32_e32 v3, v4, v3
	v_mul_f32_e32 v4, v3, v2
	v_fma_f32 v3, -v3, v2, v2
	v_cndmask_b32_e32 v6, v3, v4, vcc
	ds_read_b128 v[2:5], v1 offset:96
	s_waitcnt lgkmcnt(0)
	v_add_f32_e32 v2, v14, v2
	v_mul_f32_e32 v2, v6, v2
	v_lshlrev_b64 v[6:7], 11, v[62:63]
	v_cvt_pk_bf16_f32 v2, v2, s0
	v_lshl_add_u64 v[6:7], v[106:107], 0, v[6:7]
	global_store_short v[6:7], v2, off sc1
	s_waitcnt vmcnt(31)
	v_lshlrev_b32_e32 v2, 16, v133
	v_fma_f32 v6, |v2|, s92, 1.0
	v_rcp_f32_e32 v6, v6
	v_cmp_gt_f32_e32 vcc, 0, v2
	v_add_f32_e32 v3, v15, v3
	v_mad_i64_i32 v[14:15], s[6:7], v122, s87, v[92:93]
	v_fmamk_f32 v7, v6, 0x3f07dc22, v236
	v_fmaak_f32 v7, v6, v7, 0x3f35f0e3
	v_fmaak_f32 v7, v6, v7, 0xbe11a98e
	v_fmaak_f32 v7, v6, v7, 0x3e027906
	v_mul_f32_e32 v6, v6, v7
	v_mul_f32_e32 v7, v2, v2
	v_mul_f32_e32 v7, 0xbf38aa3b, v7
	v_exp_f32_e32 v7, v7
	v_ashrrev_i32_e32 v133, 31, v132
	v_mul_f32_e32 v6, v7, v6
	v_mul_f32_e32 v7, v6, v2
	v_fma_f32 v6, -v6, v2, v2
	v_cndmask_b32_e32 v2, v6, v7, vcc
	v_mul_f32_e32 v2, v2, v3
	v_cvt_pk_bf16_f32 v6, v2, s0
	v_lshlrev_b64 v[2:3], 11, v[60:61]
	v_lshl_add_u64 v[2:3], v[106:107], 0, v[2:3]
	global_store_short v[2:3], v6, off sc1
	s_waitcnt vmcnt(31)
	v_lshlrev_b32_e32 v2, 16, v134
	v_fma_f32 v3, |v2|, s92, 1.0
	v_rcp_f32_e32 v3, v3
	v_cmp_gt_f32_e32 vcc, 0, v2
	v_add_u32_e32 v134, 0x42, v94
	v_mad_i64_i32 v[8:9], s[6:7], v134, s87, v[92:93]
	v_fmamk_f32 v6, v3, 0x3f07dc22, v236
	v_fmaak_f32 v6, v3, v6, 0x3f35f0e3
	v_fmaak_f32 v6, v3, v6, 0xbe11a98e
	v_fmaak_f32 v6, v3, v6, 0x3e027906
	v_mul_f32_e32 v3, v3, v6
	v_mul_f32_e32 v6, v2, v2
	v_mul_f32_e32 v6, 0xbf38aa3b, v6
	v_exp_f32_e32 v6, v6
	s_nop 0
	v_mul_f32_e32 v3, v6, v3
	v_mul_f32_e32 v6, v3, v2
	v_fma_f32 v3, -v3, v2, v2
	v_cndmask_b32_e32 v2, v3, v6, vcc
	v_add_f32_e32 v3, v16, v4
	v_mul_f32_e32 v2, v2, v3
	v_cvt_pk_bf16_f32 v4, v2, s0
	v_lshlrev_b64 v[2:3], 11, v[58:59]
	v_lshl_add_u64 v[2:3], v[106:107], 0, v[2:3]
	global_store_short v[2:3], v4, off sc1
	s_waitcnt vmcnt(31)
	v_lshlrev_b32_e32 v2, 16, v135
	v_fma_f32 v3, |v2|, s92, 1.0
	v_rcp_f32_e32 v3, v3
	v_cmp_gt_f32_e32 vcc, 0, v2
	v_mad_i64_i32 v[6:7], s[6:7], v136, s87, v[92:93]
	v_fmamk_f32 v4, v3, 0x3f07dc22, v236
	v_fmaak_f32 v4, v3, v4, 0x3f35f0e3
	v_fmaak_f32 v4, v3, v4, 0xbe11a98e
	v_fmaak_f32 v4, v3, v4, 0x3e027906
	v_mul_f32_e32 v3, v3, v4
	v_mul_f32_e32 v4, v2, v2
	v_mul_f32_e32 v4, 0xbf38aa3b, v4
	v_exp_f32_e32 v4, v4
	v_ashrrev_i32_e32 v135, 31, v134
	v_mul_f32_e32 v3, v4, v3
	v_mul_f32_e32 v4, v3, v2
	v_fma_f32 v3, -v3, v2, v2
	v_cndmask_b32_e32 v2, v3, v4, vcc
	v_add_f32_e32 v3, v17, v5
	v_mul_f32_e32 v2, v2, v3
	v_cvt_pk_bf16_f32 v4, v2, s0
	v_lshlrev_b64 v[2:3], 11, v[56:57]
	v_lshl_add_u64 v[2:3], v[106:107], 0, v[2:3]
	global_store_short v[2:3], v4, off sc1
	v_mad_i64_i32 v[2:3], s[6:7], v140, s87, v[92:93]
	v_mad_i64_i32 v[4:5], s[6:7], v138, s87, v[92:93]
	v_mad_i64_i32 v[16:17], s[6:7], v118, s87, v[92:93]
	global_load_dwordx4 v[50:53], v[54:55], off offset:2048
	s_nop 0
	global_load_dwordx4 v[54:57], v[54:55], off offset:3072
	s_nop 0
	global_load_dwordx4 v[58:61], v[70:71], off
	global_load_dwordx4 v[62:65], v[70:71], off offset:1024
	global_load_dwordx4 v[66:69], v[70:71], off offset:2048
	s_nop 0
	global_load_dwordx4 v[70:73], v[70:71], off offset:3072
	s_nop 0
	global_load_ushort v202, v[2:3], off
	global_load_ushort v201, v[4:5], off
	global_load_ushort v200, v[6:7], off
	global_load_ushort v199, v[8:9], off
	global_load_ushort v198, v[10:11], off
	global_load_ushort v197, v[12:13], off
	global_load_ushort v196, v[14:15], off
	global_load_ushort v195, v[16:17], off
	global_load_ushort v194, v[164:165], off
	global_load_ushort v193, v[166:167], off
	global_load_ushort v192, v[168:169], off
	global_load_ushort v191, v[170:171], off
	global_load_ushort v190, v[188:189], off
	s_nop 0
	global_load_ushort v189, v[204:205], off
	global_load_ushort v188, v[206:207], off
	global_load_ushort v130, v[208:209], off
	v_mfma_f32_32x32x16_bf16 v[2:17], v[74:77], v[18:21], 0
	s_waitcnt vmcnt(53)
	v_lshlrev_b32_e32 v74, 16, v187
	v_fma_f32 v75, |v74|, s92, 1.0
	v_rcp_f32_e32 v75, v75
	v_cmp_gt_f32_e32 vcc, 0, v74
	v_add_u32_e32 v170, 0x6f, v94
	v_fmamk_f32 v76, v75, 0x3f07dc22, v236
	v_mfma_f32_32x32x16_bf16 v[2:17], v[78:81], v[22:25], v[2:17]
	v_fmaak_f32 v76, v75, v76, 0x3f35f0e3
	v_fmaak_f32 v76, v75, v76, 0xbe11a98e
	v_fmaak_f32 v76, v75, v76, 0x3e027906
	v_mul_f32_e32 v75, v75, v76
	v_mul_f32_e32 v76, v74, v74
	v_mul_f32_e32 v76, 0xbf38aa3b, v76
	v_exp_f32_e32 v76, v76
	v_mfma_f32_32x32x16_bf16 v[2:17], v[82:85], v[26:29], v[2:17]
	v_add_u32_e32 v168, 0x70, v94
	v_add_u32_e32 v166, 0x71, v94
	v_mul_f32_e32 v75, v76, v75
	v_mul_f32_e32 v76, v75, v74
	v_fma_f32 v75, -v75, v74, v74
	v_cndmask_b32_e32 v82, v75, v76, vcc
	ds_read_b128 v[74:77], v1 offset:128
	ds_read_b128 v[78:81], v1 offset:160
	v_mfma_f32_32x32x16_bf16 v[2:17], v[86:89], v[30:33], v[2:17]
	v_add_u32_e32 v164, 0x72, v94
	v_ashrrev_i32_e32 v171, 31, v170
	v_ashrrev_i32_e32 v169, 31, v168
	v_ashrrev_i32_e32 v167, 31, v166
	v_ashrrev_i32_e32 v165, 31, v164
	s_waitcnt lgkmcnt(1)
	s_nop 5
	v_add_f32_e32 v2, v2, v74
	v_mul_f32_e32 v2, v82, v2
	v_lshlrev_b64 v[82:83], 11, v[162:163]
	v_cvt_pk_bf16_f32 v2, v2, s0
	v_lshl_add_u64 v[82:83], v[106:107], 0, v[82:83]
	global_store_short v[82:83], v2, off sc1
	s_waitcnt vmcnt(53)
	v_lshlrev_b32_e32 v2, 16, v186
	v_fma_f32 v74, |v2|, s92, 1.0
	v_rcp_f32_e32 v74, v74
	v_cmp_gt_f32_e32 vcc, 0, v2
	v_add_f32_e32 v3, v3, v75
	v_add_u32_e32 v162, 0x77, v94
	v_fmamk_f32 v82, v74, 0x3f07dc22, v236
	v_fmaak_f32 v82, v74, v82, 0x3f35f0e3
	v_fmaak_f32 v82, v74, v82, 0xbe11a98e
	v_fmaak_f32 v82, v74, v82, 0x3e027906
	v_mul_f32_e32 v74, v74, v82
	v_mul_f32_e32 v82, v2, v2
	v_mul_f32_e32 v82, 0xbf38aa3b, v82
	v_exp_f32_e32 v82, v82
	v_ashrrev_i32_e32 v163, 31, v162
	v_mul_f32_e32 v74, v82, v74
	v_mul_f32_e32 v82, v74, v2
	v_fma_f32 v74, -v74, v2, v2
	v_cndmask_b32_e32 v2, v74, v82, vcc
	v_mul_f32_e32 v2, v2, v3
	v_cvt_pk_bf16_f32 v74, v2, s0
	v_lshlrev_b64 v[2:3], 11, v[160:161]
	v_lshl_add_u64 v[2:3], v[106:107], 0, v[2:3]
	global_store_short v[2:3], v74, off sc1
	s_waitcnt vmcnt(53)
	v_lshlrev_b32_e32 v2, 16, v185
	v_fma_f32 v3, |v2|, s92, 1.0
	v_rcp_f32_e32 v3, v3
	v_cmp_gt_f32_e32 vcc, 0, v2
	v_add_u32_e32 v160, 0x78, v94
	v_ashrrev_i32_e32 v161, 31, v160
	v_fmamk_f32 v74, v3, 0x3f07dc22, v236
	v_fmaak_f32 v74, v3, v74, 0x3f35f0e3
	v_fmaak_f32 v74, v3, v74, 0xbe11a98e
	v_fmaak_f32 v74, v3, v74, 0x3e027906
	v_mul_f32_e32 v3, v3, v74
	v_mul_f32_e32 v74, v2, v2
	v_mul_f32_e32 v74, 0xbf38aa3b, v74
	v_exp_f32_e32 v74, v74
	s_nop 0
	v_mul_f32_e32 v3, v74, v3
	v_mul_f32_e32 v74, v3, v2
	v_fma_f32 v3, -v3, v2, v2
	v_cndmask_b32_e32 v2, v3, v74, vcc
	v_add_f32_e32 v3, v4, v76
	v_mul_f32_e32 v2, v2, v3
	v_cvt_pk_bf16_f32 v4, v2, s0
	v_lshlrev_b64 v[2:3], 11, v[158:159]
	v_lshl_add_u64 v[2:3], v[106:107], 0, v[2:3]
	global_store_short v[2:3], v4, off sc1
	s_waitcnt vmcnt(53)
	v_lshlrev_b32_e32 v2, 16, v184
	v_fma_f32 v3, |v2|, s92, 1.0
	v_rcp_f32_e32 v3, v3
	v_cmp_gt_f32_e32 vcc, 0, v2
	v_add_u32_e32 v158, 0x79, v94
	v_mad_i64_i32 v[184:185], s[6:7], v160, s87, v[92:93]
	v_fmamk_f32 v4, v3, 0x3f07dc22, v236
	v_fmaak_f32 v4, v3, v4, 0x3f35f0e3
	v_fmaak_f32 v4, v3, v4, 0xbe11a98e
	v_fmaak_f32 v4, v3, v4, 0x3e027906
	v_mul_f32_e32 v3, v3, v4
	v_mul_f32_e32 v4, v2, v2
	v_mul_f32_e32 v4, 0xbf38aa3b, v4
	v_exp_f32_e32 v4, v4
	v_mad_i64_i32 v[186:187], s[6:7], v158, s87, v[92:93]
	v_ashrrev_i32_e32 v159, 31, v158
	v_mul_f32_e32 v3, v4, v3
	v_mul_f32_e32 v4, v3, v2
	v_fma_f32 v3, -v3, v2, v2
	v_cndmask_b32_e32 v2, v3, v4, vcc
	v_add_f32_e32 v3, v5, v77
	v_mul_f32_e32 v2, v2, v3
	v_cvt_pk_bf16_f32 v4, v2, s0
	v_lshlrev_b64 v[2:3], 11, v[156:157]
	v_lshl_add_u64 v[2:3], v[106:107], 0, v[2:3]
	global_store_short v[2:3], v4, off sc1
	s_waitcnt vmcnt(53)
	v_lshlrev_b32_e32 v2, 16, v183
	v_fma_f32 v3, |v2|, s92, 1.0
	v_rcp_f32_e32 v3, v3
	v_cmp_gt_f32_e32 vcc, 0, v2
	v_add_u32_e32 v156, 0x7a, v94
	v_mad_i64_i32 v[214:215], s[6:7], v156, s87, v[92:93]
	v_fmamk_f32 v4, v3, 0x3f07dc22, v236
	v_fmaak_f32 v4, v3, v4, 0x3f35f0e3
	v_fmaak_f32 v4, v3, v4, 0xbe11a98e
	v_fmaak_f32 v4, v3, v4, 0x3e027906
	v_mul_f32_e32 v3, v3, v4
	v_mul_f32_e32 v4, v2, v2
	v_mul_f32_e32 v4, 0xbf38aa3b, v4
	v_exp_f32_e32 v4, v4
	v_ashrrev_i32_e32 v157, 31, v156
	v_mul_f32_e32 v3, v4, v3
	v_mul_f32_e32 v4, v3, v2
	v_fma_f32 v3, -v3, v2, v2
	v_cndmask_b32_e32 v2, v3, v4, vcc
	s_waitcnt lgkmcnt(0)
	v_add_f32_e32 v3, v6, v78
	v_mul_f32_e32 v2, v2, v3
	v_cvt_pk_bf16_f32 v4, v2, s0
	v_lshlrev_b64 v[2:3], 11, v[154:155]
	v_lshl_add_u64 v[2:3], v[106:107], 0, v[2:3]
	global_store_short v[2:3], v4, off sc1
	s_waitcnt vmcnt(53)
	v_lshlrev_b32_e32 v2, 16, v182
	v_fma_f32 v3, |v2|, s92, 1.0
	v_rcp_f32_e32 v3, v3
	v_cmp_gt_f32_e32 vcc, 0, v2
	v_add_u32_e32 v154, 0x60, v94
	v_mad_i64_i32 v[182:183], s[6:7], v162, s87, v[92:93]
	v_fmamk_f32 v4, v3, 0x3f07dc22, v236
	v_fmaak_f32 v4, v3, v4, 0x3f35f0e3
	v_fmaak_f32 v4, v3, v4, 0xbe11a98e
	v_fmaak_f32 v4, v3, v4, 0x3e027906
	v_mul_f32_e32 v3, v3, v4
	v_mul_f32_e32 v4, v2, v2
	v_mul_f32_e32 v4, 0xbf38aa3b, v4
	v_exp_f32_e32 v4, v4
	v_ashrrev_i32_e32 v155, 31, v154
	v_mul_f32_e32 v3, v4, v3
	v_mul_f32_e32 v4, v3, v2
	v_fma_f32 v3, -v3, v2, v2
	v_cndmask_b32_e32 v2, v3, v4, vcc
	v_add_f32_e32 v3, v7, v79
	v_mul_f32_e32 v2, v2, v3
	v_cvt_pk_bf16_f32 v4, v2, s0
	v_lshlrev_b64 v[2:3], 11, v[152:153]
	v_lshl_add_u64 v[2:3], v[106:107], 0, v[2:3]
	global_store_short v[2:3], v4, off sc1
	s_waitcnt vmcnt(53)
	v_lshlrev_b32_e32 v2, 16, v181
	v_fma_f32 v3, |v2|, s92, 1.0
	v_rcp_f32_e32 v3, v3
	v_cmp_gt_f32_e32 vcc, 0, v2
	v_add_u32_e32 v152, 0x61, v94
	v_ashrrev_i32_e32 v153, 31, v152
	v_fmamk_f32 v4, v3, 0x3f07dc22, v236
	v_fmaak_f32 v4, v3, v4, 0x3f35f0e3
	v_fmaak_f32 v4, v3, v4, 0xbe11a98e
	v_fmaak_f32 v4, v3, v4, 0x3e027906
	v_mul_f32_e32 v3, v3, v4
	v_mul_f32_e32 v4, v2, v2
	v_mul_f32_e32 v4, 0xbf38aa3b, v4
	v_exp_f32_e32 v4, v4
	s_nop 0
	v_mul_f32_e32 v3, v4, v3
	v_mul_f32_e32 v4, v3, v2
	v_fma_f32 v3, -v3, v2, v2
	v_cndmask_b32_e32 v2, v3, v4, vcc
	v_add_f32_e32 v3, v8, v80
	v_mul_f32_e32 v2, v2, v3
	v_cvt_pk_bf16_f32 v4, v2, s0
	v_lshlrev_b64 v[2:3], 11, v[150:151]
	v_lshl_add_u64 v[2:3], v[106:107], 0, v[2:3]
	global_store_short v[2:3], v4, off sc1
	s_waitcnt vmcnt(53)
	v_lshlrev_b32_e32 v2, 16, v180
	v_fma_f32 v3, |v2|, s92, 1.0
	v_rcp_f32_e32 v3, v3
	v_cmp_gt_f32_e32 vcc, 0, v2
	v_add_u32_e32 v150, 0x67, v94
	v_mad_i64_i32 v[180:181], s[6:7], v164, s87, v[92:93]
	v_fmamk_f32 v4, v3, 0x3f07dc22, v236
	v_fmaak_f32 v4, v3, v4, 0x3f35f0e3
	v_fmaak_f32 v4, v3, v4, 0xbe11a98e
	v_fmaak_f32 v4, v3, v4, 0x3e027906
	v_mul_f32_e32 v3, v3, v4
	v_mul_f32_e32 v4, v2, v2
	v_mul_f32_e32 v4, 0xbf38aa3b, v4
	v_exp_f32_e32 v4, v4
	v_ashrrev_i32_e32 v151, 31, v150
	v_mul_f32_e32 v3, v4, v3
	v_mul_f32_e32 v4, v3, v2
	v_fma_f32 v3, -v3, v2, v2
	v_cndmask_b32_e32 v2, v3, v4, vcc
	v_add_f32_e32 v3, v9, v81
	v_mul_f32_e32 v2, v2, v3
	v_cvt_pk_bf16_f32 v4, v2, s0
	v_lshlrev_b64 v[2:3], 11, v[148:149]
	v_lshl_add_u64 v[2:3], v[106:107], 0, v[2:3]
	global_store_short v[2:3], v4, off sc1
	s_waitcnt vmcnt(53)
	v_lshlrev_b32_e32 v2, 16, v179
	v_fma_f32 v3, |v2|, s92, 1.0
	v_rcp_f32_e32 v3, v3
	v_cmp_gt_f32_e32 vcc, 0, v2
	v_add_u32_e32 v148, 0x62, v94
	v_mad_i64_i32 v[8:9], s[6:7], v148, s87, v[92:93]
	v_fmamk_f32 v4, v3, 0x3f07dc22, v236
	v_fmaak_f32 v4, v3, v4, 0x3f35f0e3
	v_fmaak_f32 v4, v3, v4, 0xbe11a98e
	v_fmaak_f32 v4, v3, v4, 0x3e027906
	v_mul_f32_e32 v3, v3, v4
	v_mul_f32_e32 v4, v2, v2
	v_mul_f32_e32 v4, 0xbf38aa3b, v4
	v_exp_f32_e32 v4, v4
	v_ashrrev_i32_e32 v149, 31, v148
	v_mul_f32_e32 v3, v4, v3
	v_mul_f32_e32 v4, v3, v2
	v_fma_f32 v3, -v3, v2, v2
	v_cndmask_b32_e32 v6, v3, v4, vcc
	ds_read_b128 v[2:5], v1 offset:192
	s_waitcnt lgkmcnt(0)
	v_add_f32_e32 v2, v10, v2
	v_mul_f32_e32 v2, v6, v2
	v_lshlrev_b64 v[6:7], 11, v[146:147]
	v_cvt_pk_bf16_f32 v2, v2, s0
	v_lshl_add_u64 v[6:7], v[106:107], 0, v[6:7]
	global_store_short v[6:7], v2, off sc1
	s_waitcnt vmcnt(53)
	v_lshlrev_b32_e32 v2, 16, v178
	v_fma_f32 v6, |v2|, s92, 1.0
	v_rcp_f32_e32 v6, v6
	v_cmp_gt_f32_e32 vcc, 0, v2
	v_add_f32_e32 v3, v11, v3
	v_add_u32_e32 v146, 0x68, v94
	v_fmamk_f32 v7, v6, 0x3f07dc22, v236
	v_fmaak_f32 v7, v6, v7, 0x3f35f0e3
	v_fmaak_f32 v7, v6, v7, 0xbe11a98e
	v_fmaak_f32 v7, v6, v7, 0x3e027906
	v_mul_f32_e32 v6, v6, v7
	v_mul_f32_e32 v7, v2, v2
	v_mul_f32_e32 v7, 0xbf38aa3b, v7
	v_exp_f32_e32 v7, v7
	v_mad_i64_i32 v[10:11], s[6:7], v150, s87, v[92:93]
	v_mad_i64_i32 v[178:179], s[6:7], v166, s87, v[92:93]
	v_mul_f32_e32 v6, v7, v6
	v_mul_f32_e32 v7, v6, v2
	v_fma_f32 v6, -v6, v2, v2
	v_cndmask_b32_e32 v2, v6, v7, vcc
	v_mul_f32_e32 v2, v2, v3
	v_cvt_pk_bf16_f32 v6, v2, s0
	v_lshlrev_b64 v[2:3], 11, v[144:145]
	v_lshl_add_u64 v[2:3], v[106:107], 0, v[2:3]
	global_store_short v[2:3], v6, off sc1
	s_waitcnt vmcnt(53)
	v_lshlrev_b32_e32 v2, 16, v177
	v_fma_f32 v3, |v2|, s92, 1.0
	v_rcp_f32_e32 v3, v3
	v_cmp_gt_f32_e32 vcc, 0, v2
	v_add_u32_e32 v144, 0x69, v94
	v_ashrrev_i32_e32 v147, 31, v146
	v_fmamk_f32 v6, v3, 0x3f07dc22, v236
	v_fmaak_f32 v6, v3, v6, 0x3f35f0e3
	v_fmaak_f32 v6, v3, v6, 0xbe11a98e
	v_fmaak_f32 v6, v3, v6, 0x3e027906
	v_mul_f32_e32 v3, v3, v6
	v_mul_f32_e32 v6, v2, v2
	v_mul_f32_e32 v6, 0xbf38aa3b, v6
	v_exp_f32_e32 v6, v6
	v_ashrrev_i32_e32 v145, 31, v144
	v_mul_f32_e32 v3, v6, v3
	v_mul_f32_e32 v6, v3, v2
	v_fma_f32 v3, -v3, v2, v2
	v_cndmask_b32_e32 v2, v3, v6, vcc
	v_add_f32_e32 v3, v12, v4
	v_mul_f32_e32 v2, v2, v3
	v_cvt_pk_bf16_f32 v4, v2, s0
	v_lshlrev_b64 v[2:3], 11, v[142:143]
	v_lshl_add_u64 v[2:3], v[106:107], 0, v[2:3]
	global_store_short v[2:3], v4, off sc1
	s_waitcnt vmcnt(53)
	v_lshlrev_b32_e32 v2, 16, v176
	v_fma_f32 v3, |v2|, s92, 1.0
	v_rcp_f32_e32 v3, v3
	v_cmp_gt_f32_e32 vcc, 0, v2
	v_add_u32_e32 v142, 0x5f, v94
	v_mad_i64_i32 v[176:177], s[6:7], v168, s87, v[92:93]
	v_fmamk_f32 v4, v3, 0x3f07dc22, v236
	v_fmaak_f32 v4, v3, v4, 0x3f35f0e3
	v_fmaak_f32 v4, v3, v4, 0xbe11a98e
	v_fmaak_f32 v4, v3, v4, 0x3e027906
	v_mul_f32_e32 v3, v3, v4
	v_mul_f32_e32 v4, v2, v2
	v_mul_f32_e32 v4, 0xbf38aa3b, v4
	v_exp_f32_e32 v4, v4
	v_ashrrev_i32_e32 v143, 31, v142
	v_mul_f32_e32 v3, v4, v3
	v_mul_f32_e32 v4, v3, v2
	v_fma_f32 v3, -v3, v2, v2
	v_cndmask_b32_e32 v2, v3, v4, vcc
	v_add_f32_e32 v3, v13, v5
	v_mul_f32_e32 v2, v2, v3
	v_cvt_pk_bf16_f32 v4, v2, s0
	v_lshlrev_b64 v[2:3], 11, v[104:105]
	v_lshl_add_u64 v[2:3], v[106:107], 0, v[2:3]
	global_store_short v[2:3], v4, off sc1
	s_waitcnt vmcnt(53)
	v_lshlrev_b32_e32 v2, 16, v175
	v_fma_f32 v3, |v2|, s92, 1.0
	v_rcp_f32_e32 v3, v3
	v_cmp_gt_f32_e32 vcc, 0, v2
	v_mad_i64_i32 v[12:13], s[6:7], v146, s87, v[92:93]
	v_fmamk_f32 v4, v3, 0x3f07dc22, v236
	v_fmaak_f32 v4, v3, v4, 0x3f35f0e3
	v_fmaak_f32 v4, v3, v4, 0xbe11a98e
	v_fmaak_f32 v4, v3, v4, 0x3e027906
	v_mul_f32_e32 v3, v3, v4
	v_mul_f32_e32 v4, v2, v2
	v_mul_f32_e32 v4, 0xbf38aa3b, v4
	v_exp_f32_e32 v4, v4
	s_nop 0
	v_mul_f32_e32 v3, v4, v3
	v_mul_f32_e32 v4, v3, v2
	v_fma_f32 v3, -v3, v2, v2
	v_cndmask_b32_e32 v6, v3, v4, vcc
	ds_read_b128 v[2:5], v1 offset:224
	s_waitcnt lgkmcnt(0)
	v_add_f32_e32 v2, v14, v2
	v_mul_f32_e32 v2, v6, v2
	v_lshlrev_b64 v[6:7], 11, v[102:103]
	v_cvt_pk_bf16_f32 v2, v2, s0
	v_lshl_add_u64 v[6:7], v[106:107], 0, v[6:7]
	global_store_short v[6:7], v2, off sc1
	s_waitcnt vmcnt(53)
	v_lshlrev_b32_e32 v2, 16, v174
	v_fma_f32 v6, |v2|, s92, 1.0
	v_rcp_f32_e32 v6, v6
	v_cmp_gt_f32_e32 vcc, 0, v2
	v_add_f32_e32 v3, v15, v3
	v_mad_i64_i32 v[14:15], s[6:7], v144, s87, v[92:93]
	v_fmamk_f32 v7, v6, 0x3f07dc22, v236
	v_fmaak_f32 v7, v6, v7, 0x3f35f0e3
	v_fmaak_f32 v7, v6, v7, 0xbe11a98e
	v_fmaak_f32 v7, v6, v7, 0x3e027906
	v_mul_f32_e32 v6, v6, v7
	v_mul_f32_e32 v7, v2, v2
	v_mul_f32_e32 v7, 0xbf38aa3b, v7
	v_exp_f32_e32 v7, v7
	v_mad_i64_i32 v[174:175], s[6:7], v170, s87, v[92:93]
	v_mul_f32_e32 v6, v7, v6
	v_mul_f32_e32 v7, v6, v2
	v_fma_f32 v6, -v6, v2, v2
	v_cndmask_b32_e32 v2, v6, v7, vcc
	v_mul_f32_e32 v2, v2, v3
	v_cvt_pk_bf16_f32 v6, v2, s0
	v_lshlrev_b64 v[2:3], 11, v[100:101]
	v_lshl_add_u64 v[2:3], v[106:107], 0, v[2:3]
	global_store_short v[2:3], v6, off sc1
	s_waitcnt vmcnt(53)
	v_lshlrev_b32_e32 v2, 16, v173
	v_fma_f32 v3, |v2|, s92, 1.0
	v_rcp_f32_e32 v3, v3
	v_cmp_gt_f32_e32 vcc, 0, v2
	v_fmamk_f32 v6, v3, 0x3f07dc22, v236
	v_fmaak_f32 v6, v3, v6, 0x3f35f0e3
	v_fmaak_f32 v6, v3, v6, 0xbe11a98e
	v_fmaak_f32 v6, v3, v6, 0x3e027906
	v_mul_f32_e32 v3, v3, v6
	v_mul_f32_e32 v6, v2, v2
	v_mul_f32_e32 v6, 0xbf38aa3b, v6
	v_exp_f32_e32 v6, v6
	s_nop 0
	v_mul_f32_e32 v3, v6, v3
	v_mul_f32_e32 v6, v3, v2
	v_fma_f32 v3, -v3, v2, v2
	v_cndmask_b32_e32 v2, v3, v6, vcc
	v_add_f32_e32 v3, v16, v4
	v_mul_f32_e32 v2, v2, v3
	v_cvt_pk_bf16_f32 v4, v2, s0
	v_lshlrev_b64 v[2:3], 11, v[98:99]
	v_lshl_add_u64 v[2:3], v[106:107], 0, v[2:3]
	global_store_short v[2:3], v4, off sc1
	s_waitcnt vmcnt(53)
	v_lshlrev_b32_e32 v2, 16, v172
	v_fma_f32 v3, |v2|, s92, 1.0
	v_rcp_f32_e32 v3, v3
	v_cmp_gt_f32_e32 vcc, 0, v2
	v_add_u32_e32 v172, 0x6a, v94
	v_mad_i64_i32 v[6:7], s[6:7], v152, s87, v[92:93]
	v_fmamk_f32 v4, v3, 0x3f07dc22, v236
	v_fmaak_f32 v4, v3, v4, 0x3f35f0e3
	v_fmaak_f32 v4, v3, v4, 0xbe11a98e
	v_fmaak_f32 v4, v3, v4, 0x3e027906
	v_mul_f32_e32 v3, v3, v4
	v_mul_f32_e32 v4, v2, v2
	v_mul_f32_e32 v4, 0xbf38aa3b, v4
	v_exp_f32_e32 v4, v4
	v_ashrrev_i32_e32 v173, 31, v172
	v_mul_f32_e32 v3, v4, v3
	v_mul_f32_e32 v4, v3, v2
	v_fma_f32 v3, -v3, v2, v2
	v_cndmask_b32_e32 v2, v3, v4, vcc
	v_add_f32_e32 v3, v17, v5
	v_mul_f32_e32 v2, v2, v3
	v_cvt_pk_bf16_f32 v4, v2, s0
	v_lshlrev_b64 v[2:3], 11, v[96:97]
	v_add_co_u32_e32 v86, vcc, s5, v90
	v_lshl_add_u64 v[2:3], v[106:107], 0, v[2:3]
	s_nop 0
	v_addc_co_u32_e32 v87, vcc, 0, v91, vcc
	global_store_short v[2:3], v4, off sc1
	v_add_co_u32_e32 v102, vcc, s97, v90
	v_mad_i64_i32 v[2:3], s[6:7], v142, s87, v[92:93]
	v_mad_i64_i32 v[4:5], s[6:7], v154, s87, v[92:93]
	v_mad_i64_i32 v[16:17], s[6:7], v172, s87, v[92:93]
	v_addc_co_u32_e32 v103, vcc, 0, v91, vcc
	global_load_dwordx4 v[74:77], v[102:103], off offset:-4096
	global_load_dwordx4 v[78:81], v[86:87], off offset:1024
	global_load_dwordx4 v[82:85], v[86:87], off offset:2048
	s_nop 0
	global_load_dwordx4 v[86:89], v[86:87], off offset:3072
	s_nop 0
	global_load_dwordx4 v[90:93], v[102:103], off
	global_load_dwordx4 v[94:97], v[102:103], off offset:1024
	global_load_dwordx4 v[98:101], v[102:103], off offset:2048
	s_nop 0
	global_load_dwordx4 v[102:105], v[102:103], off offset:3072
	s_nop 0
	global_load_ushort v212, v[2:3], off
	global_load_ushort v211, v[4:5], off
	global_load_ushort v210, v[6:7], off
	global_load_ushort v209, v[8:9], off
	global_load_ushort v208, v[10:11], off
	global_load_ushort v207, v[12:13], off
	global_load_ushort v206, v[14:15], off
	global_load_ushort v205, v[16:17], off
	global_load_ushort v204, v[174:175], off
	global_load_ushort v203, v[176:177], off
	s_nop 0
	global_load_ushort v179, v[178:179], off
	s_nop 0
	global_load_ushort v178, v[180:181], off
	global_load_ushort v177, v[182:183], off
	global_load_ushort v176, v[184:185], off
	global_load_ushort v175, v[186:187], off
	global_load_ushort v174, v[214:215], off
	s_waitcnt vmcnt(61)
	v_mfma_f32_32x32x16_bf16 v[2:17], v[50:53], v[18:21], 0
	s_waitcnt vmcnt(55)
	v_lshlrev_b32_e32 v50, 16, v202
	v_fma_f32 v51, |v50|, s92, 1.0
	v_rcp_f32_e32 v51, v51
	v_cmp_gt_f32_e32 vcc, 0, v50
	v_readlane_b32 s6, v254, 27
	v_fmamk_f32 v52, v51, 0x3f07dc22, v236
	v_mfma_f32_32x32x16_bf16 v[2:17], v[54:57], v[22:25], v[2:17]
	v_fmaak_f32 v52, v51, v52, 0x3f35f0e3
	v_fmaak_f32 v52, v51, v52, 0xbe11a98e
	v_fmaak_f32 v52, v51, v52, 0x3e027906
	v_mul_f32_e32 v51, v51, v52
	v_mul_f32_e32 v52, v50, v50
	v_mul_f32_e32 v52, 0xbf38aa3b, v52
	v_exp_f32_e32 v52, v52
	v_mfma_f32_32x32x16_bf16 v[2:17], v[58:61], v[26:29], v[2:17]
	v_readlane_b32 s5, v254, 33
	s_add_i32 s6, s6, s19
	v_mul_f32_e32 v51, v52, v51
	v_mul_f32_e32 v52, v51, v50
	v_fma_f32 v51, -v51, v50, v50
	v_cndmask_b32_e32 v58, v51, v52, vcc
	ds_read_b128 v[54:57], v1 offset:256
	ds_read_b128 v[50:53], v1 offset:288
	v_mfma_f32_32x32x16_bf16 v[2:17], v[62:65], v[30:33], v[2:17]
	s_add_i32 s17, s17, s5
	s_cmpk_gt_i32 s6, 0xff
	v_mfma_f32_32x32x16_bf16 v[2:17], v[66:69], v[34:37], v[2:17]
	v_mfma_f32_32x32x16_bf16 v[2:17], v[70:73], v[38:41], v[2:17]
	s_waitcnt lgkmcnt(1)
	s_nop 10
	v_add_f32_e32 v2, v2, v54
	v_mul_f32_e32 v2, v58, v2
	v_lshlrev_b64 v[58:59], 11, v[140:141]
	v_cvt_pk_bf16_f32 v2, v2, s0
	v_lshl_add_u64 v[58:59], v[106:107], 0, v[58:59]
	global_store_short v[58:59], v2, off sc1
	s_waitcnt vmcnt(55)
	v_lshlrev_b32_e32 v2, 16, v201
	v_fma_f32 v54, |v2|, s92, 1.0
	v_rcp_f32_e32 v54, v54
	v_cmp_gt_f32_e32 vcc, 0, v2
	v_add_f32_e32 v3, v3, v55
	v_fmamk_f32 v58, v54, 0x3f07dc22, v236
	v_fmaak_f32 v58, v54, v58, 0x3f35f0e3
	v_fmaak_f32 v58, v54, v58, 0xbe11a98e
	v_fmaak_f32 v58, v54, v58, 0x3e027906
	v_mul_f32_e32 v54, v54, v58
	v_mul_f32_e32 v58, v2, v2
	v_mul_f32_e32 v58, 0xbf38aa3b, v58
	v_exp_f32_e32 v58, v58
	s_nop 0
	v_mul_f32_e32 v54, v58, v54
	v_mul_f32_e32 v58, v54, v2
	v_fma_f32 v54, -v54, v2, v2
	v_cndmask_b32_e32 v2, v54, v58, vcc
	v_mul_f32_e32 v2, v2, v3
	v_cvt_pk_bf16_f32 v54, v2, s0
	v_lshlrev_b64 v[2:3], 11, v[138:139]
	v_lshl_add_u64 v[2:3], v[106:107], 0, v[2:3]
	global_store_short v[2:3], v54, off sc1
	s_waitcnt vmcnt(55)
	v_lshlrev_b32_e32 v2, 16, v200
	v_fma_f32 v3, |v2|, s92, 1.0
	v_rcp_f32_e32 v3, v3
	v_cmp_gt_f32_e32 vcc, 0, v2
	v_fmamk_f32 v54, v3, 0x3f07dc22, v236
	v_fmaak_f32 v54, v3, v54, 0x3f35f0e3
	v_fmaak_f32 v54, v3, v54, 0xbe11a98e
	v_fmaak_f32 v54, v3, v54, 0x3e027906
	v_mul_f32_e32 v3, v3, v54
	v_mul_f32_e32 v54, v2, v2
	v_mul_f32_e32 v54, 0xbf38aa3b, v54
	v_exp_f32_e32 v54, v54
	s_nop 0
	v_mul_f32_e32 v3, v54, v3
	v_mul_f32_e32 v54, v3, v2
	v_fma_f32 v3, -v3, v2, v2
	v_cndmask_b32_e32 v2, v3, v54, vcc
	v_add_f32_e32 v3, v4, v56
	v_mul_f32_e32 v2, v2, v3
	v_cvt_pk_bf16_f32 v4, v2, s0
	v_lshlrev_b64 v[2:3], 11, v[136:137]
	v_lshl_add_u64 v[2:3], v[106:107], 0, v[2:3]
	global_store_short v[2:3], v4, off sc1
	s_waitcnt vmcnt(55)
	v_lshlrev_b32_e32 v2, 16, v199
	v_fma_f32 v3, |v2|, s92, 1.0
	v_rcp_f32_e32 v3, v3
	v_cmp_gt_f32_e32 vcc, 0, v2
	v_fmamk_f32 v4, v3, 0x3f07dc22, v236
	v_fmaak_f32 v4, v3, v4, 0x3f35f0e3
	v_fmaak_f32 v4, v3, v4, 0xbe11a98e
	v_fmaak_f32 v4, v3, v4, 0x3e027906
	v_mul_f32_e32 v3, v3, v4
	v_mul_f32_e32 v4, v2, v2
	v_mul_f32_e32 v4, 0xbf38aa3b, v4
	v_exp_f32_e32 v4, v4
	s_nop 0
	v_mul_f32_e32 v3, v4, v3
	v_mul_f32_e32 v4, v3, v2
	v_fma_f32 v3, -v3, v2, v2
	v_cndmask_b32_e32 v2, v3, v4, vcc
	v_add_f32_e32 v3, v5, v57
	v_mul_f32_e32 v2, v2, v3
	v_cvt_pk_bf16_f32 v4, v2, s0
	v_lshlrev_b64 v[2:3], 11, v[134:135]
	v_lshl_add_u64 v[2:3], v[106:107], 0, v[2:3]
	global_store_short v[2:3], v4, off sc1
	s_waitcnt vmcnt(55)
	v_lshlrev_b32_e32 v2, 16, v198
	v_fma_f32 v3, |v2|, s92, 1.0
	v_rcp_f32_e32 v3, v3
	v_cmp_gt_f32_e32 vcc, 0, v2
	v_fmamk_f32 v4, v3, 0x3f07dc22, v236
	v_fmaak_f32 v4, v3, v4, 0x3f35f0e3
	v_fmaak_f32 v4, v3, v4, 0xbe11a98e
	v_fmaak_f32 v4, v3, v4, 0x3e027906
	v_mul_f32_e32 v3, v3, v4
	v_mul_f32_e32 v4, v2, v2
	v_mul_f32_e32 v4, 0xbf38aa3b, v4
	v_exp_f32_e32 v4, v4
	s_nop 0
	v_mul_f32_e32 v3, v4, v3
	v_mul_f32_e32 v4, v3, v2
	v_fma_f32 v3, -v3, v2, v2
	v_cndmask_b32_e32 v2, v3, v4, vcc
	s_waitcnt lgkmcnt(0)
	v_add_f32_e32 v3, v6, v50
	v_mul_f32_e32 v2, v2, v3
	v_cvt_pk_bf16_f32 v4, v2, s0
	v_lshlrev_b64 v[2:3], 11, v[132:133]
	v_lshl_add_u64 v[2:3], v[106:107], 0, v[2:3]
	global_store_short v[2:3], v4, off sc1
	s_waitcnt vmcnt(55)
	v_lshlrev_b32_e32 v2, 16, v197
	v_fma_f32 v3, |v2|, s92, 1.0
	v_rcp_f32_e32 v3, v3
	v_cmp_gt_f32_e32 vcc, 0, v2
	v_fmamk_f32 v4, v3, 0x3f07dc22, v236
	v_fmaak_f32 v4, v3, v4, 0x3f35f0e3
	v_fmaak_f32 v4, v3, v4, 0xbe11a98e
	v_fmaak_f32 v4, v3, v4, 0x3e027906
	v_mul_f32_e32 v3, v3, v4
	v_mul_f32_e32 v4, v2, v2
	v_mul_f32_e32 v4, 0xbf38aa3b, v4
	v_exp_f32_e32 v4, v4
	s_nop 0
	v_mul_f32_e32 v3, v4, v3
	v_mul_f32_e32 v4, v3, v2
	v_fma_f32 v3, -v3, v2, v2
	v_cndmask_b32_e32 v2, v3, v4, vcc
	v_add_f32_e32 v3, v7, v51
	v_mul_f32_e32 v2, v2, v3
	v_cvt_pk_bf16_f32 v4, v2, s0
	v_lshlrev_b64 v[2:3], 11, v[126:127]
	v_lshl_add_u64 v[2:3], v[106:107], 0, v[2:3]
	global_store_short v[2:3], v4, off sc1
	s_waitcnt vmcnt(55)
	v_lshlrev_b32_e32 v2, 16, v196
	v_fma_f32 v3, |v2|, s92, 1.0
	v_rcp_f32_e32 v3, v3
	v_cmp_gt_f32_e32 vcc, 0, v2
	v_fmamk_f32 v4, v3, 0x3f07dc22, v236
	v_fmaak_f32 v4, v3, v4, 0x3f35f0e3
	v_fmaak_f32 v4, v3, v4, 0xbe11a98e
	v_fmaak_f32 v4, v3, v4, 0x3e027906
	v_mul_f32_e32 v3, v3, v4
	v_mul_f32_e32 v4, v2, v2
	v_mul_f32_e32 v4, 0xbf38aa3b, v4
	v_exp_f32_e32 v4, v4
	s_nop 0
	v_mul_f32_e32 v3, v4, v3
	v_mul_f32_e32 v4, v3, v2
	v_fma_f32 v3, -v3, v2, v2
	v_cndmask_b32_e32 v2, v3, v4, vcc
	v_add_f32_e32 v3, v8, v52
	v_mul_f32_e32 v2, v2, v3
	v_cvt_pk_bf16_f32 v4, v2, s0
	v_lshlrev_b64 v[2:3], 11, v[122:123]
	v_lshl_add_u64 v[2:3], v[106:107], 0, v[2:3]
	global_store_short v[2:3], v4, off sc1
	s_waitcnt vmcnt(55)
	v_lshlrev_b32_e32 v2, 16, v195
	v_fma_f32 v3, |v2|, s92, 1.0
	v_rcp_f32_e32 v3, v3
	v_cmp_gt_f32_e32 vcc, 0, v2
	v_fmamk_f32 v4, v3, 0x3f07dc22, v236
	v_fmaak_f32 v4, v3, v4, 0x3f35f0e3
	v_fmaak_f32 v4, v3, v4, 0xbe11a98e
	v_fmaak_f32 v4, v3, v4, 0x3e027906
	v_mul_f32_e32 v3, v3, v4
	v_mul_f32_e32 v4, v2, v2
	v_mul_f32_e32 v4, 0xbf38aa3b, v4
	v_exp_f32_e32 v4, v4
	s_nop 0
	v_mul_f32_e32 v3, v4, v3
	v_mul_f32_e32 v4, v3, v2
	v_fma_f32 v3, -v3, v2, v2
	v_cndmask_b32_e32 v2, v3, v4, vcc
	v_add_f32_e32 v3, v9, v53
	v_mul_f32_e32 v2, v2, v3
	v_cvt_pk_bf16_f32 v4, v2, s0
	v_lshlrev_b64 v[2:3], 11, v[118:119]
	v_lshl_add_u64 v[2:3], v[106:107], 0, v[2:3]
	global_store_short v[2:3], v4, off sc1
	s_waitcnt vmcnt(55)
	v_lshlrev_b32_e32 v2, 16, v194
	v_fma_f32 v3, |v2|, s92, 1.0
	v_rcp_f32_e32 v3, v3
	v_cmp_gt_f32_e32 vcc, 0, v2
	v_fmamk_f32 v4, v3, 0x3f07dc22, v236
	v_fmaak_f32 v4, v3, v4, 0x3f35f0e3
	v_fmaak_f32 v4, v3, v4, 0xbe11a98e
	v_fmaak_f32 v4, v3, v4, 0x3e027906
	v_mul_f32_e32 v3, v3, v4
	v_mul_f32_e32 v4, v2, v2
	v_mul_f32_e32 v4, 0xbf38aa3b, v4
	v_exp_f32_e32 v4, v4
	s_nop 0
	v_mul_f32_e32 v3, v4, v3
	v_mul_f32_e32 v4, v3, v2
	v_fma_f32 v3, -v3, v2, v2
	v_cndmask_b32_e32 v6, v3, v4, vcc
	ds_read_b128 v[2:5], v1 offset:320
	s_waitcnt lgkmcnt(0)
	v_add_f32_e32 v2, v10, v2
	v_mul_f32_e32 v2, v6, v2
	v_lshlrev_b64 v[6:7], 11, v[116:117]
	v_cvt_pk_bf16_f32 v2, v2, s0
	v_lshl_add_u64 v[6:7], v[106:107], 0, v[6:7]
	global_store_short v[6:7], v2, off sc1
	s_waitcnt vmcnt(55)
	v_lshlrev_b32_e32 v2, 16, v193
	v_fma_f32 v6, |v2|, s92, 1.0
	v_rcp_f32_e32 v6, v6
	v_cmp_gt_f32_e32 vcc, 0, v2
	v_add_f32_e32 v3, v11, v3
	v_fmamk_f32 v7, v6, 0x3f07dc22, v236
	v_fmaak_f32 v7, v6, v7, 0x3f35f0e3
	v_fmaak_f32 v7, v6, v7, 0xbe11a98e
	v_fmaak_f32 v7, v6, v7, 0x3e027906
	v_mul_f32_e32 v6, v6, v7
	v_mul_f32_e32 v7, v2, v2
	v_mul_f32_e32 v7, 0xbf38aa3b, v7
	v_exp_f32_e32 v7, v7
	s_nop 0
	v_mul_f32_e32 v6, v7, v6
	v_mul_f32_e32 v7, v6, v2
	v_fma_f32 v6, -v6, v2, v2
	v_cndmask_b32_e32 v2, v6, v7, vcc
	v_mul_f32_e32 v2, v2, v3
	v_cvt_pk_bf16_f32 v6, v2, s0
	v_lshlrev_b64 v[2:3], 11, v[112:113]
	v_lshl_add_u64 v[2:3], v[106:107], 0, v[2:3]
	global_store_short v[2:3], v6, off sc1
	s_waitcnt vmcnt(55)
	v_lshlrev_b32_e32 v2, 16, v192
	v_fma_f32 v3, |v2|, s92, 1.0
	v_rcp_f32_e32 v3, v3
	v_cmp_gt_f32_e32 vcc, 0, v2
	v_fmamk_f32 v6, v3, 0x3f07dc22, v236
	v_fmaak_f32 v6, v3, v6, 0x3f35f0e3
	v_fmaak_f32 v6, v3, v6, 0xbe11a98e
	v_fmaak_f32 v6, v3, v6, 0x3e027906
	v_mul_f32_e32 v3, v3, v6
	v_mul_f32_e32 v6, v2, v2
	v_mul_f32_e32 v6, 0xbf38aa3b, v6
	v_exp_f32_e32 v6, v6
	s_nop 0
	v_mul_f32_e32 v3, v6, v3
	v_mul_f32_e32 v6, v3, v2
	v_fma_f32 v3, -v3, v2, v2
	v_cndmask_b32_e32 v2, v3, v6, vcc
	v_add_f32_e32 v3, v12, v4
	v_mul_f32_e32 v2, v2, v3
	v_cvt_pk_bf16_f32 v4, v2, s0
	v_lshlrev_b64 v[2:3], 11, v[110:111]
	v_lshl_add_u64 v[2:3], v[106:107], 0, v[2:3]
	global_store_short v[2:3], v4, off sc1
	s_waitcnt vmcnt(55)
	v_lshlrev_b32_e32 v2, 16, v191
	v_fma_f32 v3, |v2|, s92, 1.0
	v_rcp_f32_e32 v3, v3
	v_cmp_gt_f32_e32 vcc, 0, v2
	v_fmamk_f32 v4, v3, 0x3f07dc22, v236
	v_fmaak_f32 v4, v3, v4, 0x3f35f0e3
	v_fmaak_f32 v4, v3, v4, 0xbe11a98e
	v_fmaak_f32 v4, v3, v4, 0x3e027906
	v_mul_f32_e32 v3, v3, v4
	v_mul_f32_e32 v4, v2, v2
	v_mul_f32_e32 v4, 0xbf38aa3b, v4
	v_exp_f32_e32 v4, v4
	s_nop 0
	v_mul_f32_e32 v3, v4, v3
	v_mul_f32_e32 v4, v3, v2
	v_fma_f32 v3, -v3, v2, v2
	v_cndmask_b32_e32 v2, v3, v4, vcc
	v_add_f32_e32 v3, v13, v5
	v_mul_f32_e32 v2, v2, v3
	v_cvt_pk_bf16_f32 v4, v2, s0
	v_lshlrev_b64 v[2:3], 11, v[108:109]
	v_lshl_add_u64 v[2:3], v[106:107], 0, v[2:3]
	global_store_short v[2:3], v4, off sc1
	s_waitcnt vmcnt(55)
	v_lshlrev_b32_e32 v2, 16, v190
	v_fma_f32 v3, |v2|, s92, 1.0
	v_rcp_f32_e32 v3, v3
	v_cmp_gt_f32_e32 vcc, 0, v2
	v_fmamk_f32 v4, v3, 0x3f07dc22, v236
	v_fmaak_f32 v4, v3, v4, 0x3f35f0e3
	v_fmaak_f32 v4, v3, v4, 0xbe11a98e
	v_fmaak_f32 v4, v3, v4, 0x3e027906
	v_mul_f32_e32 v3, v3, v4
	v_mul_f32_e32 v4, v2, v2
	v_mul_f32_e32 v4, 0xbf38aa3b, v4
	v_exp_f32_e32 v4, v4
	s_nop 0
	v_mul_f32_e32 v3, v4, v3
	v_mul_f32_e32 v4, v3, v2
	v_fma_f32 v3, -v3, v2, v2
	v_cndmask_b32_e32 v6, v3, v4, vcc
	ds_read_b128 v[2:5], v1 offset:352
	s_waitcnt lgkmcnt(0)
	v_add_f32_e32 v2, v14, v2
	v_mul_f32_e32 v2, v6, v2
	v_lshlrev_b64 v[6:7], 11, v[128:129]
	v_cvt_pk_bf16_f32 v2, v2, s0
	v_lshl_add_u64 v[6:7], v[106:107], 0, v[6:7]
	global_store_short v[6:7], v2, off sc1
	s_waitcnt vmcnt(55)
	v_lshlrev_b32_e32 v2, 16, v189
	v_fma_f32 v6, |v2|, s92, 1.0
	v_rcp_f32_e32 v6, v6
	v_cmp_gt_f32_e32 vcc, 0, v2
	v_add_f32_e32 v3, v15, v3
	v_fmamk_f32 v7, v6, 0x3f07dc22, v236
	v_fmaak_f32 v7, v6, v7, 0x3f35f0e3
	v_fmaak_f32 v7, v6, v7, 0xbe11a98e
	v_fmaak_f32 v7, v6, v7, 0x3e027906
	v_mul_f32_e32 v6, v6, v7
	v_mul_f32_e32 v7, v2, v2
	v_mul_f32_e32 v7, 0xbf38aa3b, v7
	v_exp_f32_e32 v7, v7
	s_nop 0
	v_mul_f32_e32 v6, v7, v6
	v_mul_f32_e32 v7, v6, v2
	v_fma_f32 v6, -v6, v2, v2
	v_cndmask_b32_e32 v2, v6, v7, vcc
	v_mul_f32_e32 v2, v2, v3
	v_cvt_pk_bf16_f32 v6, v2, s0
	v_lshlrev_b64 v[2:3], 11, v[124:125]
	v_lshl_add_u64 v[2:3], v[106:107], 0, v[2:3]
	global_store_short v[2:3], v6, off sc1
	s_waitcnt vmcnt(55)
	v_lshlrev_b32_e32 v2, 16, v188
	v_fma_f32 v3, |v2|, s92, 1.0
	v_rcp_f32_e32 v3, v3
	v_cmp_gt_f32_e32 vcc, 0, v2
	v_fmamk_f32 v6, v3, 0x3f07dc22, v236
	v_fmaak_f32 v6, v3, v6, 0x3f35f0e3
	v_fmaak_f32 v6, v3, v6, 0xbe11a98e
	v_fmaak_f32 v6, v3, v6, 0x3e027906
	v_mul_f32_e32 v3, v3, v6
	v_mul_f32_e32 v6, v2, v2
	v_mul_f32_e32 v6, 0xbf38aa3b, v6
	v_exp_f32_e32 v6, v6
	s_nop 0
	v_mul_f32_e32 v3, v6, v3
	v_mul_f32_e32 v6, v3, v2
	v_fma_f32 v3, -v3, v2, v2
	v_cndmask_b32_e32 v2, v3, v6, vcc
	v_add_f32_e32 v3, v16, v4
	v_mul_f32_e32 v2, v2, v3
	v_cvt_pk_bf16_f32 v4, v2, s0
	v_lshlrev_b64 v[2:3], 11, v[120:121]
	v_lshl_add_u64 v[2:3], v[106:107], 0, v[2:3]
	global_store_short v[2:3], v4, off sc1
	s_waitcnt vmcnt(55)
	v_lshlrev_b32_e32 v2, 16, v130
	v_fma_f32 v3, |v2|, s92, 1.0
	v_rcp_f32_e32 v3, v3
	v_cmp_gt_f32_e32 vcc, 0, v2
	v_fmamk_f32 v4, v3, 0x3f07dc22, v236
	v_fmaak_f32 v4, v3, v4, 0x3f35f0e3
	v_fmaak_f32 v4, v3, v4, 0xbe11a98e
	v_fmaak_f32 v4, v3, v4, 0x3e027906
	v_mul_f32_e32 v3, v3, v4
	v_mul_f32_e32 v4, v2, v2
	v_mul_f32_e32 v4, 0xbf38aa3b, v4
	v_exp_f32_e32 v4, v4
	s_nop 0
	v_mul_f32_e32 v3, v4, v3
	v_mul_f32_e32 v4, v3, v2
	v_fma_f32 v3, -v3, v2, v2
	v_cndmask_b32_e32 v2, v3, v4, vcc
	v_add_f32_e32 v3, v17, v5
	v_mul_f32_e32 v2, v2, v3
	v_cvt_pk_bf16_f32 v4, v2, s0
	v_lshlrev_b64 v[2:3], 11, v[114:115]
	v_lshl_add_u64 v[2:3], v[106:107], 0, v[2:3]
	global_store_short v[2:3], v4, off sc1
	s_waitcnt vmcnt(39)
	v_mfma_f32_32x32x16_bf16 v[2:17], v[74:77], v[18:21], 0
	s_waitcnt vmcnt(31)
	v_lshlrev_b32_e32 v18, 16, v212
	v_fma_f32 v19, |v18|, s92, 1.0
	v_rcp_f32_e32 v19, v19
	v_cmp_gt_f32_e32 vcc, 0, v18
	v_fmamk_f32 v20, v19, 0x3f07dc22, v236
	v_mfma_f32_32x32x16_bf16 v[2:17], v[78:81], v[22:25], v[2:17]
	v_fmaak_f32 v20, v19, v20, 0x3f35f0e3
	v_fmaak_f32 v20, v19, v20, 0xbe11a98e
	v_fmaak_f32 v20, v19, v20, 0x3e027906
	v_mul_f32_e32 v19, v19, v20
	v_mul_f32_e32 v20, v18, v18
	v_mul_f32_e32 v20, 0xbf38aa3b, v20
	v_exp_f32_e32 v20, v20
	v_mfma_f32_32x32x16_bf16 v[2:17], v[82:85], v[26:29], v[2:17]
	v_mul_f32_e32 v19, v20, v19
	v_mul_f32_e32 v20, v19, v18
	v_fma_f32 v19, -v19, v18, v18
	v_cndmask_b32_e32 v26, v19, v20, vcc
	ds_read_b128 v[22:25], v1 offset:384
	ds_read_b128 v[18:21], v1 offset:416
	v_mfma_f32_32x32x16_bf16 v[2:17], v[86:89], v[30:33], v[2:17]
	v_mfma_f32_32x32x16_bf16 v[2:17], v[90:93], v[34:37], v[2:17]
	v_mfma_f32_32x32x16_bf16 v[2:17], v[94:97], v[38:41], v[2:17]
	v_mfma_f32_32x32x16_bf16 v[2:17], v[98:101], v[42:45], v[2:17]
	v_mfma_f32_32x32x16_bf16 v[2:17], v[102:105], v[46:49], v[2:17]
	s_waitcnt lgkmcnt(1)
	s_nop 10
	v_add_f32_e32 v2, v2, v22
	v_mul_f32_e32 v2, v26, v2
	v_lshlrev_b64 v[26:27], 11, v[142:143]
	v_cvt_pk_bf16_f32 v2, v2, s0
	v_lshl_add_u64 v[26:27], v[106:107], 0, v[26:27]
	global_store_short v[26:27], v2, off sc1
	s_waitcnt vmcnt(31)
	v_lshlrev_b32_e32 v2, 16, v211
	v_fma_f32 v22, |v2|, s92, 1.0
	v_rcp_f32_e32 v22, v22
	v_cmp_gt_f32_e32 vcc, 0, v2
	v_add_f32_e32 v3, v3, v23
	v_fmamk_f32 v26, v22, 0x3f07dc22, v236
	v_fmaak_f32 v26, v22, v26, 0x3f35f0e3
	v_fmaak_f32 v26, v22, v26, 0xbe11a98e
	v_fmaak_f32 v26, v22, v26, 0x3e027906
	v_mul_f32_e32 v22, v22, v26
	v_mul_f32_e32 v26, v2, v2
	v_mul_f32_e32 v26, 0xbf38aa3b, v26
	v_exp_f32_e32 v26, v26
	s_nop 0
	v_mul_f32_e32 v22, v26, v22
	v_mul_f32_e32 v26, v22, v2
	v_fma_f32 v22, -v22, v2, v2
	v_cndmask_b32_e32 v2, v22, v26, vcc
	v_mul_f32_e32 v2, v2, v3
	v_cvt_pk_bf16_f32 v22, v2, s0
	v_lshlrev_b64 v[2:3], 11, v[154:155]
	v_lshl_add_u64 v[2:3], v[106:107], 0, v[2:3]
	global_store_short v[2:3], v22, off sc1
	s_waitcnt vmcnt(31)
	v_lshlrev_b32_e32 v2, 16, v210
	v_fma_f32 v3, |v2|, s92, 1.0
	v_rcp_f32_e32 v3, v3
	v_cmp_gt_f32_e32 vcc, 0, v2
	v_fmamk_f32 v22, v3, 0x3f07dc22, v236
	v_fmaak_f32 v22, v3, v22, 0x3f35f0e3
	v_fmaak_f32 v22, v3, v22, 0xbe11a98e
	v_fmaak_f32 v22, v3, v22, 0x3e027906
	v_mul_f32_e32 v3, v3, v22
	v_mul_f32_e32 v22, v2, v2
	v_mul_f32_e32 v22, 0xbf38aa3b, v22
	v_exp_f32_e32 v22, v22
	s_nop 0
	v_mul_f32_e32 v3, v22, v3
	v_mul_f32_e32 v22, v3, v2
	v_fma_f32 v3, -v3, v2, v2
	v_cndmask_b32_e32 v2, v3, v22, vcc
	v_add_f32_e32 v3, v4, v24
	v_mul_f32_e32 v2, v2, v3
	v_cvt_pk_bf16_f32 v4, v2, s0
	v_lshlrev_b64 v[2:3], 11, v[152:153]
	v_lshl_add_u64 v[2:3], v[106:107], 0, v[2:3]
	global_store_short v[2:3], v4, off sc1
	s_waitcnt vmcnt(31)
	v_lshlrev_b32_e32 v2, 16, v209
	v_fma_f32 v3, |v2|, s92, 1.0
	v_rcp_f32_e32 v3, v3
	v_cmp_gt_f32_e32 vcc, 0, v2
	v_fmamk_f32 v4, v3, 0x3f07dc22, v236
	v_fmaak_f32 v4, v3, v4, 0x3f35f0e3
	v_fmaak_f32 v4, v3, v4, 0xbe11a98e
	v_fmaak_f32 v4, v3, v4, 0x3e027906
	v_mul_f32_e32 v3, v3, v4
	v_mul_f32_e32 v4, v2, v2
	v_mul_f32_e32 v4, 0xbf38aa3b, v4
	v_exp_f32_e32 v4, v4
	s_nop 0
	v_mul_f32_e32 v3, v4, v3
	v_mul_f32_e32 v4, v3, v2
	v_fma_f32 v3, -v3, v2, v2
	v_cndmask_b32_e32 v2, v3, v4, vcc
	v_add_f32_e32 v3, v5, v25
	v_mul_f32_e32 v2, v2, v3
	v_cvt_pk_bf16_f32 v4, v2, s0
	v_lshlrev_b64 v[2:3], 11, v[148:149]
	v_lshl_add_u64 v[2:3], v[106:107], 0, v[2:3]
	global_store_short v[2:3], v4, off sc1
	s_waitcnt vmcnt(31)
	v_lshlrev_b32_e32 v2, 16, v208
	v_fma_f32 v3, |v2|, s92, 1.0
	v_rcp_f32_e32 v3, v3
	v_cmp_gt_f32_e32 vcc, 0, v2
	v_fmamk_f32 v4, v3, 0x3f07dc22, v236
	v_fmaak_f32 v4, v3, v4, 0x3f35f0e3
	v_fmaak_f32 v4, v3, v4, 0xbe11a98e
	v_fmaak_f32 v4, v3, v4, 0x3e027906
	v_mul_f32_e32 v3, v3, v4
	v_mul_f32_e32 v4, v2, v2
	v_mul_f32_e32 v4, 0xbf38aa3b, v4
	v_exp_f32_e32 v4, v4
	s_nop 0
	v_mul_f32_e32 v3, v4, v3
	v_mul_f32_e32 v4, v3, v2
	v_fma_f32 v3, -v3, v2, v2
	v_cndmask_b32_e32 v2, v3, v4, vcc
	s_waitcnt lgkmcnt(0)
	v_add_f32_e32 v3, v6, v18
	v_mul_f32_e32 v2, v2, v3
	v_cvt_pk_bf16_f32 v4, v2, s0
	v_lshlrev_b64 v[2:3], 11, v[150:151]
	v_lshl_add_u64 v[2:3], v[106:107], 0, v[2:3]
	global_store_short v[2:3], v4, off sc1
	s_waitcnt vmcnt(31)
	v_lshlrev_b32_e32 v2, 16, v207
	v_fma_f32 v3, |v2|, s92, 1.0
	v_rcp_f32_e32 v3, v3
	v_cmp_gt_f32_e32 vcc, 0, v2
	v_fmamk_f32 v4, v3, 0x3f07dc22, v236
	v_fmaak_f32 v4, v3, v4, 0x3f35f0e3
	v_fmaak_f32 v4, v3, v4, 0xbe11a98e
	v_fmaak_f32 v4, v3, v4, 0x3e027906
	v_mul_f32_e32 v3, v3, v4
	v_mul_f32_e32 v4, v2, v2
	v_mul_f32_e32 v4, 0xbf38aa3b, v4
	v_exp_f32_e32 v4, v4
	s_nop 0
	v_mul_f32_e32 v3, v4, v3
	v_mul_f32_e32 v4, v3, v2
	v_fma_f32 v3, -v3, v2, v2
	v_cndmask_b32_e32 v2, v3, v4, vcc
	v_add_f32_e32 v3, v7, v19
	v_mul_f32_e32 v2, v2, v3
	v_cvt_pk_bf16_f32 v4, v2, s0
	v_lshlrev_b64 v[2:3], 11, v[146:147]
	v_lshl_add_u64 v[2:3], v[106:107], 0, v[2:3]
	global_store_short v[2:3], v4, off sc1
	s_waitcnt vmcnt(31)
	v_lshlrev_b32_e32 v2, 16, v206
	v_fma_f32 v3, |v2|, s92, 1.0
	v_rcp_f32_e32 v3, v3
	v_cmp_gt_f32_e32 vcc, 0, v2
	v_fmamk_f32 v4, v3, 0x3f07dc22, v236
	v_fmaak_f32 v4, v3, v4, 0x3f35f0e3
	v_fmaak_f32 v4, v3, v4, 0xbe11a98e
	v_fmaak_f32 v4, v3, v4, 0x3e027906
	v_mul_f32_e32 v3, v3, v4
	v_mul_f32_e32 v4, v2, v2
	v_mul_f32_e32 v4, 0xbf38aa3b, v4
	v_exp_f32_e32 v4, v4
	s_nop 0
	v_mul_f32_e32 v3, v4, v3
	v_mul_f32_e32 v4, v3, v2
	v_fma_f32 v3, -v3, v2, v2
	v_cndmask_b32_e32 v2, v3, v4, vcc
	v_add_f32_e32 v3, v8, v20
	v_mul_f32_e32 v2, v2, v3
	v_cvt_pk_bf16_f32 v4, v2, s0
	v_lshlrev_b64 v[2:3], 11, v[144:145]
	v_lshl_add_u64 v[2:3], v[106:107], 0, v[2:3]
	global_store_short v[2:3], v4, off sc1
	s_waitcnt vmcnt(31)
	v_lshlrev_b32_e32 v2, 16, v205
	v_fma_f32 v3, |v2|, s92, 1.0
	v_rcp_f32_e32 v3, v3
	v_cmp_gt_f32_e32 vcc, 0, v2
	v_fmamk_f32 v4, v3, 0x3f07dc22, v236
	v_fmaak_f32 v4, v3, v4, 0x3f35f0e3
	v_fmaak_f32 v4, v3, v4, 0xbe11a98e
	v_fmaak_f32 v4, v3, v4, 0x3e027906
	v_mul_f32_e32 v3, v3, v4
	v_mul_f32_e32 v4, v2, v2
	v_mul_f32_e32 v4, 0xbf38aa3b, v4
	v_exp_f32_e32 v4, v4
	s_nop 0
	v_mul_f32_e32 v3, v4, v3
	v_mul_f32_e32 v4, v3, v2
	v_fma_f32 v3, -v3, v2, v2
	v_cndmask_b32_e32 v2, v3, v4, vcc
	v_add_f32_e32 v3, v9, v21
	v_mul_f32_e32 v2, v2, v3
	v_cvt_pk_bf16_f32 v4, v2, s0
	v_lshlrev_b64 v[2:3], 11, v[172:173]
	v_lshl_add_u64 v[2:3], v[106:107], 0, v[2:3]
	global_store_short v[2:3], v4, off sc1
	s_waitcnt vmcnt(31)
	v_lshlrev_b32_e32 v2, 16, v204
	v_fma_f32 v3, |v2|, s92, 1.0
	v_rcp_f32_e32 v3, v3
	v_cmp_gt_f32_e32 vcc, 0, v2
	v_fmamk_f32 v4, v3, 0x3f07dc22, v236
	v_fmaak_f32 v4, v3, v4, 0x3f35f0e3
	v_fmaak_f32 v4, v3, v4, 0xbe11a98e
	v_fmaak_f32 v4, v3, v4, 0x3e027906
	v_mul_f32_e32 v3, v3, v4
	v_mul_f32_e32 v4, v2, v2
	v_mul_f32_e32 v4, 0xbf38aa3b, v4
	v_exp_f32_e32 v4, v4
	s_nop 0
	v_mul_f32_e32 v3, v4, v3
	v_mul_f32_e32 v4, v3, v2
	v_fma_f32 v3, -v3, v2, v2
	v_cndmask_b32_e32 v6, v3, v4, vcc
	ds_read_b128 v[2:5], v1 offset:448
	s_waitcnt lgkmcnt(0)
	v_add_f32_e32 v2, v10, v2
	v_mul_f32_e32 v2, v6, v2
	v_lshlrev_b64 v[6:7], 11, v[170:171]
	v_cvt_pk_bf16_f32 v2, v2, s0
	v_lshl_add_u64 v[6:7], v[106:107], 0, v[6:7]
	global_store_short v[6:7], v2, off sc1
	s_waitcnt vmcnt(31)
	v_lshlrev_b32_e32 v2, 16, v203
	v_fma_f32 v6, |v2|, s92, 1.0
	v_rcp_f32_e32 v6, v6
	v_cmp_gt_f32_e32 vcc, 0, v2
	v_add_f32_e32 v3, v11, v3
	v_fmamk_f32 v7, v6, 0x3f07dc22, v236
	v_fmaak_f32 v7, v6, v7, 0x3f35f0e3
	v_fmaak_f32 v7, v6, v7, 0xbe11a98e
	v_fmaak_f32 v7, v6, v7, 0x3e027906
	v_mul_f32_e32 v6, v6, v7
	v_mul_f32_e32 v7, v2, v2
	v_mul_f32_e32 v7, 0xbf38aa3b, v7
	v_exp_f32_e32 v7, v7
	s_nop 0
	v_mul_f32_e32 v6, v7, v6
	v_mul_f32_e32 v7, v6, v2
	v_fma_f32 v6, -v6, v2, v2
	v_cndmask_b32_e32 v2, v6, v7, vcc
	v_mul_f32_e32 v2, v2, v3
	v_cvt_pk_bf16_f32 v6, v2, s0
	v_lshlrev_b64 v[2:3], 11, v[168:169]
	v_lshl_add_u64 v[2:3], v[106:107], 0, v[2:3]
	global_store_short v[2:3], v6, off sc1
	s_waitcnt vmcnt(31)
	v_lshlrev_b32_e32 v2, 16, v179
	v_fma_f32 v3, |v2|, s92, 1.0
	v_rcp_f32_e32 v3, v3
	v_cmp_gt_f32_e32 vcc, 0, v2
	v_fmamk_f32 v6, v3, 0x3f07dc22, v236
	v_fmaak_f32 v6, v3, v6, 0x3f35f0e3
	v_fmaak_f32 v6, v3, v6, 0xbe11a98e
	v_fmaak_f32 v6, v3, v6, 0x3e027906
	v_mul_f32_e32 v3, v3, v6
	v_mul_f32_e32 v6, v2, v2
	v_mul_f32_e32 v6, 0xbf38aa3b, v6
	v_exp_f32_e32 v6, v6
	s_nop 0
	v_mul_f32_e32 v3, v6, v3
	v_mul_f32_e32 v6, v3, v2
	v_fma_f32 v3, -v3, v2, v2
	v_cndmask_b32_e32 v2, v3, v6, vcc
	v_add_f32_e32 v3, v12, v4
	v_mul_f32_e32 v2, v2, v3
	v_cvt_pk_bf16_f32 v4, v2, s0
	v_lshlrev_b64 v[2:3], 11, v[166:167]
	v_lshl_add_u64 v[2:3], v[106:107], 0, v[2:3]
	global_store_short v[2:3], v4, off sc1
	s_waitcnt vmcnt(31)
	v_lshlrev_b32_e32 v2, 16, v178
	v_fma_f32 v3, |v2|, s92, 1.0
	v_rcp_f32_e32 v3, v3
	v_cmp_gt_f32_e32 vcc, 0, v2
	v_fmamk_f32 v4, v3, 0x3f07dc22, v236
	v_fmaak_f32 v4, v3, v4, 0x3f35f0e3
	v_fmaak_f32 v4, v3, v4, 0xbe11a98e
	v_fmaak_f32 v4, v3, v4, 0x3e027906
	v_mul_f32_e32 v3, v3, v4
	v_mul_f32_e32 v4, v2, v2
	v_mul_f32_e32 v4, 0xbf38aa3b, v4
	v_exp_f32_e32 v4, v4
	s_nop 0
	v_mul_f32_e32 v3, v4, v3
	v_mul_f32_e32 v4, v3, v2
	v_fma_f32 v3, -v3, v2, v2
	v_cndmask_b32_e32 v2, v3, v4, vcc
	v_add_f32_e32 v3, v13, v5
	v_mul_f32_e32 v2, v2, v3
	v_cvt_pk_bf16_f32 v4, v2, s0
	v_lshlrev_b64 v[2:3], 11, v[164:165]
	v_lshl_add_u64 v[2:3], v[106:107], 0, v[2:3]
	global_store_short v[2:3], v4, off sc1
	s_waitcnt vmcnt(31)
	v_lshlrev_b32_e32 v2, 16, v177
	v_fma_f32 v3, |v2|, s92, 1.0
	v_rcp_f32_e32 v3, v3
	v_cmp_gt_f32_e32 vcc, 0, v2
	v_fmamk_f32 v4, v3, 0x3f07dc22, v236
	v_fmaak_f32 v4, v3, v4, 0x3f35f0e3
	v_fmaak_f32 v4, v3, v4, 0xbe11a98e
	v_fmaak_f32 v4, v3, v4, 0x3e027906
	v_mul_f32_e32 v3, v3, v4
	v_mul_f32_e32 v4, v2, v2
	v_mul_f32_e32 v4, 0xbf38aa3b, v4
	v_exp_f32_e32 v4, v4
	s_nop 0
	v_mul_f32_e32 v3, v4, v3
	v_mul_f32_e32 v4, v3, v2
	v_fma_f32 v3, -v3, v2, v2
	v_cndmask_b32_e32 v6, v3, v4, vcc
	ds_read_b128 v[2:5], v1 offset:480
	s_waitcnt lgkmcnt(0)
	v_add_f32_e32 v1, v14, v2
	v_mul_f32_e32 v1, v6, v1
	v_lshlrev_b64 v[6:7], 11, v[162:163]
	v_cvt_pk_bf16_f32 v1, v1, s0
	v_lshl_add_u64 v[6:7], v[106:107], 0, v[6:7]
	global_store_short v[6:7], v1, off sc1
	s_waitcnt vmcnt(31)
	v_lshlrev_b32_e32 v1, 16, v176
	v_fma_f32 v2, |v1|, s92, 1.0
	v_rcp_f32_e32 v2, v2
	v_cmp_gt_f32_e32 vcc, 0, v1
	v_fmamk_f32 v6, v2, 0x3f07dc22, v236
	v_fmaak_f32 v6, v2, v6, 0x3f35f0e3
	v_fmaak_f32 v6, v2, v6, 0xbe11a98e
	v_fmaak_f32 v6, v2, v6, 0x3e027906
	v_mul_f32_e32 v2, v2, v6
	v_mul_f32_e32 v6, v1, v1
	v_mul_f32_e32 v6, 0xbf38aa3b, v6
	v_exp_f32_e32 v6, v6
	s_nop 0
	v_mul_f32_e32 v2, v6, v2
	v_mul_f32_e32 v6, v2, v1
	v_fma_f32 v2, -v2, v1, v1
	v_cndmask_b32_e32 v1, v2, v6, vcc
	v_add_f32_e32 v2, v15, v3
	v_mul_f32_e32 v1, v1, v2
	v_lshlrev_b64 v[2:3], 11, v[160:161]
	v_cvt_pk_bf16_f32 v1, v1, s0
	v_lshl_add_u64 v[2:3], v[106:107], 0, v[2:3]
	global_store_short v[2:3], v1, off sc1
	s_waitcnt vmcnt(31)
	v_lshlrev_b32_e32 v1, 16, v175
	v_fma_f32 v2, |v1|, s92, 1.0
	v_rcp_f32_e32 v2, v2
	v_cmp_gt_f32_e32 vcc, 0, v1
	v_fmamk_f32 v3, v2, 0x3f07dc22, v236
	v_fmaak_f32 v3, v2, v3, 0x3f35f0e3
	v_fmaak_f32 v3, v2, v3, 0xbe11a98e
	v_fmaak_f32 v3, v2, v3, 0x3e027906
	v_mul_f32_e32 v2, v2, v3
	v_mul_f32_e32 v3, v1, v1
	v_mul_f32_e32 v3, 0xbf38aa3b, v3
	v_exp_f32_e32 v3, v3
	s_nop 0
	v_mul_f32_e32 v2, v3, v2
	v_mul_f32_e32 v3, v2, v1
	v_fma_f32 v2, -v2, v1, v1
	v_cndmask_b32_e32 v1, v2, v3, vcc
	v_add_f32_e32 v2, v16, v4
	v_mul_f32_e32 v1, v1, v2
	v_lshlrev_b64 v[2:3], 11, v[158:159]
	v_cvt_pk_bf16_f32 v1, v1, s0
	v_lshl_add_u64 v[2:3], v[106:107], 0, v[2:3]
	global_store_short v[2:3], v1, off sc1
	s_waitcnt vmcnt(31)
	v_lshlrev_b32_e32 v1, 16, v174
	v_fma_f32 v2, |v1|, s92, 1.0
	v_rcp_f32_e32 v2, v2
	v_cmp_gt_f32_e32 vcc, 0, v1
	v_fmamk_f32 v3, v2, 0x3f07dc22, v236
	v_fmaak_f32 v3, v2, v3, 0x3f35f0e3
	v_fmaak_f32 v3, v2, v3, 0xbe11a98e
	v_fmaak_f32 v3, v2, v3, 0x3e027906
	v_mul_f32_e32 v2, v2, v3
	v_mul_f32_e32 v3, v1, v1
	v_mul_f32_e32 v3, 0xbf38aa3b, v3
	v_exp_f32_e32 v3, v3
	s_nop 0
	v_mul_f32_e32 v2, v3, v2
	v_mul_f32_e32 v3, v2, v1
	v_fma_f32 v2, -v2, v1, v1
	v_cndmask_b32_e32 v1, v2, v3, vcc
	v_add_f32_e32 v2, v17, v5
	v_mul_f32_e32 v1, v1, v2
	v_lshlrev_b64 v[2:3], 11, v[156:157]
	v_cvt_pk_bf16_f32 v1, v1, s0
	v_lshl_add_u64 v[2:3], v[106:107], 0, v[2:3]
	global_store_short v[2:3], v1, off sc1
	s_barrier
	s_cbranch_scc0 .LBB0_254

.LBB0_257:
	s_add_i32 s7, s50, s54
	s_add_i32 s8, s51, s54
	s_cmpk_lt_i32 s8, 0x200
	s_cselect_b32 s7, s8, s7
	s_lshl_b32 s7, s7, 6
	s_and_b32 s8, s7, 0xfc0
	s_sub_i32 s10, s8, 30
	s_add_i32 s8, s10, s49
	s_and_b32 s7, s7, 0xfffff000
	s_max_i32 s8, s8, 0
	s_add_i32 s8, s8, s7
	v_and_b32_e32 v14, 0xff, v10
	v_mad_i64_i32 v[10:11], s[8:9], s8, v238, v[42:43]
	s_add_i32 s8, s10, s48
	s_max_i32 s8, s8, 0
	s_add_i32 s8, s8, s7
	v_mad_i64_i32 v[12:13], s[8:9], s8, v238, v[42:43]
	s_add_i32 s8, s10, s47
	s_max_i32 s8, s8, 0
	s_add_i32 s8, s8, s7
	s_waitcnt lgkmcnt(0)
	s_barrier
	global_load_dwordx2 v[152:153], v[10:11], off offset:1024
	global_load_dwordx2 v[154:155], v[10:11], off offset:1536
	global_load_dwordx2 v[148:149], v[12:13], off offset:1024
	global_load_dwordx2 v[150:151], v[12:13], off offset:1536
	v_mad_i64_i32 v[10:11], s[8:9], s8, v238, v[42:43]
	s_add_i32 s8, s10, s46
	s_max_i32 s8, s8, 0
	s_add_i32 s8, s8, s7
	v_mad_i64_i32 v[12:13], s[8:9], s8, v238, v[42:43]
	s_add_i32 s8, s10, s45
	s_max_i32 s8, s8, 0
	s_add_i32 s8, s8, s7
	global_load_dwordx2 v[144:145], v[10:11], off offset:1024
	global_load_dwordx2 v[146:147], v[10:11], off offset:1536
	global_load_dwordx2 v[140:141], v[12:13], off offset:1024
	global_load_dwordx2 v[142:143], v[12:13], off offset:1536
	v_mad_i64_i32 v[10:11], s[8:9], s8, v238, v[42:43]
	s_add_i32 s8, s10, s44
	s_max_i32 s8, s8, 0
	s_add_i32 s8, s8, s7
	v_mad_i64_i32 v[12:13], s[8:9], s8, v238, v[42:43]
	s_add_i32 s8, s10, s43
	s_max_i32 s8, s8, 0
	s_add_i32 s8, s8, s7
	global_load_dwordx2 v[136:137], v[10:11], off offset:1024
	global_load_dwordx2 v[138:139], v[10:11], off offset:1536
	global_load_dwordx2 v[132:133], v[12:13], off offset:1024
	global_load_dwordx2 v[134:135], v[12:13], off offset:1536
	v_mad_i64_i32 v[10:11], s[8:9], s8, v238, v[42:43]
	s_add_i32 s8, s10, s42
	s_max_i32 s8, s8, 0
	s_add_i32 s8, s8, s7
	v_mad_i64_i32 v[12:13], s[8:9], s8, v238, v[42:43]
	s_add_i32 s8, s10, s41
	s_max_i32 s8, s8, 0
	s_add_i32 s8, s8, s7
	global_load_dwordx2 v[126:127], v[10:11], off offset:1024
	global_load_dwordx2 v[128:129], v[10:11], off offset:1536
	global_load_dwordx2 v[122:123], v[12:13], off offset:1024
	global_load_dwordx2 v[124:125], v[12:13], off offset:1536
	v_mad_i64_i32 v[10:11], s[8:9], s8, v238, v[42:43]
	s_add_i32 s8, s10, s40
	s_max_i32 s8, s8, 0
	s_add_i32 s8, s8, s7
	v_mad_i64_i32 v[12:13], s[8:9], s8, v238, v[42:43]
	s_add_i32 s8, s10, s34
	s_max_i32 s8, s8, 0
	s_add_i32 s8, s8, s7
	global_load_dwordx2 v[118:119], v[10:11], off offset:1024
	global_load_dwordx2 v[120:121], v[10:11], off offset:1536
	global_load_dwordx2 v[114:115], v[12:13], off offset:1024
	global_load_dwordx2 v[116:117], v[12:13], off offset:1536
	v_mad_i64_i32 v[10:11], s[8:9], s8, v238, v[42:43]
	s_add_i32 s10, s10, s5
	s_lshl_b32 s6, s6, 7
	s_max_i32 s8, s10, 0
	s_and_b32 s6, s6, 0xffff8000
	s_add_i32 s8, s8, s7
	s_add_i32 s6, s6, 0
	v_mad_i64_i32 v[12:13], s[8:9], s8, v238, v[42:43]
	v_lshl_add_u32 v163, v14, 2, s6
	global_load_dwordx2 v[110:111], v[10:11], off offset:1024
	global_load_dwordx2 v[112:113], v[10:11], off offset:1536
	global_load_dwordx2 v[106:107], v[12:13], off offset:1024
	global_load_dwordx2 v[108:109], v[12:13], off offset:1536
	ds_read2st64_b32 v[26:27], v163 offset1:4
	ds_read2st64_b32 v[28:29], v163 offset0:8 offset1:12
	ds_read2st64_b32 v[30:31], v163 offset0:16 offset1:20
	ds_read2st64_b32 v[32:33], v163 offset0:24 offset1:28
	ds_read2st64_b32 v[160:161], v163 offset0:32 offset1:36
	ds_read2st64_b32 v[158:159], v163 offset0:40 offset1:44
	ds_read2st64_b32 v[156:157], v163 offset0:48 offset1:52
	ds_read2st64_b32 v[40:41], v163 offset0:56 offset1:60
	ds_read2st64_b32 v[38:39], v163 offset0:64 offset1:68
	ds_read2st64_b32 v[36:37], v163 offset0:72 offset1:76
	ds_read2st64_b32 v[34:35], v163 offset0:80 offset1:84
	ds_read2st64_b32 v[24:25], v163 offset0:88 offset1:92
	ds_read2st64_b32 v[22:23], v163 offset0:96 offset1:100
	ds_read2st64_b32 v[20:21], v163 offset0:104 offset1:108
	ds_read2st64_b32 v[10:11], v163 offset0:120 offset1:124
	ds_read2st64_b32 v[18:19], v163 offset0:112 offset1:116
	ds_read2st64_b32 v[12:13], v163 offset0:128 offset1:132
	ds_read2st64_b32 v[14:15], v163 offset0:136 offset1:140
	ds_read2st64_b32 v[16:17], v163 offset0:144 offset1:148
	s_waitcnt vmcnt(49) lgkmcnt(4)
	v_mul_f32_e32 v105, v103, v10
	v_mul_f32_e32 v165, v44, v27
	s_waitcnt vmcnt(24)
	v_mov_b32_e32 v164, v104
	v_pk_fma_f32 v[26:27], v[44:45], v[26:27], v[104:105]
	v_pk_fma_f32 v[164:165], v[46:47], v[28:29], v[164:165]
	v_pk_fma_f32 v[26:27], v[48:49], v[28:29], v[26:27]
	v_pk_fma_f32 v[164:165], v[50:51], v[30:31], v[164:165]
	v_pk_fma_f32 v[26:27], v[52:53], v[30:31], v[26:27]
	v_pk_fma_f32 v[164:165], v[54:55], v[32:33], v[164:165]
	v_pk_fma_f32 v[26:27], v[56:57], v[32:33], v[26:27]
	v_pk_fma_f32 v[164:165], v[58:59], v[160:161], v[164:165]
	v_pk_fma_f32 v[26:27], v[60:61], v[160:161], v[26:27]
	v_pk_fma_f32 v[164:165], v[62:63], v[158:159], v[164:165]
	v_pk_fma_f32 v[26:27], v[64:65], v[158:159], v[26:27]
	v_pk_fma_f32 v[164:165], v[66:67], v[156:157], v[164:165]
	v_pk_fma_f32 v[26:27], v[68:69], v[156:157], v[26:27]
	v_pk_fma_f32 v[164:165], v[70:71], v[40:41], v[164:165]
	v_pk_fma_f32 v[26:27], v[72:73], v[40:41], v[26:27]
	v_pk_fma_f32 v[164:165], v[74:75], v[38:39], v[164:165]
	v_pk_fma_f32 v[26:27], v[76:77], v[38:39], v[26:27]
	v_pk_fma_f32 v[164:165], v[78:79], v[36:37], v[164:165]
	v_pk_fma_f32 v[26:27], v[80:81], v[36:37], v[26:27]
	v_pk_fma_f32 v[164:165], v[82:83], v[34:35], v[164:165]
	v_pk_fma_f32 v[26:27], v[84:85], v[34:35], v[26:27]
	v_pk_fma_f32 v[164:165], v[86:87], v[24:25], v[164:165]
	v_pk_fma_f32 v[26:27], v[88:89], v[24:25], v[26:27]
	v_pk_fma_f32 v[164:165], v[90:91], v[22:23], v[164:165]
	v_pk_fma_f32 v[26:27], v[92:93], v[22:23], v[26:27]
	v_pk_fma_f32 v[164:165], v[94:95], v[20:21], v[164:165]
	v_pk_fma_f32 v[26:27], v[96:97], v[20:21], v[26:27]
	s_waitcnt lgkmcnt(3)
	v_pk_fma_f32 v[164:165], v[98:99], v[18:19], v[164:165]
	v_pk_fma_f32 v[26:27], v[100:101], v[18:19], v[26:27]
	v_pk_fma_f32 v[166:167], v[102:103], v[10:11], v[164:165]
	v_add_f32_e32 v164, v26, v27
	v_mul_f32_e32 v27, v44, v29
	v_mov_b32_e32 v26, v104
	v_pk_fma_f32 v[26:27], v[46:47], v[30:31], v[26:27]
	v_add_f32_e32 v165, v166, v167
	v_pk_fma_f32 v[26:27], v[50:51], v[32:33], v[26:27]
	s_waitcnt lgkmcnt(2)
	v_mul_f32_e32 v105, v103, v12
	v_pk_fma_f32 v[26:27], v[54:55], v[160:161], v[26:27]
	v_pk_fma_f32 v[28:29], v[44:45], v[28:29], v[104:105]
	v_pk_fma_f32 v[26:27], v[58:59], v[158:159], v[26:27]
	v_pk_fma_f32 v[28:29], v[48:49], v[30:31], v[28:29]
	v_pk_fma_f32 v[26:27], v[62:63], v[156:157], v[26:27]
	v_pk_fma_f32 v[28:29], v[52:53], v[32:33], v[28:29]
	v_pk_fma_f32 v[26:27], v[66:67], v[40:41], v[26:27]
	v_pk_fma_f32 v[28:29], v[56:57], v[160:161], v[28:29]
	v_pk_fma_f32 v[26:27], v[70:71], v[38:39], v[26:27]
	v_pk_fma_f32 v[28:29], v[60:61], v[158:159], v[28:29]
	v_pk_fma_f32 v[26:27], v[74:75], v[36:37], v[26:27]
	v_pk_fma_f32 v[28:29], v[64:65], v[156:157], v[28:29]
	v_pk_fma_f32 v[26:27], v[78:79], v[34:35], v[26:27]
	v_pk_fma_f32 v[28:29], v[68:69], v[40:41], v[28:29]
	v_pk_fma_f32 v[26:27], v[82:83], v[24:25], v[26:27]
	v_pk_fma_f32 v[28:29], v[72:73], v[38:39], v[28:29]
	v_pk_fma_f32 v[26:27], v[86:87], v[22:23], v[26:27]
	v_pk_fma_f32 v[28:29], v[76:77], v[36:37], v[28:29]
	v_pk_fma_f32 v[26:27], v[90:91], v[20:21], v[26:27]
	v_pk_fma_f32 v[28:29], v[80:81], v[34:35], v[28:29]
	v_pk_fma_f32 v[26:27], v[94:95], v[18:19], v[26:27]
	v_pk_fma_f32 v[28:29], v[84:85], v[24:25], v[28:29]
	v_pk_fma_f32 v[26:27], v[98:99], v[10:11], v[26:27]
	v_pk_fma_f32 v[28:29], v[88:89], v[22:23], v[28:29]
	v_pk_fma_f32 v[26:27], v[102:103], v[12:13], v[26:27]
	v_pk_fma_f32 v[28:29], v[92:93], v[20:21], v[28:29]
	v_add_f32_e32 v167, v26, v27
	v_mul_f32_e32 v27, v44, v31
	v_mov_b32_e32 v26, v104
	v_pk_fma_f32 v[26:27], v[46:47], v[32:33], v[26:27]
	v_pk_fma_f32 v[28:29], v[96:97], v[18:19], v[28:29]
	v_pk_fma_f32 v[26:27], v[50:51], v[160:161], v[26:27]
	v_pk_fma_f32 v[28:29], v[100:101], v[10:11], v[28:29]
	v_pk_fma_f32 v[26:27], v[54:55], v[158:159], v[26:27]
	s_waitcnt lgkmcnt(1)
	v_mul_f32_e32 v105, v103, v14
	v_pk_fma_f32 v[26:27], v[58:59], v[156:157], v[26:27]
	v_add_f32_e32 v166, v28, v29
	v_pk_fma_f32 v[26:27], v[62:63], v[40:41], v[26:27]
	v_pk_fma_f32 v[28:29], v[44:45], v[30:31], v[104:105]
	v_pk_fma_f32 v[26:27], v[66:67], v[38:39], v[26:27]
	v_pk_fma_f32 v[28:29], v[48:49], v[32:33], v[28:29]
	v_pk_fma_f32 v[26:27], v[70:71], v[36:37], v[26:27]
	v_pk_fma_f32 v[28:29], v[52:53], v[160:161], v[28:29]
	v_pk_fma_f32 v[26:27], v[74:75], v[34:35], v[26:27]
	v_pk_fma_f32 v[28:29], v[56:57], v[158:159], v[28:29]
	v_pk_fma_f32 v[26:27], v[78:79], v[24:25], v[26:27]
	v_pk_fma_f32 v[28:29], v[60:61], v[156:157], v[28:29]
	v_pk_fma_f32 v[26:27], v[82:83], v[22:23], v[26:27]
	v_pk_fma_f32 v[28:29], v[64:65], v[40:41], v[28:29]
	v_pk_fma_f32 v[26:27], v[86:87], v[20:21], v[26:27]
	v_pk_fma_f32 v[28:29], v[68:69], v[38:39], v[28:29]
	v_pk_fma_f32 v[26:27], v[90:91], v[18:19], v[26:27]
	v_pk_fma_f32 v[28:29], v[72:73], v[36:37], v[28:29]
	v_pk_fma_f32 v[26:27], v[94:95], v[10:11], v[26:27]
	v_pk_fma_f32 v[28:29], v[76:77], v[34:35], v[28:29]
	v_pk_fma_f32 v[26:27], v[98:99], v[12:13], v[26:27]
	v_pk_fma_f32 v[28:29], v[80:81], v[24:25], v[28:29]
	v_pk_fma_f32 v[26:27], v[102:103], v[14:15], v[26:27]
	v_pk_fma_f32 v[28:29], v[84:85], v[22:23], v[28:29]
	v_add_f32_e32 v169, v26, v27
	v_mul_f32_e32 v27, v44, v33
	v_mov_b32_e32 v26, v104
	v_pk_fma_f32 v[26:27], v[46:47], v[160:161], v[26:27]
	v_pk_fma_f32 v[28:29], v[88:89], v[20:21], v[28:29]
	v_pk_fma_f32 v[26:27], v[50:51], v[158:159], v[26:27]
	v_pk_fma_f32 v[28:29], v[92:93], v[18:19], v[28:29]
	v_pk_fma_f32 v[26:27], v[54:55], v[156:157], v[26:27]
	v_pk_fma_f32 v[28:29], v[96:97], v[10:11], v[28:29]
	v_pk_fma_f32 v[26:27], v[58:59], v[40:41], v[26:27]
	v_pk_fma_f32 v[28:29], v[100:101], v[12:13], v[28:29]
	v_pk_fma_f32 v[26:27], v[62:63], v[38:39], v[26:27]
	s_waitcnt lgkmcnt(0)
	v_mul_f32_e32 v105, v103, v16
	v_pk_fma_f32 v[26:27], v[66:67], v[36:37], v[26:27]
	v_add_f32_e32 v168, v28, v29
	v_pk_fma_f32 v[26:27], v[70:71], v[34:35], v[26:27]
	v_pk_fma_f32 v[28:29], v[44:45], v[32:33], v[104:105]
	v_pk_fma_f32 v[26:27], v[74:75], v[24:25], v[26:27]
	v_pk_fma_f32 v[28:29], v[48:49], v[160:161], v[28:29]
	v_pk_fma_f32 v[26:27], v[78:79], v[22:23], v[26:27]
	v_pk_fma_f32 v[28:29], v[52:53], v[158:159], v[28:29]
	v_pk_fma_f32 v[26:27], v[82:83], v[20:21], v[26:27]
	v_pk_fma_f32 v[28:29], v[56:57], v[156:157], v[28:29]
	v_pk_fma_f32 v[26:27], v[86:87], v[18:19], v[26:27]
	v_pk_fma_f32 v[28:29], v[60:61], v[40:41], v[28:29]
	v_pk_fma_f32 v[26:27], v[90:91], v[10:11], v[26:27]
	v_mul_f32_e32 v173, v44, v161
	v_pk_fma_f32 v[26:27], v[94:95], v[12:13], v[26:27]
	v_pk_fma_f32 v[28:29], v[64:65], v[38:39], v[28:29]
	v_pk_fma_f32 v[26:27], v[98:99], v[14:15], v[26:27]
	v_pk_fma_f32 v[28:29], v[68:69], v[36:37], v[28:29]
	v_pk_fma_f32 v[30:31], v[102:103], v[16:17], v[26:27]
	ds_read2st64_b32 v[26:27], v163 offset0:152 offset1:156
	v_pk_fma_f32 v[28:29], v[72:73], v[34:35], v[28:29]
	v_add_f32_e32 v171, v30, v31
	v_pk_fma_f32 v[28:29], v[76:77], v[24:25], v[28:29]
	v_mov_b32_e32 v172, v104
	s_waitcnt lgkmcnt(0)
	v_mul_f32_e32 v105, v103, v26
	v_pk_fma_f32 v[160:161], v[44:45], v[160:161], v[104:105]
	v_pk_fma_f32 v[28:29], v[80:81], v[22:23], v[28:29]
	v_pk_fma_f32 v[160:161], v[48:49], v[158:159], v[160:161]
	v_pk_fma_f32 v[28:29], v[84:85], v[20:21], v[28:29]
	v_pk_fma_f32 v[160:161], v[52:53], v[156:157], v[160:161]
	v_pk_fma_f32 v[28:29], v[88:89], v[18:19], v[28:29]
	v_pk_fma_f32 v[160:161], v[56:57], v[40:41], v[160:161]
	v_pk_fma_f32 v[28:29], v[92:93], v[10:11], v[28:29]
	v_pk_fma_f32 v[160:161], v[60:61], v[38:39], v[160:161]
	v_pk_fma_f32 v[28:29], v[96:97], v[12:13], v[28:29]
	v_pk_fma_f32 v[160:161], v[64:65], v[36:37], v[160:161]
	v_pk_fma_f32 v[28:29], v[100:101], v[14:15], v[28:29]
	v_pk_fma_f32 v[160:161], v[68:69], v[34:35], v[160:161]
	v_add_f32_e32 v170, v28, v29
	v_pk_fma_f32 v[160:161], v[72:73], v[24:25], v[160:161]
	ds_read2st64_b32 v[28:29], v163 offset0:160 offset1:164
	ds_read2st64_b32 v[30:31], v163 offset0:168 offset1:172
	ds_read2st64_b32 v[32:33], v163 offset0:176 offset1:180
	v_pk_fma_f32 v[160:161], v[76:77], v[22:23], v[160:161]
	v_pk_fma_f32 v[172:173], v[46:47], v[158:159], v[172:173]
	v_pk_fma_f32 v[160:161], v[80:81], v[20:21], v[160:161]
	s_waitcnt lgkmcnt(2)
	v_mul_f32_e32 v105, v103, v28
	v_pk_fma_f32 v[160:161], v[84:85], v[18:19], v[160:161]
	v_pk_fma_f32 v[172:173], v[50:51], v[156:157], v[172:173]
	v_pk_fma_f32 v[160:161], v[88:89], v[10:11], v[160:161]
	v_pk_fma_f32 v[172:173], v[54:55], v[40:41], v[172:173]
	v_pk_fma_f32 v[160:161], v[92:93], v[12:13], v[160:161]
	v_pk_fma_f32 v[172:173], v[58:59], v[38:39], v[172:173]
	v_pk_fma_f32 v[160:161], v[96:97], v[14:15], v[160:161]
	v_pk_fma_f32 v[172:173], v[62:63], v[36:37], v[172:173]
	v_pk_fma_f32 v[160:161], v[100:101], v[16:17], v[160:161]
	v_pk_fma_f32 v[172:173], v[66:67], v[34:35], v[172:173]
	v_add_f32_e32 v174, v160, v161
	v_mul_f32_e32 v161, v44, v159
	v_pk_fma_f32 v[158:159], v[44:45], v[158:159], v[104:105]
	v_mov_b32_e32 v160, v104
	v_pk_fma_f32 v[158:159], v[48:49], v[156:157], v[158:159]
	s_waitcnt lgkmcnt(1)
	v_mul_f32_e32 v105, v103, v30
	v_pk_fma_f32 v[158:159], v[52:53], v[40:41], v[158:159]
	v_pk_fma_f32 v[160:161], v[46:47], v[156:157], v[160:161]
	v_pk_fma_f32 v[158:159], v[56:57], v[38:39], v[158:159]
	v_pk_fma_f32 v[160:161], v[50:51], v[40:41], v[160:161]
	v_pk_fma_f32 v[158:159], v[60:61], v[36:37], v[158:159]
	v_pk_fma_f32 v[172:173], v[70:71], v[24:25], v[172:173]
	v_pk_fma_f32 v[158:159], v[64:65], v[34:35], v[158:159]
	v_pk_fma_f32 v[172:173], v[74:75], v[22:23], v[172:173]
	v_pk_fma_f32 v[158:159], v[68:69], v[24:25], v[158:159]
	v_pk_fma_f32 v[172:173], v[78:79], v[20:21], v[172:173]
	v_pk_fma_f32 v[158:159], v[72:73], v[22:23], v[158:159]
	v_pk_fma_f32 v[172:173], v[82:83], v[18:19], v[172:173]
	v_pk_fma_f32 v[158:159], v[76:77], v[20:21], v[158:159]
	v_pk_fma_f32 v[172:173], v[86:87], v[10:11], v[172:173]
	v_pk_fma_f32 v[158:159], v[80:81], v[18:19], v[158:159]
	v_pk_fma_f32 v[172:173], v[90:91], v[12:13], v[172:173]
	v_pk_fma_f32 v[158:159], v[84:85], v[10:11], v[158:159]
	v_pk_fma_f32 v[172:173], v[94:95], v[14:15], v[172:173]
	v_pk_fma_f32 v[158:159], v[88:89], v[12:13], v[158:159]
	v_pk_fma_f32 v[172:173], v[98:99], v[16:17], v[172:173]
	v_pk_fma_f32 v[158:159], v[92:93], v[14:15], v[158:159]
	v_pk_fma_f32 v[160:161], v[54:55], v[38:39], v[160:161]
	v_pk_fma_f32 v[158:159], v[96:97], v[16:17], v[158:159]
	v_pk_fma_f32 v[172:173], v[102:103], v[26:27], v[172:173]
	v_pk_fma_f32 v[158:159], v[100:101], v[26:27], v[158:159]
	v_pk_fma_f32 v[160:161], v[58:59], v[36:37], v[160:161]
	v_add_f32_e32 v176, v158, v159
	v_mul_f32_e32 v159, v44, v157
	v_pk_fma_f32 v[156:157], v[44:45], v[156:157], v[104:105]
	v_mov_b32_e32 v158, v104
	v_pk_fma_f32 v[156:157], v[48:49], v[40:41], v[156:157]
	s_waitcnt lgkmcnt(0)
	v_mul_f32_e32 v105, v103, v32
	v_pk_fma_f32 v[156:157], v[52:53], v[38:39], v[156:157]
	v_pk_fma_f32 v[158:159], v[46:47], v[40:41], v[158:159]
	v_pk_fma_f32 v[156:157], v[56:57], v[36:37], v[156:157]
	v_pk_fma_f32 v[158:159], v[50:51], v[38:39], v[158:159]
	v_pk_fma_f32 v[156:157], v[60:61], v[34:35], v[156:157]
	v_pk_fma_f32 v[158:159], v[54:55], v[36:37], v[158:159]
	v_pk_fma_f32 v[156:157], v[64:65], v[24:25], v[156:157]
	v_pk_fma_f32 v[158:159], v[58:59], v[34:35], v[158:159]
	v_pk_fma_f32 v[156:157], v[68:69], v[22:23], v[156:157]
	v_add_f32_e32 v175, v172, v173
	v_pk_fma_f32 v[156:157], v[72:73], v[20:21], v[156:157]
	v_pk_fma_f32 v[160:161], v[62:63], v[34:35], v[160:161]
	v_pk_fma_f32 v[156:157], v[76:77], v[18:19], v[156:157]
	v_pk_fma_f32 v[158:159], v[62:63], v[24:25], v[158:159]
	v_pk_fma_f32 v[156:157], v[80:81], v[10:11], v[156:157]
	v_mul_f32_e32 v173, v44, v39
	v_pk_fma_f32 v[156:157], v[84:85], v[12:13], v[156:157]
	v_pk_fma_f32 v[160:161], v[66:67], v[24:25], v[160:161]
	v_pk_fma_f32 v[156:157], v[88:89], v[14:15], v[156:157]
	v_pk_fma_f32 v[158:159], v[66:67], v[22:23], v[158:159]
	v_pk_fma_f32 v[156:157], v[92:93], v[16:17], v[156:157]
	v_pk_fma_f32 v[160:161], v[70:71], v[22:23], v[160:161]
	v_pk_fma_f32 v[156:157], v[96:97], v[26:27], v[156:157]
	v_pk_fma_f32 v[158:159], v[70:71], v[20:21], v[158:159]
	v_pk_fma_f32 v[156:157], v[100:101], v[28:29], v[156:157]
	v_pk_fma_f32 v[160:161], v[74:75], v[20:21], v[160:161]
	v_add_f32_e32 v178, v156, v157
	v_mul_f32_e32 v157, v44, v41
	v_pk_fma_f32 v[40:41], v[44:45], v[40:41], v[104:105]
	v_mov_b32_e32 v156, v104
	v_pk_fma_f32 v[40:41], v[48:49], v[38:39], v[40:41]
	v_pk_fma_f32 v[156:157], v[46:47], v[38:39], v[156:157]
	v_pk_fma_f32 v[40:41], v[52:53], v[36:37], v[40:41]
	v_pk_fma_f32 v[156:157], v[50:51], v[36:37], v[156:157]
	v_pk_fma_f32 v[40:41], v[56:57], v[34:35], v[40:41]
	v_pk_fma_f32 v[156:157], v[54:55], v[34:35], v[156:157]
	v_pk_fma_f32 v[40:41], v[60:61], v[24:25], v[40:41]
	v_pk_fma_f32 v[156:157], v[58:59], v[24:25], v[156:157]
	v_pk_fma_f32 v[40:41], v[64:65], v[22:23], v[40:41]
	v_pk_fma_f32 v[156:157], v[62:63], v[22:23], v[156:157]
	v_pk_fma_f32 v[40:41], v[68:69], v[20:21], v[40:41]
	v_pk_fma_f32 v[156:157], v[66:67], v[20:21], v[156:157]
	v_pk_fma_f32 v[40:41], v[72:73], v[18:19], v[40:41]
	v_pk_fma_f32 v[156:157], v[70:71], v[18:19], v[156:157]
	v_pk_fma_f32 v[40:41], v[76:77], v[10:11], v[40:41]
	v_pk_fma_f32 v[158:159], v[74:75], v[18:19], v[158:159]
	v_pk_fma_f32 v[40:41], v[80:81], v[12:13], v[40:41]
	v_pk_fma_f32 v[156:157], v[74:75], v[10:11], v[156:157]
	v_pk_fma_f32 v[40:41], v[84:85], v[14:15], v[40:41]
	v_pk_fma_f32 v[160:161], v[78:79], v[18:19], v[160:161]
	v_pk_fma_f32 v[40:41], v[88:89], v[16:17], v[40:41]
	v_pk_fma_f32 v[158:159], v[78:79], v[10:11], v[158:159]
	v_pk_fma_f32 v[40:41], v[92:93], v[26:27], v[40:41]
	v_pk_fma_f32 v[156:157], v[78:79], v[12:13], v[156:157]
	v_pk_fma_f32 v[40:41], v[96:97], v[28:29], v[40:41]
	v_pk_fma_f32 v[160:161], v[82:83], v[10:11], v[160:161]
	v_pk_fma_f32 v[40:41], v[100:101], v[30:31], v[40:41]
	v_pk_fma_f32 v[158:159], v[82:83], v[12:13], v[158:159]
	v_add_f32_e32 v180, v40, v41
	ds_read2st64_b32 v[40:41], v163 offset0:184 offset1:188
	v_pk_fma_f32 v[156:157], v[82:83], v[14:15], v[156:157]
	v_pk_fma_f32 v[160:161], v[86:87], v[12:13], v[160:161]
	v_pk_fma_f32 v[158:159], v[86:87], v[14:15], v[158:159]
	v_pk_fma_f32 v[156:157], v[86:87], v[16:17], v[156:157]
	s_waitcnt lgkmcnt(0)
	v_mul_f32_e32 v105, v103, v40
	v_pk_fma_f32 v[38:39], v[44:45], v[38:39], v[104:105]
	v_pk_fma_f32 v[160:161], v[90:91], v[14:15], v[160:161]
	v_pk_fma_f32 v[38:39], v[48:49], v[36:37], v[38:39]
	v_pk_fma_f32 v[158:159], v[90:91], v[16:17], v[158:159]
	v_pk_fma_f32 v[38:39], v[52:53], v[34:35], v[38:39]
	v_pk_fma_f32 v[156:157], v[90:91], v[26:27], v[156:157]
	v_pk_fma_f32 v[38:39], v[56:57], v[24:25], v[38:39]
	v_pk_fma_f32 v[160:161], v[94:95], v[16:17], v[160:161]
	v_pk_fma_f32 v[38:39], v[60:61], v[22:23], v[38:39]
	v_pk_fma_f32 v[158:159], v[94:95], v[26:27], v[158:159]
	v_pk_fma_f32 v[38:39], v[64:65], v[20:21], v[38:39]
	v_pk_fma_f32 v[156:157], v[94:95], v[28:29], v[156:157]
	v_pk_fma_f32 v[38:39], v[68:69], v[18:19], v[38:39]
	v_pk_fma_f32 v[160:161], v[98:99], v[26:27], v[160:161]
	v_pk_fma_f32 v[38:39], v[72:73], v[10:11], v[38:39]
	v_pk_fma_f32 v[158:159], v[98:99], v[28:29], v[158:159]
	v_pk_fma_f32 v[38:39], v[76:77], v[12:13], v[38:39]
	v_pk_fma_f32 v[156:157], v[98:99], v[30:31], v[156:157]
	v_pk_fma_f32 v[38:39], v[80:81], v[14:15], v[38:39]
	v_pk_fma_f32 v[160:161], v[102:103], v[28:29], v[160:161]
	v_pk_fma_f32 v[158:159], v[102:103], v[30:31], v[158:159]
	v_pk_fma_f32 v[156:157], v[102:103], v[32:33], v[156:157]
	v_pk_fma_f32 v[38:39], v[84:85], v[16:17], v[38:39]
	v_add_f32_e32 v177, v160, v161
	v_add_f32_e32 v179, v158, v159
	v_add_f32_e32 v181, v156, v157
	ds_read2st64_b32 v[156:157], v163 offset0:192 offset1:196
	ds_read2st64_b32 v[158:159], v163 offset0:200 offset1:204
	ds_read2st64_b32 v[160:161], v163 offset0:208 offset1:212
	v_pk_fma_f32 v[38:39], v[88:89], v[26:27], v[38:39]
	v_mov_b32_e32 v172, v104
	v_pk_fma_f32 v[38:39], v[92:93], v[28:29], v[38:39]
	s_waitcnt lgkmcnt(2)
	v_mul_f32_e32 v105, v103, v156
	v_pk_fma_f32 v[38:39], v[96:97], v[30:31], v[38:39]
	v_pk_fma_f32 v[172:173], v[46:47], v[36:37], v[172:173]
	v_pk_fma_f32 v[38:39], v[100:101], v[32:33], v[38:39]
	v_pk_fma_f32 v[172:173], v[50:51], v[34:35], v[172:173]
	v_add_f32_e32 v182, v38, v39
	v_mul_f32_e32 v39, v44, v37
	v_pk_fma_f32 v[36:37], v[44:45], v[36:37], v[104:105]
	v_mov_b32_e32 v38, v104
	v_pk_fma_f32 v[36:37], v[48:49], v[34:35], v[36:37]
	s_waitcnt lgkmcnt(1)
	v_mul_f32_e32 v105, v103, v158
	v_pk_fma_f32 v[36:37], v[52:53], v[24:25], v[36:37]
	v_pk_fma_f32 v[38:39], v[46:47], v[34:35], v[38:39]
	v_pk_fma_f32 v[36:37], v[56:57], v[22:23], v[36:37]
	v_pk_fma_f32 v[172:173], v[54:55], v[24:25], v[172:173]
	v_pk_fma_f32 v[36:37], v[60:61], v[20:21], v[36:37]
	v_pk_fma_f32 v[38:39], v[50:51], v[24:25], v[38:39]
	v_pk_fma_f32 v[36:37], v[64:65], v[18:19], v[36:37]
	v_pk_fma_f32 v[172:173], v[58:59], v[22:23], v[172:173]
	v_pk_fma_f32 v[36:37], v[68:69], v[10:11], v[36:37]
	v_pk_fma_f32 v[172:173], v[62:63], v[20:21], v[172:173]
	v_pk_fma_f32 v[36:37], v[72:73], v[12:13], v[36:37]
	v_pk_fma_f32 v[172:173], v[66:67], v[18:19], v[172:173]
	v_pk_fma_f32 v[36:37], v[76:77], v[14:15], v[36:37]
	v_pk_fma_f32 v[172:173], v[70:71], v[10:11], v[172:173]
	v_pk_fma_f32 v[36:37], v[80:81], v[16:17], v[36:37]
	v_pk_fma_f32 v[172:173], v[74:75], v[12:13], v[172:173]
	v_pk_fma_f32 v[36:37], v[84:85], v[26:27], v[36:37]
	v_pk_fma_f32 v[172:173], v[78:79], v[14:15], v[172:173]
	v_pk_fma_f32 v[36:37], v[88:89], v[28:29], v[36:37]
	v_pk_fma_f32 v[172:173], v[82:83], v[16:17], v[172:173]
	v_pk_fma_f32 v[36:37], v[92:93], v[30:31], v[36:37]
	v_pk_fma_f32 v[172:173], v[86:87], v[26:27], v[172:173]
	v_pk_fma_f32 v[36:37], v[96:97], v[32:33], v[36:37]
	v_pk_fma_f32 v[172:173], v[90:91], v[28:29], v[172:173]
	v_pk_fma_f32 v[36:37], v[100:101], v[40:41], v[36:37]
	v_pk_fma_f32 v[172:173], v[94:95], v[30:31], v[172:173]
	v_add_f32_e32 v184, v36, v37
	v_mul_f32_e32 v37, v44, v35
	v_pk_fma_f32 v[34:35], v[44:45], v[34:35], v[104:105]
	v_mov_b32_e32 v36, v104
	v_pk_fma_f32 v[34:35], v[48:49], v[24:25], v[34:35]
	s_waitcnt lgkmcnt(0)
	v_mul_f32_e32 v105, v103, v160
	v_pk_fma_f32 v[34:35], v[52:53], v[22:23], v[34:35]
	v_pk_fma_f32 v[36:37], v[46:47], v[24:25], v[36:37]
	v_pk_fma_f32 v[34:35], v[56:57], v[20:21], v[34:35]
	v_pk_fma_f32 v[36:37], v[50:51], v[22:23], v[36:37]
	v_pk_fma_f32 v[34:35], v[60:61], v[18:19], v[34:35]
	v_pk_fma_f32 v[172:173], v[98:99], v[32:33], v[172:173]
	v_pk_fma_f32 v[34:35], v[64:65], v[10:11], v[34:35]
	v_pk_fma_f32 v[38:39], v[54:55], v[22:23], v[38:39]
	v_pk_fma_f32 v[34:35], v[68:69], v[12:13], v[34:35]
	v_pk_fma_f32 v[36:37], v[54:55], v[20:21], v[36:37]
	v_pk_fma_f32 v[34:35], v[72:73], v[14:15], v[34:35]
	v_pk_fma_f32 v[172:173], v[102:103], v[40:41], v[172:173]
	v_pk_fma_f32 v[34:35], v[76:77], v[16:17], v[34:35]
	v_pk_fma_f32 v[38:39], v[58:59], v[20:21], v[38:39]
	v_pk_fma_f32 v[34:35], v[80:81], v[26:27], v[34:35]
	v_pk_fma_f32 v[36:37], v[58:59], v[18:19], v[36:37]
	v_pk_fma_f32 v[34:35], v[84:85], v[28:29], v[34:35]
	v_add_f32_e32 v183, v172, v173
	v_pk_fma_f32 v[34:35], v[88:89], v[30:31], v[34:35]
	v_pk_fma_f32 v[38:39], v[62:63], v[18:19], v[38:39]
	v_pk_fma_f32 v[34:35], v[92:93], v[32:33], v[34:35]
	v_pk_fma_f32 v[36:37], v[62:63], v[10:11], v[36:37]
	v_pk_fma_f32 v[34:35], v[96:97], v[40:41], v[34:35]
	v_mul_f32_e32 v173, v44, v23
	v_pk_fma_f32 v[34:35], v[100:101], v[156:157], v[34:35]
	v_pk_fma_f32 v[38:39], v[66:67], v[10:11], v[38:39]
	v_add_f32_e32 v186, v34, v35
	v_mul_f32_e32 v35, v44, v25
	v_pk_fma_f32 v[24:25], v[44:45], v[24:25], v[104:105]
	v_mov_b32_e32 v34, v104
	v_pk_fma_f32 v[24:25], v[48:49], v[22:23], v[24:25]
	v_pk_fma_f32 v[34:35], v[46:47], v[22:23], v[34:35]
	v_pk_fma_f32 v[24:25], v[52:53], v[20:21], v[24:25]
	v_pk_fma_f32 v[34:35], v[50:51], v[20:21], v[34:35]
	v_pk_fma_f32 v[24:25], v[56:57], v[18:19], v[24:25]
	v_pk_fma_f32 v[34:35], v[54:55], v[18:19], v[34:35]
	v_pk_fma_f32 v[24:25], v[60:61], v[10:11], v[24:25]
	v_pk_fma_f32 v[34:35], v[58:59], v[10:11], v[34:35]
	v_pk_fma_f32 v[24:25], v[64:65], v[12:13], v[24:25]
	v_pk_fma_f32 v[34:35], v[62:63], v[12:13], v[34:35]
	v_pk_fma_f32 v[24:25], v[68:69], v[14:15], v[24:25]
	v_pk_fma_f32 v[36:37], v[66:67], v[12:13], v[36:37]
	v_pk_fma_f32 v[24:25], v[72:73], v[16:17], v[24:25]
	v_pk_fma_f32 v[34:35], v[66:67], v[14:15], v[34:35]
	v_pk_fma_f32 v[24:25], v[76:77], v[26:27], v[24:25]
	v_pk_fma_f32 v[38:39], v[70:71], v[12:13], v[38:39]
	v_pk_fma_f32 v[24:25], v[80:81], v[28:29], v[24:25]
	v_pk_fma_f32 v[36:37], v[70:71], v[14:15], v[36:37]
	v_pk_fma_f32 v[24:25], v[84:85], v[30:31], v[24:25]
	v_pk_fma_f32 v[34:35], v[70:71], v[16:17], v[34:35]
	v_pk_fma_f32 v[24:25], v[88:89], v[32:33], v[24:25]
	v_pk_fma_f32 v[38:39], v[74:75], v[14:15], v[38:39]
	v_pk_fma_f32 v[24:25], v[92:93], v[40:41], v[24:25]
	v_pk_fma_f32 v[36:37], v[74:75], v[16:17], v[36:37]
	v_pk_fma_f32 v[24:25], v[96:97], v[156:157], v[24:25]
	v_pk_fma_f32 v[34:35], v[74:75], v[26:27], v[34:35]
	v_pk_fma_f32 v[24:25], v[100:101], v[158:159], v[24:25]
	v_pk_fma_f32 v[38:39], v[78:79], v[16:17], v[38:39]
	v_add_f32_e32 v188, v24, v25
	ds_read2st64_b32 v[24:25], v163 offset0:216 offset1:220
	v_pk_fma_f32 v[36:37], v[78:79], v[26:27], v[36:37]
	v_pk_fma_f32 v[34:35], v[78:79], v[28:29], v[34:35]
	v_pk_fma_f32 v[38:39], v[82:83], v[26:27], v[38:39]
	v_pk_fma_f32 v[36:37], v[82:83], v[28:29], v[36:37]
	s_waitcnt lgkmcnt(0)
	v_mul_f32_e32 v105, v103, v24
	v_pk_fma_f32 v[22:23], v[44:45], v[22:23], v[104:105]
	v_pk_fma_f32 v[34:35], v[82:83], v[30:31], v[34:35]
	v_pk_fma_f32 v[22:23], v[48:49], v[20:21], v[22:23]
	v_pk_fma_f32 v[38:39], v[86:87], v[28:29], v[38:39]
	v_pk_fma_f32 v[22:23], v[52:53], v[18:19], v[22:23]
	v_pk_fma_f32 v[36:37], v[86:87], v[30:31], v[36:37]
	v_pk_fma_f32 v[22:23], v[56:57], v[10:11], v[22:23]
	v_pk_fma_f32 v[34:35], v[86:87], v[32:33], v[34:35]
	v_pk_fma_f32 v[22:23], v[60:61], v[12:13], v[22:23]
	v_pk_fma_f32 v[38:39], v[90:91], v[30:31], v[38:39]
	v_pk_fma_f32 v[22:23], v[64:65], v[14:15], v[22:23]
	v_pk_fma_f32 v[36:37], v[90:91], v[32:33], v[36:37]
	v_pk_fma_f32 v[22:23], v[68:69], v[16:17], v[22:23]
	v_pk_fma_f32 v[34:35], v[90:91], v[40:41], v[34:35]
	v_pk_fma_f32 v[22:23], v[72:73], v[26:27], v[22:23]
	v_pk_fma_f32 v[38:39], v[94:95], v[32:33], v[38:39]
	v_pk_fma_f32 v[36:37], v[94:95], v[40:41], v[36:37]
	v_pk_fma_f32 v[34:35], v[94:95], v[156:157], v[34:35]
	v_pk_fma_f32 v[22:23], v[76:77], v[28:29], v[22:23]
	v_pk_fma_f32 v[38:39], v[98:99], v[40:41], v[38:39]
	v_pk_fma_f32 v[36:37], v[98:99], v[156:157], v[36:37]
	v_pk_fma_f32 v[34:35], v[98:99], v[158:159], v[34:35]
	v_pk_fma_f32 v[22:23], v[80:81], v[30:31], v[22:23]
	v_pk_fma_f32 v[38:39], v[102:103], v[156:157], v[38:39]
	v_pk_fma_f32 v[36:37], v[102:103], v[158:159], v[36:37]
	v_pk_fma_f32 v[34:35], v[102:103], v[160:161], v[34:35]
	v_pk_fma_f32 v[22:23], v[84:85], v[32:33], v[22:23]
	v_add_f32_e32 v185, v38, v39
	v_add_f32_e32 v187, v36, v37
	v_add_f32_e32 v189, v34, v35
	ds_read2st64_b32 v[34:35], v163 offset0:224 offset1:228
	ds_read2st64_b32 v[36:37], v163 offset0:232 offset1:236
	ds_read2st64_b32 v[38:39], v163 offset0:240 offset1:244
	v_pk_fma_f32 v[22:23], v[88:89], v[40:41], v[22:23]
	v_mov_b32_e32 v172, v104
	v_pk_fma_f32 v[22:23], v[92:93], v[156:157], v[22:23]
	s_waitcnt lgkmcnt(2)
	v_mul_f32_e32 v105, v103, v34
	v_pk_fma_f32 v[22:23], v[96:97], v[158:159], v[22:23]
	v_pk_fma_f32 v[172:173], v[46:47], v[20:21], v[172:173]
	v_pk_fma_f32 v[22:23], v[100:101], v[160:161], v[22:23]
	v_pk_fma_f32 v[172:173], v[50:51], v[18:19], v[172:173]
	v_add_f32_e32 v190, v22, v23
	v_mul_f32_e32 v23, v44, v21
	v_pk_fma_f32 v[20:21], v[44:45], v[20:21], v[104:105]
	v_pk_fma_f32 v[172:173], v[54:55], v[10:11], v[172:173]
	v_pk_fma_f32 v[20:21], v[48:49], v[18:19], v[20:21]
	v_pk_fma_f32 v[172:173], v[58:59], v[12:13], v[172:173]
	v_pk_fma_f32 v[20:21], v[52:53], v[10:11], v[20:21]
	v_pk_fma_f32 v[172:173], v[62:63], v[14:15], v[172:173]
	v_pk_fma_f32 v[20:21], v[56:57], v[12:13], v[20:21]
	v_pk_fma_f32 v[172:173], v[66:67], v[16:17], v[172:173]
	v_pk_fma_f32 v[20:21], v[60:61], v[14:15], v[20:21]
	v_pk_fma_f32 v[172:173], v[70:71], v[26:27], v[172:173]
	v_pk_fma_f32 v[20:21], v[64:65], v[16:17], v[20:21]
	v_pk_fma_f32 v[172:173], v[74:75], v[28:29], v[172:173]
	v_pk_fma_f32 v[20:21], v[68:69], v[26:27], v[20:21]
	v_pk_fma_f32 v[172:173], v[78:79], v[30:31], v[172:173]
	v_pk_fma_f32 v[20:21], v[72:73], v[28:29], v[20:21]
	v_pk_fma_f32 v[172:173], v[82:83], v[32:33], v[172:173]
	v_pk_fma_f32 v[20:21], v[76:77], v[30:31], v[20:21]
	v_pk_fma_f32 v[172:173], v[86:87], v[40:41], v[172:173]
	v_pk_fma_f32 v[20:21], v[80:81], v[32:33], v[20:21]
	v_pk_fma_f32 v[172:173], v[90:91], v[156:157], v[172:173]
	v_pk_fma_f32 v[20:21], v[84:85], v[40:41], v[20:21]
	v_pk_fma_f32 v[172:173], v[94:95], v[158:159], v[172:173]
	v_pk_fma_f32 v[20:21], v[88:89], v[156:157], v[20:21]
	v_pk_fma_f32 v[172:173], v[98:99], v[160:161], v[172:173]
	v_pk_fma_f32 v[20:21], v[92:93], v[158:159], v[20:21]
	v_pk_fma_f32 v[172:173], v[102:103], v[24:25], v[172:173]
	v_pk_fma_f32 v[20:21], v[96:97], v[160:161], v[20:21]
	v_mov_b32_e32 v22, v104
	v_pk_fma_f32 v[20:21], v[100:101], v[24:25], v[20:21]
	s_waitcnt lgkmcnt(1)
	v_mul_f32_e32 v105, v103, v36
	v_add_f32_e32 v172, v172, v173
	v_pk_fma_f32 v[22:23], v[46:47], v[18:19], v[22:23]
	v_add_f32_e32 v173, v20, v21
	v_mul_f32_e32 v21, v44, v19
	v_pk_fma_f32 v[18:19], v[44:45], v[18:19], v[104:105]
	v_pk_fma_f32 v[22:23], v[50:51], v[10:11], v[22:23]
	v_pk_fma_f32 v[18:19], v[48:49], v[10:11], v[18:19]
	v_pk_fma_f32 v[22:23], v[54:55], v[12:13], v[22:23]
	v_pk_fma_f32 v[18:19], v[52:53], v[12:13], v[18:19]
	v_pk_fma_f32 v[22:23], v[58:59], v[14:15], v[22:23]
	v_pk_fma_f32 v[18:19], v[56:57], v[14:15], v[18:19]
	v_pk_fma_f32 v[22:23], v[62:63], v[16:17], v[22:23]
	v_pk_fma_f32 v[18:19], v[60:61], v[16:17], v[18:19]
	v_pk_fma_f32 v[22:23], v[66:67], v[26:27], v[22:23]
	v_pk_fma_f32 v[18:19], v[64:65], v[26:27], v[18:19]
	v_pk_fma_f32 v[22:23], v[70:71], v[28:29], v[22:23]
	v_pk_fma_f32 v[18:19], v[68:69], v[28:29], v[18:19]
	v_pk_fma_f32 v[22:23], v[74:75], v[30:31], v[22:23]
	v_pk_fma_f32 v[18:19], v[72:73], v[30:31], v[18:19]
	v_pk_fma_f32 v[22:23], v[78:79], v[32:33], v[22:23]
	v_pk_fma_f32 v[18:19], v[76:77], v[32:33], v[18:19]
	v_pk_fma_f32 v[22:23], v[82:83], v[40:41], v[22:23]
	v_pk_fma_f32 v[18:19], v[80:81], v[40:41], v[18:19]
	v_pk_fma_f32 v[22:23], v[86:87], v[156:157], v[22:23]
	v_pk_fma_f32 v[18:19], v[84:85], v[156:157], v[18:19]
	v_pk_fma_f32 v[22:23], v[90:91], v[158:159], v[22:23]
	v_pk_fma_f32 v[18:19], v[88:89], v[158:159], v[18:19]
	v_pk_fma_f32 v[22:23], v[94:95], v[160:161], v[22:23]
	v_pk_fma_f32 v[18:19], v[92:93], v[160:161], v[18:19]
	v_pk_fma_f32 v[22:23], v[98:99], v[24:25], v[22:23]
	v_pk_fma_f32 v[18:19], v[96:97], v[24:25], v[18:19]
	v_pk_fma_f32 v[22:23], v[102:103], v[34:35], v[22:23]
	v_pk_fma_f32 v[18:19], v[100:101], v[34:35], v[18:19]
	v_add_f32_e32 v22, v22, v23
	v_mov_b32_e32 v20, v104
	v_add_f32_e32 v23, v18, v19
	s_waitcnt lgkmcnt(0)
	v_mul_f32_e32 v105, v103, v38
	v_mul_f32_e32 v19, v44, v11
	v_mov_b32_e32 v18, v104
	v_pk_fma_f32 v[20:21], v[46:47], v[10:11], v[20:21]
	v_pk_fma_f32 v[10:11], v[44:45], v[10:11], v[104:105]
	v_pk_fma_f32 v[18:19], v[46:47], v[12:13], v[18:19]
	v_pk_fma_f32 v[20:21], v[50:51], v[12:13], v[20:21]
	v_pk_fma_f32 v[10:11], v[48:49], v[12:13], v[10:11]
	v_pk_fma_f32 v[12:13], v[50:51], v[14:15], v[18:19]
	v_pk_fma_f32 v[20:21], v[54:55], v[14:15], v[20:21]
	v_pk_fma_f32 v[10:11], v[52:53], v[14:15], v[10:11]
	v_pk_fma_f32 v[12:13], v[54:55], v[16:17], v[12:13]
	v_pk_fma_f32 v[20:21], v[58:59], v[16:17], v[20:21]
	v_pk_fma_f32 v[10:11], v[56:57], v[16:17], v[10:11]
	v_pk_fma_f32 v[12:13], v[58:59], v[26:27], v[12:13]
	v_pk_fma_f32 v[20:21], v[62:63], v[26:27], v[20:21]
	v_pk_fma_f32 v[10:11], v[60:61], v[26:27], v[10:11]
	v_pk_fma_f32 v[12:13], v[62:63], v[28:29], v[12:13]
	v_pk_fma_f32 v[20:21], v[66:67], v[28:29], v[20:21]
	v_pk_fma_f32 v[10:11], v[64:65], v[28:29], v[10:11]
	v_pk_fma_f32 v[12:13], v[66:67], v[30:31], v[12:13]
	v_pk_fma_f32 v[20:21], v[70:71], v[30:31], v[20:21]
	v_pk_fma_f32 v[10:11], v[68:69], v[30:31], v[10:11]
	v_pk_fma_f32 v[12:13], v[70:71], v[32:33], v[12:13]
	v_pk_fma_f32 v[20:21], v[74:75], v[32:33], v[20:21]
	v_pk_fma_f32 v[10:11], v[72:73], v[32:33], v[10:11]
	v_pk_fma_f32 v[12:13], v[74:75], v[40:41], v[12:13]
	v_pk_fma_f32 v[20:21], v[78:79], v[40:41], v[20:21]
	v_pk_fma_f32 v[10:11], v[76:77], v[40:41], v[10:11]
	v_pk_fma_f32 v[12:13], v[78:79], v[156:157], v[12:13]
	v_pk_fma_f32 v[20:21], v[82:83], v[156:157], v[20:21]
	v_pk_fma_f32 v[10:11], v[80:81], v[156:157], v[10:11]
	v_pk_fma_f32 v[12:13], v[82:83], v[158:159], v[12:13]
	v_pk_fma_f32 v[20:21], v[86:87], v[158:159], v[20:21]
	v_pk_fma_f32 v[10:11], v[84:85], v[158:159], v[10:11]
	v_pk_fma_f32 v[12:13], v[86:87], v[160:161], v[12:13]
	v_pk_fma_f32 v[20:21], v[90:91], v[160:161], v[20:21]
	v_pk_fma_f32 v[10:11], v[88:89], v[160:161], v[10:11]
	v_pk_fma_f32 v[12:13], v[90:91], v[24:25], v[12:13]
	v_pk_fma_f32 v[20:21], v[94:95], v[24:25], v[20:21]
	v_pk_fma_f32 v[10:11], v[92:93], v[24:25], v[10:11]
	v_pk_fma_f32 v[12:13], v[94:95], v[34:35], v[12:13]
	s_lshl_b32 s6, s28, 10
	v_pk_fma_f32 v[20:21], v[98:99], v[34:35], v[20:21]
	v_pk_fma_f32 v[10:11], v[96:97], v[34:35], v[10:11]
	v_pk_fma_f32 v[12:13], v[98:99], v[36:37], v[12:13]
	s_add_i32 s6, s6, 0
	v_pk_fma_f32 v[20:21], v[102:103], v[36:37], v[20:21]
	v_pk_fma_f32 v[10:11], v[100:101], v[36:37], v[10:11]
	v_pk_fma_f32 v[12:13], v[102:103], v[38:39], v[12:13]
	v_add_u32_e32 v105, s6, v162
	v_add_f32_e32 v20, v20, v21
	v_add_f32_e32 v10, v10, v11
	v_add_f32_e32 v11, v12, v13
	s_barrier
	ds_write2st64_b32 v163, v164, v165 offset1:4
	ds_write2st64_b32 v163, v166, v167 offset0:8 offset1:12
	ds_write2st64_b32 v163, v168, v169 offset0:16 offset1:20
	ds_write2st64_b32 v163, v170, v171 offset0:24 offset1:28
	ds_write2st64_b32 v163, v174, v175 offset0:32 offset1:36
	ds_write2st64_b32 v163, v176, v177 offset0:40 offset1:44
	ds_write2st64_b32 v163, v178, v179 offset0:48 offset1:52
	ds_write2st64_b32 v163, v180, v181 offset0:56 offset1:60
	ds_write2st64_b32 v163, v182, v183 offset0:64 offset1:68
	ds_write2st64_b32 v163, v184, v185 offset0:72 offset1:76
	ds_write2st64_b32 v163, v186, v187 offset0:80 offset1:84
	ds_write2st64_b32 v163, v188, v189 offset0:88 offset1:92
	ds_write2st64_b32 v163, v190, v172 offset0:96 offset1:100
	ds_write2st64_b32 v163, v173, v22 offset0:104 offset1:108
	ds_write2st64_b32 v163, v23, v20 offset0:112 offset1:116
	ds_write2st64_b32 v163, v10, v11 offset0:120 offset1:124
	s_waitcnt lgkmcnt(0)
	s_barrier
	ds_read_b128 v[38:41], v105
	ds_read_b128 v[34:37], v105 offset:8192
	ds_read_b128 v[30:33], v105 offset:16384
	ds_read_b128 v[26:29], v105 offset:24576
	ds_read_b128 v[22:25], v105 offset:32768
	ds_read_b128 v[18:21], v105 offset:40960
	s_waitcnt lgkmcnt(5)
	v_mov_b32_e32 v10, v39
	v_mov_b32_e32 v11, v40
	v_mov_b32_e32 v12, v38
	v_mov_b32_e32 v13, v41
	v_pk_add_f32 v[10:11], v[10:11], v[12:13]
	s_waitcnt lgkmcnt(4)
	v_mov_b32_e32 v12, v34
	v_add_f32_e32 v160, v10, v11
	v_mov_b32_e32 v10, v35
	v_mov_b32_e32 v11, v36
	v_mov_b32_e32 v13, v37
	v_pk_add_f32 v[10:11], v[10:11], v[12:13]
	s_waitcnt lgkmcnt(3)
	v_mov_b32_e32 v12, v30
	v_add_f32_e32 v161, v10, v11
	v_mov_b32_e32 v10, v31
	v_mov_b32_e32 v11, v32
	v_mov_b32_e32 v13, v33
	v_pk_add_f32 v[10:11], v[10:11], v[12:13]
	s_waitcnt lgkmcnt(2)
	v_mov_b32_e32 v12, v26
	v_add_f32_e32 v162, v10, v11
	v_mov_b32_e32 v10, v27
	v_mov_b32_e32 v11, v28
	v_mov_b32_e32 v13, v29
	v_pk_add_f32 v[10:11], v[10:11], v[12:13]
	s_waitcnt lgkmcnt(1)
	v_mov_b32_e32 v12, v22
	v_add_f32_e32 v163, v10, v11
	v_mov_b32_e32 v10, v23
	v_mov_b32_e32 v11, v24
	v_mov_b32_e32 v13, v25
	v_pk_add_f32 v[10:11], v[10:11], v[12:13]
	s_waitcnt lgkmcnt(0)
	v_mov_b32_e32 v12, v18
	v_add_f32_e32 v164, v10, v11
	v_mov_b32_e32 v10, v19
	v_mov_b32_e32 v11, v20
	ds_read_b128 v[14:17], v105 offset:49152
	v_mov_b32_e32 v13, v21
	v_pk_add_f32 v[10:11], v[10:11], v[12:13]
	s_add_i32 s28, s52, s28
	v_add_f32_e32 v165, v10, v11
	ds_read_b128 v[10:13], v105 offset:57344
	s_waitcnt lgkmcnt(1)
	v_mov_b32_e32 v156, v15
	v_mov_b32_e32 v157, v16
	v_mov_b32_e32 v158, v14
	v_mov_b32_e32 v159, v17
	v_pk_add_f32 v[156:157], v[156:157], v[158:159]
	s_waitcnt lgkmcnt(0)
	v_mov_b32_e32 v158, v10
	v_add_f32_e32 v105, v156, v157
	v_mov_b32_e32 v156, v11
	v_mov_b32_e32 v157, v12
	v_mov_b32_e32 v159, v13
	v_pk_add_f32 v[156:157], v[156:157], v[158:159]
	v_add_f32_dpp v158, v161, v161 quad_perm:[1,0,3,2] row_mask:0xf bank_mask:0xf bound_ctrl:1
	v_add_f32_e32 v156, v156, v157
	v_add_f32_dpp v157, v160, v160 quad_perm:[1,0,3,2] row_mask:0xf bank_mask:0xf bound_ctrl:1
	v_add_f32_dpp v160, v163, v163 quad_perm:[1,0,3,2] row_mask:0xf bank_mask:0xf bound_ctrl:1
	v_add_f32_dpp v158, v158, v158 quad_perm:[2,3,0,1] row_mask:0xf bank_mask:0xf bound_ctrl:1
	v_add_f32_dpp v157, v157, v157 quad_perm:[2,3,0,1] row_mask:0xf bank_mask:0xf bound_ctrl:1
	v_add_f32_dpp v159, v162, v162 quad_perm:[1,0,3,2] row_mask:0xf bank_mask:0xf bound_ctrl:1
	s_nop 0
	v_add_f32_dpp v157, v157, v157 row_half_mirror row_mask:0xf bank_mask:0xf bound_ctrl:1
	v_add_f32_dpp v158, v158, v158 row_half_mirror row_mask:0xf bank_mask:0xf bound_ctrl:1
	v_add_f32_dpp v159, v159, v159 quad_perm:[2,3,0,1] row_mask:0xf bank_mask:0xf bound_ctrl:1
	v_add_f32_dpp v157, v157, v157 row_mirror row_mask:0xf bank_mask:0xf bound_ctrl:1
	v_add_f32_dpp v158, v158, v158 row_mirror row_mask:0xf bank_mask:0xf bound_ctrl:1
	v_add_f32_dpp v159, v159, v159 row_half_mirror row_mask:0xf bank_mask:0xf bound_ctrl:1
	v_add_f32_dpp v157, v157, v157 row_bcast:15 row_mask:0xa bank_mask:0xf
	v_add_f32_dpp v160, v160, v160 quad_perm:[2,3,0,1] row_mask:0xf bank_mask:0xf bound_ctrl:1
	v_add_f32_dpp v159, v159, v159 row_mirror row_mask:0xf bank_mask:0xf bound_ctrl:1
	v_add_f32_dpp v158, v158, v158 row_bcast:15 row_mask:0xa bank_mask:0xf
	v_add_f32_dpp v161, v164, v164 quad_perm:[1,0,3,2] row_mask:0xf bank_mask:0xf bound_ctrl:1
	v_add_f32_dpp v160, v160, v160 row_half_mirror row_mask:0xf bank_mask:0xf bound_ctrl:1
	v_add_f32_dpp v159, v159, v159 row_bcast:15 row_mask:0xa bank_mask:0xf
	v_add_f32_dpp v161, v161, v161 quad_perm:[2,3,0,1] row_mask:0xf bank_mask:0xf bound_ctrl:1
	v_add_f32_dpp v160, v160, v160 row_mirror row_mask:0xf bank_mask:0xf bound_ctrl:1
	v_add_f32_dpp v162, v165, v165 quad_perm:[1,0,3,2] row_mask:0xf bank_mask:0xf bound_ctrl:1
	v_add_f32_dpp v161, v161, v161 row_half_mirror row_mask:0xf bank_mask:0xf bound_ctrl:1
	v_add_f32_dpp v160, v160, v160 row_bcast:15 row_mask:0xa bank_mask:0xf
	v_add_f32_dpp v162, v162, v162 quad_perm:[2,3,0,1] row_mask:0xf bank_mask:0xf bound_ctrl:1
	v_add_f32_dpp v161, v161, v161 row_mirror row_mask:0xf bank_mask:0xf bound_ctrl:1
	v_add_f32_dpp v105, v105, v105 quad_perm:[1,0,3,2] row_mask:0xf bank_mask:0xf bound_ctrl:1
	v_add_f32_dpp v162, v162, v162 row_half_mirror row_mask:0xf bank_mask:0xf bound_ctrl:1
	v_add_f32_dpp v161, v161, v161 row_bcast:15 row_mask:0xa bank_mask:0xf
	v_add_f32_dpp v105, v105, v105 quad_perm:[2,3,0,1] row_mask:0xf bank_mask:0xf bound_ctrl:1
	v_add_f32_dpp v162, v162, v162 row_mirror row_mask:0xf bank_mask:0xf bound_ctrl:1
	v_add_f32_dpp v156, v156, v156 quad_perm:[1,0,3,2] row_mask:0xf bank_mask:0xf bound_ctrl:1
	v_add_f32_dpp v105, v105, v105 row_half_mirror row_mask:0xf bank_mask:0xf bound_ctrl:1
	v_add_f32_dpp v162, v162, v162 row_bcast:15 row_mask:0xa bank_mask:0xf
	v_add_f32_dpp v156, v156, v156 quad_perm:[2,3,0,1] row_mask:0xf bank_mask:0xf bound_ctrl:1
	v_add_f32_dpp v105, v105, v105 row_mirror row_mask:0xf bank_mask:0xf bound_ctrl:1
	s_nop 0
	v_add_f32_dpp v156, v156, v156 row_half_mirror row_mask:0xf bank_mask:0xf bound_ctrl:1
	s_nop 0
	v_add_f32_dpp v105, v105, v105 row_bcast:15 row_mask:0xa bank_mask:0xf
	v_add_f32_dpp v156, v156, v156 row_mirror row_mask:0xf bank_mask:0xf bound_ctrl:1
	s_nop 1
	v_add_f32_dpp v156, v156, v156 row_bcast:15 row_mask:0xa bank_mask:0xf
	s_nop 1
	v_add_f32_dpp v157, v157, v157 row_bcast:31 row_mask:0xc bank_mask:0xf
	s_nop 0
	v_readlane_b32 s6, v157, 63
	s_nop 0
	v_add_f32_dpp v158, v158, v158 row_bcast:31 row_mask:0xc bank_mask:0xf
	v_fma_f32 v39, s6, v239, v39
	v_fma_f32 v38, s6, v239, v38
	v_add_f32_dpp v159, v159, v159 row_bcast:31 row_mask:0xc bank_mask:0xf
	v_fma_f32 v41, s6, v239, v41
	v_fmac_f32_e32 v40, s6, v239
	v_add_f32_dpp v160, v160, v160 row_bcast:31 row_mask:0xc bank_mask:0xf
	v_readlane_b32 s7, v158, 63
	v_readlane_b32 s8, v159, 63
	v_add_f32_dpp v161, v161, v161 row_bcast:31 row_mask:0xc bank_mask:0xf
	v_pk_mul_f32 v[158:159], v[38:39], v[38:39]
	v_readlane_b32 s9, v160, 63
	v_add_f32_dpp v162, v162, v162 row_bcast:31 row_mask:0xc bank_mask:0xf
	v_readlane_b32 s10, v161, 63
	v_fma_f32 v35, s7, v239, v35
	v_add_f32_dpp v105, v105, v105 row_bcast:31 row_mask:0xc bank_mask:0xf
	v_fma_f32 v34, s7, v239, v34
	v_fma_f32 v37, s7, v239, v37
	v_add_f32_dpp v156, v156, v156 row_bcast:31 row_mask:0xc bank_mask:0xf
	v_fmac_f32_e32 v36, s7, v239
	v_readlane_b32 s55, v156, 63
	v_pk_mul_f32 v[156:157], v[40:41], v[40:41]
	v_readlane_b32 s29, v105, 63
	v_pk_mov_b32 v[160:161], v[158:159], v[156:157] op_sel:[1,0]
	v_mov_b32_e32 v159, v157
	v_pk_add_f32 v[156:157], v[160:161], v[158:159]
	v_pk_mul_f32 v[158:159], v[34:35], v[34:35]
	v_add_f32_e32 v105, v156, v157
	v_pk_mul_f32 v[156:157], v[36:37], v[36:37]
	v_fma_f32 v31, s8, v239, v31
	v_pk_mov_b32 v[160:161], v[158:159], v[156:157] op_sel:[1,0]
	v_mov_b32_e32 v159, v157
	v_pk_add_f32 v[156:157], v[160:161], v[158:159]
	v_fma_f32 v30, s8, v239, v30
	v_fma_f32 v33, s8, v239, v33
	v_fmac_f32_e32 v32, s8, v239
	v_readlane_b32 s11, v162, 63
	v_add_f32_e32 v162, v156, v157
	v_pk_mul_f32 v[156:157], v[32:33], v[32:33]
	v_pk_mul_f32 v[158:159], v[30:31], v[30:31]
	v_fma_f32 v27, s9, v239, v27
	v_pk_mov_b32 v[160:161], v[158:159], v[156:157] op_sel:[1,0]
	v_mov_b32_e32 v159, v157
	v_pk_add_f32 v[156:157], v[160:161], v[158:159]
	v_fma_f32 v26, s9, v239, v26
	v_fma_f32 v29, s9, v239, v29
	v_fmac_f32_e32 v28, s9, v239
	v_add_f32_e32 v163, v156, v157
	v_pk_mul_f32 v[156:157], v[28:29], v[28:29]
	v_pk_mul_f32 v[158:159], v[26:27], v[26:27]
	v_fma_f32 v23, s10, v239, v23
	v_pk_mov_b32 v[160:161], v[158:159], v[156:157] op_sel:[1,0]
	v_mov_b32_e32 v159, v157
	v_pk_add_f32 v[156:157], v[160:161], v[158:159]
	v_fma_f32 v22, s10, v239, v22
	v_fma_f32 v25, s10, v239, v25
	v_fmac_f32_e32 v24, s10, v239
	v_add_f32_e32 v164, v156, v157
	v_pk_mul_f32 v[156:157], v[24:25], v[24:25]
	v_pk_mul_f32 v[158:159], v[22:23], v[22:23]
	v_fma_f32 v19, s11, v239, v19
	v_pk_mov_b32 v[160:161], v[158:159], v[156:157] op_sel:[1,0]
	v_mov_b32_e32 v159, v157
	v_pk_add_f32 v[156:157], v[160:161], v[158:159]
	v_fma_f32 v18, s11, v239, v18
	v_fma_f32 v21, s11, v239, v21
	v_fmac_f32_e32 v20, s11, v239
	v_add_f32_e32 v165, v156, v157
	v_pk_mul_f32 v[156:157], v[20:21], v[20:21]
	v_pk_mul_f32 v[158:159], v[18:19], v[18:19]
	v_fma_f32 v15, s29, v239, v15
	v_pk_mov_b32 v[160:161], v[158:159], v[156:157] op_sel:[1,0]
	v_mov_b32_e32 v159, v157
	v_pk_add_f32 v[156:157], v[160:161], v[158:159]
	v_fma_f32 v14, s29, v239, v14
	v_fma_f32 v17, s29, v239, v17
	v_fmac_f32_e32 v16, s29, v239
	v_add_f32_e32 v166, v156, v157
	v_pk_mul_f32 v[156:157], v[16:17], v[16:17]
	v_pk_mul_f32 v[158:159], v[14:15], v[14:15]
	v_fma_f32 v11, s55, v239, v11
	v_pk_mov_b32 v[160:161], v[158:159], v[156:157] op_sel:[1,0]
	v_mov_b32_e32 v159, v157
	v_pk_add_f32 v[156:157], v[160:161], v[158:159]
	v_fma_f32 v10, s55, v239, v10
	v_fma_f32 v13, s55, v239, v13
	v_fmac_f32_e32 v12, s55, v239
	v_add_f32_e32 v167, v156, v157
	v_pk_mul_f32 v[156:157], v[12:13], v[12:13]
	v_pk_mul_f32 v[158:159], v[10:11], v[10:11]
	v_add_f32_dpp v105, v105, v105 quad_perm:[1,0,3,2] row_mask:0xf bank_mask:0xf bound_ctrl:1
	v_pk_mov_b32 v[160:161], v[158:159], v[156:157] op_sel:[1,0]
	v_mov_b32_e32 v159, v157
	v_pk_add_f32 v[156:157], v[160:161], v[158:159]
	v_add_f32_dpp v105, v105, v105 quad_perm:[2,3,0,1] row_mask:0xf bank_mask:0xf bound_ctrl:1
	v_add_f32_e32 v156, v156, v157
	v_add_f32_dpp v157, v162, v162 quad_perm:[1,0,3,2] row_mask:0xf bank_mask:0xf bound_ctrl:1
	v_add_f32_dpp v105, v105, v105 row_half_mirror row_mask:0xf bank_mask:0xf bound_ctrl:1
	v_add_f32_dpp v158, v163, v163 quad_perm:[1,0,3,2] row_mask:0xf bank_mask:0xf bound_ctrl:1
	v_add_f32_dpp v157, v157, v157 quad_perm:[2,3,0,1] row_mask:0xf bank_mask:0xf bound_ctrl:1
	v_add_f32_dpp v105, v105, v105 row_mirror row_mask:0xf bank_mask:0xf bound_ctrl:1
	s_nop 0
	v_add_f32_dpp v157, v157, v157 row_half_mirror row_mask:0xf bank_mask:0xf bound_ctrl:1
	v_add_f32_dpp v158, v158, v158 quad_perm:[2,3,0,1] row_mask:0xf bank_mask:0xf bound_ctrl:1
	v_add_f32_dpp v105, v105, v105 row_bcast:15 row_mask:0xa bank_mask:0xf
	v_add_f32_dpp v157, v157, v157 row_mirror row_mask:0xf bank_mask:0xf bound_ctrl:1
	v_add_f32_dpp v159, v164, v164 quad_perm:[1,0,3,2] row_mask:0xf bank_mask:0xf bound_ctrl:1
	v_add_f32_dpp v158, v158, v158 row_half_mirror row_mask:0xf bank_mask:0xf bound_ctrl:1
	v_add_f32_dpp v157, v157, v157 row_bcast:15 row_mask:0xa bank_mask:0xf
	v_add_f32_dpp v159, v159, v159 quad_perm:[2,3,0,1] row_mask:0xf bank_mask:0xf bound_ctrl:1
	v_add_f32_dpp v158, v158, v158 row_mirror row_mask:0xf bank_mask:0xf bound_ctrl:1
	v_add_f32_dpp v160, v165, v165 quad_perm:[1,0,3,2] row_mask:0xf bank_mask:0xf bound_ctrl:1
	v_add_f32_dpp v159, v159, v159 row_half_mirror row_mask:0xf bank_mask:0xf bound_ctrl:1
	v_add_f32_dpp v158, v158, v158 row_bcast:15 row_mask:0xa bank_mask:0xf
	v_add_f32_dpp v160, v160, v160 quad_perm:[2,3,0,1] row_mask:0xf bank_mask:0xf bound_ctrl:1
	v_add_f32_dpp v159, v159, v159 row_mirror row_mask:0xf bank_mask:0xf bound_ctrl:1
	v_add_f32_dpp v161, v166, v166 quad_perm:[1,0,3,2] row_mask:0xf bank_mask:0xf bound_ctrl:1
	v_add_f32_dpp v160, v160, v160 row_half_mirror row_mask:0xf bank_mask:0xf bound_ctrl:1
	v_add_f32_dpp v159, v159, v159 row_bcast:15 row_mask:0xa bank_mask:0xf
	v_add_f32_dpp v161, v161, v161 quad_perm:[2,3,0,1] row_mask:0xf bank_mask:0xf bound_ctrl:1
	v_add_f32_dpp v160, v160, v160 row_mirror row_mask:0xf bank_mask:0xf bound_ctrl:1
	v_add_f32_dpp v162, v167, v167 quad_perm:[1,0,3,2] row_mask:0xf bank_mask:0xf bound_ctrl:1
	v_add_f32_dpp v161, v161, v161 row_half_mirror row_mask:0xf bank_mask:0xf bound_ctrl:1
	v_add_f32_dpp v160, v160, v160 row_bcast:15 row_mask:0xa bank_mask:0xf
	v_add_f32_dpp v162, v162, v162 quad_perm:[2,3,0,1] row_mask:0xf bank_mask:0xf bound_ctrl:1
	v_add_f32_dpp v161, v161, v161 row_mirror row_mask:0xf bank_mask:0xf bound_ctrl:1
	v_add_f32_dpp v156, v156, v156 quad_perm:[1,0,3,2] row_mask:0xf bank_mask:0xf bound_ctrl:1
	v_add_f32_dpp v162, v162, v162 row_half_mirror row_mask:0xf bank_mask:0xf bound_ctrl:1
	v_add_f32_dpp v161, v161, v161 row_bcast:15 row_mask:0xa bank_mask:0xf
	v_add_f32_dpp v156, v156, v156 quad_perm:[2,3,0,1] row_mask:0xf bank_mask:0xf bound_ctrl:1
	v_add_f32_dpp v162, v162, v162 row_mirror row_mask:0xf bank_mask:0xf bound_ctrl:1
	s_nop 0
	v_add_f32_dpp v156, v156, v156 row_half_mirror row_mask:0xf bank_mask:0xf bound_ctrl:1
	s_add_i32 s8, s28, -8
	v_add_f32_dpp v162, v162, v162 row_bcast:15 row_mask:0xa bank_mask:0xf
	v_add_f32_dpp v156, v156, v156 row_mirror row_mask:0xf bank_mask:0xf bound_ctrl:1
	s_ashr_i32 s9, s8, 31
	s_lshl_b64 s[8:9], s[8:9], 11
	v_add_f32_dpp v156, v156, v156 row_bcast:15 row_mask:0xa bank_mask:0xf
	s_add_u32 s8, s76, s8
	s_addc_u32 s9, s77, s9
	v_add_f32_dpp v105, v105, v105 row_bcast:31 row_mask:0xc bank_mask:0xf
	s_nop 0
	v_readlane_b32 s6, v105, 63
	s_ashr_i32 s29, s28, 31
	v_add_f32_dpp v157, v157, v157 row_bcast:31 row_mask:0xc bank_mask:0xf
	v_fma_f32 v105, s6, v235, v225
	v_readlane_b32 s10, v157, 63
	v_add_f32_dpp v158, v158, v158 row_bcast:31 row_mask:0xc bank_mask:0xf
	s_nop 0
	v_readlane_b32 s11, v158, 63
	s_nop 0
	v_add_f32_dpp v159, v159, v159 row_bcast:31 row_mask:0xc bank_mask:0xf
	s_nop 0
	v_readlane_b32 s57, v159, 63
	s_nop 0
	v_add_f32_dpp v160, v160, v160 row_bcast:31 row_mask:0xc bank_mask:0xf
	s_nop 0
	v_readlane_b32 s56, v160, 63
	s_nop 0
	v_add_f32_dpp v161, v161, v161 row_bcast:31 row_mask:0xc bank_mask:0xf
	s_nop 0
	v_readlane_b32 s55, v161, 63
	s_nop 0
	v_add_f32_dpp v162, v162, v162 row_bcast:31 row_mask:0xc bank_mask:0xf
	v_mov_b32_e32 v163, v131
	v_readlane_b32 s7, v162, 63
	s_nop 0
	v_mov_b32_dpp v163, v156 row_bcast:31 row_mask:0xc bank_mask:0xf
	v_add_f32_e32 v163, v156, v163
	v_rsq_f32_e32 v156, v105
	v_readlane_b32 s6, v163, 63
	v_pk_mul_f32 v[38:39], v[38:39], v[156:157] op_sel_hi:[1,0]
	s_nop 0
	v_pk_fma_f32 v[38:39], v[2:3], v[38:39], v[6:7]
	v_pk_mul_f32 v[40:41], v[40:41], v[156:157] op_sel_hi:[1,0]
	v_mul_f32_e32 v105, 0xbfb8aa3b, v38
	v_exp_f32_e32 v105, v105
	v_mul_f32_e32 v156, 0xbfb8aa3b, v39
	v_exp_f32_e32 v157, v156
	v_pk_fma_f32 v[40:41], v[4:5], v[40:41], v[8:9]
	v_add_f32_e32 v105, 1.0, v105
	v_rcp_f32_e32 v156, v105
	v_add_f32_e32 v105, 1.0, v157
	v_mul_f32_e32 v157, 0xbfb8aa3b, v40
	v_exp_f32_e32 v158, v157
	v_mul_f32_e32 v157, 0xbfb8aa3b, v41
	v_exp_f32_e32 v159, v157
	v_rcp_f32_e32 v157, v105
	v_add_f32_e32 v105, 1.0, v158
	v_rcp_f32_e32 v158, v105
	v_add_f32_e32 v105, 1.0, v159
	v_rcp_f32_e32 v159, v105
	v_pk_mul_f32 v[38:39], v[38:39], v[156:157]
	v_lshlrev_b32_e32 v105, 3, v130
	v_cvt_pk_bf16_f32 v38, v38, v39
	v_pk_mul_f32 v[40:41], v[40:41], v[158:159]
	v_cvt_pk_bf16_f32 v39, v40, v41
	v_fma_f32 v40, s10, v235, v225
	v_rsq_f32_e32 v40, v40
	global_store_dwordx2 v105, v[38:39], s[8:9] offset:512 sc1
	s_lshl_b64 s[8:9], s[28:29], 11
	s_add_u32 s8, s76, s8
	v_pk_mul_f32 v[36:37], v[36:37], v[40:41] op_sel_hi:[1,0]
	v_pk_mul_f32 v[34:35], v[34:35], v[40:41] op_sel_hi:[1,0]
	v_pk_fma_f32 v[36:37], v[4:5], v[36:37], v[8:9]
	v_pk_fma_f32 v[34:35], v[2:3], v[34:35], v[6:7]
	v_mul_f32_e32 v130, 0xbfb8aa3b, v36
	v_pk_mul_f32 v[40:41], v[34:35], s[96:97] op_sel_hi:[1,0]
	v_exp_f32_e32 v130, v130
	v_mul_f32_e32 v156, 0xbfb8aa3b, v37
	v_exp_f32_e32 v40, v40
	v_exp_f32_e32 v41, v41
	v_exp_f32_e32 v157, v156
	v_add_f32_e32 v130, 1.0, v130
	v_pk_add_f32 v[40:41], v[40:41], 1.0 op_sel_hi:[1,0]
	v_rcp_f32_e32 v156, v130
	v_add_f32_e32 v130, 1.0, v157
	v_rcp_f32_e32 v40, v40
	v_rcp_f32_e32 v41, v41
	v_rcp_f32_e32 v157, v130
	s_addc_u32 s9, s77, s9
	v_pk_mul_f32 v[34:35], v[34:35], v[40:41]
	v_pk_mul_f32 v[36:37], v[36:37], v[156:157]
	v_cvt_pk_bf16_f32 v34, v34, v35
	v_cvt_pk_bf16_f32 v35, v36, v37
	v_fma_f32 v36, s11, v235, v225
	v_rsq_f32_e32 v36, v36
	global_store_dwordx2 v105, v[34:35], s[8:9] offset:512 sc1
	s_add_i32 s8, s28, 8
	s_ashr_i32 s9, s8, 31
	v_pk_mul_f32 v[30:31], v[30:31], v[36:37] op_sel_hi:[1,0]
	v_pk_mul_f32 v[32:33], v[32:33], v[36:37] op_sel_hi:[1,0]
	v_pk_fma_f32 v[30:31], v[2:3], v[30:31], v[6:7]
	v_pk_fma_f32 v[32:33], v[4:5], v[32:33], v[8:9]
	v_pk_mul_f32 v[36:37], v[30:31], s[96:97] op_sel_hi:[1,0]
	v_pk_mul_f32 v[38:39], v[32:33], s[96:97] op_sel_hi:[1,0]
	v_exp_f32_e32 v36, v36
	v_exp_f32_e32 v37, v37
	v_exp_f32_e32 v38, v38
	v_exp_f32_e32 v39, v39
	v_pk_add_f32 v[36:37], v[36:37], 1.0 op_sel_hi:[1,0]
	v_pk_add_f32 v[38:39], v[38:39], 1.0 op_sel_hi:[1,0]
	v_rcp_f32_e32 v36, v36
	v_rcp_f32_e32 v37, v37
	v_rcp_f32_e32 v38, v38
	v_rcp_f32_e32 v39, v39
	s_lshl_b64 s[8:9], s[8:9], 11
	v_pk_mul_f32 v[30:31], v[30:31], v[36:37]
	s_add_u32 s8, s76, s8
	v_pk_mul_f32 v[32:33], v[32:33], v[38:39]
	v_cvt_pk_bf16_f32 v30, v30, v31
	v_cvt_pk_bf16_f32 v31, v32, v33
	v_fma_f32 v32, s57, v235, v225
	v_rsq_f32_e32 v32, v32
	s_addc_u32 s9, s77, s9
	global_store_dwordx2 v105, v[30:31], s[8:9] offset:512 sc1
	s_add_i32 s8, s28, 16
	v_pk_mul_f32 v[26:27], v[26:27], v[32:33] op_sel_hi:[1,0]
	v_pk_mul_f32 v[28:29], v[28:29], v[32:33] op_sel_hi:[1,0]
	v_pk_fma_f32 v[26:27], v[2:3], v[26:27], v[6:7]
	v_pk_fma_f32 v[28:29], v[4:5], v[28:29], v[8:9]
	v_pk_mul_f32 v[32:33], v[26:27], s[96:97] op_sel_hi:[1,0]
	v_pk_mul_f32 v[34:35], v[28:29], s[96:97] op_sel_hi:[1,0]
	v_exp_f32_e32 v32, v32
	v_exp_f32_e32 v33, v33
	v_exp_f32_e32 v34, v34
	v_exp_f32_e32 v35, v35
	v_pk_add_f32 v[32:33], v[32:33], 1.0 op_sel_hi:[1,0]
	v_pk_add_f32 v[34:35], v[34:35], 1.0 op_sel_hi:[1,0]
	v_rcp_f32_e32 v32, v32
	v_rcp_f32_e32 v33, v33
	v_rcp_f32_e32 v34, v34
	v_rcp_f32_e32 v35, v35
	s_ashr_i32 s9, s8, 31
	v_pk_mul_f32 v[26:27], v[26:27], v[32:33]
	s_lshl_b64 s[8:9], s[8:9], 11
	v_pk_mul_f32 v[28:29], v[28:29], v[34:35]
	v_cvt_pk_bf16_f32 v26, v26, v27
	v_cvt_pk_bf16_f32 v27, v28, v29
	v_fma_f32 v28, s56, v235, v225
	v_rsq_f32_e32 v28, v28
	s_add_u32 s8, s76, s8
	s_addc_u32 s9, s77, s9
	global_store_dwordx2 v105, v[26:27], s[8:9] offset:512 sc1
	v_pk_mul_f32 v[22:23], v[22:23], v[28:29] op_sel_hi:[1,0]
	v_pk_mul_f32 v[24:25], v[24:25], v[28:29] op_sel_hi:[1,0]
	v_pk_fma_f32 v[22:23], v[2:3], v[22:23], v[6:7]
	v_pk_fma_f32 v[24:25], v[4:5], v[24:25], v[8:9]
	v_pk_mul_f32 v[28:29], v[22:23], s[96:97] op_sel_hi:[1,0]
	v_pk_mul_f32 v[30:31], v[24:25], s[96:97] op_sel_hi:[1,0]
	v_exp_f32_e32 v28, v28
	v_exp_f32_e32 v29, v29
	v_exp_f32_e32 v30, v30
	v_exp_f32_e32 v31, v31
	v_pk_add_f32 v[28:29], v[28:29], 1.0 op_sel_hi:[1,0]
	v_pk_add_f32 v[30:31], v[30:31], 1.0 op_sel_hi:[1,0]
	v_rcp_f32_e32 v28, v28
	v_rcp_f32_e32 v29, v29
	v_rcp_f32_e32 v30, v30
	v_rcp_f32_e32 v31, v31
	s_add_i32 s8, s28, 24
	v_pk_mul_f32 v[22:23], v[22:23], v[28:29]
	s_ashr_i32 s9, s8, 31
	v_pk_mul_f32 v[24:25], v[24:25], v[30:31]
	v_cvt_pk_bf16_f32 v22, v22, v23
	v_cvt_pk_bf16_f32 v23, v24, v25
	v_fma_f32 v24, s55, v235, v225
	v_rsq_f32_e32 v24, v24
	s_lshl_b64 s[8:9], s[8:9], 11
	s_add_u32 s8, s76, s8
	s_addc_u32 s9, s77, s9
	v_pk_mul_f32 v[18:19], v[18:19], v[24:25] op_sel_hi:[1,0]
	v_pk_mul_f32 v[20:21], v[20:21], v[24:25] op_sel_hi:[1,0]
	v_pk_fma_f32 v[18:19], v[2:3], v[18:19], v[6:7]
	v_pk_fma_f32 v[20:21], v[4:5], v[20:21], v[8:9]
	v_pk_mul_f32 v[24:25], v[18:19], s[96:97] op_sel_hi:[1,0]
	v_pk_mul_f32 v[26:27], v[20:21], s[96:97] op_sel_hi:[1,0]
	v_exp_f32_e32 v24, v24
	v_exp_f32_e32 v25, v25
	v_exp_f32_e32 v26, v26
	v_exp_f32_e32 v27, v27
	v_pk_add_f32 v[24:25], v[24:25], 1.0 op_sel_hi:[1,0]
	v_pk_add_f32 v[26:27], v[26:27], 1.0 op_sel_hi:[1,0]
	v_rcp_f32_e32 v24, v24
	v_rcp_f32_e32 v25, v25
	v_rcp_f32_e32 v26, v26
	v_rcp_f32_e32 v27, v27
	global_store_dwordx2 v105, v[22:23], s[8:9] offset:512 sc1
	v_pk_mul_f32 v[18:19], v[18:19], v[24:25]
	s_add_i32 s8, s28, 32
	v_pk_mul_f32 v[20:21], v[20:21], v[26:27]
	v_cvt_pk_bf16_f32 v18, v18, v19
	v_cvt_pk_bf16_f32 v19, v20, v21
	v_fma_f32 v20, s7, v235, v225
	v_rsq_f32_e32 v20, v20
	s_ashr_i32 s9, s8, 31
	s_lshl_b64 s[8:9], s[8:9], 11
	s_add_u32 s8, s76, s8
	v_pk_mul_f32 v[14:15], v[14:15], v[20:21] op_sel_hi:[1,0]
	v_pk_mul_f32 v[16:17], v[16:17], v[20:21] op_sel_hi:[1,0]
	v_pk_fma_f32 v[14:15], v[2:3], v[14:15], v[6:7]
	v_pk_fma_f32 v[16:17], v[4:5], v[16:17], v[8:9]
	v_pk_mul_f32 v[20:21], v[14:15], s[96:97] op_sel_hi:[1,0]
	v_pk_mul_f32 v[22:23], v[16:17], s[96:97] op_sel_hi:[1,0]
	v_exp_f32_e32 v20, v20
	v_exp_f32_e32 v21, v21
	v_exp_f32_e32 v22, v22
	v_exp_f32_e32 v23, v23
	v_pk_add_f32 v[20:21], v[20:21], 1.0 op_sel_hi:[1,0]
	v_pk_add_f32 v[22:23], v[22:23], 1.0 op_sel_hi:[1,0]
	v_rcp_f32_e32 v20, v20
	v_rcp_f32_e32 v21, v21
	v_rcp_f32_e32 v22, v22
	v_rcp_f32_e32 v23, v23
	s_addc_u32 s9, s77, s9
	v_pk_mul_f32 v[14:15], v[14:15], v[20:21]
	global_store_dwordx2 v105, v[18:19], s[8:9] offset:512 sc1
	v_pk_mul_f32 v[16:17], v[16:17], v[22:23]
	v_cvt_pk_bf16_f32 v14, v14, v15
	v_cvt_pk_bf16_f32 v15, v16, v17
	v_fma_f32 v16, s6, v235, v225
	v_rsq_f32_e32 v16, v16
	s_add_i32 s8, s28, 40
	s_ashr_i32 s9, s8, 31
	s_lshl_b64 s[6:7], s[8:9], 11
	v_pk_mul_f32 v[10:11], v[10:11], v[16:17] op_sel_hi:[1,0]
	v_pk_mul_f32 v[12:13], v[12:13], v[16:17] op_sel_hi:[1,0]
	v_pk_fma_f32 v[10:11], v[2:3], v[10:11], v[6:7]
	v_pk_fma_f32 v[12:13], v[4:5], v[12:13], v[8:9]
	v_pk_mul_f32 v[16:17], v[10:11], s[96:97] op_sel_hi:[1,0]
	v_pk_mul_f32 v[18:19], v[12:13], s[96:97] op_sel_hi:[1,0]
	v_exp_f32_e32 v16, v16
	v_exp_f32_e32 v17, v17
	v_exp_f32_e32 v18, v18
	v_exp_f32_e32 v19, v19
	s_add_u32 s6, s76, s6
	v_pk_add_f32 v[16:17], v[16:17], 1.0 op_sel_hi:[1,0]
	v_pk_add_f32 v[18:19], v[18:19], 1.0 op_sel_hi:[1,0]
	s_addc_u32 s7, s77, s7
	v_rcp_f32_e32 v16, v16
	v_rcp_f32_e32 v17, v17
	v_rcp_f32_e32 v18, v18
	v_rcp_f32_e32 v19, v19
	global_store_dwordx2 v105, v[14:15], s[6:7] offset:512 sc1
	s_add_i32 s6, s28, 48
	s_ashr_i32 s7, s6, 31
	s_lshl_b64 s[6:7], s[6:7], 11
	v_pk_mul_f32 v[10:11], v[10:11], v[16:17]
	v_pk_mul_f32 v[12:13], v[12:13], v[18:19]
	s_add_u32 s6, s76, s6
	v_cvt_pk_bf16_f32 v10, v10, v11
	v_cvt_pk_bf16_f32 v11, v12, v13
	s_addc_u32 s7, s77, s7
	s_add_i32 s54, s54, s60
	global_store_dwordx2 v105, v[10:11], s[6:7] offset:512 sc1
	s_add_i32 s6, s50, s54
	s_add_i32 s52, s52, s53
	s_cmpk_gt_i32 s6, 0x1ff
	s_barrier
	s_cbranch_scc1 .LBB0_282

.LBB0_283:
	s_andn2_b64 vcc, exec, s[28:29]
	s_cbranch_vccnz .LBB0_345
	v_readlane_b32 s6, v250, 24
	v_readlane_b32 s7, v250, 25
	s_mov_b64 s[28:29], -1
	s_and_b64 vcc, exec, s[6:7]
	s_cbranch_vccz .LBB0_317
	s_waitcnt vmcnt(0)
	v_mov_b32_e32 v1, v242
	v_readlane_b32 s65, v250, 26
	v_readfirstlane_b32 s5, v1
	s_ashr_i32 s34, s5, 6
	s_lshl_b32 s6, s34, 4
	s_add_i32 s6, s6, s65
	s_mul_i32 s8, s6, 0x1800
	s_mul_hi_i32 s7, s6, 0x1800
	s_add_u32 s28, s80, s8
	s_addc_u32 s29, s81, s7
	s_or_b32 s7, s6, 1
	s_mul_hi_i32 s8, s7, 0x1800
	s_mulk_i32 s7, 0x1800
	s_add_u32 s40, s80, s7
	v_and_b32_e32 v66, 63, v1
	s_addc_u32 s41, s81, s8
	v_lshlrev_b32_e32 v38, 1, v66
	global_load_ushort v3, v38, s[40:41] offset:512
	global_load_ushort v14, v38, s[40:41] offset:640
	global_load_ushort v20, v38, s[40:41] offset:768
	global_load_ushort v24, v38, s[40:41] offset:896
	global_load_ushort v2, v38, s[28:29] offset:512
	global_load_ushort v15, v38, s[28:29] offset:640
	global_load_ushort v21, v38, s[28:29] offset:768
	global_load_ushort v25, v38, s[28:29] offset:896
	s_or_b32 s7, s6, 2
	s_mul_hi_i32 s9, s7, 0x1800
	s_mulk_i32 s7, 0x1800
	s_add_u32 s8, s80, s7
	s_addc_u32 s9, s81, s9
	s_or_b32 s7, s6, 3
	s_mul_hi_i32 s11, s7, 0x1800
	s_mulk_i32 s7, 0x1800
	s_add_u32 s10, s80, s7
	s_addc_u32 s11, s81, s11
	global_load_ushort v12, v38, s[10:11] offset:512
	global_load_ushort v13, v38, s[10:11] offset:640
	global_load_ushort v16, v38, s[10:11] offset:768
	global_load_ushort v26, v38, s[10:11] offset:896
	global_load_ushort v17, v38, s[8:9] offset:512
	global_load_ushort v22, v38, s[8:9] offset:640
	global_load_ushort v23, v38, s[8:9] offset:768
	global_load_ushort v27, v38, s[8:9] offset:896
	s_mov_b32 s8, 0xbf3a00e3
	v_mov_b64_e32 v[18:19], s[8:9]
	s_mov_b32 s10, 0x3f07dc22
	s_mov_b32 s14, 0x3f35f0e3
	s_mov_b32 s16, 0xbe11a98e
	s_mov_b32 s18, 0x3e027906
	s_or_b32 s7, s6, 4
	s_mul_hi_i32 s8, s7, 0x1800
	s_mulk_i32 s7, 0x1800
	s_add_u32 s28, s80, s7
	s_addc_u32 s29, s81, s8
	s_or_b32 s7, s6, 5
	s_mul_hi_i32 s8, s7, 0x1800
	s_mulk_i32 s7, 0x1800
	s_add_u32 s40, s80, s7
	s_addc_u32 s41, s81, s8
	s_or_b32 s7, s6, 6
	v_writelane_b32 v255, s58, 23
	s_mul_hi_i32 s8, s7, 0x1800
	s_mulk_i32 s7, 0x1800
	v_writelane_b32 v255, s59, 24
	s_add_u32 s58, s80, s7
	s_addc_u32 s59, s81, s8
	s_or_b32 s7, s6, 7
	s_mul_hi_i32 s8, s7, 0x1800
	s_mulk_i32 s7, 0x1800
	s_add_u32 s60, s80, s7
	s_addc_u32 s61, s81, s8
	s_or_b32 s7, s6, 8
	s_mul_hi_i32 s8, s7, 0x1800
	s_mulk_i32 s7, 0x1800
	s_add_u32 s46, s80, s7
	s_addc_u32 s47, s81, s8
	s_or_b32 s7, s6, 9
	s_mul_hi_i32 s8, s7, 0x1800
	s_mulk_i32 s7, 0x1800
	s_add_u32 s54, s80, s7
	s_addc_u32 s55, s81, s8
	s_or_b32 s7, s6, 10
	s_mul_hi_i32 s8, s7, 0x1800
	s_mulk_i32 s7, 0x1800
	s_add_u32 s48, s80, s7
	s_addc_u32 s49, s81, s8
	s_or_b32 s7, s6, 11
	s_mul_hi_i32 s8, s7, 0x1800
	s_mulk_i32 s7, 0x1800
	s_add_u32 s56, s80, s7
	s_addc_u32 s57, s81, s8
	s_or_b32 s7, s6, 12
	s_mul_hi_i32 s8, s7, 0x1800
	s_mulk_i32 s7, 0x1800
	s_add_u32 s42, s80, s7
	s_addc_u32 s43, s81, s8
	s_or_b32 s7, s6, 13
	s_mul_hi_i32 s8, s7, 0x1800
	s_mulk_i32 s7, 0x1800
	s_add_u32 s50, s80, s7
	s_addc_u32 s51, s81, s8
	s_or_b32 s7, s6, 14
	s_mul_hi_i32 s8, s7, 0x1800
	s_mulk_i32 s7, 0x1800
	s_waitcnt vmcnt(15)
	v_lshlrev_b32_e32 v3, 16, v3
	v_mul_f32_e32 v7, v3, v3
	v_mul_f32_e32 v7, 0xbf38aa3b, v7
	v_exp_f32_e32 v7, v7
	s_waitcnt vmcnt(11)
	v_lshlrev_b32_e32 v2, 16, v2
	s_waitcnt lgkmcnt(0)
	v_mul_f32_e32 v5, v2, v2
	v_mul_f32_e32 v5, 0xbf38aa3b, v5
	v_fma_f32 v4, |v2|, s92, 1.0
	v_exp_f32_e32 v6, v5
	v_fma_f32 v5, |v3|, s92, 1.0
	v_rcp_f32_e32 v4, v4
	v_rcp_f32_e32 v5, v5
	v_cmp_gt_f32_e32 vcc, 0, v3
	s_add_u32 s44, s80, s7
	s_addc_u32 s45, s81, s8
	v_pk_fma_f32 v[8:9], v[4:5], s[10:11], v[18:19] op_sel_hi:[1,0,0]
	s_or_b32 s6, s6, 15
	v_pk_fma_f32 v[8:9], v[4:5], v[8:9], s[14:15] op_sel_hi:[1,1,0]
	s_mul_hi_i32 s7, s6, 0x1800
	v_pk_fma_f32 v[8:9], v[4:5], v[8:9], s[16:17] op_sel_hi:[1,1,0]
	s_mulk_i32 s6, 0x1800
	v_pk_fma_f32 v[8:9], v[4:5], v[8:9], s[18:19] op_sel_hi:[1,1,0]
	s_add_u32 s52, s80, s6
	v_pk_mul_f32 v[4:5], v[4:5], v[8:9]
	s_addc_u32 s53, s81, s7
	v_pk_mul_f32 v[4:5], v[6:7], v[4:5]
	s_mov_b32 s8, 0x3b800000
	v_pk_mul_f32 v[6:7], v[4:5], v[2:3]
	v_pk_fma_f32 v[4:5], v[4:5], v[2:3], v[2:3] neg_lo:[1,0,0] neg_hi:[1,0,0]
	s_ashr_i32 s5, s5, 7
	v_cndmask_b32_e32 v11, v5, v7, vcc
	v_cmp_gt_f32_e32 vcc, 0, v2
	s_waitcnt vmcnt(3)
	v_lshlrev_b32_e32 v2, 16, v17
	v_fma_f32 v3, |v2|, s92, 1.0
	v_mul_f32_e32 v5, v2, v2
	v_cndmask_b32_e32 v10, v4, v6, vcc
	v_rcp_f32_e32 v4, v3
	v_mul_f32_e32 v5, 0xbf38aa3b, v5
	v_lshlrev_b32_e32 v3, 16, v12
	v_exp_f32_e32 v6, v5
	v_fma_f32 v5, |v3|, s92, 1.0
	v_rcp_f32_e32 v5, v5
	v_mul_f32_e32 v7, v3, v3
	v_mul_f32_e32 v7, 0xbf38aa3b, v7
	v_exp_f32_e32 v7, v7
	v_pk_fma_f32 v[8:9], v[4:5], s[10:11], v[18:19] op_sel_hi:[1,0,0]
	v_cmp_gt_f32_e32 vcc, 0, v3
	v_pk_fma_f32 v[8:9], v[4:5], v[8:9], s[14:15] op_sel_hi:[1,1,0]
	v_lshlrev_b32_e32 v130, 4, v66
	v_pk_fma_f32 v[8:9], v[4:5], v[8:9], s[16:17] op_sel_hi:[1,1,0]
	s_nop 0
	v_pk_fma_f32 v[8:9], v[4:5], v[8:9], s[18:19] op_sel_hi:[1,1,0]
	v_pk_mul_f32 v[4:5], v[4:5], v[8:9]
	v_pk_mul_f32 v[4:5], v[6:7], v[4:5]
	v_pk_mul_f32 v[6:7], v[4:5], v[2:3]
	v_pk_fma_f32 v[4:5], v[4:5], v[2:3], v[2:3] neg_lo:[1,0,0] neg_hi:[1,0,0]
	s_nop 0
	v_cndmask_b32_e32 v3, v5, v7, vcc
	v_cmp_gt_f32_e32 vcc, 0, v2
	s_nop 1
	v_cndmask_b32_e32 v2, v4, v6, vcc
	s_waitcnt vmcnt(2)
	v_lshlrev_b32_e32 v4, 16, v22
	v_fma_f32 v5, |v4|, s92, 1.0
	v_mul_f32_e32 v7, v4, v4
	v_rcp_f32_e32 v6, v5
	v_mul_f32_e32 v7, 0xbf38aa3b, v7
	v_lshlrev_b32_e32 v5, 16, v13
	v_exp_f32_e32 v8, v7
	v_fma_f32 v7, |v5|, s92, 1.0
	v_rcp_f32_e32 v7, v7
	v_mul_f32_e32 v9, v5, v5
	v_mul_f32_e32 v9, 0xbf38aa3b, v9
	v_exp_f32_e32 v9, v9
	v_pk_fma_f32 v[12:13], v[6:7], s[10:11], v[18:19] op_sel_hi:[1,0,0]
	v_cmp_gt_f32_e32 vcc, 0, v5
	v_pk_fma_f32 v[12:13], v[6:7], v[12:13], s[14:15] op_sel_hi:[1,1,0]
	s_nop 0
	v_pk_fma_f32 v[12:13], v[6:7], v[12:13], s[16:17] op_sel_hi:[1,1,0]
	s_nop 0
	v_pk_fma_f32 v[12:13], v[6:7], v[12:13], s[18:19] op_sel_hi:[1,1,0]
	v_pk_mul_f32 v[6:7], v[6:7], v[12:13]
	v_pk_mul_f32 v[6:7], v[8:9], v[6:7]
	v_pk_mul_f32 v[8:9], v[6:7], v[4:5]
	v_pk_fma_f32 v[6:7], v[6:7], v[4:5], v[4:5] neg_lo:[1,0,0] neg_hi:[1,0,0]
	v_lshlrev_b32_e32 v5, 16, v14
	v_cndmask_b32_e32 v7, v7, v9, vcc
	v_cmp_gt_f32_e32 vcc, 0, v4
	v_lshlrev_b32_e32 v4, 16, v15
	v_mul_f32_e32 v9, v4, v4
	v_mul_f32_e32 v9, 0xbf38aa3b, v9
	v_cndmask_b32_e32 v6, v6, v8, vcc
	v_fma_f32 v8, |v4|, s92, 1.0
	v_exp_f32_e32 v12, v9
	v_fma_f32 v9, |v5|, s92, 1.0
	v_rcp_f32_e32 v8, v8
	v_rcp_f32_e32 v9, v9
	v_mul_f32_e32 v13, v5, v5
	v_mul_f32_e32 v13, 0xbf38aa3b, v13
	v_exp_f32_e32 v13, v13
	v_pk_fma_f32 v[14:15], v[8:9], s[10:11], v[18:19] op_sel_hi:[1,0,0]
	v_cmp_gt_f32_e32 vcc, 0, v5
	v_pk_fma_f32 v[14:15], v[8:9], v[14:15], s[14:15] op_sel_hi:[1,1,0]
	s_nop 0
	v_pk_fma_f32 v[14:15], v[8:9], v[14:15], s[16:17] op_sel_hi:[1,1,0]
	s_nop 0
	v_pk_fma_f32 v[14:15], v[8:9], v[14:15], s[18:19] op_sel_hi:[1,1,0]
	v_pk_mul_f32 v[8:9], v[8:9], v[14:15]
	v_pk_mul_f32 v[8:9], v[12:13], v[8:9]
	v_pk_mul_f32 v[12:13], v[8:9], v[4:5]
	v_pk_fma_f32 v[8:9], v[8:9], v[4:5], v[4:5] neg_lo:[1,0,0] neg_hi:[1,0,0]
	v_lshlrev_b32_e32 v5, 16, v16
	v_cndmask_b32_e32 v13, v9, v13, vcc
	v_cmp_gt_f32_e32 vcc, 0, v4
	s_waitcnt vmcnt(1)
	v_lshlrev_b32_e32 v4, 16, v23
	v_fma_f32 v9, |v5|, s92, 1.0
	v_cndmask_b32_e32 v12, v8, v12, vcc
	v_fma_f32 v8, |v4|, s92, 1.0
	v_rcp_f32_e32 v8, v8
	v_rcp_f32_e32 v9, v9
	v_mul_f32_e32 v14, v4, v4
	v_mul_f32_e32 v15, v5, v5
	v_mul_f32_e32 v14, 0xbf38aa3b, v14
	v_pk_fma_f32 v[16:17], v[8:9], s[10:11], v[18:19] op_sel_hi:[1,0,0]
	v_mul_f32_e32 v15, 0xbf38aa3b, v15
	v_exp_f32_e32 v14, v14
	v_pk_fma_f32 v[16:17], v[8:9], v[16:17], s[14:15] op_sel_hi:[1,1,0]
	v_exp_f32_e32 v15, v15
	v_pk_fma_f32 v[16:17], v[8:9], v[16:17], s[16:17] op_sel_hi:[1,1,0]
	v_cmp_gt_f32_e32 vcc, 0, v5
	v_pk_fma_f32 v[16:17], v[8:9], v[16:17], s[18:19] op_sel_hi:[1,1,0]
	s_nop 0
	v_pk_mul_f32 v[8:9], v[8:9], v[16:17]
	v_pk_mul_f32 v[8:9], v[14:15], v[8:9]
	v_pk_mul_f32 v[14:15], v[8:9], v[4:5]
	v_pk_fma_f32 v[8:9], v[8:9], v[4:5], v[4:5] neg_lo:[1,0,0] neg_hi:[1,0,0]
	v_lshlrev_b32_e32 v5, 16, v20
	v_cndmask_b32_e32 v15, v9, v15, vcc
	v_cmp_gt_f32_e32 vcc, 0, v4
	v_lshlrev_b32_e32 v4, 16, v21
	v_mul_f32_e32 v9, v4, v4
	v_mul_f32_e32 v9, 0xbf38aa3b, v9
	v_cndmask_b32_e32 v14, v8, v14, vcc
	v_fma_f32 v8, |v4|, s92, 1.0
	v_exp_f32_e32 v16, v9
	v_fma_f32 v9, |v5|, s92, 1.0
	v_rcp_f32_e32 v8, v8
	v_rcp_f32_e32 v9, v9
	v_mul_f32_e32 v17, v5, v5
	v_mul_f32_e32 v17, 0xbf38aa3b, v17
	v_exp_f32_e32 v17, v17
	v_pk_fma_f32 v[20:21], v[8:9], s[10:11], v[18:19] op_sel_hi:[1,0,0]
	v_cmp_gt_f32_e32 vcc, 0, v5
	v_pk_fma_f32 v[20:21], v[8:9], v[20:21], s[14:15] op_sel_hi:[1,1,0]
	s_nop 0
	v_pk_fma_f32 v[20:21], v[8:9], v[20:21], s[16:17] op_sel_hi:[1,1,0]
	s_nop 0
	v_pk_fma_f32 v[20:21], v[8:9], v[20:21], s[18:19] op_sel_hi:[1,1,0]
	v_pk_mul_f32 v[8:9], v[8:9], v[20:21]
	v_pk_mul_f32 v[8:9], v[16:17], v[8:9]
	v_pk_mul_f32 v[16:17], v[8:9], v[4:5]
	v_pk_fma_f32 v[8:9], v[8:9], v[4:5], v[4:5] neg_lo:[1,0,0] neg_hi:[1,0,0]
	v_lshlrev_b32_e32 v5, 16, v26
	v_cndmask_b32_e32 v23, v9, v17, vcc
	v_cmp_gt_f32_e32 vcc, 0, v4
	s_waitcnt vmcnt(0)
	v_lshlrev_b32_e32 v4, 16, v27
	v_fma_f32 v9, |v5|, s92, 1.0
	v_cndmask_b32_e32 v22, v8, v16, vcc
	v_fma_f32 v8, |v4|, s92, 1.0
	v_rcp_f32_e32 v8, v8
	v_rcp_f32_e32 v9, v9
	v_mul_f32_e32 v16, v4, v4
	v_mul_f32_e32 v17, v5, v5
	v_mul_f32_e32 v16, 0xbf38aa3b, v16
	v_pk_fma_f32 v[20:21], v[8:9], s[10:11], v[18:19] op_sel_hi:[1,0,0]
	v_mul_f32_e32 v17, 0xbf38aa3b, v17
	v_exp_f32_e32 v16, v16
	v_pk_fma_f32 v[20:21], v[8:9], v[20:21], s[14:15] op_sel_hi:[1,1,0]
	v_exp_f32_e32 v17, v17
	v_pk_fma_f32 v[20:21], v[8:9], v[20:21], s[16:17] op_sel_hi:[1,1,0]
	v_cmp_gt_f32_e32 vcc, 0, v5
	v_pk_fma_f32 v[20:21], v[8:9], v[20:21], s[18:19] op_sel_hi:[1,1,0]
	v_mov_b32_e32 v26, v13
	v_pk_mul_f32 v[8:9], v[8:9], v[20:21]
	v_pk_mul_f32 v[8:9], v[16:17], v[8:9]
	v_pk_mul_f32 v[16:17], v[8:9], v[4:5]
	v_pk_fma_f32 v[8:9], v[8:9], v[4:5], v[4:5] neg_lo:[1,0,0] neg_hi:[1,0,0]
	v_lshlrev_b32_e32 v5, 16, v24
	v_cndmask_b32_e32 v17, v9, v17, vcc
	v_cmp_gt_f32_e32 vcc, 0, v4
	v_lshlrev_b32_e32 v4, 16, v25
	v_mul_f32_e32 v9, v4, v4
	v_mul_f32_e32 v9, 0xbf38aa3b, v9
	v_cndmask_b32_e32 v16, v8, v16, vcc
	v_fma_f32 v8, |v4|, s92, 1.0
	v_exp_f32_e32 v20, v9
	v_fma_f32 v9, |v5|, s92, 1.0
	v_rcp_f32_e32 v8, v8
	v_rcp_f32_e32 v9, v9
	v_mul_f32_e32 v21, v5, v5
	v_mul_f32_e32 v21, 0xbf38aa3b, v21
	v_exp_f32_e32 v21, v21
	v_pk_fma_f32 v[24:25], v[8:9], s[10:11], v[18:19] op_sel_hi:[1,0,0]
	v_cmp_gt_f32_e32 vcc, 0, v5
	v_pk_fma_f32 v[24:25], v[8:9], v[24:25], s[14:15] op_sel_hi:[1,1,0]
	s_nop 0
	v_pk_fma_f32 v[24:25], v[8:9], v[24:25], s[16:17] op_sel_hi:[1,1,0]
	s_nop 0
	v_pk_fma_f32 v[24:25], v[8:9], v[24:25], s[18:19] op_sel_hi:[1,1,0]
	v_pk_mul_f32 v[8:9], v[8:9], v[24:25]
	v_pk_mul_f32 v[8:9], v[20:21], v[8:9]
	v_pk_mul_f32 v[20:21], v[8:9], v[4:5]
	v_pk_fma_f32 v[8:9], v[8:9], v[4:5], v[4:5] neg_lo:[1,0,0] neg_hi:[1,0,0]
	v_mov_b32_e32 v5, v14
	v_cndmask_b32_e32 v25, v9, v21, vcc
	v_cmp_gt_f32_e32 vcc, 0, v4
	v_mov_b32_e32 v4, v2
	v_mov_b32_e32 v9, v16
	v_cndmask_b32_e32 v24, v8, v20, vcc
	v_mov_b32_e32 v8, v6
	v_pk_add_f32 v[4:5], v[4:5], v[8:9]
	v_mov_b32_e32 v8, v3
	v_add_f32_e32 v4, v4, v5
	v_mov_b32_e32 v9, v15
	s_nop 0
	v_add_f32_dpp v4, v4, v4 quad_perm:[1,0,3,2] row_mask:0xf bank_mask:0xf bound_ctrl:1
	v_mov_b32_e32 v20, v7
	v_mov_b32_e32 v21, v17
	v_add_f32_dpp v4, v4, v4 quad_perm:[2,3,0,1] row_mask:0xf bank_mask:0xf bound_ctrl:1
	v_pk_add_f32 v[8:9], v[8:9], v[20:21]
	v_mov_b64_e32 v[20:21], s[8:9]
	v_add_f32_dpp v4, v4, v4 row_half_mirror row_mask:0xf bank_mask:0xf bound_ctrl:1
	v_mov_b32_e32 v27, v25
	s_mov_b32 s8, 0x3e027906
	v_add_f32_dpp v4, v4, v4 row_mirror row_mask:0xf bank_mask:0xf bound_ctrl:1
	s_nop 1
	v_add_f32_dpp v4, v4, v4 row_bcast:15 row_mask:0xa bank_mask:0xf
	s_nop 1
	v_add_f32_dpp v4, v4, v4 row_bcast:31 row_mask:0xc bank_mask:0xf
	v_add_f32_e32 v5, v8, v9
	v_readlane_b32 s6, v4, 63
	s_nop 0
	v_add_f32_dpp v5, v5, v5 quad_perm:[1,0,3,2] row_mask:0xf bank_mask:0xf bound_ctrl:1
	s_xor_b32 s6, s6, 0x80000000
	s_nop 0
	v_add_f32_dpp v5, v5, v5 quad_perm:[2,3,0,1] row_mask:0xf bank_mask:0xf bound_ctrl:1
	s_nop 1
	v_add_f32_dpp v5, v5, v5 row_half_mirror row_mask:0xf bank_mask:0xf bound_ctrl:1
	s_nop 1
	v_add_f32_dpp v5, v5, v5 row_mirror row_mask:0xf bank_mask:0xf bound_ctrl:1
	s_nop 1
	v_add_f32_dpp v5, v5, v5 row_bcast:15 row_mask:0xa bank_mask:0xf
	s_nop 1
	v_add_f32_dpp v5, v5, v5 row_bcast:31 row_mask:0xc bank_mask:0xf
	s_nop 0
	v_readlane_b32 s7, v5, 63
	s_xor_b32 s7, s7, 0x80000000
	s_nop 0
	v_pk_fma_f32 v[4:5], s[6:7], v[20:21], v[2:3] op_sel_hi:[1,0,1]
	v_pk_fma_f32 v[8:9], s[6:7], v[20:21], v[6:7] op_sel_hi:[1,0,1]
	v_pk_fma_f32 v[6:7], s[6:7], v[20:21], v[14:15] op_sel_hi:[1,0,1]
	v_pk_fma_f32 v[2:3], s[6:7], v[20:21], v[16:17] op_sel_hi:[1,0,1]
	v_mov_b32_e32 v14, v10
	v_mov_b32_e32 v15, v22
	v_mov_b32_e32 v16, v12
	v_mov_b32_e32 v17, v24
	v_pk_add_f32 v[14:15], v[14:15], v[16:17]
	v_mov_b32_e32 v16, v11
	v_add_f32_e32 v14, v14, v15
	v_mov_b32_e32 v17, v23
	s_nop 0
	v_add_f32_dpp v14, v14, v14 quad_perm:[1,0,3,2] row_mask:0xf bank_mask:0xf bound_ctrl:1
	v_pk_add_f32 v[16:17], v[16:17], v[26:27]
	s_nop 0
	v_add_f32_dpp v14, v14, v14 quad_perm:[2,3,0,1] row_mask:0xf bank_mask:0xf bound_ctrl:1
	s_nop 1
	v_add_f32_dpp v14, v14, v14 row_half_mirror row_mask:0xf bank_mask:0xf bound_ctrl:1
	s_nop 1
	v_add_f32_dpp v14, v14, v14 row_mirror row_mask:0xf bank_mask:0xf bound_ctrl:1
	s_nop 1
	v_add_f32_dpp v14, v14, v14 row_bcast:15 row_mask:0xa bank_mask:0xf
	s_nop 1
	v_add_f32_dpp v14, v14, v14 row_bcast:31 row_mask:0xc bank_mask:0xf
	v_add_f32_e32 v15, v16, v17
	v_readlane_b32 s6, v14, 63
	s_nop 0
	v_add_f32_dpp v15, v15, v15 quad_perm:[1,0,3,2] row_mask:0xf bank_mask:0xf bound_ctrl:1
	s_xor_b32 s6, s6, 0x80000000
	s_nop 0
	v_add_f32_dpp v15, v15, v15 quad_perm:[2,3,0,1] row_mask:0xf bank_mask:0xf bound_ctrl:1
	s_nop 1
	v_add_f32_dpp v15, v15, v15 row_half_mirror row_mask:0xf bank_mask:0xf bound_ctrl:1
	s_nop 1
	v_add_f32_dpp v15, v15, v15 row_mirror row_mask:0xf bank_mask:0xf bound_ctrl:1
	s_nop 1
	v_add_f32_dpp v15, v15, v15 row_bcast:15 row_mask:0xa bank_mask:0xf
	s_nop 1
	v_add_f32_dpp v15, v15, v15 row_bcast:31 row_mask:0xc bank_mask:0xf
	s_nop 0
	v_readlane_b32 s7, v15, 63
	s_xor_b32 s7, s7, 0x80000000
	s_nop 0
	v_pk_fma_f32 v[16:17], s[6:7], v[20:21], v[10:11] op_sel_hi:[1,0,1]
	v_pk_fma_f32 v[14:15], s[6:7], v[20:21], v[12:13] op_sel_hi:[1,0,1]
	v_pk_fma_f32 v[12:13], s[6:7], v[20:21], v[22:23] op_sel_hi:[1,0,1]
	v_pk_fma_f32 v[10:11], s[6:7], v[20:21], v[24:25] op_sel_hi:[1,0,1]
	global_load_ushort v22, v38, s[60:61] offset:512
	global_load_ushort v32, v38, s[60:61] offset:640
	global_load_ushort v36, v38, s[60:61] offset:768
	global_load_ushort v39, v38, s[60:61] offset:896
	global_load_ushort v24, v38, s[58:59] offset:512
	global_load_ushort v33, v38, s[58:59] offset:640
	global_load_ushort v37, v38, s[58:59] offset:768
	global_load_ushort v42, v38, s[58:59] offset:896
	s_waitcnt vmcnt(7)
	v_lshlrev_b32_e32 v23, 16, v22
	v_fma_f32 v25, |v23|, s92, 1.0
	v_rcp_f32_e32 v25, v25
	v_mul_f32_e32 v27, v23, v23
	s_waitcnt vmcnt(3)
	v_lshlrev_b32_e32 v22, 16, v24
	v_fma_f32 v24, |v22|, s92, 1.0
	v_rcp_f32_e32 v24, v24
	v_mul_f32_e32 v26, v22, v22
	v_mul_f32_e32 v26, 0xbf38aa3b, v26
	v_mul_f32_e32 v27, 0xbf38aa3b, v27
	v_pk_fma_f32 v[28:29], v[24:25], s[10:11], v[18:19] op_sel_hi:[1,0,0]
	v_exp_f32_e32 v26, v26
	v_pk_fma_f32 v[28:29], v[24:25], v[28:29], s[14:15] op_sel_hi:[1,1,0]
	v_exp_f32_e32 v27, v27
	v_pk_fma_f32 v[28:29], v[24:25], v[28:29], s[16:17] op_sel_hi:[1,1,0]
	v_cmp_gt_f32_e32 vcc, 0, v23
	v_pk_fma_f32 v[28:29], v[24:25], v[28:29], s[18:19] op_sel_hi:[1,1,0]
	v_readlane_b32 s11, v254, 26
	v_pk_mul_f32 v[24:25], v[24:25], v[28:29]
	s_nop 0
	v_pk_mul_f32 v[24:25], v[26:27], v[24:25]
	v_pk_mul_f32 v[26:27], v[24:25], v[22:23]
	v_pk_fma_f32 v[24:25], v[24:25], v[22:23], v[22:23] neg_lo:[1,0,0] neg_hi:[1,0,0]
	s_nop 0
	v_cndmask_b32_e32 v23, v25, v27, vcc
	v_cmp_gt_f32_e32 vcc, 0, v22
	s_nop 1
	v_cndmask_b32_e32 v22, v24, v26, vcc
	global_load_ushort v24, v38, s[40:41] offset:512
	global_load_ushort v34, v38, s[40:41] offset:640
	global_load_ushort v40, v38, s[40:41] offset:768
	global_load_ushort v44, v38, s[40:41] offset:896
	global_load_ushort v26, v38, s[28:29] offset:512
	global_load_ushort v35, v38, s[28:29] offset:640
	global_load_ushort v41, v38, s[28:29] offset:768
	global_load_ushort v45, v38, s[28:29] offset:896
	s_waitcnt vmcnt(7)
	v_lshlrev_b32_e32 v25, 16, v24
	s_waitcnt vmcnt(3)
	v_lshlrev_b32_e32 v24, 16, v26
	v_mul_f32_e32 v27, v24, v24
	v_mul_f32_e32 v27, 0xbf38aa3b, v27
	v_fma_f32 v26, |v24|, s92, 1.0
	v_exp_f32_e32 v28, v27
	v_fma_f32 v27, |v25|, s92, 1.0
	v_rcp_f32_e32 v26, v26
	v_rcp_f32_e32 v27, v27
	v_mul_f32_e32 v29, v25, v25
	v_mul_f32_e32 v29, 0xbf38aa3b, v29
	v_exp_f32_e32 v29, v29
	v_pk_fma_f32 v[30:31], v[26:27], s[10:11], v[18:19] op_sel_hi:[1,0,0]
	v_cmp_gt_f32_e32 vcc, 0, v25
	v_pk_fma_f32 v[30:31], v[26:27], v[30:31], s[14:15] op_sel_hi:[1,1,0]
	s_nop 0
	v_pk_fma_f32 v[30:31], v[26:27], v[30:31], s[16:17] op_sel_hi:[1,1,0]
	s_nop 0
	v_pk_fma_f32 v[30:31], v[26:27], v[30:31], s[18:19] op_sel_hi:[1,1,0]
	v_pk_mul_f32 v[26:27], v[26:27], v[30:31]
	v_pk_mul_f32 v[26:27], v[28:29], v[26:27]
	v_pk_mul_f32 v[28:29], v[26:27], v[24:25]
	v_pk_fma_f32 v[26:27], v[26:27], v[24:25], v[24:25] neg_lo:[1,0,0] neg_hi:[1,0,0]
	v_lshlrev_b32_e32 v25, 16, v32
	v_cndmask_b32_e32 v31, v27, v29, vcc
	v_cmp_gt_f32_e32 vcc, 0, v24
	v_lshlrev_b32_e32 v24, 16, v33
	v_fma_f32 v27, |v25|, s92, 1.0
	v_cndmask_b32_e32 v30, v26, v28, vcc
	v_fma_f32 v26, |v24|, s92, 1.0
	v_rcp_f32_e32 v26, v26
	v_rcp_f32_e32 v27, v27
	v_mul_f32_e32 v28, v24, v24
	v_mul_f32_e32 v29, v25, v25
	v_mul_f32_e32 v28, 0xbf38aa3b, v28
	v_pk_fma_f32 v[32:33], v[26:27], s[10:11], v[18:19] op_sel_hi:[1,0,0]
	v_mul_f32_e32 v29, 0xbf38aa3b, v29
	v_exp_f32_e32 v28, v28
	v_pk_fma_f32 v[32:33], v[26:27], v[32:33], s[14:15] op_sel_hi:[1,1,0]
	v_exp_f32_e32 v29, v29
	v_pk_fma_f32 v[32:33], v[26:27], v[32:33], s[16:17] op_sel_hi:[1,1,0]
	v_cmp_gt_f32_e32 vcc, 0, v25
	v_pk_fma_f32 v[32:33], v[26:27], v[32:33], s[18:19] op_sel_hi:[1,1,0]
	s_nop 0
	v_pk_mul_f32 v[26:27], v[26:27], v[32:33]
	v_pk_mul_f32 v[26:27], v[28:29], v[26:27]
	v_pk_mul_f32 v[28:29], v[26:27], v[24:25]
	v_pk_fma_f32 v[26:27], v[26:27], v[24:25], v[24:25] neg_lo:[1,0,0] neg_hi:[1,0,0]
	s_nop 0
	v_cndmask_b32_e32 v25, v27, v29, vcc
	v_cmp_gt_f32_e32 vcc, 0, v24
	v_lshlrev_b32_e32 v27, 16, v34
	v_mul_f32_e32 v33, v27, v27
	v_cndmask_b32_e32 v24, v26, v28, vcc
	s_waitcnt vmcnt(2)
	v_lshlrev_b32_e32 v26, 16, v35
	v_mul_f32_e32 v29, v26, v26
	v_mul_f32_e32 v29, 0xbf38aa3b, v29
	v_fma_f32 v28, |v26|, s92, 1.0
	v_exp_f32_e32 v32, v29
	v_fma_f32 v29, |v27|, s92, 1.0
	v_rcp_f32_e32 v28, v28
	v_rcp_f32_e32 v29, v29
	v_mul_f32_e32 v33, 0xbf38aa3b, v33
	v_exp_f32_e32 v33, v33
	v_cmp_gt_f32_e32 vcc, 0, v27
	v_pk_fma_f32 v[34:35], v[28:29], s[10:11], v[18:19] op_sel_hi:[1,0,0]
	s_nop 0
	v_pk_fma_f32 v[34:35], v[28:29], v[34:35], s[14:15] op_sel_hi:[1,1,0]
	s_nop 0
	v_pk_fma_f32 v[34:35], v[28:29], v[34:35], s[16:17] op_sel_hi:[1,1,0]
	s_nop 0
	v_pk_fma_f32 v[34:35], v[28:29], v[34:35], s[18:19] op_sel_hi:[1,1,0]
	v_pk_mul_f32 v[28:29], v[28:29], v[34:35]
	v_pk_mul_f32 v[28:29], v[32:33], v[28:29]
	v_pk_mul_f32 v[32:33], v[28:29], v[26:27]
	v_pk_fma_f32 v[28:29], v[28:29], v[26:27], v[26:27] neg_lo:[1,0,0] neg_hi:[1,0,0]
	v_lshlrev_b32_e32 v27, 16, v36
	v_cndmask_b32_e32 v33, v29, v33, vcc
	v_cmp_gt_f32_e32 vcc, 0, v26
	v_lshlrev_b32_e32 v26, 16, v37
	v_fma_f32 v29, |v27|, s92, 1.0
	v_cndmask_b32_e32 v32, v28, v32, vcc
	v_fma_f32 v28, |v26|, s92, 1.0
	v_rcp_f32_e32 v28, v28
	v_rcp_f32_e32 v29, v29
	v_mul_f32_e32 v34, v26, v26
	v_mul_f32_e32 v35, v27, v27
	v_mul_f32_e32 v34, 0xbf38aa3b, v34
	v_pk_fma_f32 v[36:37], v[28:29], s[10:11], v[18:19] op_sel_hi:[1,0,0]
	v_mul_f32_e32 v35, 0xbf38aa3b, v35
	v_exp_f32_e32 v34, v34
	v_pk_fma_f32 v[36:37], v[28:29], v[36:37], s[14:15] op_sel_hi:[1,1,0]
	v_exp_f32_e32 v35, v35
	v_pk_fma_f32 v[36:37], v[28:29], v[36:37], s[16:17] op_sel_hi:[1,1,0]
	v_cmp_gt_f32_e32 vcc, 0, v27
	v_pk_fma_f32 v[36:37], v[28:29], v[36:37], s[18:19] op_sel_hi:[1,1,0]
	s_nop 0
	v_pk_mul_f32 v[28:29], v[28:29], v[36:37]
	v_pk_mul_f32 v[28:29], v[34:35], v[28:29]
	v_pk_mul_f32 v[34:35], v[28:29], v[26:27]
	v_pk_fma_f32 v[28:29], v[28:29], v[26:27], v[26:27] neg_lo:[1,0,0] neg_hi:[1,0,0]
	v_lshlrev_b32_e32 v27, 16, v40
	v_cndmask_b32_e32 v35, v29, v35, vcc
	v_cmp_gt_f32_e32 vcc, 0, v26
	s_waitcnt vmcnt(1)
	v_lshlrev_b32_e32 v26, 16, v41
	v_mul_f32_e32 v29, v26, v26
	v_mul_f32_e32 v29, 0xbf38aa3b, v29
	v_cndmask_b32_e32 v34, v28, v34, vcc
	v_fma_f32 v28, |v26|, s92, 1.0
	v_exp_f32_e32 v36, v29
	v_fma_f32 v29, |v27|, s92, 1.0
	v_rcp_f32_e32 v28, v28
	v_rcp_f32_e32 v29, v29
	v_mul_f32_e32 v37, v27, v27
	v_mul_f32_e32 v37, 0xbf38aa3b, v37
	v_exp_f32_e32 v37, v37
	v_pk_fma_f32 v[40:41], v[28:29], s[10:11], v[18:19] op_sel_hi:[1,0,0]
	v_cmp_gt_f32_e32 vcc, 0, v27
	v_pk_fma_f32 v[40:41], v[28:29], v[40:41], s[14:15] op_sel_hi:[1,1,0]
	s_nop 0
	v_pk_fma_f32 v[40:41], v[28:29], v[40:41], s[16:17] op_sel_hi:[1,1,0]
	s_nop 0
	v_pk_fma_f32 v[40:41], v[28:29], v[40:41], s[18:19] op_sel_hi:[1,1,0]
	v_pk_mul_f32 v[28:29], v[28:29], v[40:41]
	v_pk_mul_f32 v[28:29], v[36:37], v[28:29]
	v_pk_mul_f32 v[36:37], v[28:29], v[26:27]
	v_pk_fma_f32 v[28:29], v[28:29], v[26:27], v[26:27] neg_lo:[1,0,0] neg_hi:[1,0,0]
	v_lshlrev_b32_e32 v27, 16, v39
	v_cndmask_b32_e32 v41, v29, v37, vcc
	v_cmp_gt_f32_e32 vcc, 0, v26
	v_lshlrev_b32_e32 v26, 16, v42
	v_fma_f32 v29, |v27|, s92, 1.0
	v_cndmask_b32_e32 v40, v28, v36, vcc
	v_fma_f32 v28, |v26|, s92, 1.0
	v_rcp_f32_e32 v28, v28
	v_rcp_f32_e32 v29, v29
	v_mul_f32_e32 v36, v26, v26
	v_mul_f32_e32 v37, v27, v27
	v_mul_f32_e32 v36, 0xbf38aa3b, v36
	v_pk_fma_f32 v[42:43], v[28:29], s[10:11], v[18:19] op_sel_hi:[1,0,0]
	v_mul_f32_e32 v37, 0xbf38aa3b, v37
	v_exp_f32_e32 v36, v36
	v_pk_fma_f32 v[42:43], v[28:29], v[42:43], s[14:15] op_sel_hi:[1,1,0]
	v_exp_f32_e32 v37, v37
	v_pk_fma_f32 v[42:43], v[28:29], v[42:43], s[16:17] op_sel_hi:[1,1,0]
	v_cmp_gt_f32_e32 vcc, 0, v27
	v_pk_fma_f32 v[42:43], v[28:29], v[42:43], s[18:19] op_sel_hi:[1,1,0]
	s_nop 0
	v_pk_mul_f32 v[28:29], v[28:29], v[42:43]
	v_pk_mul_f32 v[28:29], v[36:37], v[28:29]
	v_pk_mul_f32 v[36:37], v[28:29], v[26:27]
	v_pk_fma_f32 v[28:29], v[28:29], v[26:27], v[26:27] neg_lo:[1,0,0] neg_hi:[1,0,0]
	v_lshlrev_b32_e32 v27, 16, v44
	v_cndmask_b32_e32 v37, v29, v37, vcc
	v_cmp_gt_f32_e32 vcc, 0, v26
	s_waitcnt vmcnt(0)
	v_lshlrev_b32_e32 v26, 16, v45
	v_mul_f32_e32 v29, v26, v26
	v_mul_f32_e32 v29, 0xbf38aa3b, v29
	v_cndmask_b32_e32 v36, v28, v36, vcc
	v_fma_f32 v28, |v26|, s92, 1.0
	v_exp_f32_e32 v42, v29
	v_fma_f32 v29, |v27|, s92, 1.0
	v_rcp_f32_e32 v28, v28
	v_rcp_f32_e32 v29, v29
	v_mul_f32_e32 v39, v27, v27
	v_mul_f32_e32 v39, 0xbf38aa3b, v39
	v_exp_f32_e32 v43, v39
	v_pk_fma_f32 v[44:45], v[28:29], s[10:11], v[18:19] op_sel_hi:[1,0,0]
	v_cmp_gt_f32_e32 vcc, 0, v27
	v_pk_fma_f32 v[44:45], v[28:29], v[44:45], s[14:15] op_sel_hi:[1,1,0]
	s_nop 0
	v_pk_fma_f32 v[44:45], v[28:29], v[44:45], s[16:17] op_sel_hi:[1,1,0]
	s_nop 0
	v_pk_fma_f32 v[44:45], v[28:29], v[44:45], s[18:19] op_sel_hi:[1,1,0]
	v_pk_mul_f32 v[28:29], v[28:29], v[44:45]
	v_mov_b32_e32 v44, v25
	v_pk_mul_f32 v[28:29], v[42:43], v[28:29]
	v_mov_b32_e32 v45, v37
	v_pk_mul_f32 v[42:43], v[28:29], v[26:27]
	v_pk_fma_f32 v[28:29], v[28:29], v[26:27], v[26:27] neg_lo:[1,0,0] neg_hi:[1,0,0]
	v_mov_b32_e32 v27, v34
	v_cndmask_b32_e32 v43, v29, v43, vcc
	v_cmp_gt_f32_e32 vcc, 0, v26
	v_mov_b32_e32 v26, v22
	v_mov_b32_e32 v29, v36
	v_cndmask_b32_e32 v42, v28, v42, vcc
	v_mov_b32_e32 v28, v24
	v_pk_add_f32 v[26:27], v[26:27], v[28:29]
	v_mov_b32_e32 v28, v23
	v_add_f32_e32 v26, v26, v27
	v_mov_b32_e32 v29, v35
	s_nop 0
	v_add_f32_dpp v26, v26, v26 quad_perm:[1,0,3,2] row_mask:0xf bank_mask:0xf bound_ctrl:1
	v_pk_add_f32 v[28:29], v[28:29], v[44:45]
	v_mov_b32_e32 v44, v33
	v_add_f32_dpp v26, v26, v26 quad_perm:[2,3,0,1] row_mask:0xf bank_mask:0xf bound_ctrl:1
	v_mov_b32_e32 v45, v43
	s_nop 0
	v_add_f32_dpp v26, v26, v26 row_half_mirror row_mask:0xf bank_mask:0xf bound_ctrl:1
	s_nop 1
	v_add_f32_dpp v26, v26, v26 row_mirror row_mask:0xf bank_mask:0xf bound_ctrl:1
	s_nop 1
	v_add_f32_dpp v26, v26, v26 row_bcast:15 row_mask:0xa bank_mask:0xf
	s_nop 1
	v_add_f32_dpp v26, v26, v26 row_bcast:31 row_mask:0xc bank_mask:0xf
	v_add_f32_e32 v27, v28, v29
	v_readlane_b32 s6, v26, 63
	s_nop 0
	v_add_f32_dpp v27, v27, v27 quad_perm:[1,0,3,2] row_mask:0xf bank_mask:0xf bound_ctrl:1
	s_xor_b32 s6, s6, 0x80000000
	s_nop 0
	v_add_f32_dpp v27, v27, v27 quad_perm:[2,3,0,1] row_mask:0xf bank_mask:0xf bound_ctrl:1
	s_nop 1
	v_add_f32_dpp v27, v27, v27 row_half_mirror row_mask:0xf bank_mask:0xf bound_ctrl:1
	s_nop 1
	v_add_f32_dpp v27, v27, v27 row_mirror row_mask:0xf bank_mask:0xf bound_ctrl:1
	s_nop 1
	v_add_f32_dpp v27, v27, v27 row_bcast:15 row_mask:0xa bank_mask:0xf
	s_nop 1
	v_add_f32_dpp v27, v27, v27 row_bcast:31 row_mask:0xc bank_mask:0xf
	s_nop 0
	v_readlane_b32 s7, v27, 63
	s_xor_b32 s7, s7, 0x80000000
	s_nop 0
	v_pk_fma_f32 v[28:29], s[6:7], v[20:21], v[22:23] op_sel_hi:[1,0,1]
	v_pk_fma_f32 v[26:27], s[6:7], v[20:21], v[24:25] op_sel_hi:[1,0,1]
	v_pk_fma_f32 v[24:25], s[6:7], v[20:21], v[34:35] op_sel_hi:[1,0,1]
	v_pk_fma_f32 v[22:23], s[6:7], v[20:21], v[36:37] op_sel_hi:[1,0,1]
	v_mov_b32_e32 v34, v30
	v_mov_b32_e32 v35, v40
	v_mov_b32_e32 v36, v32
	v_mov_b32_e32 v37, v42
	v_pk_add_f32 v[34:35], v[34:35], v[36:37]
	v_mov_b32_e32 v36, v31
	v_add_f32_e32 v34, v34, v35
	v_mov_b32_e32 v37, v41
	s_nop 0
	v_add_f32_dpp v34, v34, v34 quad_perm:[1,0,3,2] row_mask:0xf bank_mask:0xf bound_ctrl:1
	v_pk_add_f32 v[36:37], v[36:37], v[44:45]
	s_nop 0
	v_add_f32_dpp v34, v34, v34 quad_perm:[2,3,0,1] row_mask:0xf bank_mask:0xf bound_ctrl:1
	s_nop 1
	v_add_f32_dpp v34, v34, v34 row_half_mirror row_mask:0xf bank_mask:0xf bound_ctrl:1
	s_nop 1
	v_add_f32_dpp v34, v34, v34 row_mirror row_mask:0xf bank_mask:0xf bound_ctrl:1
	s_nop 1
	v_add_f32_dpp v34, v34, v34 row_bcast:15 row_mask:0xa bank_mask:0xf
	s_nop 1
	v_add_f32_dpp v34, v34, v34 row_bcast:31 row_mask:0xc bank_mask:0xf
	v_add_f32_e32 v35, v36, v37
	v_readlane_b32 s6, v34, 63
	s_nop 0
	v_add_f32_dpp v35, v35, v35 quad_perm:[1,0,3,2] row_mask:0xf bank_mask:0xf bound_ctrl:1
	s_xor_b32 s6, s6, 0x80000000
	s_nop 0
	v_add_f32_dpp v35, v35, v35 quad_perm:[2,3,0,1] row_mask:0xf bank_mask:0xf bound_ctrl:1
	s_nop 1
	v_add_f32_dpp v35, v35, v35 row_half_mirror row_mask:0xf bank_mask:0xf bound_ctrl:1
	s_nop 1
	v_add_f32_dpp v35, v35, v35 row_mirror row_mask:0xf bank_mask:0xf bound_ctrl:1
	s_nop 1
	v_add_f32_dpp v35, v35, v35 row_bcast:15 row_mask:0xa bank_mask:0xf
	s_nop 1
	v_add_f32_dpp v35, v35, v35 row_bcast:31 row_mask:0xc bank_mask:0xf
	s_nop 0
	v_readlane_b32 s7, v35, 63
	s_xor_b32 s7, s7, 0x80000000
	s_nop 0
	v_pk_fma_f32 v[34:35], s[6:7], v[20:21], v[32:33] op_sel_hi:[1,0,1]
	v_pk_fma_f32 v[32:33], s[6:7], v[20:21], v[40:41] op_sel_hi:[1,0,1]
	global_load_ushort v46, v38, s[54:55] offset:512
	global_load_ushort v50, v38, s[54:55] offset:640
	global_load_ushort v71, v38, s[54:55] offset:768
	global_load_ushort v76, v38, s[54:55] offset:896
	global_load_ushort v47, v38, s[46:47] offset:512
	global_load_ushort v51, v38, s[46:47] offset:640
	global_load_ushort v72, v38, s[46:47] offset:768
	global_load_ushort v77, v38, s[46:47] offset:896
	global_load_ushort v39, v38, s[56:57] offset:512
	global_load_ushort v48, v38, s[56:57] offset:640
	global_load_ushort v52, v38, s[56:57] offset:768
	global_load_ushort v74, v38, s[56:57] offset:896
	global_load_ushort v40, v38, s[48:49] offset:512
	global_load_ushort v49, v38, s[48:49] offset:640
	global_load_ushort v53, v38, s[48:49] offset:768
	global_load_ushort v75, v38, s[48:49] offset:896
	global_load_ushort v60, v38, s[50:51] offset:512
	global_load_ushort v62, v38, s[50:51] offset:640
	global_load_ushort v67, v38, s[50:51] offset:768
	global_load_ushort v58, v38, s[50:51] offset:896
	global_load_ushort v61, v38, s[42:43] offset:512
	global_load_ushort v63, v38, s[42:43] offset:640
	global_load_ushort v68, v38, s[42:43] offset:768
	global_load_ushort v59, v38, s[42:43] offset:896
	global_load_ushort v54, v38, s[52:53] offset:512
	global_load_ushort v56, v38, s[52:53] offset:640
	global_load_ushort v69, v38, s[52:53] offset:768
	global_load_ushort v64, v38, s[52:53] offset:896
	global_load_ushort v55, v38, s[44:45] offset:512
	global_load_ushort v57, v38, s[44:45] offset:640
	global_load_ushort v70, v38, s[44:45] offset:768
	global_load_ushort v65, v38, s[44:45] offset:896
	v_pk_fma_f32 v[36:37], s[6:7], v[20:21], v[30:31] op_sel_hi:[1,0,1]
	v_pk_fma_f32 v[30:31], s[6:7], v[20:21], v[42:43] op_sel_hi:[1,0,1]
	s_load_dwordx2 s[42:43], s[0:1], 0x30
	s_load_dwordx4 s[52:55], s[0:1], 0x18
	s_waitcnt vmcnt(23)
	v_lshlrev_b32_e32 v39, 16, v39
	v_fma_f32 v41, |v39|, s92, 1.0
	v_rcp_f32_e32 v41, v41
	v_mul_f32_e32 v43, v39, v39
	s_waitcnt vmcnt(19)
	v_lshlrev_b32_e32 v38, 16, v40
	v_fma_f32 v40, |v38|, s92, 1.0
	v_rcp_f32_e32 v40, v40
	v_mul_f32_e32 v42, v38, v38
	v_mul_f32_e32 v42, 0xbf38aa3b, v42
	v_mul_f32_e32 v43, 0xbf38aa3b, v43
	v_pk_fma_f32 v[44:45], v[40:41], s[10:11], v[18:19] op_sel_hi:[1,0,0]
	v_exp_f32_e32 v42, v42
	v_pk_fma_f32 v[44:45], v[40:41], v[44:45], s[14:15] op_sel_hi:[1,1,0]
	v_exp_f32_e32 v43, v43
	v_pk_fma_f32 v[44:45], v[40:41], v[44:45], s[16:17] op_sel_hi:[1,1,0]
	v_cmp_gt_f32_e32 vcc, 0, v39
	v_pk_fma_f32 v[44:45], v[40:41], v[44:45], s[18:19] op_sel_hi:[1,1,0]
	s_waitcnt vmcnt(9)
	v_lshlrev_b32_e32 v68, 16, v68
	v_pk_mul_f32 v[40:41], v[40:41], v[44:45]
	s_waitcnt vmcnt(1)
	v_lshlrev_b32_e32 v70, 16, v70
	v_pk_mul_f32 v[40:41], v[42:43], v[40:41]
	v_pk_mul_f32 v[42:43], v[40:41], v[38:39]
	v_pk_fma_f32 v[40:41], v[40:41], v[38:39], v[38:39] neg_lo:[1,0,0] neg_hi:[1,0,0]
	s_nop 0
	v_cndmask_b32_e32 v39, v41, v43, vcc
	v_cmp_gt_f32_e32 vcc, 0, v38
	v_lshlrev_b32_e32 v41, 16, v46
	v_mul_f32_e32 v45, v41, v41
	v_cndmask_b32_e32 v38, v40, v42, vcc
	v_lshlrev_b32_e32 v40, 16, v47
	v_mul_f32_e32 v43, v40, v40
	v_mul_f32_e32 v43, 0xbf38aa3b, v43
	v_fma_f32 v42, |v40|, s92, 1.0
	v_exp_f32_e32 v44, v43
	v_fma_f32 v43, |v41|, s92, 1.0
	v_rcp_f32_e32 v42, v42
	v_rcp_f32_e32 v43, v43
	v_mul_f32_e32 v45, 0xbf38aa3b, v45
	v_exp_f32_e32 v45, v45
	v_cmp_gt_f32_e32 vcc, 0, v41
	v_pk_fma_f32 v[46:47], v[42:43], s[10:11], v[18:19] op_sel_hi:[1,0,0]
	s_nop 0
	v_pk_fma_f32 v[46:47], v[42:43], v[46:47], s[14:15] op_sel_hi:[1,1,0]
	s_nop 0
	v_pk_fma_f32 v[46:47], v[42:43], v[46:47], s[16:17] op_sel_hi:[1,1,0]
	s_nop 0
	v_pk_fma_f32 v[46:47], v[42:43], v[46:47], s[18:19] op_sel_hi:[1,1,0]
	v_pk_mul_f32 v[42:43], v[42:43], v[46:47]
	v_pk_mul_f32 v[42:43], v[44:45], v[42:43]
	v_pk_mul_f32 v[44:45], v[42:43], v[40:41]
	v_pk_fma_f32 v[42:43], v[42:43], v[40:41], v[40:41] neg_lo:[1,0,0] neg_hi:[1,0,0]
	v_lshlrev_b32_e32 v41, 16, v48
	v_cndmask_b32_e32 v47, v43, v45, vcc
	v_cmp_gt_f32_e32 vcc, 0, v40
	v_lshlrev_b32_e32 v40, 16, v49
	v_fma_f32 v43, |v41|, s92, 1.0
	v_cndmask_b32_e32 v46, v42, v44, vcc
	v_fma_f32 v42, |v40|, s92, 1.0
	v_rcp_f32_e32 v42, v42
	v_rcp_f32_e32 v43, v43
	v_mul_f32_e32 v44, v40, v40
	v_mul_f32_e32 v45, v41, v41
	v_mul_f32_e32 v44, 0xbf38aa3b, v44
	v_pk_fma_f32 v[48:49], v[42:43], s[10:11], v[18:19] op_sel_hi:[1,0,0]
	v_mul_f32_e32 v45, 0xbf38aa3b, v45
	v_exp_f32_e32 v44, v44
	v_pk_fma_f32 v[48:49], v[42:43], v[48:49], s[14:15] op_sel_hi:[1,1,0]
	v_exp_f32_e32 v45, v45
	v_pk_fma_f32 v[48:49], v[42:43], v[48:49], s[16:17] op_sel_hi:[1,1,0]
	v_cmp_gt_f32_e32 vcc, 0, v41
	v_pk_fma_f32 v[48:49], v[42:43], v[48:49], s[18:19] op_sel_hi:[1,1,0]
	s_nop 0
	v_pk_mul_f32 v[42:43], v[42:43], v[48:49]
	v_pk_mul_f32 v[42:43], v[44:45], v[42:43]
	v_pk_mul_f32 v[44:45], v[42:43], v[40:41]
	v_pk_fma_f32 v[42:43], v[42:43], v[40:41], v[40:41] neg_lo:[1,0,0] neg_hi:[1,0,0]
	v_lshlrev_b32_e32 v41, 16, v50
	v_cndmask_b32_e32 v43, v43, v45, vcc
	v_cmp_gt_f32_e32 vcc, 0, v40
	v_lshlrev_b32_e32 v40, 16, v51
	v_mul_f32_e32 v45, v40, v40
	v_mul_f32_e32 v45, 0xbf38aa3b, v45
	v_cndmask_b32_e32 v42, v42, v44, vcc
	v_fma_f32 v44, |v40|, s92, 1.0
	v_exp_f32_e32 v48, v45
	v_fma_f32 v45, |v41|, s92, 1.0
	v_rcp_f32_e32 v44, v44
	v_rcp_f32_e32 v45, v45
	v_mul_f32_e32 v49, v41, v41
	v_mul_f32_e32 v49, 0xbf38aa3b, v49
	v_exp_f32_e32 v49, v49
	v_pk_fma_f32 v[50:51], v[44:45], s[10:11], v[18:19] op_sel_hi:[1,0,0]
	v_cmp_gt_f32_e32 vcc, 0, v41
	v_pk_fma_f32 v[50:51], v[44:45], v[50:51], s[14:15] op_sel_hi:[1,1,0]
	s_nop 0
	v_pk_fma_f32 v[50:51], v[44:45], v[50:51], s[16:17] op_sel_hi:[1,1,0]
	s_nop 0
	v_pk_fma_f32 v[50:51], v[44:45], v[50:51], s[18:19] op_sel_hi:[1,1,0]
	v_pk_mul_f32 v[44:45], v[44:45], v[50:51]
	v_pk_mul_f32 v[44:45], v[48:49], v[44:45]
	v_pk_mul_f32 v[48:49], v[44:45], v[40:41]
	v_pk_fma_f32 v[44:45], v[44:45], v[40:41], v[40:41] neg_lo:[1,0,0] neg_hi:[1,0,0]
	v_lshlrev_b32_e32 v41, 16, v52
	v_cndmask_b32_e32 v49, v45, v49, vcc
	v_cmp_gt_f32_e32 vcc, 0, v40
	v_lshlrev_b32_e32 v40, 16, v53
	v_fma_f32 v45, |v41|, s92, 1.0
	v_cndmask_b32_e32 v48, v44, v48, vcc
	v_fma_f32 v44, |v40|, s92, 1.0
	v_rcp_f32_e32 v44, v44
	v_rcp_f32_e32 v45, v45
	v_mul_f32_e32 v50, v40, v40
	v_mul_f32_e32 v51, v41, v41
	v_mul_f32_e32 v50, 0xbf38aa3b, v50
	v_pk_fma_f32 v[52:53], v[44:45], s[10:11], v[18:19] op_sel_hi:[1,0,0]
	v_mul_f32_e32 v51, 0xbf38aa3b, v51
	v_exp_f32_e32 v50, v50
	v_pk_fma_f32 v[52:53], v[44:45], v[52:53], s[14:15] op_sel_hi:[1,1,0]
	v_exp_f32_e32 v51, v51
	v_pk_fma_f32 v[52:53], v[44:45], v[52:53], s[16:17] op_sel_hi:[1,1,0]
	v_cmp_gt_f32_e32 vcc, 0, v41
	v_pk_fma_f32 v[52:53], v[44:45], v[52:53], s[18:19] op_sel_hi:[1,1,0]
	s_nop 0
	v_pk_mul_f32 v[44:45], v[44:45], v[52:53]
	v_pk_mul_f32 v[44:45], v[50:51], v[44:45]
	v_pk_mul_f32 v[50:51], v[44:45], v[40:41]
	v_pk_fma_f32 v[44:45], v[44:45], v[40:41], v[40:41] neg_lo:[1,0,0] neg_hi:[1,0,0]
	v_lshlrev_b32_e32 v41, 16, v71
	v_cndmask_b32_e32 v51, v45, v51, vcc
	v_cmp_gt_f32_e32 vcc, 0, v40
	v_lshlrev_b32_e32 v40, 16, v72
	v_mul_f32_e32 v45, v40, v40
	v_mul_f32_e32 v45, 0xbf38aa3b, v45
	v_cndmask_b32_e32 v50, v44, v50, vcc
	v_fma_f32 v44, |v40|, s92, 1.0
	v_exp_f32_e32 v52, v45
	v_fma_f32 v45, |v41|, s92, 1.0
	v_rcp_f32_e32 v44, v44
	v_rcp_f32_e32 v45, v45
	v_mul_f32_e32 v53, v41, v41
	v_mul_f32_e32 v53, 0xbf38aa3b, v53
	v_exp_f32_e32 v53, v53
	v_pk_fma_f32 v[72:73], v[44:45], s[10:11], v[18:19] op_sel_hi:[1,0,0]
	v_cmp_gt_f32_e32 vcc, 0, v41
	v_pk_fma_f32 v[72:73], v[44:45], v[72:73], s[14:15] op_sel_hi:[1,1,0]
	s_nop 0
	v_pk_fma_f32 v[72:73], v[44:45], v[72:73], s[16:17] op_sel_hi:[1,1,0]
	s_nop 0
	v_pk_fma_f32 v[72:73], v[44:45], v[72:73], s[18:19] op_sel_hi:[1,1,0]
	v_pk_mul_f32 v[44:45], v[44:45], v[72:73]
	v_pk_mul_f32 v[44:45], v[52:53], v[44:45]
	v_pk_mul_f32 v[52:53], v[44:45], v[40:41]
	v_pk_fma_f32 v[44:45], v[44:45], v[40:41], v[40:41] neg_lo:[1,0,0] neg_hi:[1,0,0]
	v_lshlrev_b32_e32 v41, 16, v74
	v_cndmask_b32_e32 v73, v45, v53, vcc
	v_cmp_gt_f32_e32 vcc, 0, v40
	v_lshlrev_b32_e32 v40, 16, v75
	v_fma_f32 v45, |v41|, s92, 1.0
	v_cndmask_b32_e32 v72, v44, v52, vcc
	v_fma_f32 v44, |v40|, s92, 1.0
	v_rcp_f32_e32 v44, v44
	v_rcp_f32_e32 v45, v45
	v_mul_f32_e32 v52, v40, v40
	v_mul_f32_e32 v53, v41, v41
	v_mul_f32_e32 v52, 0xbf38aa3b, v52
	v_pk_fma_f32 v[74:75], v[44:45], s[10:11], v[18:19] op_sel_hi:[1,0,0]
	v_mul_f32_e32 v53, 0xbf38aa3b, v53
	v_exp_f32_e32 v52, v52
	v_pk_fma_f32 v[74:75], v[44:45], v[74:75], s[14:15] op_sel_hi:[1,1,0]
	v_exp_f32_e32 v53, v53
	v_pk_fma_f32 v[74:75], v[44:45], v[74:75], s[16:17] op_sel_hi:[1,1,0]
	v_cmp_gt_f32_e32 vcc, 0, v41
	v_pk_fma_f32 v[74:75], v[44:45], v[74:75], s[18:19] op_sel_hi:[1,1,0]
	s_nop 0
	v_pk_mul_f32 v[44:45], v[44:45], v[74:75]
	v_pk_mul_f32 v[44:45], v[52:53], v[44:45]
	v_pk_mul_f32 v[52:53], v[44:45], v[40:41]
	v_pk_fma_f32 v[44:45], v[44:45], v[40:41], v[40:41] neg_lo:[1,0,0] neg_hi:[1,0,0]
	v_lshlrev_b32_e32 v41, 16, v76
	v_cndmask_b32_e32 v53, v45, v53, vcc
	v_cmp_gt_f32_e32 vcc, 0, v40
	v_lshlrev_b32_e32 v40, 16, v77
	v_mul_f32_e32 v45, v40, v40
	v_mul_f32_e32 v45, 0xbf38aa3b, v45
	v_cndmask_b32_e32 v52, v44, v52, vcc
	v_fma_f32 v44, |v40|, s92, 1.0
	v_exp_f32_e32 v74, v45
	v_fma_f32 v45, |v41|, s92, 1.0
	v_rcp_f32_e32 v44, v44
	v_rcp_f32_e32 v45, v45
	v_mul_f32_e32 v71, v41, v41
	v_mul_f32_e32 v71, 0xbf38aa3b, v71
	v_exp_f32_e32 v75, v71
	v_pk_fma_f32 v[76:77], v[44:45], s[10:11], v[18:19] op_sel_hi:[1,0,0]
	v_cmp_gt_f32_e32 vcc, 0, v41
	v_pk_fma_f32 v[76:77], v[44:45], v[76:77], s[14:15] op_sel_hi:[1,1,0]
	s_nop 0
	v_pk_fma_f32 v[76:77], v[44:45], v[76:77], s[16:17] op_sel_hi:[1,1,0]
	s_nop 0
	v_pk_fma_f32 v[76:77], v[44:45], v[76:77], s[18:19] op_sel_hi:[1,1,0]
	v_pk_mul_f32 v[44:45], v[44:45], v[76:77]
	v_mov_b32_e32 v76, v43
	v_pk_mul_f32 v[44:45], v[74:75], v[44:45]
	v_mov_b32_e32 v77, v53
	v_pk_mul_f32 v[74:75], v[44:45], v[40:41]
	v_pk_fma_f32 v[44:45], v[44:45], v[40:41], v[40:41] neg_lo:[1,0,0] neg_hi:[1,0,0]
	v_mov_b32_e32 v41, v50
	v_cndmask_b32_e32 v75, v45, v75, vcc
	v_cmp_gt_f32_e32 vcc, 0, v40
	v_mov_b32_e32 v40, v38
	v_mov_b32_e32 v45, v52
	v_cndmask_b32_e32 v74, v44, v74, vcc
	v_mov_b32_e32 v44, v42
	v_pk_add_f32 v[40:41], v[40:41], v[44:45]
	v_mov_b32_e32 v44, v39
	v_add_f32_e32 v40, v40, v41
	v_mov_b32_e32 v45, v51
	s_nop 0
	v_add_f32_dpp v40, v40, v40 quad_perm:[1,0,3,2] row_mask:0xf bank_mask:0xf bound_ctrl:1
	v_pk_add_f32 v[44:45], v[44:45], v[76:77]
	v_mov_b32_e32 v76, v49
	v_add_f32_dpp v40, v40, v40 quad_perm:[2,3,0,1] row_mask:0xf bank_mask:0xf bound_ctrl:1
	v_mov_b32_e32 v77, v75
	s_nop 0
	v_add_f32_dpp v40, v40, v40 row_half_mirror row_mask:0xf bank_mask:0xf bound_ctrl:1
	s_nop 1
	v_add_f32_dpp v40, v40, v40 row_mirror row_mask:0xf bank_mask:0xf bound_ctrl:1
	s_nop 1
	v_add_f32_dpp v40, v40, v40 row_bcast:15 row_mask:0xa bank_mask:0xf
	s_nop 1
	v_add_f32_dpp v40, v40, v40 row_bcast:31 row_mask:0xc bank_mask:0xf
	v_add_f32_e32 v41, v44, v45
	v_readlane_b32 s6, v40, 63
	s_nop 0
	v_add_f32_dpp v41, v41, v41 quad_perm:[1,0,3,2] row_mask:0xf bank_mask:0xf bound_ctrl:1
	s_xor_b32 s6, s6, 0x80000000
	s_nop 0
	v_add_f32_dpp v41, v41, v41 quad_perm:[2,3,0,1] row_mask:0xf bank_mask:0xf bound_ctrl:1
	s_nop 1
	v_add_f32_dpp v41, v41, v41 row_half_mirror row_mask:0xf bank_mask:0xf bound_ctrl:1
	s_nop 1
	v_add_f32_dpp v41, v41, v41 row_mirror row_mask:0xf bank_mask:0xf bound_ctrl:1
	s_nop 1
	v_add_f32_dpp v41, v41, v41 row_bcast:15 row_mask:0xa bank_mask:0xf
	s_nop 1
	v_add_f32_dpp v41, v41, v41 row_bcast:31 row_mask:0xc bank_mask:0xf
	s_nop 0
	v_readlane_b32 s7, v41, 63
	s_xor_b32 s7, s7, 0x80000000
	s_nop 0
	v_pk_fma_f32 v[40:41], s[6:7], v[20:21], v[38:39] op_sel_hi:[1,0,1]
	v_pk_fma_f32 v[44:45], s[6:7], v[20:21], v[42:43] op_sel_hi:[1,0,1]
	v_pk_fma_f32 v[42:43], s[6:7], v[20:21], v[50:51] op_sel_hi:[1,0,1]
	v_pk_fma_f32 v[38:39], s[6:7], v[20:21], v[52:53] op_sel_hi:[1,0,1]
	v_mov_b32_e32 v50, v46
	v_mov_b32_e32 v51, v72
	v_mov_b32_e32 v52, v48
	v_mov_b32_e32 v53, v74
	v_pk_add_f32 v[50:51], v[50:51], v[52:53]
	v_mov_b32_e32 v52, v47
	v_add_f32_e32 v50, v50, v51
	v_mov_b32_e32 v53, v73
	s_nop 0
	v_add_f32_dpp v50, v50, v50 quad_perm:[1,0,3,2] row_mask:0xf bank_mask:0xf bound_ctrl:1
	v_pk_add_f32 v[52:53], v[52:53], v[76:77]
	s_nop 0
	v_add_f32_dpp v50, v50, v50 quad_perm:[2,3,0,1] row_mask:0xf bank_mask:0xf bound_ctrl:1
	s_nop 1
	v_add_f32_dpp v50, v50, v50 row_half_mirror row_mask:0xf bank_mask:0xf bound_ctrl:1
	s_nop 1
	v_add_f32_dpp v50, v50, v50 row_mirror row_mask:0xf bank_mask:0xf bound_ctrl:1
	s_nop 1
	v_add_f32_dpp v50, v50, v50 row_bcast:15 row_mask:0xa bank_mask:0xf
	s_nop 1
	v_add_f32_dpp v50, v50, v50 row_bcast:31 row_mask:0xc bank_mask:0xf
	v_add_f32_e32 v51, v52, v53
	v_readlane_b32 s6, v50, 63
	s_nop 0
	v_add_f32_dpp v51, v51, v51 quad_perm:[1,0,3,2] row_mask:0xf bank_mask:0xf bound_ctrl:1
	s_xor_b32 s6, s6, 0x80000000
	s_nop 0
	v_add_f32_dpp v51, v51, v51 quad_perm:[2,3,0,1] row_mask:0xf bank_mask:0xf bound_ctrl:1
	s_nop 1
	v_add_f32_dpp v51, v51, v51 row_half_mirror row_mask:0xf bank_mask:0xf bound_ctrl:1
	s_nop 1
	v_add_f32_dpp v51, v51, v51 row_mirror row_mask:0xf bank_mask:0xf bound_ctrl:1
	s_nop 1
	v_add_f32_dpp v51, v51, v51 row_bcast:15 row_mask:0xa bank_mask:0xf
	s_nop 1
	v_add_f32_dpp v51, v51, v51 row_bcast:31 row_mask:0xc bank_mask:0xf
	s_nop 0
	v_readlane_b32 s7, v51, 63
	s_xor_b32 s7, s7, 0x80000000
	s_nop 0
	v_pk_fma_f32 v[50:51], s[6:7], v[20:21], v[48:49] op_sel_hi:[1,0,1]
	v_pk_fma_f32 v[48:49], s[6:7], v[20:21], v[72:73] op_sel_hi:[1,0,1]
	v_lshlrev_b32_e32 v73, 16, v54
	v_lshlrev_b32_e32 v72, 16, v55
	v_fma_f32 v54, |v72|, s92, 1.0
	v_fma_f32 v55, |v73|, s92, 1.0
	v_rcp_f32_e32 v54, v54
	v_rcp_f32_e32 v55, v55
	v_mul_f32_e32 v71, v72, v72
	v_mul_f32_e32 v71, 0xbf38aa3b, v71
	v_pk_fma_f32 v[52:53], s[6:7], v[20:21], v[46:47] op_sel_hi:[1,0,1]
	v_pk_fma_f32 v[46:47], s[6:7], v[20:21], v[74:75] op_sel_hi:[1,0,1]
	v_exp_f32_e32 v74, v71
	v_mul_f32_e32 v71, v73, v73
	v_pk_fma_f32 v[76:77], v[54:55], s[10:11], v[18:19] op_sel_hi:[1,0,0]
	v_mul_f32_e32 v71, 0xbf38aa3b, v71
	v_pk_fma_f32 v[76:77], v[54:55], v[76:77], s[14:15] op_sel_hi:[1,1,0]
	v_exp_f32_e32 v75, v71
	v_pk_fma_f32 v[76:77], v[54:55], v[76:77], s[16:17] op_sel_hi:[1,1,0]
	v_cmp_gt_f32_e32 vcc, 0, v73
	v_pk_fma_f32 v[76:77], v[54:55], v[76:77], s[18:19] op_sel_hi:[1,1,0]
	s_mov_b32 s6, 0xbe11a98e
	v_pk_mul_f32 v[54:55], v[54:55], v[76:77]
	v_pk_mul_f32 v[54:55], v[74:75], v[54:55]
	v_pk_mul_f32 v[74:75], v[54:55], v[72:73]
	v_pk_fma_f32 v[54:55], v[54:55], v[72:73], v[72:73] neg_lo:[1,0,0] neg_hi:[1,0,0]
	v_lshlrev_b32_e32 v73, 16, v60
	v_cndmask_b32_e32 v55, v55, v75, vcc
	v_cmp_gt_f32_e32 vcc, 0, v72
	v_lshlrev_b32_e32 v72, 16, v61
	v_mul_f32_e32 v61, v72, v72
	v_mul_f32_e32 v61, 0xbf38aa3b, v61
	v_cndmask_b32_e32 v54, v54, v74, vcc
	v_fma_f32 v60, |v72|, s92, 1.0
	v_exp_f32_e32 v74, v61
	v_fma_f32 v61, |v73|, s92, 1.0
	v_rcp_f32_e32 v60, v60
	v_rcp_f32_e32 v61, v61
	v_mul_f32_e32 v71, v73, v73
	v_mul_f32_e32 v71, 0xbf38aa3b, v71
	v_exp_f32_e32 v75, v71
	v_pk_fma_f32 v[76:77], v[60:61], s[10:11], v[18:19] op_sel_hi:[1,0,0]
	v_cmp_gt_f32_e32 vcc, 0, v73
	v_pk_fma_f32 v[76:77], v[60:61], v[76:77], s[14:15] op_sel_hi:[1,1,0]
	s_nop 0
	v_pk_fma_f32 v[76:77], v[60:61], v[76:77], s[16:17] op_sel_hi:[1,1,0]
	s_nop 0
	v_pk_fma_f32 v[76:77], v[60:61], v[76:77], s[18:19] op_sel_hi:[1,1,0]
	v_pk_mul_f32 v[60:61], v[60:61], v[76:77]
	v_pk_mul_f32 v[60:61], v[74:75], v[60:61]
	v_pk_mul_f32 v[74:75], v[60:61], v[72:73]
	v_pk_fma_f32 v[60:61], v[60:61], v[72:73], v[72:73] neg_lo:[1,0,0] neg_hi:[1,0,0]
	v_lshlrev_b32_e32 v73, 16, v56
	v_cndmask_b32_e32 v61, v61, v75, vcc
	v_cmp_gt_f32_e32 vcc, 0, v72
	v_lshlrev_b32_e32 v72, 16, v57
	v_fma_f32 v56, |v72|, s92, 1.0
	v_fma_f32 v57, |v73|, s92, 1.0
	v_rcp_f32_e32 v56, v56
	v_rcp_f32_e32 v57, v57
	v_mul_f32_e32 v71, v72, v72
	v_mul_f32_e32 v71, 0xbf38aa3b, v71
	v_cndmask_b32_e32 v60, v60, v74, vcc
	v_exp_f32_e32 v74, v71
	v_mul_f32_e32 v71, v73, v73
	v_pk_fma_f32 v[76:77], v[56:57], s[10:11], v[18:19] op_sel_hi:[1,0,0]
	v_mul_f32_e32 v71, 0xbf38aa3b, v71
	v_pk_fma_f32 v[76:77], v[56:57], v[76:77], s[14:15] op_sel_hi:[1,1,0]
	v_exp_f32_e32 v75, v71
	v_pk_fma_f32 v[76:77], v[56:57], v[76:77], s[16:17] op_sel_hi:[1,1,0]
	v_cmp_gt_f32_e32 vcc, 0, v73
	v_pk_fma_f32 v[76:77], v[56:57], v[76:77], s[18:19] op_sel_hi:[1,1,0]
	s_nop 0
	v_pk_mul_f32 v[56:57], v[56:57], v[76:77]
	v_pk_mul_f32 v[56:57], v[74:75], v[56:57]
	v_pk_mul_f32 v[74:75], v[56:57], v[72:73]
	v_pk_fma_f32 v[56:57], v[56:57], v[72:73], v[72:73] neg_lo:[1,0,0] neg_hi:[1,0,0]
	v_lshlrev_b32_e32 v73, 16, v62
	v_cndmask_b32_e32 v57, v57, v75, vcc
	v_cmp_gt_f32_e32 vcc, 0, v72
	v_lshlrev_b32_e32 v72, 16, v63
	v_mul_f32_e32 v63, v72, v72
	v_mul_f32_e32 v63, 0xbf38aa3b, v63
	v_cndmask_b32_e32 v56, v56, v74, vcc
	v_fma_f32 v62, |v72|, s92, 1.0
	v_exp_f32_e32 v74, v63
	v_fma_f32 v63, |v73|, s92, 1.0
	v_rcp_f32_e32 v62, v62
	v_rcp_f32_e32 v63, v63
	v_mul_f32_e32 v71, v73, v73
	v_mul_f32_e32 v71, 0xbf38aa3b, v71
	v_exp_f32_e32 v75, v71
	v_pk_fma_f32 v[76:77], v[62:63], s[10:11], v[18:19] op_sel_hi:[1,0,0]
	v_cmp_gt_f32_e32 vcc, 0, v73
	v_pk_fma_f32 v[76:77], v[62:63], v[76:77], s[14:15] op_sel_hi:[1,1,0]
	v_lshlrev_b32_e32 v71, 16, v69
	v_pk_fma_f32 v[76:77], v[62:63], v[76:77], s[16:17] op_sel_hi:[1,1,0]
	v_fma_f32 v69, |v70|, s92, 1.0
	v_pk_fma_f32 v[76:77], v[62:63], v[76:77], s[18:19] op_sel_hi:[1,1,0]
	v_pk_mul_f32 v[62:63], v[62:63], v[76:77]
	v_pk_mul_f32 v[62:63], v[74:75], v[62:63]
	v_pk_mul_f32 v[74:75], v[62:63], v[72:73]
	v_pk_fma_f32 v[62:63], v[62:63], v[72:73], v[72:73] neg_lo:[1,0,0] neg_hi:[1,0,0]
	s_nop 0
	v_cndmask_b32_e32 v63, v63, v75, vcc
	v_cmp_gt_f32_e32 vcc, 0, v72
	v_rcp_f32_e32 v72, v69
	v_fma_f32 v69, |v71|, s92, 1.0
	v_rcp_f32_e32 v73, v69
	v_mul_f32_e32 v69, v70, v70
	v_mul_f32_e32 v69, 0xbf38aa3b, v69
	v_cndmask_b32_e32 v62, v62, v74, vcc
	v_exp_f32_e32 v74, v69
	v_mul_f32_e32 v69, v71, v71
	v_pk_fma_f32 v[76:77], v[72:73], s[10:11], v[18:19] op_sel_hi:[1,0,0]
	v_mul_f32_e32 v69, 0xbf38aa3b, v69
	v_pk_fma_f32 v[76:77], v[72:73], v[76:77], s[14:15] op_sel_hi:[1,1,0]
	v_exp_f32_e32 v75, v69
	v_pk_fma_f32 v[76:77], v[72:73], v[76:77], s[16:17] op_sel_hi:[1,1,0]
	v_cmp_gt_f32_e32 vcc, 0, v71
	v_pk_fma_f32 v[76:77], v[72:73], v[76:77], s[18:19] op_sel_hi:[1,1,0]
	v_lshlrev_b32_e32 v69, 16, v67
	v_pk_mul_f32 v[72:73], v[72:73], v[76:77]
	v_fma_f32 v67, |v68|, s92, 1.0
	v_pk_mul_f32 v[72:73], v[74:75], v[72:73]
	v_pk_mul_f32 v[74:75], v[72:73], v[70:71]
	v_pk_fma_f32 v[72:73], v[72:73], v[70:71], v[70:71] neg_lo:[1,0,0] neg_hi:[1,0,0]
	s_nop 0
	v_cndmask_b32_e32 v71, v73, v75, vcc
	v_cmp_gt_f32_e32 vcc, 0, v70
	s_nop 1
	v_cndmask_b32_e32 v70, v72, v74, vcc
	v_rcp_f32_e32 v72, v67
	v_mul_f32_e32 v67, v68, v68
	v_mul_f32_e32 v67, 0xbf38aa3b, v67
	v_exp_f32_e32 v74, v67
	v_fma_f32 v67, |v69|, s92, 1.0
	v_rcp_f32_e32 v73, v67
	v_mul_f32_e32 v67, v69, v69
	v_mul_f32_e32 v67, 0xbf38aa3b, v67
	v_exp_f32_e32 v75, v67
	v_pk_fma_f32 v[76:77], v[72:73], s[10:11], v[18:19] op_sel_hi:[1,0,0]
	v_cmp_gt_f32_e32 vcc, 0, v69
	v_pk_fma_f32 v[76:77], v[72:73], v[76:77], s[14:15] op_sel_hi:[1,1,0]
	s_nop 0
	v_pk_fma_f32 v[76:77], v[72:73], v[76:77], s[16:17] op_sel_hi:[1,1,0]
	s_nop 0
	v_pk_fma_f32 v[76:77], v[72:73], v[76:77], s[18:19] op_sel_hi:[1,1,0]
	v_pk_mul_f32 v[72:73], v[72:73], v[76:77]
	v_pk_mul_f32 v[72:73], v[74:75], v[72:73]
	v_pk_mul_f32 v[74:75], v[72:73], v[68:69]
	v_pk_fma_f32 v[72:73], v[72:73], v[68:69], v[68:69] neg_lo:[1,0,0] neg_hi:[1,0,0]
	s_nop 0
	v_cndmask_b32_e32 v69, v73, v75, vcc
	v_cmp_gt_f32_e32 vcc, 0, v68
	v_lshlrev_b32_e32 v73, 16, v64
	s_nop 0
	v_cndmask_b32_e32 v68, v72, v74, vcc
	s_waitcnt vmcnt(0)
	v_lshlrev_b32_e32 v72, 16, v65
	v_fma_f32 v64, |v72|, s92, 1.0
	v_fma_f32 v65, |v73|, s92, 1.0
	v_rcp_f32_e32 v64, v64
	v_rcp_f32_e32 v65, v65
	v_mul_f32_e32 v67, v72, v72
	v_mul_f32_e32 v67, 0xbf38aa3b, v67
	v_exp_f32_e32 v74, v67
	v_mul_f32_e32 v67, v73, v73
	v_pk_fma_f32 v[76:77], v[64:65], s[10:11], v[18:19] op_sel_hi:[1,0,0]
	v_mul_f32_e32 v67, 0xbf38aa3b, v67
	v_pk_fma_f32 v[76:77], v[64:65], v[76:77], s[14:15] op_sel_hi:[1,1,0]
	v_exp_f32_e32 v75, v67
	v_pk_fma_f32 v[76:77], v[64:65], v[76:77], s[16:17] op_sel_hi:[1,1,0]
	v_cmp_gt_f32_e32 vcc, 0, v73
	v_pk_fma_f32 v[76:77], v[64:65], v[76:77], s[18:19] op_sel_hi:[1,1,0]
	s_nop 0
	v_pk_mul_f32 v[64:65], v[64:65], v[76:77]
	v_pk_mul_f32 v[64:65], v[74:75], v[64:65]
	v_pk_mul_f32 v[74:75], v[64:65], v[72:73]
	v_pk_fma_f32 v[64:65], v[64:65], v[72:73], v[72:73] neg_lo:[1,0,0] neg_hi:[1,0,0]
	v_lshlrev_b32_e32 v73, 16, v58
	v_cndmask_b32_e32 v65, v65, v75, vcc
	v_cmp_gt_f32_e32 vcc, 0, v72
	v_lshlrev_b32_e32 v72, 16, v59
	v_mul_f32_e32 v59, v72, v72
	v_mul_f32_e32 v59, 0xbf38aa3b, v59
	v_cndmask_b32_e32 v64, v64, v74, vcc
	v_fma_f32 v58, |v72|, s92, 1.0
	v_exp_f32_e32 v74, v59
	v_fma_f32 v59, |v73|, s92, 1.0
	v_rcp_f32_e32 v58, v58
	v_rcp_f32_e32 v59, v59
	v_mul_f32_e32 v67, v73, v73
	v_mul_f32_e32 v67, 0xbf38aa3b, v67
	v_exp_f32_e32 v75, v67
	v_pk_fma_f32 v[18:19], v[58:59], s[10:11], v[18:19] op_sel_hi:[1,0,0]
	v_cmp_gt_f32_e32 vcc, 0, v73
	v_pk_fma_f32 v[18:19], v[58:59], v[18:19], s[14:15] op_sel_hi:[1,1,0]
	v_mov_b32_e32 v67, v131
	v_pk_fma_f32 v[18:19], v[58:59], v[18:19], s[6:7] op_sel_hi:[1,1,0]
	s_nop 0
	v_pk_fma_f32 v[18:19], v[58:59], v[18:19], s[8:9] op_sel_hi:[1,1,0]
	v_readlane_b32 s9, v253, 54
	v_pk_mul_f32 v[18:19], v[58:59], v[18:19]
	s_nop 0
	v_pk_mul_f32 v[18:19], v[74:75], v[18:19]
	v_mov_b32_e32 v74, v57
	v_pk_mul_f32 v[58:59], v[18:19], v[72:73]
	v_pk_fma_f32 v[18:19], v[18:19], v[72:73], v[72:73] neg_lo:[1,0,0] neg_hi:[1,0,0]
	v_mov_b32_e32 v75, v65
	v_cndmask_b32_e32 v73, v19, v59, vcc
	v_cmp_gt_f32_e32 vcc, 0, v72
	v_mov_b32_e32 v19, v70
	v_mov_b32_e32 v59, v64
	v_cndmask_b32_e32 v72, v18, v58, vcc
	v_mov_b32_e32 v18, v54
	v_mov_b32_e32 v58, v56
	v_pk_add_f32 v[18:19], v[18:19], v[58:59]
	v_mov_b32_e32 v58, v55
	v_add_f32_e32 v18, v18, v19
	v_mov_b32_e32 v59, v71
	s_nop 0
	v_add_f32_dpp v18, v18, v18 quad_perm:[1,0,3,2] row_mask:0xf bank_mask:0xf bound_ctrl:1
	v_pk_add_f32 v[58:59], v[58:59], v[74:75]
	v_mov_b32_e32 v74, v63
	v_add_f32_dpp v18, v18, v18 quad_perm:[2,3,0,1] row_mask:0xf bank_mask:0xf bound_ctrl:1
	v_mov_b32_e32 v75, v73
	s_nop 0
	v_add_f32_dpp v18, v18, v18 row_half_mirror row_mask:0xf bank_mask:0xf bound_ctrl:1
	s_nop 1
	v_add_f32_dpp v18, v18, v18 row_mirror row_mask:0xf bank_mask:0xf bound_ctrl:1
	s_nop 1
	v_add_f32_dpp v18, v18, v18 row_bcast:15 row_mask:0xa bank_mask:0xf
	s_nop 1
	v_add_f32_dpp v18, v18, v18 row_bcast:31 row_mask:0xc bank_mask:0xf
	v_add_f32_e32 v19, v58, v59
	v_readlane_b32 s6, v18, 63
	s_nop 0
	v_add_f32_dpp v19, v19, v19 quad_perm:[1,0,3,2] row_mask:0xf bank_mask:0xf bound_ctrl:1
	s_xor_b32 s6, s6, 0x80000000
	s_nop 0
	v_add_f32_dpp v19, v19, v19 quad_perm:[2,3,0,1] row_mask:0xf bank_mask:0xf bound_ctrl:1
	s_nop 1
	v_add_f32_dpp v19, v19, v19 row_half_mirror row_mask:0xf bank_mask:0xf bound_ctrl:1
	s_nop 1
	v_add_f32_dpp v19, v19, v19 row_mirror row_mask:0xf bank_mask:0xf bound_ctrl:1
	s_nop 1
	v_add_f32_dpp v19, v19, v19 row_bcast:15 row_mask:0xa bank_mask:0xf
	s_nop 1
	v_add_f32_dpp v19, v19, v19 row_bcast:31 row_mask:0xc bank_mask:0xf
	s_nop 0
	v_readlane_b32 s7, v19, 63
	s_xor_b32 s7, s7, 0x80000000
	s_nop 0
	v_pk_fma_f32 v[58:59], s[6:7], v[20:21], v[54:55] op_sel_hi:[1,0,1]
	v_pk_fma_f32 v[54:55], s[6:7], v[20:21], v[70:71] op_sel_hi:[1,0,1]
	v_pk_fma_f32 v[18:19], s[6:7], v[20:21], v[64:65] op_sel_hi:[1,0,1]
	v_mov_b32_e32 v64, v60
	v_mov_b32_e32 v65, v68
	v_mov_b32_e32 v70, v62
	v_mov_b32_e32 v71, v72
	v_pk_add_f32 v[64:65], v[64:65], v[70:71]
	v_mov_b32_e32 v70, v61
	v_add_f32_e32 v64, v64, v65
	v_mov_b32_e32 v71, v69
	s_nop 0
	v_add_f32_dpp v64, v64, v64 quad_perm:[1,0,3,2] row_mask:0xf bank_mask:0xf bound_ctrl:1
	v_pk_add_f32 v[70:71], v[70:71], v[74:75]
	v_pk_fma_f32 v[56:57], s[6:7], v[20:21], v[56:57] op_sel_hi:[1,0,1]
	v_add_f32_dpp v64, v64, v64 quad_perm:[2,3,0,1] row_mask:0xf bank_mask:0xf bound_ctrl:1
	s_nop 1
	v_add_f32_dpp v64, v64, v64 row_half_mirror row_mask:0xf bank_mask:0xf bound_ctrl:1
	s_nop 1
	v_add_f32_dpp v64, v64, v64 row_mirror row_mask:0xf bank_mask:0xf bound_ctrl:1
	s_nop 1
	v_add_f32_dpp v64, v64, v64 row_bcast:15 row_mask:0xa bank_mask:0xf
	s_nop 1
	v_add_f32_dpp v64, v64, v64 row_bcast:31 row_mask:0xc bank_mask:0xf
	v_add_f32_e32 v65, v70, v71
	v_readlane_b32 s6, v64, 63
	s_xor_b32 s6, s6, 0x80000000
	v_add_f32_dpp v65, v65, v65 quad_perm:[1,0,3,2] row_mask:0xf bank_mask:0xf bound_ctrl:1
	v_mov_b32_e32 v70, v14
	v_mov_b32_e32 v71, v10
	v_add_f32_dpp v65, v65, v65 quad_perm:[2,3,0,1] row_mask:0xf bank_mask:0xf bound_ctrl:1
	v_pk_mul_f32 v[70:71], v[70:71], v[70:71]
	s_nop 0
	v_add_f32_dpp v65, v65, v65 row_half_mirror row_mask:0xf bank_mask:0xf bound_ctrl:1
	s_nop 1
	v_add_f32_dpp v65, v65, v65 row_mirror row_mask:0xf bank_mask:0xf bound_ctrl:1
	s_nop 1
	v_mov_b32_dpp v67, v65 row_bcast:15 row_mask:0xa bank_mask:0xf
	v_add_f32_e32 v65, v65, v67
	s_nop 1
	v_add_f32_dpp v65, v65, v65 row_bcast:31 row_mask:0xc bank_mask:0xf
	s_nop 0
	v_readlane_b32 s7, v65, 63
	s_xor_b32 s7, s7, 0x80000000
	s_nop 0
	v_pk_fma_f32 v[64:65], s[6:7], v[20:21], v[60:61] op_sel_hi:[1,0,1]
	v_pk_fma_f32 v[60:61], s[6:7], v[20:21], v[68:69] op_sel_hi:[1,0,1]
	v_mov_b32_e32 v68, v16
	v_mov_b32_e32 v69, v12
	v_pk_fma_f32 v[68:69], v[68:69], v[68:69], v[70:71]
	v_pk_fma_f32 v[62:63], s[6:7], v[20:21], v[62:63] op_sel_hi:[1,0,1]
	v_add_f32_e32 v68, v68, v69
	v_pk_fma_f32 v[20:21], s[6:7], v[20:21], v[72:73] op_sel_hi:[1,0,1]
	s_nop 0
	v_add_f32_dpp v68, v68, v68 quad_perm:[1,0,3,2] row_mask:0xf bank_mask:0xf bound_ctrl:1
	s_lshl_b32 s6, s34, 5
	s_add_i32 s7, s6, 0
	v_add_f32_dpp v68, v68, v68 quad_perm:[2,3,0,1] row_mask:0xf bank_mask:0xf bound_ctrl:1
	v_mov_b32_e32 v70, v15
	v_mov_b32_e32 v71, v11
	v_add_f32_dpp v68, v68, v68 row_half_mirror row_mask:0xf bank_mask:0xf bound_ctrl:1
	v_mov_b32_e32 v67, s7
	v_pk_mul_f32 v[70:71], v[70:71], v[70:71]
	v_add_f32_dpp v68, v68, v68 row_mirror row_mask:0xf bank_mask:0xf bound_ctrl:1
	s_nop 1
	v_add_f32_dpp v68, v68, v68 row_bcast:15 row_mask:0xa bank_mask:0xf
	s_nop 1
	v_add_f32_dpp v68, v68, v68 row_bcast:31 row_mask:0xc bank_mask:0xf
	v_mov_b32_e32 v69, v13
	v_readlane_b32 s7, v68, 63
	v_mov_b32_e32 v68, v17
	v_pk_fma_f32 v[68:69], v[68:69], v[68:69], v[70:71]
	v_mov_b32_e32 v70, v8
	v_add_f32_e32 v68, v68, v69
	v_mov_b32_e32 v71, v2
	s_nop 0
	v_add_f32_dpp v68, v68, v68 quad_perm:[1,0,3,2] row_mask:0xf bank_mask:0xf bound_ctrl:1
	v_fma_f32 v73, s7, v235, v225
	v_pk_mul_f32 v[70:71], v[70:71], v[70:71]
	v_add_f32_dpp v68, v68, v68 quad_perm:[2,3,0,1] row_mask:0xf bank_mask:0xf bound_ctrl:1
	v_rsq_f32_e32 v84, v73
	s_nop 0
	v_add_f32_dpp v68, v68, v68 row_half_mirror row_mask:0xf bank_mask:0xf bound_ctrl:1
	s_nop 1
	v_add_f32_dpp v68, v68, v68 row_mirror row_mask:0xf bank_mask:0xf bound_ctrl:1
	s_nop 1
	v_add_f32_dpp v68, v68, v68 row_bcast:15 row_mask:0xa bank_mask:0xf
	s_nop 1
	v_add_f32_dpp v68, v68, v68 row_bcast:31 row_mask:0xc bank_mask:0xf
	v_mov_b32_e32 v69, v6
	v_readlane_b32 s7, v68, 63
	v_mov_b32_e32 v68, v4
	v_pk_fma_f32 v[68:69], v[68:69], v[68:69], v[70:71]
	v_mov_b32_e32 v70, v9
	v_add_f32_e32 v68, v68, v69
	v_mov_b32_e32 v71, v3
	s_nop 0
	v_add_f32_dpp v68, v68, v68 quad_perm:[1,0,3,2] row_mask:0xf bank_mask:0xf bound_ctrl:1
	v_fma_f32 v75, s7, v235, v225
	v_pk_mul_f32 v[70:71], v[70:71], v[70:71]
	v_add_f32_dpp v68, v68, v68 quad_perm:[2,3,0,1] row_mask:0xf bank_mask:0xf bound_ctrl:1
	v_rsq_f32_e32 v85, v75
	s_nop 0
	v_add_f32_dpp v68, v68, v68 row_half_mirror row_mask:0xf bank_mask:0xf bound_ctrl:1
	v_pk_mul_f32 v[16:17], v[16:17], v[84:85]
	s_nop 0
	v_add_f32_dpp v68, v68, v68 row_mirror row_mask:0xf bank_mask:0xf bound_ctrl:1
	s_nop 1
	v_add_f32_dpp v68, v68, v68 row_bcast:15 row_mask:0xa bank_mask:0xf
	s_nop 1
	v_add_f32_dpp v68, v68, v68 row_bcast:31 row_mask:0xc bank_mask:0xf
	v_mov_b32_e32 v69, v7
	v_readlane_b32 s7, v68, 63
	v_mov_b32_e32 v68, v5
	v_pk_fma_f32 v[68:69], v[68:69], v[68:69], v[70:71]
	v_mov_b32_e32 v70, v34
	v_add_f32_e32 v68, v68, v69
	v_mov_b32_e32 v71, v30
	s_nop 0
	v_add_f32_dpp v68, v68, v68 quad_perm:[1,0,3,2] row_mask:0xf bank_mask:0xf bound_ctrl:1
	v_fma_f32 v77, s7, v235, v225
	v_pk_mul_f32 v[70:71], v[70:71], v[70:71]
	v_add_f32_dpp v68, v68, v68 quad_perm:[2,3,0,1] row_mask:0xf bank_mask:0xf bound_ctrl:1
	v_rsq_f32_e32 v86, v77
	s_nop 0
	v_add_f32_dpp v68, v68, v68 row_half_mirror row_mask:0xf bank_mask:0xf bound_ctrl:1
	s_nop 1
	v_add_f32_dpp v68, v68, v68 row_mirror row_mask:0xf bank_mask:0xf bound_ctrl:1
	s_nop 1
	v_add_f32_dpp v68, v68, v68 row_bcast:15 row_mask:0xa bank_mask:0xf
	s_nop 1
	v_add_f32_dpp v68, v68, v68 row_bcast:31 row_mask:0xc bank_mask:0xf
	v_mov_b32_e32 v69, v32
	v_readlane_b32 s7, v68, 63
	v_mov_b32_e32 v68, v36
	v_pk_fma_f32 v[68:69], v[68:69], v[68:69], v[70:71]
	v_mov_b32_e32 v70, v35
	v_add_f32_e32 v68, v68, v69
	v_mov_b32_e32 v71, v31
	s_nop 0
	v_add_f32_dpp v68, v68, v68 quad_perm:[1,0,3,2] row_mask:0xf bank_mask:0xf bound_ctrl:1
	v_fma_f32 v79, s7, v235, v225
	v_pk_mul_f32 v[70:71], v[70:71], v[70:71]
	v_add_f32_dpp v68, v68, v68 quad_perm:[2,3,0,1] row_mask:0xf bank_mask:0xf bound_ctrl:1
	v_rsq_f32_e32 v87, v79
	s_nop 0
	v_add_f32_dpp v68, v68, v68 row_half_mirror row_mask:0xf bank_mask:0xf bound_ctrl:1
	v_pk_mul_f32 v[4:5], v[4:5], v[86:87]
	s_nop 0
	v_add_f32_dpp v68, v68, v68 row_mirror row_mask:0xf bank_mask:0xf bound_ctrl:1
	v_pk_mul_f32 v[2:3], v[2:3], v[86:87]
	v_pk_mul_f32 v[8:9], v[8:9], v[86:87]
	v_add_f32_dpp v68, v68, v68 row_bcast:15 row_mask:0xa bank_mask:0xf
	v_pk_mul_f32 v[6:7], v[6:7], v[86:87]
	s_nop 0
	v_add_f32_dpp v68, v68, v68 row_bcast:31 row_mask:0xc bank_mask:0xf
	v_mov_b32_e32 v69, v33
	v_readlane_b32 s7, v68, 63
	v_mov_b32_e32 v68, v37
	v_pk_fma_f32 v[68:69], v[68:69], v[68:69], v[70:71]
	v_mov_b32_e32 v70, v26
	v_add_f32_e32 v68, v68, v69
	v_mov_b32_e32 v71, v22
	s_nop 0
	v_add_f32_dpp v68, v68, v68 quad_perm:[1,0,3,2] row_mask:0xf bank_mask:0xf bound_ctrl:1
	v_fma_f32 v81, s7, v235, v225
	v_pk_mul_f32 v[70:71], v[70:71], v[70:71]
	v_add_f32_dpp v68, v68, v68 quad_perm:[2,3,0,1] row_mask:0xf bank_mask:0xf bound_ctrl:1
	s_nop 1
	v_add_f32_dpp v68, v68, v68 row_half_mirror row_mask:0xf bank_mask:0xf bound_ctrl:1
	s_nop 1
	v_add_f32_dpp v68, v68, v68 row_mirror row_mask:0xf bank_mask:0xf bound_ctrl:1
	s_nop 1
	v_add_f32_dpp v68, v68, v68 row_bcast:15 row_mask:0xa bank_mask:0xf
	s_nop 1
	v_add_f32_dpp v68, v68, v68 row_bcast:31 row_mask:0xc bank_mask:0xf
	v_mov_b32_e32 v69, v24
	v_readlane_b32 s7, v68, 63
	v_mov_b32_e32 v68, v28
	v_pk_fma_f32 v[68:69], v[68:69], v[68:69], v[70:71]
	v_mov_b32_e32 v70, v27
	v_add_f32_e32 v68, v68, v69
	v_mov_b32_e32 v71, v23
	s_nop 0
	v_add_f32_dpp v68, v68, v68 quad_perm:[1,0,3,2] row_mask:0xf bank_mask:0xf bound_ctrl:1
	v_fma_f32 v83, s7, v235, v225
	v_pk_mul_f32 v[70:71], v[70:71], v[70:71]
	v_add_f32_dpp v68, v68, v68 quad_perm:[2,3,0,1] row_mask:0xf bank_mask:0xf bound_ctrl:1
	s_nop 1
	v_add_f32_dpp v68, v68, v68 row_half_mirror row_mask:0xf bank_mask:0xf bound_ctrl:1
	s_nop 1
	v_add_f32_dpp v68, v68, v68 row_mirror row_mask:0xf bank_mask:0xf bound_ctrl:1
	s_nop 1
	v_add_f32_dpp v68, v68, v68 row_bcast:15 row_mask:0xa bank_mask:0xf
	s_nop 1
	v_add_f32_dpp v68, v68, v68 row_bcast:31 row_mask:0xc bank_mask:0xf
	v_mov_b32_e32 v69, v25
	v_readlane_b32 s7, v68, 63
	v_mov_b32_e32 v68, v29
	v_pk_fma_f32 v[68:69], v[68:69], v[68:69], v[70:71]
	v_mov_b32_e32 v70, v50
	v_add_f32_e32 v68, v68, v69
	v_mov_b32_e32 v71, v46
	s_nop 0
	v_add_f32_dpp v68, v68, v68 quad_perm:[1,0,3,2] row_mask:0xf bank_mask:0xf bound_ctrl:1
	v_fma_f32 v90, s7, v235, v225
	v_pk_mul_f32 v[70:71], v[70:71], v[70:71]
	v_add_f32_dpp v68, v68, v68 quad_perm:[2,3,0,1] row_mask:0xf bank_mask:0xf bound_ctrl:1
	s_nop 1
	v_add_f32_dpp v68, v68, v68 row_half_mirror row_mask:0xf bank_mask:0xf bound_ctrl:1
	s_nop 1
	v_add_f32_dpp v68, v68, v68 row_mirror row_mask:0xf bank_mask:0xf bound_ctrl:1
	s_nop 1
	v_add_f32_dpp v68, v68, v68 row_bcast:15 row_mask:0xa bank_mask:0xf
	s_nop 1
	v_add_f32_dpp v68, v68, v68 row_bcast:31 row_mask:0xc bank_mask:0xf
	v_mov_b32_e32 v69, v48
	v_readlane_b32 s7, v68, 63
	v_mov_b32_e32 v68, v52
	v_pk_fma_f32 v[68:69], v[68:69], v[68:69], v[70:71]
	v_mov_b32_e32 v70, v51
	v_add_f32_e32 v68, v68, v69
	v_mov_b32_e32 v71, v47
	s_nop 0
	v_add_f32_dpp v68, v68, v68 quad_perm:[1,0,3,2] row_mask:0xf bank_mask:0xf bound_ctrl:1
	v_fma_f32 v91, s7, v235, v225
	v_pk_mul_f32 v[70:71], v[70:71], v[70:71]
	v_add_f32_dpp v68, v68, v68 quad_perm:[2,3,0,1] row_mask:0xf bank_mask:0xf bound_ctrl:1
	s_nop 1
	v_add_f32_dpp v68, v68, v68 row_half_mirror row_mask:0xf bank_mask:0xf bound_ctrl:1
	s_nop 1
	v_add_f32_dpp v68, v68, v68 row_mirror row_mask:0xf bank_mask:0xf bound_ctrl:1
	s_nop 1
	v_add_f32_dpp v68, v68, v68 row_bcast:15 row_mask:0xa bank_mask:0xf
	s_nop 1
	v_add_f32_dpp v68, v68, v68 row_bcast:31 row_mask:0xc bank_mask:0xf
	v_mov_b32_e32 v69, v49
	v_readlane_b32 s7, v68, 63
	v_mov_b32_e32 v68, v53
	v_pk_fma_f32 v[68:69], v[68:69], v[68:69], v[70:71]
	v_mov_b32_e32 v70, v44
	v_add_f32_e32 v68, v68, v69
	v_mov_b32_e32 v71, v38
	s_nop 0
	v_add_f32_dpp v68, v68, v68 quad_perm:[1,0,3,2] row_mask:0xf bank_mask:0xf bound_ctrl:1
	v_fma_f32 v92, s7, v235, v225
	v_pk_mul_f32 v[70:71], v[70:71], v[70:71]
	v_add_f32_dpp v68, v68, v68 quad_perm:[2,3,0,1] row_mask:0xf bank_mask:0xf bound_ctrl:1
	s_nop 1
	v_add_f32_dpp v68, v68, v68 row_half_mirror row_mask:0xf bank_mask:0xf bound_ctrl:1
	s_nop 1
	v_add_f32_dpp v68, v68, v68 row_mirror row_mask:0xf bank_mask:0xf bound_ctrl:1
	s_nop 1
	v_add_f32_dpp v68, v68, v68 row_bcast:15 row_mask:0xa bank_mask:0xf
	s_nop 1
	v_add_f32_dpp v68, v68, v68 row_bcast:31 row_mask:0xc bank_mask:0xf
	v_mov_b32_e32 v69, v42
	v_readlane_b32 s7, v68, 63
	v_mov_b32_e32 v68, v40
	v_pk_fma_f32 v[68:69], v[68:69], v[68:69], v[70:71]
	v_mov_b32_e32 v70, v45
	v_add_f32_e32 v68, v68, v69
	v_mov_b32_e32 v71, v39
	s_nop 0
	v_add_f32_dpp v68, v68, v68 quad_perm:[1,0,3,2] row_mask:0xf bank_mask:0xf bound_ctrl:1
	v_fma_f32 v93, s7, v235, v225
	v_pk_mul_f32 v[70:71], v[70:71], v[70:71]
	v_add_f32_dpp v68, v68, v68 quad_perm:[2,3,0,1] row_mask:0xf bank_mask:0xf bound_ctrl:1
	s_nop 1
	v_add_f32_dpp v68, v68, v68 row_half_mirror row_mask:0xf bank_mask:0xf bound_ctrl:1
	s_nop 1
	v_add_f32_dpp v68, v68, v68 row_mirror row_mask:0xf bank_mask:0xf bound_ctrl:1
	s_nop 1
	v_add_f32_dpp v68, v68, v68 row_bcast:15 row_mask:0xa bank_mask:0xf
	s_nop 1
	v_add_f32_dpp v68, v68, v68 row_bcast:31 row_mask:0xc bank_mask:0xf
	v_mov_b32_e32 v69, v43
	v_readlane_b32 s7, v68, 63
	v_mov_b32_e32 v68, v41
	v_pk_fma_f32 v[68:69], v[68:69], v[68:69], v[70:71]
	v_mov_b32_e32 v70, v62
	v_add_f32_e32 v68, v68, v69
	v_mov_b32_e32 v71, v20
	s_nop 0
	v_add_f32_dpp v68, v68, v68 quad_perm:[1,0,3,2] row_mask:0xf bank_mask:0xf bound_ctrl:1
	v_fma_f32 v94, s7, v235, v225
	v_pk_mul_f32 v[70:71], v[70:71], v[70:71]
	v_add_f32_dpp v68, v68, v68 quad_perm:[2,3,0,1] row_mask:0xf bank_mask:0xf bound_ctrl:1
	s_nop 1
	v_add_f32_dpp v68, v68, v68 row_half_mirror row_mask:0xf bank_mask:0xf bound_ctrl:1
	s_nop 1
	v_add_f32_dpp v68, v68, v68 row_mirror row_mask:0xf bank_mask:0xf bound_ctrl:1
	s_nop 1
	v_add_f32_dpp v68, v68, v68 row_bcast:15 row_mask:0xa bank_mask:0xf
	s_nop 1
	v_add_f32_dpp v68, v68, v68 row_bcast:31 row_mask:0xc bank_mask:0xf
	v_mov_b32_e32 v69, v60
	v_readlane_b32 s7, v68, 63
	v_mov_b32_e32 v68, v64
	v_pk_fma_f32 v[68:69], v[68:69], v[68:69], v[70:71]
	v_mov_b32_e32 v70, v63
	v_add_f32_e32 v68, v68, v69
	v_mov_b32_e32 v71, v21
	s_nop 0
	v_add_f32_dpp v68, v68, v68 quad_perm:[1,0,3,2] row_mask:0xf bank_mask:0xf bound_ctrl:1
	v_fma_f32 v95, s7, v235, v225
	v_pk_mul_f32 v[70:71], v[70:71], v[70:71]
	v_add_f32_dpp v68, v68, v68 quad_perm:[2,3,0,1] row_mask:0xf bank_mask:0xf bound_ctrl:1
	s_nop 1
	v_add_f32_dpp v68, v68, v68 row_half_mirror row_mask:0xf bank_mask:0xf bound_ctrl:1
	s_nop 1
	v_add_f32_dpp v68, v68, v68 row_mirror row_mask:0xf bank_mask:0xf bound_ctrl:1
	s_nop 1
	v_add_f32_dpp v68, v68, v68 row_bcast:15 row_mask:0xa bank_mask:0xf
	s_nop 1
	v_add_f32_dpp v68, v68, v68 row_bcast:31 row_mask:0xc bank_mask:0xf
	v_mov_b32_e32 v69, v61
	v_readlane_b32 s7, v68, 63
	v_mov_b32_e32 v68, v65
	v_pk_fma_f32 v[68:69], v[68:69], v[68:69], v[70:71]
	v_mov_b32_e32 v70, v56
	v_add_f32_e32 v68, v68, v69
	v_mov_b32_e32 v71, v18
	s_nop 0
	v_add_f32_dpp v68, v68, v68 quad_perm:[1,0,3,2] row_mask:0xf bank_mask:0xf bound_ctrl:1
	v_fma_f32 v96, s7, v235, v225
	v_pk_mul_f32 v[70:71], v[70:71], v[70:71]
	v_add_f32_dpp v68, v68, v68 quad_perm:[2,3,0,1] row_mask:0xf bank_mask:0xf bound_ctrl:1
	s_nop 1
	v_add_f32_dpp v68, v68, v68 row_half_mirror row_mask:0xf bank_mask:0xf bound_ctrl:1
	s_nop 1
	v_add_f32_dpp v68, v68, v68 row_mirror row_mask:0xf bank_mask:0xf bound_ctrl:1
	s_nop 1
	v_add_f32_dpp v68, v68, v68 row_bcast:15 row_mask:0xa bank_mask:0xf
	s_nop 1
	v_add_f32_dpp v68, v68, v68 row_bcast:31 row_mask:0xc bank_mask:0xf
	v_mov_b32_e32 v69, v54
	v_readlane_b32 s7, v68, 63
	v_mov_b32_e32 v68, v58
	v_pk_fma_f32 v[68:69], v[68:69], v[68:69], v[70:71]
	v_mov_b32_e32 v70, v57
	v_add_f32_e32 v68, v68, v69
	v_mov_b32_e32 v71, v19
	s_nop 0
	v_add_f32_dpp v68, v68, v68 quad_perm:[1,0,3,2] row_mask:0xf bank_mask:0xf bound_ctrl:1
	v_fma_f32 v97, s7, v235, v225
	v_pk_mul_f32 v[70:71], v[70:71], v[70:71]
	v_add_f32_dpp v68, v68, v68 quad_perm:[2,3,0,1] row_mask:0xf bank_mask:0xf bound_ctrl:1
	s_nop 1
	v_add_f32_dpp v68, v68, v68 row_half_mirror row_mask:0xf bank_mask:0xf bound_ctrl:1
	s_nop 1
	v_add_f32_dpp v68, v68, v68 row_mirror row_mask:0xf bank_mask:0xf bound_ctrl:1
	s_nop 1
	v_add_f32_dpp v68, v68, v68 row_bcast:15 row_mask:0xa bank_mask:0xf
	s_nop 1
	v_add_f32_dpp v68, v68, v68 row_bcast:31 row_mask:0xc bank_mask:0xf
	v_mov_b32_e32 v69, v55
	v_readlane_b32 s7, v68, 63
	v_mov_b32_e32 v68, v59
	v_pk_fma_f32 v[68:69], v[68:69], v[68:69], v[70:71]
	v_fma_f32 v98, s7, v235, v225
	v_add_f32_e32 v68, v68, v69
	s_nop 0
	s_nop 0
	v_add_f32_dpp v68, v68, v68 quad_perm:[1,0,3,2] row_mask:0xf bank_mask:0xf bound_ctrl:1
	s_nop 1
	v_add_f32_dpp v68, v68, v68 quad_perm:[2,3,0,1] row_mask:0xf bank_mask:0xf bound_ctrl:1
	s_nop 1
	v_add_f32_dpp v68, v68, v68 row_half_mirror row_mask:0xf bank_mask:0xf bound_ctrl:1
	s_nop 1
	v_add_f32_dpp v68, v68, v68 row_mirror row_mask:0xf bank_mask:0xf bound_ctrl:1
	s_nop 1
	v_add_f32_dpp v68, v68, v68 row_bcast:15 row_mask:0xa bank_mask:0xf
	s_nop 1
	v_add_f32_dpp v68, v68, v68 row_bcast:31 row_mask:0xc bank_mask:0xf
	s_nop 0
	v_readlane_b32 s7, v68, 63
	v_add_u32_e32 v68, s66, v1
	v_ashrrev_i32_e32 v69, 31, v68
	s_waitcnt lgkmcnt(0)
	v_lshl_add_u64 v[68:69], v[68:69], 2, s[42:43]
	global_load_dword v88, v[68:69], off
	v_or_b32_e32 v68, s84, v66
	v_ashrrev_i32_e32 v69, 31, v68
	v_lshlrev_b64 v[68:69], 2, v[68:69]
	v_lshl_add_u64 v[70:71], s[52:53], 0, v[68:69]
	v_lshl_add_u64 v[68:69], s[54:55], 0, v[68:69]
	global_load_dword v72, v[68:69], off
	global_load_dword v74, v[70:71], off
	global_load_dword v76, v[70:71], off offset:256
	global_load_dword v78, v[68:69], off offset:256
	global_load_dword v80, v[68:69], off offset:512
	global_load_dword v82, v[70:71], off offset:512
	s_nop 0
	global_load_dword v70, v[70:71], off offset:768
	s_nop 0
	global_load_dword v68, v[68:69], off offset:768
	v_lshl_add_u32 v69, v1, 2, s9
	v_fma_f32 v99, s7, v235, v225
	s_add_i32 s7, s5, s11
	s_lshl_b32 s5, s5, 9
	s_add_u32 s34, s78, 0x3420000
	s_mul_hi_i32 s8, s7, 0x5000
	s_mulk_i32 s7, 0x5000
	s_addc_u32 s64, s79, 0
	s_add_u32 s28, s34, s7
	s_addc_u32 s29, s64, s8
	s_movk_i32 s8, 0x110
	v_mad_u32_u24 v67, v66, s8, v67
	s_movk_i32 s7, 0x2000
	s_add_i32 s5, s9, s5
	s_waitcnt vmcnt(8)
	ds_write_b32 v69, v88
	s_waitcnt vmcnt(6)
	v_pk_fma_f32 v[88:89], v[74:75], v[4:5], v[72:73] op_sel_hi:[0,1,0]
	v_pk_mul_f32 v[4:5], v[14:15], v[84:85]
	v_pk_fma_f32 v[16:17], v[74:75], v[16:17], v[72:73] op_sel_hi:[0,1,0]
	s_waitcnt vmcnt(4)
	v_pk_fma_f32 v[14:15], v[76:77], v[4:5], v[78:79] op_sel_hi:[0,1,0]
	v_pk_mul_f32 v[4:5], v[12:13], v[84:85]
	s_waitcnt vmcnt(0)
	v_pk_fma_f32 v[86:87], v[70:71], v[2:3], v[68:69] op_sel_hi:[0,1,0]
	v_pk_fma_f32 v[12:13], v[82:83], v[4:5], v[80:81] op_sel_hi:[0,1,0]
	v_pk_mul_f32 v[4:5], v[10:11], v[84:85]
	v_rsq_f32_e32 v10, v81
	v_rsq_f32_e32 v11, v83
	v_rsq_f32_e32 v84, v90
	v_rsq_f32_e32 v85, v91
	v_pk_fma_f32 v[90:91], v[70:71], v[4:5], v[68:69] op_sel_hi:[0,1,0]
	v_pk_mul_f32 v[2:3], v[36:37], v[10:11]
	v_pk_fma_f32 v[8:9], v[76:77], v[8:9], v[78:79] op_sel_hi:[0,1,0]
	v_pk_mul_f32 v[4:5], v[28:29], v[84:85]
	v_pk_fma_f32 v[2:3], v[74:75], v[2:3], v[72:73] op_sel_hi:[0,1,0]
	v_pk_fma_f32 v[4:5], v[74:75], v[4:5], v[72:73] op_sel_hi:[0,1,0]
	v_cvt_pk_bf16_f32 v5, v4, v5
	v_cvt_pk_bf16_f32 v4, v2, v3
	v_cvt_pk_bf16_f32 v3, v88, v89
	v_cvt_pk_bf16_f32 v2, v16, v17
	ds_write_b128 v67, v[2:5]
	v_pk_mul_f32 v[2:3], v[34:35], v[10:11]
	v_pk_mul_f32 v[4:5], v[26:27], v[84:85]
	v_pk_fma_f32 v[2:3], v[76:77], v[2:3], v[78:79] op_sel_hi:[0,1,0]
	v_pk_fma_f32 v[4:5], v[76:77], v[4:5], v[78:79] op_sel_hi:[0,1,0]
	v_cvt_pk_bf16_f32 v5, v4, v5
	v_cvt_pk_bf16_f32 v4, v2, v3
	v_cvt_pk_bf16_f32 v3, v8, v9
	v_cvt_pk_bf16_f32 v2, v14, v15
	ds_write_b128 v67, v[2:5] offset:17408
	v_pk_mul_f32 v[2:3], v[32:33], v[10:11]
	v_pk_mul_f32 v[4:5], v[24:25], v[84:85]
	v_pk_fma_f32 v[6:7], v[82:83], v[6:7], v[80:81] op_sel_hi:[0,1,0]
	v_pk_fma_f32 v[4:5], v[82:83], v[4:5], v[80:81] op_sel_hi:[0,1,0]
	v_pk_fma_f32 v[2:3], v[82:83], v[2:3], v[80:81] op_sel_hi:[0,1,0]
	v_cvt_pk_bf16_f32 v5, v4, v5
	v_cvt_pk_bf16_f32 v4, v2, v3
	v_cvt_pk_bf16_f32 v3, v6, v7
	v_cvt_pk_bf16_f32 v2, v12, v13
	v_rsq_f32_e32 v6, v92
	v_rsq_f32_e32 v7, v93
	v_rsq_f32_e32 v8, v94
	v_rsq_f32_e32 v9, v95
	ds_write_b128 v67, v[2:5] offset:34816
	v_pk_mul_f32 v[2:3], v[30:31], v[10:11]
	v_pk_mul_f32 v[4:5], v[22:23], v[84:85]
	v_pk_fma_f32 v[2:3], v[70:71], v[2:3], v[68:69] op_sel_hi:[0,1,0]
	v_pk_fma_f32 v[4:5], v[70:71], v[4:5], v[68:69] op_sel_hi:[0,1,0]
	v_cvt_pk_bf16_f32 v5, v4, v5
	v_cvt_pk_bf16_f32 v4, v2, v3
	v_cvt_pk_bf16_f32 v3, v86, v87
	v_cvt_pk_bf16_f32 v2, v90, v91
	ds_write_b128 v67, v[2:5] offset:52224
	v_pk_mul_f32 v[2:3], v[52:53], v[6:7]
	v_pk_mul_f32 v[4:5], v[40:41], v[8:9]
	v_pk_fma_f32 v[12:13], v[74:75], v[2:3], v[72:73] op_sel_hi:[0,1,0]
	v_pk_fma_f32 v[10:11], v[74:75], v[4:5], v[72:73] op_sel_hi:[0,1,0]
	v_pk_mul_f32 v[2:3], v[50:51], v[6:7]
	v_pk_mul_f32 v[4:5], v[44:45], v[8:9]
	v_pk_fma_f32 v[16:17], v[76:77], v[2:3], v[78:79] op_sel_hi:[0,1,0]
	v_pk_fma_f32 v[14:15], v[76:77], v[4:5], v[78:79] op_sel_hi:[0,1,0]
	v_pk_mul_f32 v[2:3], v[48:49], v[6:7]
	v_pk_mul_f32 v[4:5], v[42:43], v[8:9]
	v_pk_fma_f32 v[24:25], v[82:83], v[2:3], v[80:81] op_sel_hi:[0,1,0]
	v_pk_fma_f32 v[22:23], v[82:83], v[4:5], v[80:81] op_sel_hi:[0,1,0]
	v_pk_mul_f32 v[2:3], v[46:47], v[6:7]
	v_pk_mul_f32 v[4:5], v[38:39], v[8:9]
	v_rsq_f32_e32 v6, v96
	v_rsq_f32_e32 v7, v97
	v_rsq_f32_e32 v8, v98
	v_rsq_f32_e32 v9, v99
	v_pk_fma_f32 v[26:27], v[70:71], v[4:5], v[68:69] op_sel_hi:[0,1,0]
	v_pk_fma_f32 v[28:29], v[70:71], v[2:3], v[68:69] op_sel_hi:[0,1,0]
	v_pk_mul_f32 v[2:3], v[64:65], v[6:7]
	v_pk_mul_f32 v[4:5], v[58:59], v[8:9]
	v_pk_fma_f32 v[2:3], v[74:75], v[2:3], v[72:73] op_sel_hi:[0,1,0]
	v_pk_fma_f32 v[4:5], v[74:75], v[4:5], v[72:73] op_sel_hi:[0,1,0]
	v_cvt_pk_bf16_f32 v5, v4, v5
	v_cvt_pk_bf16_f32 v4, v2, v3
	v_cvt_pk_bf16_f32 v3, v10, v11
	v_cvt_pk_bf16_f32 v2, v12, v13
	ds_write_b128 v67, v[2:5] offset:16
	v_pk_mul_f32 v[2:3], v[62:63], v[6:7]
	v_pk_mul_f32 v[4:5], v[56:57], v[8:9]
	v_pk_fma_f32 v[2:3], v[76:77], v[2:3], v[78:79] op_sel_hi:[0,1,0]
	v_pk_fma_f32 v[4:5], v[76:77], v[4:5], v[78:79] op_sel_hi:[0,1,0]
	v_cvt_pk_bf16_f32 v5, v4, v5
	v_cvt_pk_bf16_f32 v4, v2, v3
	v_cvt_pk_bf16_f32 v3, v14, v15
	v_cvt_pk_bf16_f32 v2, v16, v17
	ds_write_b128 v67, v[2:5] offset:17424
	v_pk_mul_f32 v[2:3], v[60:61], v[6:7]
	v_pk_mul_f32 v[4:5], v[54:55], v[8:9]
	v_pk_fma_f32 v[2:3], v[82:83], v[2:3], v[80:81] op_sel_hi:[0,1,0]
	v_pk_fma_f32 v[4:5], v[82:83], v[4:5], v[80:81] op_sel_hi:[0,1,0]
	v_cvt_pk_bf16_f32 v5, v4, v5
	v_cvt_pk_bf16_f32 v4, v2, v3
	v_cvt_pk_bf16_f32 v3, v22, v23
	v_cvt_pk_bf16_f32 v2, v24, v25
	ds_write_b128 v67, v[2:5] offset:34832
	v_pk_mul_f32 v[2:3], v[20:21], v[6:7]
	v_pk_mul_f32 v[4:5], v[18:19], v[8:9]
	v_and_or_b32 v8, v1, 31, s6
	v_pk_fma_f32 v[4:5], v[70:71], v[4:5], v[68:69] op_sel_hi:[0,1,0]
	v_pk_fma_f32 v[2:3], v[70:71], v[2:3], v[68:69] op_sel_hi:[0,1,0]
	v_lshl_add_u64 v[6:7], s[28:29], 0, v[130:131]
	v_bfe_u32 v10, v1, 5, 1
	v_ashrrev_i32_e32 v9, 31, v8
	v_cvt_pk_bf16_f32 v5, v4, v5
	v_cvt_pk_bf16_f32 v4, v2, v3
	v_cvt_pk_bf16_f32 v3, v26, v27
	v_cvt_pk_bf16_f32 v2, v28, v29
	v_add_co_u32_e32 v66, vcc, s90, v6
	v_lshlrev_b32_e32 v1, 2, v10
	v_lshlrev_b64 v[68:69], 1, v[8:9]
	ds_write_b128 v67, v[2:5] offset:52240
	v_addc_co_u32_e32 v67, vcc, 0, v7, vcc
	v_or_b32_e32 v82, s65, v1
	v_lshl_add_u64 v[84:85], s[80:81], 0, v[68:69]
	v_add_co_u32_e32 v86, vcc, s7, v6
	v_mad_u64_u32 v[12:13], s[6:7], v82, s87, v[84:85]
	s_waitcnt lgkmcnt(0)
	s_barrier
	global_load_dwordx4 v[2:5], v130, s[28:29]
	global_load_dwordx4 v[58:61], v130, s[28:29] offset:1024
	global_load_dwordx4 v[22:25], v130, s[28:29] offset:2048
	global_load_dwordx4 v[18:21], v130, s[28:29] offset:3072
	global_load_ushort v9, v[12:13], off
	v_or_b32_e32 v11, 1, v82
	v_mad_u64_u32 v[12:13], s[6:7], v11, s87, v[84:85]
	global_load_ushort v11, v[12:13], off
	v_or_b32_e32 v12, 2, v82
	v_mad_u64_u32 v[12:13], s[6:7], v12, s87, v[84:85]
	global_load_ushort v28, v[12:13], off
	v_or_b32_e32 v12, 3, v82
	v_mad_u64_u32 v[12:13], s[6:7], v12, s87, v[84:85]
	global_load_ushort v29, v[12:13], off
	v_or_b32_e32 v12, 8, v82
	v_or_b32_e32 v14, 9, v82
	v_mad_u64_u32 v[12:13], s[6:7], v12, s87, v[84:85]
	v_mad_u64_u32 v[14:15], s[6:7], v14, s87, v[84:85]
	v_or_b32_e32 v16, 10, v82
	v_or_b32_e32 v26, 11, v82
	v_mad_u64_u32 v[16:17], s[6:7], v16, s87, v[84:85]
	v_mad_u64_u32 v[26:27], s[6:7], v26, s87, v[84:85]
	global_load_ushort v12, v[12:13], off
	s_nop 0
	global_load_ushort v13, v[14:15], off
	s_nop 0
	global_load_ushort v14, v[16:17], off
	global_load_ushort v15, v[26:27], off
	v_addc_co_u32_e32 v87, vcc, 0, v7, vcc
	v_mov_b32_e32 v83, v131
	v_lshl_add_u64 v[88:89], s[76:77], 0, v[68:69]
	v_lshlrev_b64 v[68:69], 11, v[82:83]
	v_lshl_add_u64 v[68:69], v[88:89], 0, v[68:69]
	s_mov_b64 s[28:29], -1
	s_waitcnt vmcnt(7)
	v_lshlrev_b32_e32 v9, 16, v9
	v_fma_f32 v16, |v9|, s92, 1.0
	v_rcp_f32_e32 v16, v16
	v_mul_f32_e32 v26, v9, v9
	v_mul_f32_e32 v26, 0xbf38aa3b, v26
	v_exp_f32_e32 v26, v26
	v_fmamk_f32 v17, v16, 0x3f07dc22, v236
	v_fmaak_f32 v17, v16, v17, 0x3f35f0e3
	v_fmaak_f32 v17, v16, v17, 0xbe11a98e
	v_fmaak_f32 v17, v16, v17, 0x3e027906
	v_mul_f32_e32 v16, v16, v17
	v_mul_f32_e32 v16, v26, v16
	v_mul_f32_e32 v17, v16, v9
	v_fma_f32 v16, -v16, v9, v9
	v_cmp_gt_f32_e32 vcc, 0, v9
	s_waitcnt vmcnt(6)
	v_lshlrev_b32_e32 v9, 16, v11
	v_fma_f32 v11, |v9|, s92, 1.0
	v_rcp_f32_e32 v11, v11
	v_cndmask_b32_e32 v70, v16, v17, vcc
	v_mul_f32_e32 v17, v9, v9
	v_mul_f32_e32 v17, 0xbf38aa3b, v17
	v_fmamk_f32 v16, v11, 0x3f07dc22, v236
	v_fmaak_f32 v16, v11, v16, 0x3f35f0e3
	v_exp_f32_e32 v17, v17
	v_fmaak_f32 v16, v11, v16, 0xbe11a98e
	v_fmaak_f32 v16, v11, v16, 0x3e027906
	v_mul_f32_e32 v11, v11, v16
	v_mul_f32_e32 v11, v17, v11
	v_mul_f32_e32 v16, v11, v9
	v_fma_f32 v11, -v11, v9, v9
	v_cmp_gt_f32_e32 vcc, 0, v9
	s_waitcnt vmcnt(5)
	v_lshlrev_b32_e32 v9, 16, v28
	v_mul_f32_e32 v17, v9, v9
	v_cndmask_b32_e32 v71, v11, v16, vcc
	v_fma_f32 v11, |v9|, s92, 1.0
	v_rcp_f32_e32 v11, v11
	v_mul_f32_e32 v17, 0xbf38aa3b, v17
	v_exp_f32_e32 v17, v17
	v_cmp_gt_f32_e32 vcc, 0, v9
	v_fmamk_f32 v16, v11, 0x3f07dc22, v236
	v_fmaak_f32 v16, v11, v16, 0x3f35f0e3
	v_fmaak_f32 v16, v11, v16, 0xbe11a98e
	v_fmaak_f32 v16, v11, v16, 0x3e027906
	v_mul_f32_e32 v11, v11, v16
	v_mul_f32_e32 v11, v17, v11
	v_mul_f32_e32 v16, v11, v9
	v_fma_f32 v11, -v11, v9, v9
	s_waitcnt vmcnt(4)
	v_lshlrev_b32_e32 v9, 16, v29
	v_cndmask_b32_e32 v72, v11, v16, vcc
	v_fma_f32 v11, |v9|, s92, 1.0
	v_rcp_f32_e32 v11, v11
	v_mul_f32_e32 v17, v9, v9
	v_mul_f32_e32 v17, 0xbf38aa3b, v17
	v_exp_f32_e32 v17, v17
	v_fmamk_f32 v16, v11, 0x3f07dc22, v236
	v_fmaak_f32 v16, v11, v16, 0x3f35f0e3
	v_fmaak_f32 v16, v11, v16, 0xbe11a98e
	v_fmaak_f32 v16, v11, v16, 0x3e027906
	v_mul_f32_e32 v11, v11, v16
	v_mul_f32_e32 v11, v17, v11
	v_mul_f32_e32 v16, v11, v9
	v_fma_f32 v11, -v11, v9, v9
	v_cmp_gt_f32_e32 vcc, 0, v9
	s_waitcnt vmcnt(3)
	v_lshlrev_b32_e32 v9, 16, v12
	v_or_b32_e32 v26, 27, v82
	v_cndmask_b32_e32 v73, v11, v16, vcc
	v_fma_f32 v11, |v9|, s92, 1.0
	v_rcp_f32_e32 v11, v11
	v_mul_f32_e32 v16, v9, v9
	v_mul_f32_e32 v16, 0xbf38aa3b, v16
	v_exp_f32_e32 v16, v16
	v_fmamk_f32 v12, v11, 0x3f07dc22, v236
	v_fmaak_f32 v12, v11, v12, 0x3f35f0e3
	v_fmaak_f32 v12, v11, v12, 0xbe11a98e
	v_fmaak_f32 v12, v11, v12, 0x3e027906
	v_mul_f32_e32 v11, v11, v12
	v_mul_f32_e32 v11, v16, v11
	v_mul_f32_e32 v12, v11, v9
	v_fma_f32 v11, -v11, v9, v9
	v_cmp_gt_f32_e32 vcc, 0, v9
	s_waitcnt vmcnt(2)
	v_lshlrev_b32_e32 v9, 16, v13
	v_mul_f32_e32 v13, v9, v9
	v_cndmask_b32_e32 v74, v11, v12, vcc
	v_fma_f32 v11, |v9|, s92, 1.0
	v_rcp_f32_e32 v11, v11
	v_mul_f32_e32 v13, 0xbf38aa3b, v13
	v_exp_f32_e32 v13, v13
	v_cmp_gt_f32_e32 vcc, 0, v9
	v_fmamk_f32 v12, v11, 0x3f07dc22, v236
	v_fmaak_f32 v12, v11, v12, 0x3f35f0e3
	v_fmaak_f32 v12, v11, v12, 0xbe11a98e
	v_fmaak_f32 v12, v11, v12, 0x3e027906
	v_mul_f32_e32 v11, v11, v12
	v_mul_f32_e32 v11, v13, v11
	v_mul_f32_e32 v12, v11, v9
	v_fma_f32 v11, -v11, v9, v9
	s_waitcnt vmcnt(1)
	v_lshlrev_b32_e32 v9, 16, v14
	v_cndmask_b32_e32 v75, v11, v12, vcc
	v_fma_f32 v11, |v9|, s92, 1.0
	v_rcp_f32_e32 v11, v11
	v_mul_f32_e32 v13, v9, v9
	v_mul_f32_e32 v13, 0xbf38aa3b, v13
	v_exp_f32_e32 v13, v13
	v_fmamk_f32 v12, v11, 0x3f07dc22, v236
	v_fmaak_f32 v12, v11, v12, 0x3f35f0e3
	v_fmaak_f32 v12, v11, v12, 0xbe11a98e
	v_fmaak_f32 v12, v11, v12, 0x3e027906
	v_mul_f32_e32 v11, v11, v12
	v_mul_f32_e32 v11, v13, v11
	v_mul_f32_e32 v12, v11, v9
	v_fma_f32 v11, -v11, v9, v9
	v_cmp_gt_f32_e32 vcc, 0, v9
	s_waitcnt vmcnt(0)
	v_lshlrev_b32_e32 v9, 16, v15
	v_mul_f32_e32 v13, v9, v9
	v_cndmask_b32_e32 v76, v11, v12, vcc
	v_fma_f32 v11, |v9|, s92, 1.0
	v_rcp_f32_e32 v11, v11
	v_mul_f32_e32 v13, 0xbf38aa3b, v13
	v_exp_f32_e32 v13, v13
	v_cmp_gt_f32_e32 vcc, 0, v9
	v_fmamk_f32 v12, v11, 0x3f07dc22, v236
	v_fmaak_f32 v12, v11, v12, 0x3f35f0e3
	v_fmaak_f32 v12, v11, v12, 0xbe11a98e
	v_fmaak_f32 v12, v11, v12, 0x3e027906
	v_mul_f32_e32 v11, v11, v12
	v_mul_f32_e32 v11, v13, v11
	v_mul_f32_e32 v12, v11, v9
	v_fma_f32 v11, -v11, v9, v9
	v_or_b32_e32 v9, 16, v82
	v_cndmask_b32_e32 v77, v11, v12, vcc
	v_mad_u64_u32 v[12:13], s[6:7], v9, s87, v[84:85]
	global_load_ushort v9, v[12:13], off
	v_or_b32_e32 v11, 17, v82
	v_mad_u64_u32 v[12:13], s[6:7], v11, s87, v[84:85]
	global_load_ushort v11, v[12:13], off
	v_or_b32_e32 v12, 18, v82
	v_mad_u64_u32 v[12:13], s[6:7], v12, s87, v[84:85]
	global_load_ushort v28, v[12:13], off
	v_or_b32_e32 v12, 19, v82
	v_mad_u64_u32 v[12:13], s[6:7], v12, s87, v[84:85]
	global_load_ushort v29, v[12:13], off
	v_or_b32_e32 v12, 24, v82
	v_or_b32_e32 v14, 25, v82
	v_mad_u64_u32 v[12:13], s[6:7], v12, s87, v[84:85]
	v_mad_u64_u32 v[14:15], s[6:7], v14, s87, v[84:85]
	v_or_b32_e32 v16, 26, v82
	v_mad_u64_u32 v[16:17], s[6:7], v16, s87, v[84:85]
	v_mad_u64_u32 v[26:27], s[6:7], v26, s87, v[84:85]
	global_load_ushort v12, v[12:13], off
	s_nop 0
	global_load_ushort v13, v[14:15], off
	s_nop 0
	global_load_ushort v14, v[16:17], off
	global_load_ushort v15, v[26:27], off
	s_waitcnt vmcnt(7)
	v_lshlrev_b32_e32 v9, 16, v9
	v_fma_f32 v16, |v9|, s92, 1.0
	v_rcp_f32_e32 v16, v16
	v_mul_f32_e32 v26, v9, v9
	v_mul_f32_e32 v26, 0xbf38aa3b, v26
	v_exp_f32_e32 v26, v26
	v_fmamk_f32 v17, v16, 0x3f07dc22, v236
	v_fmaak_f32 v17, v16, v17, 0x3f35f0e3
	v_fmaak_f32 v17, v16, v17, 0xbe11a98e
	v_fmaak_f32 v17, v16, v17, 0x3e027906
	v_mul_f32_e32 v16, v16, v17
	v_mul_f32_e32 v16, v26, v16
	v_mul_f32_e32 v17, v16, v9
	v_fma_f32 v16, -v16, v9, v9
	v_cmp_gt_f32_e32 vcc, 0, v9
	s_waitcnt vmcnt(6)
	v_lshlrev_b32_e32 v9, 16, v11
	v_fma_f32 v11, |v9|, s92, 1.0
	v_rcp_f32_e32 v11, v11
	v_cndmask_b32_e32 v95, v16, v17, vcc
	v_mul_f32_e32 v17, v9, v9
	v_mul_f32_e32 v17, 0xbf38aa3b, v17
	v_fmamk_f32 v16, v11, 0x3f07dc22, v236
	v_fmaak_f32 v16, v11, v16, 0x3f35f0e3
	v_exp_f32_e32 v17, v17
	v_fmaak_f32 v16, v11, v16, 0xbe11a98e
	v_fmaak_f32 v16, v11, v16, 0x3e027906
	v_mul_f32_e32 v11, v11, v16
	v_mul_f32_e32 v11, v17, v11
	v_mul_f32_e32 v16, v11, v9
	v_fma_f32 v11, -v11, v9, v9
	v_cmp_gt_f32_e32 vcc, 0, v9
	s_waitcnt vmcnt(5)
	v_lshlrev_b32_e32 v9, 16, v28
	v_mul_f32_e32 v17, v9, v9
	v_cndmask_b32_e32 v96, v11, v16, vcc
	v_fma_f32 v11, |v9|, s92, 1.0
	v_rcp_f32_e32 v11, v11
	v_mul_f32_e32 v17, 0xbf38aa3b, v17
	v_exp_f32_e32 v17, v17
	v_cmp_gt_f32_e32 vcc, 0, v9
	v_fmamk_f32 v16, v11, 0x3f07dc22, v236
	v_fmaak_f32 v16, v11, v16, 0x3f35f0e3
	v_fmaak_f32 v16, v11, v16, 0xbe11a98e
	v_fmaak_f32 v16, v11, v16, 0x3e027906
	v_mul_f32_e32 v11, v11, v16
	v_mul_f32_e32 v11, v17, v11
	v_mul_f32_e32 v16, v11, v9
	v_fma_f32 v11, -v11, v9, v9
	s_waitcnt vmcnt(4)
	v_lshlrev_b32_e32 v9, 16, v29
	v_cndmask_b32_e32 v98, v11, v16, vcc
	v_fma_f32 v11, |v9|, s92, 1.0
	v_rcp_f32_e32 v11, v11
	v_mul_f32_e32 v17, v9, v9
	v_mul_f32_e32 v17, 0xbf38aa3b, v17
	v_exp_f32_e32 v17, v17
	v_fmamk_f32 v16, v11, 0x3f07dc22, v236
	v_fmaak_f32 v16, v11, v16, 0x3f35f0e3
	v_fmaak_f32 v16, v11, v16, 0xbe11a98e
	v_fmaak_f32 v16, v11, v16, 0x3e027906
	v_mul_f32_e32 v11, v11, v16
	v_mul_f32_e32 v11, v17, v11
	v_mul_f32_e32 v16, v11, v9
	v_fma_f32 v11, -v11, v9, v9
	v_cmp_gt_f32_e32 vcc, 0, v9
	s_waitcnt vmcnt(3)
	v_lshlrev_b32_e32 v9, 16, v12
	v_or_b32_e32 v26, 43, v82
	v_cndmask_b32_e32 v100, v11, v16, vcc
	v_fma_f32 v11, |v9|, s92, 1.0
	v_rcp_f32_e32 v11, v11
	v_mul_f32_e32 v16, v9, v9
	v_mul_f32_e32 v16, 0xbf38aa3b, v16
	v_exp_f32_e32 v16, v16
	v_fmamk_f32 v12, v11, 0x3f07dc22, v236
	v_fmaak_f32 v12, v11, v12, 0x3f35f0e3
	v_fmaak_f32 v12, v11, v12, 0xbe11a98e
	v_fmaak_f32 v12, v11, v12, 0x3e027906
	v_mul_f32_e32 v11, v11, v12
	v_mul_f32_e32 v11, v16, v11
	v_mul_f32_e32 v12, v11, v9
	v_fma_f32 v11, -v11, v9, v9
	v_cmp_gt_f32_e32 vcc, 0, v9
	s_waitcnt vmcnt(2)
	v_lshlrev_b32_e32 v9, 16, v13
	v_mul_f32_e32 v13, v9, v9
	v_cndmask_b32_e32 v102, v11, v12, vcc
	v_fma_f32 v11, |v9|, s92, 1.0
	v_rcp_f32_e32 v11, v11
	v_mul_f32_e32 v13, 0xbf38aa3b, v13
	v_exp_f32_e32 v13, v13
	v_cmp_gt_f32_e32 vcc, 0, v9
	v_fmamk_f32 v12, v11, 0x3f07dc22, v236
	v_fmaak_f32 v12, v11, v12, 0x3f35f0e3
	v_fmaak_f32 v12, v11, v12, 0xbe11a98e
	v_fmaak_f32 v12, v11, v12, 0x3e027906
	v_mul_f32_e32 v11, v11, v12
	v_mul_f32_e32 v11, v13, v11
	v_mul_f32_e32 v12, v11, v9
	v_fma_f32 v11, -v11, v9, v9
	s_waitcnt vmcnt(1)
	v_lshlrev_b32_e32 v9, 16, v14
	v_cndmask_b32_e32 v104, v11, v12, vcc
	v_fma_f32 v11, |v9|, s92, 1.0
	v_rcp_f32_e32 v11, v11
	v_mul_f32_e32 v13, v9, v9
	v_mul_f32_e32 v13, 0xbf38aa3b, v13
	v_exp_f32_e32 v13, v13
	v_fmamk_f32 v12, v11, 0x3f07dc22, v236
	v_fmaak_f32 v12, v11, v12, 0x3f35f0e3
	v_fmaak_f32 v12, v11, v12, 0xbe11a98e
	v_fmaak_f32 v12, v11, v12, 0x3e027906
	v_mul_f32_e32 v11, v11, v12
	v_mul_f32_e32 v11, v13, v11
	v_mul_f32_e32 v12, v11, v9
	v_fma_f32 v11, -v11, v9, v9
	v_cmp_gt_f32_e32 vcc, 0, v9
	s_waitcnt vmcnt(0)
	v_lshlrev_b32_e32 v9, 16, v15
	v_mul_f32_e32 v13, v9, v9
	v_cndmask_b32_e32 v106, v11, v12, vcc
	v_fma_f32 v11, |v9|, s92, 1.0
	v_rcp_f32_e32 v11, v11
	v_mul_f32_e32 v13, 0xbf38aa3b, v13
	v_exp_f32_e32 v13, v13
	v_cmp_gt_f32_e32 vcc, 0, v9
	v_fmamk_f32 v12, v11, 0x3f07dc22, v236
	v_fmaak_f32 v12, v11, v12, 0x3f35f0e3
	v_fmaak_f32 v12, v11, v12, 0xbe11a98e
	v_fmaak_f32 v12, v11, v12, 0x3e027906
	v_mul_f32_e32 v11, v11, v12
	v_mul_f32_e32 v11, v13, v11
	v_mul_f32_e32 v12, v11, v9
	v_fma_f32 v11, -v11, v9, v9
	v_or_b32_e32 v9, 32, v82
	v_cndmask_b32_e32 v110, v11, v12, vcc
	v_mad_u64_u32 v[12:13], s[6:7], v9, s87, v[84:85]
	global_load_ushort v9, v[12:13], off
	v_or_b32_e32 v11, 33, v82
	v_mad_u64_u32 v[12:13], s[6:7], v11, s87, v[84:85]
	global_load_ushort v11, v[12:13], off
	v_or_b32_e32 v12, 34, v82
	v_mad_u64_u32 v[12:13], s[6:7], v12, s87, v[84:85]
	global_load_ushort v28, v[12:13], off
	v_or_b32_e32 v12, 35, v82
	v_mad_u64_u32 v[12:13], s[6:7], v12, s87, v[84:85]
	global_load_ushort v29, v[12:13], off
	v_or_b32_e32 v12, 40, v82
	v_or_b32_e32 v14, 41, v82
	v_mad_u64_u32 v[12:13], s[6:7], v12, s87, v[84:85]
	v_mad_u64_u32 v[14:15], s[6:7], v14, s87, v[84:85]
	v_or_b32_e32 v16, 42, v82
	v_mad_u64_u32 v[16:17], s[6:7], v16, s87, v[84:85]
	v_mad_u64_u32 v[26:27], s[6:7], v26, s87, v[84:85]
	global_load_ushort v12, v[12:13], off
	s_nop 0
	global_load_ushort v13, v[14:15], off
	s_nop 0
	global_load_ushort v14, v[16:17], off
	global_load_ushort v15, v[26:27], off
	s_waitcnt vmcnt(7)
	v_lshlrev_b32_e32 v9, 16, v9
	v_fma_f32 v16, |v9|, s92, 1.0
	v_rcp_f32_e32 v16, v16
	v_mul_f32_e32 v26, v9, v9
	v_mul_f32_e32 v26, 0xbf38aa3b, v26
	v_exp_f32_e32 v26, v26
	v_fmamk_f32 v17, v16, 0x3f07dc22, v236
	v_fmaak_f32 v17, v16, v17, 0x3f35f0e3
	v_fmaak_f32 v17, v16, v17, 0xbe11a98e
	v_fmaak_f32 v17, v16, v17, 0x3e027906
	v_mul_f32_e32 v16, v16, v17
	v_mul_f32_e32 v16, v26, v16
	v_mul_f32_e32 v17, v16, v9
	v_fma_f32 v16, -v16, v9, v9
	v_cmp_gt_f32_e32 vcc, 0, v9
	s_waitcnt vmcnt(6)
	v_lshlrev_b32_e32 v9, 16, v11
	v_fma_f32 v11, |v9|, s92, 1.0
	v_rcp_f32_e32 v11, v11
	v_cndmask_b32_e32 v97, v16, v17, vcc
	v_mul_f32_e32 v17, v9, v9
	v_mul_f32_e32 v17, 0xbf38aa3b, v17
	v_fmamk_f32 v16, v11, 0x3f07dc22, v236
	v_fmaak_f32 v16, v11, v16, 0x3f35f0e3
	v_exp_f32_e32 v17, v17
	v_fmaak_f32 v16, v11, v16, 0xbe11a98e
	v_fmaak_f32 v16, v11, v16, 0x3e027906
	v_mul_f32_e32 v11, v11, v16
	v_mul_f32_e32 v11, v17, v11
	v_mul_f32_e32 v16, v11, v9
	v_fma_f32 v11, -v11, v9, v9
	v_cmp_gt_f32_e32 vcc, 0, v9
	s_waitcnt vmcnt(5)
	v_lshlrev_b32_e32 v9, 16, v28
	v_mul_f32_e32 v17, v9, v9
	v_cndmask_b32_e32 v99, v11, v16, vcc
	v_fma_f32 v11, |v9|, s92, 1.0
	v_rcp_f32_e32 v11, v11
	v_mul_f32_e32 v17, 0xbf38aa3b, v17
	v_exp_f32_e32 v17, v17
	v_cmp_gt_f32_e32 vcc, 0, v9
	v_fmamk_f32 v16, v11, 0x3f07dc22, v236
	v_fmaak_f32 v16, v11, v16, 0x3f35f0e3
	v_fmaak_f32 v16, v11, v16, 0xbe11a98e
	v_fmaak_f32 v16, v11, v16, 0x3e027906
	v_mul_f32_e32 v11, v11, v16
	v_mul_f32_e32 v11, v17, v11
	v_mul_f32_e32 v16, v11, v9
	v_fma_f32 v11, -v11, v9, v9
	s_waitcnt vmcnt(4)
	v_lshlrev_b32_e32 v9, 16, v29
	v_cndmask_b32_e32 v101, v11, v16, vcc
	v_fma_f32 v11, |v9|, s92, 1.0
	v_rcp_f32_e32 v11, v11
	v_mul_f32_e32 v17, v9, v9
	v_mul_f32_e32 v17, 0xbf38aa3b, v17
	v_exp_f32_e32 v17, v17
	v_fmamk_f32 v16, v11, 0x3f07dc22, v236
	v_fmaak_f32 v16, v11, v16, 0x3f35f0e3
	v_fmaak_f32 v16, v11, v16, 0xbe11a98e
	v_fmaak_f32 v16, v11, v16, 0x3e027906
	v_mul_f32_e32 v11, v11, v16
	v_mul_f32_e32 v11, v17, v11
	v_mul_f32_e32 v16, v11, v9
	v_fma_f32 v11, -v11, v9, v9
	v_cmp_gt_f32_e32 vcc, 0, v9
	s_waitcnt vmcnt(3)
	v_lshlrev_b32_e32 v9, 16, v12
	v_or_b32_e32 v26, 59, v82
	v_cndmask_b32_e32 v103, v11, v16, vcc
	v_fma_f32 v11, |v9|, s92, 1.0
	v_rcp_f32_e32 v11, v11
	v_mul_f32_e32 v16, v9, v9
	v_mul_f32_e32 v16, 0xbf38aa3b, v16
	v_exp_f32_e32 v16, v16
	v_fmamk_f32 v12, v11, 0x3f07dc22, v236
	v_fmaak_f32 v12, v11, v12, 0x3f35f0e3
	v_fmaak_f32 v12, v11, v12, 0xbe11a98e
	v_fmaak_f32 v12, v11, v12, 0x3e027906
	v_mul_f32_e32 v11, v11, v12
	v_mul_f32_e32 v11, v16, v11
	v_mul_f32_e32 v12, v11, v9
	v_fma_f32 v11, -v11, v9, v9
	v_cmp_gt_f32_e32 vcc, 0, v9
	s_waitcnt vmcnt(2)
	v_lshlrev_b32_e32 v9, 16, v13
	v_mul_f32_e32 v13, v9, v9
	v_cndmask_b32_e32 v105, v11, v12, vcc
	v_fma_f32 v11, |v9|, s92, 1.0
	v_rcp_f32_e32 v11, v11
	v_mul_f32_e32 v13, 0xbf38aa3b, v13
	v_exp_f32_e32 v13, v13
	v_cmp_gt_f32_e32 vcc, 0, v9
	v_fmamk_f32 v12, v11, 0x3f07dc22, v236
	v_fmaak_f32 v12, v11, v12, 0x3f35f0e3
	v_fmaak_f32 v12, v11, v12, 0xbe11a98e
	v_fmaak_f32 v12, v11, v12, 0x3e027906
	v_mul_f32_e32 v11, v11, v12
	v_mul_f32_e32 v11, v13, v11
	v_mul_f32_e32 v12, v11, v9
	v_fma_f32 v11, -v11, v9, v9
	s_waitcnt vmcnt(1)
	v_lshlrev_b32_e32 v9, 16, v14
	v_cndmask_b32_e32 v107, v11, v12, vcc
	v_fma_f32 v11, |v9|, s92, 1.0
	v_rcp_f32_e32 v11, v11
	v_mul_f32_e32 v13, v9, v9
	v_mul_f32_e32 v13, 0xbf38aa3b, v13
	v_exp_f32_e32 v13, v13
	v_fmamk_f32 v12, v11, 0x3f07dc22, v236
	v_fmaak_f32 v12, v11, v12, 0x3f35f0e3
	v_fmaak_f32 v12, v11, v12, 0xbe11a98e
	v_fmaak_f32 v12, v11, v12, 0x3e027906
	v_mul_f32_e32 v11, v11, v12
	v_mul_f32_e32 v11, v13, v11
	v_mul_f32_e32 v12, v11, v9
	v_fma_f32 v11, -v11, v9, v9
	v_cmp_gt_f32_e32 vcc, 0, v9
	s_waitcnt vmcnt(0)
	v_lshlrev_b32_e32 v9, 16, v15
	v_mul_f32_e32 v13, v9, v9
	v_cndmask_b32_e32 v108, v11, v12, vcc
	v_fma_f32 v11, |v9|, s92, 1.0
	v_rcp_f32_e32 v11, v11
	v_mul_f32_e32 v13, 0xbf38aa3b, v13
	v_exp_f32_e32 v13, v13
	v_cmp_gt_f32_e32 vcc, 0, v9
	v_fmamk_f32 v12, v11, 0x3f07dc22, v236
	v_fmaak_f32 v12, v11, v12, 0x3f35f0e3
	v_fmaak_f32 v12, v11, v12, 0xbe11a98e
	v_fmaak_f32 v12, v11, v12, 0x3e027906
	v_mul_f32_e32 v11, v11, v12
	v_mul_f32_e32 v11, v13, v11
	v_mul_f32_e32 v12, v11, v9
	v_fma_f32 v11, -v11, v9, v9
	v_or_b32_e32 v9, 48, v82
	v_cndmask_b32_e32 v109, v11, v12, vcc
	v_mad_u64_u32 v[12:13], s[6:7], v9, s87, v[84:85]
	global_load_ushort v9, v[12:13], off
	v_or_b32_e32 v11, 49, v82
	v_mad_u64_u32 v[12:13], s[6:7], v11, s87, v[84:85]
	global_load_ushort v11, v[12:13], off
	v_or_b32_e32 v12, 50, v82
	v_mad_u64_u32 v[12:13], s[6:7], v12, s87, v[84:85]
	global_load_ushort v28, v[12:13], off
	v_or_b32_e32 v12, 51, v82
	v_mad_u64_u32 v[12:13], s[6:7], v12, s87, v[84:85]
	global_load_ushort v29, v[12:13], off
	v_or_b32_e32 v12, 56, v82
	v_or_b32_e32 v14, 57, v82
	v_mad_u64_u32 v[12:13], s[6:7], v12, s87, v[84:85]
	v_mad_u64_u32 v[14:15], s[6:7], v14, s87, v[84:85]
	v_or_b32_e32 v16, 58, v82
	v_mad_u64_u32 v[16:17], s[6:7], v16, s87, v[84:85]
	v_mad_u64_u32 v[26:27], s[6:7], v26, s87, v[84:85]
	global_load_ushort v12, v[12:13], off
	s_nop 0
	global_load_ushort v13, v[14:15], off
	s_nop 0
	global_load_ushort v14, v[16:17], off
	global_load_ushort v15, v[26:27], off
	s_movk_i32 s6, 0x3000
	s_waitcnt vmcnt(7)
	v_lshlrev_b32_e32 v9, 16, v9
	v_fma_f32 v16, |v9|, s92, 1.0
	v_rcp_f32_e32 v16, v16
	v_mul_f32_e32 v26, v9, v9
	v_mul_f32_e32 v26, 0xbf38aa3b, v26
	v_exp_f32_e32 v26, v26
	v_fmamk_f32 v17, v16, 0x3f07dc22, v236
	v_fmaak_f32 v17, v16, v17, 0x3f35f0e3
	v_fmaak_f32 v17, v16, v17, 0xbe11a98e
	v_fmaak_f32 v17, v16, v17, 0x3e027906
	v_mul_f32_e32 v16, v16, v17
	v_mul_f32_e32 v16, v26, v16
	v_mul_f32_e32 v17, v16, v9
	v_fma_f32 v16, -v16, v9, v9
	v_cmp_gt_f32_e32 vcc, 0, v9
	s_waitcnt vmcnt(6)
	v_lshlrev_b32_e32 v9, 16, v11
	v_fma_f32 v11, |v9|, s92, 1.0
	v_rcp_f32_e32 v11, v11
	v_cndmask_b32_e32 v113, v16, v17, vcc
	v_mul_f32_e32 v17, v9, v9
	v_mul_f32_e32 v17, 0xbf38aa3b, v17
	v_fmamk_f32 v16, v11, 0x3f07dc22, v236
	v_fmaak_f32 v16, v11, v16, 0x3f35f0e3
	v_exp_f32_e32 v17, v17
	v_fmaak_f32 v16, v11, v16, 0xbe11a98e
	v_fmaak_f32 v16, v11, v16, 0x3e027906
	v_mul_f32_e32 v11, v11, v16
	v_mul_f32_e32 v11, v17, v11
	v_mul_f32_e32 v16, v11, v9
	v_fma_f32 v11, -v11, v9, v9
	v_cmp_gt_f32_e32 vcc, 0, v9
	s_waitcnt vmcnt(5)
	v_lshlrev_b32_e32 v9, 16, v28
	v_mul_f32_e32 v17, v9, v9
	v_cndmask_b32_e32 v115, v11, v16, vcc
	v_fma_f32 v11, |v9|, s92, 1.0
	v_rcp_f32_e32 v11, v11
	v_mul_f32_e32 v17, 0xbf38aa3b, v17
	v_exp_f32_e32 v17, v17
	v_cmp_gt_f32_e32 vcc, 0, v9
	v_fmamk_f32 v16, v11, 0x3f07dc22, v236
	v_fmaak_f32 v16, v11, v16, 0x3f35f0e3
	v_fmaak_f32 v16, v11, v16, 0xbe11a98e
	v_fmaak_f32 v16, v11, v16, 0x3e027906
	v_mul_f32_e32 v11, v11, v16
	v_mul_f32_e32 v11, v17, v11
	v_mul_f32_e32 v16, v11, v9
	v_fma_f32 v11, -v11, v9, v9
	s_waitcnt vmcnt(4)
	v_lshlrev_b32_e32 v9, 16, v29
	v_cndmask_b32_e32 v117, v11, v16, vcc
	v_fma_f32 v11, |v9|, s92, 1.0
	v_rcp_f32_e32 v11, v11
	v_mul_f32_e32 v17, v9, v9
	v_mul_f32_e32 v17, 0xbf38aa3b, v17
	v_exp_f32_e32 v17, v17
	v_fmamk_f32 v16, v11, 0x3f07dc22, v236
	v_fmaak_f32 v16, v11, v16, 0x3f35f0e3
	v_fmaak_f32 v16, v11, v16, 0xbe11a98e
	v_fmaak_f32 v16, v11, v16, 0x3e027906
	v_mul_f32_e32 v11, v11, v16
	v_mul_f32_e32 v11, v17, v11
	v_mul_f32_e32 v16, v11, v9
	v_fma_f32 v11, -v11, v9, v9
	v_cmp_gt_f32_e32 vcc, 0, v9
	s_waitcnt vmcnt(3)
	v_lshlrev_b32_e32 v9, 16, v12
	v_cndmask_b32_e32 v119, v11, v16, vcc
	v_fma_f32 v11, |v9|, s92, 1.0
	v_rcp_f32_e32 v11, v11
	v_mul_f32_e32 v16, v9, v9
	v_mul_f32_e32 v16, 0xbf38aa3b, v16
	v_exp_f32_e32 v16, v16
	v_fmamk_f32 v12, v11, 0x3f07dc22, v236
	v_fmaak_f32 v12, v11, v12, 0x3f35f0e3
	v_fmaak_f32 v12, v11, v12, 0xbe11a98e
	v_fmaak_f32 v12, v11, v12, 0x3e027906
	v_mul_f32_e32 v11, v11, v12
	v_mul_f32_e32 v11, v16, v11
	v_mul_f32_e32 v12, v11, v9
	v_fma_f32 v11, -v11, v9, v9
	v_cmp_gt_f32_e32 vcc, 0, v9
	s_waitcnt vmcnt(2)
	v_lshlrev_b32_e32 v9, 16, v13
	v_mul_f32_e32 v13, v9, v9
	v_cndmask_b32_e32 v120, v11, v12, vcc
	v_fma_f32 v11, |v9|, s92, 1.0
	v_rcp_f32_e32 v11, v11
	v_mul_f32_e32 v13, 0xbf38aa3b, v13
	v_exp_f32_e32 v13, v13
	v_cmp_gt_f32_e32 vcc, 0, v9
	v_fmamk_f32 v12, v11, 0x3f07dc22, v236
	v_fmaak_f32 v12, v11, v12, 0x3f35f0e3
	v_fmaak_f32 v12, v11, v12, 0xbe11a98e
	v_fmaak_f32 v12, v11, v12, 0x3e027906
	v_mul_f32_e32 v11, v11, v12
	v_mul_f32_e32 v11, v13, v11
	v_mul_f32_e32 v12, v11, v9
	v_fma_f32 v11, -v11, v9, v9
	s_waitcnt vmcnt(1)
	v_lshlrev_b32_e32 v9, 16, v14
	v_cndmask_b32_e32 v121, v11, v12, vcc
	v_fma_f32 v11, |v9|, s92, 1.0
	v_rcp_f32_e32 v11, v11
	v_mul_f32_e32 v13, v9, v9
	v_mul_f32_e32 v13, 0xbf38aa3b, v13
	v_exp_f32_e32 v13, v13
	v_fmamk_f32 v12, v11, 0x3f07dc22, v236
	v_fmaak_f32 v12, v11, v12, 0x3f35f0e3
	v_fmaak_f32 v12, v11, v12, 0xbe11a98e
	v_fmaak_f32 v12, v11, v12, 0x3e027906
	v_mul_f32_e32 v11, v11, v12
	v_mul_f32_e32 v11, v13, v11
	v_mul_f32_e32 v12, v11, v9
	v_fma_f32 v11, -v11, v9, v9
	v_cmp_gt_f32_e32 vcc, 0, v9
	s_waitcnt vmcnt(0)
	v_lshlrev_b32_e32 v9, 16, v15
	v_mul_f32_e32 v13, v9, v9
	v_cndmask_b32_e32 v122, v11, v12, vcc
	v_fma_f32 v11, |v9|, s92, 1.0
	v_rcp_f32_e32 v11, v11
	v_mul_f32_e32 v13, 0xbf38aa3b, v13
	v_exp_f32_e32 v13, v13
	v_cmp_gt_f32_e32 vcc, 0, v9
	v_fmamk_f32 v12, v11, 0x3f07dc22, v236
	v_fmaak_f32 v12, v11, v12, 0x3f35f0e3
	v_fmaak_f32 v12, v11, v12, 0xbe11a98e
	v_fmaak_f32 v12, v11, v12, 0x3e027906
	v_mul_f32_e32 v11, v11, v12
	v_mul_f32_e32 v11, v13, v11
	v_mul_f32_e32 v12, v11, v9
	v_fma_f32 v11, -v11, v9, v9
	v_cndmask_b32_e32 v123, v11, v12, vcc
	v_add_co_u32_e32 v90, vcc, s6, v6
	s_nop 1
	v_addc_co_u32_e32 v91, vcc, 0, v7, vcc
	v_add_co_u32_e32 v92, vcc, s97, v6
	v_lshlrev_b32_e32 v6, 4, v10
	s_nop 0
	v_addc_co_u32_e32 v93, vcc, 0, v7, vcc
	v_mul_lo_u32 v7, v8, s8
	v_add3_u32 v26, 0, v7, v6
	ds_read_b128 v[54:57], v26
	ds_read_b128 v[50:53], v26 offset:32
	ds_read_b128 v[46:49], v26 offset:64
	ds_read_b128 v[42:45], v26 offset:96
	v_add_u32_e32 v94, s5, v6
	s_waitcnt lgkmcnt(3)
	v_mfma_f32_32x32x16_bf16 v[2:17], v[2:5], v[54:57], 0
	global_load_dwordx4 v[78:81], v[66:67], off offset:1024
	ds_read_b128 v[38:41], v26 offset:128
	ds_read_b128 v[34:37], v26 offset:160
	ds_read_b128 v[30:33], v26 offset:192
	ds_read_b128 v[26:29], v26 offset:224
	global_load_dwordx4 v[62:65], v[86:87], off offset:-4096
	ds_read_b128 v[124:127], v94
	v_readlane_b32 s5, v251, 32
	s_waitcnt lgkmcnt(7)
	v_mfma_f32_32x32x16_bf16 v[2:17], v[58:61], v[50:53], v[2:17]
	ds_read_b128 v[58:61], v94 offset:32
	v_or_b32_e32 v130, s5, v1
	v_readlane_b32 s5, v251, 33
	s_waitcnt lgkmcnt(1)
	s_nop 7
	v_add_f32_e32 v2, v2, v124
	v_mul_f32_e32 v2, v70, v2
	v_cvt_pk_bf16_f32 v2, v2, s0
	global_store_short v[68:69], v2, off sc1
	v_add_f32_e32 v2, v3, v125
	v_mul_f32_e32 v2, v71, v2
	v_cvt_pk_bf16_f32 v68, v2, s0
	v_lshlrev_b64 v[2:3], 11, v[130:131]
	v_lshl_add_u64 v[2:3], v[88:89], 0, v[2:3]
	global_store_short v[2:3], v68, off sc1
	v_add_f32_e32 v2, v4, v126
	v_mul_f32_e32 v2, v72, v2
	v_or_b32_e32 v130, s5, v1
	v_cvt_pk_bf16_f32 v4, v2, s0
	v_lshlrev_b64 v[2:3], 11, v[130:131]
	v_lshl_add_u64 v[2:3], v[88:89], 0, v[2:3]
	global_store_short v[2:3], v4, off sc1
	v_add_f32_e32 v2, v5, v127
	v_readlane_b32 s5, v251, 34
	v_mul_f32_e32 v2, v73, v2
	v_cvt_pk_bf16_f32 v4, v2, s0
	v_or_b32_e32 v130, s5, v1
	v_lshlrev_b64 v[2:3], 11, v[130:131]
	v_lshl_add_u64 v[2:3], v[88:89], 0, v[2:3]
	global_store_short v[2:3], v4, off sc1
	s_waitcnt lgkmcnt(0)
	v_add_f32_e32 v2, v6, v58
	v_readlane_b32 s5, v251, 35
	v_mul_f32_e32 v2, v74, v2
	v_cvt_pk_bf16_f32 v4, v2, s0
	v_or_b32_e32 v130, s5, v1
	v_lshlrev_b64 v[2:3], 11, v[130:131]
	v_lshl_add_u64 v[2:3], v[88:89], 0, v[2:3]
	global_store_short v[2:3], v4, off sc1
	v_add_f32_e32 v2, v7, v59
	v_readlane_b32 s5, v251, 36
	v_mul_f32_e32 v2, v75, v2
	v_cvt_pk_bf16_f32 v4, v2, s0
	v_or_b32_e32 v130, s5, v1
	v_lshlrev_b64 v[2:3], 11, v[130:131]
	v_lshl_add_u64 v[2:3], v[88:89], 0, v[2:3]
	global_store_short v[2:3], v4, off sc1
	v_add_f32_e32 v2, v8, v60
	v_readlane_b32 s5, v251, 37
	v_mul_f32_e32 v2, v76, v2
	v_cvt_pk_bf16_f32 v4, v2, s0
	v_or_b32_e32 v130, s5, v1
	v_lshlrev_b64 v[2:3], 11, v[130:131]
	v_lshl_add_u64 v[2:3], v[88:89], 0, v[2:3]
	global_store_short v[2:3], v4, off sc1
	v_add_f32_e32 v2, v9, v61
	v_mul_f32_e32 v2, v77, v2
	v_cvt_pk_bf16_f32 v8, v2, s0
	ds_read_b128 v[2:5], v94 offset:64
	v_readlane_b32 s5, v251, 38
	s_nop 1
	v_or_b32_e32 v130, s5, v1
	v_lshlrev_b64 v[6:7], 11, v[130:131]
	v_lshl_add_u64 v[6:7], v[88:89], 0, v[6:7]
	v_readlane_b32 s5, v251, 39
	global_store_short v[6:7], v8, off sc1
	ds_read_b128 v[6:9], v94 offset:96
	s_waitcnt lgkmcnt(1)
	v_add_f32_e32 v2, v10, v2
	v_or_b32_e32 v130, s5, v1
	v_mul_f32_e32 v2, v95, v2
	v_lshlrev_b64 v[58:59], 11, v[130:131]
	v_cvt_pk_bf16_f32 v2, v2, s0
	v_lshl_add_u64 v[58:59], v[88:89], 0, v[58:59]
	global_store_short v[58:59], v2, off sc1
	v_add_f32_e32 v2, v11, v3
	v_readlane_b32 s5, v251, 40
	v_mul_f32_e32 v2, v96, v2
	v_cvt_pk_bf16_f32 v10, v2, s0
	v_or_b32_e32 v130, s5, v1
	v_lshlrev_b64 v[2:3], 11, v[130:131]
	v_lshl_add_u64 v[2:3], v[88:89], 0, v[2:3]
	global_store_short v[2:3], v10, off sc1
	v_add_f32_e32 v2, v12, v4
	v_readlane_b32 s5, v251, 41
	v_mul_f32_e32 v2, v98, v2
	v_cvt_pk_bf16_f32 v4, v2, s0
	v_or_b32_e32 v130, s5, v1
	v_lshlrev_b64 v[2:3], 11, v[130:131]
	v_lshl_add_u64 v[2:3], v[88:89], 0, v[2:3]
	global_store_short v[2:3], v4, off sc1
	v_add_f32_e32 v2, v13, v5
	v_readlane_b32 s5, v251, 42
	v_mul_f32_e32 v2, v100, v2
	v_cvt_pk_bf16_f32 v4, v2, s0
	v_or_b32_e32 v130, s5, v1
	v_lshlrev_b64 v[2:3], 11, v[130:131]
	v_lshl_add_u64 v[2:3], v[88:89], 0, v[2:3]
	global_store_short v[2:3], v4, off sc1
	s_waitcnt lgkmcnt(0)
	v_add_f32_e32 v2, v14, v6
	v_readlane_b32 s5, v251, 43
	v_mul_f32_e32 v2, v102, v2
	v_cvt_pk_bf16_f32 v4, v2, s0
	v_or_b32_e32 v130, s5, v1
	v_lshlrev_b64 v[2:3], 11, v[130:131]
	v_lshl_add_u64 v[2:3], v[88:89], 0, v[2:3]
	global_store_short v[2:3], v4, off sc1
	v_add_f32_e32 v2, v15, v7
	v_readlane_b32 s5, v251, 44
	v_mul_f32_e32 v2, v104, v2
	v_cvt_pk_bf16_f32 v4, v2, s0
	v_or_b32_e32 v130, s5, v1
	v_lshlrev_b64 v[2:3], 11, v[130:131]
	v_lshl_add_u64 v[2:3], v[88:89], 0, v[2:3]
	global_store_short v[2:3], v4, off sc1
	v_add_f32_e32 v2, v16, v8
	v_readlane_b32 s5, v251, 45
	v_mul_f32_e32 v2, v106, v2
	v_cvt_pk_bf16_f32 v4, v2, s0
	v_or_b32_e32 v130, s5, v1
	v_lshlrev_b64 v[2:3], 11, v[130:131]
	v_lshl_add_u64 v[2:3], v[88:89], 0, v[2:3]
	global_store_short v[2:3], v4, off sc1
	v_add_f32_e32 v2, v17, v9
	v_readlane_b32 s5, v251, 46
	v_mul_f32_e32 v2, v110, v2
	v_cvt_pk_bf16_f32 v4, v2, s0
	v_or_b32_e32 v130, s5, v1
	v_lshlrev_b64 v[2:3], 11, v[130:131]
	v_lshl_add_u64 v[2:3], v[88:89], 0, v[2:3]
	global_store_short v[2:3], v4, off sc1
	v_or_b32_e32 v2, 64, v82
	v_mad_i64_i32 v[2:3], s[6:7], v2, s87, v[84:85]
	global_load_ushort v10, v[2:3], off
	v_or_b32_e32 v2, 0x41, v82
	v_mad_i64_i32 v[2:3], s[6:7], v2, s87, v[84:85]
	global_load_ushort v11, v[2:3], off
	v_or_b32_e32 v2, 0x42, v82
	v_mad_i64_i32 v[2:3], s[6:7], v2, s87, v[84:85]
	global_load_ushort v12, v[2:3], off
	v_or_b32_e32 v2, 0x43, v82
	v_mad_i64_i32 v[2:3], s[6:7], v2, s87, v[84:85]
	global_load_ushort v13, v[2:3], off
	v_or_b32_e32 v2, 0x48, v82
	v_or_b32_e32 v4, 0x49, v82
	v_mad_i64_i32 v[2:3], s[6:7], v2, s87, v[84:85]
	v_mad_i64_i32 v[4:5], s[6:7], v4, s87, v[84:85]
	v_or_b32_e32 v6, 0x4a, v82
	v_or_b32_e32 v8, 0x4b, v82
	v_mad_i64_i32 v[6:7], s[6:7], v6, s87, v[84:85]
	v_mad_i64_i32 v[8:9], s[6:7], v8, s87, v[84:85]
	global_load_ushort v2, v[2:3], off
	s_nop 0
	global_load_ushort v3, v[4:5], off
	s_nop 0
	global_load_ushort v4, v[6:7], off
	global_load_ushort v5, v[8:9], off
	v_readlane_b32 s5, v251, 47
	s_waitcnt vmcnt(7)
	v_lshlrev_b32_e32 v6, 16, v10
	v_fma_f32 v7, |v6|, s92, 1.0
	v_rcp_f32_e32 v7, v7
	v_mul_f32_e32 v9, v6, v6
	v_mul_f32_e32 v9, 0xbf38aa3b, v9
	v_exp_f32_e32 v9, v9
	v_fmamk_f32 v8, v7, 0x3f07dc22, v236
	v_fmaak_f32 v8, v7, v8, 0x3f35f0e3
	v_fmaak_f32 v8, v7, v8, 0xbe11a98e
	v_fmaak_f32 v8, v7, v8, 0x3e027906
	v_mul_f32_e32 v7, v7, v8
	v_mul_f32_e32 v7, v9, v7
	v_mul_f32_e32 v8, v7, v6
	v_fma_f32 v7, -v7, v6, v6
	v_cmp_gt_f32_e32 vcc, 0, v6
	s_waitcnt vmcnt(6)
	v_lshlrev_b32_e32 v6, 16, v11
	v_mul_f32_e32 v9, v6, v6
	v_cndmask_b32_e32 v83, v7, v8, vcc
	v_fma_f32 v7, |v6|, s92, 1.0
	v_rcp_f32_e32 v7, v7
	v_mul_f32_e32 v9, 0xbf38aa3b, v9
	v_exp_f32_e32 v9, v9
	v_cmp_gt_f32_e32 vcc, 0, v6
	v_fmamk_f32 v8, v7, 0x3f07dc22, v236
	v_fmaak_f32 v8, v7, v8, 0x3f35f0e3
	v_fmaak_f32 v8, v7, v8, 0xbe11a98e
	v_fmaak_f32 v8, v7, v8, 0x3e027906
	v_mul_f32_e32 v7, v7, v8
	v_mul_f32_e32 v7, v9, v7
	v_mul_f32_e32 v8, v7, v6
	v_fma_f32 v7, -v7, v6, v6
	s_waitcnt vmcnt(5)
	v_lshlrev_b32_e32 v6, 16, v12
	v_cndmask_b32_e32 v95, v7, v8, vcc
	v_fma_f32 v7, |v6|, s92, 1.0
	v_rcp_f32_e32 v7, v7
	v_mul_f32_e32 v9, v6, v6
	v_mul_f32_e32 v9, 0xbf38aa3b, v9
	v_exp_f32_e32 v9, v9
	v_fmamk_f32 v8, v7, 0x3f07dc22, v236
	v_fmaak_f32 v8, v7, v8, 0x3f35f0e3
	v_fmaak_f32 v8, v7, v8, 0xbe11a98e
	v_fmaak_f32 v8, v7, v8, 0x3e027906
	v_mul_f32_e32 v7, v7, v8
	v_mul_f32_e32 v7, v9, v7
	v_mul_f32_e32 v8, v7, v6
	v_fma_f32 v7, -v7, v6, v6
	v_cmp_gt_f32_e32 vcc, 0, v6
	s_waitcnt vmcnt(4)
	v_lshlrev_b32_e32 v6, 16, v13
	v_mul_f32_e32 v9, v6, v6
	v_cndmask_b32_e32 v96, v7, v8, vcc
	v_fma_f32 v7, |v6|, s92, 1.0
	v_rcp_f32_e32 v7, v7
	v_mul_f32_e32 v9, 0xbf38aa3b, v9
	v_exp_f32_e32 v9, v9
	s_waitcnt vmcnt(3)
	v_lshlrev_b32_e32 v2, 16, v2
	v_fmamk_f32 v8, v7, 0x3f07dc22, v236
	v_fmaak_f32 v8, v7, v8, 0x3f35f0e3
	v_fmaak_f32 v8, v7, v8, 0xbe11a98e
	v_fmaak_f32 v8, v7, v8, 0x3e027906
	v_mul_f32_e32 v7, v7, v8
	v_mul_f32_e32 v7, v9, v7
	v_mul_f32_e32 v8, v7, v6
	v_fma_f32 v7, -v7, v6, v6
	v_cmp_gt_f32_e32 vcc, 0, v6
	v_fma_f32 v6, |v2|, s92, 1.0
	v_rcp_f32_e32 v6, v6
	v_cndmask_b32_e32 v98, v7, v8, vcc
	v_mul_f32_e32 v8, v2, v2
	v_mul_f32_e32 v8, 0xbf38aa3b, v8
	v_fmamk_f32 v7, v6, 0x3f07dc22, v236
	v_fmaak_f32 v7, v6, v7, 0x3f35f0e3
	v_exp_f32_e32 v8, v8
	v_fmaak_f32 v7, v6, v7, 0xbe11a98e
	v_fmaak_f32 v7, v6, v7, 0x3e027906
	v_mul_f32_e32 v6, v6, v7
	v_mul_f32_e32 v6, v8, v6
	v_mul_f32_e32 v7, v6, v2
	v_fma_f32 v6, -v6, v2, v2
	v_cmp_gt_f32_e32 vcc, 0, v2
	s_waitcnt vmcnt(2)
	v_lshlrev_b32_e32 v2, 16, v3
	v_fma_f32 v3, |v2|, s92, 1.0
	v_rcp_f32_e32 v3, v3
	v_cndmask_b32_e32 v100, v6, v7, vcc
	v_mul_f32_e32 v7, v2, v2
	v_mul_f32_e32 v7, 0xbf38aa3b, v7
	v_fmamk_f32 v6, v3, 0x3f07dc22, v236
	v_fmaak_f32 v6, v3, v6, 0x3f35f0e3
	v_exp_f32_e32 v7, v7
	v_fmaak_f32 v6, v3, v6, 0xbe11a98e
	v_fmaak_f32 v6, v3, v6, 0x3e027906
	v_mul_f32_e32 v3, v3, v6
	v_mul_f32_e32 v3, v7, v3
	v_mul_f32_e32 v6, v3, v2
	v_fma_f32 v3, -v3, v2, v2
	v_cmp_gt_f32_e32 vcc, 0, v2
	s_waitcnt vmcnt(1)
	v_lshlrev_b32_e32 v2, 16, v4
	v_or_b32_e32 v8, 0x5b, v82
	v_cndmask_b32_e32 v102, v3, v6, vcc
	v_fma_f32 v3, |v2|, s92, 1.0
	v_rcp_f32_e32 v3, v3
	v_mul_f32_e32 v6, v2, v2
	v_mul_f32_e32 v6, 0xbf38aa3b, v6
	v_exp_f32_e32 v6, v6
	v_fmamk_f32 v4, v3, 0x3f07dc22, v236
	v_fmaak_f32 v4, v3, v4, 0x3f35f0e3
	v_fmaak_f32 v4, v3, v4, 0xbe11a98e
	v_fmaak_f32 v4, v3, v4, 0x3e027906
	v_mul_f32_e32 v3, v3, v4
	v_mul_f32_e32 v3, v6, v3
	v_mul_f32_e32 v4, v3, v2
	v_fma_f32 v3, -v3, v2, v2
	v_cmp_gt_f32_e32 vcc, 0, v2
	s_waitcnt vmcnt(0)
	v_lshlrev_b32_e32 v2, 16, v5
	v_mul_f32_e32 v5, v2, v2
	v_cndmask_b32_e32 v104, v3, v4, vcc
	v_fma_f32 v3, |v2|, s92, 1.0
	v_rcp_f32_e32 v3, v3
	v_mul_f32_e32 v5, 0xbf38aa3b, v5
	v_exp_f32_e32 v5, v5
	v_cmp_gt_f32_e32 vcc, 0, v2
	v_fmamk_f32 v4, v3, 0x3f07dc22, v236
	v_fmaak_f32 v4, v3, v4, 0x3f35f0e3
	v_fmaak_f32 v4, v3, v4, 0xbe11a98e
	v_fmaak_f32 v4, v3, v4, 0x3e027906
	v_mul_f32_e32 v3, v3, v4
	v_mul_f32_e32 v3, v5, v3
	v_mul_f32_e32 v4, v3, v2
	v_fma_f32 v3, -v3, v2, v2
	v_or_b32_e32 v2, 0x50, v82
	v_cndmask_b32_e32 v106, v3, v4, vcc
	v_mad_i64_i32 v[2:3], s[6:7], v2, s87, v[84:85]
	global_load_ushort v10, v[2:3], off
	v_or_b32_e32 v2, 0x51, v82
	v_mad_i64_i32 v[2:3], s[6:7], v2, s87, v[84:85]
	global_load_ushort v11, v[2:3], off
	v_or_b32_e32 v2, 0x52, v82
	v_mad_i64_i32 v[2:3], s[6:7], v2, s87, v[84:85]
	global_load_ushort v12, v[2:3], off
	v_or_b32_e32 v2, 0x53, v82
	v_mad_i64_i32 v[2:3], s[6:7], v2, s87, v[84:85]
	global_load_ushort v13, v[2:3], off
	v_or_b32_e32 v2, 0x58, v82
	v_or_b32_e32 v4, 0x59, v82
	v_mad_i64_i32 v[2:3], s[6:7], v2, s87, v[84:85]
	v_mad_i64_i32 v[4:5], s[6:7], v4, s87, v[84:85]
	v_or_b32_e32 v6, 0x5a, v82
	v_mad_i64_i32 v[6:7], s[6:7], v6, s87, v[84:85]
	v_mad_i64_i32 v[8:9], s[6:7], v8, s87, v[84:85]
	global_load_ushort v2, v[2:3], off
	s_nop 0
	global_load_ushort v3, v[4:5], off
	s_nop 0
	global_load_ushort v4, v[6:7], off
	global_load_ushort v58, v[8:9], off
	v_or_b32_e32 v130, s5, v1
	v_readlane_b32 s5, v251, 48
	s_waitcnt vmcnt(7)
	v_lshlrev_b32_e32 v5, 16, v10
	v_fma_f32 v6, |v5|, s92, 1.0
	v_rcp_f32_e32 v6, v6
	v_mul_f32_e32 v8, v5, v5
	v_mul_f32_e32 v8, 0xbf38aa3b, v8
	v_exp_f32_e32 v8, v8
	v_fmamk_f32 v7, v6, 0x3f07dc22, v236
	v_fmaak_f32 v7, v6, v7, 0x3f35f0e3
	v_fmaak_f32 v7, v6, v7, 0xbe11a98e
	v_fmaak_f32 v7, v6, v7, 0x3e027906
	v_mul_f32_e32 v6, v6, v7
	v_mul_f32_e32 v6, v8, v6
	v_mul_f32_e32 v7, v6, v5
	v_fma_f32 v6, -v6, v5, v5
	v_cmp_gt_f32_e32 vcc, 0, v5
	s_waitcnt vmcnt(6)
	v_lshlrev_b32_e32 v5, 16, v11
	v_mul_f32_e32 v8, v5, v5
	v_cndmask_b32_e32 v110, v6, v7, vcc
	v_fma_f32 v6, |v5|, s92, 1.0
	v_rcp_f32_e32 v6, v6
	v_mul_f32_e32 v8, 0xbf38aa3b, v8
	v_exp_f32_e32 v8, v8
	v_cmp_gt_f32_e32 vcc, 0, v5
	v_fmamk_f32 v7, v6, 0x3f07dc22, v236
	v_fmaak_f32 v7, v6, v7, 0x3f35f0e3
	v_fmaak_f32 v7, v6, v7, 0xbe11a98e
	v_fmaak_f32 v7, v6, v7, 0x3e027906
	v_mul_f32_e32 v6, v6, v7
	v_mul_f32_e32 v6, v8, v6
	v_mul_f32_e32 v7, v6, v5
	v_fma_f32 v6, -v6, v5, v5
	s_waitcnt vmcnt(5)
	v_lshlrev_b32_e32 v5, 16, v12
	v_cndmask_b32_e32 v111, v6, v7, vcc
	v_fma_f32 v6, |v5|, s92, 1.0
	v_rcp_f32_e32 v6, v6
	v_mul_f32_e32 v8, v5, v5
	v_mul_f32_e32 v8, 0xbf38aa3b, v8
	v_exp_f32_e32 v8, v8
	v_fmamk_f32 v7, v6, 0x3f07dc22, v236
	v_fmaak_f32 v7, v6, v7, 0x3f35f0e3
	v_fmaak_f32 v7, v6, v7, 0xbe11a98e
	v_fmaak_f32 v7, v6, v7, 0x3e027906
	v_mul_f32_e32 v6, v6, v7
	v_mul_f32_e32 v6, v8, v6
	v_mul_f32_e32 v7, v6, v5
	v_fma_f32 v6, -v6, v5, v5
	v_cmp_gt_f32_e32 vcc, 0, v5
	s_waitcnt vmcnt(4)
	v_lshlrev_b32_e32 v5, 16, v13
	v_mul_f32_e32 v8, v5, v5
	v_cndmask_b32_e32 v112, v6, v7, vcc
	v_fma_f32 v6, |v5|, s92, 1.0
	v_rcp_f32_e32 v6, v6
	v_mul_f32_e32 v8, 0xbf38aa3b, v8
	v_exp_f32_e32 v8, v8
	s_waitcnt vmcnt(3)
	v_lshlrev_b32_e32 v2, 16, v2
	v_fmamk_f32 v7, v6, 0x3f07dc22, v236
	v_fmaak_f32 v7, v6, v7, 0x3f35f0e3
	v_fmaak_f32 v7, v6, v7, 0xbe11a98e
	v_fmaak_f32 v7, v6, v7, 0x3e027906
	v_mul_f32_e32 v6, v6, v7
	v_mul_f32_e32 v6, v8, v6
	v_mul_f32_e32 v7, v6, v5
	v_fma_f32 v6, -v6, v5, v5
	v_cmp_gt_f32_e32 vcc, 0, v5
	v_fma_f32 v5, |v2|, s92, 1.0
	v_rcp_f32_e32 v5, v5
	v_cndmask_b32_e32 v114, v6, v7, vcc
	v_mul_f32_e32 v7, v2, v2
	v_mul_f32_e32 v7, 0xbf38aa3b, v7
	v_fmamk_f32 v6, v5, 0x3f07dc22, v236
	v_fmaak_f32 v6, v5, v6, 0x3f35f0e3
	v_exp_f32_e32 v7, v7
	v_fmaak_f32 v6, v5, v6, 0xbe11a98e
	v_fmaak_f32 v6, v5, v6, 0x3e027906
	v_mul_f32_e32 v5, v5, v6
	v_mul_f32_e32 v5, v7, v5
	v_mul_f32_e32 v6, v5, v2
	v_fma_f32 v5, -v5, v2, v2
	v_cmp_gt_f32_e32 vcc, 0, v2
	s_waitcnt vmcnt(2)
	v_lshlrev_b32_e32 v2, 16, v3
	v_fma_f32 v3, |v2|, s92, 1.0
	v_rcp_f32_e32 v3, v3
	v_cndmask_b32_e32 v116, v5, v6, vcc
	v_mul_f32_e32 v6, v2, v2
	v_mul_f32_e32 v6, 0xbf38aa3b, v6
	v_fmamk_f32 v5, v3, 0x3f07dc22, v236
	v_fmaak_f32 v5, v3, v5, 0x3f35f0e3
	v_exp_f32_e32 v6, v6
	v_fmaak_f32 v5, v3, v5, 0xbe11a98e
	v_fmaak_f32 v5, v3, v5, 0x3e027906
	v_mul_f32_e32 v3, v3, v5
	v_mul_f32_e32 v3, v6, v3
	s_waitcnt vmcnt(1)
	v_lshlrev_b32_e32 v59, 16, v4
	v_mul_f32_e32 v5, v3, v2
	v_fma_f32 v3, -v3, v2, v2
	v_cmp_gt_f32_e32 vcc, 0, v2
	v_fma_f32 v2, |v59|, s92, 1.0
	v_rcp_f32_e32 v60, v2
	v_cndmask_b32_e32 v118, v3, v5, vcc
	v_mfma_f32_32x32x16_bf16 v[2:17], v[22:25], v[54:57], 0
	v_mul_f32_e32 v23, v59, v59
	v_fmamk_f32 v22, v60, 0x3f07dc22, v236
	v_mul_f32_e32 v23, 0xbf38aa3b, v23
	v_fmaak_f32 v22, v60, v22, 0x3f35f0e3
	v_exp_f32_e32 v23, v23
	v_fmaak_f32 v22, v60, v22, 0xbe11a98e
	v_fmaak_f32 v22, v60, v22, 0x3e027906
	v_mfma_f32_32x32x16_bf16 v[2:17], v[18:21], v[50:53], v[2:17]
	v_mul_f32_e32 v22, v60, v22
	v_mul_f32_e32 v22, v23, v22
	v_mul_f32_e32 v23, v22, v59
	v_fma_f32 v22, -v22, v59, v59
	v_cmp_gt_f32_e32 vcc, 0, v59
	s_nop 1
	v_cndmask_b32_e32 v24, v22, v23, vcc
	s_waitcnt vmcnt(0)
	v_lshlrev_b32_e32 v22, 16, v58
	v_fma_f32 v23, |v22|, s92, 1.0
	v_rcp_f32_e32 v23, v23
	v_mfma_f32_32x32x16_bf16 v[2:17], v[62:65], v[46:49], v[2:17]
	v_mul_f32_e32 v19, v22, v22
	v_mul_f32_e32 v19, 0xbf38aa3b, v19
	v_fmamk_f32 v18, v23, 0x3f07dc22, v236
	v_fmaak_f32 v18, v23, v18, 0x3f35f0e3
	v_exp_f32_e32 v19, v19
	v_fmaak_f32 v18, v23, v18, 0xbe11a98e
	v_fmaak_f32 v18, v23, v18, 0x3e027906
	v_mul_f32_e32 v18, v23, v18
	v_mul_f32_e32 v18, v19, v18
	v_mfma_f32_32x32x16_bf16 v[2:17], v[78:81], v[42:45], v[2:17]
	v_mul_f32_e32 v19, v18, v22
	v_fma_f32 v18, -v18, v22, v22
	v_cmp_gt_f32_e32 vcc, 0, v22
	v_lshlrev_b64 v[22:23], 11, v[130:131]
	v_lshl_add_u64 v[22:23], v[88:89], 0, v[22:23]
	v_cndmask_b32_e32 v25, v18, v19, vcc
	global_load_dwordx4 v[18:21], v[66:67], off offset:2048
	global_load_dwordx4 v[74:77], v[66:67], off offset:3072
	global_load_dwordx4 v[70:73], v[86:87], off
	s_nop 0
	global_load_dwordx4 v[66:69], v[86:87], off offset:1024
	global_load_dwordx4 v[62:65], v[86:87], off offset:2048
	global_load_dwordx4 v[58:61], v[86:87], off offset:3072
	ds_read_b128 v[124:127], v94 offset:128
	ds_read_b128 v[78:81], v94 offset:160
	v_or_b32_e32 v130, s5, v1
	v_readlane_b32 s5, v251, 49
	s_waitcnt lgkmcnt(1)
	v_add_f32_e32 v2, v2, v124
	v_mul_f32_e32 v2, v97, v2
	v_cvt_pk_bf16_f32 v2, v2, s0
	global_store_short v[22:23], v2, off sc1
	v_add_f32_e32 v2, v3, v125
	v_mul_f32_e32 v2, v99, v2
	v_cvt_pk_bf16_f32 v22, v2, s0
	v_lshlrev_b64 v[2:3], 11, v[130:131]
	v_lshl_add_u64 v[2:3], v[88:89], 0, v[2:3]
	global_store_short v[2:3], v22, off sc1
	v_add_f32_e32 v2, v4, v126
	v_mul_f32_e32 v2, v101, v2
	v_or_b32_e32 v130, s5, v1
	v_cvt_pk_bf16_f32 v4, v2, s0
	v_lshlrev_b64 v[2:3], 11, v[130:131]
	v_lshl_add_u64 v[2:3], v[88:89], 0, v[2:3]
	global_store_short v[2:3], v4, off sc1
	v_add_f32_e32 v2, v5, v127
	v_readlane_b32 s5, v251, 50
	v_mul_f32_e32 v2, v103, v2
	v_cvt_pk_bf16_f32 v4, v2, s0
	v_or_b32_e32 v130, s5, v1
	v_lshlrev_b64 v[2:3], 11, v[130:131]
	v_lshl_add_u64 v[2:3], v[88:89], 0, v[2:3]
	global_store_short v[2:3], v4, off sc1
	s_waitcnt lgkmcnt(0)
	v_add_f32_e32 v2, v6, v78
	v_readlane_b32 s5, v251, 51
	v_mul_f32_e32 v2, v105, v2
	v_cvt_pk_bf16_f32 v4, v2, s0
	v_or_b32_e32 v130, s5, v1
	v_lshlrev_b64 v[2:3], 11, v[130:131]
	v_lshl_add_u64 v[2:3], v[88:89], 0, v[2:3]
	global_store_short v[2:3], v4, off sc1
	v_add_f32_e32 v2, v7, v79
	v_readlane_b32 s5, v251, 52
	v_mul_f32_e32 v2, v107, v2
	v_cvt_pk_bf16_f32 v4, v2, s0
	v_or_b32_e32 v130, s5, v1
	v_lshlrev_b64 v[2:3], 11, v[130:131]
	v_lshl_add_u64 v[2:3], v[88:89], 0, v[2:3]
	global_store_short v[2:3], v4, off sc1
	v_add_f32_e32 v2, v8, v80
	v_readlane_b32 s5, v251, 53
	v_mul_f32_e32 v2, v108, v2
	v_cvt_pk_bf16_f32 v4, v2, s0
	v_or_b32_e32 v130, s5, v1
	v_lshlrev_b64 v[2:3], 11, v[130:131]
	v_lshl_add_u64 v[2:3], v[88:89], 0, v[2:3]
	global_store_short v[2:3], v4, off sc1
	v_add_f32_e32 v2, v9, v81
	v_mul_f32_e32 v2, v109, v2
	v_cvt_pk_bf16_f32 v8, v2, s0
	ds_read_b128 v[2:5], v94 offset:192
	v_readlane_b32 s5, v251, 54
	s_nop 1
	v_or_b32_e32 v130, s5, v1
	v_lshlrev_b64 v[6:7], 11, v[130:131]
	v_lshl_add_u64 v[6:7], v[88:89], 0, v[6:7]
	v_readlane_b32 s5, v251, 55
	global_store_short v[6:7], v8, off sc1
	ds_read_b128 v[6:9], v94 offset:224
	s_waitcnt lgkmcnt(1)
	v_add_f32_e32 v2, v10, v2
	v_or_b32_e32 v130, s5, v1
	v_mul_f32_e32 v2, v113, v2
	v_lshlrev_b64 v[22:23], 11, v[130:131]
	v_cvt_pk_bf16_f32 v2, v2, s0
	v_lshl_add_u64 v[22:23], v[88:89], 0, v[22:23]
	global_store_short v[22:23], v2, off sc1
	v_add_f32_e32 v2, v11, v3
	v_readlane_b32 s5, v251, 56
	v_mul_f32_e32 v2, v115, v2
	v_cvt_pk_bf16_f32 v10, v2, s0
	v_or_b32_e32 v130, s5, v1
	v_lshlrev_b64 v[2:3], 11, v[130:131]
	v_lshl_add_u64 v[2:3], v[88:89], 0, v[2:3]
	global_store_short v[2:3], v10, off sc1
	v_add_f32_e32 v2, v12, v4
	v_readlane_b32 s5, v251, 57
	v_mul_f32_e32 v2, v117, v2
	v_cvt_pk_bf16_f32 v4, v2, s0
	v_or_b32_e32 v130, s5, v1
	v_lshlrev_b64 v[2:3], 11, v[130:131]
	v_lshl_add_u64 v[2:3], v[88:89], 0, v[2:3]
	global_store_short v[2:3], v4, off sc1
	v_add_f32_e32 v2, v13, v5
	v_readlane_b32 s5, v251, 58
	v_mul_f32_e32 v2, v119, v2
	v_cvt_pk_bf16_f32 v4, v2, s0
	v_or_b32_e32 v130, s5, v1
	v_lshlrev_b64 v[2:3], 11, v[130:131]
	v_lshl_add_u64 v[2:3], v[88:89], 0, v[2:3]
	global_store_short v[2:3], v4, off sc1
	s_waitcnt lgkmcnt(0)
	v_add_f32_e32 v2, v14, v6
	v_readlane_b32 s5, v251, 59
	v_mul_f32_e32 v2, v120, v2
	v_cvt_pk_bf16_f32 v4, v2, s0
	v_or_b32_e32 v130, s5, v1
	v_lshlrev_b64 v[2:3], 11, v[130:131]
	v_lshl_add_u64 v[2:3], v[88:89], 0, v[2:3]
	global_store_short v[2:3], v4, off sc1
	v_add_f32_e32 v2, v15, v7
	v_readlane_b32 s5, v251, 60
	v_mul_f32_e32 v2, v121, v2
	v_cvt_pk_bf16_f32 v4, v2, s0
	v_or_b32_e32 v130, s5, v1
	v_lshlrev_b64 v[2:3], 11, v[130:131]
	v_lshl_add_u64 v[2:3], v[88:89], 0, v[2:3]
	global_store_short v[2:3], v4, off sc1
	v_add_f32_e32 v2, v16, v8
	v_readlane_b32 s5, v251, 61
	v_mul_f32_e32 v2, v122, v2
	v_cvt_pk_bf16_f32 v4, v2, s0
	v_or_b32_e32 v130, s5, v1
	v_lshlrev_b64 v[2:3], 11, v[130:131]
	v_lshl_add_u64 v[2:3], v[88:89], 0, v[2:3]
	global_store_short v[2:3], v4, off sc1
	v_add_f32_e32 v2, v17, v9
	v_readlane_b32 s5, v251, 62
	v_mul_f32_e32 v2, v123, v2
	v_cvt_pk_bf16_f32 v4, v2, s0
	v_or_b32_e32 v130, s5, v1
	v_lshlrev_b64 v[2:3], 11, v[130:131]
	v_lshl_add_u64 v[2:3], v[88:89], 0, v[2:3]
	global_store_short v[2:3], v4, off sc1
	v_or_b32_e32 v2, 0x60, v82
	v_mad_i64_i32 v[2:3], s[6:7], v2, s87, v[84:85]
	global_load_ushort v10, v[2:3], off
	v_or_b32_e32 v2, 0x61, v82
	v_mad_i64_i32 v[2:3], s[6:7], v2, s87, v[84:85]
	global_load_ushort v11, v[2:3], off
	v_or_b32_e32 v2, 0x62, v82
	v_mad_i64_i32 v[2:3], s[6:7], v2, s87, v[84:85]
	global_load_ushort v12, v[2:3], off
	v_or_b32_e32 v2, 0x63, v82
	v_mad_i64_i32 v[2:3], s[6:7], v2, s87, v[84:85]
	global_load_ushort v13, v[2:3], off
	v_or_b32_e32 v2, 0x68, v82
	v_or_b32_e32 v4, 0x69, v82
	v_mad_i64_i32 v[2:3], s[6:7], v2, s87, v[84:85]
	v_mad_i64_i32 v[4:5], s[6:7], v4, s87, v[84:85]
	v_or_b32_e32 v6, 0x6a, v82
	v_or_b32_e32 v8, 0x6b, v82
	v_mad_i64_i32 v[6:7], s[6:7], v6, s87, v[84:85]
	v_mad_i64_i32 v[8:9], s[6:7], v8, s87, v[84:85]
	global_load_ushort v2, v[2:3], off
	s_nop 0
	global_load_ushort v3, v[4:5], off
	s_nop 0
	global_load_ushort v4, v[6:7], off
	global_load_ushort v5, v[8:9], off
	v_readlane_b32 s5, v251, 63
	s_waitcnt vmcnt(7)
	v_lshlrev_b32_e32 v6, 16, v10
	v_fma_f32 v7, |v6|, s92, 1.0
	v_rcp_f32_e32 v7, v7
	v_mul_f32_e32 v9, v6, v6
	v_mul_f32_e32 v9, 0xbf38aa3b, v9
	v_exp_f32_e32 v9, v9
	v_fmamk_f32 v8, v7, 0x3f07dc22, v236
	v_fmaak_f32 v8, v7, v8, 0x3f35f0e3
	v_fmaak_f32 v8, v7, v8, 0xbe11a98e
	v_fmaak_f32 v8, v7, v8, 0x3e027906
	v_mul_f32_e32 v7, v7, v8
	v_mul_f32_e32 v7, v9, v7
	v_mul_f32_e32 v8, v7, v6
	v_fma_f32 v7, -v7, v6, v6
	v_cmp_gt_f32_e32 vcc, 0, v6
	s_waitcnt vmcnt(6)
	v_lshlrev_b32_e32 v6, 16, v11
	v_mul_f32_e32 v9, v6, v6
	v_cndmask_b32_e32 v78, v7, v8, vcc
	v_fma_f32 v7, |v6|, s92, 1.0
	v_rcp_f32_e32 v7, v7
	v_mul_f32_e32 v9, 0xbf38aa3b, v9
	v_exp_f32_e32 v9, v9
	v_cmp_gt_f32_e32 vcc, 0, v6
	v_fmamk_f32 v8, v7, 0x3f07dc22, v236
	v_fmaak_f32 v8, v7, v8, 0x3f35f0e3
	v_fmaak_f32 v8, v7, v8, 0xbe11a98e
	v_fmaak_f32 v8, v7, v8, 0x3e027906
	v_mul_f32_e32 v7, v7, v8
	v_mul_f32_e32 v7, v9, v7
	v_mul_f32_e32 v8, v7, v6
	v_fma_f32 v7, -v7, v6, v6
	s_waitcnt vmcnt(5)
	v_lshlrev_b32_e32 v6, 16, v12
	v_cndmask_b32_e32 v79, v7, v8, vcc
	v_fma_f32 v7, |v6|, s92, 1.0
	v_rcp_f32_e32 v7, v7
	v_mul_f32_e32 v9, v6, v6
	v_mul_f32_e32 v9, 0xbf38aa3b, v9
	v_exp_f32_e32 v9, v9
	v_fmamk_f32 v8, v7, 0x3f07dc22, v236
	v_fmaak_f32 v8, v7, v8, 0x3f35f0e3
	v_fmaak_f32 v8, v7, v8, 0xbe11a98e
	v_fmaak_f32 v8, v7, v8, 0x3e027906
	v_mul_f32_e32 v7, v7, v8
	v_mul_f32_e32 v7, v9, v7
	v_mul_f32_e32 v8, v7, v6
	v_fma_f32 v7, -v7, v6, v6
	v_cmp_gt_f32_e32 vcc, 0, v6
	s_waitcnt vmcnt(4)
	v_lshlrev_b32_e32 v6, 16, v13
	v_mul_f32_e32 v9, v6, v6
	v_cndmask_b32_e32 v80, v7, v8, vcc
	v_fma_f32 v7, |v6|, s92, 1.0
	v_rcp_f32_e32 v7, v7
	v_mul_f32_e32 v9, 0xbf38aa3b, v9
	v_exp_f32_e32 v9, v9
	s_waitcnt vmcnt(3)
	v_lshlrev_b32_e32 v2, 16, v2
	v_fmamk_f32 v8, v7, 0x3f07dc22, v236
	v_fmaak_f32 v8, v7, v8, 0x3f35f0e3
	v_fmaak_f32 v8, v7, v8, 0xbe11a98e
	v_fmaak_f32 v8, v7, v8, 0x3e027906
	v_mul_f32_e32 v7, v7, v8
	v_mul_f32_e32 v7, v9, v7
	v_mul_f32_e32 v8, v7, v6
	v_fma_f32 v7, -v7, v6, v6
	v_cmp_gt_f32_e32 vcc, 0, v6
	v_fma_f32 v6, |v2|, s92, 1.0
	v_rcp_f32_e32 v6, v6
	v_cndmask_b32_e32 v81, v7, v8, vcc
	v_mul_f32_e32 v8, v2, v2
	v_mul_f32_e32 v8, 0xbf38aa3b, v8
	v_fmamk_f32 v7, v6, 0x3f07dc22, v236
	v_fmaak_f32 v7, v6, v7, 0x3f35f0e3
	v_exp_f32_e32 v8, v8
	v_fmaak_f32 v7, v6, v7, 0xbe11a98e
	v_fmaak_f32 v7, v6, v7, 0x3e027906
	v_mul_f32_e32 v6, v6, v7
	v_mul_f32_e32 v6, v8, v6
	v_mul_f32_e32 v7, v6, v2
	v_fma_f32 v6, -v6, v2, v2
	v_cmp_gt_f32_e32 vcc, 0, v2
	s_waitcnt vmcnt(2)
	v_lshlrev_b32_e32 v2, 16, v3
	v_fma_f32 v3, |v2|, s92, 1.0
	v_rcp_f32_e32 v3, v3
	v_cndmask_b32_e32 v86, v6, v7, vcc
	v_mul_f32_e32 v7, v2, v2
	v_mul_f32_e32 v7, 0xbf38aa3b, v7
	v_fmamk_f32 v6, v3, 0x3f07dc22, v236
	v_fmaak_f32 v6, v3, v6, 0x3f35f0e3
	v_exp_f32_e32 v7, v7
	v_fmaak_f32 v6, v3, v6, 0xbe11a98e
	v_fmaak_f32 v6, v3, v6, 0x3e027906
	v_mul_f32_e32 v3, v3, v6
	v_mul_f32_e32 v3, v7, v3
	v_mul_f32_e32 v6, v3, v2
	v_fma_f32 v3, -v3, v2, v2
	v_cmp_gt_f32_e32 vcc, 0, v2
	s_waitcnt vmcnt(1)
	v_lshlrev_b32_e32 v2, 16, v4
	v_or_b32_e32 v8, 0x7b, v82
	v_cndmask_b32_e32 v87, v3, v6, vcc
	v_fma_f32 v3, |v2|, s92, 1.0
	v_rcp_f32_e32 v3, v3
	v_mul_f32_e32 v6, v2, v2
	v_mul_f32_e32 v6, 0xbf38aa3b, v6
	v_exp_f32_e32 v6, v6
	v_fmamk_f32 v4, v3, 0x3f07dc22, v236
	v_fmaak_f32 v4, v3, v4, 0x3f35f0e3
	v_fmaak_f32 v4, v3, v4, 0xbe11a98e
	v_fmaak_f32 v4, v3, v4, 0x3e027906
	v_mul_f32_e32 v3, v3, v4
	v_mul_f32_e32 v3, v6, v3
	v_mul_f32_e32 v4, v3, v2
	v_fma_f32 v3, -v3, v2, v2
	v_cmp_gt_f32_e32 vcc, 0, v2
	s_waitcnt vmcnt(0)
	v_lshlrev_b32_e32 v2, 16, v5
	v_mul_f32_e32 v5, v2, v2
	v_cndmask_b32_e32 v97, v3, v4, vcc
	v_fma_f32 v3, |v2|, s92, 1.0
	v_rcp_f32_e32 v3, v3
	v_mul_f32_e32 v5, 0xbf38aa3b, v5
	v_exp_f32_e32 v5, v5
	v_cmp_gt_f32_e32 vcc, 0, v2
	v_fmamk_f32 v4, v3, 0x3f07dc22, v236
	v_fmaak_f32 v4, v3, v4, 0x3f35f0e3
	v_fmaak_f32 v4, v3, v4, 0xbe11a98e
	v_fmaak_f32 v4, v3, v4, 0x3e027906
	v_mul_f32_e32 v3, v3, v4
	v_mul_f32_e32 v3, v5, v3
	v_mul_f32_e32 v4, v3, v2
	v_fma_f32 v3, -v3, v2, v2
	v_or_b32_e32 v2, 0x70, v82
	v_cndmask_b32_e32 v99, v3, v4, vcc
	v_mad_i64_i32 v[2:3], s[6:7], v2, s87, v[84:85]
	global_load_ushort v10, v[2:3], off
	v_or_b32_e32 v2, 0x71, v82
	v_mad_i64_i32 v[2:3], s[6:7], v2, s87, v[84:85]
	global_load_ushort v11, v[2:3], off
	v_or_b32_e32 v2, 0x72, v82
	v_mad_i64_i32 v[2:3], s[6:7], v2, s87, v[84:85]
	global_load_ushort v12, v[2:3], off
	v_or_b32_e32 v2, 0x73, v82
	v_mad_i64_i32 v[2:3], s[6:7], v2, s87, v[84:85]
	global_load_ushort v13, v[2:3], off
	v_or_b32_e32 v2, 0x78, v82
	v_or_b32_e32 v4, 0x79, v82
	v_mad_i64_i32 v[2:3], s[6:7], v2, s87, v[84:85]
	v_mad_i64_i32 v[4:5], s[6:7], v4, s87, v[84:85]
	v_or_b32_e32 v6, 0x7a, v82
	v_mad_i64_i32 v[6:7], s[6:7], v6, s87, v[84:85]
	v_mad_i64_i32 v[8:9], s[6:7], v8, s87, v[84:85]
	global_load_ushort v2, v[2:3], off
	s_nop 0
	global_load_ushort v3, v[4:5], off
	s_nop 0
	global_load_ushort v4, v[6:7], off
	global_load_ushort v5, v[8:9], off
	v_or_b32_e32 v130, s5, v1
	v_readlane_b32 s5, v252, 0
	v_readlane_b32 s6, v250, 27
	v_readlane_b32 s7, v250, 28
	s_waitcnt vmcnt(7)
	v_lshlrev_b32_e32 v6, 16, v10
	v_fma_f32 v7, |v6|, s92, 1.0
	v_rcp_f32_e32 v7, v7
	v_mul_f32_e32 v9, v6, v6
	v_mul_f32_e32 v9, 0xbf38aa3b, v9
	v_exp_f32_e32 v9, v9
	v_fmamk_f32 v8, v7, 0x3f07dc22, v236
	v_fmaak_f32 v8, v7, v8, 0x3f35f0e3
	v_fmaak_f32 v8, v7, v8, 0xbe11a98e
	v_fmaak_f32 v8, v7, v8, 0x3e027906
	v_mul_f32_e32 v7, v7, v8
	v_mul_f32_e32 v7, v9, v7
	v_mul_f32_e32 v8, v7, v6
	v_fma_f32 v7, -v7, v6, v6
	v_cmp_gt_f32_e32 vcc, 0, v6
	s_waitcnt vmcnt(6)
	v_lshlrev_b32_e32 v6, 16, v11
	v_mul_f32_e32 v9, v6, v6
	v_cndmask_b32_e32 v82, v7, v8, vcc
	v_fma_f32 v7, |v6|, s92, 1.0
	v_rcp_f32_e32 v7, v7
	v_mul_f32_e32 v9, 0xbf38aa3b, v9
	v_exp_f32_e32 v9, v9
	v_cmp_gt_f32_e32 vcc, 0, v6
	v_fmamk_f32 v8, v7, 0x3f07dc22, v236
	v_fmaak_f32 v8, v7, v8, 0x3f35f0e3
	v_fmaak_f32 v8, v7, v8, 0xbe11a98e
	v_fmaak_f32 v8, v7, v8, 0x3e027906
	v_mul_f32_e32 v7, v7, v8
	v_mul_f32_e32 v7, v9, v7
	v_mul_f32_e32 v8, v7, v6
	v_fma_f32 v7, -v7, v6, v6
	s_waitcnt vmcnt(5)
	v_lshlrev_b32_e32 v6, 16, v12
	v_cndmask_b32_e32 v84, v7, v8, vcc
	v_fma_f32 v7, |v6|, s92, 1.0
	v_rcp_f32_e32 v7, v7
	v_mul_f32_e32 v9, v6, v6
	v_mul_f32_e32 v9, 0xbf38aa3b, v9
	v_exp_f32_e32 v9, v9
	v_fmamk_f32 v8, v7, 0x3f07dc22, v236
	v_fmaak_f32 v8, v7, v8, 0x3f35f0e3
	v_fmaak_f32 v8, v7, v8, 0xbe11a98e
	v_fmaak_f32 v8, v7, v8, 0x3e027906
	v_mul_f32_e32 v7, v7, v8
	v_mul_f32_e32 v7, v9, v7
	v_mul_f32_e32 v8, v7, v6
	v_fma_f32 v7, -v7, v6, v6
	v_cmp_gt_f32_e32 vcc, 0, v6
	s_waitcnt vmcnt(4)
	v_lshlrev_b32_e32 v6, 16, v13
	v_mul_f32_e32 v9, v6, v6
	v_cndmask_b32_e32 v85, v7, v8, vcc
	v_fma_f32 v7, |v6|, s92, 1.0
	v_rcp_f32_e32 v7, v7
	v_mul_f32_e32 v9, 0xbf38aa3b, v9
	v_exp_f32_e32 v9, v9
	s_waitcnt vmcnt(3)
	v_lshlrev_b32_e32 v2, 16, v2
	v_fmamk_f32 v8, v7, 0x3f07dc22, v236
	v_fmaak_f32 v8, v7, v8, 0x3f35f0e3
	v_fmaak_f32 v8, v7, v8, 0xbe11a98e
	v_fmaak_f32 v8, v7, v8, 0x3e027906
	v_mul_f32_e32 v7, v7, v8
	v_mul_f32_e32 v7, v9, v7
	v_mul_f32_e32 v8, v7, v6
	v_fma_f32 v7, -v7, v6, v6
	v_cmp_gt_f32_e32 vcc, 0, v6
	v_fma_f32 v6, |v2|, s92, 1.0
	v_rcp_f32_e32 v6, v6
	v_cndmask_b32_e32 v101, v7, v8, vcc
	v_mul_f32_e32 v8, v2, v2
	v_mul_f32_e32 v8, 0xbf38aa3b, v8
	v_fmamk_f32 v7, v6, 0x3f07dc22, v236
	v_fmaak_f32 v7, v6, v7, 0x3f35f0e3
	v_exp_f32_e32 v8, v8
	v_fmaak_f32 v7, v6, v7, 0xbe11a98e
	v_fmaak_f32 v7, v6, v7, 0x3e027906
	v_mul_f32_e32 v6, v6, v7
	v_mul_f32_e32 v6, v8, v6
	v_mul_f32_e32 v7, v6, v2
	v_fma_f32 v6, -v6, v2, v2
	v_cmp_gt_f32_e32 vcc, 0, v2
	s_waitcnt vmcnt(2)
	v_lshlrev_b32_e32 v2, 16, v3
	v_fma_f32 v3, |v2|, s92, 1.0
	v_rcp_f32_e32 v3, v3
	v_cndmask_b32_e32 v107, v6, v7, vcc
	v_mul_f32_e32 v7, v2, v2
	v_mul_f32_e32 v7, 0xbf38aa3b, v7
	v_fmamk_f32 v6, v3, 0x3f07dc22, v236
	v_fmaak_f32 v6, v3, v6, 0x3f35f0e3
	v_exp_f32_e32 v7, v7
	v_fmaak_f32 v6, v3, v6, 0xbe11a98e
	v_fmaak_f32 v6, v3, v6, 0x3e027906
	v_mul_f32_e32 v3, v3, v6
	v_mul_f32_e32 v3, v7, v3
	v_mul_f32_e32 v6, v3, v2
	v_fma_f32 v3, -v3, v2, v2
	v_cmp_gt_f32_e32 vcc, 0, v2
	s_waitcnt vmcnt(1)
	v_lshlrev_b32_e32 v2, 16, v4
	v_mfma_f32_32x32x16_bf16 v[8:23], v[18:21], v[54:57], 0
	v_cndmask_b32_e32 v108, v3, v6, vcc
	v_fma_f32 v3, |v2|, s92, 1.0
	v_rcp_f32_e32 v3, v3
	v_mul_f32_e32 v6, v2, v2
	v_mul_f32_e32 v6, 0xbf38aa3b, v6
	v_exp_f32_e32 v6, v6
	v_fmamk_f32 v4, v3, 0x3f07dc22, v236
	v_fmaak_f32 v4, v3, v4, 0x3f35f0e3
	v_fmaak_f32 v4, v3, v4, 0xbe11a98e
	v_fmaak_f32 v4, v3, v4, 0x3e027906
	v_mfma_f32_32x32x16_bf16 v[8:23], v[74:77], v[50:53], v[8:23]
	v_mul_f32_e32 v3, v3, v4
	v_mul_f32_e32 v3, v6, v3
	v_mul_f32_e32 v4, v3, v2
	v_fma_f32 v3, -v3, v2, v2
	v_cmp_gt_f32_e32 vcc, 0, v2
	s_waitcnt vmcnt(0)
	v_lshlrev_b32_e32 v2, 16, v5
	v_mul_f32_e32 v5, v2, v2
	v_cndmask_b32_e32 v109, v3, v4, vcc
	v_fma_f32 v3, |v2|, s92, 1.0
	v_rcp_f32_e32 v3, v3
	v_mfma_f32_32x32x16_bf16 v[8:23], v[70:73], v[46:49], v[8:23]
	v_mul_f32_e32 v5, 0xbf38aa3b, v5
	v_exp_f32_e32 v5, v5
	v_fmamk_f32 v4, v3, 0x3f07dc22, v236
	v_fmaak_f32 v4, v3, v4, 0x3f35f0e3
	v_fmaak_f32 v4, v3, v4, 0xbe11a98e
	v_fmaak_f32 v4, v3, v4, 0x3e027906
	v_mul_f32_e32 v3, v3, v4
	v_mul_f32_e32 v3, v5, v3
	v_mul_f32_e32 v4, v3, v2
	v_fma_f32 v3, -v3, v2, v2
	v_cmp_gt_f32_e32 vcc, 0, v2
	v_mfma_f32_32x32x16_bf16 v[8:23], v[66:69], v[42:45], v[8:23]
	s_nop 0
	v_cndmask_b32_e32 v113, v3, v4, vcc
	global_load_dwordx4 v[2:5], v[92:93], off offset:-4096
	global_load_dwordx4 v[66:69], v[90:91], off offset:1024
	global_load_dwordx4 v[70:73], v[90:91], off offset:2048
	s_and_b64 vcc, exec, s[6:7]
	v_mfma_f32_32x32x16_bf16 v[8:23], v[62:65], v[38:41], v[8:23]
	global_load_dwordx4 v[62:65], v[90:91], off offset:3072
	global_load_dwordx4 v[74:77], v[92:93], off
	global_load_dwordx4 v[120:123], v[92:93], off offset:1024
	global_load_dwordx4 v[124:127], v[92:93], off offset:2048
	s_nop 0
	global_load_dwordx4 v[90:93], v[92:93], off offset:3072
	ds_read_b128 v[132:135], v94 offset:256
	v_mfma_f32_32x32x16_bf16 v[8:23], v[58:61], v[34:37], v[8:23]
	ds_read_b128 v[58:61], v94 offset:288
	s_waitcnt lgkmcnt(1)
	s_nop 9
	v_add_f32_e32 v6, v8, v132
	v_mul_f32_e32 v6, v83, v6
	v_cvt_pk_bf16_f32 v8, v6, s0
	v_lshlrev_b64 v[6:7], 11, v[130:131]
	v_lshl_add_u64 v[6:7], v[88:89], 0, v[6:7]
	global_store_short v[6:7], v8, off sc1
	v_add_f32_e32 v6, v9, v133
	v_mul_f32_e32 v6, v95, v6
	v_or_b32_e32 v130, s5, v1
	v_cvt_pk_bf16_f32 v8, v6, s0
	v_lshlrev_b64 v[6:7], 11, v[130:131]
	v_lshl_add_u64 v[6:7], v[88:89], 0, v[6:7]
	global_store_short v[6:7], v8, off sc1
	v_add_f32_e32 v6, v10, v134
	v_readlane_b32 s5, v252, 1
	v_mul_f32_e32 v6, v96, v6
	v_cvt_pk_bf16_f32 v8, v6, s0
	v_or_b32_e32 v130, s5, v1
	v_lshlrev_b64 v[6:7], 11, v[130:131]
	v_lshl_add_u64 v[6:7], v[88:89], 0, v[6:7]
	global_store_short v[6:7], v8, off sc1
	v_add_f32_e32 v6, v11, v135
	v_readlane_b32 s5, v252, 2
	v_mul_f32_e32 v6, v98, v6
	v_cvt_pk_bf16_f32 v8, v6, s0
	v_or_b32_e32 v130, s5, v1
	v_lshlrev_b64 v[6:7], 11, v[130:131]
	v_lshl_add_u64 v[6:7], v[88:89], 0, v[6:7]
	global_store_short v[6:7], v8, off sc1
	s_waitcnt lgkmcnt(0)
	v_add_f32_e32 v6, v12, v58
	v_readlane_b32 s5, v252, 3
	v_mul_f32_e32 v6, v100, v6
	v_cvt_pk_bf16_f32 v8, v6, s0
	v_or_b32_e32 v130, s5, v1
	v_lshlrev_b64 v[6:7], 11, v[130:131]
	v_lshl_add_u64 v[6:7], v[88:89], 0, v[6:7]
	global_store_short v[6:7], v8, off sc1
	v_add_f32_e32 v6, v13, v59
	v_readlane_b32 s5, v252, 4
	v_mul_f32_e32 v6, v102, v6
	v_cvt_pk_bf16_f32 v8, v6, s0
	v_or_b32_e32 v130, s5, v1
	v_lshlrev_b64 v[6:7], 11, v[130:131]
	v_lshl_add_u64 v[6:7], v[88:89], 0, v[6:7]
	global_store_short v[6:7], v8, off sc1
	v_add_f32_e32 v6, v14, v60
	v_readlane_b32 s5, v252, 5
	v_mul_f32_e32 v6, v104, v6
	v_cvt_pk_bf16_f32 v8, v6, s0
	v_or_b32_e32 v130, s5, v1
	v_lshlrev_b64 v[6:7], 11, v[130:131]
	v_lshl_add_u64 v[6:7], v[88:89], 0, v[6:7]
	global_store_short v[6:7], v8, off sc1
	v_add_f32_e32 v6, v15, v61
	ds_read_b128 v[58:61], v94 offset:320
	ds_read_b128 v[102:105], v94 offset:352
	v_readlane_b32 s5, v252, 6
	v_mul_f32_e32 v6, v106, v6
	v_cvt_pk_bf16_f32 v8, v6, s0
	v_or_b32_e32 v130, s5, v1
	v_lshlrev_b64 v[6:7], 11, v[130:131]
	v_lshl_add_u64 v[6:7], v[88:89], 0, v[6:7]
	global_store_short v[6:7], v8, off sc1
	s_waitcnt lgkmcnt(1)
	v_add_f32_e32 v6, v16, v58
	v_readlane_b32 s5, v252, 7
	v_mul_f32_e32 v6, v110, v6
	v_cvt_pk_bf16_f32 v8, v6, s0
	v_or_b32_e32 v130, s5, v1
	v_lshlrev_b64 v[6:7], 11, v[130:131]
	v_lshl_add_u64 v[6:7], v[88:89], 0, v[6:7]
	global_store_short v[6:7], v8, off sc1
	v_add_f32_e32 v6, v17, v59
	v_mul_f32_e32 v58, v111, v6
	s_waitcnt vmcnt(16)
	v_mfma_f32_32x32x16_bf16 v[2:17], v[2:5], v[54:57], 0
	v_readlane_b32 s5, v252, 8
	v_add_f32_e32 v18, v18, v60
	v_mul_f32_e32 v18, v112, v18
	v_or_b32_e32 v130, s5, v1
	v_readlane_b32 s5, v252, 9
	v_lshlrev_b64 v[54:55], 11, v[130:131]
	v_cvt_pk_bf16_f32 v18, v18, s0
	s_waitcnt vmcnt(15)
	v_mfma_f32_32x32x16_bf16 v[2:17], v[66:69], v[50:53], v[2:17]
	v_or_b32_e32 v130, s5, v1
	v_lshlrev_b64 v[50:51], 11, v[130:131]
	v_lshl_add_u64 v[50:51], v[88:89], 0, v[50:51]
	global_store_short v[50:51], v18, off sc1
	v_add_f32_e32 v18, v19, v61
	v_readlane_b32 s5, v252, 10
	v_mul_f32_e32 v18, v114, v18
	s_waitcnt vmcnt(15)
	v_mfma_f32_32x32x16_bf16 v[2:17], v[70:73], v[46:49], v[2:17]
	v_or_b32_e32 v130, s5, v1
	v_cvt_pk_bf16_f32 v46, v18, s0
	v_lshlrev_b64 v[18:19], 11, v[130:131]
	v_lshl_add_u64 v[18:19], v[88:89], 0, v[18:19]
	global_store_short v[18:19], v46, off sc1
	s_waitcnt lgkmcnt(0)
	v_add_f32_e32 v18, v20, v102
	v_readlane_b32 s5, v252, 11
	s_waitcnt vmcnt(15)
	v_mfma_f32_32x32x16_bf16 v[2:17], v[62:65], v[42:45], v[2:17]
	v_mul_f32_e32 v18, v116, v18
	v_or_b32_e32 v130, s5, v1
	v_cvt_pk_bf16_f32 v20, v18, s0
	v_lshlrev_b64 v[18:19], 11, v[130:131]
	v_lshl_add_u64 v[18:19], v[88:89], 0, v[18:19]
	global_store_short v[18:19], v20, off sc1
	v_add_f32_e32 v18, v21, v103
	s_waitcnt vmcnt(15)
	v_mfma_f32_32x32x16_bf16 v[2:17], v[74:77], v[38:41], v[2:17]
	v_readlane_b32 s5, v252, 12
	v_mul_f32_e32 v18, v118, v18
	v_cvt_pk_bf16_f32 v20, v18, s0
	v_or_b32_e32 v130, s5, v1
	v_lshlrev_b64 v[18:19], 11, v[130:131]
	v_lshl_add_u64 v[18:19], v[88:89], 0, v[18:19]
	global_store_short v[18:19], v20, off sc1
	s_waitcnt vmcnt(15)
	v_mfma_f32_32x32x16_bf16 v[2:17], v[120:123], v[34:37], v[2:17]
	v_add_f32_e32 v18, v22, v104
	v_readlane_b32 s5, v252, 13
	v_mul_f32_e32 v18, v24, v18
	v_cvt_pk_bf16_f32 v20, v18, s0
	v_or_b32_e32 v130, s5, v1
	v_lshlrev_b64 v[18:19], 11, v[130:131]
	v_lshl_add_u64 v[18:19], v[88:89], 0, v[18:19]
	s_waitcnt vmcnt(14)
	v_mfma_f32_32x32x16_bf16 v[2:17], v[124:127], v[30:33], v[2:17]
	global_store_short v[18:19], v20, off sc1
	v_add_f32_e32 v18, v23, v105
	v_readlane_b32 s5, v252, 14
	v_mul_f32_e32 v18, v25, v18
	v_cvt_pk_bf16_f32 v20, v18, s0
	v_or_b32_e32 v130, s5, v1
	v_lshlrev_b64 v[18:19], 11, v[130:131]
	v_cvt_pk_bf16_f32 v56, v58, s0
	v_lshl_add_u64 v[54:55], v[88:89], 0, v[54:55]
	v_lshl_add_u64 v[18:19], v[88:89], 0, v[18:19]
	s_waitcnt vmcnt(14)
	v_mfma_f32_32x32x16_bf16 v[2:17], v[90:93], v[26:29], v[2:17]
	global_store_short v[54:55], v56, off sc1
	global_store_short v[18:19], v20, off sc1
	ds_read_b128 v[18:21], v94 offset:384
	ds_read_b128 v[22:25], v94 offset:416
	v_readlane_b32 s5, v252, 15
	s_waitcnt lgkmcnt(1)
	s_nop 5
	v_add_f32_e32 v2, v2, v18
	v_or_b32_e32 v130, s5, v1
	v_mul_f32_e32 v2, v78, v2
	v_lshlrev_b64 v[26:27], 11, v[130:131]
	v_cvt_pk_bf16_f32 v2, v2, s0
	v_lshl_add_u64 v[26:27], v[88:89], 0, v[26:27]
	global_store_short v[26:27], v2, off sc1
	v_add_f32_e32 v2, v3, v19
	v_readlane_b32 s5, v252, 16
	v_mul_f32_e32 v2, v79, v2
	v_cvt_pk_bf16_f32 v18, v2, s0
	v_or_b32_e32 v130, s5, v1
	v_lshlrev_b64 v[2:3], 11, v[130:131]
	v_lshl_add_u64 v[2:3], v[88:89], 0, v[2:3]
	global_store_short v[2:3], v18, off sc1
	v_add_f32_e32 v2, v4, v20
	v_readlane_b32 s5, v252, 17
	v_mul_f32_e32 v2, v80, v2
	v_cvt_pk_bf16_f32 v4, v2, s0
	v_or_b32_e32 v130, s5, v1
	v_lshlrev_b64 v[2:3], 11, v[130:131]
	v_lshl_add_u64 v[2:3], v[88:89], 0, v[2:3]
	global_store_short v[2:3], v4, off sc1
	v_add_f32_e32 v2, v5, v21
	v_readlane_b32 s5, v252, 18
	v_mul_f32_e32 v2, v81, v2
	v_cvt_pk_bf16_f32 v4, v2, s0
	v_or_b32_e32 v130, s5, v1
	v_lshlrev_b64 v[2:3], 11, v[130:131]
	v_lshl_add_u64 v[2:3], v[88:89], 0, v[2:3]
	global_store_short v[2:3], v4, off sc1
	s_waitcnt lgkmcnt(0)
	v_add_f32_e32 v2, v6, v22
	v_readlane_b32 s5, v252, 19
	v_mul_f32_e32 v2, v86, v2
	v_cvt_pk_bf16_f32 v4, v2, s0
	v_or_b32_e32 v130, s5, v1
	v_lshlrev_b64 v[2:3], 11, v[130:131]
	v_lshl_add_u64 v[2:3], v[88:89], 0, v[2:3]
	global_store_short v[2:3], v4, off sc1
	v_add_f32_e32 v2, v7, v23
	v_readlane_b32 s5, v252, 20
	v_mul_f32_e32 v2, v87, v2
	v_cvt_pk_bf16_f32 v4, v2, s0
	v_or_b32_e32 v130, s5, v1
	v_lshlrev_b64 v[2:3], 11, v[130:131]
	v_lshl_add_u64 v[2:3], v[88:89], 0, v[2:3]
	global_store_short v[2:3], v4, off sc1
	v_add_f32_e32 v2, v8, v24
	v_readlane_b32 s5, v252, 21
	v_mul_f32_e32 v2, v97, v2
	v_cvt_pk_bf16_f32 v4, v2, s0
	v_or_b32_e32 v130, s5, v1
	v_lshlrev_b64 v[2:3], 11, v[130:131]
	v_lshl_add_u64 v[2:3], v[88:89], 0, v[2:3]
	global_store_short v[2:3], v4, off sc1
	v_add_f32_e32 v2, v9, v25
	v_mul_f32_e32 v2, v99, v2
	v_cvt_pk_bf16_f32 v8, v2, s0
	ds_read_b128 v[2:5], v94 offset:448
	v_readlane_b32 s5, v252, 22
	s_nop 1
	v_or_b32_e32 v130, s5, v1
	v_lshlrev_b64 v[6:7], 11, v[130:131]
	v_lshl_add_u64 v[6:7], v[88:89], 0, v[6:7]
	v_readlane_b32 s5, v252, 23
	global_store_short v[6:7], v8, off sc1
	ds_read_b128 v[6:9], v94 offset:480
	s_waitcnt lgkmcnt(1)
	v_add_f32_e32 v2, v10, v2
	v_or_b32_e32 v130, s5, v1
	v_mul_f32_e32 v2, v82, v2
	v_lshlrev_b64 v[18:19], 11, v[130:131]
	v_cvt_pk_bf16_f32 v2, v2, s0
	v_lshl_add_u64 v[18:19], v[88:89], 0, v[18:19]
	global_store_short v[18:19], v2, off sc1
	v_add_f32_e32 v2, v11, v3
	v_readlane_b32 s5, v252, 24
	v_mul_f32_e32 v2, v84, v2
	v_cvt_pk_bf16_f32 v10, v2, s0
	v_or_b32_e32 v130, s5, v1
	v_lshlrev_b64 v[2:3], 11, v[130:131]
	v_lshl_add_u64 v[2:3], v[88:89], 0, v[2:3]
	global_store_short v[2:3], v10, off sc1
	v_add_f32_e32 v2, v12, v4
	v_readlane_b32 s5, v252, 25
	v_mul_f32_e32 v2, v85, v2
	v_cvt_pk_bf16_f32 v4, v2, s0
	v_or_b32_e32 v130, s5, v1
	v_lshlrev_b64 v[2:3], 11, v[130:131]
	v_lshl_add_u64 v[2:3], v[88:89], 0, v[2:3]
	global_store_short v[2:3], v4, off sc1
	v_add_f32_e32 v2, v13, v5
	v_readlane_b32 s5, v252, 26
	v_mul_f32_e32 v2, v101, v2
	v_cvt_pk_bf16_f32 v4, v2, s0
	v_or_b32_e32 v130, s5, v1
	v_lshlrev_b64 v[2:3], 11, v[130:131]
	v_lshl_add_u64 v[2:3], v[88:89], 0, v[2:3]
	global_store_short v[2:3], v4, off sc1
	s_waitcnt lgkmcnt(0)
	v_add_f32_e32 v2, v14, v6
	v_readlane_b32 s5, v252, 27
	v_mul_f32_e32 v2, v107, v2
	v_cvt_pk_bf16_f32 v4, v2, s0
	v_or_b32_e32 v130, s5, v1
	v_lshlrev_b64 v[2:3], 11, v[130:131]
	v_lshl_add_u64 v[2:3], v[88:89], 0, v[2:3]
	global_store_short v[2:3], v4, off sc1
	v_add_f32_e32 v2, v15, v7
	v_readlane_b32 s5, v252, 28
	v_mul_f32_e32 v2, v108, v2
	v_cvt_pk_bf16_f32 v4, v2, s0
	v_or_b32_e32 v130, s5, v1
	v_lshlrev_b64 v[2:3], 11, v[130:131]
	v_lshl_add_u64 v[2:3], v[88:89], 0, v[2:3]
	global_store_short v[2:3], v4, off sc1
	v_add_f32_e32 v2, v16, v8
	v_readlane_b32 s5, v252, 29
	v_mul_f32_e32 v2, v109, v2
	v_cvt_pk_bf16_f32 v4, v2, s0
	v_or_b32_e32 v130, s5, v1
	v_lshlrev_b64 v[2:3], 11, v[130:131]
	v_lshl_add_u64 v[2:3], v[88:89], 0, v[2:3]
	global_store_short v[2:3], v4, off sc1
	v_add_f32_e32 v2, v17, v9
	v_readlane_b32 s5, v252, 30
	v_mul_f32_e32 v2, v113, v2
	v_cvt_pk_bf16_f32 v4, v2, s0
	v_or_b32_e32 v130, s5, v1
	v_lshlrev_b64 v[2:3], 11, v[130:131]
	v_lshl_add_u64 v[2:3], v[88:89], 0, v[2:3]
	global_store_short v[2:3], v4, off sc1
	s_barrier
	s_cbranch_vccz .LBB0_314
	v_readlane_b32 s6, v253, 48
	v_mov_b32_e32 v1, v242
	v_readlane_b32 s7, v253, 49
	s_andn2_b64 vcc, exec, s[6:7]
	v_readfirstlane_b32 s5, v1
	s_cbranch_vccnz .LBB0_313
	s_load_dwordx8 s[44:51], s[0:1], 0x38
	v_mov_b32_e32 v2, 2
	v_lshlrev_b32_sdwa v130, v2, v1 dst_sel:DWORD dst_unused:UNUSED_PAD src0_sel:DWORD src1_sel:BYTE_0
	v_readlane_b32 s8, v254, 39
	v_readlane_b32 s9, v254, 40
	s_waitcnt lgkmcnt(0)
	v_lshl_add_u64 v[2:3], s[44:45], 0, v[130:131]
	v_lshl_add_u64 v[4:5], v[2:3], 0, s[62:63]
	global_load_dword v42, v[4:5], off
	v_lshl_add_u64 v[4:5], v[2:3], 0, s[8:9]
	v_readlane_b32 s8, v254, 41
	v_readlane_b32 s9, v254, 42
	global_load_dword v43, v[4:5], off
	s_ashr_i32 s6, s5, 6
	v_lshl_add_u64 v[4:5], v[2:3], 0, s[8:9]
	v_readlane_b32 s8, v254, 43
	v_readlane_b32 s9, v254, 44
	global_load_dword v45, v[4:5], off
	v_mov_b32_e32 v10, s46
	v_lshl_add_u64 v[4:5], v[2:3], 0, s[8:9]
	v_readlane_b32 s8, v254, 45
	v_readlane_b32 s9, v254, 46
	global_load_dword v47, v[4:5], off
	v_mov_b32_e32 v11, s47
	v_lshl_add_u64 v[4:5], v[2:3], 0, s[8:9]
	v_readlane_b32 s8, v254, 47
	v_readlane_b32 s9, v254, 48
	global_load_dword v49, v[4:5], off
	v_readlane_b32 s57, v253, 32
	v_lshl_add_u64 v[4:5], v[2:3], 0, s[8:9]
	v_readlane_b32 s8, v254, 49
	v_readlane_b32 s9, v254, 50
	global_load_dword v51, v[4:5], off
	s_mov_b32 s58, s2
	v_lshl_add_u64 v[4:5], v[2:3], 0, s[8:9]
	v_readlane_b32 s8, v254, 51
	v_readlane_b32 s9, v254, 52
	global_load_dword v53, v[4:5], off
	s_waitcnt vmcnt(5)
	v_mov_b32_e32 v44, v43
	v_lshl_add_u64 v[4:5], v[2:3], 0, s[8:9]
	v_readlane_b32 s8, v254, 53
	v_readlane_b32 s9, v254, 54
	global_load_dword v55, v[4:5], off
	s_waitcnt vmcnt(5)
	v_mov_b32_e32 v46, v45
	v_lshl_add_u64 v[4:5], v[2:3], 0, s[8:9]
	v_readlane_b32 s8, v254, 55
	v_readlane_b32 s9, v254, 56
	global_load_dword v57, v[4:5], off
	s_waitcnt vmcnt(5)
	v_mov_b32_e32 v48, v47
	v_lshl_add_u64 v[4:5], v[2:3], 0, s[8:9]
	v_readlane_b32 s8, v254, 57
	v_readlane_b32 s9, v254, 58
	global_load_dword v59, v[4:5], off
	s_waitcnt vmcnt(5)
	v_mov_b32_e32 v50, v49
	v_lshl_add_u64 v[4:5], v[2:3], 0, s[8:9]
	v_readlane_b32 s8, v254, 59
	v_readlane_b32 s9, v254, 60
	global_load_dword v61, v[4:5], off
	s_waitcnt vmcnt(5)
	v_mov_b32_e32 v52, v51
	v_lshl_add_u64 v[4:5], v[2:3], 0, s[8:9]
	v_readlane_b32 s8, v254, 61
	v_readlane_b32 s9, v254, 62
	global_load_dword v63, v[4:5], off
	s_waitcnt vmcnt(5)
	v_mov_b32_e32 v54, v53
	v_lshl_add_u64 v[4:5], v[2:3], 0, s[8:9]
	v_readlane_b32 s8, v254, 63
	v_readlane_b32 s9, v255, 0
	global_load_dword v65, v[4:5], off
	s_waitcnt vmcnt(5)
	v_mov_b32_e32 v56, v55
	v_lshl_add_u64 v[4:5], v[2:3], 0, s[8:9]
	v_readlane_b32 s8, v255, 1
	v_readlane_b32 s9, v255, 2
	global_load_dword v67, v[4:5], off
	s_waitcnt vmcnt(5)
	v_mov_b32_e32 v58, v57
	v_lshl_add_u64 v[4:5], v[2:3], 0, s[8:9]
	v_readlane_b32 s8, v255, 3
	v_readlane_b32 s9, v255, 4
	global_load_dword v69, v[4:5], off
	s_waitcnt vmcnt(5)
	v_mov_b32_e32 v60, v59
	v_lshl_add_u64 v[4:5], v[2:3], 0, s[8:9]
	v_readlane_b32 s8, v255, 5
	v_readlane_b32 s9, v255, 6
	global_load_dword v71, v[4:5], off
	s_waitcnt vmcnt(5)
	v_mov_b32_e32 v62, v61
	v_lshl_add_u64 v[4:5], v[2:3], 0, s[8:9]
	v_readlane_b32 s8, v255, 7
	v_readlane_b32 s9, v255, 8
	global_load_dword v73, v[4:5], off
	s_waitcnt vmcnt(5)
	v_mov_b32_e32 v64, v63
	v_lshl_add_u64 v[4:5], v[2:3], 0, s[8:9]
	v_readlane_b32 s8, v255, 9
	v_readlane_b32 s9, v255, 10
	global_load_dword v75, v[4:5], off
	s_waitcnt vmcnt(5)
	v_mov_b32_e32 v66, v65
	v_lshl_add_u64 v[4:5], v[2:3], 0, s[8:9]
	v_readlane_b32 s8, v255, 11
	v_readlane_b32 s9, v255, 12
	global_load_dword v77, v[4:5], off
	s_waitcnt vmcnt(5)
	v_mov_b32_e32 v68, v67
	v_lshl_add_u64 v[4:5], v[2:3], 0, s[8:9]
	v_readlane_b32 s8, v255, 13
	v_readlane_b32 s9, v255, 14
	global_load_dword v79, v[4:5], off
	s_waitcnt vmcnt(5)
	v_mov_b32_e32 v70, v69
	v_lshl_add_u64 v[4:5], v[2:3], 0, s[8:9]
	v_readlane_b32 s8, v255, 15
	v_readlane_b32 s9, v255, 16
	global_load_dword v81, v[4:5], off
	s_waitcnt vmcnt(5)
	v_mov_b32_e32 v72, v71
	v_lshl_add_u64 v[4:5], v[2:3], 0, s[8:9]
	v_readlane_b32 s8, v255, 17
	v_readlane_b32 s9, v255, 18
	global_load_dword v83, v[4:5], off
	s_waitcnt vmcnt(5)
	v_mov_b32_e32 v74, v73
	v_lshl_add_u64 v[4:5], v[2:3], 0, s[8:9]
	v_readlane_b32 s8, v255, 19
	v_readlane_b32 s9, v255, 20
	global_load_dword v85, v[4:5], off
	s_waitcnt vmcnt(5)
	v_mov_b32_e32 v76, v75
	v_lshl_add_u64 v[4:5], v[2:3], 0, s[8:9]
	v_readlane_b32 s8, v255, 21
	v_readlane_b32 s9, v255, 22
	global_load_dword v87, v[4:5], off
	s_waitcnt vmcnt(5)
	v_mov_b32_e32 v78, v77
	v_lshl_add_u64 v[4:5], v[2:3], 0, s[8:9]
	v_readlane_b32 s8, v254, 37
	v_readlane_b32 s9, v254, 38
	global_load_dword v89, v[4:5], off
	s_waitcnt vmcnt(5)
	v_mov_b32_e32 v80, v79
	v_lshl_add_u64 v[4:5], v[2:3], 0, s[8:9]
	v_readlane_b32 s8, v254, 35
	v_readlane_b32 s9, v254, 36
	global_load_dword v91, v[4:5], off
	s_waitcnt vmcnt(5)
	v_mov_b32_e32 v82, v81
	v_lshl_add_u64 v[4:5], v[2:3], 0, s[8:9]
	v_readlane_b32 s8, v255, 23
	v_readlane_b32 s9, v255, 24
	global_load_dword v93, v[4:5], off
	s_waitcnt vmcnt(5)
	v_mov_b32_e32 v84, v83
	v_lshl_add_u64 v[4:5], v[2:3], 0, s[8:9]
	global_load_dword v95, v[4:5], off
	v_lshl_add_u64 v[4:5], v[2:3], 0, s[68:69]
	s_lshl_b64 s[8:9], s[84:85], 2
	global_load_dword v97, v[4:5], off
	v_lshl_add_u64 v[4:5], v[2:3], 0, s[94:95]
	v_lshl_add_u64 v[2:3], v[2:3], 0, s[88:89]
	s_add_u32 s10, s48, s8
	global_load_dword v99, v[4:5], off
	global_load_dword v101, v[2:3], off
	s_addc_u32 s11, s49, s9
	v_lshlrev_b32_e32 v2, 2, v1
	v_and_b32_e32 v12, 0xfc, v2
	s_add_u32 s8, s50, s8
	v_lshlrev_b32_e32 v6, 2, v12
	s_addc_u32 s9, s51, s9
	s_min_i32 s5, s6, 5
	global_load_dwordx4 v[2:5], v6, s[10:11]
	s_addk_i32 s5, 0x58
	v_readlane_b32 s10, v250, 29
	s_add_i32 s7, s5, s10
	v_lshlrev_b32_e32 v130, 1, v12
	s_max_i32 s7, s7, 0
	v_readlane_b32 s11, v250, 30
	s_min_i32 s40, s6, 13
	v_lshl_add_u64 v[102:103], s[80:81], 0, v[130:131]
	s_add_i32 s7, s7, s11
	s_addk_i32 s40, 0x50
	global_load_dwordx4 v[6:9], v6, s[8:9]
	v_mad_u64_u32 v[12:13], s[8:9], s7, v238, v[102:103]
	s_add_i32 s7, s40, s10
	s_max_i32 s7, s7, 0
	s_min_i32 s41, s6, 21
	s_add_i32 s7, s7, s11
	s_addk_i32 s41, 0x48
	global_load_dwordx2 v[106:107], v[12:13], off offset:1536
	global_load_dwordx2 v[104:105], v[12:13], off offset:1024
	v_mad_u64_u32 v[12:13], s[8:9], s7, v238, v[102:103]
	s_add_i32 s7, s41, s10
	s_max_i32 s7, s7, 0
	s_min_i32 s44, s6, 29
	s_add_i32 s7, s7, s11
	s_add_i32 s44, s44, 64
	global_load_dwordx2 v[112:113], v[12:13], off offset:1536
	global_load_dwordx2 v[110:111], v[12:13], off offset:1024
	v_mad_u64_u32 v[12:13], s[8:9], s7, v238, v[102:103]
	s_add_i32 s7, s44, s10
	s_max_i32 s7, s7, 0
	s_min_i32 s45, s6, 37
	s_add_i32 s7, s7, s11
	s_add_i32 s45, s45, 56
	global_load_dwordx2 v[116:117], v[12:13], off offset:1536
	global_load_dwordx2 v[114:115], v[12:13], off offset:1024
	v_mad_u64_u32 v[12:13], s[8:9], s7, v238, v[102:103]
	s_add_i32 s7, s45, s10
	s_max_i32 s7, s7, 0
	s_min_i32 s46, s6, 45
	s_add_i32 s7, s7, s11
	s_add_i32 s46, s46, 48
	global_load_dwordx2 v[120:121], v[12:13], off offset:1536
	global_load_dwordx2 v[118:119], v[12:13], off offset:1024
	v_mad_u64_u32 v[12:13], s[8:9], s7, v238, v[102:103]
	s_add_i32 s7, s46, s10
	s_max_i32 s7, s7, 0
	s_min_i32 s47, s6, 53
	s_add_i32 s7, s7, s11
	s_add_i32 s47, s47, 40
	global_load_dwordx2 v[124:125], v[12:13], off offset:1536
	global_load_dwordx2 v[122:123], v[12:13], off offset:1024
	v_mad_u64_u32 v[12:13], s[8:9], s7, v238, v[102:103]
	s_add_i32 s7, s47, s10
	s_max_i32 s7, s7, 0
	s_min_i32 s48, s6, 61
	s_add_i32 s7, s7, s11
	s_add_i32 s48, s48, 32
	global_load_dwordx2 v[128:129], v[12:13], off offset:1536
	global_load_dwordx2 v[126:127], v[12:13], off offset:1024
	v_mad_u64_u32 v[12:13], s[8:9], s7, v238, v[102:103]
	s_add_i32 s7, s48, s10
	s_max_i32 s7, s7, 0
	s_min_i32 s49, s6, 0x45
	s_add_i32 s7, s7, s11
	s_add_i32 s49, s49, 24
	global_load_dwordx2 v[134:135], v[12:13], off offset:1536
	global_load_dwordx2 v[132:133], v[12:13], off offset:1024
	v_mad_u64_u32 v[12:13], s[8:9], s7, v238, v[102:103]
	s_add_i32 s7, s49, s10
	s_max_i32 s7, s7, 0
	s_min_i32 s50, s6, 0x4d
	s_add_i32 s7, s7, s11
	s_add_i32 s50, s50, 16
	global_load_dwordx2 v[138:139], v[12:13], off offset:1536
	global_load_dwordx2 v[136:137], v[12:13], off offset:1024
	v_mad_u64_u32 v[12:13], s[8:9], s7, v238, v[102:103]
	s_add_i32 s7, s50, s10
	s_max_i32 s7, s7, 0
	s_min_i32 s51, s6, 0x55
	s_add_i32 s7, s7, s11
	s_add_i32 s51, s51, 8
	global_load_dwordx2 v[142:143], v[12:13], off offset:1536
	global_load_dwordx2 v[140:141], v[12:13], off offset:1024
	v_mad_u64_u32 v[12:13], s[8:9], s7, v238, v[102:103]
	s_add_i32 s7, s51, s10
	s_min_i32 s56, s6, 0x5d
	s_max_i32 s7, s7, 0
	s_add_i32 s6, s56, s10
	s_add_i32 s7, s7, s11
	s_max_i32 s6, s6, 0
	global_load_dwordx2 v[146:147], v[12:13], off offset:1536
	global_load_dwordx2 v[144:145], v[12:13], off offset:1024
	v_mad_u64_u32 v[12:13], s[8:9], s7, v238, v[102:103]
	s_add_i32 s6, s6, s11
	global_load_dwordx2 v[150:151], v[12:13], off offset:1536
	global_load_dwordx2 v[148:149], v[12:13], off offset:1024
	v_mad_u64_u32 v[12:13], s[6:7], s6, v238, v[102:103]
	global_load_dwordx2 v[154:155], v[12:13], off offset:1536
	global_load_dwordx2 v[152:153], v[12:13], off offset:1024
	v_or_b32_sdwa v12, v1, s84 dst_sel:DWORD dst_unused:UNUSED_PAD src0_sel:BYTE_0 src1_sel:DWORD
	v_ashrrev_i32_e32 v13, 31, v12
	v_lshl_add_u64 v[10:11], v[12:13], 2, v[10:11]
	global_load_dword v108, v[10:11], off
	s_waitcnt vmcnt(35)
	v_mov_b32_e32 v86, v85
	s_waitcnt vmcnt(34)
	v_mov_b32_e32 v88, v87
	s_waitcnt vmcnt(33)
	v_mov_b32_e32 v90, v89
	s_waitcnt vmcnt(32)
	v_mov_b32_e32 v92, v91
	s_waitcnt vmcnt(31)
	v_mov_b32_e32 v94, v93
	s_waitcnt vmcnt(30)
	v_mov_b32_e32 v96, v95
	s_waitcnt vmcnt(29)
	v_mov_b32_e32 v98, v97
	s_waitcnt vmcnt(28)
	v_mov_b32_e32 v100, v99
	s_branch .LBB0_289
.LBB0_288:
	s_add_i32 s59, s58, 0xffffff80
	s_cmpk_lt_i32 s59, 0x100
	s_cselect_b32 s7, s58, s59
	s_lshl_b32 s7, s7, 6
	s_and_b32 s8, s7, 0xfc0
	s_sub_i32 s10, s8, 30
	s_add_i32 s8, s10, s56
	s_and_b32 s7, s7, 0xfffff000
	s_max_i32 s8, s8, 0
	s_add_i32 s8, s8, s7
	v_and_b32_e32 v14, 0xff, v10
	v_mad_i64_i32 v[10:11], s[8:9], s8, v238, v[102:103]
	s_add_i32 s8, s10, s51
	s_max_i32 s8, s8, 0
	s_add_i32 s8, s8, s7
	v_mad_i64_i32 v[12:13], s[8:9], s8, v238, v[102:103]
	s_add_i32 s8, s10, s50
	s_max_i32 s8, s8, 0
	s_add_i32 s8, s8, s7
	s_waitcnt lgkmcnt(0)
	s_barrier
	global_load_dwordx2 v[152:153], v[10:11], off offset:1024
	global_load_dwordx2 v[154:155], v[10:11], off offset:1536
	global_load_dwordx2 v[148:149], v[12:13], off offset:1024
	global_load_dwordx2 v[150:151], v[12:13], off offset:1536
	v_mad_i64_i32 v[10:11], s[8:9], s8, v238, v[102:103]
	s_add_i32 s8, s10, s49
	s_max_i32 s8, s8, 0
	s_add_i32 s8, s8, s7
	v_mad_i64_i32 v[12:13], s[8:9], s8, v238, v[102:103]
	s_add_i32 s8, s10, s48
	s_max_i32 s8, s8, 0
	s_add_i32 s8, s8, s7
	global_load_dwordx2 v[144:145], v[10:11], off offset:1024
	global_load_dwordx2 v[146:147], v[10:11], off offset:1536
	global_load_dwordx2 v[140:141], v[12:13], off offset:1024
	global_load_dwordx2 v[142:143], v[12:13], off offset:1536
	v_mad_i64_i32 v[10:11], s[8:9], s8, v238, v[102:103]
	s_add_i32 s8, s10, s47
	s_max_i32 s8, s8, 0
	s_add_i32 s8, s8, s7
	v_mad_i64_i32 v[12:13], s[8:9], s8, v238, v[102:103]
	s_add_i32 s8, s10, s46
	s_max_i32 s8, s8, 0
	s_add_i32 s8, s8, s7
	global_load_dwordx2 v[136:137], v[10:11], off offset:1024
	global_load_dwordx2 v[138:139], v[10:11], off offset:1536
	global_load_dwordx2 v[132:133], v[12:13], off offset:1024
	global_load_dwordx2 v[134:135], v[12:13], off offset:1536
	v_mad_i64_i32 v[10:11], s[8:9], s8, v238, v[102:103]
	s_add_i32 s8, s10, s45
	s_max_i32 s8, s8, 0
	s_add_i32 s8, s8, s7
	v_mad_i64_i32 v[12:13], s[8:9], s8, v238, v[102:103]
	s_add_i32 s8, s10, s44
	s_max_i32 s8, s8, 0
	s_add_i32 s8, s8, s7
	global_load_dwordx2 v[126:127], v[10:11], off offset:1024
	global_load_dwordx2 v[128:129], v[10:11], off offset:1536
	global_load_dwordx2 v[122:123], v[12:13], off offset:1024
	global_load_dwordx2 v[124:125], v[12:13], off offset:1536
	v_mad_i64_i32 v[10:11], s[8:9], s8, v238, v[102:103]
	s_add_i32 s8, s10, s41
	s_max_i32 s8, s8, 0
	s_add_i32 s8, s8, s7
	v_mad_i64_i32 v[12:13], s[8:9], s8, v238, v[102:103]
	s_add_i32 s8, s10, s40
	s_max_i32 s8, s8, 0
	s_add_i32 s8, s8, s7
	global_load_dwordx2 v[118:119], v[10:11], off offset:1024
	global_load_dwordx2 v[120:121], v[10:11], off offset:1536
	global_load_dwordx2 v[114:115], v[12:13], off offset:1024
	global_load_dwordx2 v[116:117], v[12:13], off offset:1536
	v_mad_i64_i32 v[10:11], s[8:9], s8, v238, v[102:103]
	s_add_i32 s10, s10, s5
	s_lshl_b32 s6, s6, 7
	s_max_i32 s8, s10, 0
	s_and_b32 s6, s6, 0xffff8000
	s_add_i32 s8, s8, s7
	s_add_i32 s6, s6, 0
	v_mad_i64_i32 v[12:13], s[8:9], s8, v238, v[102:103]
	v_lshl_add_u32 v163, v14, 2, s6
	global_load_dwordx2 v[110:111], v[10:11], off offset:1024
	global_load_dwordx2 v[112:113], v[10:11], off offset:1536
	global_load_dwordx2 v[104:105], v[12:13], off offset:1024
	global_load_dwordx2 v[106:107], v[12:13], off offset:1536
	ds_read2st64_b32 v[26:27], v163 offset1:4
	ds_read2st64_b32 v[28:29], v163 offset0:8 offset1:12
	ds_read2st64_b32 v[30:31], v163 offset0:16 offset1:20
	ds_read2st64_b32 v[32:33], v163 offset0:24 offset1:28
	ds_read2st64_b32 v[160:161], v163 offset0:32 offset1:36
	ds_read2st64_b32 v[158:159], v163 offset0:40 offset1:44
	ds_read2st64_b32 v[156:157], v163 offset0:48 offset1:52
	ds_read2st64_b32 v[40:41], v163 offset0:56 offset1:60
	ds_read2st64_b32 v[38:39], v163 offset0:64 offset1:68
	ds_read2st64_b32 v[36:37], v163 offset0:72 offset1:76
	ds_read2st64_b32 v[34:35], v163 offset0:80 offset1:84
	ds_read2st64_b32 v[24:25], v163 offset0:88 offset1:92
	ds_read2st64_b32 v[22:23], v163 offset0:96 offset1:100
	ds_read2st64_b32 v[20:21], v163 offset0:104 offset1:108
	ds_read2st64_b32 v[10:11], v163 offset0:120 offset1:124
	ds_read2st64_b32 v[18:19], v163 offset0:112 offset1:116
	ds_read2st64_b32 v[12:13], v163 offset0:128 offset1:132
	ds_read2st64_b32 v[14:15], v163 offset0:136 offset1:140
	ds_read2st64_b32 v[16:17], v163 offset0:144 offset1:148
	s_waitcnt vmcnt(51) lgkmcnt(4)
	v_mul_f32_e32 v109, v101, v10
	v_mul_f32_e32 v165, v42, v27
	s_waitcnt vmcnt(24)
	v_mov_b32_e32 v164, v108
	v_pk_fma_f32 v[26:27], v[42:43], v[26:27], v[108:109]
	v_pk_fma_f32 v[164:165], v[44:45], v[28:29], v[164:165]
	v_pk_fma_f32 v[26:27], v[46:47], v[28:29], v[26:27]
	v_pk_fma_f32 v[164:165], v[48:49], v[30:31], v[164:165]
	v_pk_fma_f32 v[26:27], v[50:51], v[30:31], v[26:27]
	v_pk_fma_f32 v[164:165], v[52:53], v[32:33], v[164:165]
	v_pk_fma_f32 v[26:27], v[54:55], v[32:33], v[26:27]
	v_pk_fma_f32 v[164:165], v[56:57], v[160:161], v[164:165]
	v_pk_fma_f32 v[26:27], v[58:59], v[160:161], v[26:27]
	v_pk_fma_f32 v[164:165], v[60:61], v[158:159], v[164:165]
	v_pk_fma_f32 v[26:27], v[62:63], v[158:159], v[26:27]
	v_pk_fma_f32 v[164:165], v[64:65], v[156:157], v[164:165]
	v_pk_fma_f32 v[26:27], v[66:67], v[156:157], v[26:27]
	v_pk_fma_f32 v[164:165], v[68:69], v[40:41], v[164:165]
	v_pk_fma_f32 v[26:27], v[70:71], v[40:41], v[26:27]
	v_pk_fma_f32 v[164:165], v[72:73], v[38:39], v[164:165]
	v_pk_fma_f32 v[26:27], v[74:75], v[38:39], v[26:27]
	v_pk_fma_f32 v[164:165], v[76:77], v[36:37], v[164:165]
	v_pk_fma_f32 v[26:27], v[78:79], v[36:37], v[26:27]
	v_pk_fma_f32 v[164:165], v[80:81], v[34:35], v[164:165]
	v_pk_fma_f32 v[26:27], v[82:83], v[34:35], v[26:27]
	v_pk_fma_f32 v[164:165], v[84:85], v[24:25], v[164:165]
	v_pk_fma_f32 v[26:27], v[86:87], v[24:25], v[26:27]
	v_pk_fma_f32 v[164:165], v[88:89], v[22:23], v[164:165]
	v_pk_fma_f32 v[26:27], v[90:91], v[22:23], v[26:27]
	v_pk_fma_f32 v[164:165], v[92:93], v[20:21], v[164:165]
	v_pk_fma_f32 v[26:27], v[94:95], v[20:21], v[26:27]
	s_waitcnt lgkmcnt(3)
	v_pk_fma_f32 v[164:165], v[96:97], v[18:19], v[164:165]
	v_pk_fma_f32 v[26:27], v[98:99], v[18:19], v[26:27]
	v_pk_fma_f32 v[166:167], v[100:101], v[10:11], v[164:165]
	v_add_f32_e32 v164, v26, v27
	v_mul_f32_e32 v27, v42, v29
	v_mov_b32_e32 v26, v108
	v_pk_fma_f32 v[26:27], v[44:45], v[30:31], v[26:27]
	v_add_f32_e32 v165, v166, v167
	v_pk_fma_f32 v[26:27], v[48:49], v[32:33], v[26:27]
	s_waitcnt lgkmcnt(2)
	v_mul_f32_e32 v109, v101, v12
	v_pk_fma_f32 v[26:27], v[52:53], v[160:161], v[26:27]
	v_pk_fma_f32 v[28:29], v[42:43], v[28:29], v[108:109]
	v_pk_fma_f32 v[26:27], v[56:57], v[158:159], v[26:27]
	v_pk_fma_f32 v[28:29], v[46:47], v[30:31], v[28:29]
	v_pk_fma_f32 v[26:27], v[60:61], v[156:157], v[26:27]
	v_pk_fma_f32 v[28:29], v[50:51], v[32:33], v[28:29]
	v_pk_fma_f32 v[26:27], v[64:65], v[40:41], v[26:27]
	v_pk_fma_f32 v[28:29], v[54:55], v[160:161], v[28:29]
	v_pk_fma_f32 v[26:27], v[68:69], v[38:39], v[26:27]
	v_pk_fma_f32 v[28:29], v[58:59], v[158:159], v[28:29]
	v_pk_fma_f32 v[26:27], v[72:73], v[36:37], v[26:27]
	v_pk_fma_f32 v[28:29], v[62:63], v[156:157], v[28:29]
	v_pk_fma_f32 v[26:27], v[76:77], v[34:35], v[26:27]
	v_pk_fma_f32 v[28:29], v[66:67], v[40:41], v[28:29]
	v_pk_fma_f32 v[26:27], v[80:81], v[24:25], v[26:27]
	v_pk_fma_f32 v[28:29], v[70:71], v[38:39], v[28:29]
	v_pk_fma_f32 v[26:27], v[84:85], v[22:23], v[26:27]
	v_pk_fma_f32 v[28:29], v[74:75], v[36:37], v[28:29]
	v_pk_fma_f32 v[26:27], v[88:89], v[20:21], v[26:27]
	v_pk_fma_f32 v[28:29], v[78:79], v[34:35], v[28:29]
	v_pk_fma_f32 v[26:27], v[92:93], v[18:19], v[26:27]
	v_pk_fma_f32 v[28:29], v[82:83], v[24:25], v[28:29]
	v_pk_fma_f32 v[26:27], v[96:97], v[10:11], v[26:27]
	v_pk_fma_f32 v[28:29], v[86:87], v[22:23], v[28:29]
	v_pk_fma_f32 v[26:27], v[100:101], v[12:13], v[26:27]
	v_pk_fma_f32 v[28:29], v[90:91], v[20:21], v[28:29]
	v_add_f32_e32 v167, v26, v27
	v_mul_f32_e32 v27, v42, v31
	v_mov_b32_e32 v26, v108
	v_pk_fma_f32 v[26:27], v[44:45], v[32:33], v[26:27]
	v_pk_fma_f32 v[28:29], v[94:95], v[18:19], v[28:29]
	v_pk_fma_f32 v[26:27], v[48:49], v[160:161], v[26:27]
	v_pk_fma_f32 v[28:29], v[98:99], v[10:11], v[28:29]
	v_pk_fma_f32 v[26:27], v[52:53], v[158:159], v[26:27]
	s_waitcnt lgkmcnt(1)
	v_mul_f32_e32 v109, v101, v14
	v_pk_fma_f32 v[26:27], v[56:57], v[156:157], v[26:27]
	v_add_f32_e32 v166, v28, v29
	v_pk_fma_f32 v[26:27], v[60:61], v[40:41], v[26:27]
	v_pk_fma_f32 v[28:29], v[42:43], v[30:31], v[108:109]
	v_pk_fma_f32 v[26:27], v[64:65], v[38:39], v[26:27]
	v_pk_fma_f32 v[28:29], v[46:47], v[32:33], v[28:29]
	v_pk_fma_f32 v[26:27], v[68:69], v[36:37], v[26:27]
	v_pk_fma_f32 v[28:29], v[50:51], v[160:161], v[28:29]
	v_pk_fma_f32 v[26:27], v[72:73], v[34:35], v[26:27]
	v_pk_fma_f32 v[28:29], v[54:55], v[158:159], v[28:29]
	v_pk_fma_f32 v[26:27], v[76:77], v[24:25], v[26:27]
	v_pk_fma_f32 v[28:29], v[58:59], v[156:157], v[28:29]
	v_pk_fma_f32 v[26:27], v[80:81], v[22:23], v[26:27]
	v_pk_fma_f32 v[28:29], v[62:63], v[40:41], v[28:29]
	v_pk_fma_f32 v[26:27], v[84:85], v[20:21], v[26:27]
	v_pk_fma_f32 v[28:29], v[66:67], v[38:39], v[28:29]
	v_pk_fma_f32 v[26:27], v[88:89], v[18:19], v[26:27]
	v_pk_fma_f32 v[28:29], v[70:71], v[36:37], v[28:29]
	v_pk_fma_f32 v[26:27], v[92:93], v[10:11], v[26:27]
	v_pk_fma_f32 v[28:29], v[74:75], v[34:35], v[28:29]
	v_pk_fma_f32 v[26:27], v[96:97], v[12:13], v[26:27]
	v_pk_fma_f32 v[28:29], v[78:79], v[24:25], v[28:29]
	v_pk_fma_f32 v[26:27], v[100:101], v[14:15], v[26:27]
	v_pk_fma_f32 v[28:29], v[82:83], v[22:23], v[28:29]
	v_add_f32_e32 v169, v26, v27
	v_mul_f32_e32 v27, v42, v33
	v_mov_b32_e32 v26, v108
	v_pk_fma_f32 v[26:27], v[44:45], v[160:161], v[26:27]
	v_pk_fma_f32 v[28:29], v[86:87], v[20:21], v[28:29]
	v_pk_fma_f32 v[26:27], v[48:49], v[158:159], v[26:27]
	v_pk_fma_f32 v[28:29], v[90:91], v[18:19], v[28:29]
	v_pk_fma_f32 v[26:27], v[52:53], v[156:157], v[26:27]
	v_pk_fma_f32 v[28:29], v[94:95], v[10:11], v[28:29]
	v_pk_fma_f32 v[26:27], v[56:57], v[40:41], v[26:27]
	v_pk_fma_f32 v[28:29], v[98:99], v[12:13], v[28:29]
	v_pk_fma_f32 v[26:27], v[60:61], v[38:39], v[26:27]
	s_waitcnt lgkmcnt(0)
	v_mul_f32_e32 v109, v101, v16
	v_pk_fma_f32 v[26:27], v[64:65], v[36:37], v[26:27]
	v_add_f32_e32 v168, v28, v29
	v_pk_fma_f32 v[26:27], v[68:69], v[34:35], v[26:27]
	v_pk_fma_f32 v[28:29], v[42:43], v[32:33], v[108:109]
	v_pk_fma_f32 v[26:27], v[72:73], v[24:25], v[26:27]
	v_pk_fma_f32 v[28:29], v[46:47], v[160:161], v[28:29]
	v_pk_fma_f32 v[26:27], v[76:77], v[22:23], v[26:27]
	v_pk_fma_f32 v[28:29], v[50:51], v[158:159], v[28:29]
	v_pk_fma_f32 v[26:27], v[80:81], v[20:21], v[26:27]
	v_pk_fma_f32 v[28:29], v[54:55], v[156:157], v[28:29]
	v_pk_fma_f32 v[26:27], v[84:85], v[18:19], v[26:27]
	v_pk_fma_f32 v[28:29], v[58:59], v[40:41], v[28:29]
	v_pk_fma_f32 v[26:27], v[88:89], v[10:11], v[26:27]
	v_mul_f32_e32 v173, v42, v161
	v_pk_fma_f32 v[26:27], v[92:93], v[12:13], v[26:27]
	v_pk_fma_f32 v[28:29], v[62:63], v[38:39], v[28:29]
	v_pk_fma_f32 v[26:27], v[96:97], v[14:15], v[26:27]
	v_pk_fma_f32 v[28:29], v[66:67], v[36:37], v[28:29]
	v_pk_fma_f32 v[30:31], v[100:101], v[16:17], v[26:27]
	ds_read2st64_b32 v[26:27], v163 offset0:152 offset1:156
	v_pk_fma_f32 v[28:29], v[70:71], v[34:35], v[28:29]
	v_add_f32_e32 v171, v30, v31
	v_pk_fma_f32 v[28:29], v[74:75], v[24:25], v[28:29]
	v_mov_b32_e32 v172, v108
	s_waitcnt lgkmcnt(0)
	v_mul_f32_e32 v109, v101, v26
	v_pk_fma_f32 v[160:161], v[42:43], v[160:161], v[108:109]
	v_pk_fma_f32 v[28:29], v[78:79], v[22:23], v[28:29]
	v_pk_fma_f32 v[160:161], v[46:47], v[158:159], v[160:161]
	v_pk_fma_f32 v[28:29], v[82:83], v[20:21], v[28:29]
	v_pk_fma_f32 v[160:161], v[50:51], v[156:157], v[160:161]
	v_pk_fma_f32 v[28:29], v[86:87], v[18:19], v[28:29]
	v_pk_fma_f32 v[160:161], v[54:55], v[40:41], v[160:161]
	v_pk_fma_f32 v[28:29], v[90:91], v[10:11], v[28:29]
	v_pk_fma_f32 v[160:161], v[58:59], v[38:39], v[160:161]
	v_pk_fma_f32 v[28:29], v[94:95], v[12:13], v[28:29]
	v_pk_fma_f32 v[160:161], v[62:63], v[36:37], v[160:161]
	v_pk_fma_f32 v[28:29], v[98:99], v[14:15], v[28:29]
	v_pk_fma_f32 v[160:161], v[66:67], v[34:35], v[160:161]
	v_add_f32_e32 v170, v28, v29
	v_pk_fma_f32 v[160:161], v[70:71], v[24:25], v[160:161]
	ds_read2st64_b32 v[28:29], v163 offset0:160 offset1:164
	ds_read2st64_b32 v[30:31], v163 offset0:168 offset1:172
	ds_read2st64_b32 v[32:33], v163 offset0:176 offset1:180
	v_pk_fma_f32 v[160:161], v[74:75], v[22:23], v[160:161]
	v_pk_fma_f32 v[172:173], v[44:45], v[158:159], v[172:173]
	v_pk_fma_f32 v[160:161], v[78:79], v[20:21], v[160:161]
	s_waitcnt lgkmcnt(2)
	v_mul_f32_e32 v109, v101, v28
	v_pk_fma_f32 v[160:161], v[82:83], v[18:19], v[160:161]
	v_pk_fma_f32 v[172:173], v[48:49], v[156:157], v[172:173]
	v_pk_fma_f32 v[160:161], v[86:87], v[10:11], v[160:161]
	v_pk_fma_f32 v[172:173], v[52:53], v[40:41], v[172:173]
	v_pk_fma_f32 v[160:161], v[90:91], v[12:13], v[160:161]
	v_pk_fma_f32 v[172:173], v[56:57], v[38:39], v[172:173]
	v_pk_fma_f32 v[160:161], v[94:95], v[14:15], v[160:161]
	v_pk_fma_f32 v[172:173], v[60:61], v[36:37], v[172:173]
	v_pk_fma_f32 v[160:161], v[98:99], v[16:17], v[160:161]
	v_pk_fma_f32 v[172:173], v[64:65], v[34:35], v[172:173]
	v_add_f32_e32 v174, v160, v161
	v_mul_f32_e32 v161, v42, v159
	v_pk_fma_f32 v[158:159], v[42:43], v[158:159], v[108:109]
	v_mov_b32_e32 v160, v108
	v_pk_fma_f32 v[158:159], v[46:47], v[156:157], v[158:159]
	s_waitcnt lgkmcnt(1)
	v_mul_f32_e32 v109, v101, v30
	v_pk_fma_f32 v[158:159], v[50:51], v[40:41], v[158:159]
	v_pk_fma_f32 v[160:161], v[44:45], v[156:157], v[160:161]
	v_pk_fma_f32 v[158:159], v[54:55], v[38:39], v[158:159]
	v_pk_fma_f32 v[160:161], v[48:49], v[40:41], v[160:161]
	v_pk_fma_f32 v[158:159], v[58:59], v[36:37], v[158:159]
	v_pk_fma_f32 v[172:173], v[68:69], v[24:25], v[172:173]
	v_pk_fma_f32 v[158:159], v[62:63], v[34:35], v[158:159]
	v_pk_fma_f32 v[172:173], v[72:73], v[22:23], v[172:173]
	v_pk_fma_f32 v[158:159], v[66:67], v[24:25], v[158:159]
	v_pk_fma_f32 v[172:173], v[76:77], v[20:21], v[172:173]
	v_pk_fma_f32 v[158:159], v[70:71], v[22:23], v[158:159]
	v_pk_fma_f32 v[172:173], v[80:81], v[18:19], v[172:173]
	v_pk_fma_f32 v[158:159], v[74:75], v[20:21], v[158:159]
	v_pk_fma_f32 v[172:173], v[84:85], v[10:11], v[172:173]
	v_pk_fma_f32 v[158:159], v[78:79], v[18:19], v[158:159]
	v_pk_fma_f32 v[172:173], v[88:89], v[12:13], v[172:173]
	v_pk_fma_f32 v[158:159], v[82:83], v[10:11], v[158:159]
	v_pk_fma_f32 v[172:173], v[92:93], v[14:15], v[172:173]
	v_pk_fma_f32 v[158:159], v[86:87], v[12:13], v[158:159]
	v_pk_fma_f32 v[172:173], v[96:97], v[16:17], v[172:173]
	v_pk_fma_f32 v[158:159], v[90:91], v[14:15], v[158:159]
	v_pk_fma_f32 v[160:161], v[52:53], v[38:39], v[160:161]
	v_pk_fma_f32 v[158:159], v[94:95], v[16:17], v[158:159]
	v_pk_fma_f32 v[172:173], v[100:101], v[26:27], v[172:173]
	v_pk_fma_f32 v[158:159], v[98:99], v[26:27], v[158:159]
	v_pk_fma_f32 v[160:161], v[56:57], v[36:37], v[160:161]
	v_add_f32_e32 v176, v158, v159
	v_mul_f32_e32 v159, v42, v157
	v_pk_fma_f32 v[156:157], v[42:43], v[156:157], v[108:109]
	v_mov_b32_e32 v158, v108
	v_pk_fma_f32 v[156:157], v[46:47], v[40:41], v[156:157]
	s_waitcnt lgkmcnt(0)
	v_mul_f32_e32 v109, v101, v32
	v_pk_fma_f32 v[156:157], v[50:51], v[38:39], v[156:157]
	v_pk_fma_f32 v[158:159], v[44:45], v[40:41], v[158:159]
	v_pk_fma_f32 v[156:157], v[54:55], v[36:37], v[156:157]
	v_pk_fma_f32 v[158:159], v[48:49], v[38:39], v[158:159]
	v_pk_fma_f32 v[156:157], v[58:59], v[34:35], v[156:157]
	v_pk_fma_f32 v[158:159], v[52:53], v[36:37], v[158:159]
	v_pk_fma_f32 v[156:157], v[62:63], v[24:25], v[156:157]
	v_pk_fma_f32 v[158:159], v[56:57], v[34:35], v[158:159]
	v_pk_fma_f32 v[156:157], v[66:67], v[22:23], v[156:157]
	v_add_f32_e32 v175, v172, v173
	v_pk_fma_f32 v[156:157], v[70:71], v[20:21], v[156:157]
	v_pk_fma_f32 v[160:161], v[60:61], v[34:35], v[160:161]
	v_pk_fma_f32 v[156:157], v[74:75], v[18:19], v[156:157]
	v_pk_fma_f32 v[158:159], v[60:61], v[24:25], v[158:159]
	v_pk_fma_f32 v[156:157], v[78:79], v[10:11], v[156:157]
	v_mul_f32_e32 v173, v42, v39
	v_pk_fma_f32 v[156:157], v[82:83], v[12:13], v[156:157]
	v_pk_fma_f32 v[160:161], v[64:65], v[24:25], v[160:161]
	v_pk_fma_f32 v[156:157], v[86:87], v[14:15], v[156:157]
	v_pk_fma_f32 v[158:159], v[64:65], v[22:23], v[158:159]
	v_pk_fma_f32 v[156:157], v[90:91], v[16:17], v[156:157]
	v_pk_fma_f32 v[160:161], v[68:69], v[22:23], v[160:161]
	v_pk_fma_f32 v[156:157], v[94:95], v[26:27], v[156:157]
	v_pk_fma_f32 v[158:159], v[68:69], v[20:21], v[158:159]
	v_pk_fma_f32 v[156:157], v[98:99], v[28:29], v[156:157]
	v_pk_fma_f32 v[160:161], v[72:73], v[20:21], v[160:161]
	v_add_f32_e32 v178, v156, v157
	v_mul_f32_e32 v157, v42, v41
	v_pk_fma_f32 v[40:41], v[42:43], v[40:41], v[108:109]
	v_mov_b32_e32 v156, v108
	v_pk_fma_f32 v[40:41], v[46:47], v[38:39], v[40:41]
	v_pk_fma_f32 v[156:157], v[44:45], v[38:39], v[156:157]
	v_pk_fma_f32 v[40:41], v[50:51], v[36:37], v[40:41]
	v_pk_fma_f32 v[156:157], v[48:49], v[36:37], v[156:157]
	v_pk_fma_f32 v[40:41], v[54:55], v[34:35], v[40:41]
	v_pk_fma_f32 v[156:157], v[52:53], v[34:35], v[156:157]
	v_pk_fma_f32 v[40:41], v[58:59], v[24:25], v[40:41]
	v_pk_fma_f32 v[156:157], v[56:57], v[24:25], v[156:157]
	v_pk_fma_f32 v[40:41], v[62:63], v[22:23], v[40:41]
	v_pk_fma_f32 v[156:157], v[60:61], v[22:23], v[156:157]
	v_pk_fma_f32 v[40:41], v[66:67], v[20:21], v[40:41]
	v_pk_fma_f32 v[156:157], v[64:65], v[20:21], v[156:157]
	v_pk_fma_f32 v[40:41], v[70:71], v[18:19], v[40:41]
	v_pk_fma_f32 v[156:157], v[68:69], v[18:19], v[156:157]
	v_pk_fma_f32 v[40:41], v[74:75], v[10:11], v[40:41]
	v_pk_fma_f32 v[158:159], v[72:73], v[18:19], v[158:159]
	v_pk_fma_f32 v[40:41], v[78:79], v[12:13], v[40:41]
	v_pk_fma_f32 v[156:157], v[72:73], v[10:11], v[156:157]
	v_pk_fma_f32 v[40:41], v[82:83], v[14:15], v[40:41]
	v_pk_fma_f32 v[160:161], v[76:77], v[18:19], v[160:161]
	v_pk_fma_f32 v[40:41], v[86:87], v[16:17], v[40:41]
	v_pk_fma_f32 v[158:159], v[76:77], v[10:11], v[158:159]
	v_pk_fma_f32 v[40:41], v[90:91], v[26:27], v[40:41]
	v_pk_fma_f32 v[156:157], v[76:77], v[12:13], v[156:157]
	v_pk_fma_f32 v[40:41], v[94:95], v[28:29], v[40:41]
	v_pk_fma_f32 v[160:161], v[80:81], v[10:11], v[160:161]
	v_pk_fma_f32 v[40:41], v[98:99], v[30:31], v[40:41]
	v_pk_fma_f32 v[158:159], v[80:81], v[12:13], v[158:159]
	v_add_f32_e32 v180, v40, v41
	ds_read2st64_b32 v[40:41], v163 offset0:184 offset1:188
	v_pk_fma_f32 v[156:157], v[80:81], v[14:15], v[156:157]
	v_pk_fma_f32 v[160:161], v[84:85], v[12:13], v[160:161]
	v_pk_fma_f32 v[158:159], v[84:85], v[14:15], v[158:159]
	v_pk_fma_f32 v[156:157], v[84:85], v[16:17], v[156:157]
	s_waitcnt lgkmcnt(0)
	v_mul_f32_e32 v109, v101, v40
	v_pk_fma_f32 v[38:39], v[42:43], v[38:39], v[108:109]
	v_pk_fma_f32 v[160:161], v[88:89], v[14:15], v[160:161]
	v_pk_fma_f32 v[38:39], v[46:47], v[36:37], v[38:39]
	v_pk_fma_f32 v[158:159], v[88:89], v[16:17], v[158:159]
	v_pk_fma_f32 v[38:39], v[50:51], v[34:35], v[38:39]
	v_pk_fma_f32 v[156:157], v[88:89], v[26:27], v[156:157]
	v_pk_fma_f32 v[38:39], v[54:55], v[24:25], v[38:39]
	v_pk_fma_f32 v[160:161], v[92:93], v[16:17], v[160:161]
	v_pk_fma_f32 v[38:39], v[58:59], v[22:23], v[38:39]
	v_pk_fma_f32 v[158:159], v[92:93], v[26:27], v[158:159]
	v_pk_fma_f32 v[38:39], v[62:63], v[20:21], v[38:39]
	v_pk_fma_f32 v[156:157], v[92:93], v[28:29], v[156:157]
	v_pk_fma_f32 v[38:39], v[66:67], v[18:19], v[38:39]
	v_pk_fma_f32 v[160:161], v[96:97], v[26:27], v[160:161]
	v_pk_fma_f32 v[38:39], v[70:71], v[10:11], v[38:39]
	v_pk_fma_f32 v[158:159], v[96:97], v[28:29], v[158:159]
	v_pk_fma_f32 v[38:39], v[74:75], v[12:13], v[38:39]
	v_pk_fma_f32 v[156:157], v[96:97], v[30:31], v[156:157]
	v_pk_fma_f32 v[38:39], v[78:79], v[14:15], v[38:39]
	v_pk_fma_f32 v[160:161], v[100:101], v[28:29], v[160:161]
	v_pk_fma_f32 v[158:159], v[100:101], v[30:31], v[158:159]
	v_pk_fma_f32 v[156:157], v[100:101], v[32:33], v[156:157]
	v_pk_fma_f32 v[38:39], v[82:83], v[16:17], v[38:39]
	v_add_f32_e32 v177, v160, v161
	v_add_f32_e32 v179, v158, v159
	v_add_f32_e32 v181, v156, v157
	ds_read2st64_b32 v[156:157], v163 offset0:192 offset1:196
	ds_read2st64_b32 v[158:159], v163 offset0:200 offset1:204
	ds_read2st64_b32 v[160:161], v163 offset0:208 offset1:212
	v_pk_fma_f32 v[38:39], v[86:87], v[26:27], v[38:39]
	v_mov_b32_e32 v172, v108
	v_pk_fma_f32 v[38:39], v[90:91], v[28:29], v[38:39]
	s_waitcnt lgkmcnt(2)
	v_mul_f32_e32 v109, v101, v156
	v_pk_fma_f32 v[38:39], v[94:95], v[30:31], v[38:39]
	v_pk_fma_f32 v[172:173], v[44:45], v[36:37], v[172:173]
	v_pk_fma_f32 v[38:39], v[98:99], v[32:33], v[38:39]
	v_pk_fma_f32 v[172:173], v[48:49], v[34:35], v[172:173]
	v_add_f32_e32 v182, v38, v39
	v_mul_f32_e32 v39, v42, v37
	v_pk_fma_f32 v[36:37], v[42:43], v[36:37], v[108:109]
	v_mov_b32_e32 v38, v108
	v_pk_fma_f32 v[36:37], v[46:47], v[34:35], v[36:37]
	s_waitcnt lgkmcnt(1)
	v_mul_f32_e32 v109, v101, v158
	v_pk_fma_f32 v[36:37], v[50:51], v[24:25], v[36:37]
	v_pk_fma_f32 v[38:39], v[44:45], v[34:35], v[38:39]
	v_pk_fma_f32 v[36:37], v[54:55], v[22:23], v[36:37]
	v_pk_fma_f32 v[172:173], v[52:53], v[24:25], v[172:173]
	v_pk_fma_f32 v[36:37], v[58:59], v[20:21], v[36:37]
	v_pk_fma_f32 v[38:39], v[48:49], v[24:25], v[38:39]
	v_pk_fma_f32 v[36:37], v[62:63], v[18:19], v[36:37]
	v_pk_fma_f32 v[172:173], v[56:57], v[22:23], v[172:173]
	v_pk_fma_f32 v[36:37], v[66:67], v[10:11], v[36:37]
	v_pk_fma_f32 v[172:173], v[60:61], v[20:21], v[172:173]
	v_pk_fma_f32 v[36:37], v[70:71], v[12:13], v[36:37]
	v_pk_fma_f32 v[172:173], v[64:65], v[18:19], v[172:173]
	v_pk_fma_f32 v[36:37], v[74:75], v[14:15], v[36:37]
	v_pk_fma_f32 v[172:173], v[68:69], v[10:11], v[172:173]
	v_pk_fma_f32 v[36:37], v[78:79], v[16:17], v[36:37]
	v_pk_fma_f32 v[172:173], v[72:73], v[12:13], v[172:173]
	v_pk_fma_f32 v[36:37], v[82:83], v[26:27], v[36:37]
	v_pk_fma_f32 v[172:173], v[76:77], v[14:15], v[172:173]
	v_pk_fma_f32 v[36:37], v[86:87], v[28:29], v[36:37]
	v_pk_fma_f32 v[172:173], v[80:81], v[16:17], v[172:173]
	v_pk_fma_f32 v[36:37], v[90:91], v[30:31], v[36:37]
	v_pk_fma_f32 v[172:173], v[84:85], v[26:27], v[172:173]
	v_pk_fma_f32 v[36:37], v[94:95], v[32:33], v[36:37]
	v_pk_fma_f32 v[172:173], v[88:89], v[28:29], v[172:173]
	v_pk_fma_f32 v[36:37], v[98:99], v[40:41], v[36:37]
	v_pk_fma_f32 v[172:173], v[92:93], v[30:31], v[172:173]
	v_add_f32_e32 v184, v36, v37
	v_mul_f32_e32 v37, v42, v35
	v_pk_fma_f32 v[34:35], v[42:43], v[34:35], v[108:109]
	v_mov_b32_e32 v36, v108
	v_pk_fma_f32 v[34:35], v[46:47], v[24:25], v[34:35]
	s_waitcnt lgkmcnt(0)
	v_mul_f32_e32 v109, v101, v160
	v_pk_fma_f32 v[34:35], v[50:51], v[22:23], v[34:35]
	v_pk_fma_f32 v[36:37], v[44:45], v[24:25], v[36:37]
	v_pk_fma_f32 v[34:35], v[54:55], v[20:21], v[34:35]
	v_pk_fma_f32 v[36:37], v[48:49], v[22:23], v[36:37]
	v_pk_fma_f32 v[34:35], v[58:59], v[18:19], v[34:35]
	v_pk_fma_f32 v[172:173], v[96:97], v[32:33], v[172:173]
	v_pk_fma_f32 v[34:35], v[62:63], v[10:11], v[34:35]
	v_pk_fma_f32 v[38:39], v[52:53], v[22:23], v[38:39]
	v_pk_fma_f32 v[34:35], v[66:67], v[12:13], v[34:35]
	v_pk_fma_f32 v[36:37], v[52:53], v[20:21], v[36:37]
	v_pk_fma_f32 v[34:35], v[70:71], v[14:15], v[34:35]
	v_pk_fma_f32 v[172:173], v[100:101], v[40:41], v[172:173]
	v_pk_fma_f32 v[34:35], v[74:75], v[16:17], v[34:35]
	v_pk_fma_f32 v[38:39], v[56:57], v[20:21], v[38:39]
	v_pk_fma_f32 v[34:35], v[78:79], v[26:27], v[34:35]
	v_pk_fma_f32 v[36:37], v[56:57], v[18:19], v[36:37]
	v_pk_fma_f32 v[34:35], v[82:83], v[28:29], v[34:35]
	v_add_f32_e32 v183, v172, v173
	v_pk_fma_f32 v[34:35], v[86:87], v[30:31], v[34:35]
	v_pk_fma_f32 v[38:39], v[60:61], v[18:19], v[38:39]
	v_pk_fma_f32 v[34:35], v[90:91], v[32:33], v[34:35]
	v_pk_fma_f32 v[36:37], v[60:61], v[10:11], v[36:37]
	v_pk_fma_f32 v[34:35], v[94:95], v[40:41], v[34:35]
	v_mul_f32_e32 v173, v42, v23
	v_pk_fma_f32 v[34:35], v[98:99], v[156:157], v[34:35]
	v_pk_fma_f32 v[38:39], v[64:65], v[10:11], v[38:39]
	v_add_f32_e32 v186, v34, v35
	v_mul_f32_e32 v35, v42, v25
	v_pk_fma_f32 v[24:25], v[42:43], v[24:25], v[108:109]
	v_mov_b32_e32 v34, v108
	v_pk_fma_f32 v[24:25], v[46:47], v[22:23], v[24:25]
	v_pk_fma_f32 v[34:35], v[44:45], v[22:23], v[34:35]
	v_pk_fma_f32 v[24:25], v[50:51], v[20:21], v[24:25]
	v_pk_fma_f32 v[34:35], v[48:49], v[20:21], v[34:35]
	v_pk_fma_f32 v[24:25], v[54:55], v[18:19], v[24:25]
	v_pk_fma_f32 v[34:35], v[52:53], v[18:19], v[34:35]
	v_pk_fma_f32 v[24:25], v[58:59], v[10:11], v[24:25]
	v_pk_fma_f32 v[34:35], v[56:57], v[10:11], v[34:35]
	v_pk_fma_f32 v[24:25], v[62:63], v[12:13], v[24:25]
	v_pk_fma_f32 v[34:35], v[60:61], v[12:13], v[34:35]
	v_pk_fma_f32 v[24:25], v[66:67], v[14:15], v[24:25]
	v_pk_fma_f32 v[36:37], v[64:65], v[12:13], v[36:37]
	v_pk_fma_f32 v[24:25], v[70:71], v[16:17], v[24:25]
	v_pk_fma_f32 v[34:35], v[64:65], v[14:15], v[34:35]
	v_pk_fma_f32 v[24:25], v[74:75], v[26:27], v[24:25]
	v_pk_fma_f32 v[38:39], v[68:69], v[12:13], v[38:39]
	v_pk_fma_f32 v[24:25], v[78:79], v[28:29], v[24:25]
	v_pk_fma_f32 v[36:37], v[68:69], v[14:15], v[36:37]
	v_pk_fma_f32 v[24:25], v[82:83], v[30:31], v[24:25]
	v_pk_fma_f32 v[34:35], v[68:69], v[16:17], v[34:35]
	v_pk_fma_f32 v[24:25], v[86:87], v[32:33], v[24:25]
	v_pk_fma_f32 v[38:39], v[72:73], v[14:15], v[38:39]
	v_pk_fma_f32 v[24:25], v[90:91], v[40:41], v[24:25]
	v_pk_fma_f32 v[36:37], v[72:73], v[16:17], v[36:37]
	v_pk_fma_f32 v[24:25], v[94:95], v[156:157], v[24:25]
	v_pk_fma_f32 v[34:35], v[72:73], v[26:27], v[34:35]
	v_pk_fma_f32 v[24:25], v[98:99], v[158:159], v[24:25]
	v_pk_fma_f32 v[38:39], v[76:77], v[16:17], v[38:39]
	v_add_f32_e32 v188, v24, v25
	ds_read2st64_b32 v[24:25], v163 offset0:216 offset1:220
	v_pk_fma_f32 v[36:37], v[76:77], v[26:27], v[36:37]
	v_pk_fma_f32 v[34:35], v[76:77], v[28:29], v[34:35]
	v_pk_fma_f32 v[38:39], v[80:81], v[26:27], v[38:39]
	v_pk_fma_f32 v[36:37], v[80:81], v[28:29], v[36:37]
	s_waitcnt lgkmcnt(0)
	v_mul_f32_e32 v109, v101, v24
	v_pk_fma_f32 v[22:23], v[42:43], v[22:23], v[108:109]
	v_pk_fma_f32 v[34:35], v[80:81], v[30:31], v[34:35]
	v_pk_fma_f32 v[22:23], v[46:47], v[20:21], v[22:23]
	v_pk_fma_f32 v[38:39], v[84:85], v[28:29], v[38:39]
	v_pk_fma_f32 v[22:23], v[50:51], v[18:19], v[22:23]
	v_pk_fma_f32 v[36:37], v[84:85], v[30:31], v[36:37]
	v_pk_fma_f32 v[22:23], v[54:55], v[10:11], v[22:23]
	v_pk_fma_f32 v[34:35], v[84:85], v[32:33], v[34:35]
	v_pk_fma_f32 v[22:23], v[58:59], v[12:13], v[22:23]
	v_pk_fma_f32 v[38:39], v[88:89], v[30:31], v[38:39]
	v_pk_fma_f32 v[22:23], v[62:63], v[14:15], v[22:23]
	v_pk_fma_f32 v[36:37], v[88:89], v[32:33], v[36:37]
	v_pk_fma_f32 v[22:23], v[66:67], v[16:17], v[22:23]
	v_pk_fma_f32 v[34:35], v[88:89], v[40:41], v[34:35]
	v_pk_fma_f32 v[22:23], v[70:71], v[26:27], v[22:23]
	v_pk_fma_f32 v[38:39], v[92:93], v[32:33], v[38:39]
	v_pk_fma_f32 v[36:37], v[92:93], v[40:41], v[36:37]
	v_pk_fma_f32 v[34:35], v[92:93], v[156:157], v[34:35]
	v_pk_fma_f32 v[22:23], v[74:75], v[28:29], v[22:23]
	v_pk_fma_f32 v[38:39], v[96:97], v[40:41], v[38:39]
	v_pk_fma_f32 v[36:37], v[96:97], v[156:157], v[36:37]
	v_pk_fma_f32 v[34:35], v[96:97], v[158:159], v[34:35]
	v_pk_fma_f32 v[22:23], v[78:79], v[30:31], v[22:23]
	v_pk_fma_f32 v[38:39], v[100:101], v[156:157], v[38:39]
	v_pk_fma_f32 v[36:37], v[100:101], v[158:159], v[36:37]
	v_pk_fma_f32 v[34:35], v[100:101], v[160:161], v[34:35]
	v_pk_fma_f32 v[22:23], v[82:83], v[32:33], v[22:23]
	v_add_f32_e32 v185, v38, v39
	v_add_f32_e32 v187, v36, v37
	v_add_f32_e32 v189, v34, v35
	ds_read2st64_b32 v[34:35], v163 offset0:224 offset1:228
	ds_read2st64_b32 v[36:37], v163 offset0:232 offset1:236
	ds_read2st64_b32 v[38:39], v163 offset0:240 offset1:244
	v_pk_fma_f32 v[22:23], v[86:87], v[40:41], v[22:23]
	v_mov_b32_e32 v172, v108
	v_pk_fma_f32 v[22:23], v[90:91], v[156:157], v[22:23]
	s_waitcnt lgkmcnt(2)
	v_mul_f32_e32 v109, v101, v34
	v_pk_fma_f32 v[22:23], v[94:95], v[158:159], v[22:23]
	v_pk_fma_f32 v[172:173], v[44:45], v[20:21], v[172:173]
	v_pk_fma_f32 v[22:23], v[98:99], v[160:161], v[22:23]
	v_pk_fma_f32 v[172:173], v[48:49], v[18:19], v[172:173]
	v_add_f32_e32 v190, v22, v23
	v_mul_f32_e32 v23, v42, v21
	v_pk_fma_f32 v[20:21], v[42:43], v[20:21], v[108:109]
	v_pk_fma_f32 v[172:173], v[52:53], v[10:11], v[172:173]
	v_pk_fma_f32 v[20:21], v[46:47], v[18:19], v[20:21]
	v_pk_fma_f32 v[172:173], v[56:57], v[12:13], v[172:173]
	v_pk_fma_f32 v[20:21], v[50:51], v[10:11], v[20:21]
	v_pk_fma_f32 v[172:173], v[60:61], v[14:15], v[172:173]
	v_pk_fma_f32 v[20:21], v[54:55], v[12:13], v[20:21]
	v_pk_fma_f32 v[172:173], v[64:65], v[16:17], v[172:173]
	v_pk_fma_f32 v[20:21], v[58:59], v[14:15], v[20:21]
	v_pk_fma_f32 v[172:173], v[68:69], v[26:27], v[172:173]
	v_pk_fma_f32 v[20:21], v[62:63], v[16:17], v[20:21]
	v_pk_fma_f32 v[172:173], v[72:73], v[28:29], v[172:173]
	v_pk_fma_f32 v[20:21], v[66:67], v[26:27], v[20:21]
	v_pk_fma_f32 v[172:173], v[76:77], v[30:31], v[172:173]
	v_pk_fma_f32 v[20:21], v[70:71], v[28:29], v[20:21]
	v_pk_fma_f32 v[172:173], v[80:81], v[32:33], v[172:173]
	v_pk_fma_f32 v[20:21], v[74:75], v[30:31], v[20:21]
	v_pk_fma_f32 v[172:173], v[84:85], v[40:41], v[172:173]
	v_pk_fma_f32 v[20:21], v[78:79], v[32:33], v[20:21]
	v_pk_fma_f32 v[172:173], v[88:89], v[156:157], v[172:173]
	v_pk_fma_f32 v[20:21], v[82:83], v[40:41], v[20:21]
	v_pk_fma_f32 v[172:173], v[92:93], v[158:159], v[172:173]
	v_pk_fma_f32 v[20:21], v[86:87], v[156:157], v[20:21]
	v_pk_fma_f32 v[172:173], v[96:97], v[160:161], v[172:173]
	v_pk_fma_f32 v[20:21], v[90:91], v[158:159], v[20:21]
	v_pk_fma_f32 v[172:173], v[100:101], v[24:25], v[172:173]
	v_pk_fma_f32 v[20:21], v[94:95], v[160:161], v[20:21]
	v_mov_b32_e32 v22, v108
	v_pk_fma_f32 v[20:21], v[98:99], v[24:25], v[20:21]
	s_waitcnt lgkmcnt(1)
	v_mul_f32_e32 v109, v101, v36
	v_add_f32_e32 v172, v172, v173
	v_pk_fma_f32 v[22:23], v[44:45], v[18:19], v[22:23]
	v_add_f32_e32 v173, v20, v21
	v_mul_f32_e32 v21, v42, v19
	v_pk_fma_f32 v[18:19], v[42:43], v[18:19], v[108:109]
	v_pk_fma_f32 v[22:23], v[48:49], v[10:11], v[22:23]
	v_pk_fma_f32 v[18:19], v[46:47], v[10:11], v[18:19]
	v_pk_fma_f32 v[22:23], v[52:53], v[12:13], v[22:23]
	v_pk_fma_f32 v[18:19], v[50:51], v[12:13], v[18:19]
	v_pk_fma_f32 v[22:23], v[56:57], v[14:15], v[22:23]
	v_pk_fma_f32 v[18:19], v[54:55], v[14:15], v[18:19]
	v_pk_fma_f32 v[22:23], v[60:61], v[16:17], v[22:23]
	v_pk_fma_f32 v[18:19], v[58:59], v[16:17], v[18:19]
	v_pk_fma_f32 v[22:23], v[64:65], v[26:27], v[22:23]
	v_pk_fma_f32 v[18:19], v[62:63], v[26:27], v[18:19]
	v_pk_fma_f32 v[22:23], v[68:69], v[28:29], v[22:23]
	v_pk_fma_f32 v[18:19], v[66:67], v[28:29], v[18:19]
	v_pk_fma_f32 v[22:23], v[72:73], v[30:31], v[22:23]
	v_pk_fma_f32 v[18:19], v[70:71], v[30:31], v[18:19]
	v_pk_fma_f32 v[22:23], v[76:77], v[32:33], v[22:23]
	v_pk_fma_f32 v[18:19], v[74:75], v[32:33], v[18:19]
	v_pk_fma_f32 v[22:23], v[80:81], v[40:41], v[22:23]
	v_pk_fma_f32 v[18:19], v[78:79], v[40:41], v[18:19]
	v_pk_fma_f32 v[22:23], v[84:85], v[156:157], v[22:23]
	v_pk_fma_f32 v[18:19], v[82:83], v[156:157], v[18:19]
	v_pk_fma_f32 v[22:23], v[88:89], v[158:159], v[22:23]
	v_pk_fma_f32 v[18:19], v[86:87], v[158:159], v[18:19]
	v_pk_fma_f32 v[22:23], v[92:93], v[160:161], v[22:23]
	v_pk_fma_f32 v[18:19], v[90:91], v[160:161], v[18:19]
	v_pk_fma_f32 v[22:23], v[96:97], v[24:25], v[22:23]
	v_pk_fma_f32 v[18:19], v[94:95], v[24:25], v[18:19]
	v_pk_fma_f32 v[22:23], v[100:101], v[34:35], v[22:23]
	v_pk_fma_f32 v[18:19], v[98:99], v[34:35], v[18:19]
	v_add_f32_e32 v22, v22, v23
	v_mov_b32_e32 v20, v108
	v_add_f32_e32 v23, v18, v19
	s_waitcnt lgkmcnt(0)
	v_mul_f32_e32 v109, v101, v38
	v_mul_f32_e32 v19, v42, v11
	v_mov_b32_e32 v18, v108
	v_pk_fma_f32 v[20:21], v[44:45], v[10:11], v[20:21]
	v_pk_fma_f32 v[10:11], v[42:43], v[10:11], v[108:109]
	v_pk_fma_f32 v[18:19], v[44:45], v[12:13], v[18:19]
	v_pk_fma_f32 v[20:21], v[48:49], v[12:13], v[20:21]
	v_pk_fma_f32 v[10:11], v[46:47], v[12:13], v[10:11]
	v_pk_fma_f32 v[12:13], v[48:49], v[14:15], v[18:19]
	v_pk_fma_f32 v[20:21], v[52:53], v[14:15], v[20:21]
	v_pk_fma_f32 v[10:11], v[50:51], v[14:15], v[10:11]
	v_pk_fma_f32 v[12:13], v[52:53], v[16:17], v[12:13]
	v_pk_fma_f32 v[20:21], v[56:57], v[16:17], v[20:21]
	v_pk_fma_f32 v[10:11], v[54:55], v[16:17], v[10:11]
	v_pk_fma_f32 v[12:13], v[56:57], v[26:27], v[12:13]
	v_pk_fma_f32 v[20:21], v[60:61], v[26:27], v[20:21]
	v_pk_fma_f32 v[10:11], v[58:59], v[26:27], v[10:11]
	v_pk_fma_f32 v[12:13], v[60:61], v[28:29], v[12:13]
	v_pk_fma_f32 v[20:21], v[64:65], v[28:29], v[20:21]
	v_pk_fma_f32 v[10:11], v[62:63], v[28:29], v[10:11]
	v_pk_fma_f32 v[12:13], v[64:65], v[30:31], v[12:13]
	v_pk_fma_f32 v[20:21], v[68:69], v[30:31], v[20:21]
	v_pk_fma_f32 v[10:11], v[66:67], v[30:31], v[10:11]
	v_pk_fma_f32 v[12:13], v[68:69], v[32:33], v[12:13]
	v_pk_fma_f32 v[20:21], v[72:73], v[32:33], v[20:21]
	v_pk_fma_f32 v[10:11], v[70:71], v[32:33], v[10:11]
	v_pk_fma_f32 v[12:13], v[72:73], v[40:41], v[12:13]
	v_pk_fma_f32 v[20:21], v[76:77], v[40:41], v[20:21]
	v_pk_fma_f32 v[10:11], v[74:75], v[40:41], v[10:11]
	v_pk_fma_f32 v[12:13], v[76:77], v[156:157], v[12:13]
	v_pk_fma_f32 v[20:21], v[80:81], v[156:157], v[20:21]
	v_pk_fma_f32 v[10:11], v[78:79], v[156:157], v[10:11]
	v_pk_fma_f32 v[12:13], v[80:81], v[158:159], v[12:13]
	v_pk_fma_f32 v[20:21], v[84:85], v[158:159], v[20:21]
	v_pk_fma_f32 v[10:11], v[82:83], v[158:159], v[10:11]
	v_pk_fma_f32 v[12:13], v[84:85], v[160:161], v[12:13]
	v_pk_fma_f32 v[20:21], v[88:89], v[160:161], v[20:21]
	v_pk_fma_f32 v[10:11], v[86:87], v[160:161], v[10:11]
	v_pk_fma_f32 v[12:13], v[88:89], v[24:25], v[12:13]
	v_pk_fma_f32 v[20:21], v[92:93], v[24:25], v[20:21]
	v_pk_fma_f32 v[10:11], v[90:91], v[24:25], v[10:11]
	v_pk_fma_f32 v[12:13], v[92:93], v[34:35], v[12:13]
	s_lshl_b32 s6, s28, 10
	v_pk_fma_f32 v[20:21], v[96:97], v[34:35], v[20:21]
	v_pk_fma_f32 v[10:11], v[94:95], v[34:35], v[10:11]
	v_pk_fma_f32 v[12:13], v[96:97], v[36:37], v[12:13]
	s_add_i32 s6, s6, 0
	v_pk_fma_f32 v[20:21], v[100:101], v[36:37], v[20:21]
	v_pk_fma_f32 v[10:11], v[98:99], v[36:37], v[10:11]
	v_pk_fma_f32 v[12:13], v[100:101], v[38:39], v[12:13]
	v_add_u32_e32 v109, s6, v162
	v_add_f32_e32 v20, v20, v21
	v_add_f32_e32 v10, v10, v11
	v_add_f32_e32 v11, v12, v13
	s_barrier
	ds_write2st64_b32 v163, v164, v165 offset1:4
	ds_write2st64_b32 v163, v166, v167 offset0:8 offset1:12
	ds_write2st64_b32 v163, v168, v169 offset0:16 offset1:20
	ds_write2st64_b32 v163, v170, v171 offset0:24 offset1:28
	ds_write2st64_b32 v163, v174, v175 offset0:32 offset1:36
	ds_write2st64_b32 v163, v176, v177 offset0:40 offset1:44
	ds_write2st64_b32 v163, v178, v179 offset0:48 offset1:52
	ds_write2st64_b32 v163, v180, v181 offset0:56 offset1:60
	ds_write2st64_b32 v163, v182, v183 offset0:64 offset1:68
	ds_write2st64_b32 v163, v184, v185 offset0:72 offset1:76
	ds_write2st64_b32 v163, v186, v187 offset0:80 offset1:84
	ds_write2st64_b32 v163, v188, v189 offset0:88 offset1:92
	ds_write2st64_b32 v163, v190, v172 offset0:96 offset1:100
	ds_write2st64_b32 v163, v173, v22 offset0:104 offset1:108
	ds_write2st64_b32 v163, v23, v20 offset0:112 offset1:116
	ds_write2st64_b32 v163, v10, v11 offset0:120 offset1:124
	s_waitcnt lgkmcnt(0)
	s_barrier
	ds_read_b128 v[38:41], v109
	ds_read_b128 v[34:37], v109 offset:8192
	ds_read_b128 v[30:33], v109 offset:16384
	ds_read_b128 v[26:29], v109 offset:24576
	ds_read_b128 v[22:25], v109 offset:32768
	ds_read_b128 v[18:21], v109 offset:40960
	s_waitcnt lgkmcnt(5)
	v_mov_b32_e32 v10, v39
	v_mov_b32_e32 v11, v40
	v_mov_b32_e32 v12, v38
	v_mov_b32_e32 v13, v41
	v_pk_add_f32 v[10:11], v[10:11], v[12:13]
	s_waitcnt lgkmcnt(4)
	v_mov_b32_e32 v12, v34
	v_add_f32_e32 v160, v10, v11
	v_mov_b32_e32 v10, v35
	v_mov_b32_e32 v11, v36
	v_mov_b32_e32 v13, v37
	v_pk_add_f32 v[10:11], v[10:11], v[12:13]
	s_waitcnt lgkmcnt(3)
	v_mov_b32_e32 v12, v30
	v_add_f32_e32 v161, v10, v11
	v_mov_b32_e32 v10, v31
	v_mov_b32_e32 v11, v32
	v_mov_b32_e32 v13, v33
	v_pk_add_f32 v[10:11], v[10:11], v[12:13]
	s_waitcnt lgkmcnt(2)
	v_mov_b32_e32 v12, v26
	v_add_f32_e32 v162, v10, v11
	v_mov_b32_e32 v10, v27
	v_mov_b32_e32 v11, v28
	v_mov_b32_e32 v13, v29
	v_pk_add_f32 v[10:11], v[10:11], v[12:13]
	s_waitcnt lgkmcnt(1)
	v_mov_b32_e32 v12, v22
	v_add_f32_e32 v163, v10, v11
	v_mov_b32_e32 v10, v23
	v_mov_b32_e32 v11, v24
	v_mov_b32_e32 v13, v25
	v_pk_add_f32 v[10:11], v[10:11], v[12:13]
	s_waitcnt lgkmcnt(0)
	v_mov_b32_e32 v12, v18
	v_add_f32_e32 v164, v10, v11
	v_mov_b32_e32 v10, v19
	v_mov_b32_e32 v11, v20
	ds_read_b128 v[14:17], v109 offset:49152
	v_mov_b32_e32 v13, v21
	v_pk_add_f32 v[10:11], v[10:11], v[12:13]
	s_add_i32 s28, s57, s28
	v_add_f32_e32 v165, v10, v11
	ds_read_b128 v[10:13], v109 offset:57344
	s_waitcnt lgkmcnt(1)
	v_mov_b32_e32 v156, v15
	v_mov_b32_e32 v157, v16
	v_mov_b32_e32 v158, v14
	v_mov_b32_e32 v159, v17
	v_pk_add_f32 v[156:157], v[156:157], v[158:159]
	s_waitcnt lgkmcnt(0)
	v_mov_b32_e32 v158, v10
	v_add_f32_e32 v109, v156, v157
	v_mov_b32_e32 v156, v11
	v_mov_b32_e32 v157, v12
	v_mov_b32_e32 v159, v13
	v_pk_add_f32 v[156:157], v[156:157], v[158:159]
	v_add_f32_dpp v158, v161, v161 quad_perm:[1,0,3,2] row_mask:0xf bank_mask:0xf bound_ctrl:1
	v_add_f32_e32 v156, v156, v157
	v_add_f32_dpp v157, v160, v160 quad_perm:[1,0,3,2] row_mask:0xf bank_mask:0xf bound_ctrl:1
	v_add_f32_dpp v160, v163, v163 quad_perm:[1,0,3,2] row_mask:0xf bank_mask:0xf bound_ctrl:1
	v_add_f32_dpp v158, v158, v158 quad_perm:[2,3,0,1] row_mask:0xf bank_mask:0xf bound_ctrl:1
	v_add_f32_dpp v157, v157, v157 quad_perm:[2,3,0,1] row_mask:0xf bank_mask:0xf bound_ctrl:1
	v_add_f32_dpp v159, v162, v162 quad_perm:[1,0,3,2] row_mask:0xf bank_mask:0xf bound_ctrl:1
	s_nop 0
	v_add_f32_dpp v157, v157, v157 row_half_mirror row_mask:0xf bank_mask:0xf bound_ctrl:1
	v_add_f32_dpp v158, v158, v158 row_half_mirror row_mask:0xf bank_mask:0xf bound_ctrl:1
	v_add_f32_dpp v159, v159, v159 quad_perm:[2,3,0,1] row_mask:0xf bank_mask:0xf bound_ctrl:1
	v_add_f32_dpp v157, v157, v157 row_mirror row_mask:0xf bank_mask:0xf bound_ctrl:1
	v_add_f32_dpp v158, v158, v158 row_mirror row_mask:0xf bank_mask:0xf bound_ctrl:1
	v_add_f32_dpp v159, v159, v159 row_half_mirror row_mask:0xf bank_mask:0xf bound_ctrl:1
	v_add_f32_dpp v157, v157, v157 row_bcast:15 row_mask:0xa bank_mask:0xf
	v_add_f32_dpp v160, v160, v160 quad_perm:[2,3,0,1] row_mask:0xf bank_mask:0xf bound_ctrl:1
	v_add_f32_dpp v159, v159, v159 row_mirror row_mask:0xf bank_mask:0xf bound_ctrl:1
	v_add_f32_dpp v158, v158, v158 row_bcast:15 row_mask:0xa bank_mask:0xf
	v_add_f32_dpp v161, v164, v164 quad_perm:[1,0,3,2] row_mask:0xf bank_mask:0xf bound_ctrl:1
	v_add_f32_dpp v160, v160, v160 row_half_mirror row_mask:0xf bank_mask:0xf bound_ctrl:1
	v_add_f32_dpp v159, v159, v159 row_bcast:15 row_mask:0xa bank_mask:0xf
	v_add_f32_dpp v161, v161, v161 quad_perm:[2,3,0,1] row_mask:0xf bank_mask:0xf bound_ctrl:1
	v_add_f32_dpp v160, v160, v160 row_mirror row_mask:0xf bank_mask:0xf bound_ctrl:1
	v_add_f32_dpp v162, v165, v165 quad_perm:[1,0,3,2] row_mask:0xf bank_mask:0xf bound_ctrl:1
	v_add_f32_dpp v161, v161, v161 row_half_mirror row_mask:0xf bank_mask:0xf bound_ctrl:1
	v_add_f32_dpp v160, v160, v160 row_bcast:15 row_mask:0xa bank_mask:0xf
	v_add_f32_dpp v162, v162, v162 quad_perm:[2,3,0,1] row_mask:0xf bank_mask:0xf bound_ctrl:1
	v_add_f32_dpp v161, v161, v161 row_mirror row_mask:0xf bank_mask:0xf bound_ctrl:1
	v_add_f32_dpp v109, v109, v109 quad_perm:[1,0,3,2] row_mask:0xf bank_mask:0xf bound_ctrl:1
	v_add_f32_dpp v162, v162, v162 row_half_mirror row_mask:0xf bank_mask:0xf bound_ctrl:1
	v_add_f32_dpp v161, v161, v161 row_bcast:15 row_mask:0xa bank_mask:0xf
	v_add_f32_dpp v109, v109, v109 quad_perm:[2,3,0,1] row_mask:0xf bank_mask:0xf bound_ctrl:1
	v_add_f32_dpp v162, v162, v162 row_mirror row_mask:0xf bank_mask:0xf bound_ctrl:1
	v_add_f32_dpp v156, v156, v156 quad_perm:[1,0,3,2] row_mask:0xf bank_mask:0xf bound_ctrl:1
	v_add_f32_dpp v109, v109, v109 row_half_mirror row_mask:0xf bank_mask:0xf bound_ctrl:1
	v_add_f32_dpp v162, v162, v162 row_bcast:15 row_mask:0xa bank_mask:0xf
	v_add_f32_dpp v156, v156, v156 quad_perm:[2,3,0,1] row_mask:0xf bank_mask:0xf bound_ctrl:1
	v_add_f32_dpp v109, v109, v109 row_mirror row_mask:0xf bank_mask:0xf bound_ctrl:1
	s_nop 0
	v_add_f32_dpp v156, v156, v156 row_half_mirror row_mask:0xf bank_mask:0xf bound_ctrl:1
	s_nop 0
	v_add_f32_dpp v109, v109, v109 row_bcast:15 row_mask:0xa bank_mask:0xf
	v_add_f32_dpp v156, v156, v156 row_mirror row_mask:0xf bank_mask:0xf bound_ctrl:1
	s_nop 1
	v_add_f32_dpp v156, v156, v156 row_bcast:15 row_mask:0xa bank_mask:0xf
	s_nop 1
	v_add_f32_dpp v157, v157, v157 row_bcast:31 row_mask:0xc bank_mask:0xf
	s_nop 0
	v_readlane_b32 s6, v157, 63
	s_nop 0
	v_add_f32_dpp v158, v158, v158 row_bcast:31 row_mask:0xc bank_mask:0xf
	v_fma_f32 v39, s6, v239, v39
	v_fma_f32 v38, s6, v239, v38
	v_add_f32_dpp v159, v159, v159 row_bcast:31 row_mask:0xc bank_mask:0xf
	v_fma_f32 v41, s6, v239, v41
	v_fmac_f32_e32 v40, s6, v239
	v_add_f32_dpp v160, v160, v160 row_bcast:31 row_mask:0xc bank_mask:0xf
	v_readlane_b32 s7, v158, 63
	v_readlane_b32 s8, v159, 63
	v_add_f32_dpp v161, v161, v161 row_bcast:31 row_mask:0xc bank_mask:0xf
	v_pk_mul_f32 v[158:159], v[38:39], v[38:39]
	v_readlane_b32 s9, v160, 63
	v_add_f32_dpp v162, v162, v162 row_bcast:31 row_mask:0xc bank_mask:0xf
	v_readlane_b32 s10, v161, 63
	v_fma_f32 v35, s7, v239, v35
	v_add_f32_dpp v109, v109, v109 row_bcast:31 row_mask:0xc bank_mask:0xf
	v_fma_f32 v34, s7, v239, v34
	v_fma_f32 v37, s7, v239, v37
	v_add_f32_dpp v156, v156, v156 row_bcast:31 row_mask:0xc bank_mask:0xf
	v_fmac_f32_e32 v36, s7, v239
	v_readlane_b32 s60, v156, 63
	v_pk_mul_f32 v[156:157], v[40:41], v[40:41]
	v_readlane_b32 s29, v109, 63
	v_pk_mov_b32 v[160:161], v[158:159], v[156:157] op_sel:[1,0]
	v_mov_b32_e32 v159, v157
	v_pk_add_f32 v[156:157], v[160:161], v[158:159]
	v_pk_mul_f32 v[158:159], v[34:35], v[34:35]
	v_add_f32_e32 v109, v156, v157
	v_pk_mul_f32 v[156:157], v[36:37], v[36:37]
	v_fma_f32 v31, s8, v239, v31
	v_pk_mov_b32 v[160:161], v[158:159], v[156:157] op_sel:[1,0]
	v_mov_b32_e32 v159, v157
	v_pk_add_f32 v[156:157], v[160:161], v[158:159]
	v_fma_f32 v30, s8, v239, v30
	v_fma_f32 v33, s8, v239, v33
	v_fmac_f32_e32 v32, s8, v239
	v_readlane_b32 s11, v162, 63
	v_add_f32_e32 v162, v156, v157
	v_pk_mul_f32 v[156:157], v[32:33], v[32:33]
	v_pk_mul_f32 v[158:159], v[30:31], v[30:31]
	v_fma_f32 v27, s9, v239, v27
	v_pk_mov_b32 v[160:161], v[158:159], v[156:157] op_sel:[1,0]
	v_mov_b32_e32 v159, v157
	v_pk_add_f32 v[156:157], v[160:161], v[158:159]
	v_fma_f32 v26, s9, v239, v26
	v_fma_f32 v29, s9, v239, v29
	v_fmac_f32_e32 v28, s9, v239
	v_add_f32_e32 v163, v156, v157
	v_pk_mul_f32 v[156:157], v[28:29], v[28:29]
	v_pk_mul_f32 v[158:159], v[26:27], v[26:27]
	v_fma_f32 v23, s10, v239, v23
	v_pk_mov_b32 v[160:161], v[158:159], v[156:157] op_sel:[1,0]
	v_mov_b32_e32 v159, v157
	v_pk_add_f32 v[156:157], v[160:161], v[158:159]
	v_fma_f32 v22, s10, v239, v22
	v_fma_f32 v25, s10, v239, v25
	v_fmac_f32_e32 v24, s10, v239
	v_add_f32_e32 v164, v156, v157
	v_pk_mul_f32 v[156:157], v[24:25], v[24:25]
	v_pk_mul_f32 v[158:159], v[22:23], v[22:23]
	v_fma_f32 v19, s11, v239, v19
	v_pk_mov_b32 v[160:161], v[158:159], v[156:157] op_sel:[1,0]
	v_mov_b32_e32 v159, v157
	v_pk_add_f32 v[156:157], v[160:161], v[158:159]
	v_fma_f32 v18, s11, v239, v18
	v_fma_f32 v21, s11, v239, v21
	v_fmac_f32_e32 v20, s11, v239
	v_add_f32_e32 v165, v156, v157
	v_pk_mul_f32 v[156:157], v[20:21], v[20:21]
	v_pk_mul_f32 v[158:159], v[18:19], v[18:19]
	v_fma_f32 v15, s29, v239, v15
	v_pk_mov_b32 v[160:161], v[158:159], v[156:157] op_sel:[1,0]
	v_mov_b32_e32 v159, v157
	v_pk_add_f32 v[156:157], v[160:161], v[158:159]
	v_fma_f32 v14, s29, v239, v14
	v_fma_f32 v17, s29, v239, v17
	v_fmac_f32_e32 v16, s29, v239
	v_add_f32_e32 v166, v156, v157
	v_pk_mul_f32 v[156:157], v[16:17], v[16:17]
	v_pk_mul_f32 v[158:159], v[14:15], v[14:15]
	v_fma_f32 v11, s60, v239, v11
	v_pk_mov_b32 v[160:161], v[158:159], v[156:157] op_sel:[1,0]
	v_mov_b32_e32 v159, v157
	v_pk_add_f32 v[156:157], v[160:161], v[158:159]
	v_fma_f32 v10, s60, v239, v10
	v_fma_f32 v13, s60, v239, v13
	v_fmac_f32_e32 v12, s60, v239
	v_add_f32_e32 v167, v156, v157
	v_pk_mul_f32 v[156:157], v[12:13], v[12:13]
	v_pk_mul_f32 v[158:159], v[10:11], v[10:11]
	v_add_f32_dpp v109, v109, v109 quad_perm:[1,0,3,2] row_mask:0xf bank_mask:0xf bound_ctrl:1
	v_pk_mov_b32 v[160:161], v[158:159], v[156:157] op_sel:[1,0]
	v_mov_b32_e32 v159, v157
	v_pk_add_f32 v[156:157], v[160:161], v[158:159]
	v_add_f32_dpp v109, v109, v109 quad_perm:[2,3,0,1] row_mask:0xf bank_mask:0xf bound_ctrl:1
	v_add_f32_e32 v156, v156, v157
	v_add_f32_dpp v157, v162, v162 quad_perm:[1,0,3,2] row_mask:0xf bank_mask:0xf bound_ctrl:1
	v_add_f32_dpp v109, v109, v109 row_half_mirror row_mask:0xf bank_mask:0xf bound_ctrl:1
	v_add_f32_dpp v158, v163, v163 quad_perm:[1,0,3,2] row_mask:0xf bank_mask:0xf bound_ctrl:1
	v_add_f32_dpp v157, v157, v157 quad_perm:[2,3,0,1] row_mask:0xf bank_mask:0xf bound_ctrl:1
	v_add_f32_dpp v109, v109, v109 row_mirror row_mask:0xf bank_mask:0xf bound_ctrl:1
	s_nop 0
	v_add_f32_dpp v157, v157, v157 row_half_mirror row_mask:0xf bank_mask:0xf bound_ctrl:1
	v_add_f32_dpp v158, v158, v158 quad_perm:[2,3,0,1] row_mask:0xf bank_mask:0xf bound_ctrl:1
	v_add_f32_dpp v109, v109, v109 row_bcast:15 row_mask:0xa bank_mask:0xf
	v_add_f32_dpp v157, v157, v157 row_mirror row_mask:0xf bank_mask:0xf bound_ctrl:1
	v_add_f32_dpp v159, v164, v164 quad_perm:[1,0,3,2] row_mask:0xf bank_mask:0xf bound_ctrl:1
	v_add_f32_dpp v158, v158, v158 row_half_mirror row_mask:0xf bank_mask:0xf bound_ctrl:1
	v_add_f32_dpp v157, v157, v157 row_bcast:15 row_mask:0xa bank_mask:0xf
	v_add_f32_dpp v159, v159, v159 quad_perm:[2,3,0,1] row_mask:0xf bank_mask:0xf bound_ctrl:1
	v_add_f32_dpp v158, v158, v158 row_mirror row_mask:0xf bank_mask:0xf bound_ctrl:1
	v_add_f32_dpp v160, v165, v165 quad_perm:[1,0,3,2] row_mask:0xf bank_mask:0xf bound_ctrl:1
	v_add_f32_dpp v159, v159, v159 row_half_mirror row_mask:0xf bank_mask:0xf bound_ctrl:1
	v_add_f32_dpp v158, v158, v158 row_bcast:15 row_mask:0xa bank_mask:0xf
	v_add_f32_dpp v160, v160, v160 quad_perm:[2,3,0,1] row_mask:0xf bank_mask:0xf bound_ctrl:1
	v_add_f32_dpp v159, v159, v159 row_mirror row_mask:0xf bank_mask:0xf bound_ctrl:1
	v_add_f32_dpp v161, v166, v166 quad_perm:[1,0,3,2] row_mask:0xf bank_mask:0xf bound_ctrl:1
	v_add_f32_dpp v160, v160, v160 row_half_mirror row_mask:0xf bank_mask:0xf bound_ctrl:1
	v_add_f32_dpp v159, v159, v159 row_bcast:15 row_mask:0xa bank_mask:0xf
	v_add_f32_dpp v161, v161, v161 quad_perm:[2,3,0,1] row_mask:0xf bank_mask:0xf bound_ctrl:1
	v_add_f32_dpp v160, v160, v160 row_mirror row_mask:0xf bank_mask:0xf bound_ctrl:1
	v_add_f32_dpp v162, v167, v167 quad_perm:[1,0,3,2] row_mask:0xf bank_mask:0xf bound_ctrl:1
	v_add_f32_dpp v161, v161, v161 row_half_mirror row_mask:0xf bank_mask:0xf bound_ctrl:1
	v_add_f32_dpp v160, v160, v160 row_bcast:15 row_mask:0xa bank_mask:0xf
	v_add_f32_dpp v162, v162, v162 quad_perm:[2,3,0,1] row_mask:0xf bank_mask:0xf bound_ctrl:1
	v_add_f32_dpp v161, v161, v161 row_mirror row_mask:0xf bank_mask:0xf bound_ctrl:1
	v_add_f32_dpp v156, v156, v156 quad_perm:[1,0,3,2] row_mask:0xf bank_mask:0xf bound_ctrl:1
	v_add_f32_dpp v162, v162, v162 row_half_mirror row_mask:0xf bank_mask:0xf bound_ctrl:1
	v_add_f32_dpp v161, v161, v161 row_bcast:15 row_mask:0xa bank_mask:0xf
	v_add_f32_dpp v156, v156, v156 quad_perm:[2,3,0,1] row_mask:0xf bank_mask:0xf bound_ctrl:1
	v_add_f32_dpp v162, v162, v162 row_mirror row_mask:0xf bank_mask:0xf bound_ctrl:1
	s_nop 0
	v_add_f32_dpp v156, v156, v156 row_half_mirror row_mask:0xf bank_mask:0xf bound_ctrl:1
	s_ashr_i32 s29, s28, 31
	v_add_f32_dpp v162, v162, v162 row_bcast:15 row_mask:0xa bank_mask:0xf
	v_add_f32_dpp v156, v156, v156 row_mirror row_mask:0xf bank_mask:0xf bound_ctrl:1
	s_lshl_b64 s[8:9], s[28:29], 11
	s_add_u32 s8, s76, s8
	v_add_f32_dpp v156, v156, v156 row_bcast:15 row_mask:0xa bank_mask:0xf
	s_addc_u32 s9, s77, s9
	s_nop 0
	v_add_f32_dpp v109, v109, v109 row_bcast:31 row_mask:0xc bank_mask:0xf
	s_nop 0
	v_readlane_b32 s6, v109, 63
	s_nop 0
	v_add_f32_dpp v157, v157, v157 row_bcast:31 row_mask:0xc bank_mask:0xf
	v_fma_f32 v109, s6, v235, v225
	v_readlane_b32 s10, v157, 63
	v_add_f32_dpp v158, v158, v158 row_bcast:31 row_mask:0xc bank_mask:0xf
	s_nop 0
	v_readlane_b32 s11, v158, 63
	s_nop 0
	v_add_f32_dpp v159, v159, v159 row_bcast:31 row_mask:0xc bank_mask:0xf
	s_nop 0
	v_readlane_b32 s65, v159, 63
	s_nop 0
	v_add_f32_dpp v160, v160, v160 row_bcast:31 row_mask:0xc bank_mask:0xf
	s_nop 0
	v_readlane_b32 s61, v160, 63
	s_nop 0
	v_add_f32_dpp v161, v161, v161 row_bcast:31 row_mask:0xc bank_mask:0xf
	s_nop 0
	v_readlane_b32 s60, v161, 63
	s_nop 0
	v_add_f32_dpp v162, v162, v162 row_bcast:31 row_mask:0xc bank_mask:0xf
	v_mov_b32_e32 v163, v131
	v_readlane_b32 s7, v162, 63
	s_nop 0
	v_mov_b32_dpp v163, v156 row_bcast:31 row_mask:0xc bank_mask:0xf
	v_add_f32_e32 v163, v156, v163
	v_rsq_f32_e32 v156, v109
	v_readlane_b32 s6, v163, 63
	v_pk_mul_f32 v[38:39], v[38:39], v[156:157] op_sel_hi:[1,0]
	s_nop 0
	v_pk_fma_f32 v[38:39], v[2:3], v[38:39], v[6:7]
	v_pk_mul_f32 v[40:41], v[40:41], v[156:157] op_sel_hi:[1,0]
	v_mul_f32_e32 v109, 0xbfb8aa3b, v38
	v_exp_f32_e32 v109, v109
	v_mul_f32_e32 v156, 0xbfb8aa3b, v39
	v_exp_f32_e32 v157, v156
	v_pk_fma_f32 v[40:41], v[4:5], v[40:41], v[8:9]
	v_add_f32_e32 v109, 1.0, v109
	v_rcp_f32_e32 v156, v109
	v_add_f32_e32 v109, 1.0, v157
	v_mul_f32_e32 v157, 0xbfb8aa3b, v40
	v_exp_f32_e32 v158, v157
	v_mul_f32_e32 v157, 0xbfb8aa3b, v41
	v_exp_f32_e32 v159, v157
	v_rcp_f32_e32 v157, v109
	v_add_f32_e32 v109, 1.0, v158
	v_rcp_f32_e32 v158, v109
	v_add_f32_e32 v109, 1.0, v159
	v_rcp_f32_e32 v159, v109
	v_pk_mul_f32 v[38:39], v[38:39], v[156:157]
	v_lshlrev_b32_e32 v109, 3, v130
	v_cvt_pk_bf16_f32 v38, v38, v39
	v_pk_mul_f32 v[40:41], v[40:41], v[158:159]
	v_cvt_pk_bf16_f32 v39, v40, v41
	v_fma_f32 v40, s10, v235, v225
	v_rsq_f32_e32 v40, v40
	global_store_dwordx2 v109, v[38:39], s[8:9] offset:512 sc1
	s_add_i32 s8, s28, 8
	s_ashr_i32 s9, s8, 31
	v_pk_mul_f32 v[36:37], v[36:37], v[40:41] op_sel_hi:[1,0]
	v_pk_mul_f32 v[34:35], v[34:35], v[40:41] op_sel_hi:[1,0]
	v_pk_fma_f32 v[36:37], v[4:5], v[36:37], v[8:9]
	v_pk_fma_f32 v[34:35], v[2:3], v[34:35], v[6:7]
	v_mul_f32_e32 v130, 0xbfb8aa3b, v36
	v_pk_mul_f32 v[40:41], v[34:35], s[96:97] op_sel_hi:[1,0]
	v_exp_f32_e32 v130, v130
	v_mul_f32_e32 v156, 0xbfb8aa3b, v37
	v_exp_f32_e32 v40, v40
	v_exp_f32_e32 v41, v41
	v_exp_f32_e32 v157, v156
	v_add_f32_e32 v130, 1.0, v130
	v_pk_add_f32 v[40:41], v[40:41], 1.0 op_sel_hi:[1,0]
	v_rcp_f32_e32 v156, v130
	v_add_f32_e32 v130, 1.0, v157
	v_rcp_f32_e32 v40, v40
	v_rcp_f32_e32 v41, v41
	v_rcp_f32_e32 v157, v130
	s_lshl_b64 s[8:9], s[8:9], 11
	s_add_u32 s8, s76, s8
	v_pk_mul_f32 v[34:35], v[34:35], v[40:41]
	v_pk_mul_f32 v[36:37], v[36:37], v[156:157]
	v_cvt_pk_bf16_f32 v34, v34, v35
	v_cvt_pk_bf16_f32 v35, v36, v37
	v_fma_f32 v36, s11, v235, v225
	v_rsq_f32_e32 v36, v36
	s_addc_u32 s9, s77, s9
	global_store_dwordx2 v109, v[34:35], s[8:9] offset:512 sc1
	s_add_i32 s8, s28, 16
	v_pk_mul_f32 v[30:31], v[30:31], v[36:37] op_sel_hi:[1,0]
	v_pk_mul_f32 v[32:33], v[32:33], v[36:37] op_sel_hi:[1,0]
	v_pk_fma_f32 v[30:31], v[2:3], v[30:31], v[6:7]
	v_pk_fma_f32 v[32:33], v[4:5], v[32:33], v[8:9]
	v_pk_mul_f32 v[36:37], v[30:31], s[96:97] op_sel_hi:[1,0]
	v_pk_mul_f32 v[38:39], v[32:33], s[96:97] op_sel_hi:[1,0]
	v_exp_f32_e32 v36, v36
	v_exp_f32_e32 v37, v37
	v_exp_f32_e32 v38, v38
	v_exp_f32_e32 v39, v39
	v_pk_add_f32 v[36:37], v[36:37], 1.0 op_sel_hi:[1,0]
	v_pk_add_f32 v[38:39], v[38:39], 1.0 op_sel_hi:[1,0]
	v_rcp_f32_e32 v36, v36
	v_rcp_f32_e32 v37, v37
	v_rcp_f32_e32 v38, v38
	v_rcp_f32_e32 v39, v39
	s_ashr_i32 s9, s8, 31
	v_pk_mul_f32 v[30:31], v[30:31], v[36:37]
	s_lshl_b64 s[8:9], s[8:9], 11
	v_pk_mul_f32 v[32:33], v[32:33], v[38:39]
	v_cvt_pk_bf16_f32 v30, v30, v31
	v_cvt_pk_bf16_f32 v31, v32, v33
	v_fma_f32 v32, s65, v235, v225
	v_rsq_f32_e32 v32, v32
	s_add_u32 s8, s76, s8
	s_addc_u32 s9, s77, s9
	global_store_dwordx2 v109, v[30:31], s[8:9] offset:512 sc1
	v_pk_mul_f32 v[26:27], v[26:27], v[32:33] op_sel_hi:[1,0]
	v_pk_mul_f32 v[28:29], v[28:29], v[32:33] op_sel_hi:[1,0]
	v_pk_fma_f32 v[26:27], v[2:3], v[26:27], v[6:7]
	v_pk_fma_f32 v[28:29], v[4:5], v[28:29], v[8:9]
	v_pk_mul_f32 v[32:33], v[26:27], s[96:97] op_sel_hi:[1,0]
	v_pk_mul_f32 v[34:35], v[28:29], s[96:97] op_sel_hi:[1,0]
	v_exp_f32_e32 v32, v32
	v_exp_f32_e32 v33, v33
	v_exp_f32_e32 v34, v34
	v_exp_f32_e32 v35, v35
	v_pk_add_f32 v[32:33], v[32:33], 1.0 op_sel_hi:[1,0]
	v_pk_add_f32 v[34:35], v[34:35], 1.0 op_sel_hi:[1,0]
	v_rcp_f32_e32 v32, v32
	v_rcp_f32_e32 v33, v33
	v_rcp_f32_e32 v34, v34
	v_rcp_f32_e32 v35, v35
	s_add_i32 s8, s28, 24
	v_pk_mul_f32 v[26:27], v[26:27], v[32:33]
	s_ashr_i32 s9, s8, 31
	v_pk_mul_f32 v[28:29], v[28:29], v[34:35]
	v_cvt_pk_bf16_f32 v26, v26, v27
	v_cvt_pk_bf16_f32 v27, v28, v29
	v_fma_f32 v28, s61, v235, v225
	v_rsq_f32_e32 v28, v28
	s_lshl_b64 s[8:9], s[8:9], 11
	s_add_u32 s8, s76, s8
	s_addc_u32 s9, s77, s9
	v_pk_mul_f32 v[22:23], v[22:23], v[28:29] op_sel_hi:[1,0]
	v_pk_mul_f32 v[24:25], v[24:25], v[28:29] op_sel_hi:[1,0]
	v_pk_fma_f32 v[22:23], v[2:3], v[22:23], v[6:7]
	v_pk_fma_f32 v[24:25], v[4:5], v[24:25], v[8:9]
	v_pk_mul_f32 v[28:29], v[22:23], s[96:97] op_sel_hi:[1,0]
	v_pk_mul_f32 v[30:31], v[24:25], s[96:97] op_sel_hi:[1,0]
	v_exp_f32_e32 v28, v28
	v_exp_f32_e32 v29, v29
	v_exp_f32_e32 v30, v30
	v_exp_f32_e32 v31, v31
	v_pk_add_f32 v[28:29], v[28:29], 1.0 op_sel_hi:[1,0]
	v_pk_add_f32 v[30:31], v[30:31], 1.0 op_sel_hi:[1,0]
	v_rcp_f32_e32 v28, v28
	v_rcp_f32_e32 v29, v29
	v_rcp_f32_e32 v30, v30
	v_rcp_f32_e32 v31, v31
	global_store_dwordx2 v109, v[26:27], s[8:9] offset:512 sc1
	v_pk_mul_f32 v[22:23], v[22:23], v[28:29]
	s_add_i32 s8, s28, 32
	v_pk_mul_f32 v[24:25], v[24:25], v[30:31]
	v_cvt_pk_bf16_f32 v22, v22, v23
	v_cvt_pk_bf16_f32 v23, v24, v25
	v_fma_f32 v24, s60, v235, v225
	v_rsq_f32_e32 v24, v24
	s_ashr_i32 s9, s8, 31
	s_lshl_b64 s[8:9], s[8:9], 11
	s_add_u32 s8, s76, s8
	v_pk_mul_f32 v[18:19], v[18:19], v[24:25] op_sel_hi:[1,0]
	v_pk_mul_f32 v[20:21], v[20:21], v[24:25] op_sel_hi:[1,0]
	v_pk_fma_f32 v[18:19], v[2:3], v[18:19], v[6:7]
	v_pk_fma_f32 v[20:21], v[4:5], v[20:21], v[8:9]
	v_pk_mul_f32 v[24:25], v[18:19], s[96:97] op_sel_hi:[1,0]
	v_pk_mul_f32 v[26:27], v[20:21], s[96:97] op_sel_hi:[1,0]
	v_exp_f32_e32 v24, v24
	v_exp_f32_e32 v25, v25
	v_exp_f32_e32 v26, v26
	v_exp_f32_e32 v27, v27
	v_pk_add_f32 v[24:25], v[24:25], 1.0 op_sel_hi:[1,0]
	v_pk_add_f32 v[26:27], v[26:27], 1.0 op_sel_hi:[1,0]
	v_rcp_f32_e32 v24, v24
	v_rcp_f32_e32 v25, v25
	v_rcp_f32_e32 v26, v26
	v_rcp_f32_e32 v27, v27
	s_addc_u32 s9, s77, s9
	v_pk_mul_f32 v[18:19], v[18:19], v[24:25]
	global_store_dwordx2 v109, v[22:23], s[8:9] offset:512 sc1
	v_pk_mul_f32 v[20:21], v[20:21], v[26:27]
	v_cvt_pk_bf16_f32 v18, v18, v19
	v_cvt_pk_bf16_f32 v19, v20, v21
	v_fma_f32 v20, s7, v235, v225
	v_rsq_f32_e32 v20, v20
	s_add_i32 s8, s28, 40
	s_ashr_i32 s9, s8, 31
	s_lshl_b64 s[8:9], s[8:9], 11
	v_pk_mul_f32 v[14:15], v[14:15], v[20:21] op_sel_hi:[1,0]
	v_pk_mul_f32 v[16:17], v[16:17], v[20:21] op_sel_hi:[1,0]
	v_pk_fma_f32 v[14:15], v[2:3], v[14:15], v[6:7]
	v_pk_fma_f32 v[16:17], v[4:5], v[16:17], v[8:9]
	v_pk_mul_f32 v[20:21], v[14:15], s[96:97] op_sel_hi:[1,0]
	v_pk_mul_f32 v[22:23], v[16:17], s[96:97] op_sel_hi:[1,0]
	v_exp_f32_e32 v20, v20
	v_exp_f32_e32 v21, v21
	v_exp_f32_e32 v22, v22
	v_exp_f32_e32 v23, v23
	v_pk_add_f32 v[20:21], v[20:21], 1.0 op_sel_hi:[1,0]
	v_pk_add_f32 v[22:23], v[22:23], 1.0 op_sel_hi:[1,0]
	v_rcp_f32_e32 v20, v20
	v_rcp_f32_e32 v21, v21
	v_rcp_f32_e32 v22, v22
	v_rcp_f32_e32 v23, v23
	s_add_u32 s8, s76, s8
	v_pk_mul_f32 v[14:15], v[14:15], v[20:21]
	s_addc_u32 s9, s77, s9
	v_pk_mul_f32 v[16:17], v[16:17], v[22:23]
	v_cvt_pk_bf16_f32 v14, v14, v15
	v_cvt_pk_bf16_f32 v15, v16, v17
	v_fma_f32 v16, s6, v235, v225
	v_rsq_f32_e32 v16, v16
	global_store_dwordx2 v109, v[18:19], s[8:9] offset:512 sc1
	s_add_i32 s8, s28, 48
	s_ashr_i32 s9, s8, 31
	v_pk_mul_f32 v[10:11], v[10:11], v[16:17] op_sel_hi:[1,0]
	v_pk_mul_f32 v[12:13], v[12:13], v[16:17] op_sel_hi:[1,0]
	v_pk_fma_f32 v[10:11], v[2:3], v[10:11], v[6:7]
	v_pk_fma_f32 v[12:13], v[4:5], v[12:13], v[8:9]
	v_pk_mul_f32 v[16:17], v[10:11], s[96:97] op_sel_hi:[1,0]
	v_pk_mul_f32 v[18:19], v[12:13], s[96:97] op_sel_hi:[1,0]
	v_exp_f32_e32 v16, v16
	v_exp_f32_e32 v17, v17
	v_exp_f32_e32 v18, v18
	v_exp_f32_e32 v19, v19
	s_lshl_b64 s[6:7], s[8:9], 11
	s_add_u32 s6, s76, s6
	s_addc_u32 s7, s77, s7
	v_pk_add_f32 v[16:17], v[16:17], 1.0 op_sel_hi:[1,0]
	v_pk_add_f32 v[18:19], v[18:19], 1.0 op_sel_hi:[1,0]
	v_rcp_f32_e32 v16, v16
	v_rcp_f32_e32 v17, v17
	v_rcp_f32_e32 v18, v18
	v_rcp_f32_e32 v19, v19
	global_store_dwordx2 v109, v[14:15], s[6:7] offset:512 sc1
	s_add_i32 s6, s28, 56
	s_ashr_i32 s7, s6, 31
	s_lshl_b64 s[6:7], s[6:7], 11
	s_add_u32 s6, s76, s6
	v_pk_mul_f32 v[10:11], v[10:11], v[16:17]
	v_pk_mul_f32 v[12:13], v[12:13], v[18:19]
	s_addc_u32 s7, s77, s7
	s_addk_i32 s58, 0x80
	s_addk_i32 s57, 0x2000
	v_cvt_pk_bf16_f32 v10, v10, v11
	v_cvt_pk_bf16_f32 v11, v12, v13
	s_cmpk_gt_i32 s59, 0xff
	global_store_dwordx2 v109, v[10:11], s[6:7] offset:512 sc1
	s_barrier
	s_cbranch_scc1 .LBB0_313

.LBB0_314:
	s_andn2_b64 vcc, exec, s[28:29]
	s_cbranch_vccnz .LBB0_316
	v_mov_b32_e32 v1, v242
	s_mov_b32 s73, s11
	v_readfirstlane_b32 s5, v1
	s_ashr_i32 s65, s5, 6
	v_add_u32_e32 v6, s66, v1
	s_lshl_b32 s6, s65, 4
	v_readlane_b32 s66, v250, 31
	s_add_i32 s6, s6, s66
	s_mul_i32 s8, s6, 0x1800
	s_mul_hi_i32 s7, s6, 0x1800
	s_add_u32 s28, s80, s8
	s_addc_u32 s29, s81, s7
	s_or_b32 s7, s6, 1
	s_mul_hi_i32 s8, s7, 0x1800
	s_mulk_i32 s7, 0x1800
	v_and_b32_e32 v74, 63, v1
	s_add_u32 s40, s80, s7
	s_addc_u32 s41, s81, s8
	v_lshlrev_b32_e32 v44, 1, v74
	global_load_ushort v9, v44, s[40:41] offset:512
	global_load_ushort v20, v44, s[40:41] offset:640
	global_load_ushort v26, v44, s[40:41] offset:768
	global_load_ushort v30, v44, s[40:41] offset:896
	global_load_ushort v8, v44, s[28:29] offset:512
	global_load_ushort v21, v44, s[28:29] offset:640
	global_load_ushort v27, v44, s[28:29] offset:768
	global_load_ushort v31, v44, s[28:29] offset:896
	s_or_b32 s7, s6, 2
	s_mul_hi_i32 s9, s7, 0x1800
	s_mulk_i32 s7, 0x1800
	s_add_u32 s8, s80, s7
	s_addc_u32 s9, s81, s9
	s_or_b32 s7, s6, 3
	s_mul_hi_i32 s11, s7, 0x1800
	s_mulk_i32 s7, 0x1800
	s_add_u32 s10, s80, s7
	s_addc_u32 s11, s81, s11
	global_load_ushort v18, v44, s[10:11] offset:512
	global_load_ushort v19, v44, s[10:11] offset:640
	global_load_ushort v22, v44, s[10:11] offset:768
	global_load_ushort v32, v44, s[10:11] offset:896
	global_load_ushort v23, v44, s[8:9] offset:512
	global_load_ushort v28, v44, s[8:9] offset:640
	global_load_ushort v29, v44, s[8:9] offset:768
	global_load_ushort v33, v44, s[8:9] offset:896
	s_mov_b32 s8, 0xbf3a00e3
	v_mov_b64_e32 v[24:25], s[8:9]
	s_mov_b64 s[10:11], s[68:69]
	s_mov_b64 s[68:69], s[12:13]
	s_mov_b32 s12, 0x3f07dc22
	s_mov_b32 s14, 0x3f35f0e3
	s_mov_b32 s16, 0xbe11a98e
	s_mov_b32 s18, 0x3e027906
	s_or_b32 s7, s6, 4
	s_mul_hi_i32 s8, s7, 0x1800
	s_mulk_i32 s7, 0x1800
	s_add_u32 s28, s80, s7
	s_addc_u32 s29, s81, s8
	s_or_b32 s7, s6, 5
	s_mul_hi_i32 s8, s7, 0x1800
	s_mulk_i32 s7, 0x1800
	s_add_u32 s40, s80, s7
	s_addc_u32 s41, s81, s8
	s_or_b32 s7, s6, 6
	s_mul_hi_i32 s8, s7, 0x1800
	s_mulk_i32 s7, 0x1800
	s_add_u32 s58, s80, s7
	s_addc_u32 s59, s81, s8
	s_or_b32 s7, s6, 7
	s_mul_hi_i32 s8, s7, 0x1800
	s_mulk_i32 s7, 0x1800
	s_add_u32 s60, s80, s7
	s_addc_u32 s61, s81, s8
	s_or_b32 s7, s6, 8
	s_mul_hi_i32 s8, s7, 0x1800
	s_mulk_i32 s7, 0x1800
	v_or_b32_e32 v2, s84, v74
	s_add_u32 s46, s80, s7
	v_ashrrev_i32_e32 v3, 31, v2
	s_addc_u32 s47, s81, s8
	s_or_b32 s7, s6, 9
	v_lshlrev_b64 v[4:5], 2, v[2:3]
	s_mul_hi_i32 s8, s7, 0x1800
	s_mulk_i32 s7, 0x1800
	v_lshl_add_u64 v[2:3], s[52:53], 0, v[4:5]
	v_lshl_add_u64 v[4:5], s[54:55], 0, v[4:5]
	s_add_u32 s54, s80, s7
	s_addc_u32 s55, s81, s8
	s_or_b32 s7, s6, 10
	s_mul_hi_i32 s8, s7, 0x1800
	s_mulk_i32 s7, 0x1800
	s_add_u32 s48, s80, s7
	s_addc_u32 s49, s81, s8
	s_or_b32 s7, s6, 11
	s_mul_hi_i32 s8, s7, 0x1800
	s_mulk_i32 s7, 0x1800
	s_add_u32 s56, s80, s7
	s_addc_u32 s57, s81, s8
	s_or_b32 s7, s6, 12
	v_ashrrev_i32_e32 v7, 31, v6
	s_mul_hi_i32 s8, s7, 0x1800
	s_mulk_i32 s7, 0x1800
	v_lshl_add_u64 v[6:7], v[6:7], 2, s[42:43]
	s_add_u32 s42, s80, s7
	s_addc_u32 s43, s81, s8
	s_or_b32 s7, s6, 13
	s_waitcnt vmcnt(15)
	v_lshlrev_b32_e32 v9, 16, v9
	v_mul_f32_e32 v13, v9, v9
	v_mul_f32_e32 v13, 0xbf38aa3b, v13
	v_exp_f32_e32 v13, v13
	s_waitcnt vmcnt(11)
	v_lshlrev_b32_e32 v8, 16, v8
	v_mul_f32_e32 v11, v8, v8
	v_mul_f32_e32 v11, 0xbf38aa3b, v11
	v_fma_f32 v10, |v8|, s92, 1.0
	v_exp_f32_e32 v12, v11
	v_fma_f32 v11, |v9|, s92, 1.0
	v_rcp_f32_e32 v10, v10
	v_rcp_f32_e32 v11, v11
	v_cmp_gt_f32_e32 vcc, 0, v9
	s_mul_hi_i32 s8, s7, 0x1800
	s_mulk_i32 s7, 0x1800
	v_pk_fma_f32 v[14:15], v[10:11], s[12:13], v[24:25] op_sel_hi:[1,0,0]
	s_add_u32 s50, s80, s7
	v_pk_fma_f32 v[14:15], v[10:11], v[14:15], s[14:15] op_sel_hi:[1,1,0]
	s_addc_u32 s51, s81, s8
	v_pk_fma_f32 v[14:15], v[10:11], v[14:15], s[16:17] op_sel_hi:[1,1,0]
	s_or_b32 s7, s6, 14
	v_pk_fma_f32 v[14:15], v[10:11], v[14:15], s[18:19] op_sel_hi:[1,1,0]
	s_mul_hi_i32 s8, s7, 0x1800
	v_pk_mul_f32 v[10:11], v[10:11], v[14:15]
	s_mulk_i32 s7, 0x1800
	v_pk_mul_f32 v[10:11], v[12:13], v[10:11]
	s_add_u32 s44, s80, s7
	v_pk_mul_f32 v[12:13], v[10:11], v[8:9]
	v_pk_fma_f32 v[10:11], v[10:11], v[8:9], v[8:9] neg_lo:[1,0,0] neg_hi:[1,0,0]
	s_addc_u32 s45, s81, s8
	v_cndmask_b32_e32 v17, v11, v13, vcc
	v_cmp_gt_f32_e32 vcc, 0, v8
	s_waitcnt vmcnt(3)
	v_lshlrev_b32_e32 v8, 16, v23
	v_fma_f32 v9, |v8|, s92, 1.0
	v_mul_f32_e32 v11, v8, v8
	v_cndmask_b32_e32 v16, v10, v12, vcc
	v_rcp_f32_e32 v10, v9
	v_mul_f32_e32 v11, 0xbf38aa3b, v11
	v_lshlrev_b32_e32 v9, 16, v18
	v_exp_f32_e32 v12, v11
	v_fma_f32 v11, |v9|, s92, 1.0
	v_rcp_f32_e32 v11, v11
	v_mul_f32_e32 v13, v9, v9
	v_mul_f32_e32 v13, 0xbf38aa3b, v13
	v_exp_f32_e32 v13, v13
	v_pk_fma_f32 v[14:15], v[10:11], s[12:13], v[24:25] op_sel_hi:[1,0,0]
	v_cmp_gt_f32_e32 vcc, 0, v9
	v_pk_fma_f32 v[14:15], v[10:11], v[14:15], s[14:15] op_sel_hi:[1,1,0]
	s_or_b32 s6, s6, 15
	v_pk_fma_f32 v[14:15], v[10:11], v[14:15], s[16:17] op_sel_hi:[1,1,0]
	s_mul_hi_i32 s7, s6, 0x1800
	v_pk_fma_f32 v[14:15], v[10:11], v[14:15], s[18:19] op_sel_hi:[1,1,0]
	s_mulk_i32 s6, 0x1800
	v_pk_mul_f32 v[10:11], v[10:11], v[14:15]
	s_add_u32 s52, s80, s6
	v_pk_mul_f32 v[10:11], v[12:13], v[10:11]
	s_addc_u32 s53, s81, s7
	v_pk_mul_f32 v[12:13], v[10:11], v[8:9]
	v_pk_fma_f32 v[10:11], v[10:11], v[8:9], v[8:9] neg_lo:[1,0,0] neg_hi:[1,0,0]
	s_mov_b32 s8, 0x3b800000
	v_cndmask_b32_e32 v9, v11, v13, vcc
	v_cmp_gt_f32_e32 vcc, 0, v8
	s_ashr_i32 s5, s5, 7
	v_lshlrev_b32_e32 v130, 4, v74
	v_cndmask_b32_e32 v8, v10, v12, vcc
	s_waitcnt vmcnt(2)
	v_lshlrev_b32_e32 v10, 16, v28
	v_fma_f32 v11, |v10|, s92, 1.0
	v_rcp_f32_e32 v12, v11
	v_lshlrev_b32_e32 v11, 16, v19
	v_fma_f32 v13, |v11|, s92, 1.0
	v_rcp_f32_e32 v13, v13
	v_mul_f32_e32 v14, v10, v10
	v_mul_f32_e32 v15, v11, v11
	v_mul_f32_e32 v14, 0xbf38aa3b, v14
	v_pk_fma_f32 v[18:19], v[12:13], s[12:13], v[24:25] op_sel_hi:[1,0,0]
	v_mul_f32_e32 v15, 0xbf38aa3b, v15
	v_exp_f32_e32 v14, v14
	v_pk_fma_f32 v[18:19], v[12:13], v[18:19], s[14:15] op_sel_hi:[1,1,0]
	v_exp_f32_e32 v15, v15
	v_pk_fma_f32 v[18:19], v[12:13], v[18:19], s[16:17] op_sel_hi:[1,1,0]
	v_cmp_gt_f32_e32 vcc, 0, v11
	v_pk_fma_f32 v[18:19], v[12:13], v[18:19], s[18:19] op_sel_hi:[1,1,0]
	s_nop 0
	v_pk_mul_f32 v[12:13], v[12:13], v[18:19]
	v_pk_mul_f32 v[12:13], v[14:15], v[12:13]
	v_pk_mul_f32 v[14:15], v[12:13], v[10:11]
	v_pk_fma_f32 v[12:13], v[12:13], v[10:11], v[10:11] neg_lo:[1,0,0] neg_hi:[1,0,0]
	v_lshlrev_b32_e32 v11, 16, v20
	v_cndmask_b32_e32 v13, v13, v15, vcc
	v_cmp_gt_f32_e32 vcc, 0, v10
	v_lshlrev_b32_e32 v10, 16, v21
	v_mul_f32_e32 v15, v10, v10
	v_mul_f32_e32 v15, 0xbf38aa3b, v15
	v_cndmask_b32_e32 v12, v12, v14, vcc
	v_fma_f32 v14, |v10|, s92, 1.0
	v_exp_f32_e32 v18, v15
	v_fma_f32 v15, |v11|, s92, 1.0
	v_rcp_f32_e32 v14, v14
	v_rcp_f32_e32 v15, v15
	v_mul_f32_e32 v19, v11, v11
	v_mul_f32_e32 v19, 0xbf38aa3b, v19
	v_exp_f32_e32 v19, v19
	v_pk_fma_f32 v[20:21], v[14:15], s[12:13], v[24:25] op_sel_hi:[1,0,0]
	v_cmp_gt_f32_e32 vcc, 0, v11
	v_pk_fma_f32 v[20:21], v[14:15], v[20:21], s[14:15] op_sel_hi:[1,1,0]
	s_nop 0
	v_pk_fma_f32 v[20:21], v[14:15], v[20:21], s[16:17] op_sel_hi:[1,1,0]
	s_nop 0
	v_pk_fma_f32 v[20:21], v[14:15], v[20:21], s[18:19] op_sel_hi:[1,1,0]
	v_pk_mul_f32 v[14:15], v[14:15], v[20:21]
	v_pk_mul_f32 v[14:15], v[18:19], v[14:15]
	v_pk_mul_f32 v[18:19], v[14:15], v[10:11]
	v_pk_fma_f32 v[14:15], v[14:15], v[10:11], v[10:11] neg_lo:[1,0,0] neg_hi:[1,0,0]
	v_lshlrev_b32_e32 v11, 16, v22
	v_cndmask_b32_e32 v19, v15, v19, vcc
	v_cmp_gt_f32_e32 vcc, 0, v10
	s_waitcnt vmcnt(1)
	v_lshlrev_b32_e32 v10, 16, v29
	v_fma_f32 v15, |v11|, s92, 1.0
	v_cndmask_b32_e32 v18, v14, v18, vcc
	v_fma_f32 v14, |v10|, s92, 1.0
	v_rcp_f32_e32 v14, v14
	v_rcp_f32_e32 v15, v15
	v_mul_f32_e32 v20, v10, v10
	v_mul_f32_e32 v21, v11, v11
	v_mul_f32_e32 v20, 0xbf38aa3b, v20
	v_pk_fma_f32 v[22:23], v[14:15], s[12:13], v[24:25] op_sel_hi:[1,0,0]
	v_mul_f32_e32 v21, 0xbf38aa3b, v21
	v_exp_f32_e32 v20, v20
	v_pk_fma_f32 v[22:23], v[14:15], v[22:23], s[14:15] op_sel_hi:[1,1,0]
	v_exp_f32_e32 v21, v21
	v_pk_fma_f32 v[22:23], v[14:15], v[22:23], s[16:17] op_sel_hi:[1,1,0]
	v_cmp_gt_f32_e32 vcc, 0, v11
	v_pk_fma_f32 v[22:23], v[14:15], v[22:23], s[18:19] op_sel_hi:[1,1,0]
	s_nop 0
	v_pk_mul_f32 v[14:15], v[14:15], v[22:23]
	v_pk_mul_f32 v[14:15], v[20:21], v[14:15]
	v_pk_mul_f32 v[20:21], v[14:15], v[10:11]
	v_pk_fma_f32 v[14:15], v[14:15], v[10:11], v[10:11] neg_lo:[1,0,0] neg_hi:[1,0,0]
	v_lshlrev_b32_e32 v11, 16, v26
	v_cndmask_b32_e32 v21, v15, v21, vcc
	v_cmp_gt_f32_e32 vcc, 0, v10
	v_lshlrev_b32_e32 v10, 16, v27
	v_mul_f32_e32 v15, v10, v10
	v_mul_f32_e32 v15, 0xbf38aa3b, v15
	v_cndmask_b32_e32 v20, v14, v20, vcc
	v_fma_f32 v14, |v10|, s92, 1.0
	v_exp_f32_e32 v22, v15
	v_fma_f32 v15, |v11|, s92, 1.0
	v_rcp_f32_e32 v14, v14
	v_rcp_f32_e32 v15, v15
	v_mul_f32_e32 v23, v11, v11
	v_mul_f32_e32 v23, 0xbf38aa3b, v23
	v_exp_f32_e32 v23, v23
	v_pk_fma_f32 v[26:27], v[14:15], s[12:13], v[24:25] op_sel_hi:[1,0,0]
	v_cmp_gt_f32_e32 vcc, 0, v11
	v_pk_fma_f32 v[26:27], v[14:15], v[26:27], s[14:15] op_sel_hi:[1,1,0]
	s_nop 0
	v_pk_fma_f32 v[26:27], v[14:15], v[26:27], s[16:17] op_sel_hi:[1,1,0]
	s_nop 0
	v_pk_fma_f32 v[26:27], v[14:15], v[26:27], s[18:19] op_sel_hi:[1,1,0]
	v_pk_mul_f32 v[14:15], v[14:15], v[26:27]
	v_pk_mul_f32 v[14:15], v[22:23], v[14:15]
	v_pk_mul_f32 v[22:23], v[14:15], v[10:11]
	v_pk_fma_f32 v[14:15], v[14:15], v[10:11], v[10:11] neg_lo:[1,0,0] neg_hi:[1,0,0]
	v_lshlrev_b32_e32 v11, 16, v32
	v_cndmask_b32_e32 v29, v15, v23, vcc
	v_cmp_gt_f32_e32 vcc, 0, v10
	s_waitcnt vmcnt(0)
	v_lshlrev_b32_e32 v10, 16, v33
	v_fma_f32 v15, |v11|, s92, 1.0
	v_cndmask_b32_e32 v28, v14, v22, vcc
	v_fma_f32 v14, |v10|, s92, 1.0
	v_rcp_f32_e32 v14, v14
	v_rcp_f32_e32 v15, v15
	v_mul_f32_e32 v22, v10, v10
	v_mul_f32_e32 v23, v11, v11
	v_mul_f32_e32 v22, 0xbf38aa3b, v22
	v_pk_fma_f32 v[26:27], v[14:15], s[12:13], v[24:25] op_sel_hi:[1,0,0]
	v_mul_f32_e32 v23, 0xbf38aa3b, v23
	v_exp_f32_e32 v22, v22
	v_pk_fma_f32 v[26:27], v[14:15], v[26:27], s[14:15] op_sel_hi:[1,1,0]
	v_exp_f32_e32 v23, v23
	v_pk_fma_f32 v[26:27], v[14:15], v[26:27], s[16:17] op_sel_hi:[1,1,0]
	v_cmp_gt_f32_e32 vcc, 0, v11
	v_pk_fma_f32 v[26:27], v[14:15], v[26:27], s[18:19] op_sel_hi:[1,1,0]
	v_mov_b32_e32 v32, v19
	v_pk_mul_f32 v[14:15], v[14:15], v[26:27]
	v_pk_mul_f32 v[14:15], v[22:23], v[14:15]
	v_pk_mul_f32 v[22:23], v[14:15], v[10:11]
	v_pk_fma_f32 v[14:15], v[14:15], v[10:11], v[10:11] neg_lo:[1,0,0] neg_hi:[1,0,0]
	v_lshlrev_b32_e32 v11, 16, v30
	v_cndmask_b32_e32 v23, v15, v23, vcc
	v_cmp_gt_f32_e32 vcc, 0, v10
	v_lshlrev_b32_e32 v10, 16, v31
	v_mul_f32_e32 v15, v10, v10
	v_mul_f32_e32 v15, 0xbf38aa3b, v15
	v_cndmask_b32_e32 v22, v14, v22, vcc
	v_fma_f32 v14, |v10|, s92, 1.0
	v_exp_f32_e32 v26, v15
	v_fma_f32 v15, |v11|, s92, 1.0
	v_rcp_f32_e32 v14, v14
	v_rcp_f32_e32 v15, v15
	v_mul_f32_e32 v27, v11, v11
	v_mul_f32_e32 v27, 0xbf38aa3b, v27
	v_exp_f32_e32 v27, v27
	v_pk_fma_f32 v[30:31], v[14:15], s[12:13], v[24:25] op_sel_hi:[1,0,0]
	v_cmp_gt_f32_e32 vcc, 0, v11
	v_pk_fma_f32 v[30:31], v[14:15], v[30:31], s[14:15] op_sel_hi:[1,1,0]
	s_nop 0
	v_pk_fma_f32 v[30:31], v[14:15], v[30:31], s[16:17] op_sel_hi:[1,1,0]
	s_nop 0
	v_pk_fma_f32 v[30:31], v[14:15], v[30:31], s[18:19] op_sel_hi:[1,1,0]
	v_pk_mul_f32 v[14:15], v[14:15], v[30:31]
	v_pk_mul_f32 v[14:15], v[26:27], v[14:15]
	v_pk_mul_f32 v[26:27], v[14:15], v[10:11]
	v_pk_fma_f32 v[14:15], v[14:15], v[10:11], v[10:11] neg_lo:[1,0,0] neg_hi:[1,0,0]
	v_mov_b32_e32 v11, v20
	v_cndmask_b32_e32 v31, v15, v27, vcc
	v_cmp_gt_f32_e32 vcc, 0, v10
	v_mov_b32_e32 v10, v8
	v_mov_b32_e32 v15, v22
	v_cndmask_b32_e32 v30, v14, v26, vcc
	v_mov_b32_e32 v14, v12
	v_pk_add_f32 v[10:11], v[10:11], v[14:15]
	v_mov_b32_e32 v14, v9
	v_add_f32_e32 v10, v10, v11
	v_mov_b32_e32 v15, v21
	s_nop 0
	v_add_f32_dpp v10, v10, v10 quad_perm:[1,0,3,2] row_mask:0xf bank_mask:0xf bound_ctrl:1
	v_mov_b32_e32 v26, v13
	v_mov_b32_e32 v27, v23
	v_add_f32_dpp v10, v10, v10 quad_perm:[2,3,0,1] row_mask:0xf bank_mask:0xf bound_ctrl:1
	v_pk_add_f32 v[14:15], v[14:15], v[26:27]
	v_mov_b64_e32 v[26:27], s[8:9]
	v_add_f32_dpp v10, v10, v10 row_half_mirror row_mask:0xf bank_mask:0xf bound_ctrl:1
	v_mov_b32_e32 v33, v31
	s_mov_b32 s8, 0x3e027906
	v_add_f32_dpp v10, v10, v10 row_mirror row_mask:0xf bank_mask:0xf bound_ctrl:1
	s_nop 1
	v_add_f32_dpp v10, v10, v10 row_bcast:15 row_mask:0xa bank_mask:0xf
	s_nop 1
	v_add_f32_dpp v10, v10, v10 row_bcast:31 row_mask:0xc bank_mask:0xf
	v_add_f32_e32 v11, v14, v15
	v_readlane_b32 s6, v10, 63
	s_nop 0
	v_add_f32_dpp v11, v11, v11 quad_perm:[1,0,3,2] row_mask:0xf bank_mask:0xf bound_ctrl:1
	s_xor_b32 s6, s6, 0x80000000
	s_nop 0
	v_add_f32_dpp v11, v11, v11 quad_perm:[2,3,0,1] row_mask:0xf bank_mask:0xf bound_ctrl:1
	s_nop 1
	v_add_f32_dpp v11, v11, v11 row_half_mirror row_mask:0xf bank_mask:0xf bound_ctrl:1
	s_nop 1
	v_add_f32_dpp v11, v11, v11 row_mirror row_mask:0xf bank_mask:0xf bound_ctrl:1
	s_nop 1
	v_add_f32_dpp v11, v11, v11 row_bcast:15 row_mask:0xa bank_mask:0xf
	s_nop 1
	v_add_f32_dpp v11, v11, v11 row_bcast:31 row_mask:0xc bank_mask:0xf
	s_nop 0
	v_readlane_b32 s7, v11, 63
	s_xor_b32 s7, s7, 0x80000000
	s_nop 0
	v_pk_fma_f32 v[10:11], s[6:7], v[26:27], v[8:9] op_sel_hi:[1,0,1]
	v_pk_fma_f32 v[14:15], s[6:7], v[26:27], v[12:13] op_sel_hi:[1,0,1]
	v_pk_fma_f32 v[12:13], s[6:7], v[26:27], v[20:21] op_sel_hi:[1,0,1]
	v_pk_fma_f32 v[8:9], s[6:7], v[26:27], v[22:23] op_sel_hi:[1,0,1]
	v_mov_b32_e32 v20, v16
	v_mov_b32_e32 v21, v28
	v_mov_b32_e32 v22, v18
	v_mov_b32_e32 v23, v30
	v_pk_add_f32 v[20:21], v[20:21], v[22:23]
	v_mov_b32_e32 v22, v17
	v_add_f32_e32 v20, v20, v21
	v_mov_b32_e32 v23, v29
	s_nop 0
	v_add_f32_dpp v20, v20, v20 quad_perm:[1,0,3,2] row_mask:0xf bank_mask:0xf bound_ctrl:1
	v_pk_add_f32 v[22:23], v[22:23], v[32:33]
	s_nop 0
	v_add_f32_dpp v20, v20, v20 quad_perm:[2,3,0,1] row_mask:0xf bank_mask:0xf bound_ctrl:1
	s_nop 1
	v_add_f32_dpp v20, v20, v20 row_half_mirror row_mask:0xf bank_mask:0xf bound_ctrl:1
	s_nop 1
	v_add_f32_dpp v20, v20, v20 row_mirror row_mask:0xf bank_mask:0xf bound_ctrl:1
	s_nop 1
	v_add_f32_dpp v20, v20, v20 row_bcast:15 row_mask:0xa bank_mask:0xf
	s_nop 1
	v_add_f32_dpp v20, v20, v20 row_bcast:31 row_mask:0xc bank_mask:0xf
	v_add_f32_e32 v21, v22, v23
	v_readlane_b32 s6, v20, 63
	s_nop 0
	v_add_f32_dpp v21, v21, v21 quad_perm:[1,0,3,2] row_mask:0xf bank_mask:0xf bound_ctrl:1
	s_xor_b32 s6, s6, 0x80000000
	s_nop 0
	v_add_f32_dpp v21, v21, v21 quad_perm:[2,3,0,1] row_mask:0xf bank_mask:0xf bound_ctrl:1
	s_nop 1
	v_add_f32_dpp v21, v21, v21 row_half_mirror row_mask:0xf bank_mask:0xf bound_ctrl:1
	s_nop 1
	v_add_f32_dpp v21, v21, v21 row_mirror row_mask:0xf bank_mask:0xf bound_ctrl:1
	s_nop 1
	v_add_f32_dpp v21, v21, v21 row_bcast:15 row_mask:0xa bank_mask:0xf
	s_nop 1
	v_add_f32_dpp v21, v21, v21 row_bcast:31 row_mask:0xc bank_mask:0xf
	s_nop 0
	v_readlane_b32 s7, v21, 63
	s_xor_b32 s7, s7, 0x80000000
	s_nop 0
	v_pk_fma_f32 v[22:23], s[6:7], v[26:27], v[16:17] op_sel_hi:[1,0,1]
	v_pk_fma_f32 v[20:21], s[6:7], v[26:27], v[18:19] op_sel_hi:[1,0,1]
	v_pk_fma_f32 v[18:19], s[6:7], v[26:27], v[28:29] op_sel_hi:[1,0,1]
	v_pk_fma_f32 v[16:17], s[6:7], v[26:27], v[30:31] op_sel_hi:[1,0,1]
	global_load_ushort v28, v44, s[60:61] offset:512
	global_load_ushort v38, v44, s[60:61] offset:640
	global_load_ushort v42, v44, s[60:61] offset:768
	global_load_ushort v45, v44, s[60:61] offset:896
	global_load_ushort v30, v44, s[58:59] offset:512
	global_load_ushort v39, v44, s[58:59] offset:640
	global_load_ushort v43, v44, s[58:59] offset:768
	global_load_ushort v48, v44, s[58:59] offset:896
	s_waitcnt vmcnt(7)
	v_lshlrev_b32_e32 v29, 16, v28
	v_fma_f32 v31, |v29|, s92, 1.0
	v_rcp_f32_e32 v31, v31
	v_mul_f32_e32 v33, v29, v29
	s_waitcnt vmcnt(3)
	v_lshlrev_b32_e32 v28, 16, v30
	v_fma_f32 v30, |v28|, s92, 1.0
	v_rcp_f32_e32 v30, v30
	v_mul_f32_e32 v32, v28, v28
	v_mul_f32_e32 v32, 0xbf38aa3b, v32
	v_mul_f32_e32 v33, 0xbf38aa3b, v33
	v_pk_fma_f32 v[34:35], v[30:31], s[12:13], v[24:25] op_sel_hi:[1,0,0]
	v_exp_f32_e32 v32, v32
	v_pk_fma_f32 v[34:35], v[30:31], v[34:35], s[14:15] op_sel_hi:[1,1,0]
	v_exp_f32_e32 v33, v33
	v_pk_fma_f32 v[34:35], v[30:31], v[34:35], s[16:17] op_sel_hi:[1,1,0]
	v_cmp_gt_f32_e32 vcc, 0, v29
	v_pk_fma_f32 v[34:35], v[30:31], v[34:35], s[18:19] op_sel_hi:[1,1,0]
	s_nop 0
	v_pk_mul_f32 v[30:31], v[30:31], v[34:35]
	v_pk_mul_f32 v[30:31], v[32:33], v[30:31]
	v_pk_mul_f32 v[32:33], v[30:31], v[28:29]
	v_pk_fma_f32 v[30:31], v[30:31], v[28:29], v[28:29] neg_lo:[1,0,0] neg_hi:[1,0,0]
	s_nop 0
	v_cndmask_b32_e32 v29, v31, v33, vcc
	v_cmp_gt_f32_e32 vcc, 0, v28
	s_nop 1
	v_cndmask_b32_e32 v28, v30, v32, vcc
	global_load_ushort v30, v44, s[40:41] offset:512
	global_load_ushort v40, v44, s[40:41] offset:640
	global_load_ushort v46, v44, s[40:41] offset:768
	global_load_ushort v50, v44, s[40:41] offset:896
	global_load_ushort v32, v44, s[28:29] offset:512
	global_load_ushort v41, v44, s[28:29] offset:640
	global_load_ushort v47, v44, s[28:29] offset:768
	global_load_ushort v51, v44, s[28:29] offset:896
	s_movk_i32 s40, 0x110
	s_movk_i32 s41, 0x3000
	s_waitcnt vmcnt(7)
	v_lshlrev_b32_e32 v31, 16, v30
	v_mul_f32_e32 v35, v31, v31
	v_mul_f32_e32 v35, 0xbf38aa3b, v35
	v_exp_f32_e32 v35, v35
	s_waitcnt vmcnt(3)
	v_lshlrev_b32_e32 v30, 16, v32
	v_mul_f32_e32 v33, v30, v30
	v_mul_f32_e32 v33, 0xbf38aa3b, v33
	v_fma_f32 v32, |v30|, s92, 1.0
	v_exp_f32_e32 v34, v33
	v_fma_f32 v33, |v31|, s92, 1.0
	v_rcp_f32_e32 v32, v32
	v_rcp_f32_e32 v33, v33
	v_cmp_gt_f32_e32 vcc, 0, v31
	v_pk_fma_f32 v[36:37], v[32:33], s[12:13], v[24:25] op_sel_hi:[1,0,0]
	s_nop 0
	v_pk_fma_f32 v[36:37], v[32:33], v[36:37], s[14:15] op_sel_hi:[1,1,0]
	s_nop 0
	v_pk_fma_f32 v[36:37], v[32:33], v[36:37], s[16:17] op_sel_hi:[1,1,0]
	s_nop 0
	v_pk_fma_f32 v[36:37], v[32:33], v[36:37], s[18:19] op_sel_hi:[1,1,0]
	v_pk_mul_f32 v[32:33], v[32:33], v[36:37]
	v_pk_mul_f32 v[32:33], v[34:35], v[32:33]
	v_pk_mul_f32 v[34:35], v[32:33], v[30:31]
	v_pk_fma_f32 v[32:33], v[32:33], v[30:31], v[30:31] neg_lo:[1,0,0] neg_hi:[1,0,0]
	v_lshlrev_b32_e32 v31, 16, v38
	v_cndmask_b32_e32 v37, v33, v35, vcc
	v_cmp_gt_f32_e32 vcc, 0, v30
	v_lshlrev_b32_e32 v30, 16, v39
	v_fma_f32 v33, |v31|, s92, 1.0
	v_cndmask_b32_e32 v36, v32, v34, vcc
	v_fma_f32 v32, |v30|, s92, 1.0
	v_rcp_f32_e32 v32, v32
	v_rcp_f32_e32 v33, v33
	v_mul_f32_e32 v34, v30, v30
	v_mul_f32_e32 v35, v31, v31
	v_mul_f32_e32 v34, 0xbf38aa3b, v34
	v_pk_fma_f32 v[38:39], v[32:33], s[12:13], v[24:25] op_sel_hi:[1,0,0]
	v_mul_f32_e32 v35, 0xbf38aa3b, v35
	v_exp_f32_e32 v34, v34
	v_pk_fma_f32 v[38:39], v[32:33], v[38:39], s[14:15] op_sel_hi:[1,1,0]
	v_exp_f32_e32 v35, v35
	v_pk_fma_f32 v[38:39], v[32:33], v[38:39], s[16:17] op_sel_hi:[1,1,0]
	v_cmp_gt_f32_e32 vcc, 0, v31
	v_pk_fma_f32 v[38:39], v[32:33], v[38:39], s[18:19] op_sel_hi:[1,1,0]
	s_nop 0
	v_pk_mul_f32 v[32:33], v[32:33], v[38:39]
	v_pk_mul_f32 v[32:33], v[34:35], v[32:33]
	v_pk_mul_f32 v[34:35], v[32:33], v[30:31]
	v_pk_fma_f32 v[32:33], v[32:33], v[30:31], v[30:31] neg_lo:[1,0,0] neg_hi:[1,0,0]
	s_nop 0
	v_cndmask_b32_e32 v31, v33, v35, vcc
	v_cmp_gt_f32_e32 vcc, 0, v30
	v_lshlrev_b32_e32 v33, 16, v40
	v_mul_f32_e32 v39, v33, v33
	v_cndmask_b32_e32 v30, v32, v34, vcc
	s_waitcnt vmcnt(2)
	v_lshlrev_b32_e32 v32, 16, v41
	v_mul_f32_e32 v35, v32, v32
	v_mul_f32_e32 v35, 0xbf38aa3b, v35
	v_fma_f32 v34, |v32|, s92, 1.0
	v_exp_f32_e32 v38, v35
	v_fma_f32 v35, |v33|, s92, 1.0
	v_rcp_f32_e32 v34, v34
	v_rcp_f32_e32 v35, v35
	v_mul_f32_e32 v39, 0xbf38aa3b, v39
	v_exp_f32_e32 v39, v39
	v_cmp_gt_f32_e32 vcc, 0, v33
	v_pk_fma_f32 v[40:41], v[34:35], s[12:13], v[24:25] op_sel_hi:[1,0,0]
	s_nop 0
	v_pk_fma_f32 v[40:41], v[34:35], v[40:41], s[14:15] op_sel_hi:[1,1,0]
	s_nop 0
	v_pk_fma_f32 v[40:41], v[34:35], v[40:41], s[16:17] op_sel_hi:[1,1,0]
	s_nop 0
	v_pk_fma_f32 v[40:41], v[34:35], v[40:41], s[18:19] op_sel_hi:[1,1,0]
	v_pk_mul_f32 v[34:35], v[34:35], v[40:41]
	v_pk_mul_f32 v[34:35], v[38:39], v[34:35]
	v_pk_mul_f32 v[38:39], v[34:35], v[32:33]
	v_pk_fma_f32 v[34:35], v[34:35], v[32:33], v[32:33] neg_lo:[1,0,0] neg_hi:[1,0,0]
	v_lshlrev_b32_e32 v33, 16, v42
	v_cndmask_b32_e32 v39, v35, v39, vcc
	v_cmp_gt_f32_e32 vcc, 0, v32
	v_lshlrev_b32_e32 v32, 16, v43
	v_fma_f32 v35, |v33|, s92, 1.0
	v_cndmask_b32_e32 v38, v34, v38, vcc
	v_fma_f32 v34, |v32|, s92, 1.0
	v_rcp_f32_e32 v34, v34
	v_rcp_f32_e32 v35, v35
	v_mul_f32_e32 v40, v32, v32
	v_mul_f32_e32 v41, v33, v33
	v_mul_f32_e32 v40, 0xbf38aa3b, v40
	v_pk_fma_f32 v[42:43], v[34:35], s[12:13], v[24:25] op_sel_hi:[1,0,0]
	v_mul_f32_e32 v41, 0xbf38aa3b, v41
	v_exp_f32_e32 v40, v40
	v_pk_fma_f32 v[42:43], v[34:35], v[42:43], s[14:15] op_sel_hi:[1,1,0]
	v_exp_f32_e32 v41, v41
	v_pk_fma_f32 v[42:43], v[34:35], v[42:43], s[16:17] op_sel_hi:[1,1,0]
	v_cmp_gt_f32_e32 vcc, 0, v33
	v_pk_fma_f32 v[42:43], v[34:35], v[42:43], s[18:19] op_sel_hi:[1,1,0]
	s_nop 0
	v_pk_mul_f32 v[34:35], v[34:35], v[42:43]
	v_pk_mul_f32 v[34:35], v[40:41], v[34:35]
	v_pk_mul_f32 v[40:41], v[34:35], v[32:33]
	v_pk_fma_f32 v[34:35], v[34:35], v[32:33], v[32:33] neg_lo:[1,0,0] neg_hi:[1,0,0]
	v_lshlrev_b32_e32 v33, 16, v46
	v_cndmask_b32_e32 v41, v35, v41, vcc
	v_cmp_gt_f32_e32 vcc, 0, v32
	s_waitcnt vmcnt(1)
	v_lshlrev_b32_e32 v32, 16, v47
	v_mul_f32_e32 v35, v32, v32
	v_mul_f32_e32 v35, 0xbf38aa3b, v35
	v_cndmask_b32_e32 v40, v34, v40, vcc
	v_fma_f32 v34, |v32|, s92, 1.0
	v_exp_f32_e32 v42, v35
	v_fma_f32 v35, |v33|, s92, 1.0
	v_rcp_f32_e32 v34, v34
	v_rcp_f32_e32 v35, v35
	v_mul_f32_e32 v43, v33, v33
	v_mul_f32_e32 v43, 0xbf38aa3b, v43
	v_exp_f32_e32 v43, v43
	v_pk_fma_f32 v[46:47], v[34:35], s[12:13], v[24:25] op_sel_hi:[1,0,0]
	v_cmp_gt_f32_e32 vcc, 0, v33
	v_pk_fma_f32 v[46:47], v[34:35], v[46:47], s[14:15] op_sel_hi:[1,1,0]
	s_nop 0
	v_pk_fma_f32 v[46:47], v[34:35], v[46:47], s[16:17] op_sel_hi:[1,1,0]
	s_nop 0
	v_pk_fma_f32 v[46:47], v[34:35], v[46:47], s[18:19] op_sel_hi:[1,1,0]
	v_pk_mul_f32 v[34:35], v[34:35], v[46:47]
	v_pk_mul_f32 v[34:35], v[42:43], v[34:35]
	v_pk_mul_f32 v[42:43], v[34:35], v[32:33]
	v_pk_fma_f32 v[34:35], v[34:35], v[32:33], v[32:33] neg_lo:[1,0,0] neg_hi:[1,0,0]
	v_lshlrev_b32_e32 v33, 16, v45
	v_cndmask_b32_e32 v47, v35, v43, vcc
	v_cmp_gt_f32_e32 vcc, 0, v32
	v_lshlrev_b32_e32 v32, 16, v48
	v_fma_f32 v35, |v33|, s92, 1.0
	v_cndmask_b32_e32 v46, v34, v42, vcc
	v_fma_f32 v34, |v32|, s92, 1.0
	v_rcp_f32_e32 v34, v34
	v_rcp_f32_e32 v35, v35
	v_mul_f32_e32 v42, v32, v32
	v_mul_f32_e32 v43, v33, v33
	v_mul_f32_e32 v42, 0xbf38aa3b, v42
	v_pk_fma_f32 v[48:49], v[34:35], s[12:13], v[24:25] op_sel_hi:[1,0,0]
	v_mul_f32_e32 v43, 0xbf38aa3b, v43
	v_exp_f32_e32 v42, v42
	v_pk_fma_f32 v[48:49], v[34:35], v[48:49], s[14:15] op_sel_hi:[1,1,0]
	v_exp_f32_e32 v43, v43
	v_pk_fma_f32 v[48:49], v[34:35], v[48:49], s[16:17] op_sel_hi:[1,1,0]
	v_cmp_gt_f32_e32 vcc, 0, v33
	v_pk_fma_f32 v[48:49], v[34:35], v[48:49], s[18:19] op_sel_hi:[1,1,0]
	s_nop 0
	v_pk_mul_f32 v[34:35], v[34:35], v[48:49]
	v_pk_mul_f32 v[34:35], v[42:43], v[34:35]
	v_pk_mul_f32 v[42:43], v[34:35], v[32:33]
	v_pk_fma_f32 v[34:35], v[34:35], v[32:33], v[32:33] neg_lo:[1,0,0] neg_hi:[1,0,0]
	v_lshlrev_b32_e32 v33, 16, v50
	v_cndmask_b32_e32 v43, v35, v43, vcc
	v_cmp_gt_f32_e32 vcc, 0, v32
	s_waitcnt vmcnt(0)
	v_lshlrev_b32_e32 v32, 16, v51
	v_mul_f32_e32 v35, v32, v32
	v_mul_f32_e32 v35, 0xbf38aa3b, v35
	v_cndmask_b32_e32 v42, v34, v42, vcc
	v_fma_f32 v34, |v32|, s92, 1.0
	v_exp_f32_e32 v48, v35
	v_fma_f32 v35, |v33|, s92, 1.0
	v_rcp_f32_e32 v34, v34
	v_rcp_f32_e32 v35, v35
	v_mul_f32_e32 v45, v33, v33
	v_mul_f32_e32 v45, 0xbf38aa3b, v45
	v_exp_f32_e32 v49, v45
	v_pk_fma_f32 v[50:51], v[34:35], s[12:13], v[24:25] op_sel_hi:[1,0,0]
	v_cmp_gt_f32_e32 vcc, 0, v33
	v_pk_fma_f32 v[50:51], v[34:35], v[50:51], s[14:15] op_sel_hi:[1,1,0]
	s_nop 0
	v_pk_fma_f32 v[50:51], v[34:35], v[50:51], s[16:17] op_sel_hi:[1,1,0]
	s_nop 0
	v_pk_fma_f32 v[50:51], v[34:35], v[50:51], s[18:19] op_sel_hi:[1,1,0]
	v_pk_mul_f32 v[34:35], v[34:35], v[50:51]
	v_mov_b32_e32 v50, v31
	v_pk_mul_f32 v[34:35], v[48:49], v[34:35]
	v_mov_b32_e32 v51, v43
	v_pk_mul_f32 v[48:49], v[34:35], v[32:33]
	v_pk_fma_f32 v[34:35], v[34:35], v[32:33], v[32:33] neg_lo:[1,0,0] neg_hi:[1,0,0]
	v_mov_b32_e32 v33, v40
	v_cndmask_b32_e32 v49, v35, v49, vcc
	v_cmp_gt_f32_e32 vcc, 0, v32
	v_mov_b32_e32 v32, v28
	v_mov_b32_e32 v35, v42
	v_cndmask_b32_e32 v48, v34, v48, vcc
	v_mov_b32_e32 v34, v30
	v_pk_add_f32 v[32:33], v[32:33], v[34:35]
	v_mov_b32_e32 v34, v29
	v_add_f32_e32 v32, v32, v33
	v_mov_b32_e32 v35, v41
	s_nop 0
	v_add_f32_dpp v32, v32, v32 quad_perm:[1,0,3,2] row_mask:0xf bank_mask:0xf bound_ctrl:1
	v_pk_add_f32 v[34:35], v[34:35], v[50:51]
	v_mov_b32_e32 v50, v39
	v_add_f32_dpp v32, v32, v32 quad_perm:[2,3,0,1] row_mask:0xf bank_mask:0xf bound_ctrl:1
	v_mov_b32_e32 v51, v49
	s_nop 0
	v_add_f32_dpp v32, v32, v32 row_half_mirror row_mask:0xf bank_mask:0xf bound_ctrl:1
	s_nop 1
	v_add_f32_dpp v32, v32, v32 row_mirror row_mask:0xf bank_mask:0xf bound_ctrl:1
	s_nop 1
	v_add_f32_dpp v32, v32, v32 row_bcast:15 row_mask:0xa bank_mask:0xf
	s_nop 1
	v_add_f32_dpp v32, v32, v32 row_bcast:31 row_mask:0xc bank_mask:0xf
	v_add_f32_e32 v33, v34, v35
	v_readlane_b32 s6, v32, 63
	s_nop 0
	v_add_f32_dpp v33, v33, v33 quad_perm:[1,0,3,2] row_mask:0xf bank_mask:0xf bound_ctrl:1
	s_xor_b32 s6, s6, 0x80000000
	s_nop 0
	v_add_f32_dpp v33, v33, v33 quad_perm:[2,3,0,1] row_mask:0xf bank_mask:0xf bound_ctrl:1
	s_nop 1
	v_add_f32_dpp v33, v33, v33 row_half_mirror row_mask:0xf bank_mask:0xf bound_ctrl:1
	s_nop 1
	v_add_f32_dpp v33, v33, v33 row_mirror row_mask:0xf bank_mask:0xf bound_ctrl:1
	s_nop 1
	v_add_f32_dpp v33, v33, v33 row_bcast:15 row_mask:0xa bank_mask:0xf
	s_nop 1
	v_add_f32_dpp v33, v33, v33 row_bcast:31 row_mask:0xc bank_mask:0xf
	s_nop 0
	v_readlane_b32 s7, v33, 63
	s_xor_b32 s7, s7, 0x80000000
	s_nop 0
	v_pk_fma_f32 v[34:35], s[6:7], v[26:27], v[28:29] op_sel_hi:[1,0,1]
	v_pk_fma_f32 v[32:33], s[6:7], v[26:27], v[30:31] op_sel_hi:[1,0,1]
	v_pk_fma_f32 v[30:31], s[6:7], v[26:27], v[40:41] op_sel_hi:[1,0,1]
	v_pk_fma_f32 v[28:29], s[6:7], v[26:27], v[42:43] op_sel_hi:[1,0,1]
	v_mov_b32_e32 v40, v36
	v_mov_b32_e32 v41, v46
	v_mov_b32_e32 v42, v38
	v_mov_b32_e32 v43, v48
	v_pk_add_f32 v[40:41], v[40:41], v[42:43]
	v_mov_b32_e32 v42, v37
	v_add_f32_e32 v40, v40, v41
	v_mov_b32_e32 v43, v47
	s_nop 0
	v_add_f32_dpp v40, v40, v40 quad_perm:[1,0,3,2] row_mask:0xf bank_mask:0xf bound_ctrl:1
	v_pk_add_f32 v[42:43], v[42:43], v[50:51]
	s_nop 0
	v_add_f32_dpp v40, v40, v40 quad_perm:[2,3,0,1] row_mask:0xf bank_mask:0xf bound_ctrl:1
	s_nop 1
	v_add_f32_dpp v40, v40, v40 row_half_mirror row_mask:0xf bank_mask:0xf bound_ctrl:1
	s_nop 1
	v_add_f32_dpp v40, v40, v40 row_mirror row_mask:0xf bank_mask:0xf bound_ctrl:1
	s_nop 1
	v_add_f32_dpp v40, v40, v40 row_bcast:15 row_mask:0xa bank_mask:0xf
	s_nop 1
	v_add_f32_dpp v40, v40, v40 row_bcast:31 row_mask:0xc bank_mask:0xf
	v_add_f32_e32 v41, v42, v43
	v_readlane_b32 s6, v40, 63
	s_nop 0
	v_add_f32_dpp v41, v41, v41 quad_perm:[1,0,3,2] row_mask:0xf bank_mask:0xf bound_ctrl:1
	s_xor_b32 s6, s6, 0x80000000
	s_nop 0
	v_add_f32_dpp v41, v41, v41 quad_perm:[2,3,0,1] row_mask:0xf bank_mask:0xf bound_ctrl:1
	s_nop 1
	v_add_f32_dpp v41, v41, v41 row_half_mirror row_mask:0xf bank_mask:0xf bound_ctrl:1
	s_nop 1
	v_add_f32_dpp v41, v41, v41 row_mirror row_mask:0xf bank_mask:0xf bound_ctrl:1
	s_nop 1
	v_add_f32_dpp v41, v41, v41 row_bcast:15 row_mask:0xa bank_mask:0xf
	s_nop 1
	v_add_f32_dpp v41, v41, v41 row_bcast:31 row_mask:0xc bank_mask:0xf
	s_nop 0
	v_readlane_b32 s7, v41, 63
	s_xor_b32 s7, s7, 0x80000000
	s_nop 0
	v_pk_fma_f32 v[40:41], s[6:7], v[26:27], v[38:39] op_sel_hi:[1,0,1]
	v_pk_fma_f32 v[38:39], s[6:7], v[26:27], v[46:47] op_sel_hi:[1,0,1]
	global_load_ushort v52, v44, s[54:55] offset:512
	global_load_ushort v56, v44, s[54:55] offset:640
	global_load_ushort v77, v44, s[54:55] offset:768
	global_load_ushort v82, v44, s[54:55] offset:896
	global_load_ushort v53, v44, s[46:47] offset:512
	global_load_ushort v57, v44, s[46:47] offset:640
	global_load_ushort v78, v44, s[46:47] offset:768
	global_load_ushort v83, v44, s[46:47] offset:896
	global_load_ushort v45, v44, s[56:57] offset:512
	global_load_ushort v54, v44, s[56:57] offset:640
	global_load_ushort v58, v44, s[56:57] offset:768
	global_load_ushort v80, v44, s[56:57] offset:896
	global_load_ushort v46, v44, s[48:49] offset:512
	global_load_ushort v55, v44, s[48:49] offset:640
	global_load_ushort v59, v44, s[48:49] offset:768
	global_load_ushort v81, v44, s[48:49] offset:896
	global_load_ushort v66, v44, s[50:51] offset:512
	global_load_ushort v68, v44, s[50:51] offset:640
	global_load_ushort v72, v44, s[50:51] offset:768
	global_load_ushort v64, v44, s[50:51] offset:896
	global_load_ushort v67, v44, s[42:43] offset:512
	global_load_ushort v69, v44, s[42:43] offset:640
	global_load_ushort v73, v44, s[42:43] offset:768
	global_load_ushort v65, v44, s[42:43] offset:896
	global_load_ushort v60, v44, s[52:53] offset:512
	global_load_ushort v62, v44, s[52:53] offset:640
	global_load_ushort v75, v44, s[52:53] offset:768
	global_load_ushort v70, v44, s[52:53] offset:896
	global_load_ushort v61, v44, s[44:45] offset:512
	global_load_ushort v63, v44, s[44:45] offset:640
	global_load_ushort v76, v44, s[44:45] offset:768
	global_load_ushort v71, v44, s[44:45] offset:896
	v_pk_fma_f32 v[42:43], s[6:7], v[26:27], v[36:37] op_sel_hi:[1,0,1]
	v_pk_fma_f32 v[36:37], s[6:7], v[26:27], v[48:49] op_sel_hi:[1,0,1]
	s_movk_i32 s46, 0x2000
	s_waitcnt vmcnt(23)
	v_lshlrev_b32_e32 v45, 16, v45
	v_fma_f32 v47, |v45|, s92, 1.0
	v_rcp_f32_e32 v47, v47
	v_mul_f32_e32 v49, v45, v45
	s_waitcnt vmcnt(19)
	v_lshlrev_b32_e32 v44, 16, v46
	v_fma_f32 v46, |v44|, s92, 1.0
	v_rcp_f32_e32 v46, v46
	v_mul_f32_e32 v48, v44, v44
	v_mul_f32_e32 v48, 0xbf38aa3b, v48
	v_mul_f32_e32 v49, 0xbf38aa3b, v49
	v_pk_fma_f32 v[50:51], v[46:47], s[12:13], v[24:25] op_sel_hi:[1,0,0]
	v_exp_f32_e32 v48, v48
	v_pk_fma_f32 v[50:51], v[46:47], v[50:51], s[14:15] op_sel_hi:[1,1,0]
	v_exp_f32_e32 v49, v49
	v_pk_fma_f32 v[50:51], v[46:47], v[50:51], s[16:17] op_sel_hi:[1,1,0]
	v_cmp_gt_f32_e32 vcc, 0, v45
	v_pk_fma_f32 v[50:51], v[46:47], v[50:51], s[18:19] op_sel_hi:[1,1,0]
	s_waitcnt vmcnt(1)
	v_lshlrev_b32_e32 v76, 16, v76
	v_pk_mul_f32 v[46:47], v[46:47], v[50:51]
	v_pk_mul_f32 v[46:47], v[48:49], v[46:47]
	v_pk_mul_f32 v[48:49], v[46:47], v[44:45]
	v_pk_fma_f32 v[46:47], v[46:47], v[44:45], v[44:45] neg_lo:[1,0,0] neg_hi:[1,0,0]
	s_nop 0
	v_cndmask_b32_e32 v45, v47, v49, vcc
	v_cmp_gt_f32_e32 vcc, 0, v44
	v_lshlrev_b32_e32 v47, 16, v52
	v_mul_f32_e32 v51, v47, v47
	v_cndmask_b32_e32 v44, v46, v48, vcc
	v_lshlrev_b32_e32 v46, 16, v53
	v_mul_f32_e32 v49, v46, v46
	v_mul_f32_e32 v49, 0xbf38aa3b, v49
	v_fma_f32 v48, |v46|, s92, 1.0
	v_exp_f32_e32 v50, v49
	v_fma_f32 v49, |v47|, s92, 1.0
	v_rcp_f32_e32 v48, v48
	v_rcp_f32_e32 v49, v49
	v_mul_f32_e32 v51, 0xbf38aa3b, v51
	v_exp_f32_e32 v51, v51
	v_cmp_gt_f32_e32 vcc, 0, v47
	v_pk_fma_f32 v[52:53], v[48:49], s[12:13], v[24:25] op_sel_hi:[1,0,0]
	s_nop 0
	v_pk_fma_f32 v[52:53], v[48:49], v[52:53], s[14:15] op_sel_hi:[1,1,0]
	s_nop 0
	v_pk_fma_f32 v[52:53], v[48:49], v[52:53], s[16:17] op_sel_hi:[1,1,0]
	s_nop 0
	v_pk_fma_f32 v[52:53], v[48:49], v[52:53], s[18:19] op_sel_hi:[1,1,0]
	v_pk_mul_f32 v[48:49], v[48:49], v[52:53]
	v_pk_mul_f32 v[48:49], v[50:51], v[48:49]
	v_pk_mul_f32 v[50:51], v[48:49], v[46:47]
	v_pk_fma_f32 v[48:49], v[48:49], v[46:47], v[46:47] neg_lo:[1,0,0] neg_hi:[1,0,0]
	v_lshlrev_b32_e32 v47, 16, v54
	v_cndmask_b32_e32 v53, v49, v51, vcc
	v_cmp_gt_f32_e32 vcc, 0, v46
	v_lshlrev_b32_e32 v46, 16, v55
	v_fma_f32 v49, |v47|, s92, 1.0
	v_cndmask_b32_e32 v52, v48, v50, vcc
	v_fma_f32 v48, |v46|, s92, 1.0
	v_rcp_f32_e32 v48, v48
	v_rcp_f32_e32 v49, v49
	v_mul_f32_e32 v50, v46, v46
	v_mul_f32_e32 v51, v47, v47
	v_mul_f32_e32 v50, 0xbf38aa3b, v50
	v_pk_fma_f32 v[54:55], v[48:49], s[12:13], v[24:25] op_sel_hi:[1,0,0]
	v_mul_f32_e32 v51, 0xbf38aa3b, v51
	v_exp_f32_e32 v50, v50
	v_pk_fma_f32 v[54:55], v[48:49], v[54:55], s[14:15] op_sel_hi:[1,1,0]
	v_exp_f32_e32 v51, v51
	v_pk_fma_f32 v[54:55], v[48:49], v[54:55], s[16:17] op_sel_hi:[1,1,0]
	v_cmp_gt_f32_e32 vcc, 0, v47
	v_pk_fma_f32 v[54:55], v[48:49], v[54:55], s[18:19] op_sel_hi:[1,1,0]
	s_nop 0
	v_pk_mul_f32 v[48:49], v[48:49], v[54:55]
	v_pk_mul_f32 v[48:49], v[50:51], v[48:49]
	v_pk_mul_f32 v[50:51], v[48:49], v[46:47]
	v_pk_fma_f32 v[48:49], v[48:49], v[46:47], v[46:47] neg_lo:[1,0,0] neg_hi:[1,0,0]
	v_lshlrev_b32_e32 v47, 16, v56
	v_cndmask_b32_e32 v49, v49, v51, vcc
	v_cmp_gt_f32_e32 vcc, 0, v46
	v_lshlrev_b32_e32 v46, 16, v57
	v_mul_f32_e32 v51, v46, v46
	v_mul_f32_e32 v51, 0xbf38aa3b, v51
	v_cndmask_b32_e32 v48, v48, v50, vcc
	v_fma_f32 v50, |v46|, s92, 1.0
	v_exp_f32_e32 v54, v51
	v_fma_f32 v51, |v47|, s92, 1.0
	v_rcp_f32_e32 v50, v50
	v_rcp_f32_e32 v51, v51
	v_mul_f32_e32 v55, v47, v47
	v_mul_f32_e32 v55, 0xbf38aa3b, v55
	v_exp_f32_e32 v55, v55
	v_pk_fma_f32 v[56:57], v[50:51], s[12:13], v[24:25] op_sel_hi:[1,0,0]
	v_cmp_gt_f32_e32 vcc, 0, v47
	v_pk_fma_f32 v[56:57], v[50:51], v[56:57], s[14:15] op_sel_hi:[1,1,0]
	s_nop 0
	v_pk_fma_f32 v[56:57], v[50:51], v[56:57], s[16:17] op_sel_hi:[1,1,0]
	s_nop 0
	v_pk_fma_f32 v[56:57], v[50:51], v[56:57], s[18:19] op_sel_hi:[1,1,0]
	v_pk_mul_f32 v[50:51], v[50:51], v[56:57]
	v_pk_mul_f32 v[50:51], v[54:55], v[50:51]
	v_pk_mul_f32 v[54:55], v[50:51], v[46:47]
	v_pk_fma_f32 v[50:51], v[50:51], v[46:47], v[46:47] neg_lo:[1,0,0] neg_hi:[1,0,0]
	v_lshlrev_b32_e32 v47, 16, v58
	v_cndmask_b32_e32 v55, v51, v55, vcc
	v_cmp_gt_f32_e32 vcc, 0, v46
	v_lshlrev_b32_e32 v46, 16, v59
	v_fma_f32 v51, |v47|, s92, 1.0
	v_cndmask_b32_e32 v54, v50, v54, vcc
	v_fma_f32 v50, |v46|, s92, 1.0
	v_rcp_f32_e32 v50, v50
	v_rcp_f32_e32 v51, v51
	v_mul_f32_e32 v56, v46, v46
	v_mul_f32_e32 v57, v47, v47
	v_mul_f32_e32 v56, 0xbf38aa3b, v56
	v_pk_fma_f32 v[58:59], v[50:51], s[12:13], v[24:25] op_sel_hi:[1,0,0]
	v_mul_f32_e32 v57, 0xbf38aa3b, v57
	v_exp_f32_e32 v56, v56
	v_pk_fma_f32 v[58:59], v[50:51], v[58:59], s[14:15] op_sel_hi:[1,1,0]
	v_exp_f32_e32 v57, v57
	v_pk_fma_f32 v[58:59], v[50:51], v[58:59], s[16:17] op_sel_hi:[1,1,0]
	v_cmp_gt_f32_e32 vcc, 0, v47
	v_pk_fma_f32 v[58:59], v[50:51], v[58:59], s[18:19] op_sel_hi:[1,1,0]
	s_nop 0
	v_pk_mul_f32 v[50:51], v[50:51], v[58:59]
	v_pk_mul_f32 v[50:51], v[56:57], v[50:51]
	v_pk_mul_f32 v[56:57], v[50:51], v[46:47]
	v_pk_fma_f32 v[50:51], v[50:51], v[46:47], v[46:47] neg_lo:[1,0,0] neg_hi:[1,0,0]
	v_lshlrev_b32_e32 v47, 16, v77
	v_cndmask_b32_e32 v57, v51, v57, vcc
	v_cmp_gt_f32_e32 vcc, 0, v46
	v_lshlrev_b32_e32 v46, 16, v78
	v_mul_f32_e32 v51, v46, v46
	v_mul_f32_e32 v51, 0xbf38aa3b, v51
	v_cndmask_b32_e32 v56, v50, v56, vcc
	v_fma_f32 v50, |v46|, s92, 1.0
	v_exp_f32_e32 v58, v51
	v_fma_f32 v51, |v47|, s92, 1.0
	v_rcp_f32_e32 v50, v50
	v_rcp_f32_e32 v51, v51
	v_mul_f32_e32 v59, v47, v47
	v_mul_f32_e32 v59, 0xbf38aa3b, v59
	v_exp_f32_e32 v59, v59
	v_pk_fma_f32 v[78:79], v[50:51], s[12:13], v[24:25] op_sel_hi:[1,0,0]
	v_cmp_gt_f32_e32 vcc, 0, v47
	v_pk_fma_f32 v[78:79], v[50:51], v[78:79], s[14:15] op_sel_hi:[1,1,0]
	s_nop 0
	v_pk_fma_f32 v[78:79], v[50:51], v[78:79], s[16:17] op_sel_hi:[1,1,0]
	s_nop 0
	v_pk_fma_f32 v[78:79], v[50:51], v[78:79], s[18:19] op_sel_hi:[1,1,0]
	v_pk_mul_f32 v[50:51], v[50:51], v[78:79]
	v_pk_mul_f32 v[50:51], v[58:59], v[50:51]
	v_pk_mul_f32 v[58:59], v[50:51], v[46:47]
	v_pk_fma_f32 v[50:51], v[50:51], v[46:47], v[46:47] neg_lo:[1,0,0] neg_hi:[1,0,0]
	v_lshlrev_b32_e32 v47, 16, v80
	v_cndmask_b32_e32 v79, v51, v59, vcc
	v_cmp_gt_f32_e32 vcc, 0, v46
	v_lshlrev_b32_e32 v46, 16, v81
	v_fma_f32 v51, |v47|, s92, 1.0
	v_cndmask_b32_e32 v78, v50, v58, vcc
	v_fma_f32 v50, |v46|, s92, 1.0
	v_rcp_f32_e32 v50, v50
	v_rcp_f32_e32 v51, v51
	v_mul_f32_e32 v58, v46, v46
	v_mul_f32_e32 v59, v47, v47
	v_mul_f32_e32 v58, 0xbf38aa3b, v58
	v_pk_fma_f32 v[80:81], v[50:51], s[12:13], v[24:25] op_sel_hi:[1,0,0]
	v_mul_f32_e32 v59, 0xbf38aa3b, v59
	v_exp_f32_e32 v58, v58
	v_pk_fma_f32 v[80:81], v[50:51], v[80:81], s[14:15] op_sel_hi:[1,1,0]
	v_exp_f32_e32 v59, v59
	v_pk_fma_f32 v[80:81], v[50:51], v[80:81], s[16:17] op_sel_hi:[1,1,0]
	v_cmp_gt_f32_e32 vcc, 0, v47
	v_pk_fma_f32 v[80:81], v[50:51], v[80:81], s[18:19] op_sel_hi:[1,1,0]
	s_nop 0
	v_pk_mul_f32 v[50:51], v[50:51], v[80:81]
	v_pk_mul_f32 v[50:51], v[58:59], v[50:51]
	v_pk_mul_f32 v[58:59], v[50:51], v[46:47]
	v_pk_fma_f32 v[50:51], v[50:51], v[46:47], v[46:47] neg_lo:[1,0,0] neg_hi:[1,0,0]
	v_lshlrev_b32_e32 v47, 16, v82
	v_cndmask_b32_e32 v59, v51, v59, vcc
	v_cmp_gt_f32_e32 vcc, 0, v46
	v_lshlrev_b32_e32 v46, 16, v83
	v_mul_f32_e32 v51, v46, v46
	v_mul_f32_e32 v51, 0xbf38aa3b, v51
	v_cndmask_b32_e32 v58, v50, v58, vcc
	v_fma_f32 v50, |v46|, s92, 1.0
	v_exp_f32_e32 v80, v51
	v_fma_f32 v51, |v47|, s92, 1.0
	v_rcp_f32_e32 v50, v50
	v_rcp_f32_e32 v51, v51
	v_mul_f32_e32 v77, v47, v47
	v_mul_f32_e32 v77, 0xbf38aa3b, v77
	v_exp_f32_e32 v81, v77
	v_pk_fma_f32 v[82:83], v[50:51], s[12:13], v[24:25] op_sel_hi:[1,0,0]
	v_cmp_gt_f32_e32 vcc, 0, v47
	v_pk_fma_f32 v[82:83], v[50:51], v[82:83], s[14:15] op_sel_hi:[1,1,0]
	s_nop 0
	v_pk_fma_f32 v[82:83], v[50:51], v[82:83], s[16:17] op_sel_hi:[1,1,0]
	s_nop 0
	v_pk_fma_f32 v[82:83], v[50:51], v[82:83], s[18:19] op_sel_hi:[1,1,0]
	v_pk_mul_f32 v[50:51], v[50:51], v[82:83]
	v_mov_b32_e32 v82, v49
	v_pk_mul_f32 v[50:51], v[80:81], v[50:51]
	v_mov_b32_e32 v83, v59
	v_pk_mul_f32 v[80:81], v[50:51], v[46:47]
	v_pk_fma_f32 v[50:51], v[50:51], v[46:47], v[46:47] neg_lo:[1,0,0] neg_hi:[1,0,0]
	v_mov_b32_e32 v47, v56
	v_cndmask_b32_e32 v81, v51, v81, vcc
	v_cmp_gt_f32_e32 vcc, 0, v46
	v_mov_b32_e32 v46, v44
	v_mov_b32_e32 v51, v58
	v_cndmask_b32_e32 v80, v50, v80, vcc
	v_mov_b32_e32 v50, v48
	v_pk_add_f32 v[46:47], v[46:47], v[50:51]
	v_mov_b32_e32 v50, v45
	v_add_f32_e32 v46, v46, v47
	v_mov_b32_e32 v51, v57
	s_nop 0
	v_add_f32_dpp v46, v46, v46 quad_perm:[1,0,3,2] row_mask:0xf bank_mask:0xf bound_ctrl:1
	v_pk_add_f32 v[50:51], v[50:51], v[82:83]
	v_mov_b32_e32 v82, v55
	v_add_f32_dpp v46, v46, v46 quad_perm:[2,3,0,1] row_mask:0xf bank_mask:0xf bound_ctrl:1
	v_mov_b32_e32 v83, v81
	s_nop 0
	v_add_f32_dpp v46, v46, v46 row_half_mirror row_mask:0xf bank_mask:0xf bound_ctrl:1
	s_nop 1
	v_add_f32_dpp v46, v46, v46 row_mirror row_mask:0xf bank_mask:0xf bound_ctrl:1
	s_nop 1
	v_add_f32_dpp v46, v46, v46 row_bcast:15 row_mask:0xa bank_mask:0xf
	s_nop 1
	v_add_f32_dpp v46, v46, v46 row_bcast:31 row_mask:0xc bank_mask:0xf
	v_add_f32_e32 v47, v50, v51
	v_readlane_b32 s6, v46, 63
	s_nop 0
	v_add_f32_dpp v47, v47, v47 quad_perm:[1,0,3,2] row_mask:0xf bank_mask:0xf bound_ctrl:1
	s_xor_b32 s6, s6, 0x80000000
	s_nop 0
	v_add_f32_dpp v47, v47, v47 quad_perm:[2,3,0,1] row_mask:0xf bank_mask:0xf bound_ctrl:1
	s_nop 1
	v_add_f32_dpp v47, v47, v47 row_half_mirror row_mask:0xf bank_mask:0xf bound_ctrl:1
	s_nop 1
	v_add_f32_dpp v47, v47, v47 row_mirror row_mask:0xf bank_mask:0xf bound_ctrl:1
	s_nop 1
	v_add_f32_dpp v47, v47, v47 row_bcast:15 row_mask:0xa bank_mask:0xf
	s_nop 1
	v_add_f32_dpp v47, v47, v47 row_bcast:31 row_mask:0xc bank_mask:0xf
	s_nop 0
	v_readlane_b32 s7, v47, 63
	s_xor_b32 s7, s7, 0x80000000
	s_nop 0
	v_pk_fma_f32 v[46:47], s[6:7], v[26:27], v[44:45] op_sel_hi:[1,0,1]
	v_pk_fma_f32 v[50:51], s[6:7], v[26:27], v[48:49] op_sel_hi:[1,0,1]
	v_pk_fma_f32 v[48:49], s[6:7], v[26:27], v[56:57] op_sel_hi:[1,0,1]
	v_pk_fma_f32 v[44:45], s[6:7], v[26:27], v[58:59] op_sel_hi:[1,0,1]
	v_mov_b32_e32 v56, v52
	v_mov_b32_e32 v57, v78
	v_mov_b32_e32 v58, v54
	v_mov_b32_e32 v59, v80
	v_pk_add_f32 v[56:57], v[56:57], v[58:59]
	v_mov_b32_e32 v58, v53
	v_add_f32_e32 v56, v56, v57
	v_mov_b32_e32 v59, v79
	s_nop 0
	v_add_f32_dpp v56, v56, v56 quad_perm:[1,0,3,2] row_mask:0xf bank_mask:0xf bound_ctrl:1
	v_pk_add_f32 v[58:59], v[58:59], v[82:83]
	s_nop 0
	v_add_f32_dpp v56, v56, v56 quad_perm:[2,3,0,1] row_mask:0xf bank_mask:0xf bound_ctrl:1
	s_nop 1
	v_add_f32_dpp v56, v56, v56 row_half_mirror row_mask:0xf bank_mask:0xf bound_ctrl:1
	s_nop 1
	v_add_f32_dpp v56, v56, v56 row_mirror row_mask:0xf bank_mask:0xf bound_ctrl:1
	s_nop 1
	v_add_f32_dpp v56, v56, v56 row_bcast:15 row_mask:0xa bank_mask:0xf
	s_nop 1
	v_add_f32_dpp v56, v56, v56 row_bcast:31 row_mask:0xc bank_mask:0xf
	v_add_f32_e32 v57, v58, v59
	v_readlane_b32 s6, v56, 63
	s_nop 0
	v_add_f32_dpp v57, v57, v57 quad_perm:[1,0,3,2] row_mask:0xf bank_mask:0xf bound_ctrl:1
	s_xor_b32 s6, s6, 0x80000000
	s_nop 0
	v_add_f32_dpp v57, v57, v57 quad_perm:[2,3,0,1] row_mask:0xf bank_mask:0xf bound_ctrl:1
	s_nop 1
	v_add_f32_dpp v57, v57, v57 row_half_mirror row_mask:0xf bank_mask:0xf bound_ctrl:1
	s_nop 1
	v_add_f32_dpp v57, v57, v57 row_mirror row_mask:0xf bank_mask:0xf bound_ctrl:1
	s_nop 1
	v_add_f32_dpp v57, v57, v57 row_bcast:15 row_mask:0xa bank_mask:0xf
	s_nop 1
	v_add_f32_dpp v57, v57, v57 row_bcast:31 row_mask:0xc bank_mask:0xf
	s_nop 0
	v_readlane_b32 s7, v57, 63
	s_xor_b32 s7, s7, 0x80000000
	s_nop 0
	v_pk_fma_f32 v[56:57], s[6:7], v[26:27], v[54:55] op_sel_hi:[1,0,1]
	v_pk_fma_f32 v[54:55], s[6:7], v[26:27], v[78:79] op_sel_hi:[1,0,1]
	v_lshlrev_b32_e32 v79, 16, v60
	v_lshlrev_b32_e32 v78, 16, v61
	v_fma_f32 v60, |v78|, s92, 1.0
	v_fma_f32 v61, |v79|, s92, 1.0
	v_rcp_f32_e32 v60, v60
	v_rcp_f32_e32 v61, v61
	v_mul_f32_e32 v77, v78, v78
	v_mul_f32_e32 v77, 0xbf38aa3b, v77
	v_pk_fma_f32 v[58:59], s[6:7], v[26:27], v[52:53] op_sel_hi:[1,0,1]
	v_pk_fma_f32 v[52:53], s[6:7], v[26:27], v[80:81] op_sel_hi:[1,0,1]
	v_exp_f32_e32 v80, v77
	v_mul_f32_e32 v77, v79, v79
	v_pk_fma_f32 v[82:83], v[60:61], s[12:13], v[24:25] op_sel_hi:[1,0,0]
	v_mul_f32_e32 v77, 0xbf38aa3b, v77
	v_pk_fma_f32 v[82:83], v[60:61], v[82:83], s[14:15] op_sel_hi:[1,1,0]
	v_exp_f32_e32 v81, v77
	v_pk_fma_f32 v[82:83], v[60:61], v[82:83], s[16:17] op_sel_hi:[1,1,0]
	v_cmp_gt_f32_e32 vcc, 0, v79
	v_pk_fma_f32 v[82:83], v[60:61], v[82:83], s[18:19] op_sel_hi:[1,1,0]
	s_mov_b32 s6, 0xbe11a98e
	v_pk_mul_f32 v[60:61], v[60:61], v[82:83]
	v_pk_mul_f32 v[60:61], v[80:81], v[60:61]
	v_pk_mul_f32 v[80:81], v[60:61], v[78:79]
	v_pk_fma_f32 v[60:61], v[60:61], v[78:79], v[78:79] neg_lo:[1,0,0] neg_hi:[1,0,0]
	v_lshlrev_b32_e32 v79, 16, v66
	v_cndmask_b32_e32 v61, v61, v81, vcc
	v_cmp_gt_f32_e32 vcc, 0, v78
	v_lshlrev_b32_e32 v78, 16, v67
	v_mul_f32_e32 v67, v78, v78
	v_mul_f32_e32 v67, 0xbf38aa3b, v67
	v_cndmask_b32_e32 v60, v60, v80, vcc
	v_fma_f32 v66, |v78|, s92, 1.0
	v_exp_f32_e32 v80, v67
	v_fma_f32 v67, |v79|, s92, 1.0
	v_rcp_f32_e32 v66, v66
	v_rcp_f32_e32 v67, v67
	v_mul_f32_e32 v77, v79, v79
	v_mul_f32_e32 v77, 0xbf38aa3b, v77
	v_exp_f32_e32 v81, v77
	v_pk_fma_f32 v[82:83], v[66:67], s[12:13], v[24:25] op_sel_hi:[1,0,0]
	v_cmp_gt_f32_e32 vcc, 0, v79
	v_pk_fma_f32 v[82:83], v[66:67], v[82:83], s[14:15] op_sel_hi:[1,1,0]
	s_nop 0
	v_pk_fma_f32 v[82:83], v[66:67], v[82:83], s[16:17] op_sel_hi:[1,1,0]
	s_nop 0
	v_pk_fma_f32 v[82:83], v[66:67], v[82:83], s[18:19] op_sel_hi:[1,1,0]
	v_pk_mul_f32 v[66:67], v[66:67], v[82:83]
	v_pk_mul_f32 v[66:67], v[80:81], v[66:67]
	v_pk_mul_f32 v[80:81], v[66:67], v[78:79]
	v_pk_fma_f32 v[66:67], v[66:67], v[78:79], v[78:79] neg_lo:[1,0,0] neg_hi:[1,0,0]
	v_lshlrev_b32_e32 v79, 16, v62
	v_cndmask_b32_e32 v67, v67, v81, vcc
	v_cmp_gt_f32_e32 vcc, 0, v78
	v_lshlrev_b32_e32 v78, 16, v63
	v_fma_f32 v62, |v78|, s92, 1.0
	v_fma_f32 v63, |v79|, s92, 1.0
	v_rcp_f32_e32 v62, v62
	v_rcp_f32_e32 v63, v63
	v_mul_f32_e32 v77, v78, v78
	v_mul_f32_e32 v77, 0xbf38aa3b, v77
	v_cndmask_b32_e32 v66, v66, v80, vcc
	v_exp_f32_e32 v80, v77
	v_mul_f32_e32 v77, v79, v79
	v_pk_fma_f32 v[82:83], v[62:63], s[12:13], v[24:25] op_sel_hi:[1,0,0]
	v_mul_f32_e32 v77, 0xbf38aa3b, v77
	v_pk_fma_f32 v[82:83], v[62:63], v[82:83], s[14:15] op_sel_hi:[1,1,0]
	v_exp_f32_e32 v81, v77
	v_pk_fma_f32 v[82:83], v[62:63], v[82:83], s[16:17] op_sel_hi:[1,1,0]
	v_cmp_gt_f32_e32 vcc, 0, v79
	v_pk_fma_f32 v[82:83], v[62:63], v[82:83], s[18:19] op_sel_hi:[1,1,0]
	s_nop 0
	v_pk_mul_f32 v[62:63], v[62:63], v[82:83]
	v_pk_mul_f32 v[62:63], v[80:81], v[62:63]
	v_pk_mul_f32 v[80:81], v[62:63], v[78:79]
	v_pk_fma_f32 v[62:63], v[62:63], v[78:79], v[78:79] neg_lo:[1,0,0] neg_hi:[1,0,0]
	v_lshlrev_b32_e32 v79, 16, v68
	v_cndmask_b32_e32 v63, v63, v81, vcc
	v_cmp_gt_f32_e32 vcc, 0, v78
	v_lshlrev_b32_e32 v78, 16, v69
	v_mul_f32_e32 v69, v78, v78
	v_mul_f32_e32 v69, 0xbf38aa3b, v69
	v_cndmask_b32_e32 v62, v62, v80, vcc
	v_fma_f32 v68, |v78|, s92, 1.0
	v_exp_f32_e32 v80, v69
	v_fma_f32 v69, |v79|, s92, 1.0
	v_rcp_f32_e32 v68, v68
	v_rcp_f32_e32 v69, v69
	v_mul_f32_e32 v77, v79, v79
	v_mul_f32_e32 v77, 0xbf38aa3b, v77
	v_exp_f32_e32 v81, v77
	v_pk_fma_f32 v[82:83], v[68:69], s[12:13], v[24:25] op_sel_hi:[1,0,0]
	v_cmp_gt_f32_e32 vcc, 0, v79
	v_pk_fma_f32 v[82:83], v[68:69], v[82:83], s[14:15] op_sel_hi:[1,1,0]
	v_lshlrev_b32_e32 v77, 16, v75
	v_pk_fma_f32 v[82:83], v[68:69], v[82:83], s[16:17] op_sel_hi:[1,1,0]
	v_fma_f32 v75, |v76|, s92, 1.0
	v_pk_fma_f32 v[82:83], v[68:69], v[82:83], s[18:19] op_sel_hi:[1,1,0]
	v_pk_mul_f32 v[68:69], v[68:69], v[82:83]
	v_pk_mul_f32 v[68:69], v[80:81], v[68:69]
	v_pk_mul_f32 v[80:81], v[68:69], v[78:79]
	v_pk_fma_f32 v[68:69], v[68:69], v[78:79], v[78:79] neg_lo:[1,0,0] neg_hi:[1,0,0]
	s_nop 0
	v_cndmask_b32_e32 v69, v69, v81, vcc
	v_cmp_gt_f32_e32 vcc, 0, v78
	v_rcp_f32_e32 v78, v75
	v_fma_f32 v75, |v77|, s92, 1.0
	v_rcp_f32_e32 v79, v75
	v_mul_f32_e32 v75, v76, v76
	v_mul_f32_e32 v75, 0xbf38aa3b, v75
	v_cndmask_b32_e32 v68, v68, v80, vcc
	v_exp_f32_e32 v80, v75
	v_mul_f32_e32 v75, v77, v77
	v_pk_fma_f32 v[82:83], v[78:79], s[12:13], v[24:25] op_sel_hi:[1,0,0]
	v_mul_f32_e32 v75, 0xbf38aa3b, v75
	v_pk_fma_f32 v[82:83], v[78:79], v[82:83], s[14:15] op_sel_hi:[1,1,0]
	v_exp_f32_e32 v81, v75
	v_pk_fma_f32 v[82:83], v[78:79], v[82:83], s[16:17] op_sel_hi:[1,1,0]
	v_cmp_gt_f32_e32 vcc, 0, v77
	v_pk_fma_f32 v[82:83], v[78:79], v[82:83], s[18:19] op_sel_hi:[1,1,0]
	s_nop 0
	v_pk_mul_f32 v[78:79], v[78:79], v[82:83]
	v_pk_mul_f32 v[78:79], v[80:81], v[78:79]
	v_pk_mul_f32 v[80:81], v[78:79], v[76:77]
	v_pk_fma_f32 v[78:79], v[78:79], v[76:77], v[76:77] neg_lo:[1,0,0] neg_hi:[1,0,0]
	s_nop 0
	v_cndmask_b32_e32 v77, v79, v81, vcc
	v_cmp_gt_f32_e32 vcc, 0, v76
	v_lshlrev_b32_e32 v79, 16, v72
	v_mul_f32_e32 v75, v79, v79
	v_cndmask_b32_e32 v76, v78, v80, vcc
	v_lshlrev_b32_e32 v78, 16, v73
	v_mul_f32_e32 v73, v78, v78
	v_mul_f32_e32 v73, 0xbf38aa3b, v73
	v_fma_f32 v72, |v78|, s92, 1.0
	v_exp_f32_e32 v80, v73
	v_fma_f32 v73, |v79|, s92, 1.0
	v_rcp_f32_e32 v72, v72
	v_rcp_f32_e32 v73, v73
	v_mul_f32_e32 v75, 0xbf38aa3b, v75
	v_exp_f32_e32 v81, v75
	v_cmp_gt_f32_e32 vcc, 0, v79
	v_pk_fma_f32 v[82:83], v[72:73], s[12:13], v[24:25] op_sel_hi:[1,0,0]
	s_nop 0
	v_pk_fma_f32 v[82:83], v[72:73], v[82:83], s[14:15] op_sel_hi:[1,1,0]
	s_nop 0
	v_pk_fma_f32 v[82:83], v[72:73], v[82:83], s[16:17] op_sel_hi:[1,1,0]
	s_nop 0
	v_pk_fma_f32 v[82:83], v[72:73], v[82:83], s[18:19] op_sel_hi:[1,1,0]
	v_pk_mul_f32 v[72:73], v[72:73], v[82:83]
	v_pk_mul_f32 v[72:73], v[80:81], v[72:73]
	v_pk_mul_f32 v[80:81], v[72:73], v[78:79]
	v_pk_fma_f32 v[72:73], v[72:73], v[78:79], v[78:79] neg_lo:[1,0,0] neg_hi:[1,0,0]
	v_lshlrev_b32_e32 v79, 16, v70
	v_cndmask_b32_e32 v73, v73, v81, vcc
	v_cmp_gt_f32_e32 vcc, 0, v78
	s_waitcnt vmcnt(0)
	v_lshlrev_b32_e32 v78, 16, v71
	v_fma_f32 v70, |v78|, s92, 1.0
	v_fma_f32 v71, |v79|, s92, 1.0
	v_rcp_f32_e32 v70, v70
	v_rcp_f32_e32 v71, v71
	v_mul_f32_e32 v75, v78, v78
	v_mul_f32_e32 v75, 0xbf38aa3b, v75
	v_cndmask_b32_e32 v72, v72, v80, vcc
	v_exp_f32_e32 v80, v75
	v_mul_f32_e32 v75, v79, v79
	v_pk_fma_f32 v[82:83], v[70:71], s[12:13], v[24:25] op_sel_hi:[1,0,0]
	v_mul_f32_e32 v75, 0xbf38aa3b, v75
	v_pk_fma_f32 v[82:83], v[70:71], v[82:83], s[14:15] op_sel_hi:[1,1,0]
	v_exp_f32_e32 v81, v75
	v_pk_fma_f32 v[82:83], v[70:71], v[82:83], s[16:17] op_sel_hi:[1,1,0]
	v_cmp_gt_f32_e32 vcc, 0, v79
	v_pk_fma_f32 v[82:83], v[70:71], v[82:83], s[18:19] op_sel_hi:[1,1,0]
	s_nop 0
	v_pk_mul_f32 v[70:71], v[70:71], v[82:83]
	v_pk_mul_f32 v[70:71], v[80:81], v[70:71]
	v_pk_mul_f32 v[80:81], v[70:71], v[78:79]
	v_pk_fma_f32 v[70:71], v[70:71], v[78:79], v[78:79] neg_lo:[1,0,0] neg_hi:[1,0,0]
	v_lshlrev_b32_e32 v79, 16, v64
	v_cndmask_b32_e32 v71, v71, v81, vcc
	v_cmp_gt_f32_e32 vcc, 0, v78
	v_lshlrev_b32_e32 v78, 16, v65
	v_mul_f32_e32 v65, v78, v78
	v_mul_f32_e32 v65, 0xbf38aa3b, v65
	v_cndmask_b32_e32 v70, v70, v80, vcc
	v_fma_f32 v64, |v78|, s92, 1.0
	v_exp_f32_e32 v80, v65
	v_fma_f32 v65, |v79|, s92, 1.0
	v_rcp_f32_e32 v64, v64
	v_rcp_f32_e32 v65, v65
	v_mul_f32_e32 v75, v79, v79
	v_mul_f32_e32 v75, 0xbf38aa3b, v75
	v_exp_f32_e32 v81, v75
	v_pk_fma_f32 v[24:25], v[64:65], s[12:13], v[24:25] op_sel_hi:[1,0,0]
	v_cmp_gt_f32_e32 vcc, 0, v79
	v_pk_fma_f32 v[24:25], v[64:65], v[24:25], s[14:15] op_sel_hi:[1,1,0]
	v_mov_b32_e32 v75, v131
	v_pk_fma_f32 v[24:25], v[64:65], v[24:25], s[6:7] op_sel_hi:[1,1,0]
	s_mov_b64 s[12:13], s[68:69]
	v_pk_fma_f32 v[24:25], v[64:65], v[24:25], s[8:9] op_sel_hi:[1,1,0]
	s_mov_b64 s[68:69], s[10:11]
	v_pk_mul_f32 v[24:25], v[64:65], v[24:25]
	v_pk_mul_f32 v[24:25], v[80:81], v[24:25]
	v_mov_b32_e32 v80, v63
	v_pk_mul_f32 v[64:65], v[24:25], v[78:79]
	v_pk_fma_f32 v[24:25], v[24:25], v[78:79], v[78:79] neg_lo:[1,0,0] neg_hi:[1,0,0]
	v_mov_b32_e32 v81, v71
	v_cndmask_b32_e32 v79, v25, v65, vcc
	v_cmp_gt_f32_e32 vcc, 0, v78
	v_mov_b32_e32 v25, v76
	v_mov_b32_e32 v65, v70
	v_cndmask_b32_e32 v78, v24, v64, vcc
	v_mov_b32_e32 v24, v60
	v_mov_b32_e32 v64, v62
	v_pk_add_f32 v[24:25], v[24:25], v[64:65]
	v_mov_b32_e32 v64, v61
	v_add_f32_e32 v24, v24, v25
	v_mov_b32_e32 v65, v77
	s_nop 0
	v_add_f32_dpp v24, v24, v24 quad_perm:[1,0,3,2] row_mask:0xf bank_mask:0xf bound_ctrl:1
	v_pk_add_f32 v[64:65], v[64:65], v[80:81]
	v_mov_b32_e32 v80, v69
	v_add_f32_dpp v24, v24, v24 quad_perm:[2,3,0,1] row_mask:0xf bank_mask:0xf bound_ctrl:1
	v_mov_b32_e32 v81, v79
	s_nop 0
	v_add_f32_dpp v24, v24, v24 row_half_mirror row_mask:0xf bank_mask:0xf bound_ctrl:1
	s_nop 1
	v_add_f32_dpp v24, v24, v24 row_mirror row_mask:0xf bank_mask:0xf bound_ctrl:1
	s_nop 1
	v_add_f32_dpp v24, v24, v24 row_bcast:15 row_mask:0xa bank_mask:0xf
	s_nop 1
	v_add_f32_dpp v24, v24, v24 row_bcast:31 row_mask:0xc bank_mask:0xf
	v_add_f32_e32 v25, v64, v65
	v_readlane_b32 s6, v24, 63
	s_nop 0
	v_add_f32_dpp v25, v25, v25 quad_perm:[1,0,3,2] row_mask:0xf bank_mask:0xf bound_ctrl:1
	s_xor_b32 s6, s6, 0x80000000
	s_nop 0
	v_add_f32_dpp v25, v25, v25 quad_perm:[2,3,0,1] row_mask:0xf bank_mask:0xf bound_ctrl:1
	s_nop 1
	v_add_f32_dpp v25, v25, v25 row_half_mirror row_mask:0xf bank_mask:0xf bound_ctrl:1
	s_nop 1
	v_add_f32_dpp v25, v25, v25 row_mirror row_mask:0xf bank_mask:0xf bound_ctrl:1
	s_nop 1
	v_add_f32_dpp v25, v25, v25 row_bcast:15 row_mask:0xa bank_mask:0xf
	s_nop 1
	v_add_f32_dpp v25, v25, v25 row_bcast:31 row_mask:0xc bank_mask:0xf
	s_nop 0
	v_readlane_b32 s7, v25, 63
	s_xor_b32 s7, s7, 0x80000000
	s_nop 0
	v_pk_fma_f32 v[64:65], s[6:7], v[26:27], v[60:61] op_sel_hi:[1,0,1]
	v_pk_fma_f32 v[60:61], s[6:7], v[26:27], v[76:77] op_sel_hi:[1,0,1]
	v_pk_fma_f32 v[24:25], s[6:7], v[26:27], v[70:71] op_sel_hi:[1,0,1]
	v_mov_b32_e32 v70, v66
	v_mov_b32_e32 v71, v72
	v_mov_b32_e32 v76, v68
	v_mov_b32_e32 v77, v78
	v_pk_add_f32 v[70:71], v[70:71], v[76:77]
	v_mov_b32_e32 v76, v67
	v_add_f32_e32 v70, v70, v71
	v_mov_b32_e32 v77, v73
	s_nop 0
	v_add_f32_dpp v70, v70, v70 quad_perm:[1,0,3,2] row_mask:0xf bank_mask:0xf bound_ctrl:1
	v_pk_add_f32 v[76:77], v[76:77], v[80:81]
	v_pk_fma_f32 v[62:63], s[6:7], v[26:27], v[62:63] op_sel_hi:[1,0,1]
	v_add_f32_dpp v70, v70, v70 quad_perm:[2,3,0,1] row_mask:0xf bank_mask:0xf bound_ctrl:1
	s_nop 1
	v_add_f32_dpp v70, v70, v70 row_half_mirror row_mask:0xf bank_mask:0xf bound_ctrl:1
	s_nop 1
	v_add_f32_dpp v70, v70, v70 row_mirror row_mask:0xf bank_mask:0xf bound_ctrl:1
	s_nop 1
	v_add_f32_dpp v70, v70, v70 row_bcast:15 row_mask:0xa bank_mask:0xf
	s_nop 1
	v_add_f32_dpp v70, v70, v70 row_bcast:31 row_mask:0xc bank_mask:0xf
	v_add_f32_e32 v71, v76, v77
	v_readlane_b32 s6, v70, 63
	s_xor_b32 s6, s6, 0x80000000
	v_add_f32_dpp v71, v71, v71 quad_perm:[1,0,3,2] row_mask:0xf bank_mask:0xf bound_ctrl:1
	v_mov_b32_e32 v76, v20
	v_mov_b32_e32 v77, v16
	v_add_f32_dpp v71, v71, v71 quad_perm:[2,3,0,1] row_mask:0xf bank_mask:0xf bound_ctrl:1
	v_pk_mul_f32 v[76:77], v[76:77], v[76:77]
	s_nop 0
	v_add_f32_dpp v71, v71, v71 row_half_mirror row_mask:0xf bank_mask:0xf bound_ctrl:1
	s_nop 1
	v_add_f32_dpp v71, v71, v71 row_mirror row_mask:0xf bank_mask:0xf bound_ctrl:1
	s_nop 1
	v_mov_b32_dpp v75, v71 row_bcast:15 row_mask:0xa bank_mask:0xf
	v_add_f32_e32 v71, v71, v75
	v_mov_b32_e32 v75, v131
	s_nop 1
	v_mov_b32_dpp v75, v71 row_bcast:31 row_mask:0xc bank_mask:0xf
	v_add_f32_e32 v71, v71, v75
	s_nop 0
	v_readlane_b32 s7, v71, 63
	s_xor_b32 s7, s7, 0x80000000
	s_nop 0
	v_pk_fma_f32 v[70:71], s[6:7], v[26:27], v[66:67] op_sel_hi:[1,0,1]
	v_pk_fma_f32 v[66:67], s[6:7], v[26:27], v[72:73] op_sel_hi:[1,0,1]
	v_mov_b32_e32 v72, v22
	v_mov_b32_e32 v73, v18
	v_pk_fma_f32 v[72:73], v[72:73], v[72:73], v[76:77]
	v_pk_fma_f32 v[68:69], s[6:7], v[26:27], v[68:69] op_sel_hi:[1,0,1]
	v_add_f32_e32 v72, v72, v73
	v_pk_fma_f32 v[26:27], s[6:7], v[26:27], v[78:79] op_sel_hi:[1,0,1]
	s_nop 0
	v_add_f32_dpp v72, v72, v72 quad_perm:[1,0,3,2] row_mask:0xf bank_mask:0xf bound_ctrl:1
	s_lshl_b32 s6, s65, 5
	s_add_i32 s7, s5, s73
	v_add_f32_dpp v72, v72, v72 quad_perm:[2,3,0,1] row_mask:0xf bank_mask:0xf bound_ctrl:1
	s_mul_hi_i32 s8, s7, 0x5000
	s_mulk_i32 s7, 0x5000
	v_add_f32_dpp v72, v72, v72 row_half_mirror row_mask:0xf bank_mask:0xf bound_ctrl:1
	s_lshl_b32 s5, s5, 9
	s_add_i32 s9, s6, 0
	v_add_f32_dpp v72, v72, v72 row_mirror row_mask:0xf bank_mask:0xf bound_ctrl:1
	v_mov_b32_e32 v76, v21
	v_mov_b32_e32 v77, v17
	v_add_f32_dpp v72, v72, v72 row_bcast:15 row_mask:0xa bank_mask:0xf
	s_add_u32 s28, s34, s7
	v_pk_mul_f32 v[76:77], v[76:77], v[76:77]
	v_add_f32_dpp v72, v72, v72 row_bcast:31 row_mask:0xc bank_mask:0xf
	v_mov_b32_e32 v73, v19
	v_readlane_b32 s7, v72, 63
	v_mov_b32_e32 v72, v23
	v_pk_fma_f32 v[72:73], v[72:73], v[72:73], v[76:77]
	v_mov_b32_e32 v76, v14
	v_add_f32_e32 v72, v72, v73
	v_mov_b32_e32 v77, v8
	s_nop 0
	v_add_f32_dpp v72, v72, v72 quad_perm:[1,0,3,2] row_mask:0xf bank_mask:0xf bound_ctrl:1
	v_fma_f32 v79, s7, v235, v225
	v_pk_mul_f32 v[76:77], v[76:77], v[76:77]
	v_add_f32_dpp v72, v72, v72 quad_perm:[2,3,0,1] row_mask:0xf bank_mask:0xf bound_ctrl:1
	s_addc_u32 s29, s64, s8
	v_readlane_b32 s8, v253, 54
	v_add_f32_dpp v72, v72, v72 row_half_mirror row_mask:0xf bank_mask:0xf bound_ctrl:1
	v_mov_b32_e32 v75, s9
	s_add_i32 s5, s8, s5
	v_add_f32_dpp v72, v72, v72 row_mirror row_mask:0xf bank_mask:0xf bound_ctrl:1
	s_nop 1
	v_add_f32_dpp v72, v72, v72 row_bcast:15 row_mask:0xa bank_mask:0xf
	s_nop 1
	v_add_f32_dpp v72, v72, v72 row_bcast:31 row_mask:0xc bank_mask:0xf
	v_mov_b32_e32 v73, v12
	v_readlane_b32 s7, v72, 63
	v_mov_b32_e32 v72, v10
	v_pk_fma_f32 v[72:73], v[72:73], v[72:73], v[76:77]
	v_mov_b32_e32 v76, v15
	v_add_f32_e32 v72, v72, v73
	v_mov_b32_e32 v77, v9
	s_nop 0
	v_add_f32_dpp v72, v72, v72 quad_perm:[1,0,3,2] row_mask:0xf bank_mask:0xf bound_ctrl:1
	v_fma_f32 v81, s7, v235, v225
	v_pk_mul_f32 v[76:77], v[76:77], v[76:77]
	v_add_f32_dpp v72, v72, v72 quad_perm:[2,3,0,1] row_mask:0xf bank_mask:0xf bound_ctrl:1
	s_nop 1
	v_add_f32_dpp v72, v72, v72 row_half_mirror row_mask:0xf bank_mask:0xf bound_ctrl:1
	s_nop 1
	v_add_f32_dpp v72, v72, v72 row_mirror row_mask:0xf bank_mask:0xf bound_ctrl:1
	s_nop 1
	v_add_f32_dpp v72, v72, v72 row_bcast:15 row_mask:0xa bank_mask:0xf
	s_nop 1
	v_add_f32_dpp v72, v72, v72 row_bcast:31 row_mask:0xc bank_mask:0xf
	v_mov_b32_e32 v73, v13
	v_readlane_b32 s7, v72, 63
	v_mov_b32_e32 v72, v11
	v_pk_fma_f32 v[72:73], v[72:73], v[72:73], v[76:77]
	v_mov_b32_e32 v76, v40
	v_add_f32_e32 v72, v72, v73
	v_mov_b32_e32 v77, v36
	s_nop 0
	v_add_f32_dpp v72, v72, v72 quad_perm:[1,0,3,2] row_mask:0xf bank_mask:0xf bound_ctrl:1
	v_fma_f32 v83, s7, v235, v225
	v_pk_mul_f32 v[76:77], v[76:77], v[76:77]
	v_add_f32_dpp v72, v72, v72 quad_perm:[2,3,0,1] row_mask:0xf bank_mask:0xf bound_ctrl:1
	s_nop 1
	v_add_f32_dpp v72, v72, v72 row_half_mirror row_mask:0xf bank_mask:0xf bound_ctrl:1
	s_nop 1
	v_add_f32_dpp v72, v72, v72 row_mirror row_mask:0xf bank_mask:0xf bound_ctrl:1
	s_nop 1
	v_add_f32_dpp v72, v72, v72 row_bcast:15 row_mask:0xa bank_mask:0xf
	s_nop 1
	v_add_f32_dpp v72, v72, v72 row_bcast:31 row_mask:0xc bank_mask:0xf
	v_mov_b32_e32 v73, v38
	v_readlane_b32 s7, v72, 63
	v_mov_b32_e32 v72, v42
	v_pk_fma_f32 v[72:73], v[72:73], v[72:73], v[76:77]
	v_mov_b32_e32 v76, v41
	v_add_f32_e32 v72, v72, v73
	v_mov_b32_e32 v77, v37
	s_nop 0
	v_add_f32_dpp v72, v72, v72 quad_perm:[1,0,3,2] row_mask:0xf bank_mask:0xf bound_ctrl:1
	v_fma_f32 v85, s7, v235, v225
	v_pk_mul_f32 v[76:77], v[76:77], v[76:77]
	v_add_f32_dpp v72, v72, v72 quad_perm:[2,3,0,1] row_mask:0xf bank_mask:0xf bound_ctrl:1
	s_nop 1
	v_add_f32_dpp v72, v72, v72 row_half_mirror row_mask:0xf bank_mask:0xf bound_ctrl:1
	s_nop 1
	v_add_f32_dpp v72, v72, v72 row_mirror row_mask:0xf bank_mask:0xf bound_ctrl:1
	s_nop 1
	v_add_f32_dpp v72, v72, v72 row_bcast:15 row_mask:0xa bank_mask:0xf
	s_nop 1
	v_add_f32_dpp v72, v72, v72 row_bcast:31 row_mask:0xc bank_mask:0xf
	v_mov_b32_e32 v73, v39
	v_readlane_b32 s7, v72, 63
	v_mov_b32_e32 v72, v43
	v_pk_fma_f32 v[72:73], v[72:73], v[72:73], v[76:77]
	v_mov_b32_e32 v76, v32
	v_add_f32_e32 v72, v72, v73
	v_mov_b32_e32 v77, v28
	s_nop 0
	v_add_f32_dpp v72, v72, v72 quad_perm:[1,0,3,2] row_mask:0xf bank_mask:0xf bound_ctrl:1
	v_fma_f32 v87, s7, v235, v225
	v_pk_mul_f32 v[76:77], v[76:77], v[76:77]
	v_add_f32_dpp v72, v72, v72 quad_perm:[2,3,0,1] row_mask:0xf bank_mask:0xf bound_ctrl:1
	s_nop 1
	v_add_f32_dpp v72, v72, v72 row_half_mirror row_mask:0xf bank_mask:0xf bound_ctrl:1
	s_nop 1
	v_add_f32_dpp v72, v72, v72 row_mirror row_mask:0xf bank_mask:0xf bound_ctrl:1
	s_nop 1
	v_add_f32_dpp v72, v72, v72 row_bcast:15 row_mask:0xa bank_mask:0xf
	s_nop 1
	v_add_f32_dpp v72, v72, v72 row_bcast:31 row_mask:0xc bank_mask:0xf
	v_mov_b32_e32 v73, v30
	v_readlane_b32 s7, v72, 63
	v_mov_b32_e32 v72, v34
	v_pk_fma_f32 v[72:73], v[72:73], v[72:73], v[76:77]
	v_mov_b32_e32 v76, v33
	v_add_f32_e32 v72, v72, v73
	v_mov_b32_e32 v77, v29
	s_nop 0
	v_add_f32_dpp v72, v72, v72 quad_perm:[1,0,3,2] row_mask:0xf bank_mask:0xf bound_ctrl:1
	v_fma_f32 v88, s7, v235, v225
	v_pk_mul_f32 v[76:77], v[76:77], v[76:77]
	v_add_f32_dpp v72, v72, v72 quad_perm:[2,3,0,1] row_mask:0xf bank_mask:0xf bound_ctrl:1
	s_nop 1
	v_add_f32_dpp v72, v72, v72 row_half_mirror row_mask:0xf bank_mask:0xf bound_ctrl:1
	s_nop 1
	v_add_f32_dpp v72, v72, v72 row_mirror row_mask:0xf bank_mask:0xf bound_ctrl:1
	s_nop 1
	v_add_f32_dpp v72, v72, v72 row_bcast:15 row_mask:0xa bank_mask:0xf
	s_nop 1
	v_add_f32_dpp v72, v72, v72 row_bcast:31 row_mask:0xc bank_mask:0xf
	v_mov_b32_e32 v73, v31
	v_readlane_b32 s7, v72, 63
	v_mov_b32_e32 v72, v35
	v_pk_fma_f32 v[72:73], v[72:73], v[72:73], v[76:77]
	v_mov_b32_e32 v76, v56
	v_add_f32_e32 v72, v72, v73
	v_mov_b32_e32 v77, v52
	s_nop 0
	v_add_f32_dpp v72, v72, v72 quad_perm:[1,0,3,2] row_mask:0xf bank_mask:0xf bound_ctrl:1
	v_fma_f32 v89, s7, v235, v225
	v_pk_mul_f32 v[76:77], v[76:77], v[76:77]
	v_add_f32_dpp v72, v72, v72 quad_perm:[2,3,0,1] row_mask:0xf bank_mask:0xf bound_ctrl:1
	s_nop 1
	v_add_f32_dpp v72, v72, v72 row_half_mirror row_mask:0xf bank_mask:0xf bound_ctrl:1
	s_nop 1
	v_add_f32_dpp v72, v72, v72 row_mirror row_mask:0xf bank_mask:0xf bound_ctrl:1
	s_nop 1
	v_add_f32_dpp v72, v72, v72 row_bcast:15 row_mask:0xa bank_mask:0xf
	s_nop 1
	v_add_f32_dpp v72, v72, v72 row_bcast:31 row_mask:0xc bank_mask:0xf
	v_mov_b32_e32 v73, v54
	v_readlane_b32 s7, v72, 63
	v_mov_b32_e32 v72, v58
	v_pk_fma_f32 v[72:73], v[72:73], v[72:73], v[76:77]
	v_mov_b32_e32 v76, v57
	v_add_f32_e32 v72, v72, v73
	v_mov_b32_e32 v77, v53
	s_nop 0
	v_add_f32_dpp v72, v72, v72 quad_perm:[1,0,3,2] row_mask:0xf bank_mask:0xf bound_ctrl:1
	v_fma_f32 v90, s7, v235, v225
	v_pk_mul_f32 v[76:77], v[76:77], v[76:77]
	v_add_f32_dpp v72, v72, v72 quad_perm:[2,3,0,1] row_mask:0xf bank_mask:0xf bound_ctrl:1
	s_nop 1
	v_add_f32_dpp v72, v72, v72 row_half_mirror row_mask:0xf bank_mask:0xf bound_ctrl:1
	s_nop 1
	v_add_f32_dpp v72, v72, v72 row_mirror row_mask:0xf bank_mask:0xf bound_ctrl:1
	s_nop 1
	v_add_f32_dpp v72, v72, v72 row_bcast:15 row_mask:0xa bank_mask:0xf
	s_nop 1
	v_add_f32_dpp v72, v72, v72 row_bcast:31 row_mask:0xc bank_mask:0xf
	v_mov_b32_e32 v73, v55
	v_readlane_b32 s7, v72, 63
	v_mov_b32_e32 v72, v59
	v_pk_fma_f32 v[72:73], v[72:73], v[72:73], v[76:77]
	v_mov_b32_e32 v76, v50
	v_add_f32_e32 v72, v72, v73
	v_mov_b32_e32 v77, v44
	s_nop 0
	v_add_f32_dpp v72, v72, v72 quad_perm:[1,0,3,2] row_mask:0xf bank_mask:0xf bound_ctrl:1
	v_fma_f32 v92, s7, v235, v225
	v_pk_mul_f32 v[76:77], v[76:77], v[76:77]
	v_add_f32_dpp v72, v72, v72 quad_perm:[2,3,0,1] row_mask:0xf bank_mask:0xf bound_ctrl:1
	s_nop 1
	v_add_f32_dpp v72, v72, v72 row_half_mirror row_mask:0xf bank_mask:0xf bound_ctrl:1
	s_nop 1
	v_add_f32_dpp v72, v72, v72 row_mirror row_mask:0xf bank_mask:0xf bound_ctrl:1
	s_nop 1
	v_add_f32_dpp v72, v72, v72 row_bcast:15 row_mask:0xa bank_mask:0xf
	s_nop 1
	v_add_f32_dpp v72, v72, v72 row_bcast:31 row_mask:0xc bank_mask:0xf
	v_mov_b32_e32 v73, v48
	v_readlane_b32 s7, v72, 63
	v_mov_b32_e32 v72, v46
	v_pk_fma_f32 v[72:73], v[72:73], v[72:73], v[76:77]
	v_mov_b32_e32 v76, v51
	v_add_f32_e32 v72, v72, v73
	v_mov_b32_e32 v77, v45
	s_nop 0
	v_add_f32_dpp v72, v72, v72 quad_perm:[1,0,3,2] row_mask:0xf bank_mask:0xf bound_ctrl:1
	v_fma_f32 v93, s7, v235, v225
	v_pk_mul_f32 v[76:77], v[76:77], v[76:77]
	v_add_f32_dpp v72, v72, v72 quad_perm:[2,3,0,1] row_mask:0xf bank_mask:0xf bound_ctrl:1
	s_nop 1
	v_add_f32_dpp v72, v72, v72 row_half_mirror row_mask:0xf bank_mask:0xf bound_ctrl:1
	s_nop 1
	v_add_f32_dpp v72, v72, v72 row_mirror row_mask:0xf bank_mask:0xf bound_ctrl:1
	s_nop 1
	v_add_f32_dpp v72, v72, v72 row_bcast:15 row_mask:0xa bank_mask:0xf
	s_nop 1
	v_add_f32_dpp v72, v72, v72 row_bcast:31 row_mask:0xc bank_mask:0xf
	v_mov_b32_e32 v73, v49
	v_readlane_b32 s7, v72, 63
	v_mov_b32_e32 v72, v47
	v_pk_fma_f32 v[72:73], v[72:73], v[72:73], v[76:77]
	v_mov_b32_e32 v76, v68
	v_add_f32_e32 v72, v72, v73
	v_mov_b32_e32 v77, v26
	s_nop 0
	v_add_f32_dpp v72, v72, v72 quad_perm:[1,0,3,2] row_mask:0xf bank_mask:0xf bound_ctrl:1
	v_fma_f32 v94, s7, v235, v225
	v_pk_mul_f32 v[76:77], v[76:77], v[76:77]
	v_add_f32_dpp v72, v72, v72 quad_perm:[2,3,0,1] row_mask:0xf bank_mask:0xf bound_ctrl:1
	s_nop 1
	v_add_f32_dpp v72, v72, v72 row_half_mirror row_mask:0xf bank_mask:0xf bound_ctrl:1
	s_nop 1
	v_add_f32_dpp v72, v72, v72 row_mirror row_mask:0xf bank_mask:0xf bound_ctrl:1
	s_nop 1
	v_add_f32_dpp v72, v72, v72 row_bcast:15 row_mask:0xa bank_mask:0xf
	s_nop 1
	v_add_f32_dpp v72, v72, v72 row_bcast:31 row_mask:0xc bank_mask:0xf
	v_mov_b32_e32 v73, v66
	v_readlane_b32 s7, v72, 63
	v_mov_b32_e32 v72, v70
	v_pk_fma_f32 v[72:73], v[72:73], v[72:73], v[76:77]
	v_mov_b32_e32 v76, v69
	v_add_f32_e32 v72, v72, v73
	v_mov_b32_e32 v77, v27
	s_nop 0
	v_add_f32_dpp v72, v72, v72 quad_perm:[1,0,3,2] row_mask:0xf bank_mask:0xf bound_ctrl:1
	v_fma_f32 v95, s7, v235, v225
	v_pk_mul_f32 v[76:77], v[76:77], v[76:77]
	v_add_f32_dpp v72, v72, v72 quad_perm:[2,3,0,1] row_mask:0xf bank_mask:0xf bound_ctrl:1
	s_nop 1
	v_add_f32_dpp v72, v72, v72 row_half_mirror row_mask:0xf bank_mask:0xf bound_ctrl:1
	s_nop 1
	v_add_f32_dpp v72, v72, v72 row_mirror row_mask:0xf bank_mask:0xf bound_ctrl:1
	s_nop 1
	v_add_f32_dpp v72, v72, v72 row_bcast:15 row_mask:0xa bank_mask:0xf
	s_nop 1
	v_add_f32_dpp v72, v72, v72 row_bcast:31 row_mask:0xc bank_mask:0xf
	v_mov_b32_e32 v73, v67
	v_readlane_b32 s7, v72, 63
	v_mov_b32_e32 v72, v71
	v_pk_fma_f32 v[72:73], v[72:73], v[72:73], v[76:77]
	v_mov_b32_e32 v76, v62
	v_add_f32_e32 v72, v72, v73
	v_mov_b32_e32 v77, v24
	s_nop 0
	v_add_f32_dpp v72, v72, v72 quad_perm:[1,0,3,2] row_mask:0xf bank_mask:0xf bound_ctrl:1
	v_fma_f32 v96, s7, v235, v225
	v_pk_mul_f32 v[76:77], v[76:77], v[76:77]
	v_add_f32_dpp v72, v72, v72 quad_perm:[2,3,0,1] row_mask:0xf bank_mask:0xf bound_ctrl:1
	s_nop 1
	v_add_f32_dpp v72, v72, v72 row_half_mirror row_mask:0xf bank_mask:0xf bound_ctrl:1
	s_nop 1
	v_add_f32_dpp v72, v72, v72 row_mirror row_mask:0xf bank_mask:0xf bound_ctrl:1
	s_nop 1
	v_add_f32_dpp v72, v72, v72 row_bcast:15 row_mask:0xa bank_mask:0xf
	s_nop 1
	v_add_f32_dpp v72, v72, v72 row_bcast:31 row_mask:0xc bank_mask:0xf
	v_mov_b32_e32 v73, v60
	v_readlane_b32 s7, v72, 63
	v_mov_b32_e32 v72, v64
	v_pk_fma_f32 v[72:73], v[72:73], v[72:73], v[76:77]
	v_mov_b32_e32 v76, v63
	v_add_f32_e32 v72, v72, v73
	v_mov_b32_e32 v77, v25
	s_nop 0
	v_add_f32_dpp v72, v72, v72 quad_perm:[1,0,3,2] row_mask:0xf bank_mask:0xf bound_ctrl:1
	v_fma_f32 v97, s7, v235, v225
	v_pk_mul_f32 v[76:77], v[76:77], v[76:77]
	v_add_f32_dpp v72, v72, v72 quad_perm:[2,3,0,1] row_mask:0xf bank_mask:0xf bound_ctrl:1
	s_nop 1
	v_add_f32_dpp v72, v72, v72 row_half_mirror row_mask:0xf bank_mask:0xf bound_ctrl:1
	s_nop 1
	v_add_f32_dpp v72, v72, v72 row_mirror row_mask:0xf bank_mask:0xf bound_ctrl:1
	s_nop 1
	v_add_f32_dpp v72, v72, v72 row_bcast:15 row_mask:0xa bank_mask:0xf
	s_nop 1
	v_add_f32_dpp v72, v72, v72 row_bcast:31 row_mask:0xc bank_mask:0xf
	v_mov_b32_e32 v73, v61
	v_readlane_b32 s7, v72, 63
	v_mov_b32_e32 v72, v65
	v_pk_fma_f32 v[72:73], v[72:73], v[72:73], v[76:77]
	v_fma_f32 v98, s7, v235, v225
	v_add_f32_e32 v72, v72, v73
	v_lshl_add_u32 v77, v1, 2, s8
	s_nop 0
	v_add_f32_dpp v72, v72, v72 quad_perm:[1,0,3,2] row_mask:0xf bank_mask:0xf bound_ctrl:1
	s_nop 1
	v_add_f32_dpp v72, v72, v72 quad_perm:[2,3,0,1] row_mask:0xf bank_mask:0xf bound_ctrl:1
	s_nop 1
	v_add_f32_dpp v72, v72, v72 row_half_mirror row_mask:0xf bank_mask:0xf bound_ctrl:1
	s_nop 1
	v_add_f32_dpp v72, v72, v72 row_mirror row_mask:0xf bank_mask:0xf bound_ctrl:1
	s_nop 1
	v_add_f32_dpp v72, v72, v72 row_bcast:15 row_mask:0xa bank_mask:0xf
	s_nop 1
	v_add_f32_dpp v72, v72, v72 row_bcast:31 row_mask:0xc bank_mask:0xf
	s_nop 0
	v_readlane_b32 s7, v72, 63
	global_load_dword v7, v[6:7], off
	s_nop 0
	global_load_dword v6, v[4:5], off
	global_load_dword v72, v[2:3], off
	global_load_dword v76, v[2:3], off offset:256
	global_load_dword v78, v[4:5], off offset:256
	global_load_dword v80, v[4:5], off offset:512
	global_load_dword v82, v[2:3], off offset:512
	global_load_dword v84, v[2:3], off offset:768
	global_load_dword v86, v[4:5], off offset:768
	v_rsq_f32_e32 v2, v79
	v_rsq_f32_e32 v3, v81
	v_rsq_f32_e32 v4, v83
	v_rsq_f32_e32 v5, v85
	v_fma_f32 v73, s7, v235, v225
	v_pk_mul_f32 v[22:23], v[22:23], v[2:3]
	v_pk_mul_f32 v[20:21], v[20:21], v[2:3]
	v_pk_mul_f32 v[10:11], v[10:11], v[4:5]
	v_pk_mul_f32 v[14:15], v[14:15], v[4:5]
	v_pk_mul_f32 v[18:19], v[18:19], v[2:3]
	v_pk_mul_f32 v[12:13], v[12:13], v[4:5]
	v_pk_mul_f32 v[2:3], v[16:17], v[2:3]
	v_pk_mul_f32 v[4:5], v[8:9], v[4:5]
	v_rsq_f32_e32 v8, v87
	v_rsq_f32_e32 v9, v88
	v_rsq_f32_e32 v16, v89
	v_rsq_f32_e32 v17, v90
	s_waitcnt vmcnt(8)
	ds_write_b32 v77, v7
	v_mad_u32_u24 v7, v74, s40, v75
	s_waitcnt vmcnt(6)
	v_pk_fma_f32 v[10:11], v[72:73], v[10:11], v[6:7] op_sel_hi:[0,1,0]
	v_pk_fma_f32 v[22:23], v[72:73], v[22:23], v[6:7] op_sel_hi:[0,1,0]
	s_waitcnt vmcnt(4)
	v_pk_fma_f32 v[14:15], v[76:77], v[14:15], v[78:79] op_sel_hi:[0,1,0]
	v_pk_fma_f32 v[20:21], v[76:77], v[20:21], v[78:79] op_sel_hi:[0,1,0]
	s_waitcnt vmcnt(2)
	v_pk_fma_f32 v[12:13], v[82:83], v[12:13], v[80:81] op_sel_hi:[0,1,0]
	v_pk_fma_f32 v[18:19], v[82:83], v[18:19], v[80:81] op_sel_hi:[0,1,0]
	s_waitcnt vmcnt(0)
	v_pk_fma_f32 v[88:89], v[84:85], v[4:5], v[86:87] op_sel_hi:[0,1,0]
	v_pk_fma_f32 v[90:91], v[84:85], v[2:3], v[86:87] op_sel_hi:[0,1,0]
	v_pk_mul_f32 v[2:3], v[42:43], v[8:9]
	v_pk_mul_f32 v[4:5], v[34:35], v[16:17]
	v_pk_fma_f32 v[2:3], v[72:73], v[2:3], v[6:7] op_sel_hi:[0,1,0]
	v_pk_fma_f32 v[4:5], v[72:73], v[4:5], v[6:7] op_sel_hi:[0,1,0]
	v_cvt_pk_bf16_f32 v5, v4, v5
	v_cvt_pk_bf16_f32 v4, v2, v3
	v_cvt_pk_bf16_f32 v3, v10, v11
	v_cvt_pk_bf16_f32 v2, v22, v23
	ds_write_b128 v7, v[2:5]
	v_pk_mul_f32 v[2:3], v[40:41], v[8:9]
	v_pk_mul_f32 v[4:5], v[32:33], v[16:17]
	v_pk_fma_f32 v[2:3], v[76:77], v[2:3], v[78:79] op_sel_hi:[0,1,0]
	v_pk_fma_f32 v[4:5], v[76:77], v[4:5], v[78:79] op_sel_hi:[0,1,0]
	v_cvt_pk_bf16_f32 v5, v4, v5
	v_cvt_pk_bf16_f32 v4, v2, v3
	v_cvt_pk_bf16_f32 v3, v14, v15
	v_cvt_pk_bf16_f32 v2, v20, v21
	ds_write_b128 v7, v[2:5] offset:17408
	v_pk_mul_f32 v[2:3], v[38:39], v[8:9]
	v_pk_mul_f32 v[4:5], v[30:31], v[16:17]
	v_pk_fma_f32 v[2:3], v[82:83], v[2:3], v[80:81] op_sel_hi:[0,1,0]
	v_pk_fma_f32 v[4:5], v[82:83], v[4:5], v[80:81] op_sel_hi:[0,1,0]
	v_cvt_pk_bf16_f32 v5, v4, v5
	v_cvt_pk_bf16_f32 v4, v2, v3
	v_cvt_pk_bf16_f32 v3, v12, v13
	v_cvt_pk_bf16_f32 v2, v18, v19
	ds_write_b128 v7, v[2:5] offset:34816
	v_pk_mul_f32 v[2:3], v[36:37], v[8:9]
	v_rsq_f32_e32 v8, v92
	v_rsq_f32_e32 v9, v93
	v_rsq_f32_e32 v10, v94
	v_rsq_f32_e32 v11, v95
	v_pk_mul_f32 v[4:5], v[28:29], v[16:17]
	v_pk_fma_f32 v[2:3], v[84:85], v[2:3], v[86:87] op_sel_hi:[0,1,0]
	v_pk_fma_f32 v[4:5], v[84:85], v[4:5], v[86:87] op_sel_hi:[0,1,0]
	v_cvt_pk_bf16_f32 v5, v4, v5
	v_cvt_pk_bf16_f32 v4, v2, v3
	v_cvt_pk_bf16_f32 v3, v88, v89
	v_cvt_pk_bf16_f32 v2, v90, v91
	ds_write_b128 v7, v[2:5] offset:52224
	v_pk_mul_f32 v[2:3], v[58:59], v[8:9]
	v_pk_mul_f32 v[4:5], v[46:47], v[10:11]
	v_pk_fma_f32 v[14:15], v[72:73], v[2:3], v[6:7] op_sel_hi:[0,1,0]
	v_pk_fma_f32 v[12:13], v[72:73], v[4:5], v[6:7] op_sel_hi:[0,1,0]
	v_pk_mul_f32 v[2:3], v[56:57], v[8:9]
	v_pk_mul_f32 v[4:5], v[50:51], v[10:11]
	v_pk_fma_f32 v[18:19], v[76:77], v[2:3], v[78:79] op_sel_hi:[0,1,0]
	v_pk_fma_f32 v[16:17], v[76:77], v[4:5], v[78:79] op_sel_hi:[0,1,0]
	v_pk_mul_f32 v[2:3], v[54:55], v[8:9]
	v_pk_mul_f32 v[4:5], v[48:49], v[10:11]
	v_pk_fma_f32 v[22:23], v[82:83], v[2:3], v[80:81] op_sel_hi:[0,1,0]
	v_pk_fma_f32 v[20:21], v[82:83], v[4:5], v[80:81] op_sel_hi:[0,1,0]
	v_pk_mul_f32 v[2:3], v[52:53], v[8:9]
	v_pk_mul_f32 v[4:5], v[44:45], v[10:11]
	v_rsq_f32_e32 v8, v96
	v_rsq_f32_e32 v9, v97
	v_rsq_f32_e32 v10, v98
	v_rsq_f32_e32 v11, v73
	v_pk_fma_f32 v[28:29], v[84:85], v[4:5], v[86:87] op_sel_hi:[0,1,0]
	v_pk_fma_f32 v[30:31], v[84:85], v[2:3], v[86:87] op_sel_hi:[0,1,0]
	v_pk_mul_f32 v[2:3], v[70:71], v[8:9]
	v_pk_mul_f32 v[4:5], v[64:65], v[10:11]
	v_pk_fma_f32 v[2:3], v[72:73], v[2:3], v[6:7] op_sel_hi:[0,1,0]
	v_pk_fma_f32 v[4:5], v[72:73], v[4:5], v[6:7] op_sel_hi:[0,1,0]
	v_cvt_pk_bf16_f32 v5, v4, v5
	v_cvt_pk_bf16_f32 v4, v2, v3
	v_cvt_pk_bf16_f32 v3, v12, v13
	v_cvt_pk_bf16_f32 v2, v14, v15
	ds_write_b128 v7, v[2:5] offset:16
	v_pk_mul_f32 v[2:3], v[68:69], v[8:9]
	v_pk_mul_f32 v[4:5], v[62:63], v[10:11]
	v_pk_fma_f32 v[2:3], v[76:77], v[2:3], v[78:79] op_sel_hi:[0,1,0]
	v_pk_fma_f32 v[4:5], v[76:77], v[4:5], v[78:79] op_sel_hi:[0,1,0]
	v_cvt_pk_bf16_f32 v5, v4, v5
	v_cvt_pk_bf16_f32 v4, v2, v3
	v_cvt_pk_bf16_f32 v3, v16, v17
	v_cvt_pk_bf16_f32 v2, v18, v19
	ds_write_b128 v7, v[2:5] offset:17424
	v_pk_mul_f32 v[2:3], v[66:67], v[8:9]
	v_pk_mul_f32 v[4:5], v[60:61], v[10:11]
	v_pk_fma_f32 v[2:3], v[82:83], v[2:3], v[80:81] op_sel_hi:[0,1,0]
	v_pk_fma_f32 v[4:5], v[82:83], v[4:5], v[80:81] op_sel_hi:[0,1,0]
	v_cvt_pk_bf16_f32 v5, v4, v5
	v_cvt_pk_bf16_f32 v4, v2, v3
	v_cvt_pk_bf16_f32 v3, v20, v21
	v_cvt_pk_bf16_f32 v2, v22, v23
	ds_write_b128 v7, v[2:5] offset:34832
	v_pk_mul_f32 v[2:3], v[26:27], v[8:9]
	v_pk_mul_f32 v[4:5], v[24:25], v[10:11]
	v_pk_fma_f32 v[2:3], v[84:85], v[2:3], v[86:87] op_sel_hi:[0,1,0]
	v_pk_fma_f32 v[4:5], v[84:85], v[4:5], v[86:87] op_sel_hi:[0,1,0]
	v_cvt_pk_bf16_f32 v5, v4, v5
	v_cvt_pk_bf16_f32 v4, v2, v3
	v_cvt_pk_bf16_f32 v3, v28, v29
	v_cvt_pk_bf16_f32 v2, v30, v31
	v_lshl_add_u64 v[8:9], s[28:29], 0, v[130:131]
	v_and_or_b32 v6, v1, 31, s6
	v_bfe_u32 v73, v1, 5, 1
	ds_write_b128 v7, v[2:5] offset:52240
	v_add_co_u32_e32 v70, vcc, s90, v8
	v_lshlrev_b32_e32 v1, 2, v73
	v_ashrrev_i32_e32 v7, 31, v6
	v_addc_co_u32_e32 v71, vcc, 0, v9, vcc
	v_or_b32_e32 v72, s66, v1
	v_lshlrev_b64 v[74:75], 1, v[6:7]
	v_add_co_u32_e32 v82, vcc, s46, v8
	v_lshl_add_u64 v[26:27], s[80:81], 0, v[74:75]
	v_mul_lo_u32 v10, v72, s87
	v_mov_b32_e32 v11, v131
	v_addc_co_u32_e32 v83, vcc, 0, v9, vcc
	v_lshl_add_u64 v[10:11], v[26:27], 0, v[10:11]
	v_add_co_u32_e32 v94, vcc, s90, v10
	s_mov_b32 s6, 0xc000
	s_nop 0
	v_addc_co_u32_e32 v95, vcc, 0, v11, vcc
	v_add_co_u32_e32 v28, vcc, s41, v10
	v_or_b32_e32 v7, s33, v1
	s_nop 0
	v_addc_co_u32_e32 v29, vcc, 0, v11, vcc
	v_add_co_u32_e32 v76, vcc, s97, v10
	s_waitcnt lgkmcnt(0)
	s_nop 0
	v_addc_co_u32_e32 v77, vcc, 0, v11, vcc
	v_add_co_u32_e32 v78, vcc, s6, v10
	s_mov_b32 s6, 0xd000
	s_nop 0
	v_addc_co_u32_e32 v79, vcc, 0, v11, vcc
	v_add_co_u32_e32 v80, vcc, s6, v10
	s_mov_b32 s6, 0xf000
	s_nop 0
	v_addc_co_u32_e32 v81, vcc, 0, v11, vcc
	v_add_co_u32_e32 v84, vcc, s6, v10
	s_mov_b32 s6, 0x10000
	s_nop 0
	v_addc_co_u32_e32 v85, vcc, 0, v11, vcc
	v_add_co_u32_e32 v86, vcc, s6, v10
	s_mov_b32 s6, 0x18000
	s_nop 0
	v_addc_co_u32_e32 v87, vcc, 0, v11, vcc
	v_add_co_u32_e32 v88, vcc, s6, v10
	s_mov_b32 s6, 0x19000
	s_nop 0
	v_addc_co_u32_e32 v89, vcc, 0, v11, vcc
	v_add_co_u32_e32 v90, vcc, s6, v10
	s_mov_b32 s6, 0x1b000
	s_nop 0
	v_addc_co_u32_e32 v91, vcc, 0, v11, vcc
	v_add_co_u32_e32 v92, vcc, s6, v10
	s_mov_b32 s6, 0x1c000
	s_nop 0
	v_addc_co_u32_e32 v93, vcc, 0, v11, vcc
	v_add_co_u32_e32 v54, vcc, s6, v10
	s_mov_b32 s6, 0x24000
	s_nop 0
	v_addc_co_u32_e32 v55, vcc, 0, v11, vcc
	v_add_co_u32_e32 v56, vcc, s6, v10
	s_mov_b32 s6, 0x25000
	s_nop 0
	v_addc_co_u32_e32 v57, vcc, 0, v11, vcc
	v_add_co_u32_e32 v58, vcc, s6, v10
	s_mov_b32 s6, 0x27000
	s_nop 0
	v_addc_co_u32_e32 v59, vcc, 0, v11, vcc
	v_add_co_u32_e32 v60, vcc, s6, v10
	s_mov_b32 s6, 0x28000
	s_nop 0
	v_addc_co_u32_e32 v61, vcc, 0, v11, vcc
	v_add_co_u32_e32 v62, vcc, s6, v10
	v_mul_lo_u32 v10, v7, s87
	s_nop 0
	v_addc_co_u32_e32 v63, vcc, 0, v11, vcc
	v_mov_b32_e32 v11, v131
	v_lshl_add_u64 v[10:11], v[26:27], 0, v[10:11]
	s_mov_b32 s6, 0x6030000
	v_add_co_u32_e32 v64, vcc, s6, v10
	s_mov_b32 s6, 0x6031000
	s_nop 0
	v_addc_co_u32_e32 v65, vcc, 0, v11, vcc
	v_add_co_u32_e32 v66, vcc, s6, v10
	s_mov_b32 s6, 0x6033000
	s_nop 0
	v_addc_co_u32_e32 v67, vcc, 0, v11, vcc
	v_add_co_u32_e32 v68, vcc, s6, v10
	s_mov_b32 s6, 0x6034000
	s_nop 0
	v_addc_co_u32_e32 v69, vcc, 0, v11, vcc
	v_add_co_u32_e32 v38, vcc, s6, v10
	s_mov_b32 s6, 0x603c000
	s_nop 0
	v_addc_co_u32_e32 v39, vcc, 0, v11, vcc
	v_add_co_u32_e32 v40, vcc, s6, v10
	s_mov_b32 s6, 0x603d000
	s_nop 0
	v_addc_co_u32_e32 v41, vcc, 0, v11, vcc
	v_add_co_u32_e32 v42, vcc, s6, v10
	s_mov_b32 s6, 0x603f000
	s_nop 0
	v_addc_co_u32_e32 v43, vcc, 0, v11, vcc
	v_add_co_u32_e32 v44, vcc, s6, v10
	s_mov_b32 s6, 0x6040000
	s_nop 0
	v_addc_co_u32_e32 v45, vcc, 0, v11, vcc
	v_add_co_u32_e32 v46, vcc, s6, v10
	s_mov_b32 s6, 0x6048000
	s_nop 0
	v_addc_co_u32_e32 v47, vcc, 0, v11, vcc
	v_add_co_u32_e32 v48, vcc, s6, v10
	s_mov_b32 s6, 0x6049000
	s_nop 0
	v_addc_co_u32_e32 v49, vcc, 0, v11, vcc
	v_add_co_u32_e32 v50, vcc, s6, v10
	s_mov_b32 s6, 0x604b000
	s_nop 0
	v_addc_co_u32_e32 v51, vcc, 0, v11, vcc
	v_add_co_u32_e32 v52, vcc, s6, v10
	s_mov_b32 s6, 0x604c000
	s_nop 0
	v_addc_co_u32_e32 v53, vcc, 0, v11, vcc
	v_add_co_u32_e32 v12, vcc, s6, v10
	s_mov_b32 s6, 0x6054000
	s_nop 0
	v_addc_co_u32_e32 v13, vcc, 0, v11, vcc
	v_add_co_u32_e32 v14, vcc, s6, v10
	s_mov_b32 s6, 0x6055000
	s_nop 0
	v_addc_co_u32_e32 v15, vcc, 0, v11, vcc
	v_add_co_u32_e32 v16, vcc, s6, v10
	s_mov_b32 s6, 0x6057000
	s_nop 0
	v_addc_co_u32_e32 v17, vcc, 0, v11, vcc
	v_add_co_u32_e32 v34, vcc, s6, v10
	s_mov_b32 s6, 0x6058000
	s_nop 0
	v_addc_co_u32_e32 v35, vcc, 0, v11, vcc
	v_add_co_u32_e32 v36, vcc, s6, v10
	v_mad_u64_u32 v[26:27], s[6:7], v72, s87, v[26:27]
	s_barrier
	global_load_dwordx4 v[2:5], v130, s[28:29]
	global_load_dwordx4 v[30:33], v130, s[28:29] offset:1024
	global_load_dwordx4 v[22:25], v130, s[28:29] offset:2048
	global_load_dwordx4 v[18:21], v130, s[28:29] offset:3072
	global_load_ushort v96, v[26:27], off
	global_load_ushort v7, v[28:29], off
	s_nop 0
	global_load_dwordx4 v[26:29], v[70:71], off offset:1024
	v_addc_co_u32_e32 v37, vcc, 0, v11, vcc
	global_load_ushort v94, v[94:95], off offset:2048
	s_mov_b32 s6, 0x6060000
	v_mul_lo_u32 v6, v6, s40
	s_waitcnt vmcnt(3)
	v_lshlrev_b32_e32 v96, 16, v96
	v_fma_f32 v97, |v96|, s92, 1.0
	v_rcp_f32_e32 v97, v97
	v_mul_f32_e32 v99, v96, v96
	v_mul_f32_e32 v99, 0xbf38aa3b, v99
	v_exp_f32_e32 v99, v99
	v_fmamk_f32 v98, v97, 0x3f07dc22, v236
	v_fmaak_f32 v98, v97, v98, 0x3f35f0e3
	v_fmaak_f32 v98, v97, v98, 0xbe11a98e
	s_waitcnt vmcnt(0)
	v_lshlrev_b32_e32 v94, 16, v94
	v_fmaak_f32 v98, v97, v98, 0x3e027906
	v_fma_f32 v95, |v94|, s92, 1.0
	v_mul_f32_e32 v97, v97, v98
	v_rcp_f32_e32 v95, v95
	v_mul_f32_e32 v97, v99, v97
	v_mul_f32_e32 v98, v97, v96
	v_fma_f32 v97, -v97, v96, v96
	v_cmp_gt_f32_e32 vcc, 0, v96
	v_fmamk_f32 v96, v95, 0x3f07dc22, v236
	v_fmaak_f32 v96, v95, v96, 0x3f35f0e3
	v_cndmask_b32_e32 v130, v97, v98, vcc
	v_mul_f32_e32 v97, v94, v94
	v_mul_f32_e32 v97, 0xbf38aa3b, v97
	v_exp_f32_e32 v97, v97
	v_fmaak_f32 v96, v95, v96, 0xbe11a98e
	v_fmaak_f32 v96, v95, v96, 0x3e027906
	v_mul_f32_e32 v95, v95, v96
	v_mul_f32_e32 v95, v97, v95
	v_lshlrev_b32_e32 v7, 16, v7
	v_mul_f32_e32 v96, v95, v94
	v_fma_f32 v95, -v95, v94, v94
	v_cmp_gt_f32_e32 vcc, 0, v94
	v_fma_f32 v94, |v7|, s92, 1.0
	v_rcp_f32_e32 v94, v94
	v_cndmask_b32_e32 v167, v95, v96, vcc
	v_mul_f32_e32 v96, v7, v7
	v_mul_f32_e32 v96, 0xbf38aa3b, v96
	v_fmamk_f32 v95, v94, 0x3f07dc22, v236
	v_fmaak_f32 v95, v94, v95, 0x3f35f0e3
	v_exp_f32_e32 v96, v96
	v_fmaak_f32 v95, v94, v95, 0xbe11a98e
	v_fmaak_f32 v95, v94, v95, 0x3e027906
	v_mul_f32_e32 v94, v94, v95
	v_mul_f32_e32 v94, v96, v94
	v_mul_f32_e32 v95, v94, v7
	v_fma_f32 v94, -v94, v7, v7
	v_cmp_gt_f32_e32 vcc, 0, v7
	global_load_ushort v7, v[76:77], off offset:2048
	s_nop 0
	global_load_ushort v76, v[78:79], off
	global_load_ushort v77, v[80:81], off offset:2048
	s_nop 0
	global_load_ushort v78, v[84:85], off
	global_load_ushort v79, v[86:87], off offset:2048
	global_load_ushort v80, v[88:89], off
	global_load_ushort v81, v[90:91], off offset:2048
	s_nop 0
	global_load_ushort v84, v[92:93], off
	v_cndmask_b32_e32 v168, v94, v95, vcc
	s_waitcnt vmcnt(7)
	v_lshlrev_b32_e32 v7, 16, v7
	v_fma_f32 v85, |v7|, s92, 1.0
	v_rcp_f32_e32 v85, v85
	v_mul_f32_e32 v87, v7, v7
	v_mul_f32_e32 v87, 0xbf38aa3b, v87
	v_exp_f32_e32 v87, v87
	v_fmamk_f32 v86, v85, 0x3f07dc22, v236
	v_fmaak_f32 v86, v85, v86, 0x3f35f0e3
	v_fmaak_f32 v86, v85, v86, 0xbe11a98e
	v_fmaak_f32 v86, v85, v86, 0x3e027906
	v_mul_f32_e32 v85, v85, v86
	v_mul_f32_e32 v85, v87, v85
	v_mul_f32_e32 v86, v85, v7
	v_fma_f32 v85, -v85, v7, v7
	v_cmp_gt_f32_e32 vcc, 0, v7
	s_waitcnt vmcnt(6)
	v_lshlrev_b32_e32 v7, 16, v76
	v_fma_f32 v76, |v7|, s92, 1.0
	v_rcp_f32_e32 v76, v76
	v_cndmask_b32_e32 v169, v85, v86, vcc
	v_mul_f32_e32 v86, v7, v7
	v_mul_f32_e32 v86, 0xbf38aa3b, v86
	v_fmamk_f32 v85, v76, 0x3f07dc22, v236
	v_fmaak_f32 v85, v76, v85, 0x3f35f0e3
	v_exp_f32_e32 v86, v86
	v_fmaak_f32 v85, v76, v85, 0xbe11a98e
	v_fmaak_f32 v85, v76, v85, 0x3e027906
	v_mul_f32_e32 v76, v76, v85
	v_mul_f32_e32 v76, v86, v76
	v_mul_f32_e32 v85, v76, v7
	v_fma_f32 v76, -v76, v7, v7
	v_cmp_gt_f32_e32 vcc, 0, v7
	s_waitcnt vmcnt(5)
	v_lshlrev_b32_e32 v7, 16, v77
	v_cndmask_b32_e32 v170, v76, v85, vcc
	v_fma_f32 v76, |v7|, s92, 1.0
	v_rcp_f32_e32 v76, v76
	v_mul_f32_e32 v85, v7, v7
	v_mul_f32_e32 v85, 0xbf38aa3b, v85
	v_exp_f32_e32 v85, v85
	v_fmamk_f32 v77, v76, 0x3f07dc22, v236
	v_fmaak_f32 v77, v76, v77, 0x3f35f0e3
	v_fmaak_f32 v77, v76, v77, 0xbe11a98e
	v_fmaak_f32 v77, v76, v77, 0x3e027906
	v_mul_f32_e32 v76, v76, v77
	v_mul_f32_e32 v76, v85, v76
	v_mul_f32_e32 v77, v76, v7
	v_fma_f32 v76, -v76, v7, v7
	v_cmp_gt_f32_e32 vcc, 0, v7
	s_waitcnt vmcnt(4)
	v_lshlrev_b32_e32 v7, 16, v78
	v_mul_f32_e32 v78, v7, v7
	v_cndmask_b32_e32 v171, v76, v77, vcc
	v_fma_f32 v76, |v7|, s92, 1.0
	v_rcp_f32_e32 v76, v76
	v_mul_f32_e32 v78, 0xbf38aa3b, v78
	v_exp_f32_e32 v78, v78
	v_cmp_gt_f32_e32 vcc, 0, v7
	v_fmamk_f32 v77, v76, 0x3f07dc22, v236
	v_fmaak_f32 v77, v76, v77, 0x3f35f0e3
	v_fmaak_f32 v77, v76, v77, 0xbe11a98e
	v_fmaak_f32 v77, v76, v77, 0x3e027906
	v_mul_f32_e32 v76, v76, v77
	v_mul_f32_e32 v76, v78, v76
	v_mul_f32_e32 v77, v76, v7
	v_fma_f32 v76, -v76, v7, v7
	s_waitcnt vmcnt(3)
	v_lshlrev_b32_e32 v7, 16, v79
	v_cndmask_b32_e32 v172, v76, v77, vcc
	v_fma_f32 v76, |v7|, s92, 1.0
	v_rcp_f32_e32 v76, v76
	v_mul_f32_e32 v78, v7, v7
	v_mul_f32_e32 v78, 0xbf38aa3b, v78
	v_exp_f32_e32 v78, v78
	v_fmamk_f32 v77, v76, 0x3f07dc22, v236
	v_fmaak_f32 v77, v76, v77, 0x3f35f0e3
	v_fmaak_f32 v77, v76, v77, 0xbe11a98e
	v_fmaak_f32 v77, v76, v77, 0x3e027906
	v_mul_f32_e32 v76, v76, v77
	v_mul_f32_e32 v76, v78, v76
	v_mul_f32_e32 v77, v76, v7
	v_fma_f32 v76, -v76, v7, v7
	v_cmp_gt_f32_e32 vcc, 0, v7
	s_waitcnt vmcnt(2)
	v_lshlrev_b32_e32 v7, 16, v80
	v_mul_f32_e32 v78, v7, v7
	v_cndmask_b32_e32 v173, v76, v77, vcc
	v_fma_f32 v76, |v7|, s92, 1.0
	v_rcp_f32_e32 v76, v76
	v_mul_f32_e32 v78, 0xbf38aa3b, v78
	v_exp_f32_e32 v78, v78
	v_cmp_gt_f32_e32 vcc, 0, v7
	v_fmamk_f32 v77, v76, 0x3f07dc22, v236
	v_fmaak_f32 v77, v76, v77, 0x3f35f0e3
	v_fmaak_f32 v77, v76, v77, 0xbe11a98e
	v_fmaak_f32 v77, v76, v77, 0x3e027906
	v_mul_f32_e32 v76, v76, v77
	v_mul_f32_e32 v76, v78, v76
	v_mul_f32_e32 v77, v76, v7
	v_fma_f32 v76, -v76, v7, v7
	s_waitcnt vmcnt(1)
	v_lshlrev_b32_e32 v7, 16, v81
	v_cndmask_b32_e32 v174, v76, v77, vcc
	v_fma_f32 v76, |v7|, s92, 1.0
	v_rcp_f32_e32 v76, v76
	v_mul_f32_e32 v78, v7, v7
	v_mul_f32_e32 v78, 0xbf38aa3b, v78
	v_exp_f32_e32 v78, v78
	v_fmamk_f32 v77, v76, 0x3f07dc22, v236
	v_fmaak_f32 v77, v76, v77, 0x3f35f0e3
	v_fmaak_f32 v77, v76, v77, 0xbe11a98e
	v_fmaak_f32 v77, v76, v77, 0x3e027906
	v_mul_f32_e32 v76, v76, v77
	v_mul_f32_e32 v76, v78, v76
	v_mul_f32_e32 v77, v76, v7
	v_fma_f32 v76, -v76, v7, v7
	v_cmp_gt_f32_e32 vcc, 0, v7
	s_waitcnt vmcnt(0)
	v_lshlrev_b32_e32 v7, 16, v84
	v_mul_f32_e32 v78, v7, v7
	v_cndmask_b32_e32 v175, v76, v77, vcc
	v_fma_f32 v76, |v7|, s92, 1.0
	v_rcp_f32_e32 v76, v76
	v_mul_f32_e32 v78, 0xbf38aa3b, v78
	v_exp_f32_e32 v78, v78
	v_cmp_gt_f32_e32 vcc, 0, v7
	v_fmamk_f32 v77, v76, 0x3f07dc22, v236
	v_fmaak_f32 v77, v76, v77, 0x3f35f0e3
	v_fmaak_f32 v77, v76, v77, 0xbe11a98e
	v_fmaak_f32 v77, v76, v77, 0x3e027906
	v_mul_f32_e32 v76, v76, v77
	v_mul_f32_e32 v76, v78, v76
	v_mul_f32_e32 v77, v76, v7
	v_fma_f32 v76, -v76, v7, v7
	global_load_ushort v7, v[54:55], off offset:2048
	s_nop 0
	global_load_ushort v54, v[56:57], off
	global_load_ushort v55, v[58:59], off offset:2048
	s_nop 0
	global_load_ushort v56, v[60:61], off
	global_load_ushort v57, v[62:63], off offset:2048
	global_load_ushort v58, v[64:65], off
	global_load_ushort v59, v[66:67], off offset:2048
	s_nop 0
	global_load_ushort v60, v[68:69], off
	v_cndmask_b32_e32 v176, v76, v77, vcc
	v_lshl_add_u64 v[84:85], s[76:77], 0, v[74:75]
	s_waitcnt vmcnt(7)
	v_lshlrev_b32_e32 v7, 16, v7
	v_fma_f32 v61, |v7|, s92, 1.0
	v_rcp_f32_e32 v61, v61
	v_mul_f32_e32 v63, v7, v7
	v_mul_f32_e32 v63, 0xbf38aa3b, v63
	v_exp_f32_e32 v63, v63
	v_fmamk_f32 v62, v61, 0x3f07dc22, v236
	v_fmaak_f32 v62, v61, v62, 0x3f35f0e3
	v_fmaak_f32 v62, v61, v62, 0xbe11a98e
	v_fmaak_f32 v62, v61, v62, 0x3e027906
	v_mul_f32_e32 v61, v61, v62
	v_mul_f32_e32 v61, v63, v61
	v_mul_f32_e32 v62, v61, v7
	v_fma_f32 v61, -v61, v7, v7
	v_cmp_gt_f32_e32 vcc, 0, v7
	s_waitcnt vmcnt(6)
	v_lshlrev_b32_e32 v7, 16, v54
	v_fma_f32 v54, |v7|, s92, 1.0
	v_rcp_f32_e32 v54, v54
	v_cndmask_b32_e32 v177, v61, v62, vcc
	v_mul_f32_e32 v62, v7, v7
	v_mul_f32_e32 v62, 0xbf38aa3b, v62
	v_fmamk_f32 v61, v54, 0x3f07dc22, v236
	v_fmaak_f32 v61, v54, v61, 0x3f35f0e3
	v_exp_f32_e32 v62, v62
	v_fmaak_f32 v61, v54, v61, 0xbe11a98e
	v_fmaak_f32 v61, v54, v61, 0x3e027906
	v_mul_f32_e32 v54, v54, v61
	v_mul_f32_e32 v54, v62, v54
	v_mul_f32_e32 v61, v54, v7
	v_fma_f32 v54, -v54, v7, v7
	v_cmp_gt_f32_e32 vcc, 0, v7
	s_waitcnt vmcnt(5)
	v_lshlrev_b32_e32 v7, 16, v55
	v_cndmask_b32_e32 v178, v54, v61, vcc
	v_fma_f32 v54, |v7|, s92, 1.0
	v_rcp_f32_e32 v54, v54
	v_mul_f32_e32 v61, v7, v7
	v_mul_f32_e32 v61, 0xbf38aa3b, v61
	v_exp_f32_e32 v61, v61
	v_fmamk_f32 v55, v54, 0x3f07dc22, v236
	v_fmaak_f32 v55, v54, v55, 0x3f35f0e3
	v_fmaak_f32 v55, v54, v55, 0xbe11a98e
	v_fmaak_f32 v55, v54, v55, 0x3e027906
	v_mul_f32_e32 v54, v54, v55
	v_mul_f32_e32 v54, v61, v54
	v_mul_f32_e32 v55, v54, v7
	v_fma_f32 v54, -v54, v7, v7
	v_cmp_gt_f32_e32 vcc, 0, v7
	s_waitcnt vmcnt(4)
	v_lshlrev_b32_e32 v7, 16, v56
	v_mul_f32_e32 v56, v7, v7
	v_cndmask_b32_e32 v179, v54, v55, vcc
	v_fma_f32 v54, |v7|, s92, 1.0
	v_rcp_f32_e32 v54, v54
	v_mul_f32_e32 v56, 0xbf38aa3b, v56
	v_exp_f32_e32 v56, v56
	v_cmp_gt_f32_e32 vcc, 0, v7
	v_fmamk_f32 v55, v54, 0x3f07dc22, v236
	v_fmaak_f32 v55, v54, v55, 0x3f35f0e3
	v_fmaak_f32 v55, v54, v55, 0xbe11a98e
	v_fmaak_f32 v55, v54, v55, 0x3e027906
	v_mul_f32_e32 v54, v54, v55
	v_mul_f32_e32 v54, v56, v54
	v_mul_f32_e32 v55, v54, v7
	v_fma_f32 v54, -v54, v7, v7
	s_waitcnt vmcnt(3)
	v_lshlrev_b32_e32 v7, 16, v57
	v_cndmask_b32_e32 v180, v54, v55, vcc
	v_fma_f32 v54, |v7|, s92, 1.0
	v_rcp_f32_e32 v54, v54
	v_mul_f32_e32 v56, v7, v7
	v_mul_f32_e32 v56, 0xbf38aa3b, v56
	v_exp_f32_e32 v56, v56
	v_fmamk_f32 v55, v54, 0x3f07dc22, v236
	v_fmaak_f32 v55, v54, v55, 0x3f35f0e3
	v_fmaak_f32 v55, v54, v55, 0xbe11a98e
	v_fmaak_f32 v55, v54, v55, 0x3e027906
	v_mul_f32_e32 v54, v54, v55
	v_mul_f32_e32 v54, v56, v54
	v_mul_f32_e32 v55, v54, v7
	v_fma_f32 v54, -v54, v7, v7
	v_cmp_gt_f32_e32 vcc, 0, v7
	s_waitcnt vmcnt(2)
	v_lshlrev_b32_e32 v7, 16, v58
	v_mul_f32_e32 v56, v7, v7
	v_cndmask_b32_e32 v181, v54, v55, vcc
	v_add_co_u32_e32 v134, vcc, s6, v10
	s_mov_b32 s6, 0x6061000
	s_nop 0
	v_addc_co_u32_e32 v135, vcc, 0, v11, vcc
	v_add_co_u32_e32 v136, vcc, s6, v10
	s_mov_b32 s6, 0x6063000
	s_nop 0
	v_addc_co_u32_e32 v137, vcc, 0, v11, vcc
	v_add_co_u32_e32 v138, vcc, s6, v10
	s_mov_b32 s6, 0x6064000
	s_nop 0
	v_addc_co_u32_e32 v139, vcc, 0, v11, vcc
	v_add_co_u32_e32 v140, vcc, s6, v10
	s_mov_b32 s6, 0x606c000
	s_nop 0
	v_addc_co_u32_e32 v141, vcc, 0, v11, vcc
	v_add_co_u32_e32 v142, vcc, s6, v10
	s_mov_b32 s6, 0x606d000
	s_nop 0
	v_addc_co_u32_e32 v143, vcc, 0, v11, vcc
	v_add_co_u32_e32 v144, vcc, s6, v10
	s_mov_b32 s6, 0x606f000
	s_nop 0
	v_addc_co_u32_e32 v145, vcc, 0, v11, vcc
	v_add_co_u32_e32 v146, vcc, s6, v10
	s_mov_b32 s6, 0x6070000
	s_nop 0
	v_addc_co_u32_e32 v147, vcc, 0, v11, vcc
	v_add_co_u32_e32 v148, vcc, s6, v10
	s_mov_b32 s6, 0x6078000
	s_nop 0
	v_addc_co_u32_e32 v149, vcc, 0, v11, vcc
	v_add_co_u32_e32 v76, vcc, s6, v10
	s_mov_b32 s6, 0x6079000
	s_nop 0
	v_addc_co_u32_e32 v77, vcc, 0, v11, vcc
	v_add_co_u32_e32 v78, vcc, s6, v10
	s_mov_b32 s6, 0x607b000
	s_nop 0
	v_addc_co_u32_e32 v79, vcc, 0, v11, vcc
	v_add_co_u32_e32 v80, vcc, s6, v10
	s_mov_b32 s6, 0x607c000
	s_nop 0
	v_addc_co_u32_e32 v81, vcc, 0, v11, vcc
	v_fma_f32 v54, |v7|, s92, 1.0
	v_add_co_u32_e32 v122, vcc, s6, v10
	v_rcp_f32_e32 v54, v54
	s_nop 0
	v_addc_co_u32_e32 v123, vcc, 0, v11, vcc
	s_mov_b32 s6, 0x6084000
	v_add_co_u32_e32 v124, vcc, s6, v10
	s_mov_b32 s6, 0x6085000
	s_nop 0
	v_addc_co_u32_e32 v125, vcc, 0, v11, vcc
	v_add_co_u32_e32 v126, vcc, s6, v10
	v_fmamk_f32 v55, v54, 0x3f07dc22, v236
	v_mul_f32_e32 v56, 0xbf38aa3b, v56
	v_addc_co_u32_e32 v127, vcc, 0, v11, vcc
	s_mov_b32 s6, 0x6087000
	v_fmaak_f32 v55, v54, v55, 0x3f35f0e3
	v_exp_f32_e32 v56, v56
	v_add_co_u32_e32 v128, vcc, s6, v10
	v_fmaak_f32 v55, v54, v55, 0xbe11a98e
	s_nop 0
	v_addc_co_u32_e32 v129, vcc, 0, v11, vcc
	s_mov_b32 s6, 0x6088000
	v_fmaak_f32 v55, v54, v55, 0x3e027906
	v_add_co_u32_e32 v132, vcc, s6, v10
	v_mul_f32_e32 v54, v54, v55
	s_nop 0
	v_addc_co_u32_e32 v133, vcc, 0, v11, vcc
	v_mul_f32_e32 v54, v56, v54
	v_mul_f32_e32 v55, v54, v7
	v_fma_f32 v54, -v54, v7, v7
	v_cmp_gt_f32_e32 vcc, 0, v7
	s_waitcnt vmcnt(1)
	v_lshlrev_b32_e32 v7, 16, v59
	v_mul_f32_e32 v56, v7, v7
	v_cndmask_b32_e32 v151, v54, v55, vcc
	v_fma_f32 v54, |v7|, s92, 1.0
	v_rcp_f32_e32 v54, v54
	v_mul_f32_e32 v56, 0xbf38aa3b, v56
	v_exp_f32_e32 v56, v56
	v_cmp_gt_f32_e32 vcc, 0, v7
	v_fmamk_f32 v55, v54, 0x3f07dc22, v236
	v_fmaak_f32 v55, v54, v55, 0x3f35f0e3
	v_fmaak_f32 v55, v54, v55, 0xbe11a98e
	v_fmaak_f32 v55, v54, v55, 0x3e027906
	v_mul_f32_e32 v54, v54, v55
	v_mul_f32_e32 v54, v56, v54
	v_mul_f32_e32 v55, v54, v7
	v_fma_f32 v54, -v54, v7, v7
	s_waitcnt vmcnt(0)
	v_lshlrev_b32_e32 v7, 16, v60
	v_cndmask_b32_e32 v152, v54, v55, vcc
	v_fma_f32 v54, |v7|, s92, 1.0
	v_rcp_f32_e32 v54, v54
	v_mul_f32_e32 v56, v7, v7
	v_mul_f32_e32 v56, 0xbf38aa3b, v56
	v_exp_f32_e32 v56, v56
	v_fmamk_f32 v55, v54, 0x3f07dc22, v236
	v_fmaak_f32 v55, v54, v55, 0x3f35f0e3
	v_fmaak_f32 v55, v54, v55, 0xbe11a98e
	v_fmaak_f32 v55, v54, v55, 0x3e027906
	v_mul_f32_e32 v54, v54, v55
	v_mul_f32_e32 v54, v56, v54
	v_mul_f32_e32 v55, v54, v7
	v_fma_f32 v54, -v54, v7, v7
	v_cmp_gt_f32_e32 vcc, 0, v7
	global_load_ushort v7, v[38:39], off offset:2048
	s_nop 0
	global_load_ushort v38, v[40:41], off
	global_load_ushort v39, v[42:43], off offset:2048
	s_nop 0
	global_load_ushort v40, v[44:45], off
	global_load_ushort v41, v[46:47], off offset:2048
	global_load_ushort v42, v[48:49], off
	global_load_ushort v43, v[50:51], off offset:2048
	s_nop 0
	global_load_ushort v44, v[52:53], off
	v_cndmask_b32_e32 v153, v54, v55, vcc
	s_mov_b32 s6, 0x6090000
	s_waitcnt vmcnt(7)
	v_lshlrev_b32_e32 v7, 16, v7
	v_fma_f32 v45, |v7|, s92, 1.0
	v_rcp_f32_e32 v45, v45
	v_mul_f32_e32 v47, v7, v7
	v_mul_f32_e32 v47, 0xbf38aa3b, v47
	v_exp_f32_e32 v47, v47
	v_fmamk_f32 v46, v45, 0x3f07dc22, v236
	v_fmaak_f32 v46, v45, v46, 0x3f35f0e3
	v_fmaak_f32 v46, v45, v46, 0xbe11a98e
	v_fmaak_f32 v46, v45, v46, 0x3e027906
	v_mul_f32_e32 v45, v45, v46
	v_mul_f32_e32 v45, v47, v45
	v_mul_f32_e32 v46, v45, v7
	v_fma_f32 v45, -v45, v7, v7
	v_cmp_gt_f32_e32 vcc, 0, v7
	s_waitcnt vmcnt(6)
	v_lshlrev_b32_e32 v7, 16, v38
	v_fma_f32 v38, |v7|, s92, 1.0
	v_rcp_f32_e32 v38, v38
	v_cndmask_b32_e32 v154, v45, v46, vcc
	v_mul_f32_e32 v46, v7, v7
	v_mul_f32_e32 v46, 0xbf38aa3b, v46
	v_fmamk_f32 v45, v38, 0x3f07dc22, v236
	v_fmaak_f32 v45, v38, v45, 0x3f35f0e3
	v_exp_f32_e32 v46, v46
	v_fmaak_f32 v45, v38, v45, 0xbe11a98e
	v_fmaak_f32 v45, v38, v45, 0x3e027906
	v_mul_f32_e32 v38, v38, v45
	v_mul_f32_e32 v38, v46, v38
	v_mul_f32_e32 v45, v38, v7
	v_fma_f32 v38, -v38, v7, v7
	v_cmp_gt_f32_e32 vcc, 0, v7
	s_waitcnt vmcnt(5)
	v_lshlrev_b32_e32 v7, 16, v39
	v_cndmask_b32_e32 v155, v38, v45, vcc
	v_fma_f32 v38, |v7|, s92, 1.0
	v_rcp_f32_e32 v38, v38
	v_mul_f32_e32 v45, v7, v7
	v_mul_f32_e32 v45, 0xbf38aa3b, v45
	v_exp_f32_e32 v45, v45
	v_fmamk_f32 v39, v38, 0x3f07dc22, v236
	v_fmaak_f32 v39, v38, v39, 0x3f35f0e3
	v_fmaak_f32 v39, v38, v39, 0xbe11a98e
	v_fmaak_f32 v39, v38, v39, 0x3e027906
	v_mul_f32_e32 v38, v38, v39
	v_mul_f32_e32 v38, v45, v38
	v_mul_f32_e32 v39, v38, v7
	v_fma_f32 v38, -v38, v7, v7
	v_cmp_gt_f32_e32 vcc, 0, v7
	s_waitcnt vmcnt(4)
	v_lshlrev_b32_e32 v7, 16, v40
	v_mul_f32_e32 v40, v7, v7
	v_cndmask_b32_e32 v156, v38, v39, vcc
	v_fma_f32 v38, |v7|, s92, 1.0
	v_rcp_f32_e32 v38, v38
	v_mul_f32_e32 v40, 0xbf38aa3b, v40
	v_exp_f32_e32 v40, v40
	v_cmp_gt_f32_e32 vcc, 0, v7
	v_fmamk_f32 v39, v38, 0x3f07dc22, v236
	v_fmaak_f32 v39, v38, v39, 0x3f35f0e3
	v_fmaak_f32 v39, v38, v39, 0xbe11a98e
	v_fmaak_f32 v39, v38, v39, 0x3e027906
	v_mul_f32_e32 v38, v38, v39
	v_mul_f32_e32 v38, v40, v38
	v_mul_f32_e32 v39, v38, v7
	v_fma_f32 v38, -v38, v7, v7
	s_waitcnt vmcnt(3)
	v_lshlrev_b32_e32 v7, 16, v41
	v_cndmask_b32_e32 v157, v38, v39, vcc
	v_fma_f32 v38, |v7|, s92, 1.0
	v_rcp_f32_e32 v38, v38
	v_mul_f32_e32 v40, v7, v7
	v_mul_f32_e32 v40, 0xbf38aa3b, v40
	v_exp_f32_e32 v40, v40
	v_fmamk_f32 v39, v38, 0x3f07dc22, v236
	v_fmaak_f32 v39, v38, v39, 0x3f35f0e3
	v_fmaak_f32 v39, v38, v39, 0xbe11a98e
	v_fmaak_f32 v39, v38, v39, 0x3e027906
	v_mul_f32_e32 v38, v38, v39
	v_mul_f32_e32 v38, v40, v38
	v_mul_f32_e32 v39, v38, v7
	v_fma_f32 v38, -v38, v7, v7
	v_cmp_gt_f32_e32 vcc, 0, v7
	s_waitcnt vmcnt(2)
	v_lshlrev_b32_e32 v7, 16, v42
	v_mul_f32_e32 v40, v7, v7
	v_cndmask_b32_e32 v158, v38, v39, vcc
	v_fma_f32 v38, |v7|, s92, 1.0
	v_rcp_f32_e32 v38, v38
	v_mul_f32_e32 v40, 0xbf38aa3b, v40
	v_exp_f32_e32 v40, v40
	v_cmp_gt_f32_e32 vcc, 0, v7
	v_fmamk_f32 v39, v38, 0x3f07dc22, v236
	v_fmaak_f32 v39, v38, v39, 0x3f35f0e3
	v_fmaak_f32 v39, v38, v39, 0xbe11a98e
	v_fmaak_f32 v39, v38, v39, 0x3e027906
	v_mul_f32_e32 v38, v38, v39
	v_mul_f32_e32 v38, v40, v38
	v_mul_f32_e32 v39, v38, v7
	v_fma_f32 v38, -v38, v7, v7
	s_waitcnt vmcnt(1)
	v_lshlrev_b32_e32 v7, 16, v43
	v_cndmask_b32_e32 v159, v38, v39, vcc
	v_fma_f32 v38, |v7|, s92, 1.0
	v_rcp_f32_e32 v38, v38
	v_mul_f32_e32 v40, v7, v7
	v_mul_f32_e32 v40, 0xbf38aa3b, v40
	v_exp_f32_e32 v40, v40
	v_fmamk_f32 v39, v38, 0x3f07dc22, v236
	v_fmaak_f32 v39, v38, v39, 0x3f35f0e3
	v_fmaak_f32 v39, v38, v39, 0xbe11a98e
	v_fmaak_f32 v39, v38, v39, 0x3e027906
	v_mul_f32_e32 v38, v38, v39
	v_mul_f32_e32 v38, v40, v38
	v_mul_f32_e32 v39, v38, v7
	v_fma_f32 v38, -v38, v7, v7
	v_cmp_gt_f32_e32 vcc, 0, v7
	s_waitcnt vmcnt(0)
	v_lshlrev_b32_e32 v7, 16, v44
	v_mul_f32_e32 v40, v7, v7
	v_cndmask_b32_e32 v160, v38, v39, vcc
	v_fma_f32 v38, |v7|, s92, 1.0
	v_rcp_f32_e32 v38, v38
	v_mul_f32_e32 v40, 0xbf38aa3b, v40
	v_exp_f32_e32 v40, v40
	v_cmp_gt_f32_e32 vcc, 0, v7
	v_fmamk_f32 v39, v38, 0x3f07dc22, v236
	v_fmaak_f32 v39, v38, v39, 0x3f35f0e3
	v_fmaak_f32 v39, v38, v39, 0xbe11a98e
	v_fmaak_f32 v39, v38, v39, 0x3e027906
	v_mul_f32_e32 v38, v38, v39
	v_mul_f32_e32 v38, v40, v38
	v_mul_f32_e32 v39, v38, v7
	v_fma_f32 v38, -v38, v7, v7
	global_load_ushort v7, v[12:13], off offset:2048
	s_nop 0
	global_load_ushort v12, v[14:15], off
	global_load_ushort v13, v[16:17], off offset:2048
	s_nop 0
	global_load_ushort v14, v[34:35], off
	global_load_ushort v15, v[36:37], off offset:2048
	v_cndmask_b32_e32 v161, v38, v39, vcc
	s_waitcnt vmcnt(4)
	v_lshlrev_b32_e32 v7, 16, v7
	v_fma_f32 v16, |v7|, s92, 1.0
	v_rcp_f32_e32 v16, v16
	v_mul_f32_e32 v34, v7, v7
	v_mul_f32_e32 v34, 0xbf38aa3b, v34
	v_exp_f32_e32 v34, v34
	v_fmamk_f32 v17, v16, 0x3f07dc22, v236
	v_fmaak_f32 v17, v16, v17, 0x3f35f0e3
	v_fmaak_f32 v17, v16, v17, 0xbe11a98e
	v_fmaak_f32 v17, v16, v17, 0x3e027906
	v_mul_f32_e32 v16, v16, v17
	v_mul_f32_e32 v16, v34, v16
	v_mul_f32_e32 v17, v16, v7
	v_fma_f32 v16, -v16, v7, v7
	v_cmp_gt_f32_e32 vcc, 0, v7
	s_waitcnt vmcnt(3)
	v_lshlrev_b32_e32 v7, 16, v12
	v_fma_f32 v12, |v7|, s92, 1.0
	v_rcp_f32_e32 v12, v12
	v_cndmask_b32_e32 v162, v16, v17, vcc
	v_mul_f32_e32 v17, v7, v7
	v_mul_f32_e32 v17, 0xbf38aa3b, v17
	v_fmamk_f32 v16, v12, 0x3f07dc22, v236
	v_fmaak_f32 v16, v12, v16, 0x3f35f0e3
	v_exp_f32_e32 v17, v17
	v_fmaak_f32 v16, v12, v16, 0xbe11a98e
	v_fmaak_f32 v16, v12, v16, 0x3e027906
	v_mul_f32_e32 v12, v12, v16
	v_mul_f32_e32 v12, v17, v12
	v_mul_f32_e32 v16, v12, v7
	v_fma_f32 v12, -v12, v7, v7
	v_cmp_gt_f32_e32 vcc, 0, v7
	s_waitcnt vmcnt(2)
	v_lshlrev_b32_e32 v7, 16, v13
	v_cndmask_b32_e32 v163, v12, v16, vcc
	v_fma_f32 v12, |v7|, s92, 1.0
	v_rcp_f32_e32 v12, v12
	v_mul_f32_e32 v16, v7, v7
	v_mul_f32_e32 v16, 0xbf38aa3b, v16
	v_exp_f32_e32 v16, v16
	v_fmamk_f32 v13, v12, 0x3f07dc22, v236
	v_fmaak_f32 v13, v12, v13, 0x3f35f0e3
	v_fmaak_f32 v13, v12, v13, 0xbe11a98e
	v_fmaak_f32 v13, v12, v13, 0x3e027906
	v_mul_f32_e32 v12, v12, v13
	v_mul_f32_e32 v12, v16, v12
	v_mul_f32_e32 v13, v12, v7
	v_fma_f32 v12, -v12, v7, v7
	v_cmp_gt_f32_e32 vcc, 0, v7
	s_waitcnt vmcnt(1)
	v_lshlrev_b32_e32 v7, 16, v14
	v_mul_f32_e32 v14, v7, v7
	v_cndmask_b32_e32 v164, v12, v13, vcc
	v_fma_f32 v12, |v7|, s92, 1.0
	v_rcp_f32_e32 v12, v12
	v_mul_f32_e32 v14, 0xbf38aa3b, v14
	v_exp_f32_e32 v14, v14
	v_cmp_gt_f32_e32 vcc, 0, v7
	v_fmamk_f32 v13, v12, 0x3f07dc22, v236
	v_fmaak_f32 v13, v12, v13, 0x3f35f0e3
	v_fmaak_f32 v13, v12, v13, 0xbe11a98e
	v_fmaak_f32 v13, v12, v13, 0x3e027906
	v_mul_f32_e32 v12, v12, v13
	v_mul_f32_e32 v12, v14, v12
	v_mul_f32_e32 v13, v12, v7
	v_fma_f32 v12, -v12, v7, v7
	s_waitcnt vmcnt(0)
	v_lshlrev_b32_e32 v7, 16, v15
	v_cndmask_b32_e32 v165, v12, v13, vcc
	v_fma_f32 v12, |v7|, s92, 1.0
	v_rcp_f32_e32 v12, v12
	v_mul_f32_e32 v14, v7, v7
	v_mul_f32_e32 v14, 0xbf38aa3b, v14
	v_exp_f32_e32 v14, v14
	v_fmamk_f32 v13, v12, 0x3f07dc22, v236
	v_fmaak_f32 v13, v12, v13, 0x3f35f0e3
	v_fmaak_f32 v13, v12, v13, 0xbe11a98e
	v_fmaak_f32 v13, v12, v13, 0x3e027906
	v_mul_f32_e32 v12, v12, v13
	v_mul_f32_e32 v12, v14, v12
	v_mul_f32_e32 v13, v12, v7
	v_fma_f32 v12, -v12, v7, v7
	v_cmp_gt_f32_e32 vcc, 0, v7
	v_lshlrev_b32_e32 v7, 4, v73
	v_add3_u32 v34, 0, v6, v7
	v_cndmask_b32_e32 v166, v12, v13, vcc
	v_add_co_u32_e32 v88, vcc, s41, v8
	ds_read_b128 v[62:65], v34
	ds_read_b128 v[58:61], v34 offset:32
	ds_read_b128 v[54:57], v34 offset:64
	ds_read_b128 v[50:53], v34 offset:96
	v_addc_co_u32_e32 v89, vcc, 0, v9, vcc
	v_add_co_u32_e32 v86, vcc, s97, v8
	v_add_u32_e32 v150, s5, v7
	s_nop 0
	v_addc_co_u32_e32 v87, vcc, 0, v9, vcc
	v_add_co_u32_e32 v116, vcc, s6, v10
	s_mov_b32 s6, 0x6091000
	s_nop 0
	v_addc_co_u32_e32 v117, vcc, 0, v11, vcc
	v_add_co_u32_e32 v118, vcc, s6, v10
	s_mov_b32 s6, 0x6093000
	s_nop 0
	v_addc_co_u32_e32 v119, vcc, 0, v11, vcc
	v_add_co_u32_e32 v120, vcc, s6, v10
	s_mov_b32 s6, 0x6094000
	s_nop 0
	v_addc_co_u32_e32 v121, vcc, 0, v11, vcc
	v_add_co_u32_e32 v100, vcc, s6, v10
	s_mov_b32 s6, 0x609c000
	s_nop 0
	v_addc_co_u32_e32 v101, vcc, 0, v11, vcc
	v_add_co_u32_e32 v102, vcc, s6, v10
	s_mov_b32 s6, 0x609d000
	s_nop 0
	v_addc_co_u32_e32 v103, vcc, 0, v11, vcc
	v_add_co_u32_e32 v104, vcc, s6, v10
	s_mov_b32 s6, 0x609f000
	s_nop 0
	v_addc_co_u32_e32 v105, vcc, 0, v11, vcc
	v_add_co_u32_e32 v106, vcc, s6, v10
	s_mov_b32 s6, 0x60a0000
	s_nop 0
	v_addc_co_u32_e32 v107, vcc, 0, v11, vcc
	v_add_co_u32_e32 v108, vcc, s6, v10
	s_mov_b32 s6, 0x60a8000
	s_nop 0
	v_addc_co_u32_e32 v109, vcc, 0, v11, vcc
	v_add_co_u32_e32 v110, vcc, s6, v10
	s_mov_b32 s6, 0x60a9000
	s_nop 0
	v_addc_co_u32_e32 v111, vcc, 0, v11, vcc
	v_add_co_u32_e32 v112, vcc, s6, v10
	s_mov_b32 s6, 0x60ab000
	s_nop 0
	v_addc_co_u32_e32 v113, vcc, 0, v11, vcc
	v_add_co_u32_e32 v114, vcc, s6, v10
	s_mov_b32 s6, 0x60ac000
	s_nop 0
	v_addc_co_u32_e32 v115, vcc, 0, v11, vcc
	v_add_co_u32_e32 v90, vcc, s6, v10
	s_mov_b32 s6, 0x60b4000
	s_nop 0
	v_addc_co_u32_e32 v91, vcc, 0, v11, vcc
	v_add_co_u32_e32 v92, vcc, s6, v10
	s_mov_b32 s6, 0x60b5000
	s_nop 0
	v_addc_co_u32_e32 v93, vcc, 0, v11, vcc
	v_add_co_u32_e32 v94, vcc, s6, v10
	s_mov_b32 s6, 0x60b7000
	s_nop 0
	v_addc_co_u32_e32 v95, vcc, 0, v11, vcc
	v_add_co_u32_e32 v96, vcc, s6, v10
	s_mov_b32 s6, 0x60b8000
	s_nop 0
	v_addc_co_u32_e32 v97, vcc, 0, v11, vcc
	v_add_co_u32_e32 v98, vcc, s6, v10
	ds_read_b128 v[46:49], v34 offset:128
	ds_read_b128 v[42:45], v34 offset:160
	ds_read_b128 v[38:41], v34 offset:192
	ds_read_b128 v[34:37], v34 offset:224
	v_addc_co_u32_e32 v99, vcc, 0, v11, vcc
	s_waitcnt lgkmcnt(7)
	v_mfma_f32_32x32x16_bf16 v[2:17], v[2:5], v[62:65], 0
	global_load_dwordx4 v[66:69], v[82:83], off offset:-4096
	ds_read_b128 v[182:185], v150
	v_mov_b32_e32 v73, v131
	v_lshlrev_b64 v[72:73], 11, v[72:73]
	v_lshl_add_u64 v[72:73], v[84:85], 0, v[72:73]
	v_readlane_b32 s5, v252, 31
	s_waitcnt lgkmcnt(7)
	v_mfma_f32_32x32x16_bf16 v[2:17], v[30:33], v[58:61], v[2:17]
	ds_read_b128 v[30:33], v150 offset:32
	s_waitcnt lgkmcnt(1)
	s_nop 9
	v_add_f32_e32 v2, v2, v182
	v_mul_f32_e32 v2, v130, v2
	v_cvt_pk_bf16_f32 v2, v2, s0
	global_store_short v[72:73], v2, off sc1
	v_add_f32_e32 v2, v3, v183
	v_mul_f32_e32 v2, v167, v2
	v_cvt_pk_bf16_f32 v72, v2, s0
	v_or_b32_e32 v2, s5, v1
	v_lshlrev_b32_e32 v130, 11, v2
	v_lshl_add_u64 v[2:3], v[84:85], 0, v[130:131]
	global_store_short v[2:3], v72, off sc1
	v_add_f32_e32 v2, v4, v184
	v_mul_f32_e32 v2, v168, v2
	v_readlane_b32 s5, v252, 32
	v_cvt_pk_bf16_f32 v4, v2, s0
	s_nop 0
	v_or_b32_e32 v2, s5, v1
	v_lshlrev_b32_e32 v130, 11, v2
	v_lshl_add_u64 v[2:3], v[84:85], 0, v[130:131]
	global_store_short v[2:3], v4, off sc1
	v_add_f32_e32 v2, v5, v185
	v_mul_f32_e32 v2, v169, v2
	v_readlane_b32 s5, v252, 33
	v_cvt_pk_bf16_f32 v4, v2, s0
	s_nop 0
	v_or_b32_e32 v2, s5, v1
	v_lshlrev_b32_e32 v130, 11, v2
	v_lshl_add_u64 v[2:3], v[84:85], 0, v[130:131]
	global_store_short v[2:3], v4, off sc1
	s_waitcnt lgkmcnt(0)
	v_add_f32_e32 v2, v6, v30
	v_mul_f32_e32 v2, v170, v2
	v_readlane_b32 s5, v252, 34
	v_cvt_pk_bf16_f32 v4, v2, s0
	s_nop 0
	v_or_b32_e32 v2, s5, v1
	v_lshlrev_b32_e32 v130, 11, v2
	v_lshl_add_u64 v[2:3], v[84:85], 0, v[130:131]
	global_store_short v[2:3], v4, off sc1
	v_add_f32_e32 v2, v7, v31
	v_mul_f32_e32 v2, v171, v2
	v_readlane_b32 s5, v252, 35
	v_cvt_pk_bf16_f32 v4, v2, s0
	s_nop 0
	v_or_b32_e32 v2, s5, v1
	v_lshlrev_b32_e32 v130, 11, v2
	v_lshl_add_u64 v[2:3], v[84:85], 0, v[130:131]
	global_store_short v[2:3], v4, off sc1
	v_add_f32_e32 v2, v8, v32
	v_mul_f32_e32 v2, v172, v2
	v_readlane_b32 s5, v252, 36
	v_cvt_pk_bf16_f32 v4, v2, s0
	s_nop 0
	v_or_b32_e32 v2, s5, v1
	v_lshlrev_b32_e32 v130, 11, v2
	v_lshl_add_u64 v[2:3], v[84:85], 0, v[130:131]
	global_store_short v[2:3], v4, off sc1
	v_add_f32_e32 v2, v9, v33
	v_mul_f32_e32 v2, v173, v2
	v_cvt_pk_bf16_f32 v8, v2, s0
	ds_read_b128 v[2:5], v150 offset:64
	v_readlane_b32 s5, v252, 37
	s_nop 1
	v_or_b32_e32 v6, s5, v1
	v_lshlrev_b32_e32 v130, 11, v6
	v_lshl_add_u64 v[6:7], v[84:85], 0, v[130:131]
	v_readlane_b32 s5, v252, 38
	global_store_short v[6:7], v8, off sc1
	ds_read_b128 v[6:9], v150 offset:96
	s_waitcnt lgkmcnt(1)
	v_add_f32_e32 v2, v10, v2
	v_or_b32_e32 v10, s5, v1
	v_mul_f32_e32 v2, v174, v2
	v_lshlrev_b32_e32 v130, 11, v10
	v_cvt_pk_bf16_f32 v2, v2, s0
	v_lshl_add_u64 v[30:31], v[84:85], 0, v[130:131]
	global_store_short v[30:31], v2, off sc1
	v_add_f32_e32 v2, v11, v3
	v_mul_f32_e32 v2, v175, v2
	v_readlane_b32 s5, v252, 39
	v_cvt_pk_bf16_f32 v10, v2, s0
	s_nop 0
	v_or_b32_e32 v2, s5, v1
	v_lshlrev_b32_e32 v130, 11, v2
	v_lshl_add_u64 v[2:3], v[84:85], 0, v[130:131]
	global_store_short v[2:3], v10, off sc1
	v_add_f32_e32 v2, v12, v4
	v_mul_f32_e32 v2, v176, v2
	v_readlane_b32 s5, v252, 40
	v_cvt_pk_bf16_f32 v4, v2, s0
	s_nop 0
	v_or_b32_e32 v2, s5, v1
	v_lshlrev_b32_e32 v130, 11, v2
	v_lshl_add_u64 v[2:3], v[84:85], 0, v[130:131]
	global_store_short v[2:3], v4, off sc1
	v_add_f32_e32 v2, v13, v5
	v_mul_f32_e32 v2, v177, v2
	v_readlane_b32 s5, v252, 41
	v_cvt_pk_bf16_f32 v4, v2, s0
	s_nop 0
	v_or_b32_e32 v2, s5, v1
	v_lshlrev_b32_e32 v130, 11, v2
	v_lshl_add_u64 v[2:3], v[84:85], 0, v[130:131]
	global_store_short v[2:3], v4, off sc1
	s_waitcnt lgkmcnt(0)
	v_add_f32_e32 v2, v14, v6
	v_mul_f32_e32 v2, v178, v2
	v_readlane_b32 s5, v252, 42
	v_cvt_pk_bf16_f32 v4, v2, s0
	s_nop 0
	v_or_b32_e32 v2, s5, v1
	v_lshlrev_b32_e32 v130, 11, v2
	v_lshl_add_u64 v[2:3], v[84:85], 0, v[130:131]
	global_store_short v[2:3], v4, off sc1
	v_add_f32_e32 v2, v15, v7
	v_mul_f32_e32 v2, v179, v2
	v_readlane_b32 s5, v252, 43
	v_cvt_pk_bf16_f32 v4, v2, s0
	s_nop 0
	v_or_b32_e32 v2, s5, v1
	v_lshlrev_b32_e32 v130, 11, v2
	v_lshl_add_u64 v[2:3], v[84:85], 0, v[130:131]
	global_store_short v[2:3], v4, off sc1
	v_add_f32_e32 v2, v16, v8
	v_mul_f32_e32 v2, v180, v2
	v_readlane_b32 s5, v252, 44
	v_cvt_pk_bf16_f32 v4, v2, s0
	s_nop 0
	v_or_b32_e32 v2, s5, v1
	v_lshlrev_b32_e32 v130, 11, v2
	v_lshl_add_u64 v[2:3], v[84:85], 0, v[130:131]
	global_store_short v[2:3], v4, off sc1
	v_add_f32_e32 v2, v17, v9
	v_mul_f32_e32 v2, v181, v2
	v_readlane_b32 s5, v252, 45
	v_cvt_pk_bf16_f32 v4, v2, s0
	s_nop 0
	v_or_b32_e32 v2, s5, v1
	v_lshlrev_b32_e32 v130, 11, v2
	v_lshl_add_u64 v[2:3], v[84:85], 0, v[130:131]
	global_store_short v[2:3], v4, off sc1
	global_load_ushort v2, v[134:135], off
	global_load_ushort v3, v[136:137], off offset:2048
	global_load_ushort v4, v[138:139], off
	global_load_ushort v5, v[140:141], off offset:2048
	global_load_ushort v6, v[142:143], off
	global_load_ushort v7, v[144:145], off offset:2048
	global_load_ushort v8, v[146:147], off
	global_load_ushort v9, v[148:149], off offset:2048
	v_readlane_b32 s5, v252, 46
	s_waitcnt vmcnt(7)
	v_lshlrev_b32_e32 v2, 16, v2
	v_fma_f32 v10, |v2|, s92, 1.0
	v_rcp_f32_e32 v10, v10
	v_mul_f32_e32 v12, v2, v2
	v_mul_f32_e32 v12, 0xbf38aa3b, v12
	v_exp_f32_e32 v12, v12
	v_fmamk_f32 v11, v10, 0x3f07dc22, v236
	v_fmaak_f32 v11, v10, v11, 0x3f35f0e3
	v_fmaak_f32 v11, v10, v11, 0xbe11a98e
	v_fmaak_f32 v11, v10, v11, 0x3e027906
	v_mul_f32_e32 v10, v10, v11
	v_mul_f32_e32 v10, v12, v10
	v_mul_f32_e32 v11, v10, v2
	v_fma_f32 v10, -v10, v2, v2
	v_cmp_gt_f32_e32 vcc, 0, v2
	s_waitcnt vmcnt(6)
	v_lshlrev_b32_e32 v2, 16, v3
	v_fma_f32 v3, |v2|, s92, 1.0
	v_rcp_f32_e32 v3, v3
	v_cndmask_b32_e32 v134, v10, v11, vcc
	v_mul_f32_e32 v11, v2, v2
	v_mul_f32_e32 v11, 0xbf38aa3b, v11
	v_fmamk_f32 v10, v3, 0x3f07dc22, v236
	v_fmaak_f32 v10, v3, v10, 0x3f35f0e3
	v_exp_f32_e32 v11, v11
	v_fmaak_f32 v10, v3, v10, 0xbe11a98e
	v_fmaak_f32 v10, v3, v10, 0x3e027906
	v_mul_f32_e32 v3, v3, v10
	v_mul_f32_e32 v3, v11, v3
	v_mul_f32_e32 v10, v3, v2
	v_fma_f32 v3, -v3, v2, v2
	v_cmp_gt_f32_e32 vcc, 0, v2
	s_waitcnt vmcnt(5)
	v_lshlrev_b32_e32 v2, 16, v4
	v_cndmask_b32_e32 v135, v3, v10, vcc
	v_fma_f32 v3, |v2|, s92, 1.0
	v_rcp_f32_e32 v3, v3
	v_mul_f32_e32 v10, v2, v2
	v_mul_f32_e32 v10, 0xbf38aa3b, v10
	v_exp_f32_e32 v10, v10
	v_fmamk_f32 v4, v3, 0x3f07dc22, v236
	v_fmaak_f32 v4, v3, v4, 0x3f35f0e3
	v_fmaak_f32 v4, v3, v4, 0xbe11a98e
	v_fmaak_f32 v4, v3, v4, 0x3e027906
	v_mul_f32_e32 v3, v3, v4
	v_mul_f32_e32 v3, v10, v3
	v_mul_f32_e32 v4, v3, v2
	v_fma_f32 v3, -v3, v2, v2
	v_cmp_gt_f32_e32 vcc, 0, v2
	s_waitcnt vmcnt(4)
	v_lshlrev_b32_e32 v2, 16, v5
	v_mul_f32_e32 v5, v2, v2
	v_cndmask_b32_e32 v136, v3, v4, vcc
	v_fma_f32 v3, |v2|, s92, 1.0
	v_rcp_f32_e32 v3, v3
	v_mul_f32_e32 v5, 0xbf38aa3b, v5
	v_exp_f32_e32 v5, v5
	v_cmp_gt_f32_e32 vcc, 0, v2
	v_fmamk_f32 v4, v3, 0x3f07dc22, v236
	v_fmaak_f32 v4, v3, v4, 0x3f35f0e3
	v_fmaak_f32 v4, v3, v4, 0xbe11a98e
	v_fmaak_f32 v4, v3, v4, 0x3e027906
	v_mul_f32_e32 v3, v3, v4
	v_mul_f32_e32 v3, v5, v3
	v_mul_f32_e32 v4, v3, v2
	v_fma_f32 v3, -v3, v2, v2
	s_waitcnt vmcnt(3)
	v_lshlrev_b32_e32 v2, 16, v6
	v_cndmask_b32_e32 v137, v3, v4, vcc
	v_fma_f32 v3, |v2|, s92, 1.0
	v_rcp_f32_e32 v3, v3
	v_mul_f32_e32 v5, v2, v2
	v_mul_f32_e32 v5, 0xbf38aa3b, v5
	v_exp_f32_e32 v5, v5
	v_fmamk_f32 v4, v3, 0x3f07dc22, v236
	v_fmaak_f32 v4, v3, v4, 0x3f35f0e3
	v_fmaak_f32 v4, v3, v4, 0xbe11a98e
	v_fmaak_f32 v4, v3, v4, 0x3e027906
	v_mul_f32_e32 v3, v3, v4
	v_mul_f32_e32 v3, v5, v3
	v_mul_f32_e32 v4, v3, v2
	v_fma_f32 v3, -v3, v2, v2
	v_cmp_gt_f32_e32 vcc, 0, v2
	s_waitcnt vmcnt(2)
	v_lshlrev_b32_e32 v2, 16, v7
	v_mul_f32_e32 v5, v2, v2
	v_cndmask_b32_e32 v138, v3, v4, vcc
	v_fma_f32 v3, |v2|, s92, 1.0
	v_rcp_f32_e32 v3, v3
	v_mul_f32_e32 v5, 0xbf38aa3b, v5
	v_exp_f32_e32 v5, v5
	v_cmp_gt_f32_e32 vcc, 0, v2
	v_fmamk_f32 v4, v3, 0x3f07dc22, v236
	v_fmaak_f32 v4, v3, v4, 0x3f35f0e3
	v_fmaak_f32 v4, v3, v4, 0xbe11a98e
	v_fmaak_f32 v4, v3, v4, 0x3e027906
	v_mul_f32_e32 v3, v3, v4
	v_mul_f32_e32 v3, v5, v3
	v_mul_f32_e32 v4, v3, v2
	v_fma_f32 v3, -v3, v2, v2
	s_waitcnt vmcnt(1)
	v_lshlrev_b32_e32 v2, 16, v8
	v_cndmask_b32_e32 v139, v3, v4, vcc
	v_fma_f32 v3, |v2|, s92, 1.0
	v_rcp_f32_e32 v3, v3
	v_mul_f32_e32 v5, v2, v2
	v_mul_f32_e32 v5, 0xbf38aa3b, v5
	v_exp_f32_e32 v5, v5
	v_fmamk_f32 v4, v3, 0x3f07dc22, v236
	v_fmaak_f32 v4, v3, v4, 0x3f35f0e3
	v_fmaak_f32 v4, v3, v4, 0xbe11a98e
	v_fmaak_f32 v4, v3, v4, 0x3e027906
	v_mul_f32_e32 v3, v3, v4
	v_mul_f32_e32 v3, v5, v3
	v_mul_f32_e32 v4, v3, v2
	v_fma_f32 v3, -v3, v2, v2
	v_cmp_gt_f32_e32 vcc, 0, v2
	s_waitcnt vmcnt(0)
	v_lshlrev_b32_e32 v2, 16, v9
	v_mul_f32_e32 v5, v2, v2
	v_cndmask_b32_e32 v140, v3, v4, vcc
	v_fma_f32 v3, |v2|, s92, 1.0
	v_rcp_f32_e32 v3, v3
	v_mul_f32_e32 v5, 0xbf38aa3b, v5
	v_exp_f32_e32 v5, v5
	v_cmp_gt_f32_e32 vcc, 0, v2
	v_fmamk_f32 v4, v3, 0x3f07dc22, v236
	v_fmaak_f32 v4, v3, v4, 0x3f35f0e3
	v_fmaak_f32 v4, v3, v4, 0xbe11a98e
	v_fmaak_f32 v4, v3, v4, 0x3e027906
	v_mul_f32_e32 v3, v3, v4
	v_mul_f32_e32 v3, v5, v3
	v_mul_f32_e32 v4, v3, v2
	v_fma_f32 v3, -v3, v2, v2
	v_cndmask_b32_e32 v141, v3, v4, vcc
	global_load_ushort v2, v[76:77], off
	global_load_ushort v3, v[78:79], off offset:2048
	global_load_ushort v4, v[80:81], off
	global_load_ushort v5, v[122:123], off offset:2048
	global_load_ushort v6, v[124:125], off
	global_load_ushort v7, v[126:127], off offset:2048
	global_load_ushort v8, v[128:129], off
	global_load_ushort v30, v[132:133], off offset:2048
	s_waitcnt vmcnt(7)
	v_lshlrev_b32_e32 v2, 16, v2
	v_fma_f32 v9, |v2|, s92, 1.0
	v_rcp_f32_e32 v9, v9
	v_mul_f32_e32 v11, v2, v2
	v_mul_f32_e32 v11, 0xbf38aa3b, v11
	v_exp_f32_e32 v11, v11
	v_fmamk_f32 v10, v9, 0x3f07dc22, v236
	v_fmaak_f32 v10, v9, v10, 0x3f35f0e3
	v_fmaak_f32 v10, v9, v10, 0xbe11a98e
	v_fmaak_f32 v10, v9, v10, 0x3e027906
	v_mul_f32_e32 v9, v9, v10
	v_mul_f32_e32 v9, v11, v9
	v_mul_f32_e32 v10, v9, v2
	v_fma_f32 v9, -v9, v2, v2
	v_cmp_gt_f32_e32 vcc, 0, v2
	s_waitcnt vmcnt(6)
	v_lshlrev_b32_e32 v2, 16, v3
	v_fma_f32 v3, |v2|, s92, 1.0
	v_rcp_f32_e32 v3, v3
	v_cndmask_b32_e32 v122, v9, v10, vcc
	v_mul_f32_e32 v10, v2, v2
	v_mul_f32_e32 v10, 0xbf38aa3b, v10
	v_fmamk_f32 v9, v3, 0x3f07dc22, v236
	v_fmaak_f32 v9, v3, v9, 0x3f35f0e3
	v_exp_f32_e32 v10, v10
	v_fmaak_f32 v9, v3, v9, 0xbe11a98e
	v_fmaak_f32 v9, v3, v9, 0x3e027906
	v_mul_f32_e32 v3, v3, v9
	v_mul_f32_e32 v3, v10, v3
	v_mul_f32_e32 v9, v3, v2
	v_fma_f32 v3, -v3, v2, v2
	v_cmp_gt_f32_e32 vcc, 0, v2
	s_waitcnt vmcnt(5)
	v_lshlrev_b32_e32 v2, 16, v4
	s_waitcnt vmcnt(1)
	v_lshlrev_b32_e32 v31, 16, v8
	v_cndmask_b32_e32 v123, v3, v9, vcc
	v_fma_f32 v3, |v2|, s92, 1.0
	v_rcp_f32_e32 v3, v3
	v_mul_f32_e32 v9, v2, v2
	v_mul_f32_e32 v9, 0xbf38aa3b, v9
	v_exp_f32_e32 v9, v9
	v_fmamk_f32 v4, v3, 0x3f07dc22, v236
	v_fmaak_f32 v4, v3, v4, 0x3f35f0e3
	v_fmaak_f32 v4, v3, v4, 0xbe11a98e
	v_fmaak_f32 v4, v3, v4, 0x3e027906
	v_mul_f32_e32 v3, v3, v4
	v_mul_f32_e32 v3, v9, v3
	v_mul_f32_e32 v4, v3, v2
	v_fma_f32 v3, -v3, v2, v2
	v_cmp_gt_f32_e32 vcc, 0, v2
	v_lshlrev_b32_e32 v2, 16, v5
	v_mul_f32_e32 v5, v2, v2
	v_cndmask_b32_e32 v124, v3, v4, vcc
	v_fma_f32 v3, |v2|, s92, 1.0
	v_rcp_f32_e32 v3, v3
	v_mul_f32_e32 v5, 0xbf38aa3b, v5
	v_exp_f32_e32 v5, v5
	v_cmp_gt_f32_e32 vcc, 0, v2
	v_fmamk_f32 v4, v3, 0x3f07dc22, v236
	v_fmaak_f32 v4, v3, v4, 0x3f35f0e3
	v_fmaak_f32 v4, v3, v4, 0xbe11a98e
	v_fmaak_f32 v4, v3, v4, 0x3e027906
	v_mul_f32_e32 v3, v3, v4
	v_mul_f32_e32 v3, v5, v3
	v_mul_f32_e32 v4, v3, v2
	v_fma_f32 v3, -v3, v2, v2
	v_lshlrev_b32_e32 v2, 16, v6
	v_cndmask_b32_e32 v125, v3, v4, vcc
	v_fma_f32 v3, |v2|, s92, 1.0
	v_rcp_f32_e32 v3, v3
	v_mul_f32_e32 v5, v2, v2
	v_mul_f32_e32 v5, 0xbf38aa3b, v5
	v_exp_f32_e32 v5, v5
	v_fmamk_f32 v4, v3, 0x3f07dc22, v236
	v_fmaak_f32 v4, v3, v4, 0x3f35f0e3
	v_fmaak_f32 v4, v3, v4, 0xbe11a98e
	v_fmaak_f32 v4, v3, v4, 0x3e027906
	v_mul_f32_e32 v3, v3, v4
	v_mul_f32_e32 v3, v5, v3
	v_mul_f32_e32 v4, v3, v2
	v_fma_f32 v3, -v3, v2, v2
	v_cmp_gt_f32_e32 vcc, 0, v2
	v_lshlrev_b32_e32 v2, 16, v7
	v_mul_f32_e32 v5, v2, v2
	v_cndmask_b32_e32 v126, v3, v4, vcc
	v_fma_f32 v3, |v2|, s92, 1.0
	v_rcp_f32_e32 v3, v3
	v_mul_f32_e32 v5, 0xbf38aa3b, v5
	v_exp_f32_e32 v5, v5
	v_cmp_gt_f32_e32 vcc, 0, v2
	v_fmamk_f32 v4, v3, 0x3f07dc22, v236
	v_fmaak_f32 v4, v3, v4, 0x3f35f0e3
	v_fmaak_f32 v4, v3, v4, 0xbe11a98e
	v_fmaak_f32 v4, v3, v4, 0x3e027906
	v_mul_f32_e32 v3, v3, v4
	v_mul_f32_e32 v3, v5, v3
	v_mul_f32_e32 v4, v3, v2
	v_fma_f32 v3, -v3, v2, v2
	v_fma_f32 v2, |v31|, s92, 1.0
	v_cndmask_b32_e32 v127, v3, v4, vcc
	v_rcp_f32_e32 v32, v2
	v_mfma_f32_32x32x16_bf16 v[2:17], v[22:25], v[62:65], 0
	v_mul_f32_e32 v23, v31, v31
	v_mul_f32_e32 v23, 0xbf38aa3b, v23
	v_fmamk_f32 v22, v32, 0x3f07dc22, v236
	v_fmaak_f32 v22, v32, v22, 0x3f35f0e3
	v_exp_f32_e32 v23, v23
	v_fmaak_f32 v22, v32, v22, 0xbe11a98e
	v_fmaak_f32 v22, v32, v22, 0x3e027906
	v_mfma_f32_32x32x16_bf16 v[2:17], v[18:21], v[58:61], v[2:17]
	v_mul_f32_e32 v22, v32, v22
	v_mul_f32_e32 v22, v23, v22
	v_mul_f32_e32 v23, v22, v31
	v_fma_f32 v22, -v22, v31, v31
	v_cmp_gt_f32_e32 vcc, 0, v31
	s_nop 1
	v_cndmask_b32_e32 v128, v22, v23, vcc
	s_waitcnt vmcnt(0)
	v_lshlrev_b32_e32 v22, 16, v30
	v_fma_f32 v23, |v22|, s92, 1.0
	v_rcp_f32_e32 v23, v23
	v_mfma_f32_32x32x16_bf16 v[2:17], v[66:69], v[54:57], v[2:17]
	v_mul_f32_e32 v19, v22, v22
	v_mul_f32_e32 v19, 0xbf38aa3b, v19
	v_fmamk_f32 v18, v23, 0x3f07dc22, v236
	v_fmaak_f32 v18, v23, v18, 0x3f35f0e3
	v_exp_f32_e32 v19, v19
	v_fmaak_f32 v18, v23, v18, 0xbe11a98e
	v_fmaak_f32 v18, v23, v18, 0x3e027906
	v_mul_f32_e32 v18, v23, v18
	v_mul_f32_e32 v18, v19, v18
	v_mfma_f32_32x32x16_bf16 v[2:17], v[26:29], v[50:53], v[2:17]
	v_mul_f32_e32 v19, v18, v22
	v_fma_f32 v18, -v18, v22, v22
	v_cmp_gt_f32_e32 vcc, 0, v22
	s_nop 1
	v_cndmask_b32_e32 v129, v18, v19, vcc
	global_load_dwordx4 v[18:21], v[70:71], off offset:2048
	global_load_dwordx4 v[78:81], v[70:71], off offset:3072
	global_load_dwordx4 v[74:77], v[82:83], off
	s_nop 0
	global_load_dwordx4 v[70:73], v[82:83], off offset:1024
	global_load_dwordx4 v[66:69], v[82:83], off offset:2048
	global_load_dwordx4 v[30:33], v[82:83], off offset:3072
	ds_read_b128 v[22:25], v150 offset:128
	ds_read_b128 v[26:29], v150 offset:160
	s_waitcnt lgkmcnt(1)
	v_add_f32_e32 v2, v2, v22
	v_or_b32_e32 v22, s5, v1
	v_mul_f32_e32 v2, v151, v2
	v_lshlrev_b32_e32 v130, 11, v22
	v_cvt_pk_bf16_f32 v2, v2, s0
	v_lshl_add_u64 v[82:83], v[84:85], 0, v[130:131]
	global_store_short v[82:83], v2, off sc1
	v_add_f32_e32 v2, v3, v23
	v_mul_f32_e32 v2, v152, v2
	v_readlane_b32 s5, v252, 47
	v_cvt_pk_bf16_f32 v22, v2, s0
	s_nop 0
	v_or_b32_e32 v2, s5, v1
	v_lshlrev_b32_e32 v130, 11, v2
	v_lshl_add_u64 v[2:3], v[84:85], 0, v[130:131]
	global_store_short v[2:3], v22, off sc1
	v_add_f32_e32 v2, v4, v24
	v_mul_f32_e32 v2, v153, v2
	v_readlane_b32 s5, v252, 48
	v_cvt_pk_bf16_f32 v4, v2, s0
	s_nop 0
	v_or_b32_e32 v2, s5, v1
	v_lshlrev_b32_e32 v130, 11, v2
	v_lshl_add_u64 v[2:3], v[84:85], 0, v[130:131]
	global_store_short v[2:3], v4, off sc1
	v_add_f32_e32 v2, v5, v25
	v_mul_f32_e32 v2, v154, v2
	v_readlane_b32 s5, v252, 49
	v_cvt_pk_bf16_f32 v4, v2, s0
	s_nop 0
	v_or_b32_e32 v2, s5, v1
	v_lshlrev_b32_e32 v130, 11, v2
	v_lshl_add_u64 v[2:3], v[84:85], 0, v[130:131]
	global_store_short v[2:3], v4, off sc1
	s_waitcnt lgkmcnt(0)
	v_add_f32_e32 v2, v6, v26
	v_mul_f32_e32 v2, v155, v2
	v_readlane_b32 s5, v252, 50
	v_cvt_pk_bf16_f32 v4, v2, s0
	s_nop 0
	v_or_b32_e32 v2, s5, v1
	v_lshlrev_b32_e32 v130, 11, v2
	v_lshl_add_u64 v[2:3], v[84:85], 0, v[130:131]
	global_store_short v[2:3], v4, off sc1
	v_add_f32_e32 v2, v7, v27
	v_mul_f32_e32 v2, v156, v2
	v_readlane_b32 s5, v252, 51
	v_cvt_pk_bf16_f32 v4, v2, s0
	s_nop 0
	v_or_b32_e32 v2, s5, v1
	v_lshlrev_b32_e32 v130, 11, v2
	v_lshl_add_u64 v[2:3], v[84:85], 0, v[130:131]
	global_store_short v[2:3], v4, off sc1
	v_add_f32_e32 v2, v8, v28
	v_mul_f32_e32 v2, v157, v2
	v_readlane_b32 s5, v252, 52
	v_cvt_pk_bf16_f32 v4, v2, s0
	s_nop 0
	v_or_b32_e32 v2, s5, v1
	v_lshlrev_b32_e32 v130, 11, v2
	v_lshl_add_u64 v[2:3], v[84:85], 0, v[130:131]
	global_store_short v[2:3], v4, off sc1
	v_add_f32_e32 v2, v9, v29
	v_mul_f32_e32 v2, v158, v2
	v_cvt_pk_bf16_f32 v8, v2, s0
	ds_read_b128 v[2:5], v150 offset:192
	v_readlane_b32 s5, v252, 53
	s_nop 1
	v_or_b32_e32 v6, s5, v1
	v_lshlrev_b32_e32 v130, 11, v6
	v_lshl_add_u64 v[6:7], v[84:85], 0, v[130:131]
	v_readlane_b32 s5, v252, 54
	global_store_short v[6:7], v8, off sc1
	ds_read_b128 v[6:9], v150 offset:224
	s_waitcnt lgkmcnt(1)
	v_add_f32_e32 v2, v10, v2
	v_or_b32_e32 v10, s5, v1
	v_mul_f32_e32 v2, v159, v2
	v_lshlrev_b32_e32 v130, 11, v10
	v_cvt_pk_bf16_f32 v2, v2, s0
	v_lshl_add_u64 v[22:23], v[84:85], 0, v[130:131]
	global_store_short v[22:23], v2, off sc1
	v_add_f32_e32 v2, v11, v3
	v_mul_f32_e32 v2, v160, v2
	v_readlane_b32 s5, v252, 55
	v_cvt_pk_bf16_f32 v10, v2, s0
	s_nop 0
	v_or_b32_e32 v2, s5, v1
	v_lshlrev_b32_e32 v130, 11, v2
	v_lshl_add_u64 v[2:3], v[84:85], 0, v[130:131]
	global_store_short v[2:3], v10, off sc1
	v_add_f32_e32 v2, v12, v4
	v_mul_f32_e32 v2, v161, v2
	v_readlane_b32 s5, v252, 56
	v_cvt_pk_bf16_f32 v4, v2, s0
	s_nop 0
	v_or_b32_e32 v2, s5, v1
	v_lshlrev_b32_e32 v130, 11, v2
	v_lshl_add_u64 v[2:3], v[84:85], 0, v[130:131]
	global_store_short v[2:3], v4, off sc1
	v_add_f32_e32 v2, v13, v5
	v_mul_f32_e32 v2, v162, v2
	v_readlane_b32 s5, v252, 57
	v_cvt_pk_bf16_f32 v4, v2, s0
	s_nop 0
	v_or_b32_e32 v2, s5, v1
	v_lshlrev_b32_e32 v130, 11, v2
	v_lshl_add_u64 v[2:3], v[84:85], 0, v[130:131]
	global_store_short v[2:3], v4, off sc1
	s_waitcnt lgkmcnt(0)
	v_add_f32_e32 v2, v14, v6
	v_mul_f32_e32 v2, v163, v2
	v_readlane_b32 s5, v252, 58
	v_cvt_pk_bf16_f32 v4, v2, s0
	s_nop 0
	v_or_b32_e32 v2, s5, v1
	v_lshlrev_b32_e32 v130, 11, v2
	v_lshl_add_u64 v[2:3], v[84:85], 0, v[130:131]
	global_store_short v[2:3], v4, off sc1
	v_add_f32_e32 v2, v15, v7
	v_mul_f32_e32 v2, v164, v2
	v_readlane_b32 s5, v252, 59
	v_cvt_pk_bf16_f32 v4, v2, s0
	s_nop 0
	v_or_b32_e32 v2, s5, v1
	v_lshlrev_b32_e32 v130, 11, v2
	v_lshl_add_u64 v[2:3], v[84:85], 0, v[130:131]
	global_store_short v[2:3], v4, off sc1
	v_add_f32_e32 v2, v16, v8
	v_mul_f32_e32 v2, v165, v2
	v_readlane_b32 s5, v252, 60
	v_cvt_pk_bf16_f32 v4, v2, s0
	s_nop 0
	v_or_b32_e32 v2, s5, v1
	v_lshlrev_b32_e32 v130, 11, v2
	v_lshl_add_u64 v[2:3], v[84:85], 0, v[130:131]
	global_store_short v[2:3], v4, off sc1
	v_add_f32_e32 v2, v17, v9
	v_mul_f32_e32 v2, v166, v2
	v_readlane_b32 s5, v252, 61
	v_cvt_pk_bf16_f32 v4, v2, s0
	s_nop 0
	v_or_b32_e32 v2, s5, v1
	v_lshlrev_b32_e32 v130, 11, v2
	v_lshl_add_u64 v[2:3], v[84:85], 0, v[130:131]
	global_store_short v[2:3], v4, off sc1
	global_load_ushort v4, v[116:117], off
	global_load_ushort v3, v[118:119], off offset:2048
	global_load_ushort v2, v[120:121], off
	global_load_dwordx4 v[24:27], v[88:89], off offset:3072
	v_readlane_b32 s5, v252, 62
	s_waitcnt vmcnt(3)
	v_lshlrev_b32_e32 v4, 16, v4
	v_fma_f32 v5, |v4|, s92, 1.0
	v_rcp_f32_e32 v5, v5
	v_mul_f32_e32 v7, v4, v4
	v_mul_f32_e32 v7, 0xbf38aa3b, v7
	v_exp_f32_e32 v7, v7
	v_fmamk_f32 v6, v5, 0x3f07dc22, v236
	v_fmaak_f32 v6, v5, v6, 0x3f35f0e3
	v_fmaak_f32 v6, v5, v6, 0xbe11a98e
	v_fmaak_f32 v6, v5, v6, 0x3e027906
	v_mul_f32_e32 v5, v5, v6
	v_mul_f32_e32 v5, v7, v5
	s_waitcnt vmcnt(2)
	v_lshlrev_b32_e32 v3, 16, v3
	v_mul_f32_e32 v6, v5, v4
	v_fma_f32 v5, -v5, v4, v4
	v_cmp_gt_f32_e32 vcc, 0, v4
	v_fma_f32 v4, |v3|, s92, 1.0
	v_rcp_f32_e32 v4, v4
	v_cndmask_b32_e32 v28, v5, v6, vcc
	v_mul_f32_e32 v6, v3, v3
	v_mul_f32_e32 v6, 0xbf38aa3b, v6
	v_fmamk_f32 v5, v4, 0x3f07dc22, v236
	v_fmaak_f32 v5, v4, v5, 0x3f35f0e3
	v_exp_f32_e32 v6, v6
	v_fmaak_f32 v5, v4, v5, 0xbe11a98e
	v_fmaak_f32 v5, v4, v5, 0x3e027906
	v_mul_f32_e32 v4, v4, v5
	v_mul_f32_e32 v4, v6, v4
	s_waitcnt vmcnt(1)
	v_lshlrev_b32_e32 v2, 16, v2
	v_mul_f32_e32 v5, v4, v3
	v_fma_f32 v4, -v4, v3, v3
	v_cmp_gt_f32_e32 vcc, 0, v3
	v_fma_f32 v3, |v2|, s92, 1.0
	v_rcp_f32_e32 v3, v3
	v_cndmask_b32_e32 v29, v4, v5, vcc
	v_mul_f32_e32 v5, v2, v2
	v_mul_f32_e32 v5, 0xbf38aa3b, v5
	v_fmamk_f32 v4, v3, 0x3f07dc22, v236
	v_fmaak_f32 v4, v3, v4, 0x3f35f0e3
	v_exp_f32_e32 v5, v5
	v_fmaak_f32 v4, v3, v4, 0xbe11a98e
	v_fmaak_f32 v4, v3, v4, 0x3e027906
	v_mul_f32_e32 v3, v3, v4
	v_mul_f32_e32 v3, v5, v3
	v_mul_f32_e32 v4, v3, v2
	v_fma_f32 v3, -v3, v2, v2
	v_cmp_gt_f32_e32 vcc, 0, v2
	s_nop 1
	v_cndmask_b32_e32 v82, v3, v4, vcc
	global_load_ushort v2, v[100:101], off offset:2048
	global_load_ushort v3, v[102:103], off
	global_load_ushort v4, v[104:105], off offset:2048
	global_load_ushort v5, v[106:107], off
	global_load_ushort v6, v[108:109], off offset:2048
	global_load_ushort v7, v[110:111], off
	global_load_ushort v8, v[112:113], off offset:2048
	global_load_ushort v9, v[114:115], off
	s_waitcnt vmcnt(7)
	v_lshlrev_b32_e32 v2, 16, v2
	v_fma_f32 v10, |v2|, s92, 1.0
	v_rcp_f32_e32 v10, v10
	v_mul_f32_e32 v12, v2, v2
	v_mul_f32_e32 v12, 0xbf38aa3b, v12
	v_exp_f32_e32 v12, v12
	v_fmamk_f32 v11, v10, 0x3f07dc22, v236
	v_fmaak_f32 v11, v10, v11, 0x3f35f0e3
	v_fmaak_f32 v11, v10, v11, 0xbe11a98e
	v_fmaak_f32 v11, v10, v11, 0x3e027906
	v_mul_f32_e32 v10, v10, v11
	v_mul_f32_e32 v10, v12, v10
	v_mul_f32_e32 v11, v10, v2
	v_fma_f32 v10, -v10, v2, v2
	v_cmp_gt_f32_e32 vcc, 0, v2
	s_waitcnt vmcnt(6)
	v_lshlrev_b32_e32 v2, 16, v3
	v_fma_f32 v3, |v2|, s92, 1.0
	v_rcp_f32_e32 v3, v3
	v_cndmask_b32_e32 v83, v10, v11, vcc
	v_mul_f32_e32 v11, v2, v2
	v_mul_f32_e32 v11, 0xbf38aa3b, v11
	v_fmamk_f32 v10, v3, 0x3f07dc22, v236
	v_fmaak_f32 v10, v3, v10, 0x3f35f0e3
	v_exp_f32_e32 v11, v11
	v_fmaak_f32 v10, v3, v10, 0xbe11a98e
	v_fmaak_f32 v10, v3, v10, 0x3e027906
	v_mul_f32_e32 v3, v3, v10
	v_mul_f32_e32 v3, v11, v3
	v_mul_f32_e32 v10, v3, v2
	v_fma_f32 v3, -v3, v2, v2
	v_cmp_gt_f32_e32 vcc, 0, v2
	s_waitcnt vmcnt(5)
	v_lshlrev_b32_e32 v2, 16, v4
	v_cndmask_b32_e32 v100, v3, v10, vcc
	v_fma_f32 v3, |v2|, s92, 1.0
	v_rcp_f32_e32 v3, v3
	v_mul_f32_e32 v10, v2, v2
	v_mul_f32_e32 v10, 0xbf38aa3b, v10
	v_exp_f32_e32 v10, v10
	v_fmamk_f32 v4, v3, 0x3f07dc22, v236
	v_fmaak_f32 v4, v3, v4, 0x3f35f0e3
	v_fmaak_f32 v4, v3, v4, 0xbe11a98e
	v_fmaak_f32 v4, v3, v4, 0x3e027906
	v_mul_f32_e32 v3, v3, v4
	v_mul_f32_e32 v3, v10, v3
	v_mul_f32_e32 v4, v3, v2
	v_fma_f32 v3, -v3, v2, v2
	v_cmp_gt_f32_e32 vcc, 0, v2
	s_waitcnt vmcnt(4)
	v_lshlrev_b32_e32 v2, 16, v5
	v_mul_f32_e32 v5, v2, v2
	v_cndmask_b32_e32 v101, v3, v4, vcc
	v_fma_f32 v3, |v2|, s92, 1.0
	v_rcp_f32_e32 v3, v3
	v_mul_f32_e32 v5, 0xbf38aa3b, v5
	v_exp_f32_e32 v5, v5
	v_cmp_gt_f32_e32 vcc, 0, v2
	v_fmamk_f32 v4, v3, 0x3f07dc22, v236
	v_fmaak_f32 v4, v3, v4, 0x3f35f0e3
	v_fmaak_f32 v4, v3, v4, 0xbe11a98e
	v_fmaak_f32 v4, v3, v4, 0x3e027906
	v_mul_f32_e32 v3, v3, v4
	v_mul_f32_e32 v3, v5, v3
	v_mul_f32_e32 v4, v3, v2
	v_fma_f32 v3, -v3, v2, v2
	s_waitcnt vmcnt(3)
	v_lshlrev_b32_e32 v2, 16, v6
	v_cndmask_b32_e32 v102, v3, v4, vcc
	v_fma_f32 v3, |v2|, s92, 1.0
	v_rcp_f32_e32 v3, v3
	v_mul_f32_e32 v5, v2, v2
	v_mul_f32_e32 v5, 0xbf38aa3b, v5
	v_exp_f32_e32 v5, v5
	v_fmamk_f32 v4, v3, 0x3f07dc22, v236
	v_fmaak_f32 v4, v3, v4, 0x3f35f0e3
	v_fmaak_f32 v4, v3, v4, 0xbe11a98e
	v_fmaak_f32 v4, v3, v4, 0x3e027906
	v_mul_f32_e32 v3, v3, v4
	v_mul_f32_e32 v3, v5, v3
	v_mul_f32_e32 v4, v3, v2
	v_fma_f32 v3, -v3, v2, v2
	v_cmp_gt_f32_e32 vcc, 0, v2
	s_waitcnt vmcnt(2)
	v_lshlrev_b32_e32 v2, 16, v7
	v_mul_f32_e32 v5, v2, v2
	v_cndmask_b32_e32 v103, v3, v4, vcc
	v_fma_f32 v3, |v2|, s92, 1.0
	v_rcp_f32_e32 v3, v3
	v_mul_f32_e32 v5, 0xbf38aa3b, v5
	v_exp_f32_e32 v5, v5
	v_cmp_gt_f32_e32 vcc, 0, v2
	v_fmamk_f32 v4, v3, 0x3f07dc22, v236
	v_fmaak_f32 v4, v3, v4, 0x3f35f0e3
	v_fmaak_f32 v4, v3, v4, 0xbe11a98e
	v_fmaak_f32 v4, v3, v4, 0x3e027906
	v_mul_f32_e32 v3, v3, v4
	v_mul_f32_e32 v3, v5, v3
	v_mul_f32_e32 v4, v3, v2
	v_fma_f32 v3, -v3, v2, v2
	s_waitcnt vmcnt(1)
	v_lshlrev_b32_e32 v2, 16, v8
	v_cndmask_b32_e32 v104, v3, v4, vcc
	v_fma_f32 v3, |v2|, s92, 1.0
	v_rcp_f32_e32 v3, v3
	v_mul_f32_e32 v5, v2, v2
	v_mul_f32_e32 v5, 0xbf38aa3b, v5
	v_exp_f32_e32 v5, v5
	v_fmamk_f32 v4, v3, 0x3f07dc22, v236
	v_fmaak_f32 v4, v3, v4, 0x3f35f0e3
	v_fmaak_f32 v4, v3, v4, 0xbe11a98e
	v_fmaak_f32 v4, v3, v4, 0x3e027906
	v_mul_f32_e32 v3, v3, v4
	v_mul_f32_e32 v3, v5, v3
	v_mul_f32_e32 v4, v3, v2
	v_fma_f32 v3, -v3, v2, v2
	v_cmp_gt_f32_e32 vcc, 0, v2
	s_waitcnt vmcnt(0)
	v_lshlrev_b32_e32 v2, 16, v9
	v_mul_f32_e32 v5, v2, v2
	v_cndmask_b32_e32 v105, v3, v4, vcc
	v_fma_f32 v3, |v2|, s92, 1.0
	v_rcp_f32_e32 v3, v3
	v_mul_f32_e32 v5, 0xbf38aa3b, v5
	v_exp_f32_e32 v5, v5
	v_cmp_gt_f32_e32 vcc, 0, v2
	v_fmamk_f32 v4, v3, 0x3f07dc22, v236
	v_fmaak_f32 v4, v3, v4, 0x3f35f0e3
	v_fmaak_f32 v4, v3, v4, 0xbe11a98e
	v_fmaak_f32 v4, v3, v4, 0x3e027906
	v_mul_f32_e32 v3, v3, v4
	v_mul_f32_e32 v3, v5, v3
	v_mul_f32_e32 v4, v3, v2
	v_fma_f32 v3, -v3, v2, v2
	v_cndmask_b32_e32 v106, v3, v4, vcc
	global_load_ushort v2, v[90:91], off offset:2048
	global_load_ushort v3, v[92:93], off
	global_load_ushort v4, v[94:95], off offset:2048
	global_load_ushort v5, v[96:97], off
	global_load_ushort v6, v[98:99], off offset:2048
	s_waitcnt vmcnt(4)
	v_lshlrev_b32_e32 v2, 16, v2
	v_fma_f32 v7, |v2|, s92, 1.0
	v_rcp_f32_e32 v7, v7
	v_mul_f32_e32 v9, v2, v2
	v_mul_f32_e32 v9, 0xbf38aa3b, v9
	v_exp_f32_e32 v9, v9
	v_fmamk_f32 v8, v7, 0x3f07dc22, v236
	v_fmaak_f32 v8, v7, v8, 0x3f35f0e3
	v_fmaak_f32 v8, v7, v8, 0xbe11a98e
	v_fmaak_f32 v8, v7, v8, 0x3e027906
	v_mul_f32_e32 v7, v7, v8
	v_mul_f32_e32 v7, v9, v7
	v_mul_f32_e32 v8, v7, v2
	v_fma_f32 v7, -v7, v2, v2
	v_cmp_gt_f32_e32 vcc, 0, v2
	s_waitcnt vmcnt(3)
	v_lshlrev_b32_e32 v2, 16, v3
	v_fma_f32 v3, |v2|, s92, 1.0
	v_rcp_f32_e32 v3, v3
	v_cndmask_b32_e32 v107, v7, v8, vcc
	v_mul_f32_e32 v8, v2, v2
	v_mul_f32_e32 v8, 0xbf38aa3b, v8
	v_fmamk_f32 v7, v3, 0x3f07dc22, v236
	v_fmaak_f32 v7, v3, v7, 0x3f35f0e3
	v_exp_f32_e32 v8, v8
	v_fmaak_f32 v7, v3, v7, 0xbe11a98e
	v_fmaak_f32 v7, v3, v7, 0x3e027906
	v_mul_f32_e32 v3, v3, v7
	v_mul_f32_e32 v3, v8, v3
	v_mul_f32_e32 v7, v3, v2
	v_fma_f32 v3, -v3, v2, v2
	v_cmp_gt_f32_e32 vcc, 0, v2
	s_waitcnt vmcnt(2)
	v_lshlrev_b32_e32 v2, 16, v4
	v_mfma_f32_32x32x16_bf16 v[8:23], v[18:21], v[62:65], 0
	v_cndmask_b32_e32 v108, v3, v7, vcc
	v_fma_f32 v3, |v2|, s92, 1.0
	v_rcp_f32_e32 v3, v3
	v_mul_f32_e32 v7, v2, v2
	v_mul_f32_e32 v7, 0xbf38aa3b, v7
	v_exp_f32_e32 v7, v7
	v_fmamk_f32 v4, v3, 0x3f07dc22, v236
	v_fmaak_f32 v4, v3, v4, 0x3f35f0e3
	v_fmaak_f32 v4, v3, v4, 0xbe11a98e
	v_fmaak_f32 v4, v3, v4, 0x3e027906
	v_mul_f32_e32 v3, v3, v4
	v_mul_f32_e32 v3, v7, v3
	v_mul_f32_e32 v4, v3, v2
	v_fma_f32 v3, -v3, v2, v2
	v_cmp_gt_f32_e32 vcc, 0, v2
	s_waitcnt vmcnt(1)
	v_lshlrev_b32_e32 v2, 16, v5
	v_mul_f32_e32 v5, v2, v2
	v_cndmask_b32_e32 v109, v3, v4, vcc
	v_fma_f32 v3, |v2|, s92, 1.0
	v_rcp_f32_e32 v3, v3
	v_mul_f32_e32 v5, 0xbf38aa3b, v5
	v_exp_f32_e32 v5, v5
	v_cmp_gt_f32_e32 vcc, 0, v2
	v_fmamk_f32 v4, v3, 0x3f07dc22, v236
	v_fmaak_f32 v4, v3, v4, 0x3f35f0e3
	v_fmaak_f32 v4, v3, v4, 0xbe11a98e
	v_fmaak_f32 v4, v3, v4, 0x3e027906
	v_mul_f32_e32 v3, v3, v4
	v_mul_f32_e32 v3, v5, v3
	v_mul_f32_e32 v4, v3, v2
	v_fma_f32 v3, -v3, v2, v2
	s_waitcnt vmcnt(0)
	v_lshlrev_b32_e32 v2, 16, v6
	v_cndmask_b32_e32 v110, v3, v4, vcc
	v_fma_f32 v3, |v2|, s92, 1.0
	v_rcp_f32_e32 v3, v3
	v_mul_f32_e32 v5, v2, v2
	v_mul_f32_e32 v5, 0xbf38aa3b, v5
	v_mfma_f32_32x32x16_bf16 v[8:23], v[78:81], v[58:61], v[8:23]
	v_fmamk_f32 v4, v3, 0x3f07dc22, v236
	v_fmaak_f32 v4, v3, v4, 0x3f35f0e3
	v_exp_f32_e32 v5, v5
	v_fmaak_f32 v4, v3, v4, 0xbe11a98e
	v_fmaak_f32 v4, v3, v4, 0x3e027906
	v_mul_f32_e32 v3, v3, v4
	v_mul_f32_e32 v3, v5, v3
	v_mul_f32_e32 v4, v3, v2
	v_fma_f32 v3, -v3, v2, v2
	v_cmp_gt_f32_e32 vcc, 0, v2
	v_mfma_f32_32x32x16_bf16 v[8:23], v[74:77], v[54:57], v[8:23]
	s_nop 0
	v_cndmask_b32_e32 v111, v3, v4, vcc
	global_load_dwordx4 v[2:5], v[86:87], off offset:-4096
	v_mfma_f32_32x32x16_bf16 v[8:23], v[70:73], v[50:53], v[8:23]
	v_mfma_f32_32x32x16_bf16 v[8:23], v[66:69], v[46:49], v[8:23]
	global_load_dwordx4 v[66:69], v[88:89], off offset:1024
	global_load_dwordx4 v[70:73], v[88:89], off offset:2048
	global_load_dwordx4 v[74:77], v[86:87], off
	global_load_dwordx4 v[78:81], v[86:87], off offset:1024
	s_nop 0
	global_load_dwordx4 v[88:91], v[86:87], off offset:2048
	global_load_dwordx4 v[92:95], v[86:87], off offset:3072
	ds_read_b128 v[96:99], v150 offset:256
	v_mfma_f32_32x32x16_bf16 v[8:23], v[30:33], v[42:45], v[8:23]
	ds_read_b128 v[30:33], v150 offset:288
	s_waitcnt lgkmcnt(1)
	s_nop 9
	v_add_f32_e32 v6, v8, v96
	v_mul_f32_e32 v6, v134, v6
	v_cvt_pk_bf16_f32 v8, v6, s0
	v_or_b32_e32 v6, s5, v1
	v_lshlrev_b32_e32 v130, 11, v6
	v_lshl_add_u64 v[6:7], v[84:85], 0, v[130:131]
	global_store_short v[6:7], v8, off sc1
	v_add_f32_e32 v6, v9, v97
	v_mul_f32_e32 v6, v135, v6
	v_readlane_b32 s5, v252, 63
	v_cvt_pk_bf16_f32 v8, v6, s0
	s_nop 0
	v_or_b32_e32 v6, s5, v1
	v_lshlrev_b32_e32 v130, 11, v6
	v_lshl_add_u64 v[6:7], v[84:85], 0, v[130:131]
	global_store_short v[6:7], v8, off sc1
	v_add_f32_e32 v6, v10, v98
	v_mul_f32_e32 v6, v136, v6
	v_readlane_b32 s5, v253, 0
	v_cvt_pk_bf16_f32 v8, v6, s0
	s_nop 0
	v_or_b32_e32 v6, s5, v1
	v_lshlrev_b32_e32 v130, 11, v6
	v_lshl_add_u64 v[6:7], v[84:85], 0, v[130:131]
	global_store_short v[6:7], v8, off sc1
	v_add_f32_e32 v6, v11, v99
	v_mul_f32_e32 v6, v137, v6
	v_readlane_b32 s5, v253, 1
	v_cvt_pk_bf16_f32 v8, v6, s0
	ds_read_b128 v[96:99], v150 offset:352
	v_or_b32_e32 v6, s5, v1
	v_lshlrev_b32_e32 v130, 11, v6
	v_lshl_add_u64 v[6:7], v[84:85], 0, v[130:131]
	global_store_short v[6:7], v8, off sc1
	s_waitcnt lgkmcnt(1)
	v_add_f32_e32 v6, v12, v30
	v_mul_f32_e32 v6, v138, v6
	v_readlane_b32 s5, v253, 2
	v_cvt_pk_bf16_f32 v8, v6, s0
	s_nop 0
	v_or_b32_e32 v6, s5, v1
	v_lshlrev_b32_e32 v130, 11, v6
	v_lshl_add_u64 v[6:7], v[84:85], 0, v[130:131]
	global_store_short v[6:7], v8, off sc1
	v_add_f32_e32 v6, v13, v31
	v_mul_f32_e32 v6, v139, v6
	v_readlane_b32 s5, v253, 3
	v_cvt_pk_bf16_f32 v8, v6, s0
	s_nop 0
	v_or_b32_e32 v6, s5, v1
	v_lshlrev_b32_e32 v130, 11, v6
	v_lshl_add_u64 v[6:7], v[84:85], 0, v[130:131]
	global_store_short v[6:7], v8, off sc1
	v_add_f32_e32 v6, v14, v32
	v_mul_f32_e32 v6, v140, v6
	v_readlane_b32 s5, v253, 4
	v_cvt_pk_bf16_f32 v8, v6, s0
	s_nop 0
	v_or_b32_e32 v6, s5, v1
	v_lshlrev_b32_e32 v130, 11, v6
	v_lshl_add_u64 v[6:7], v[84:85], 0, v[130:131]
	global_store_short v[6:7], v8, off sc1
	v_add_f32_e32 v6, v15, v33
	ds_read_b128 v[30:33], v150 offset:320
	v_mul_f32_e32 v6, v141, v6
	v_readlane_b32 s5, v253, 5
	v_cvt_pk_bf16_f32 v8, v6, s0
	s_waitcnt lgkmcnt(0)
	v_add_f32_e32 v18, v18, v32
	v_or_b32_e32 v6, s5, v1
	v_lshlrev_b32_e32 v130, 11, v6
	v_lshl_add_u64 v[6:7], v[84:85], 0, v[130:131]
	global_store_short v[6:7], v8, off sc1
	v_add_f32_e32 v6, v16, v30
	v_mul_f32_e32 v6, v122, v6
	v_readlane_b32 s5, v253, 6
	v_cvt_pk_bf16_f32 v8, v6, s0
	v_mul_f32_e32 v18, v124, v18
	v_or_b32_e32 v6, s5, v1
	v_lshlrev_b32_e32 v130, 11, v6
	v_lshl_add_u64 v[6:7], v[84:85], 0, v[130:131]
	global_store_short v[6:7], v8, off sc1
	v_add_f32_e32 v6, v17, v31
	v_mul_f32_e32 v30, v123, v6
	s_waitcnt vmcnt(15)
	v_mfma_f32_32x32x16_bf16 v[2:17], v[2:5], v[62:65], 0
	v_readlane_b32 s5, v253, 7
	v_cvt_pk_bf16_f32 v62, v30, s0
	v_cvt_pk_bf16_f32 v18, v18, s0
	v_or_b32_e32 v30, s5, v1
	v_lshlrev_b32_e32 v130, 11, v30
	v_lshl_add_u64 v[30:31], v[84:85], 0, v[130:131]
	v_readlane_b32 s5, v253, 8
	s_waitcnt vmcnt(14)
	v_mfma_f32_32x32x16_bf16 v[2:17], v[66:69], v[58:61], v[2:17]
	global_store_short v[30:31], v62, off sc1
	v_or_b32_e32 v30, s5, v1
	v_lshlrev_b32_e32 v130, 11, v30
	v_lshl_add_u64 v[30:31], v[84:85], 0, v[130:131]
	global_store_short v[30:31], v18, off sc1
	v_add_f32_e32 v18, v19, v33
	v_mul_f32_e32 v18, v125, v18
	s_waitcnt vmcnt(15)
	v_mfma_f32_32x32x16_bf16 v[2:17], v[70:73], v[54:57], v[2:17]
	v_readlane_b32 s5, v253, 9
	v_cvt_pk_bf16_f32 v30, v18, s0
	s_nop 0
	v_or_b32_e32 v18, s5, v1
	v_lshlrev_b32_e32 v130, 11, v18
	v_lshl_add_u64 v[18:19], v[84:85], 0, v[130:131]
	global_store_short v[18:19], v30, off sc1
	v_mfma_f32_32x32x16_bf16 v[2:17], v[24:27], v[50:53], v[2:17]
	v_add_f32_e32 v18, v20, v96
	v_mul_f32_e32 v18, v126, v18
	v_readlane_b32 s5, v253, 10
	v_cvt_pk_bf16_f32 v20, v18, s0
	s_nop 0
	v_or_b32_e32 v18, s5, v1
	v_lshlrev_b32_e32 v130, 11, v18
	s_waitcnt vmcnt(15)
	v_mfma_f32_32x32x16_bf16 v[2:17], v[74:77], v[46:49], v[2:17]
	v_lshl_add_u64 v[18:19], v[84:85], 0, v[130:131]
	global_store_short v[18:19], v20, off sc1
	v_add_f32_e32 v18, v21, v97
	v_mul_f32_e32 v18, v127, v18
	v_readlane_b32 s5, v253, 11
	v_cvt_pk_bf16_f32 v20, v18, s0
	s_waitcnt vmcnt(15)
	v_mfma_f32_32x32x16_bf16 v[2:17], v[78:81], v[42:45], v[2:17]
	v_or_b32_e32 v18, s5, v1
	v_lshlrev_b32_e32 v130, 11, v18
	v_lshl_add_u64 v[18:19], v[84:85], 0, v[130:131]
	global_store_short v[18:19], v20, off sc1
	v_add_f32_e32 v18, v22, v98
	v_mul_f32_e32 v18, v128, v18
	v_readlane_b32 s5, v253, 12
	s_waitcnt vmcnt(15)
	v_mfma_f32_32x32x16_bf16 v[2:17], v[88:91], v[38:41], v[2:17]
	v_cvt_pk_bf16_f32 v20, v18, s0
	v_or_b32_e32 v18, s5, v1
	v_lshlrev_b32_e32 v130, 11, v18
	v_lshl_add_u64 v[18:19], v[84:85], 0, v[130:131]
	global_store_short v[18:19], v20, off sc1
	v_add_f32_e32 v18, v23, v99
	v_mul_f32_e32 v18, v129, v18
	v_readlane_b32 s5, v253, 13
	v_cvt_pk_bf16_f32 v20, v18, s0
	s_waitcnt vmcnt(15)
	v_mfma_f32_32x32x16_bf16 v[2:17], v[92:95], v[34:37], v[2:17]
	v_or_b32_e32 v18, s5, v1
	v_lshlrev_b32_e32 v130, 11, v18
	v_lshl_add_u64 v[18:19], v[84:85], 0, v[130:131]
	global_store_short v[18:19], v20, off sc1
	ds_read_b128 v[18:21], v150 offset:384
	ds_read_b128 v[22:25], v150 offset:416
	v_readlane_b32 s5, v253, 14
	s_waitcnt lgkmcnt(1)
	s_nop 3
	v_add_f32_e32 v2, v2, v18
	v_or_b32_e32 v18, s5, v1
	v_mul_f32_e32 v2, v28, v2
	v_lshlrev_b32_e32 v130, 11, v18
	v_cvt_pk_bf16_f32 v2, v2, s0
	v_lshl_add_u64 v[26:27], v[84:85], 0, v[130:131]
	global_store_short v[26:27], v2, off sc1
	v_add_f32_e32 v2, v3, v19
	v_mul_f32_e32 v2, v29, v2
	v_readlane_b32 s5, v253, 15
	v_cvt_pk_bf16_f32 v18, v2, s0
	s_nop 0
	v_or_b32_e32 v2, s5, v1
	v_lshlrev_b32_e32 v130, 11, v2
	v_lshl_add_u64 v[2:3], v[84:85], 0, v[130:131]
	global_store_short v[2:3], v18, off sc1
	v_add_f32_e32 v2, v4, v20
	v_mul_f32_e32 v2, v82, v2
	v_readlane_b32 s5, v253, 16
	v_cvt_pk_bf16_f32 v4, v2, s0
	s_nop 0
	v_or_b32_e32 v2, s5, v1
	v_lshlrev_b32_e32 v130, 11, v2
	v_lshl_add_u64 v[2:3], v[84:85], 0, v[130:131]
	global_store_short v[2:3], v4, off sc1
	v_add_f32_e32 v2, v5, v21
	v_mul_f32_e32 v2, v83, v2
	v_readlane_b32 s5, v253, 17
	v_cvt_pk_bf16_f32 v4, v2, s0
	s_nop 0
	v_or_b32_e32 v2, s5, v1
	v_lshlrev_b32_e32 v130, 11, v2
	v_lshl_add_u64 v[2:3], v[84:85], 0, v[130:131]
	global_store_short v[2:3], v4, off sc1
	s_waitcnt lgkmcnt(0)
	v_add_f32_e32 v2, v6, v22
	v_mul_f32_e32 v2, v100, v2
	v_readlane_b32 s5, v253, 18
	v_cvt_pk_bf16_f32 v4, v2, s0
	s_nop 0
	v_or_b32_e32 v2, s5, v1
	v_lshlrev_b32_e32 v130, 11, v2
	v_lshl_add_u64 v[2:3], v[84:85], 0, v[130:131]
	global_store_short v[2:3], v4, off sc1
	v_add_f32_e32 v2, v7, v23
	v_mul_f32_e32 v2, v101, v2
	v_readlane_b32 s5, v253, 19
	v_cvt_pk_bf16_f32 v4, v2, s0
	s_nop 0
	v_or_b32_e32 v2, s5, v1
	v_lshlrev_b32_e32 v130, 11, v2
	v_lshl_add_u64 v[2:3], v[84:85], 0, v[130:131]
	global_store_short v[2:3], v4, off sc1
	v_add_f32_e32 v2, v8, v24
	v_mul_f32_e32 v2, v102, v2
	v_readlane_b32 s5, v253, 20
	v_cvt_pk_bf16_f32 v4, v2, s0
	s_nop 0
	v_or_b32_e32 v2, s5, v1
	v_lshlrev_b32_e32 v130, 11, v2
	v_lshl_add_u64 v[2:3], v[84:85], 0, v[130:131]
	global_store_short v[2:3], v4, off sc1
	v_add_f32_e32 v2, v9, v25
	v_mul_f32_e32 v2, v103, v2
	v_cvt_pk_bf16_f32 v8, v2, s0
	ds_read_b128 v[2:5], v150 offset:448
	v_readlane_b32 s5, v253, 21
	s_nop 1
	v_or_b32_e32 v6, s5, v1
	v_lshlrev_b32_e32 v130, 11, v6
	v_lshl_add_u64 v[6:7], v[84:85], 0, v[130:131]
	v_readlane_b32 s5, v253, 22
	global_store_short v[6:7], v8, off sc1
	ds_read_b128 v[6:9], v150 offset:480
	s_waitcnt lgkmcnt(1)
	v_add_f32_e32 v2, v10, v2
	v_or_b32_e32 v10, s5, v1
	v_mul_f32_e32 v2, v104, v2
	v_lshlrev_b32_e32 v130, 11, v10
	v_cvt_pk_bf16_f32 v2, v2, s0
	v_lshl_add_u64 v[18:19], v[84:85], 0, v[130:131]
	global_store_short v[18:19], v2, off sc1
	v_add_f32_e32 v2, v11, v3
	v_mul_f32_e32 v2, v105, v2
	v_readlane_b32 s5, v253, 23
	v_cvt_pk_bf16_f32 v10, v2, s0
	s_nop 0
	v_or_b32_e32 v2, s5, v1
	v_lshlrev_b32_e32 v130, 11, v2
	v_lshl_add_u64 v[2:3], v[84:85], 0, v[130:131]
	global_store_short v[2:3], v10, off sc1
	v_add_f32_e32 v2, v12, v4
	v_mul_f32_e32 v2, v106, v2
	v_readlane_b32 s5, v253, 24
	v_cvt_pk_bf16_f32 v4, v2, s0
	s_nop 0
	v_or_b32_e32 v2, s5, v1
	v_lshlrev_b32_e32 v130, 11, v2
	v_lshl_add_u64 v[2:3], v[84:85], 0, v[130:131]
	global_store_short v[2:3], v4, off sc1
	v_add_f32_e32 v2, v13, v5
	v_mul_f32_e32 v2, v107, v2
	v_readlane_b32 s5, v253, 25
	v_cvt_pk_bf16_f32 v4, v2, s0
	s_nop 0
	v_or_b32_e32 v2, s5, v1
	v_lshlrev_b32_e32 v130, 11, v2
	v_lshl_add_u64 v[2:3], v[84:85], 0, v[130:131]
	global_store_short v[2:3], v4, off sc1
	s_waitcnt lgkmcnt(0)
	v_add_f32_e32 v2, v14, v6
	v_mul_f32_e32 v2, v108, v2
	v_readlane_b32 s5, v253, 26
	v_cvt_pk_bf16_f32 v4, v2, s0
	s_nop 0
	v_or_b32_e32 v2, s5, v1
	v_lshlrev_b32_e32 v130, 11, v2
	v_lshl_add_u64 v[2:3], v[84:85], 0, v[130:131]
	global_store_short v[2:3], v4, off sc1
	v_add_f32_e32 v2, v15, v7
	v_mul_f32_e32 v2, v109, v2
	v_readlane_b32 s5, v253, 27
	v_cvt_pk_bf16_f32 v4, v2, s0
	s_nop 0
	v_or_b32_e32 v2, s5, v1
	v_lshlrev_b32_e32 v130, 11, v2
	v_lshl_add_u64 v[2:3], v[84:85], 0, v[130:131]
	global_store_short v[2:3], v4, off sc1
	v_add_f32_e32 v2, v16, v8
	v_mul_f32_e32 v2, v110, v2
	v_readlane_b32 s5, v253, 28
	v_cvt_pk_bf16_f32 v4, v2, s0
	s_nop 0
	v_or_b32_e32 v2, s5, v1
	v_lshlrev_b32_e32 v130, 11, v2
	v_lshl_add_u64 v[2:3], v[84:85], 0, v[130:131]
	v_readlane_b32 s5, v253, 29
	global_store_short v[2:3], v4, off sc1
	v_add_f32_e32 v2, v17, v9
	v_or_b32_e32 v1, s5, v1
	v_mul_f32_e32 v2, v111, v2
	v_lshlrev_b32_e32 v130, 11, v1
	v_cvt_pk_bf16_f32 v4, v2, s0
	v_lshl_add_u64 v[2:3], v[84:85], 0, v[130:131]
	global_store_short v[2:3], v4, off sc1
	s_barrier

.LBB0_319:
	s_add_i32 s65, s6, 32
	s_add_i32 s6, s6, 64
	s_cmpk_lt_i32 s65, 0x1e0
	s_cselect_b32 s6, s6, s65
	s_lshl_b32 s6, s6, 6
	s_and_b32 s8, s6, 0xfc0
	s_sub_i32 s8, s8, 30
	s_add_i32 s9, s8, s63
	s_and_b32 s6, s6, 0xfffff000
	s_max_i32 s9, s9, 0
	s_add_i32 s66, s9, s6
	s_add_i32 s9, s8, s62
	s_max_i32 s9, s9, 0
	s_add_i32 s67, s9, s6
	s_add_i32 s9, s8, s61
	s_max_i32 s9, s9, 0
	s_add_i32 s68, s9, s6
	s_add_i32 s9, s8, s60
	s_max_i32 s9, s9, 0
	s_add_i32 s69, s9, s6
	s_add_i32 s9, s8, s59
	s_max_i32 s9, s9, 0
	s_add_i32 s72, s9, s6
	s_add_i32 s9, s8, s58
	s_max_i32 s9, s9, 0
	s_add_i32 s73, s9, s6
	s_add_i32 s9, s8, s41
	s_max_i32 s9, s9, 0
	s_add_i32 s84, s9, s6
	s_add_i32 s9, s8, s40
	s_max_i32 s9, s9, 0
	s_add_i32 s85, s9, s6
	s_add_i32 s9, s8, s34
	s_max_i32 s9, s9, 0
	s_add_i32 s88, s9, s6
	s_add_i32 s9, s8, s29
	s_max_i32 s9, s9, 0
	s_add_i32 s89, s9, s6
	s_add_i32 s9, s8, s28
	s_add_i32 s8, s8, s5
	s_max_i32 s9, s9, 0
	s_max_i32 s8, s8, 0
	s_add_i32 s94, s9, s6
	s_add_i32 s95, s8, s6
	s_lshl_b32 s6, s42, 7
	s_add_i32 s8, s64, s7
	s_and_b32 s6, s6, 0xffff8000
	s_sub_i32 s10, s8, 56
	s_add_i32 vcc_lo, s6, 0
	s_lshl_b32 s6, s7, 10
	s_ashr_i32 s11, s10, 31
	s_add_i32 s6, s6, 0
	s_lshl_b64 s[10:11], s[10:11], 11
	s_add_u32 s56, s76, s10
	s_addc_u32 s57, s77, s11
	s_sub_i32 s10, s8, 48
	s_ashr_i32 s11, s10, 31
	s_lshl_b64 s[10:11], s[10:11], 11
	s_add_u32 s54, s76, s10
	s_addc_u32 s55, s77, s11
	s_sub_i32 s10, s8, 40
	s_ashr_i32 s11, s10, 31
	s_lshl_b64 s[10:11], s[10:11], 11
	s_add_u32 s52, s76, s10
	s_addc_u32 s53, s77, s11
	s_sub_i32 s10, s8, 32
	s_ashr_i32 s11, s10, 31
	s_lshl_b64 s[10:11], s[10:11], 11
	s_add_u32 s50, s76, s10
	s_addc_u32 s51, s77, s11
	s_sub_i32 s10, s8, 24
	s_ashr_i32 s11, s10, 31
	s_lshl_b64 s[10:11], s[10:11], 11
	s_add_u32 s48, s76, s10
	s_addc_u32 s49, s77, s11
	s_add_i32 s10, s8, -16
	s_ashr_i32 s11, s10, 31
	s_lshl_b64 s[10:11], s[10:11], 11
	s_add_u32 s46, s76, s10
	s_addc_u32 s47, s77, s11
	s_add_i32 s10, s8, -8
	s_ashr_i32 s11, s10, 31
	s_lshl_b64 s[10:11], s[10:11], 11
	s_add_u32 s44, s76, s10
	s_addc_u32 s45, s77, s11
	s_ashr_i32 s9, s8, 31
	s_lshl_b64 s[8:9], s[8:9], 11
	s_add_u32 s42, s76, s8
	v_and_b32_e32 v12, 0xff, v10
	s_addc_u32 s43, s77, s9
	v_mad_i64_i32 v[10:11], s[8:9], s66, v238, v[102:103]
	s_waitcnt lgkmcnt(0)
	s_barrier
	global_load_dwordx2 v[152:153], v[10:11], off offset:1024
	global_load_dwordx2 v[154:155], v[10:11], off offset:1536
	v_mad_i64_i32 v[10:11], s[8:9], s67, v238, v[102:103]
	global_load_dwordx2 v[148:149], v[10:11], off offset:1024
	global_load_dwordx2 v[150:151], v[10:11], off offset:1536
	v_mad_i64_i32 v[10:11], s[8:9], s68, v238, v[102:103]
	global_load_dwordx2 v[144:145], v[10:11], off offset:1024
	global_load_dwordx2 v[146:147], v[10:11], off offset:1536
	v_mad_i64_i32 v[10:11], s[8:9], s69, v238, v[102:103]
	global_load_dwordx2 v[140:141], v[10:11], off offset:1024
	global_load_dwordx2 v[142:143], v[10:11], off offset:1536
	v_mad_i64_i32 v[10:11], s[8:9], s72, v238, v[102:103]
	global_load_dwordx2 v[136:137], v[10:11], off offset:1024
	global_load_dwordx2 v[138:139], v[10:11], off offset:1536
	v_mad_i64_i32 v[10:11], s[8:9], s73, v238, v[102:103]
	global_load_dwordx2 v[132:133], v[10:11], off offset:1024
	global_load_dwordx2 v[134:135], v[10:11], off offset:1536
	v_mad_i64_i32 v[10:11], s[8:9], s84, v238, v[102:103]
	global_load_dwordx2 v[126:127], v[10:11], off offset:1024
	global_load_dwordx2 v[128:129], v[10:11], off offset:1536
	v_mad_i64_i32 v[10:11], s[8:9], s85, v238, v[102:103]
	global_load_dwordx2 v[122:123], v[10:11], off offset:1024
	global_load_dwordx2 v[124:125], v[10:11], off offset:1536
	v_mad_i64_i32 v[10:11], s[8:9], s88, v238, v[102:103]
	global_load_dwordx2 v[118:119], v[10:11], off offset:1024
	global_load_dwordx2 v[120:121], v[10:11], off offset:1536
	v_mad_i64_i32 v[10:11], s[8:9], s89, v238, v[102:103]
	global_load_dwordx2 v[114:115], v[10:11], off offset:1024
	global_load_dwordx2 v[116:117], v[10:11], off offset:1536
	v_mad_i64_i32 v[10:11], s[8:9], s94, v238, v[102:103]
	global_load_dwordx2 v[110:111], v[10:11], off offset:1024
	global_load_dwordx2 v[112:113], v[10:11], off offset:1536
	v_mad_i64_i32 v[10:11], s[8:9], s95, v238, v[102:103]
	v_lshl_add_u32 v163, v12, 2, vcc_lo
	global_load_dwordx2 v[106:107], v[10:11], off offset:1024
	global_load_dwordx2 v[108:109], v[10:11], off offset:1536
	ds_read2st64_b32 v[26:27], v163 offset1:4
	ds_read2st64_b32 v[28:29], v163 offset0:8 offset1:12
	ds_read2st64_b32 v[30:31], v163 offset0:16 offset1:20
	ds_read2st64_b32 v[32:33], v163 offset0:24 offset1:28
	ds_read2st64_b32 v[160:161], v163 offset0:32 offset1:36
	ds_read2st64_b32 v[158:159], v163 offset0:40 offset1:44
	ds_read2st64_b32 v[156:157], v163 offset0:48 offset1:52
	ds_read2st64_b32 v[40:41], v163 offset0:56 offset1:60
	ds_read2st64_b32 v[38:39], v163 offset0:64 offset1:68
	ds_read2st64_b32 v[36:37], v163 offset0:72 offset1:76
	ds_read2st64_b32 v[34:35], v163 offset0:80 offset1:84
	ds_read2st64_b32 v[24:25], v163 offset0:88 offset1:92
	ds_read2st64_b32 v[22:23], v163 offset0:96 offset1:100
	ds_read2st64_b32 v[20:21], v163 offset0:104 offset1:108
	ds_read2st64_b32 v[18:19], v163 offset0:112 offset1:116
	ds_read2st64_b32 v[10:11], v163 offset0:120 offset1:124
	ds_read2st64_b32 v[12:13], v163 offset0:128 offset1:132
	ds_read2st64_b32 v[14:15], v163 offset0:136 offset1:140
	ds_read2st64_b32 v[16:17], v163 offset0:144 offset1:148
	s_waitcnt lgkmcnt(14)
	v_mul_f32_e32 v165, v42, v27
	s_waitcnt vmcnt(51) lgkmcnt(3)
	v_mul_f32_e32 v105, v101, v10
	s_waitcnt vmcnt(24)
	v_mov_b32_e32 v164, v104
	v_pk_fma_f32 v[26:27], v[42:43], v[26:27], v[104:105]
	v_pk_fma_f32 v[164:165], v[44:45], v[28:29], v[164:165]
	v_pk_fma_f32 v[26:27], v[46:47], v[28:29], v[26:27]
	v_pk_fma_f32 v[164:165], v[48:49], v[30:31], v[164:165]
	v_pk_fma_f32 v[26:27], v[50:51], v[30:31], v[26:27]
	v_pk_fma_f32 v[164:165], v[52:53], v[32:33], v[164:165]
	v_pk_fma_f32 v[26:27], v[54:55], v[32:33], v[26:27]
	v_pk_fma_f32 v[164:165], v[56:57], v[160:161], v[164:165]
	v_pk_fma_f32 v[26:27], v[58:59], v[160:161], v[26:27]
	v_pk_fma_f32 v[164:165], v[60:61], v[158:159], v[164:165]
	v_pk_fma_f32 v[26:27], v[62:63], v[158:159], v[26:27]
	v_pk_fma_f32 v[164:165], v[64:65], v[156:157], v[164:165]
	v_pk_fma_f32 v[26:27], v[66:67], v[156:157], v[26:27]
	v_pk_fma_f32 v[164:165], v[68:69], v[40:41], v[164:165]
	v_pk_fma_f32 v[26:27], v[70:71], v[40:41], v[26:27]
	v_pk_fma_f32 v[164:165], v[72:73], v[38:39], v[164:165]
	v_pk_fma_f32 v[26:27], v[74:75], v[38:39], v[26:27]
	v_pk_fma_f32 v[164:165], v[76:77], v[36:37], v[164:165]
	v_pk_fma_f32 v[26:27], v[78:79], v[36:37], v[26:27]
	v_pk_fma_f32 v[164:165], v[80:81], v[34:35], v[164:165]
	v_pk_fma_f32 v[26:27], v[82:83], v[34:35], v[26:27]
	v_pk_fma_f32 v[164:165], v[84:85], v[24:25], v[164:165]
	v_pk_fma_f32 v[26:27], v[86:87], v[24:25], v[26:27]
	v_pk_fma_f32 v[164:165], v[88:89], v[22:23], v[164:165]
	v_pk_fma_f32 v[26:27], v[90:91], v[22:23], v[26:27]
	v_pk_fma_f32 v[164:165], v[92:93], v[20:21], v[164:165]
	v_pk_fma_f32 v[26:27], v[94:95], v[20:21], v[26:27]
	v_pk_fma_f32 v[164:165], v[96:97], v[18:19], v[164:165]
	v_pk_fma_f32 v[26:27], v[98:99], v[18:19], v[26:27]
	v_pk_fma_f32 v[166:167], v[100:101], v[10:11], v[164:165]
	v_add_f32_e32 v164, v26, v27
	v_mul_f32_e32 v27, v42, v29
	v_mov_b32_e32 v26, v104
	v_pk_fma_f32 v[26:27], v[44:45], v[30:31], v[26:27]
	s_waitcnt lgkmcnt(2)
	v_mul_f32_e32 v105, v101, v12
	v_pk_fma_f32 v[26:27], v[48:49], v[32:33], v[26:27]
	v_pk_fma_f32 v[28:29], v[42:43], v[28:29], v[104:105]
	v_pk_fma_f32 v[26:27], v[52:53], v[160:161], v[26:27]
	v_pk_fma_f32 v[28:29], v[46:47], v[30:31], v[28:29]
	v_pk_fma_f32 v[26:27], v[56:57], v[158:159], v[26:27]
	v_pk_fma_f32 v[28:29], v[50:51], v[32:33], v[28:29]
	v_pk_fma_f32 v[26:27], v[60:61], v[156:157], v[26:27]
	v_pk_fma_f32 v[28:29], v[54:55], v[160:161], v[28:29]
	v_pk_fma_f32 v[26:27], v[64:65], v[40:41], v[26:27]
	v_pk_fma_f32 v[28:29], v[58:59], v[158:159], v[28:29]
	v_pk_fma_f32 v[26:27], v[68:69], v[38:39], v[26:27]
	v_pk_fma_f32 v[28:29], v[62:63], v[156:157], v[28:29]
	v_pk_fma_f32 v[26:27], v[72:73], v[36:37], v[26:27]
	v_pk_fma_f32 v[28:29], v[66:67], v[40:41], v[28:29]
	v_pk_fma_f32 v[26:27], v[76:77], v[34:35], v[26:27]
	v_pk_fma_f32 v[28:29], v[70:71], v[38:39], v[28:29]
	v_pk_fma_f32 v[26:27], v[80:81], v[24:25], v[26:27]
	v_pk_fma_f32 v[28:29], v[74:75], v[36:37], v[28:29]
	v_pk_fma_f32 v[26:27], v[84:85], v[22:23], v[26:27]
	v_pk_fma_f32 v[28:29], v[78:79], v[34:35], v[28:29]
	v_pk_fma_f32 v[26:27], v[88:89], v[20:21], v[26:27]
	v_pk_fma_f32 v[28:29], v[82:83], v[24:25], v[28:29]
	v_pk_fma_f32 v[26:27], v[92:93], v[18:19], v[26:27]
	v_pk_fma_f32 v[28:29], v[86:87], v[22:23], v[28:29]
	v_pk_fma_f32 v[26:27], v[96:97], v[10:11], v[26:27]
	v_pk_fma_f32 v[28:29], v[90:91], v[20:21], v[28:29]
	v_pk_fma_f32 v[26:27], v[100:101], v[12:13], v[26:27]
	v_add_f32_e32 v165, v166, v167
	v_pk_fma_f32 v[28:29], v[94:95], v[18:19], v[28:29]
	v_add_f32_e32 v167, v26, v27
	v_mul_f32_e32 v27, v42, v31
	v_mov_b32_e32 v26, v104
	v_pk_fma_f32 v[28:29], v[98:99], v[10:11], v[28:29]
	s_waitcnt lgkmcnt(1)
	v_mul_f32_e32 v105, v101, v14
	v_pk_fma_f32 v[26:27], v[44:45], v[32:33], v[26:27]
	v_add_f32_e32 v166, v28, v29
	v_pk_fma_f32 v[28:29], v[42:43], v[30:31], v[104:105]
	v_pk_fma_f32 v[26:27], v[48:49], v[160:161], v[26:27]
	v_pk_fma_f32 v[28:29], v[46:47], v[32:33], v[28:29]
	v_pk_fma_f32 v[26:27], v[52:53], v[158:159], v[26:27]
	v_pk_fma_f32 v[28:29], v[50:51], v[160:161], v[28:29]
	v_pk_fma_f32 v[26:27], v[56:57], v[156:157], v[26:27]
	v_pk_fma_f32 v[28:29], v[54:55], v[158:159], v[28:29]
	v_pk_fma_f32 v[26:27], v[60:61], v[40:41], v[26:27]
	v_pk_fma_f32 v[28:29], v[58:59], v[156:157], v[28:29]
	v_pk_fma_f32 v[26:27], v[64:65], v[38:39], v[26:27]
	v_pk_fma_f32 v[28:29], v[62:63], v[40:41], v[28:29]
	v_pk_fma_f32 v[26:27], v[68:69], v[36:37], v[26:27]
	v_pk_fma_f32 v[28:29], v[66:67], v[38:39], v[28:29]
	v_pk_fma_f32 v[26:27], v[72:73], v[34:35], v[26:27]
	v_pk_fma_f32 v[28:29], v[70:71], v[36:37], v[28:29]
	v_pk_fma_f32 v[26:27], v[76:77], v[24:25], v[26:27]
	v_pk_fma_f32 v[28:29], v[74:75], v[34:35], v[28:29]
	v_pk_fma_f32 v[26:27], v[80:81], v[22:23], v[26:27]
	v_pk_fma_f32 v[28:29], v[78:79], v[24:25], v[28:29]
	v_pk_fma_f32 v[26:27], v[84:85], v[20:21], v[26:27]
	v_pk_fma_f32 v[28:29], v[82:83], v[22:23], v[28:29]
	v_pk_fma_f32 v[26:27], v[88:89], v[18:19], v[26:27]
	v_pk_fma_f32 v[28:29], v[86:87], v[20:21], v[28:29]
	v_pk_fma_f32 v[26:27], v[92:93], v[10:11], v[26:27]
	v_pk_fma_f32 v[28:29], v[90:91], v[18:19], v[28:29]
	v_pk_fma_f32 v[26:27], v[96:97], v[12:13], v[26:27]
	v_pk_fma_f32 v[28:29], v[94:95], v[10:11], v[28:29]
	v_pk_fma_f32 v[26:27], v[100:101], v[14:15], v[26:27]
	v_pk_fma_f32 v[28:29], v[98:99], v[12:13], v[28:29]
	v_add_f32_e32 v169, v26, v27
	s_waitcnt lgkmcnt(0)
	v_mul_f32_e32 v105, v101, v16
	v_mul_f32_e32 v27, v42, v33
	v_mov_b32_e32 v26, v104
	v_add_f32_e32 v168, v28, v29
	v_pk_fma_f32 v[28:29], v[42:43], v[32:33], v[104:105]
	v_pk_fma_f32 v[26:27], v[44:45], v[160:161], v[26:27]
	v_pk_fma_f32 v[28:29], v[46:47], v[160:161], v[28:29]
	v_pk_fma_f32 v[26:27], v[48:49], v[158:159], v[26:27]
	v_pk_fma_f32 v[28:29], v[50:51], v[158:159], v[28:29]
	v_pk_fma_f32 v[26:27], v[52:53], v[156:157], v[26:27]
	v_pk_fma_f32 v[28:29], v[54:55], v[156:157], v[28:29]
	v_pk_fma_f32 v[26:27], v[56:57], v[40:41], v[26:27]
	v_pk_fma_f32 v[28:29], v[58:59], v[40:41], v[28:29]
	v_pk_fma_f32 v[26:27], v[60:61], v[38:39], v[26:27]
	v_pk_fma_f32 v[28:29], v[62:63], v[38:39], v[28:29]
	v_pk_fma_f32 v[26:27], v[64:65], v[36:37], v[26:27]
	v_pk_fma_f32 v[28:29], v[66:67], v[36:37], v[28:29]
	v_pk_fma_f32 v[26:27], v[68:69], v[34:35], v[26:27]
	v_pk_fma_f32 v[28:29], v[70:71], v[34:35], v[28:29]
	v_pk_fma_f32 v[26:27], v[72:73], v[24:25], v[26:27]
	v_pk_fma_f32 v[28:29], v[74:75], v[24:25], v[28:29]
	v_pk_fma_f32 v[26:27], v[76:77], v[22:23], v[26:27]
	v_pk_fma_f32 v[28:29], v[78:79], v[22:23], v[28:29]
	v_pk_fma_f32 v[26:27], v[80:81], v[20:21], v[26:27]
	v_pk_fma_f32 v[28:29], v[82:83], v[20:21], v[28:29]
	v_pk_fma_f32 v[26:27], v[84:85], v[18:19], v[26:27]
	v_pk_fma_f32 v[28:29], v[86:87], v[18:19], v[28:29]
	v_pk_fma_f32 v[26:27], v[88:89], v[10:11], v[26:27]
	v_pk_fma_f32 v[28:29], v[90:91], v[10:11], v[28:29]
	v_pk_fma_f32 v[26:27], v[92:93], v[12:13], v[26:27]
	v_pk_fma_f32 v[28:29], v[94:95], v[12:13], v[28:29]
	v_pk_fma_f32 v[26:27], v[96:97], v[14:15], v[26:27]
	v_pk_fma_f32 v[28:29], v[98:99], v[14:15], v[28:29]
	v_pk_fma_f32 v[26:27], v[100:101], v[16:17], v[26:27]
	v_add_f32_e32 v170, v28, v29
	v_add_f32_e32 v171, v26, v27
	ds_read2st64_b32 v[26:27], v163 offset0:152 offset1:156
	ds_read2st64_b32 v[28:29], v163 offset0:160 offset1:164
	ds_read2st64_b32 v[30:31], v163 offset0:168 offset1:172
	ds_read2st64_b32 v[32:33], v163 offset0:176 offset1:180
	v_mul_f32_e32 v173, v42, v161
	s_waitcnt lgkmcnt(3)
	v_mul_f32_e32 v105, v101, v26
	v_pk_fma_f32 v[160:161], v[42:43], v[160:161], v[104:105]
	v_mov_b32_e32 v172, v104
	v_pk_fma_f32 v[160:161], v[46:47], v[158:159], v[160:161]
	s_waitcnt lgkmcnt(2)
	v_mul_f32_e32 v105, v101, v28
	v_pk_fma_f32 v[160:161], v[50:51], v[156:157], v[160:161]
	v_pk_fma_f32 v[172:173], v[44:45], v[158:159], v[172:173]
	v_pk_fma_f32 v[160:161], v[54:55], v[40:41], v[160:161]
	v_pk_fma_f32 v[172:173], v[48:49], v[156:157], v[172:173]
	v_pk_fma_f32 v[160:161], v[58:59], v[38:39], v[160:161]
	v_pk_fma_f32 v[172:173], v[52:53], v[40:41], v[172:173]
	v_pk_fma_f32 v[160:161], v[62:63], v[36:37], v[160:161]
	v_pk_fma_f32 v[172:173], v[56:57], v[38:39], v[172:173]
	v_pk_fma_f32 v[160:161], v[66:67], v[34:35], v[160:161]
	v_pk_fma_f32 v[172:173], v[60:61], v[36:37], v[172:173]
	v_pk_fma_f32 v[160:161], v[70:71], v[24:25], v[160:161]
	v_pk_fma_f32 v[172:173], v[64:65], v[34:35], v[172:173]
	v_pk_fma_f32 v[160:161], v[74:75], v[22:23], v[160:161]
	v_pk_fma_f32 v[172:173], v[68:69], v[24:25], v[172:173]
	v_pk_fma_f32 v[160:161], v[78:79], v[20:21], v[160:161]
	v_pk_fma_f32 v[172:173], v[72:73], v[22:23], v[172:173]
	v_pk_fma_f32 v[160:161], v[82:83], v[18:19], v[160:161]
	v_pk_fma_f32 v[172:173], v[76:77], v[20:21], v[172:173]
	v_pk_fma_f32 v[160:161], v[86:87], v[10:11], v[160:161]
	v_pk_fma_f32 v[172:173], v[80:81], v[18:19], v[172:173]
	v_pk_fma_f32 v[160:161], v[90:91], v[12:13], v[160:161]
	v_pk_fma_f32 v[172:173], v[84:85], v[10:11], v[172:173]
	v_pk_fma_f32 v[160:161], v[94:95], v[14:15], v[160:161]
	v_pk_fma_f32 v[172:173], v[88:89], v[12:13], v[172:173]
	v_pk_fma_f32 v[160:161], v[98:99], v[16:17], v[160:161]
	v_pk_fma_f32 v[172:173], v[92:93], v[14:15], v[172:173]
	v_add_f32_e32 v174, v160, v161
	v_mul_f32_e32 v161, v42, v159
	v_pk_fma_f32 v[158:159], v[42:43], v[158:159], v[104:105]
	v_mov_b32_e32 v160, v104
	v_pk_fma_f32 v[158:159], v[46:47], v[156:157], v[158:159]
	s_waitcnt lgkmcnt(1)
	v_mul_f32_e32 v105, v101, v30
	v_pk_fma_f32 v[158:159], v[50:51], v[40:41], v[158:159]
	v_pk_fma_f32 v[160:161], v[44:45], v[156:157], v[160:161]
	v_pk_fma_f32 v[158:159], v[54:55], v[38:39], v[158:159]
	v_pk_fma_f32 v[160:161], v[48:49], v[40:41], v[160:161]
	v_pk_fma_f32 v[158:159], v[58:59], v[36:37], v[158:159]
	v_pk_fma_f32 v[160:161], v[52:53], v[38:39], v[160:161]
	v_pk_fma_f32 v[158:159], v[62:63], v[34:35], v[158:159]
	v_pk_fma_f32 v[160:161], v[56:57], v[36:37], v[160:161]
	v_pk_fma_f32 v[158:159], v[66:67], v[24:25], v[158:159]
	v_pk_fma_f32 v[160:161], v[60:61], v[34:35], v[160:161]
	v_pk_fma_f32 v[158:159], v[70:71], v[22:23], v[158:159]
	v_pk_fma_f32 v[160:161], v[64:65], v[24:25], v[160:161]
	v_pk_fma_f32 v[158:159], v[74:75], v[20:21], v[158:159]
	v_pk_fma_f32 v[160:161], v[68:69], v[22:23], v[160:161]
	v_pk_fma_f32 v[158:159], v[78:79], v[18:19], v[158:159]
	v_pk_fma_f32 v[160:161], v[72:73], v[20:21], v[160:161]
	v_pk_fma_f32 v[158:159], v[82:83], v[10:11], v[158:159]
	v_pk_fma_f32 v[160:161], v[76:77], v[18:19], v[160:161]
	v_pk_fma_f32 v[158:159], v[86:87], v[12:13], v[158:159]
	v_pk_fma_f32 v[160:161], v[80:81], v[10:11], v[160:161]
	v_pk_fma_f32 v[158:159], v[90:91], v[14:15], v[158:159]
	v_pk_fma_f32 v[160:161], v[84:85], v[12:13], v[160:161]
	v_pk_fma_f32 v[158:159], v[94:95], v[16:17], v[158:159]
	v_pk_fma_f32 v[160:161], v[88:89], v[14:15], v[160:161]
	v_pk_fma_f32 v[158:159], v[98:99], v[26:27], v[158:159]
	v_pk_fma_f32 v[160:161], v[92:93], v[16:17], v[160:161]
	v_add_f32_e32 v176, v158, v159
	v_mul_f32_e32 v159, v42, v157
	v_pk_fma_f32 v[156:157], v[42:43], v[156:157], v[104:105]
	v_mov_b32_e32 v158, v104
	v_pk_fma_f32 v[156:157], v[46:47], v[40:41], v[156:157]
	s_waitcnt lgkmcnt(0)
	v_mul_f32_e32 v105, v101, v32
	v_pk_fma_f32 v[156:157], v[50:51], v[38:39], v[156:157]
	v_pk_fma_f32 v[158:159], v[44:45], v[40:41], v[158:159]
	v_pk_fma_f32 v[156:157], v[54:55], v[36:37], v[156:157]
	v_pk_fma_f32 v[158:159], v[48:49], v[38:39], v[158:159]
	v_pk_fma_f32 v[156:157], v[58:59], v[34:35], v[156:157]
	v_pk_fma_f32 v[158:159], v[52:53], v[36:37], v[158:159]
	v_pk_fma_f32 v[156:157], v[62:63], v[24:25], v[156:157]
	v_pk_fma_f32 v[158:159], v[56:57], v[34:35], v[158:159]
	v_pk_fma_f32 v[156:157], v[66:67], v[22:23], v[156:157]
	v_pk_fma_f32 v[158:159], v[60:61], v[24:25], v[158:159]
	v_pk_fma_f32 v[156:157], v[70:71], v[20:21], v[156:157]
	v_pk_fma_f32 v[158:159], v[64:65], v[22:23], v[158:159]
	v_pk_fma_f32 v[156:157], v[74:75], v[18:19], v[156:157]
	v_pk_fma_f32 v[158:159], v[68:69], v[20:21], v[158:159]
	v_pk_fma_f32 v[156:157], v[78:79], v[10:11], v[156:157]
	v_pk_fma_f32 v[158:159], v[72:73], v[18:19], v[158:159]
	v_pk_fma_f32 v[156:157], v[82:83], v[12:13], v[156:157]
	v_pk_fma_f32 v[158:159], v[76:77], v[10:11], v[158:159]
	v_pk_fma_f32 v[156:157], v[86:87], v[14:15], v[156:157]
	v_pk_fma_f32 v[158:159], v[80:81], v[12:13], v[158:159]
	v_pk_fma_f32 v[156:157], v[90:91], v[16:17], v[156:157]
	v_pk_fma_f32 v[158:159], v[84:85], v[14:15], v[158:159]
	v_pk_fma_f32 v[156:157], v[94:95], v[26:27], v[156:157]
	v_pk_fma_f32 v[158:159], v[88:89], v[16:17], v[158:159]
	v_pk_fma_f32 v[156:157], v[98:99], v[28:29], v[156:157]
	v_pk_fma_f32 v[158:159], v[92:93], v[26:27], v[158:159]
	v_add_f32_e32 v178, v156, v157
	v_mul_f32_e32 v157, v42, v41
	v_mov_b32_e32 v156, v104
	v_pk_fma_f32 v[40:41], v[42:43], v[40:41], v[104:105]
	v_pk_fma_f32 v[156:157], v[44:45], v[38:39], v[156:157]
	v_pk_fma_f32 v[40:41], v[46:47], v[38:39], v[40:41]
	v_pk_fma_f32 v[156:157], v[48:49], v[36:37], v[156:157]
	v_pk_fma_f32 v[40:41], v[50:51], v[36:37], v[40:41]
	v_pk_fma_f32 v[156:157], v[52:53], v[34:35], v[156:157]
	v_pk_fma_f32 v[40:41], v[54:55], v[34:35], v[40:41]
	v_pk_fma_f32 v[156:157], v[56:57], v[24:25], v[156:157]
	v_pk_fma_f32 v[40:41], v[58:59], v[24:25], v[40:41]
	v_pk_fma_f32 v[156:157], v[60:61], v[22:23], v[156:157]
	v_pk_fma_f32 v[40:41], v[62:63], v[22:23], v[40:41]
	v_pk_fma_f32 v[156:157], v[64:65], v[20:21], v[156:157]
	v_pk_fma_f32 v[40:41], v[66:67], v[20:21], v[40:41]
	v_pk_fma_f32 v[156:157], v[68:69], v[18:19], v[156:157]
	v_pk_fma_f32 v[40:41], v[70:71], v[18:19], v[40:41]
	v_pk_fma_f32 v[156:157], v[72:73], v[10:11], v[156:157]
	v_pk_fma_f32 v[40:41], v[74:75], v[10:11], v[40:41]
	v_pk_fma_f32 v[156:157], v[76:77], v[12:13], v[156:157]
	v_pk_fma_f32 v[40:41], v[78:79], v[12:13], v[40:41]
	v_pk_fma_f32 v[156:157], v[80:81], v[14:15], v[156:157]
	v_pk_fma_f32 v[40:41], v[82:83], v[14:15], v[40:41]
	v_pk_fma_f32 v[156:157], v[84:85], v[16:17], v[156:157]
	v_pk_fma_f32 v[40:41], v[86:87], v[16:17], v[40:41]
	v_pk_fma_f32 v[156:157], v[88:89], v[26:27], v[156:157]
	v_pk_fma_f32 v[40:41], v[90:91], v[26:27], v[40:41]
	v_pk_fma_f32 v[156:157], v[92:93], v[28:29], v[156:157]
	v_pk_fma_f32 v[160:161], v[96:97], v[26:27], v[160:161]
	v_pk_fma_f32 v[158:159], v[96:97], v[28:29], v[158:159]
	v_pk_fma_f32 v[40:41], v[94:95], v[28:29], v[40:41]
	v_pk_fma_f32 v[156:157], v[96:97], v[30:31], v[156:157]
	v_pk_fma_f32 v[160:161], v[100:101], v[28:29], v[160:161]
	v_pk_fma_f32 v[158:159], v[100:101], v[30:31], v[158:159]
	v_pk_fma_f32 v[40:41], v[98:99], v[30:31], v[40:41]
	v_pk_fma_f32 v[156:157], v[100:101], v[32:33], v[156:157]
	v_add_f32_e32 v177, v160, v161
	v_add_f32_e32 v179, v158, v159
	v_add_f32_e32 v180, v40, v41
	v_add_f32_e32 v181, v156, v157
	ds_read2st64_b32 v[40:41], v163 offset0:184 offset1:188
	ds_read2st64_b32 v[156:157], v163 offset0:192 offset1:196
	ds_read2st64_b32 v[158:159], v163 offset0:200 offset1:204
	ds_read2st64_b32 v[160:161], v163 offset0:208 offset1:212
	v_pk_fma_f32 v[172:173], v[96:97], v[16:17], v[172:173]
	s_waitcnt lgkmcnt(3)
	v_mul_f32_e32 v105, v101, v40
	v_pk_fma_f32 v[172:173], v[100:101], v[26:27], v[172:173]
	s_addk_i32 s64, 0x800
	v_add_f32_e32 v175, v172, v173
	v_mul_f32_e32 v173, v42, v39
	v_pk_fma_f32 v[38:39], v[42:43], v[38:39], v[104:105]
	v_mov_b32_e32 v172, v104
	v_pk_fma_f32 v[38:39], v[46:47], v[36:37], v[38:39]
	s_waitcnt lgkmcnt(2)
	v_mul_f32_e32 v105, v101, v156
	v_pk_fma_f32 v[38:39], v[50:51], v[34:35], v[38:39]
	v_pk_fma_f32 v[172:173], v[44:45], v[36:37], v[172:173]
	v_pk_fma_f32 v[38:39], v[54:55], v[24:25], v[38:39]
	v_pk_fma_f32 v[172:173], v[48:49], v[34:35], v[172:173]
	v_pk_fma_f32 v[38:39], v[58:59], v[22:23], v[38:39]
	v_pk_fma_f32 v[172:173], v[52:53], v[24:25], v[172:173]
	v_pk_fma_f32 v[38:39], v[62:63], v[20:21], v[38:39]
	v_pk_fma_f32 v[172:173], v[56:57], v[22:23], v[172:173]
	v_pk_fma_f32 v[38:39], v[66:67], v[18:19], v[38:39]
	v_pk_fma_f32 v[172:173], v[60:61], v[20:21], v[172:173]
	v_pk_fma_f32 v[38:39], v[70:71], v[10:11], v[38:39]
	v_pk_fma_f32 v[172:173], v[64:65], v[18:19], v[172:173]
	v_pk_fma_f32 v[38:39], v[74:75], v[12:13], v[38:39]
	v_pk_fma_f32 v[172:173], v[68:69], v[10:11], v[172:173]
	v_pk_fma_f32 v[38:39], v[78:79], v[14:15], v[38:39]
	v_pk_fma_f32 v[172:173], v[72:73], v[12:13], v[172:173]
	v_pk_fma_f32 v[38:39], v[82:83], v[16:17], v[38:39]
	v_pk_fma_f32 v[172:173], v[76:77], v[14:15], v[172:173]
	v_pk_fma_f32 v[38:39], v[86:87], v[26:27], v[38:39]
	v_pk_fma_f32 v[172:173], v[80:81], v[16:17], v[172:173]
	v_pk_fma_f32 v[38:39], v[90:91], v[28:29], v[38:39]
	v_pk_fma_f32 v[172:173], v[84:85], v[26:27], v[172:173]
	v_pk_fma_f32 v[38:39], v[94:95], v[30:31], v[38:39]
	v_pk_fma_f32 v[172:173], v[88:89], v[28:29], v[172:173]
	v_pk_fma_f32 v[38:39], v[98:99], v[32:33], v[38:39]
	v_pk_fma_f32 v[172:173], v[92:93], v[30:31], v[172:173]
	v_add_f32_e32 v182, v38, v39
	v_mul_f32_e32 v39, v42, v37
	v_pk_fma_f32 v[36:37], v[42:43], v[36:37], v[104:105]
	v_mov_b32_e32 v38, v104
	v_pk_fma_f32 v[36:37], v[46:47], v[34:35], v[36:37]
	s_waitcnt lgkmcnt(1)
	v_mul_f32_e32 v105, v101, v158
	v_pk_fma_f32 v[36:37], v[50:51], v[24:25], v[36:37]
	v_pk_fma_f32 v[38:39], v[44:45], v[34:35], v[38:39]
	v_pk_fma_f32 v[36:37], v[54:55], v[22:23], v[36:37]
	v_pk_fma_f32 v[38:39], v[48:49], v[24:25], v[38:39]
	v_pk_fma_f32 v[36:37], v[58:59], v[20:21], v[36:37]
	v_pk_fma_f32 v[38:39], v[52:53], v[22:23], v[38:39]
	v_pk_fma_f32 v[36:37], v[62:63], v[18:19], v[36:37]
	v_pk_fma_f32 v[38:39], v[56:57], v[20:21], v[38:39]
	v_pk_fma_f32 v[36:37], v[66:67], v[10:11], v[36:37]
	v_pk_fma_f32 v[38:39], v[60:61], v[18:19], v[38:39]
	v_pk_fma_f32 v[36:37], v[70:71], v[12:13], v[36:37]
	v_pk_fma_f32 v[38:39], v[64:65], v[10:11], v[38:39]
	v_pk_fma_f32 v[36:37], v[74:75], v[14:15], v[36:37]
	v_pk_fma_f32 v[38:39], v[68:69], v[12:13], v[38:39]
	v_pk_fma_f32 v[36:37], v[78:79], v[16:17], v[36:37]
	v_pk_fma_f32 v[38:39], v[72:73], v[14:15], v[38:39]
	v_pk_fma_f32 v[36:37], v[82:83], v[26:27], v[36:37]
	v_pk_fma_f32 v[38:39], v[76:77], v[16:17], v[38:39]
	v_pk_fma_f32 v[36:37], v[86:87], v[28:29], v[36:37]
	v_pk_fma_f32 v[38:39], v[80:81], v[26:27], v[38:39]
	v_pk_fma_f32 v[36:37], v[90:91], v[30:31], v[36:37]
	v_pk_fma_f32 v[38:39], v[84:85], v[28:29], v[38:39]
	v_pk_fma_f32 v[36:37], v[94:95], v[32:33], v[36:37]
	v_pk_fma_f32 v[38:39], v[88:89], v[30:31], v[38:39]
	v_pk_fma_f32 v[36:37], v[98:99], v[40:41], v[36:37]
	v_pk_fma_f32 v[38:39], v[92:93], v[32:33], v[38:39]
	v_add_f32_e32 v184, v36, v37
	v_mul_f32_e32 v37, v42, v35
	v_pk_fma_f32 v[34:35], v[42:43], v[34:35], v[104:105]
	v_mov_b32_e32 v36, v104
	v_pk_fma_f32 v[34:35], v[46:47], v[24:25], v[34:35]
	s_waitcnt lgkmcnt(0)
	v_mul_f32_e32 v105, v101, v160
	v_pk_fma_f32 v[34:35], v[50:51], v[22:23], v[34:35]
	v_pk_fma_f32 v[36:37], v[44:45], v[24:25], v[36:37]
	v_pk_fma_f32 v[34:35], v[54:55], v[20:21], v[34:35]
	v_pk_fma_f32 v[36:37], v[48:49], v[22:23], v[36:37]
	v_pk_fma_f32 v[34:35], v[58:59], v[18:19], v[34:35]
	v_pk_fma_f32 v[36:37], v[52:53], v[20:21], v[36:37]
	v_pk_fma_f32 v[34:35], v[62:63], v[10:11], v[34:35]
	v_pk_fma_f32 v[36:37], v[56:57], v[18:19], v[36:37]
	v_pk_fma_f32 v[34:35], v[66:67], v[12:13], v[34:35]
	v_pk_fma_f32 v[36:37], v[60:61], v[10:11], v[36:37]
	v_pk_fma_f32 v[34:35], v[70:71], v[14:15], v[34:35]
	v_pk_fma_f32 v[36:37], v[64:65], v[12:13], v[36:37]
	v_pk_fma_f32 v[34:35], v[74:75], v[16:17], v[34:35]
	v_pk_fma_f32 v[36:37], v[68:69], v[14:15], v[36:37]
	v_pk_fma_f32 v[34:35], v[78:79], v[26:27], v[34:35]
	v_pk_fma_f32 v[36:37], v[72:73], v[16:17], v[36:37]
	v_pk_fma_f32 v[34:35], v[82:83], v[28:29], v[34:35]
	v_pk_fma_f32 v[36:37], v[76:77], v[26:27], v[36:37]
	v_pk_fma_f32 v[34:35], v[86:87], v[30:31], v[34:35]
	v_pk_fma_f32 v[36:37], v[80:81], v[28:29], v[36:37]
	v_pk_fma_f32 v[34:35], v[90:91], v[32:33], v[34:35]
	v_pk_fma_f32 v[36:37], v[84:85], v[30:31], v[36:37]
	v_pk_fma_f32 v[34:35], v[94:95], v[40:41], v[34:35]
	v_pk_fma_f32 v[36:37], v[88:89], v[32:33], v[36:37]
	v_pk_fma_f32 v[34:35], v[98:99], v[156:157], v[34:35]
	v_pk_fma_f32 v[36:37], v[92:93], v[40:41], v[36:37]
	v_add_f32_e32 v186, v34, v35
	v_mul_f32_e32 v35, v42, v25
	v_mov_b32_e32 v34, v104
	v_pk_fma_f32 v[24:25], v[42:43], v[24:25], v[104:105]
	v_pk_fma_f32 v[34:35], v[44:45], v[22:23], v[34:35]
	v_pk_fma_f32 v[24:25], v[46:47], v[22:23], v[24:25]
	v_pk_fma_f32 v[34:35], v[48:49], v[20:21], v[34:35]
	v_pk_fma_f32 v[24:25], v[50:51], v[20:21], v[24:25]
	v_pk_fma_f32 v[34:35], v[52:53], v[18:19], v[34:35]
	v_pk_fma_f32 v[24:25], v[54:55], v[18:19], v[24:25]
	v_pk_fma_f32 v[34:35], v[56:57], v[10:11], v[34:35]
	v_pk_fma_f32 v[24:25], v[58:59], v[10:11], v[24:25]
	v_pk_fma_f32 v[34:35], v[60:61], v[12:13], v[34:35]
	v_pk_fma_f32 v[24:25], v[62:63], v[12:13], v[24:25]
	v_pk_fma_f32 v[34:35], v[64:65], v[14:15], v[34:35]
	v_pk_fma_f32 v[24:25], v[66:67], v[14:15], v[24:25]
	v_pk_fma_f32 v[34:35], v[68:69], v[16:17], v[34:35]
	v_pk_fma_f32 v[24:25], v[70:71], v[16:17], v[24:25]
	v_pk_fma_f32 v[34:35], v[72:73], v[26:27], v[34:35]
	v_pk_fma_f32 v[24:25], v[74:75], v[26:27], v[24:25]
	v_pk_fma_f32 v[34:35], v[76:77], v[28:29], v[34:35]
	v_pk_fma_f32 v[24:25], v[78:79], v[28:29], v[24:25]
	v_pk_fma_f32 v[34:35], v[80:81], v[30:31], v[34:35]
	v_pk_fma_f32 v[24:25], v[82:83], v[30:31], v[24:25]
	v_pk_fma_f32 v[34:35], v[84:85], v[32:33], v[34:35]
	v_pk_fma_f32 v[24:25], v[86:87], v[32:33], v[24:25]
	v_pk_fma_f32 v[34:35], v[88:89], v[40:41], v[34:35]
	v_pk_fma_f32 v[24:25], v[90:91], v[40:41], v[24:25]
	v_pk_fma_f32 v[34:35], v[92:93], v[156:157], v[34:35]
	v_pk_fma_f32 v[38:39], v[96:97], v[40:41], v[38:39]
	v_pk_fma_f32 v[36:37], v[96:97], v[156:157], v[36:37]
	v_pk_fma_f32 v[24:25], v[94:95], v[156:157], v[24:25]
	v_pk_fma_f32 v[34:35], v[96:97], v[158:159], v[34:35]
	v_pk_fma_f32 v[38:39], v[100:101], v[156:157], v[38:39]
	v_pk_fma_f32 v[36:37], v[100:101], v[158:159], v[36:37]
	v_pk_fma_f32 v[24:25], v[98:99], v[158:159], v[24:25]
	v_pk_fma_f32 v[34:35], v[100:101], v[160:161], v[34:35]
	v_add_f32_e32 v185, v38, v39
	v_add_f32_e32 v187, v36, v37
	v_add_f32_e32 v188, v24, v25
	v_add_f32_e32 v189, v34, v35
	ds_read2st64_b32 v[24:25], v163 offset0:216 offset1:220
	ds_read2st64_b32 v[34:35], v163 offset0:224 offset1:228
	ds_read2st64_b32 v[36:37], v163 offset0:232 offset1:236
	ds_read2st64_b32 v[38:39], v163 offset0:240 offset1:244
	v_pk_fma_f32 v[172:173], v[96:97], v[32:33], v[172:173]
	s_waitcnt lgkmcnt(3)
	v_mul_f32_e32 v105, v101, v24
	v_pk_fma_f32 v[172:173], v[100:101], v[40:41], v[172:173]
	s_waitcnt lgkmcnt(0)
	v_add_f32_e32 v183, v172, v173
	v_mul_f32_e32 v173, v42, v23
	v_pk_fma_f32 v[22:23], v[42:43], v[22:23], v[104:105]
	v_mov_b32_e32 v172, v104
	v_pk_fma_f32 v[22:23], v[46:47], v[20:21], v[22:23]
	v_mul_f32_e32 v105, v101, v34
	v_pk_fma_f32 v[22:23], v[50:51], v[18:19], v[22:23]
	v_pk_fma_f32 v[172:173], v[44:45], v[20:21], v[172:173]
	v_pk_fma_f32 v[22:23], v[54:55], v[10:11], v[22:23]
	v_pk_fma_f32 v[172:173], v[48:49], v[18:19], v[172:173]
	v_pk_fma_f32 v[22:23], v[58:59], v[12:13], v[22:23]
	v_pk_fma_f32 v[172:173], v[52:53], v[10:11], v[172:173]
	v_pk_fma_f32 v[22:23], v[62:63], v[14:15], v[22:23]
	v_pk_fma_f32 v[172:173], v[56:57], v[12:13], v[172:173]
	v_pk_fma_f32 v[22:23], v[66:67], v[16:17], v[22:23]
	v_pk_fma_f32 v[172:173], v[60:61], v[14:15], v[172:173]
	v_pk_fma_f32 v[22:23], v[70:71], v[26:27], v[22:23]
	v_pk_fma_f32 v[172:173], v[64:65], v[16:17], v[172:173]
	v_pk_fma_f32 v[22:23], v[74:75], v[28:29], v[22:23]
	v_pk_fma_f32 v[172:173], v[68:69], v[26:27], v[172:173]
	v_pk_fma_f32 v[22:23], v[78:79], v[30:31], v[22:23]
	v_pk_fma_f32 v[172:173], v[72:73], v[28:29], v[172:173]
	v_pk_fma_f32 v[22:23], v[82:83], v[32:33], v[22:23]
	v_pk_fma_f32 v[172:173], v[76:77], v[30:31], v[172:173]
	v_pk_fma_f32 v[22:23], v[86:87], v[40:41], v[22:23]
	v_pk_fma_f32 v[172:173], v[80:81], v[32:33], v[172:173]
	v_pk_fma_f32 v[22:23], v[90:91], v[156:157], v[22:23]
	v_pk_fma_f32 v[172:173], v[84:85], v[40:41], v[172:173]
	v_pk_fma_f32 v[22:23], v[94:95], v[158:159], v[22:23]
	v_pk_fma_f32 v[172:173], v[88:89], v[156:157], v[172:173]
	v_pk_fma_f32 v[22:23], v[98:99], v[160:161], v[22:23]
	v_pk_fma_f32 v[172:173], v[92:93], v[158:159], v[172:173]
	v_add_f32_e32 v190, v22, v23
	v_mul_f32_e32 v23, v42, v21
	v_pk_fma_f32 v[20:21], v[42:43], v[20:21], v[104:105]
	v_pk_fma_f32 v[172:173], v[96:97], v[160:161], v[172:173]
	v_pk_fma_f32 v[20:21], v[46:47], v[18:19], v[20:21]
	v_pk_fma_f32 v[172:173], v[100:101], v[24:25], v[172:173]
	v_pk_fma_f32 v[20:21], v[50:51], v[10:11], v[20:21]
	v_mov_b32_e32 v22, v104
	v_pk_fma_f32 v[20:21], v[54:55], v[12:13], v[20:21]
	v_mul_f32_e32 v105, v101, v36
	v_pk_fma_f32 v[20:21], v[58:59], v[14:15], v[20:21]
	v_add_f32_e32 v172, v172, v173
	v_pk_fma_f32 v[20:21], v[62:63], v[16:17], v[20:21]
	v_pk_fma_f32 v[22:23], v[44:45], v[18:19], v[22:23]
	v_pk_fma_f32 v[20:21], v[66:67], v[26:27], v[20:21]
	v_pk_fma_f32 v[22:23], v[48:49], v[10:11], v[22:23]
	v_pk_fma_f32 v[20:21], v[70:71], v[28:29], v[20:21]
	v_pk_fma_f32 v[22:23], v[52:53], v[12:13], v[22:23]
	v_pk_fma_f32 v[20:21], v[74:75], v[30:31], v[20:21]
	v_pk_fma_f32 v[22:23], v[56:57], v[14:15], v[22:23]
	v_pk_fma_f32 v[20:21], v[78:79], v[32:33], v[20:21]
	v_pk_fma_f32 v[22:23], v[60:61], v[16:17], v[22:23]
	v_pk_fma_f32 v[20:21], v[82:83], v[40:41], v[20:21]
	v_pk_fma_f32 v[22:23], v[64:65], v[26:27], v[22:23]
	v_pk_fma_f32 v[20:21], v[86:87], v[156:157], v[20:21]
	v_pk_fma_f32 v[22:23], v[68:69], v[28:29], v[22:23]
	v_pk_fma_f32 v[20:21], v[90:91], v[158:159], v[20:21]
	v_pk_fma_f32 v[22:23], v[72:73], v[30:31], v[22:23]
	v_pk_fma_f32 v[20:21], v[94:95], v[160:161], v[20:21]
	v_pk_fma_f32 v[22:23], v[76:77], v[32:33], v[22:23]
	v_pk_fma_f32 v[20:21], v[98:99], v[24:25], v[20:21]
	v_pk_fma_f32 v[22:23], v[80:81], v[40:41], v[22:23]
	v_add_f32_e32 v173, v20, v21
	v_mul_f32_e32 v21, v42, v19
	v_pk_fma_f32 v[18:19], v[42:43], v[18:19], v[104:105]
	v_pk_fma_f32 v[22:23], v[84:85], v[156:157], v[22:23]
	v_pk_fma_f32 v[18:19], v[46:47], v[10:11], v[18:19]
	v_pk_fma_f32 v[22:23], v[88:89], v[158:159], v[22:23]
	v_pk_fma_f32 v[18:19], v[50:51], v[12:13], v[18:19]
	v_pk_fma_f32 v[22:23], v[92:93], v[160:161], v[22:23]
	v_pk_fma_f32 v[18:19], v[54:55], v[14:15], v[18:19]
	v_pk_fma_f32 v[22:23], v[96:97], v[24:25], v[22:23]
	v_pk_fma_f32 v[18:19], v[58:59], v[16:17], v[18:19]
	v_pk_fma_f32 v[22:23], v[100:101], v[34:35], v[22:23]
	v_pk_fma_f32 v[18:19], v[62:63], v[26:27], v[18:19]
	v_add_f32_e32 v22, v22, v23
	v_pk_fma_f32 v[18:19], v[66:67], v[28:29], v[18:19]
	v_mov_b32_e32 v20, v104
	v_pk_fma_f32 v[18:19], v[70:71], v[30:31], v[18:19]
	v_mul_f32_e32 v105, v101, v38
	v_pk_fma_f32 v[18:19], v[74:75], v[32:33], v[18:19]
	v_pk_fma_f32 v[20:21], v[44:45], v[10:11], v[20:21]
	v_pk_fma_f32 v[18:19], v[78:79], v[40:41], v[18:19]
	v_pk_fma_f32 v[20:21], v[48:49], v[12:13], v[20:21]
	v_pk_fma_f32 v[18:19], v[82:83], v[156:157], v[18:19]
	v_pk_fma_f32 v[20:21], v[52:53], v[14:15], v[20:21]
	v_pk_fma_f32 v[18:19], v[86:87], v[158:159], v[18:19]
	v_pk_fma_f32 v[20:21], v[56:57], v[16:17], v[20:21]
	v_pk_fma_f32 v[18:19], v[90:91], v[160:161], v[18:19]
	v_pk_fma_f32 v[20:21], v[60:61], v[26:27], v[20:21]
	v_pk_fma_f32 v[18:19], v[94:95], v[24:25], v[18:19]
	v_pk_fma_f32 v[20:21], v[64:65], v[28:29], v[20:21]
	v_pk_fma_f32 v[18:19], v[98:99], v[34:35], v[18:19]
	v_pk_fma_f32 v[20:21], v[68:69], v[30:31], v[20:21]
	v_add_f32_e32 v23, v18, v19
	v_mul_f32_e32 v19, v42, v11
	v_mov_b32_e32 v18, v104
	v_pk_fma_f32 v[10:11], v[42:43], v[10:11], v[104:105]
	v_pk_fma_f32 v[18:19], v[44:45], v[12:13], v[18:19]
	v_pk_fma_f32 v[10:11], v[46:47], v[12:13], v[10:11]
	v_pk_fma_f32 v[12:13], v[48:49], v[14:15], v[18:19]
	v_pk_fma_f32 v[10:11], v[50:51], v[14:15], v[10:11]
	v_pk_fma_f32 v[12:13], v[52:53], v[16:17], v[12:13]
	v_pk_fma_f32 v[10:11], v[54:55], v[16:17], v[10:11]
	v_pk_fma_f32 v[12:13], v[56:57], v[26:27], v[12:13]
	v_pk_fma_f32 v[10:11], v[58:59], v[26:27], v[10:11]
	v_pk_fma_f32 v[12:13], v[60:61], v[28:29], v[12:13]
	v_pk_fma_f32 v[10:11], v[62:63], v[28:29], v[10:11]
	v_pk_fma_f32 v[12:13], v[64:65], v[30:31], v[12:13]
	v_pk_fma_f32 v[10:11], v[66:67], v[30:31], v[10:11]
	v_pk_fma_f32 v[12:13], v[68:69], v[32:33], v[12:13]
	v_pk_fma_f32 v[20:21], v[72:73], v[32:33], v[20:21]
	v_pk_fma_f32 v[10:11], v[70:71], v[32:33], v[10:11]
	v_pk_fma_f32 v[12:13], v[72:73], v[40:41], v[12:13]
	v_pk_fma_f32 v[20:21], v[76:77], v[40:41], v[20:21]
	v_pk_fma_f32 v[10:11], v[74:75], v[40:41], v[10:11]
	v_pk_fma_f32 v[12:13], v[76:77], v[156:157], v[12:13]
	v_pk_fma_f32 v[20:21], v[80:81], v[156:157], v[20:21]
	v_pk_fma_f32 v[10:11], v[78:79], v[156:157], v[10:11]
	v_pk_fma_f32 v[12:13], v[80:81], v[158:159], v[12:13]
	v_pk_fma_f32 v[20:21], v[84:85], v[158:159], v[20:21]
	v_pk_fma_f32 v[10:11], v[82:83], v[158:159], v[10:11]
	v_pk_fma_f32 v[12:13], v[84:85], v[160:161], v[12:13]
	v_pk_fma_f32 v[20:21], v[88:89], v[160:161], v[20:21]
	v_pk_fma_f32 v[10:11], v[86:87], v[160:161], v[10:11]
	v_pk_fma_f32 v[12:13], v[88:89], v[24:25], v[12:13]
	v_pk_fma_f32 v[20:21], v[92:93], v[24:25], v[20:21]
	v_pk_fma_f32 v[10:11], v[90:91], v[24:25], v[10:11]
	v_pk_fma_f32 v[12:13], v[92:93], v[34:35], v[12:13]
	v_pk_fma_f32 v[20:21], v[96:97], v[34:35], v[20:21]
	v_pk_fma_f32 v[10:11], v[94:95], v[34:35], v[10:11]
	v_pk_fma_f32 v[12:13], v[96:97], v[36:37], v[12:13]
	v_pk_fma_f32 v[20:21], v[100:101], v[36:37], v[20:21]
	v_pk_fma_f32 v[10:11], v[98:99], v[36:37], v[10:11]
	v_pk_fma_f32 v[12:13], v[100:101], v[38:39], v[12:13]
	v_add_u32_e32 v105, s6, v162
	v_add_f32_e32 v20, v20, v21
	v_add_f32_e32 v10, v10, v11
	v_add_f32_e32 v11, v12, v13
	s_barrier
	ds_write2st64_b32 v163, v164, v165 offset1:4
	ds_write2st64_b32 v163, v166, v167 offset0:8 offset1:12
	ds_write2st64_b32 v163, v168, v169 offset0:16 offset1:20
	ds_write2st64_b32 v163, v170, v171 offset0:24 offset1:28
	ds_write2st64_b32 v163, v174, v175 offset0:32 offset1:36
	ds_write2st64_b32 v163, v176, v177 offset0:40 offset1:44
	ds_write2st64_b32 v163, v178, v179 offset0:48 offset1:52
	ds_write2st64_b32 v163, v180, v181 offset0:56 offset1:60
	ds_write2st64_b32 v163, v182, v183 offset0:64 offset1:68
	ds_write2st64_b32 v163, v184, v185 offset0:72 offset1:76
	ds_write2st64_b32 v163, v186, v187 offset0:80 offset1:84
	ds_write2st64_b32 v163, v188, v189 offset0:88 offset1:92
	ds_write2st64_b32 v163, v190, v172 offset0:96 offset1:100
	ds_write2st64_b32 v163, v173, v22 offset0:104 offset1:108
	ds_write2st64_b32 v163, v23, v20 offset0:112 offset1:116
	ds_write2st64_b32 v163, v10, v11 offset0:120 offset1:124
	s_waitcnt lgkmcnt(0)
	s_barrier
	ds_read_b128 v[38:41], v105
	ds_read_b128 v[14:17], v105 offset:49152
	ds_read_b128 v[34:37], v105 offset:8192
	ds_read_b128 v[30:33], v105 offset:16384
	ds_read_b128 v[26:29], v105 offset:24576
	s_waitcnt lgkmcnt(4)
	v_mov_b32_e32 v10, v39
	v_mov_b32_e32 v11, v40
	v_mov_b32_e32 v12, v38
	v_mov_b32_e32 v13, v41
	v_pk_add_f32 v[10:11], v[10:11], v[12:13]
	s_waitcnt lgkmcnt(2)
	v_mov_b32_e32 v12, v34
	v_add_f32_e32 v160, v10, v11
	v_mov_b32_e32 v10, v35
	v_mov_b32_e32 v11, v36
	v_mov_b32_e32 v13, v37
	v_pk_add_f32 v[10:11], v[10:11], v[12:13]
	ds_read_b128 v[22:25], v105 offset:32768
	ds_read_b128 v[18:21], v105 offset:40960
	v_add_f32_e32 v161, v10, v11
	s_waitcnt lgkmcnt(3)
	v_mov_b32_e32 v10, v31
	v_mov_b32_e32 v11, v32
	v_mov_b32_e32 v12, v30
	v_mov_b32_e32 v13, v33
	v_pk_add_f32 v[10:11], v[10:11], v[12:13]
	s_waitcnt lgkmcnt(2)
	v_mov_b32_e32 v12, v26
	v_add_f32_e32 v162, v10, v11
	v_mov_b32_e32 v10, v27
	v_mov_b32_e32 v11, v28
	v_mov_b32_e32 v13, v29
	v_pk_add_f32 v[10:11], v[10:11], v[12:13]
	s_waitcnt lgkmcnt(1)
	v_mov_b32_e32 v12, v22
	v_add_f32_e32 v163, v10, v11
	v_mov_b32_e32 v10, v23
	v_mov_b32_e32 v11, v24
	v_mov_b32_e32 v13, v25
	v_pk_add_f32 v[10:11], v[10:11], v[12:13]
	s_waitcnt lgkmcnt(0)
	v_mov_b32_e32 v12, v18
	v_add_f32_e32 v164, v10, v11
	v_mov_b32_e32 v10, v19
	v_mov_b32_e32 v11, v20
	v_mov_b32_e32 v13, v21
	v_pk_add_f32 v[10:11], v[10:11], v[12:13]
	v_mov_b32_e32 v12, v14
	v_add_f32_e32 v165, v10, v11
	v_mov_b32_e32 v10, v15
	v_mov_b32_e32 v11, v16
	v_mov_b32_e32 v13, v17
	v_pk_add_f32 v[10:11], v[10:11], v[12:13]
	s_cmpk_gt_i32 s65, 0x1df
	v_add_f32_e32 v166, v10, v11
	ds_read_b128 v[10:13], v105 offset:57344
	s_waitcnt lgkmcnt(0)
	v_mov_b32_e32 v156, v11
	v_mov_b32_e32 v157, v12
	v_mov_b32_e32 v158, v10
	v_mov_b32_e32 v159, v13
	v_pk_add_f32 v[156:157], v[156:157], v[158:159]
	v_add_f32_dpp v158, v162, v162 quad_perm:[1,0,3,2] row_mask:0xf bank_mask:0xf bound_ctrl:1
	v_add_f32_e32 v105, v156, v157
	v_add_f32_dpp v156, v160, v160 quad_perm:[1,0,3,2] row_mask:0xf bank_mask:0xf bound_ctrl:1
	v_add_f32_dpp v157, v161, v161 quad_perm:[1,0,3,2] row_mask:0xf bank_mask:0xf bound_ctrl:1
	v_add_f32_dpp v159, v163, v163 quad_perm:[1,0,3,2] row_mask:0xf bank_mask:0xf bound_ctrl:1
	v_add_f32_dpp v156, v156, v156 quad_perm:[2,3,0,1] row_mask:0xf bank_mask:0xf bound_ctrl:1
	v_add_f32_dpp v157, v157, v157 quad_perm:[2,3,0,1] row_mask:0xf bank_mask:0xf bound_ctrl:1
	s_nop 0
	v_add_f32_dpp v156, v156, v156 row_half_mirror row_mask:0xf bank_mask:0xf bound_ctrl:1
	s_nop 0
	v_add_f32_dpp v157, v157, v157 row_half_mirror row_mask:0xf bank_mask:0xf bound_ctrl:1
	v_add_f32_dpp v158, v158, v158 quad_perm:[2,3,0,1] row_mask:0xf bank_mask:0xf bound_ctrl:1
	v_add_f32_dpp v156, v156, v156 row_mirror row_mask:0xf bank_mask:0xf bound_ctrl:1
	v_add_f32_dpp v157, v157, v157 row_mirror row_mask:0xf bank_mask:0xf bound_ctrl:1
	v_add_f32_dpp v158, v158, v158 row_half_mirror row_mask:0xf bank_mask:0xf bound_ctrl:1
	v_add_f32_dpp v156, v156, v156 row_bcast:15 row_mask:0xa bank_mask:0xf
	v_add_f32_dpp v159, v159, v159 quad_perm:[2,3,0,1] row_mask:0xf bank_mask:0xf bound_ctrl:1
	v_add_f32_dpp v158, v158, v158 row_mirror row_mask:0xf bank_mask:0xf bound_ctrl:1
	v_add_f32_dpp v157, v157, v157 row_bcast:15 row_mask:0xa bank_mask:0xf
	v_add_f32_dpp v160, v164, v164 quad_perm:[1,0,3,2] row_mask:0xf bank_mask:0xf bound_ctrl:1
	v_add_f32_dpp v159, v159, v159 row_half_mirror row_mask:0xf bank_mask:0xf bound_ctrl:1
	v_add_f32_dpp v158, v158, v158 row_bcast:15 row_mask:0xa bank_mask:0xf
	v_add_f32_dpp v160, v160, v160 quad_perm:[2,3,0,1] row_mask:0xf bank_mask:0xf bound_ctrl:1
	v_add_f32_dpp v159, v159, v159 row_mirror row_mask:0xf bank_mask:0xf bound_ctrl:1
	v_add_f32_dpp v161, v165, v165 quad_perm:[1,0,3,2] row_mask:0xf bank_mask:0xf bound_ctrl:1
	v_add_f32_dpp v160, v160, v160 row_half_mirror row_mask:0xf bank_mask:0xf bound_ctrl:1
	v_add_f32_dpp v159, v159, v159 row_bcast:15 row_mask:0xa bank_mask:0xf
	v_add_f32_dpp v161, v161, v161 quad_perm:[2,3,0,1] row_mask:0xf bank_mask:0xf bound_ctrl:1
	v_add_f32_dpp v160, v160, v160 row_mirror row_mask:0xf bank_mask:0xf bound_ctrl:1
	v_add_f32_dpp v162, v166, v166 quad_perm:[1,0,3,2] row_mask:0xf bank_mask:0xf bound_ctrl:1
	v_add_f32_dpp v161, v161, v161 row_half_mirror row_mask:0xf bank_mask:0xf bound_ctrl:1
	v_add_f32_dpp v160, v160, v160 row_bcast:15 row_mask:0xa bank_mask:0xf
	v_add_f32_dpp v162, v162, v162 quad_perm:[2,3,0,1] row_mask:0xf bank_mask:0xf bound_ctrl:1
	v_add_f32_dpp v161, v161, v161 row_mirror row_mask:0xf bank_mask:0xf bound_ctrl:1
	v_add_f32_dpp v105, v105, v105 quad_perm:[1,0,3,2] row_mask:0xf bank_mask:0xf bound_ctrl:1
	v_add_f32_dpp v162, v162, v162 row_half_mirror row_mask:0xf bank_mask:0xf bound_ctrl:1
	v_add_f32_dpp v161, v161, v161 row_bcast:15 row_mask:0xa bank_mask:0xf
	v_add_f32_dpp v105, v105, v105 quad_perm:[2,3,0,1] row_mask:0xf bank_mask:0xf bound_ctrl:1
	v_add_f32_dpp v162, v162, v162 row_mirror row_mask:0xf bank_mask:0xf bound_ctrl:1
	s_nop 0
	v_add_f32_dpp v105, v105, v105 row_half_mirror row_mask:0xf bank_mask:0xf bound_ctrl:1
	s_nop 0
	v_add_f32_dpp v162, v162, v162 row_bcast:15 row_mask:0xa bank_mask:0xf
	v_add_f32_dpp v105, v105, v105 row_mirror row_mask:0xf bank_mask:0xf bound_ctrl:1
	s_nop 1
	v_add_f32_dpp v105, v105, v105 row_bcast:15 row_mask:0xa bank_mask:0xf
	s_nop 1
	v_add_f32_dpp v156, v156, v156 row_bcast:31 row_mask:0xc bank_mask:0xf
	s_nop 0
	v_readlane_b32 s6, v156, 63
	s_nop 0
	v_add_f32_dpp v157, v157, v157 row_bcast:31 row_mask:0xc bank_mask:0xf
	v_fma_f32 v39, s6, v239, v39
	v_fma_f32 v38, s6, v239, v38
	v_add_f32_dpp v158, v158, v158 row_bcast:31 row_mask:0xc bank_mask:0xf
	v_fma_f32 v41, s6, v239, v41
	v_fmac_f32_e32 v40, s6, v239
	v_add_f32_dpp v159, v159, v159 row_bcast:31 row_mask:0xc bank_mask:0xf
	v_readlane_b32 s7, v157, 63
	v_readlane_b32 s8, v158, 63
	v_add_f32_dpp v160, v160, v160 row_bcast:31 row_mask:0xc bank_mask:0xf
	v_readlane_b32 s9, v159, 63
	v_pk_mul_f32 v[156:157], v[40:41], v[40:41]
	v_add_f32_dpp v161, v161, v161 row_bcast:31 row_mask:0xc bank_mask:0xf
	v_pk_mul_f32 v[158:159], v[38:39], v[38:39]
	v_readlane_b32 s10, v160, 63
	v_add_f32_dpp v162, v162, v162 row_bcast:31 row_mask:0xc bank_mask:0xf
	v_readlane_b32 s11, v161, 63
	v_pk_mov_b32 v[160:161], v[158:159], v[156:157] op_sel:[1,0]
	v_add_f32_dpp v105, v105, v105 row_bcast:31 row_mask:0xc bank_mask:0xf
	v_mov_b32_e32 v159, v157
	v_pk_add_f32 v[156:157], v[160:161], v[158:159]
	v_fma_f32 v35, s7, v239, v35
	v_fma_f32 v34, s7, v239, v34
	v_fma_f32 v37, s7, v239, v37
	v_fmac_f32_e32 v36, s7, v239
	v_readlane_b32 s67, v105, 63
	v_add_f32_e32 v105, v156, v157
	v_pk_mul_f32 v[156:157], v[36:37], v[36:37]
	v_pk_mul_f32 v[158:159], v[34:35], v[34:35]
	v_fma_f32 v31, s8, v239, v31
	v_pk_mov_b32 v[160:161], v[158:159], v[156:157] op_sel:[1,0]
	v_mov_b32_e32 v159, v157
	v_pk_add_f32 v[156:157], v[160:161], v[158:159]
	v_fma_f32 v30, s8, v239, v30
	v_fma_f32 v33, s8, v239, v33
	v_fmac_f32_e32 v32, s8, v239
	v_readlane_b32 s66, v162, 63
	v_add_f32_e32 v162, v156, v157
	v_pk_mul_f32 v[156:157], v[32:33], v[32:33]
	v_pk_mul_f32 v[158:159], v[30:31], v[30:31]
	v_fma_f32 v27, s9, v239, v27
	v_pk_mov_b32 v[160:161], v[158:159], v[156:157] op_sel:[1,0]
	v_mov_b32_e32 v159, v157
	v_pk_add_f32 v[156:157], v[160:161], v[158:159]
	v_fma_f32 v26, s9, v239, v26
	v_fma_f32 v29, s9, v239, v29
	v_fmac_f32_e32 v28, s9, v239
	v_add_f32_e32 v163, v156, v157
	v_pk_mul_f32 v[156:157], v[28:29], v[28:29]
	v_pk_mul_f32 v[158:159], v[26:27], v[26:27]
	v_fma_f32 v23, s10, v239, v23
	v_pk_mov_b32 v[160:161], v[158:159], v[156:157] op_sel:[1,0]
	v_mov_b32_e32 v159, v157
	v_pk_add_f32 v[156:157], v[160:161], v[158:159]
	v_fma_f32 v22, s10, v239, v22
	v_fma_f32 v25, s10, v239, v25
	v_fmac_f32_e32 v24, s10, v239
	v_add_f32_e32 v164, v156, v157
	v_pk_mul_f32 v[156:157], v[24:25], v[24:25]
	v_pk_mul_f32 v[158:159], v[22:23], v[22:23]
	v_fma_f32 v19, s11, v239, v19
	v_pk_mov_b32 v[160:161], v[158:159], v[156:157] op_sel:[1,0]
	v_mov_b32_e32 v159, v157
	v_pk_add_f32 v[156:157], v[160:161], v[158:159]
	v_fma_f32 v18, s11, v239, v18
	v_fma_f32 v21, s11, v239, v21
	v_fmac_f32_e32 v20, s11, v239
	v_add_f32_e32 v165, v156, v157
	v_pk_mul_f32 v[156:157], v[20:21], v[20:21]
	v_pk_mul_f32 v[158:159], v[18:19], v[18:19]
	v_fma_f32 v15, s66, v239, v15
	v_pk_mov_b32 v[160:161], v[158:159], v[156:157] op_sel:[1,0]
	v_mov_b32_e32 v159, v157
	v_pk_add_f32 v[156:157], v[160:161], v[158:159]
	v_fma_f32 v14, s66, v239, v14
	v_fma_f32 v17, s66, v239, v17
	v_fmac_f32_e32 v16, s66, v239
	v_add_f32_e32 v166, v156, v157
	v_pk_mul_f32 v[156:157], v[16:17], v[16:17]
	v_pk_mul_f32 v[158:159], v[14:15], v[14:15]
	v_fma_f32 v11, s67, v239, v11
	v_pk_mov_b32 v[160:161], v[158:159], v[156:157] op_sel:[1,0]
	v_mov_b32_e32 v159, v157
	v_pk_add_f32 v[156:157], v[160:161], v[158:159]
	v_fma_f32 v10, s67, v239, v10
	v_fma_f32 v13, s67, v239, v13
	v_fmac_f32_e32 v12, s67, v239
	v_add_f32_e32 v167, v156, v157
	v_pk_mul_f32 v[156:157], v[12:13], v[12:13]
	v_pk_mul_f32 v[158:159], v[10:11], v[10:11]
	v_add_f32_dpp v105, v105, v105 quad_perm:[1,0,3,2] row_mask:0xf bank_mask:0xf bound_ctrl:1
	v_pk_mov_b32 v[160:161], v[158:159], v[156:157] op_sel:[1,0]
	v_mov_b32_e32 v159, v157
	v_pk_add_f32 v[156:157], v[160:161], v[158:159]
	v_add_f32_dpp v105, v105, v105 quad_perm:[2,3,0,1] row_mask:0xf bank_mask:0xf bound_ctrl:1
	v_add_f32_e32 v156, v156, v157
	v_add_f32_dpp v157, v162, v162 quad_perm:[1,0,3,2] row_mask:0xf bank_mask:0xf bound_ctrl:1
	v_add_f32_dpp v105, v105, v105 row_half_mirror row_mask:0xf bank_mask:0xf bound_ctrl:1
	v_add_f32_dpp v158, v163, v163 quad_perm:[1,0,3,2] row_mask:0xf bank_mask:0xf bound_ctrl:1
	v_add_f32_dpp v157, v157, v157 quad_perm:[2,3,0,1] row_mask:0xf bank_mask:0xf bound_ctrl:1
	v_add_f32_dpp v105, v105, v105 row_mirror row_mask:0xf bank_mask:0xf bound_ctrl:1
	s_nop 0
	v_add_f32_dpp v157, v157, v157 row_half_mirror row_mask:0xf bank_mask:0xf bound_ctrl:1
	v_add_f32_dpp v158, v158, v158 quad_perm:[2,3,0,1] row_mask:0xf bank_mask:0xf bound_ctrl:1
	v_add_f32_dpp v105, v105, v105 row_bcast:15 row_mask:0xa bank_mask:0xf
	v_add_f32_dpp v157, v157, v157 row_mirror row_mask:0xf bank_mask:0xf bound_ctrl:1
	v_add_f32_dpp v159, v164, v164 quad_perm:[1,0,3,2] row_mask:0xf bank_mask:0xf bound_ctrl:1
	v_add_f32_dpp v158, v158, v158 row_half_mirror row_mask:0xf bank_mask:0xf bound_ctrl:1
	v_add_f32_dpp v157, v157, v157 row_bcast:15 row_mask:0xa bank_mask:0xf
	v_add_f32_dpp v159, v159, v159 quad_perm:[2,3,0,1] row_mask:0xf bank_mask:0xf bound_ctrl:1
	v_add_f32_dpp v158, v158, v158 row_mirror row_mask:0xf bank_mask:0xf bound_ctrl:1
	v_add_f32_dpp v160, v165, v165 quad_perm:[1,0,3,2] row_mask:0xf bank_mask:0xf bound_ctrl:1
	v_add_f32_dpp v159, v159, v159 row_half_mirror row_mask:0xf bank_mask:0xf bound_ctrl:1
	v_add_f32_dpp v158, v158, v158 row_bcast:15 row_mask:0xa bank_mask:0xf
	v_add_f32_dpp v160, v160, v160 quad_perm:[2,3,0,1] row_mask:0xf bank_mask:0xf bound_ctrl:1
	v_add_f32_dpp v159, v159, v159 row_mirror row_mask:0xf bank_mask:0xf bound_ctrl:1
	v_add_f32_dpp v161, v166, v166 quad_perm:[1,0,3,2] row_mask:0xf bank_mask:0xf bound_ctrl:1
	v_add_f32_dpp v160, v160, v160 row_half_mirror row_mask:0xf bank_mask:0xf bound_ctrl:1
	v_add_f32_dpp v159, v159, v159 row_bcast:15 row_mask:0xa bank_mask:0xf
	v_add_f32_dpp v161, v161, v161 quad_perm:[2,3,0,1] row_mask:0xf bank_mask:0xf bound_ctrl:1
	v_add_f32_dpp v160, v160, v160 row_mirror row_mask:0xf bank_mask:0xf bound_ctrl:1
	v_add_f32_dpp v162, v167, v167 quad_perm:[1,0,3,2] row_mask:0xf bank_mask:0xf bound_ctrl:1
	v_add_f32_dpp v161, v161, v161 row_half_mirror row_mask:0xf bank_mask:0xf bound_ctrl:1
	v_add_f32_dpp v160, v160, v160 row_bcast:15 row_mask:0xa bank_mask:0xf
	v_add_f32_dpp v162, v162, v162 quad_perm:[2,3,0,1] row_mask:0xf bank_mask:0xf bound_ctrl:1
	v_add_f32_dpp v161, v161, v161 row_mirror row_mask:0xf bank_mask:0xf bound_ctrl:1
	v_add_f32_dpp v156, v156, v156 quad_perm:[1,0,3,2] row_mask:0xf bank_mask:0xf bound_ctrl:1
	v_add_f32_dpp v162, v162, v162 row_half_mirror row_mask:0xf bank_mask:0xf bound_ctrl:1
	v_add_f32_dpp v161, v161, v161 row_bcast:15 row_mask:0xa bank_mask:0xf
	v_add_f32_dpp v156, v156, v156 quad_perm:[2,3,0,1] row_mask:0xf bank_mask:0xf bound_ctrl:1
	v_add_f32_dpp v162, v162, v162 row_mirror row_mask:0xf bank_mask:0xf bound_ctrl:1
	s_nop 0
	v_add_f32_dpp v156, v156, v156 row_half_mirror row_mask:0xf bank_mask:0xf bound_ctrl:1
	s_nop 0
	v_add_f32_dpp v162, v162, v162 row_bcast:15 row_mask:0xa bank_mask:0xf
	v_add_f32_dpp v156, v156, v156 row_mirror row_mask:0xf bank_mask:0xf bound_ctrl:1
	s_nop 1
	v_add_f32_dpp v156, v156, v156 row_bcast:15 row_mask:0xa bank_mask:0xf
	s_nop 1
	v_add_f32_dpp v105, v105, v105 row_bcast:31 row_mask:0xc bank_mask:0xf
	s_nop 0
	v_readlane_b32 s8, v105, 63
	s_nop 0
	v_add_f32_dpp v157, v157, v157 row_bcast:31 row_mask:0xc bank_mask:0xf
	v_fma_f32 v105, s8, v235, v225
	v_readlane_b32 s9, v157, 63
	v_add_f32_dpp v158, v158, v158 row_bcast:31 row_mask:0xc bank_mask:0xf
	s_nop 0
	v_readlane_b32 s69, v158, 63
	s_nop 0
	v_add_f32_dpp v159, v159, v159 row_bcast:31 row_mask:0xc bank_mask:0xf
	s_nop 0
	v_readlane_b32 s68, v159, 63
	s_nop 0
	v_add_f32_dpp v160, v160, v160 row_bcast:31 row_mask:0xc bank_mask:0xf
	s_nop 0
	v_readlane_b32 s67, v160, 63
	s_nop 0
	v_add_f32_dpp v161, v161, v161 row_bcast:31 row_mask:0xc bank_mask:0xf
	s_nop 0
	v_readlane_b32 s66, v161, 63
	s_nop 0
	v_add_f32_dpp v162, v162, v162 row_bcast:31 row_mask:0xc bank_mask:0xf
	v_mov_b32_e32 v163, v131
	v_readlane_b32 s7, v162, 63
	s_nop 0
	v_mov_b32_dpp v163, v156 row_bcast:31 row_mask:0xc bank_mask:0xf
	v_add_f32_e32 v156, v156, v163
	s_nop 0
	v_readlane_b32 s6, v156, 63
	v_rsq_f32_e32 v156, v105
	s_nop 0
	v_pk_mul_f32 v[38:39], v[38:39], v[156:157] op_sel_hi:[1,0]
	v_pk_fma_f32 v[38:39], v[2:3], v[38:39], v[6:7]
	v_pk_mul_f32 v[40:41], v[40:41], v[156:157] op_sel_hi:[1,0]
	v_mul_f32_e32 v105, 0xbfb8aa3b, v38
	v_exp_f32_e32 v105, v105
	v_pk_fma_f32 v[40:41], v[4:5], v[40:41], v[8:9]
	v_add_f32_e32 v105, 1.0, v105
	v_rcp_f32_e32 v156, v105
	v_mul_f32_e32 v105, 0xbfb8aa3b, v39
	v_exp_f32_e32 v105, v105
	s_nop 0
	v_add_f32_e32 v105, 1.0, v105
	v_rcp_f32_e32 v157, v105
	v_mul_f32_e32 v105, 0xbfb8aa3b, v40
	v_exp_f32_e32 v105, v105
	v_pk_mul_f32 v[38:39], v[38:39], v[156:157]
	v_add_f32_e32 v105, 1.0, v105
	v_rcp_f32_e32 v156, v105
	v_mul_f32_e32 v105, 0xbfb8aa3b, v41
	v_exp_f32_e32 v105, v105
	s_nop 0
	v_add_f32_e32 v105, 1.0, v105
	v_rcp_f32_e32 v157, v105
	s_nop 0
	v_pk_mul_f32 v[40:41], v[40:41], v[156:157]
	v_cvt_pk_bf16_f32 v156, v38, v39
	v_fma_f32 v39, s9, v235, v225
	v_cvt_pk_bf16_f32 v157, v40, v41
	v_rsq_f32_e32 v40, v39
	v_lshlrev_b32_e32 v38, 3, v130
	global_store_dwordx2 v38, v[156:157], s[56:57] offset:512 sc1
	v_pk_mul_f32 v[34:35], v[34:35], v[40:41] op_sel_hi:[1,0]
	s_nop 0
	v_pk_fma_f32 v[34:35], v[2:3], v[34:35], v[6:7]
	v_pk_mul_f32 v[36:37], v[36:37], v[40:41] op_sel_hi:[1,0]
	v_mul_f32_e32 v39, 0xbfb8aa3b, v34
	v_exp_f32_e32 v39, v39
	v_pk_fma_f32 v[36:37], v[4:5], v[36:37], v[8:9]
	v_add_f32_e32 v39, 1.0, v39
	v_rcp_f32_e32 v40, v39
	v_mul_f32_e32 v39, 0xbfb8aa3b, v35
	v_exp_f32_e32 v39, v39
	s_nop 0
	v_add_f32_e32 v39, 1.0, v39
	v_rcp_f32_e32 v41, v39
	v_mul_f32_e32 v39, 0xbfb8aa3b, v36
	v_exp_f32_e32 v39, v39
	v_pk_mul_f32 v[34:35], v[34:35], v[40:41]
	s_nop 0
	v_cvt_pk_bf16_f32 v34, v34, v35
	v_add_f32_e32 v39, 1.0, v39
	v_rcp_f32_e32 v40, v39
	v_mul_f32_e32 v39, 0xbfb8aa3b, v37
	v_exp_f32_e32 v39, v39
	s_nop 0
	v_add_f32_e32 v39, 1.0, v39
	v_rcp_f32_e32 v41, v39
	s_nop 0
	v_pk_mul_f32 v[36:37], v[36:37], v[40:41]
	v_cvt_pk_bf16_f32 v35, v36, v37
	global_store_dwordx2 v38, v[34:35], s[54:55] offset:512 sc1
	v_fma_f32 v34, s69, v235, v225
	v_rsq_f32_e32 v34, v34
	s_nop 0
	v_pk_mul_f32 v[30:31], v[30:31], v[34:35] op_sel_hi:[1,0]
	v_pk_fma_f32 v[30:31], v[2:3], v[30:31], v[6:7]
	v_pk_mul_f32 v[32:33], v[32:33], v[34:35] op_sel_hi:[1,0]
	v_pk_mul_f32 v[34:35], v[30:31], s[96:97] op_sel_hi:[1,0]
	v_exp_f32_e32 v34, v34
	v_exp_f32_e32 v35, v35
	v_pk_fma_f32 v[32:33], v[4:5], v[32:33], v[8:9]
	v_pk_add_f32 v[34:35], v[34:35], 1.0 op_sel_hi:[1,0]
	v_rcp_f32_e32 v34, v34
	v_rcp_f32_e32 v35, v35
	s_nop 0
	v_pk_mul_f32 v[30:31], v[30:31], v[34:35]
	v_pk_mul_f32 v[34:35], v[32:33], s[96:97] op_sel_hi:[1,0]
	v_exp_f32_e32 v34, v34
	v_exp_f32_e32 v35, v35
	v_cvt_pk_bf16_f32 v30, v30, v31
	v_pk_add_f32 v[34:35], v[34:35], 1.0 op_sel_hi:[1,0]
	v_rcp_f32_e32 v34, v34
	v_rcp_f32_e32 v35, v35
	s_nop 0
	v_pk_mul_f32 v[32:33], v[32:33], v[34:35]
	v_cvt_pk_bf16_f32 v31, v32, v33
	global_store_dwordx2 v38, v[30:31], s[52:53] offset:512 sc1
	v_fma_f32 v30, s68, v235, v225
	v_rsq_f32_e32 v30, v30
	s_nop 0
	v_pk_mul_f32 v[26:27], v[26:27], v[30:31] op_sel_hi:[1,0]
	v_pk_fma_f32 v[26:27], v[2:3], v[26:27], v[6:7]
	v_pk_mul_f32 v[28:29], v[28:29], v[30:31] op_sel_hi:[1,0]
	v_pk_mul_f32 v[30:31], v[26:27], s[96:97] op_sel_hi:[1,0]
	v_exp_f32_e32 v30, v30
	v_exp_f32_e32 v31, v31
	v_pk_fma_f32 v[28:29], v[4:5], v[28:29], v[8:9]
	v_pk_add_f32 v[30:31], v[30:31], 1.0 op_sel_hi:[1,0]
	v_rcp_f32_e32 v30, v30
	v_rcp_f32_e32 v31, v31
	s_nop 0
	v_pk_mul_f32 v[26:27], v[26:27], v[30:31]
	v_pk_mul_f32 v[30:31], v[28:29], s[96:97] op_sel_hi:[1,0]
	v_exp_f32_e32 v30, v30
	v_exp_f32_e32 v31, v31
	v_cvt_pk_bf16_f32 v26, v26, v27
	v_pk_add_f32 v[30:31], v[30:31], 1.0 op_sel_hi:[1,0]
	v_rcp_f32_e32 v30, v30
	v_rcp_f32_e32 v31, v31
	s_nop 0
	v_pk_mul_f32 v[28:29], v[28:29], v[30:31]
	v_cvt_pk_bf16_f32 v27, v28, v29
	global_store_dwordx2 v38, v[26:27], s[50:51] offset:512 sc1
	v_fma_f32 v26, s67, v235, v225
	v_rsq_f32_e32 v26, v26
	s_nop 0
	v_pk_mul_f32 v[22:23], v[22:23], v[26:27] op_sel_hi:[1,0]
	v_pk_fma_f32 v[22:23], v[2:3], v[22:23], v[6:7]
	v_pk_mul_f32 v[24:25], v[24:25], v[26:27] op_sel_hi:[1,0]
	v_pk_mul_f32 v[26:27], v[22:23], s[96:97] op_sel_hi:[1,0]
	v_exp_f32_e32 v26, v26
	v_exp_f32_e32 v27, v27
	v_pk_fma_f32 v[24:25], v[4:5], v[24:25], v[8:9]
	v_pk_add_f32 v[26:27], v[26:27], 1.0 op_sel_hi:[1,0]
	v_rcp_f32_e32 v26, v26
	v_rcp_f32_e32 v27, v27
	s_nop 0
	v_pk_mul_f32 v[22:23], v[22:23], v[26:27]
	v_pk_mul_f32 v[26:27], v[24:25], s[96:97] op_sel_hi:[1,0]
	v_exp_f32_e32 v26, v26
	v_exp_f32_e32 v27, v27
	v_cvt_pk_bf16_f32 v22, v22, v23
	v_pk_add_f32 v[26:27], v[26:27], 1.0 op_sel_hi:[1,0]
	v_rcp_f32_e32 v26, v26
	v_rcp_f32_e32 v27, v27
	s_nop 0
	v_pk_mul_f32 v[24:25], v[24:25], v[26:27]
	v_cvt_pk_bf16_f32 v23, v24, v25
	global_store_dwordx2 v38, v[22:23], s[48:49] offset:512 sc1
	v_fma_f32 v22, s66, v235, v225
	v_rsq_f32_e32 v22, v22
	s_nop 0
	v_pk_mul_f32 v[18:19], v[18:19], v[22:23] op_sel_hi:[1,0]
	v_pk_fma_f32 v[18:19], v[2:3], v[18:19], v[6:7]
	v_pk_mul_f32 v[20:21], v[20:21], v[22:23] op_sel_hi:[1,0]
	v_pk_mul_f32 v[22:23], v[18:19], s[96:97] op_sel_hi:[1,0]
	v_exp_f32_e32 v22, v22
	v_exp_f32_e32 v23, v23
	v_pk_fma_f32 v[20:21], v[4:5], v[20:21], v[8:9]
	v_pk_add_f32 v[22:23], v[22:23], 1.0 op_sel_hi:[1,0]
	v_rcp_f32_e32 v22, v22
	v_rcp_f32_e32 v23, v23
	s_nop 0
	v_pk_mul_f32 v[18:19], v[18:19], v[22:23]
	v_pk_mul_f32 v[22:23], v[20:21], s[96:97] op_sel_hi:[1,0]
	v_exp_f32_e32 v22, v22
	v_exp_f32_e32 v23, v23
	v_cvt_pk_bf16_f32 v18, v18, v19
	v_pk_add_f32 v[22:23], v[22:23], 1.0 op_sel_hi:[1,0]
	v_rcp_f32_e32 v22, v22
	v_rcp_f32_e32 v23, v23
	s_nop 0
	v_pk_mul_f32 v[20:21], v[20:21], v[22:23]
	v_cvt_pk_bf16_f32 v19, v20, v21
	global_store_dwordx2 v38, v[18:19], s[46:47] offset:512 sc1
	v_fma_f32 v18, s7, v235, v225
	v_rsq_f32_e32 v18, v18
	s_nop 0
	v_pk_mul_f32 v[14:15], v[14:15], v[18:19] op_sel_hi:[1,0]
	v_pk_fma_f32 v[14:15], v[2:3], v[14:15], v[6:7]
	v_pk_mul_f32 v[16:17], v[16:17], v[18:19] op_sel_hi:[1,0]
	v_pk_mul_f32 v[18:19], v[14:15], s[96:97] op_sel_hi:[1,0]
	v_exp_f32_e32 v18, v18
	v_exp_f32_e32 v19, v19
	v_pk_fma_f32 v[16:17], v[4:5], v[16:17], v[8:9]
	v_pk_add_f32 v[18:19], v[18:19], 1.0 op_sel_hi:[1,0]
	v_rcp_f32_e32 v18, v18
	v_rcp_f32_e32 v19, v19
	s_nop 0
	v_pk_mul_f32 v[14:15], v[14:15], v[18:19]
	v_pk_mul_f32 v[18:19], v[16:17], s[96:97] op_sel_hi:[1,0]
	v_exp_f32_e32 v18, v18
	v_exp_f32_e32 v19, v19
	v_cvt_pk_bf16_f32 v14, v14, v15
	v_pk_add_f32 v[18:19], v[18:19], 1.0 op_sel_hi:[1,0]
	v_rcp_f32_e32 v18, v18
	v_rcp_f32_e32 v19, v19
	s_nop 0
	v_pk_mul_f32 v[16:17], v[16:17], v[18:19]
	v_cvt_pk_bf16_f32 v15, v16, v17
	global_store_dwordx2 v38, v[14:15], s[44:45] offset:512 sc1
	v_fma_f32 v14, s6, v235, v225
	v_rsq_f32_e32 v14, v14
	s_mov_b32 s6, s65
	v_pk_mul_f32 v[10:11], v[10:11], v[14:15] op_sel_hi:[1,0]
	v_pk_fma_f32 v[10:11], v[2:3], v[10:11], v[6:7]
	v_pk_mul_f32 v[12:13], v[12:13], v[14:15] op_sel_hi:[1,0]
	v_pk_mul_f32 v[14:15], v[10:11], s[96:97] op_sel_hi:[1,0]
	v_exp_f32_e32 v14, v14
	v_exp_f32_e32 v15, v15
	v_pk_fma_f32 v[12:13], v[4:5], v[12:13], v[8:9]
	v_pk_add_f32 v[14:15], v[14:15], 1.0 op_sel_hi:[1,0]
	v_rcp_f32_e32 v14, v14
	v_rcp_f32_e32 v15, v15
	s_nop 0
	v_pk_mul_f32 v[10:11], v[10:11], v[14:15]
	v_pk_mul_f32 v[14:15], v[12:13], s[96:97] op_sel_hi:[1,0]
	v_exp_f32_e32 v14, v14
	v_exp_f32_e32 v15, v15
	v_cvt_pk_bf16_f32 v10, v10, v11
	v_pk_add_f32 v[14:15], v[14:15], 1.0 op_sel_hi:[1,0]
	v_rcp_f32_e32 v14, v14
	v_rcp_f32_e32 v15, v15
	s_nop 0
	v_pk_mul_f32 v[12:13], v[12:13], v[14:15]
	v_cvt_pk_bf16_f32 v11, v12, v13
	global_store_dwordx2 v38, v[10:11], s[42:43] offset:512 sc1
	s_barrier
	s_cbranch_scc1 .LBB0_344

.LBB0_349:
	s_bitcmp1_b32 s28, 0
	s_cselect_b32 s6, 0x12400, 0
	s_add_i32 s6, s6, 0
	v_add_u32_e32 v1, s6, v130
	ds_read_b128 v[66:69], v1
	ds_read_b128 v[70:73], v1 offset:8192
	ds_read_b128 v[74:77], v1 offset:16384
	ds_read_b128 v[114:117], v1 offset:24576
	ds_read_b128 v[122:125], v1 offset:1024
	ds_read_b128 v[126:129], v1 offset:9216
	ds_read_b128 v[132:135], v1 offset:17408
	ds_read_b128 v[188:191], v1 offset:25600
	v_cvt_pk_bf16_f32 v121, v56, v57
	v_cvt_pk_bf16_f32 v120, v54, v55
	v_cvt_pk_bf16_f32 v119, v52, v53
	v_cvt_pk_bf16_f32 v118, v50, v51
	s_waitcnt lgkmcnt(7)
	s_nop 0
	v_mfma_f32_32x32x16_bf16 v[98:113], v[66:69], v[118:121], 0
	s_waitcnt lgkmcnt(6)
	v_mfma_f32_32x32x16_bf16 v[82:97], v[70:73], v[118:121], 0
	s_waitcnt lgkmcnt(5)
	v_mfma_f32_32x32x16_bf16 v[66:81], v[74:77], v[118:121], 0
	ds_read_b128 v[136:139], v1 offset:2048
	ds_read_b128 v[140:143], v1 offset:10240
	ds_read_b128 v[144:147], v1 offset:18432
	ds_read_b128 v[180:183], v1 offset:26624
	v_cvt_pk_bf16_f32 v207, v64, v65
	v_cvt_pk_bf16_f32 v206, v62, v63
	v_cvt_pk_bf16_f32 v205, v60, v61
	v_cvt_pk_bf16_f32 v204, v58, v59
	s_waitcnt lgkmcnt(7)
	s_nop 0
	v_mfma_f32_32x32x16_bf16 v[98:113], v[122:125], v[204:207], v[98:113]
	s_waitcnt lgkmcnt(6)
	v_mfma_f32_32x32x16_bf16 v[82:97], v[126:129], v[204:207], v[82:97]
	s_waitcnt lgkmcnt(5)
	v_mfma_f32_32x32x16_bf16 v[66:81], v[132:135], v[204:207], v[66:81]
	ds_read_b128 v[122:125], v1 offset:3072
	ds_read_b128 v[126:129], v1 offset:11264
	ds_read_b128 v[132:135], v1 offset:19456
	ds_read_b128 v[168:171], v1 offset:27648
	v_cvt_pk_bf16_f32 v199, v40, v41
	v_cvt_pk_bf16_f32 v198, v38, v39
	v_cvt_pk_bf16_f32 v197, v36, v37
	v_cvt_pk_bf16_f32 v196, v34, v35
	s_waitcnt lgkmcnt(7)
	s_nop 0
	v_mfma_f32_32x32x16_bf16 v[98:113], v[136:139], v[196:199], v[98:113]
	s_waitcnt lgkmcnt(6)
	v_mfma_f32_32x32x16_bf16 v[82:97], v[140:143], v[196:199], v[82:97]
	s_waitcnt lgkmcnt(5)
	v_mfma_f32_32x32x16_bf16 v[66:81], v[144:147], v[196:199], v[66:81]
	ds_read_b128 v[136:139], v1 offset:4096
	ds_read_b128 v[140:143], v1 offset:12288
	ds_read_b128 v[144:147], v1 offset:20480
	ds_read_b128 v[160:163], v1 offset:28672
	v_cvt_pk_bf16_f32 v195, v48, v49
	v_cvt_pk_bf16_f32 v194, v46, v47
	v_cvt_pk_bf16_f32 v193, v44, v45
	v_cvt_pk_bf16_f32 v192, v42, v43
	s_waitcnt lgkmcnt(7)
	s_nop 0
	v_mfma_f32_32x32x16_bf16 v[98:113], v[122:125], v[192:195], v[98:113]
	s_waitcnt lgkmcnt(6)
	v_mfma_f32_32x32x16_bf16 v[82:97], v[126:129], v[192:195], v[82:97]
	s_waitcnt lgkmcnt(5)
	v_mfma_f32_32x32x16_bf16 v[66:81], v[132:135], v[192:195], v[66:81]
	ds_read_b128 v[122:125], v1 offset:5120
	ds_read_b128 v[126:129], v1 offset:13312
	ds_read_b128 v[132:135], v1 offset:21504
	ds_read_b128 v[156:159], v1 offset:29696
	v_cvt_pk_bf16_f32 v187, v24, v25
	v_cvt_pk_bf16_f32 v186, v22, v23
	v_cvt_pk_bf16_f32 v185, v20, v21
	v_cvt_pk_bf16_f32 v184, v18, v19
	s_waitcnt lgkmcnt(7)
	s_nop 0
	v_mfma_f32_32x32x16_bf16 v[98:113], v[136:139], v[184:187], v[98:113]
	s_waitcnt lgkmcnt(6)
	v_mfma_f32_32x32x16_bf16 v[82:97], v[140:143], v[184:187], v[82:97]
	s_waitcnt lgkmcnt(5)
	v_mfma_f32_32x32x16_bf16 v[66:81], v[144:147], v[184:187], v[66:81]
	ds_read_b128 v[136:139], v1 offset:6144
	ds_read_b128 v[140:143], v1 offset:14336
	ds_read_b128 v[148:151], v1 offset:22528
	ds_read_b128 v[144:147], v1 offset:30720
	v_cvt_pk_bf16_f32 v175, v32, v33
	v_cvt_pk_bf16_f32 v174, v30, v31
	v_cvt_pk_bf16_f32 v173, v28, v29
	v_cvt_pk_bf16_f32 v172, v26, v27
	s_waitcnt lgkmcnt(7)
	s_nop 0
	v_mfma_f32_32x32x16_bf16 v[98:113], v[122:125], v[172:175], v[98:113]
	s_waitcnt lgkmcnt(6)
	v_mfma_f32_32x32x16_bf16 v[82:97], v[126:129], v[172:175], v[82:97]
	s_waitcnt lgkmcnt(5)
	v_mfma_f32_32x32x16_bf16 v[66:81], v[132:135], v[172:175], v[66:81]
	ds_read_b128 v[122:125], v1 offset:7168
	ds_read_b128 v[126:129], v1 offset:15360
	ds_read_b128 v[244:247], v1 offset:23552
	ds_read_b128 v[152:155], v1 offset:31744
	v_cvt_pk_bf16_f32 v167, v8, v9
	v_cvt_pk_bf16_f32 v166, v6, v7
	v_cvt_pk_bf16_f32 v165, v4, v5
	v_cvt_pk_bf16_f32 v164, v2, v3
	s_waitcnt lgkmcnt(7)
	s_nop 0
	v_mfma_f32_32x32x16_bf16 v[98:113], v[136:139], v[164:167], v[98:113]
	s_waitcnt lgkmcnt(6)
	v_mfma_f32_32x32x16_bf16 v[82:97], v[140:143], v[164:167], v[82:97]
	s_waitcnt lgkmcnt(5)
	v_mfma_f32_32x32x16_bf16 v[66:81], v[148:151], v[164:167], v[66:81]
	s_add_i32 s6, s6, 0x12000
	s_waitcnt lgkmcnt(0)
	s_barrier
	v_mov_b32_e32 v132, s6
	v_add_u32_e32 v133, s5, v1
	ds_read_b32 v228, v132
	ds_read_b128 v[216:219], v133 offset:57344
	ds_read_b128 v[208:211], v133 offset:58368
	ds_read_b128 v[212:215], v133 offset:59392
	ds_read_b128 v[200:203], v133 offset:60416
	ds_read_b128 v[148:151], v1 offset:32768
	ds_read_b128 v[140:143], v1 offset:33792
	ds_read_b128 v[136:139], v1 offset:34816
	ds_read_b128 v[132:135], v1 offset:35840
	v_cvt_pk_bf16_f32 v179, v16, v17
	v_cvt_pk_bf16_f32 v178, v14, v15
	v_cvt_pk_bf16_f32 v177, v12, v13
	v_cvt_pk_bf16_f32 v176, v10, v11
	s_waitcnt lgkmcnt(12)
	s_nop 0
	v_mfma_f32_32x32x16_bf16 v[98:113], v[122:125], v[176:179], v[98:113]
	s_waitcnt lgkmcnt(11)
	v_mfma_f32_32x32x16_bf16 v[82:97], v[126:129], v[176:179], v[82:97]
	s_waitcnt lgkmcnt(10)
	v_mfma_f32_32x32x16_bf16 v[66:81], v[244:247], v[176:179], v[66:81]
	s_waitcnt lgkmcnt(7)
	v_lshlrev_b32_e32 v122, 16, v216
	v_and_b32_e32 v123, 0xffff0000, v216
	s_nop 4
	v_add_f32_e64 v230, v122, -v98
	v_add_f32_e64 v231, v123, -v99
	v_mfma_f32_32x32x16_bf16 v[114:129], v[114:117], v[118:121], 0
	s_waitcnt lgkmcnt(5)
	v_lshlrev_b32_e32 v98, 16, v212
	v_and_b32_e32 v99, 0xffff0000, v212
	v_add_f32_e64 v98, v98, -v82
	v_add_f32_e64 v99, v99, -v83
	v_lshlrev_b32_e32 v82, 16, v217
	v_and_b32_e32 v83, 0xffff0000, v217
	v_pk_add_f32 v[82:83], v[82:83], v[100:101] neg_lo:[0,1] neg_hi:[0,1]
	v_lshlrev_b32_e32 v100, 16, v213
	v_mfma_f32_32x32x16_bf16 v[114:129], v[188:191], v[204:207], v[114:129]
	v_and_b32_e32 v101, 0xffff0000, v213
	v_add_f32_e64 v100, v100, -v84
	v_add_f32_e64 v101, v101, -v85
	v_lshlrev_b32_e32 v84, 16, v218
	v_and_b32_e32 v85, 0xffff0000, v218
	v_pk_add_f32 v[102:103], v[84:85], v[102:103] neg_lo:[0,1] neg_hi:[0,1]
	v_lshlrev_b32_e32 v84, 16, v214
	v_and_b32_e32 v85, 0xffff0000, v214
	v_mfma_f32_32x32x16_bf16 v[114:129], v[180:183], v[196:199], v[114:129]
	v_add_f32_e64 v188, v84, -v86
	v_add_f32_e64 v189, v85, -v87
	v_lshlrev_b32_e32 v84, 16, v219
	v_and_b32_e32 v85, 0xffff0000, v219
	v_lshlrev_b32_e32 v86, 16, v215
	v_and_b32_e32 v87, 0xffff0000, v215
	v_pk_add_f32 v[84:85], v[84:85], v[104:105] neg_lo:[0,1] neg_hi:[0,1]
	v_pk_add_f32 v[104:105], v[86:87], v[88:89] neg_lo:[0,1] neg_hi:[0,1]
	v_mfma_f32_32x32x16_bf16 v[114:129], v[168:171], v[192:195], v[114:129]
	v_lshlrev_b32_e32 v86, 16, v208
	v_and_b32_e32 v87, 0xffff0000, v208
	v_add_f32_e64 v106, v86, -v106
	v_add_f32_e64 v107, v87, -v107
	s_waitcnt lgkmcnt(4)
	v_lshlrev_b32_e32 v86, 16, v200
	v_and_b32_e32 v87, 0xffff0000, v200
	v_pk_add_f32 v[168:169], v[86:87], v[90:91] neg_lo:[0,1] neg_hi:[0,1]
	v_lshlrev_b32_e32 v86, 16, v209
	v_mfma_f32_32x32x16_bf16 v[114:129], v[160:163], v[184:187], v[114:129]
	v_and_b32_e32 v87, 0xffff0000, v209
	v_lshlrev_b32_e32 v88, 16, v201
	v_and_b32_e32 v89, 0xffff0000, v201
	v_add_f32_e64 v86, v86, -v108
	v_add_f32_e64 v87, v87, -v109
	v_pk_add_f32 v[108:109], v[88:89], v[92:93] neg_lo:[0,1] neg_hi:[0,1]
	v_lshlrev_b32_e32 v88, 16, v210
	v_and_b32_e32 v89, 0xffff0000, v210
	v_mfma_f32_32x32x16_bf16 v[114:129], v[156:159], v[172:175], v[114:129]
	v_add_f32_e64 v90, v88, -v110
	v_add_f32_e64 v91, v89, -v111
	v_lshlrev_b32_e32 v88, 16, v202
	v_and_b32_e32 v89, 0xffff0000, v202
	v_add_f32_e64 v94, v88, -v94
	v_add_f32_e64 v95, v89, -v95
	v_lshlrev_b32_e32 v88, 16, v211
	v_and_b32_e32 v89, 0xffff0000, v211
	v_lshlrev_b32_e32 v92, 16, v203
	v_mfma_f32_32x32x16_bf16 v[114:129], v[144:147], v[164:167], v[114:129]
	v_and_b32_e32 v93, 0xffff0000, v203
	v_add_f32_e64 v88, v88, -v112
	v_add_f32_e64 v89, v89, -v113
	v_add_f32_e64 v96, v92, -v96
	v_add_f32_e64 v97, v93, -v97
	v_cvt_pk_bf16_f32 v85, v84, v85
	v_cvt_pk_bf16_f32 v84, v102, v103
	v_cvt_pk_bf16_f32 v83, v82, v83
	v_cvt_pk_bf16_f32 v82, v230, v231
	v_cvt_pk_bf16_f32 v89, v88, v89
	v_cvt_pk_bf16_f32 v88, v90, v91
	v_cvt_pk_bf16_f32 v87, v86, v87
	v_mfma_f32_32x32x16_bf16 v[114:129], v[152:155], v[176:179], v[114:129]
	v_cvt_pk_bf16_f32 v86, v106, v107
	v_cvt_pk_bf16_f32 v93, v104, v105
	v_cvt_pk_bf16_f32 v92, v188, v189
	v_cvt_pk_bf16_f32 v91, v100, v101
	v_cvt_pk_bf16_f32 v90, v98, v99
	v_cvt_pk_bf16_f32 v97, v96, v97
	v_cvt_pk_bf16_f32 v96, v94, v95
	v_cvt_pk_bf16_f32 v95, v108, v109
	v_cvt_pk_bf16_f32 v94, v168, v169
	ds_read_b128 v[98:101], v1 offset:36864
	ds_read_b128 v[102:105], v1 offset:37888
	ds_read_b128 v[106:109], v1 offset:38912
	ds_read_b128 v[110:113], v1 offset:39936
	s_waitcnt lgkmcnt(7)
	v_mfma_f32_32x32x16_bf16 v[66:81], v[148:151], v[82:85], v[66:81]
	s_waitcnt lgkmcnt(6)
	v_mfma_f32_32x32x16_bf16 v[66:81], v[140:143], v[86:89], v[66:81]
	s_waitcnt lgkmcnt(5)
	v_mfma_f32_32x32x16_bf16 v[66:81], v[136:139], v[90:93], v[66:81]
	s_waitcnt lgkmcnt(4)
	v_mfma_f32_32x32x16_bf16 v[66:81], v[132:135], v[94:97], v[66:81]
	ds_read_b128 v[132:135], v1 offset:40960
	ds_read_b128 v[136:139], v1 offset:41984
	ds_read_b128 v[140:143], v1 offset:43008
	ds_read_b128 v[144:147], v1 offset:44032
	s_waitcnt lgkmcnt(7)
	v_mfma_f32_32x32x16_bf16 v[114:129], v[98:101], v[82:85], v[114:129]
	s_waitcnt lgkmcnt(6)
	v_mfma_f32_32x32x16_bf16 v[114:129], v[102:105], v[86:89], v[114:129]
	s_waitcnt lgkmcnt(5)
	v_mfma_f32_32x32x16_bf16 v[114:129], v[106:109], v[90:93], v[114:129]
	s_waitcnt lgkmcnt(4)
	v_mfma_f32_32x32x16_bf16 v[114:129], v[110:113], v[94:97], v[114:129]
	ds_read_b128 v[98:101], v1 offset:45056
	ds_read_b128 v[102:105], v1 offset:46080
	ds_read_b128 v[106:109], v1 offset:47104
	ds_read_b128 v[110:113], v1 offset:48128
	v_mul_f32_e64 v64, v64, v228
	v_mul_f32_e64 v65, v65, v228
	v_pk_mul_f32 v[62:63], v[62:63], v[228:229] op_sel_hi:[1,0]
	v_pk_mul_f32 v[60:61], v[60:61], v[228:229] op_sel_hi:[1,0]
	v_pk_mul_f32 v[58:59], v[58:59], v[228:229] op_sel_hi:[1,0]
	v_pk_mul_f32 v[56:57], v[56:57], v[228:229] op_sel_hi:[1,0]
	v_pk_mul_f32 v[54:55], v[54:55], v[228:229] op_sel_hi:[1,0]
	v_pk_mul_f32 v[52:53], v[52:53], v[228:229] op_sel_hi:[1,0]
	v_pk_mul_f32 v[50:51], v[50:51], v[228:229] op_sel_hi:[1,0]
	v_pk_mul_f32 v[48:49], v[48:49], v[228:229] op_sel_hi:[1,0]
	v_pk_mul_f32 v[46:47], v[46:47], v[228:229] op_sel_hi:[1,0]
	v_pk_mul_f32 v[44:45], v[44:45], v[228:229] op_sel_hi:[1,0]
	v_pk_mul_f32 v[42:43], v[42:43], v[228:229] op_sel_hi:[1,0]
	v_pk_mul_f32 v[40:41], v[40:41], v[228:229] op_sel_hi:[1,0]
	v_pk_mul_f32 v[38:39], v[38:39], v[228:229] op_sel_hi:[1,0]
	v_pk_mul_f32 v[36:37], v[36:37], v[228:229] op_sel_hi:[1,0]
	v_pk_mul_f32 v[34:35], v[34:35], v[228:229] op_sel_hi:[1,0]
	v_pk_mul_f32 v[32:33], v[32:33], v[228:229] op_sel_hi:[1,0]
	v_pk_mul_f32 v[30:31], v[30:31], v[228:229] op_sel_hi:[1,0]
	v_pk_mul_f32 v[28:29], v[28:29], v[228:229] op_sel_hi:[1,0]
	v_pk_mul_f32 v[26:27], v[26:27], v[228:229] op_sel_hi:[1,0]
	v_pk_mul_f32 v[24:25], v[24:25], v[228:229] op_sel_hi:[1,0]
	v_pk_mul_f32 v[22:23], v[22:23], v[228:229] op_sel_hi:[1,0]
	v_pk_mul_f32 v[20:21], v[20:21], v[228:229] op_sel_hi:[1,0]
	v_pk_mul_f32 v[18:19], v[18:19], v[228:229] op_sel_hi:[1,0]
	v_pk_mul_f32 v[16:17], v[16:17], v[228:229] op_sel_hi:[1,0]
	v_pk_mul_f32 v[14:15], v[14:15], v[228:229] op_sel_hi:[1,0]
	v_pk_mul_f32 v[12:13], v[12:13], v[228:229] op_sel_hi:[1,0]
	v_pk_mul_f32 v[10:11], v[10:11], v[228:229] op_sel_hi:[1,0]
	v_pk_mul_f32 v[8:9], v[8:9], v[228:229] op_sel_hi:[1,0]
	v_pk_mul_f32 v[6:7], v[6:7], v[228:229] op_sel_hi:[1,0]
	v_pk_mul_f32 v[4:5], v[4:5], v[228:229] op_sel_hi:[1,0]
	v_pk_mul_f32 v[2:3], v[2:3], v[228:229] op_sel_hi:[1,0]
	s_waitcnt lgkmcnt(7)
	v_mfma_f32_32x32x16_bf16 v[50:65], v[132:135], v[82:85], v[50:65]
	s_waitcnt lgkmcnt(6)
	v_mfma_f32_32x32x16_bf16 v[50:65], v[136:139], v[86:89], v[50:65]
	s_waitcnt lgkmcnt(5)
	v_mfma_f32_32x32x16_bf16 v[50:65], v[140:143], v[90:93], v[50:65]
	s_waitcnt lgkmcnt(4)
	v_mfma_f32_32x32x16_bf16 v[50:65], v[144:147], v[94:97], v[50:65]
	ds_read_b128 v[132:135], v1 offset:49152
	ds_read_b128 v[136:139], v1 offset:50176
	ds_read_b128 v[140:143], v1 offset:51200
	ds_read_b128 v[144:147], v1 offset:52224
	s_waitcnt lgkmcnt(7)
	v_mfma_f32_32x32x16_bf16 v[34:49], v[98:101], v[82:85], v[34:49]
	s_waitcnt lgkmcnt(6)
	v_mfma_f32_32x32x16_bf16 v[34:49], v[102:105], v[86:89], v[34:49]
	s_waitcnt lgkmcnt(5)
	v_mfma_f32_32x32x16_bf16 v[34:49], v[106:109], v[90:93], v[34:49]
	s_waitcnt lgkmcnt(4)
	v_mfma_f32_32x32x16_bf16 v[34:49], v[110:113], v[94:97], v[34:49]
	ds_read_b128 v[98:101], v1 offset:53248
	ds_read_b128 v[102:105], v1 offset:54272
	ds_read_b128 v[106:109], v1 offset:55296
	ds_read_b128 v[110:113], v1 offset:56320
	s_waitcnt lgkmcnt(7)
	v_mfma_f32_32x32x16_bf16 v[18:33], v[132:135], v[82:85], v[18:33]
	s_waitcnt lgkmcnt(6)
	v_mfma_f32_32x32x16_bf16 v[18:33], v[136:139], v[86:89], v[18:33]
	s_waitcnt lgkmcnt(5)
	v_mfma_f32_32x32x16_bf16 v[18:33], v[140:143], v[90:93], v[18:33]
	s_waitcnt lgkmcnt(4)
	v_mfma_f32_32x32x16_bf16 v[18:33], v[144:147], v[94:97], v[18:33]
	s_waitcnt lgkmcnt(3)
	v_mfma_f32_32x32x16_bf16 v[2:17], v[98:101], v[82:85], v[2:17]
	s_waitcnt lgkmcnt(2)
	v_mfma_f32_32x32x16_bf16 v[2:17], v[102:105], v[86:89], v[2:17]
	s_waitcnt lgkmcnt(1)
	v_mfma_f32_32x32x16_bf16 v[2:17], v[106:109], v[90:93], v[2:17]
	s_waitcnt lgkmcnt(0)
	v_mfma_f32_32x32x16_bf16 v[2:17], v[110:113], v[94:97], v[2:17]
	v_cvt_pk_bf16_f32 v73, v72, v73
	v_cvt_pk_bf16_f32 v72, v70, v71
	v_cvt_pk_bf16_f32 v71, v68, v69
	v_cvt_pk_bf16_f32 v70, v66, v67
	v_cvt_pk_bf16_f32 v69, v80, v81
	v_cvt_pk_bf16_f32 v68, v78, v79
	v_cvt_pk_bf16_f32 v67, v76, v77
	v_cvt_pk_bf16_f32 v66, v74, v75
	global_store_dwordx4 v[226:227], v[66:69], off offset:-1024 sc1
	global_store_dwordx4 v[226:227], v[70:73], off offset:-2048 sc1
	s_add_i32 s28, s28, 1
	v_cvt_pk_bf16_f32 v69, v120, v121
	v_cvt_pk_bf16_f32 v68, v118, v119
	v_cvt_pk_bf16_f32 v67, v116, v117
	v_cvt_pk_bf16_f32 v66, v114, v115
	global_store_dwordx4 v[226:227], v[66:69], off sc1
	s_cmp_eq_u32 s28, 64
	s_nop 0
	v_cvt_pk_bf16_f32 v69, v128, v129
	v_cvt_pk_bf16_f32 v68, v126, v127
	v_cvt_pk_bf16_f32 v67, v124, v125
	v_cvt_pk_bf16_f32 v66, v122, v123
	global_store_dwordx4 v[226:227], v[66:69], off offset:1024 sc1
	s_waitcnt lgkmcnt(0)
	s_barrier
	v_lshl_add_u64 v[226:227], v[226:227], 0, s[8:9]
	s_cbranch_scc0 .LBB0_349
	s_mov_b64 s[28:29], 0
	v_mov_b64_e32 v[226:227], v[240:241]

.LBB0_475:
	s_waitcnt lgkmcnt(0)
	s_nop 0
	global_load_dwordx4 v[2:5], v[8:9], off
	v_add_u32_e32 v12, s5, v1
	v_ashrrev_i32_e32 v13, 31, v12
	v_lshlrev_b64 v[14:15], 11, v[12:13]
	v_lshl_add_u64 v[78:79], v[6:7], 0, v[14:15]
	global_load_dwordx4 v[14:17], v[8:9], off offset:64
	global_load_dwordx4 v[18:21], v[78:79], off
	global_load_dwordx4 v[22:25], v[78:79], off offset:64
	global_load_dwordx4 v[26:29], v[8:9], off offset:128
	global_load_dwordx4 v[30:33], v[8:9], off offset:192
	global_load_dwordx4 v[34:37], v[78:79], off offset:128
	global_load_dwordx4 v[38:41], v[8:9], off offset:256
	global_load_dwordx4 v[42:45], v[78:79], off offset:192
	global_load_dwordx4 v[46:49], v[78:79], off offset:256
	global_load_dwordx4 v[50:53], v[8:9], off offset:320
	global_load_dwordx4 v[54:57], v[78:79], off offset:320
	global_load_dwordx4 v[58:61], v[8:9], off offset:384
	global_load_dwordx4 v[62:65], v[8:9], off offset:448
	global_load_dwordx4 v[66:69], v[78:79], off offset:384
	global_load_dwordx4 v[70:73], v[78:79], off offset:448
	s_waitcnt vmcnt(13)
	v_mfma_f32_16x16x32_bf16 v[2:5], v[2:5], v[18:21], 0
	global_load_dwordx4 v[18:21], v[8:9], off offset:512
	global_load_dwordx4 v[74:77], v[8:9], off offset:576
	s_waitcnt vmcnt(14)
	v_mfma_f32_16x16x32_bf16 v[2:5], v[14:17], v[22:25], v[2:5]
	global_load_dwordx4 v[14:17], v[78:79], off offset:512
	global_load_dwordx4 v[22:25], v[78:79], off offset:576
	s_waitcnt vmcnt(13)
	v_mfma_f32_16x16x32_bf16 v[2:5], v[26:29], v[34:37], v[2:5]
	global_load_dwordx4 v[26:29], v[8:9], off offset:640
	global_load_dwordx4 v[34:37], v[8:9], off offset:704
	s_waitcnt vmcnt(13)
	v_mfma_f32_16x16x32_bf16 v[2:5], v[30:33], v[42:45], v[2:5]
	global_load_dwordx4 v[30:33], v[78:79], off offset:640
	s_waitcnt vmcnt(13)
	v_mfma_f32_16x16x32_bf16 v[2:5], v[38:41], v[46:49], v[2:5]
	global_load_dwordx4 v[38:41], v[78:79], off offset:704
	global_load_dwordx4 v[42:45], v[8:9], off offset:768
	global_load_dwordx4 v[46:49], v[8:9], off offset:832
	s_waitcnt vmcnt(14)
	v_mfma_f32_16x16x32_bf16 v[2:5], v[50:53], v[54:57], v[2:5]
	global_load_dwordx4 v[50:53], v[78:79], off offset:768
	global_load_dwordx4 v[54:57], v[78:79], off offset:832
	s_waitcnt vmcnt(13)
	v_mfma_f32_16x16x32_bf16 v[2:5], v[58:61], v[66:69], v[2:5]
	s_waitcnt vmcnt(12)
	v_mfma_f32_16x16x32_bf16 v[2:5], v[62:65], v[70:73], v[2:5]
	global_load_dwordx4 v[58:61], v[8:9], off offset:896
	global_load_dwordx4 v[62:65], v[8:9], off offset:960
	s_waitcnt vmcnt(11)
	v_mfma_f32_16x16x32_bf16 v[2:5], v[18:21], v[14:17], v[2:5]
	global_load_dwordx4 v[14:17], v[78:79], off offset:896
	global_load_dwordx4 v[18:21], v[78:79], off offset:960
	s_waitcnt vmcnt(12)
	v_mfma_f32_16x16x32_bf16 v[2:5], v[74:77], v[22:25], v[2:5]
	global_load_dwordx4 v[22:25], v[8:9], off offset:1024
	global_load_dwordx4 v[66:69], v[8:9], off offset:1088
	s_waitcnt vmcnt(11)
	v_mfma_f32_16x16x32_bf16 v[2:5], v[26:29], v[30:33], v[2:5]
	global_load_dwordx4 v[26:29], v[78:79], off offset:1024
	global_load_dwordx4 v[30:33], v[78:79], off offset:1088
	s_waitcnt vmcnt(12)
	v_mfma_f32_16x16x32_bf16 v[2:5], v[34:37], v[38:41], v[2:5]
	global_load_dwordx4 v[34:37], v[8:9], off offset:1152
	global_load_dwordx4 v[38:41], v[8:9], off offset:1216
	s_waitcnt vmcnt(11)
	v_mfma_f32_16x16x32_bf16 v[2:5], v[42:45], v[50:53], v[2:5]
	s_waitcnt vmcnt(10)
	v_mfma_f32_16x16x32_bf16 v[2:5], v[46:49], v[54:57], v[2:5]
	global_load_dwordx4 v[42:45], v[78:79], off offset:1152
	global_load_dwordx4 v[46:49], v[78:79], off offset:1216
	s_waitcnt vmcnt(9)
	v_mfma_f32_16x16x32_bf16 v[2:5], v[58:61], v[14:17], v[2:5]
	global_load_dwordx4 v[14:17], v[8:9], off offset:1280
	global_load_dwordx4 v[50:53], v[8:9], off offset:1344
	s_waitcnt vmcnt(10)
	v_mfma_f32_16x16x32_bf16 v[2:5], v[62:65], v[18:21], v[2:5]
	global_load_dwordx4 v[18:21], v[78:79], off offset:1280
	global_load_dwordx4 v[54:57], v[8:9], off offset:1408
	s_waitcnt vmcnt(9)
	v_mfma_f32_16x16x32_bf16 v[2:5], v[22:25], v[26:29], v[2:5]
	global_load_dwordx4 v[22:25], v[78:79], off offset:1344
	global_load_dwordx4 v[26:29], v[78:79], off offset:1408
	s_waitcnt vmcnt(10)
	v_mfma_f32_16x16x32_bf16 v[2:5], v[66:69], v[30:33], v[2:5]
	s_waitcnt vmcnt(7)
	v_mfma_f32_16x16x32_bf16 v[2:5], v[34:37], v[42:45], v[2:5]
	global_load_dwordx4 v[30:33], v[8:9], off offset:1472
	global_load_dwordx4 v[34:37], v[78:79], off offset:1472
	s_waitcnt vmcnt(8)
	v_mfma_f32_16x16x32_bf16 v[2:5], v[38:41], v[46:49], v[2:5]
	global_load_dwordx4 v[38:41], v[8:9], off offset:1536
	global_load_dwordx4 v[42:45], v[8:9], off offset:1600
	s_waitcnt vmcnt(7)
	v_mfma_f32_16x16x32_bf16 v[2:5], v[14:17], v[18:21], v[2:5]
	global_load_dwordx4 v[14:17], v[78:79], off offset:1536
	global_load_dwordx4 v[18:21], v[8:9], off offset:1664
	s_waitcnt vmcnt(7)
	v_mfma_f32_16x16x32_bf16 v[2:5], v[50:53], v[22:25], v[2:5]
	global_load_dwordx4 v[22:25], v[78:79], off offset:1600
	s_waitcnt vmcnt(7)
	v_mfma_f32_16x16x32_bf16 v[2:5], v[54:57], v[26:29], v[2:5]
	global_load_dwordx4 v[26:29], v[78:79], off offset:1664
	s_waitcnt vmcnt(6)
	v_mfma_f32_16x16x32_bf16 v[2:5], v[30:33], v[34:37], v[2:5]
	global_load_dwordx4 v[30:33], v[8:9], off offset:1728
	global_load_dwordx4 v[34:37], v[78:79], off offset:1728
	s_waitcnt vmcnt(5)
	v_mfma_f32_16x16x32_bf16 v[2:5], v[38:41], v[14:17], v[2:5]
	global_load_dwordx4 v[14:17], v[8:9], off offset:1792
	global_load_dwordx4 v[38:41], v[8:9], off offset:1856
	s_waitcnt vmcnt(5)
	v_mfma_f32_16x16x32_bf16 v[2:5], v[42:45], v[22:25], v[2:5]
	global_load_dwordx4 v[22:25], v[78:79], off offset:1792
	s_waitcnt vmcnt(5)
	v_mfma_f32_16x16x32_bf16 v[2:5], v[18:21], v[26:29], v[2:5]
	global_load_dwordx4 v[18:21], v[78:79], off offset:1856
	s_waitcnt vmcnt(4)
	v_mfma_f32_16x16x32_bf16 v[2:5], v[30:33], v[34:37], v[2:5]
	global_load_dwordx4 v[26:29], v[8:9], off offset:1920
	global_load_dwordx4 v[30:33], v[8:9], off offset:1984
	s_waitcnt vmcnt(3)
	v_mfma_f32_16x16x32_bf16 v[2:5], v[14:17], v[22:25], v[2:5]
	global_load_dwordx4 v[14:17], v[78:79], off offset:1920
	s_waitcnt vmcnt(3)
	v_mfma_f32_16x16x32_bf16 v[2:5], v[38:41], v[18:21], v[2:5]
	global_load_dwordx4 v[18:21], v[78:79], off offset:1984
	s_waitcnt vmcnt(1)
	v_mfma_f32_16x16x32_bf16 v[2:5], v[26:29], v[14:17], v[2:5]
	s_waitcnt vmcnt(0)
	v_mfma_f32_16x16x32_bf16 v[2:5], v[30:33], v[18:21], v[2:5]
	s_and_saveexec_b64 s[28:29], vcc
	s_cbranch_execz .LBB0_474
	v_lshlrev_b64 v[14:15], 6, v[12:13]
	v_lshl_add_u64 v[26:27], s[30:31], 0, v[14:15]
	global_load_dwordx4 v[14:17], v[26:27], off offset:32
	global_load_dwordx4 v[18:21], v[26:27], off
	global_load_dwordx4 v[22:25], v[26:27], off offset:48
	s_nop 0
	global_load_dwordx4 v[26:29], v[26:27], off offset:16
	v_lshlrev_b64 v[12:13], 5, v[12:13]
	v_lshl_add_u64 v[12:13], v[10:11], 0, v[12:13]
	s_waitcnt vmcnt(3)
	v_mov_b32_e32 v30, v14
	s_waitcnt vmcnt(2)
	v_mov_b32_e32 v31, v18
	v_mov_b32_e32 v18, v15
	v_mov_b32_e32 v14, v16
	v_mov_b32_e32 v15, v20
	v_mov_b32_e32 v20, v17
	s_waitcnt vmcnt(1)
	v_mov_b32_e32 v16, v22
	s_waitcnt vmcnt(0)
	v_mov_b32_e32 v17, v26
	v_mov_b32_e32 v26, v23
	v_mov_b32_e32 v22, v24
	v_mov_b32_e32 v23, v28
	v_mov_b32_e32 v28, v25
	v_pk_add_f32 v[18:19], v[30:31], v[18:19]
	v_pk_add_f32 v[14:15], v[14:15], v[20:21]
	v_pk_add_f32 v[16:17], v[16:17], v[26:27]
	v_pk_add_f32 v[20:21], v[22:23], v[28:29]
	v_pk_add_f32 v[14:15], v[18:19], v[14:15]
	v_pk_add_f32 v[16:17], v[16:17], v[20:21]
	v_pk_add_f32 v[14:15], v[16:17], v[14:15]
	v_add_f32_e32 v14, v14, v15
	v_fmamk_f32 v14, v14, 0x3a800000, v225
	v_rsq_f32_e32 v14, v14
	s_nop 0
	v_pk_mul_f32 v[4:5], v[4:5], v[14:15] op_sel_hi:[1,0]
	v_pk_mul_f32 v[2:3], v[2:3], v[14:15] op_sel_hi:[1,0]
	global_store_dwordx4 v[12:13], v[2:5], off sc1
	s_branch .LBB0_474

.LBB0_508:
	s_nop 1
	global_load_dwordx4 v[2:5], v[8:9], off
	v_add_u32_e32 v12, s5, v1
	v_ashrrev_i32_e32 v13, 31, v12
	v_lshlrev_b64 v[14:15], 11, v[12:13]
	v_lshl_add_u64 v[78:79], v[6:7], 0, v[14:15]
	global_load_dwordx4 v[14:17], v[8:9], off offset:64
	global_load_dwordx4 v[18:21], v[78:79], off
	global_load_dwordx4 v[22:25], v[78:79], off offset:64
	global_load_dwordx4 v[26:29], v[8:9], off offset:128
	global_load_dwordx4 v[30:33], v[8:9], off offset:192
	global_load_dwordx4 v[34:37], v[78:79], off offset:128
	global_load_dwordx4 v[38:41], v[8:9], off offset:256
	global_load_dwordx4 v[42:45], v[78:79], off offset:192
	global_load_dwordx4 v[46:49], v[78:79], off offset:256
	global_load_dwordx4 v[50:53], v[8:9], off offset:320
	global_load_dwordx4 v[54:57], v[78:79], off offset:320
	global_load_dwordx4 v[58:61], v[8:9], off offset:384
	global_load_dwordx4 v[62:65], v[8:9], off offset:448
	global_load_dwordx4 v[66:69], v[78:79], off offset:384
	global_load_dwordx4 v[70:73], v[78:79], off offset:448
	s_waitcnt vmcnt(0)
	v_mfma_f32_16x16x32_bf16 v[2:5], v[2:5], v[18:21], 0
	global_load_dwordx4 v[18:21], v[8:9], off offset:512
	global_load_dwordx4 v[74:77], v[8:9], off offset:576
	v_mfma_f32_16x16x32_bf16 v[2:5], v[14:17], v[22:25], v[2:5]
	global_load_dwordx4 v[14:17], v[78:79], off offset:512
	global_load_dwordx4 v[22:25], v[78:79], off offset:576
	v_mfma_f32_16x16x32_bf16 v[2:5], v[26:29], v[34:37], v[2:5]
	global_load_dwordx4 v[26:29], v[8:9], off offset:640
	global_load_dwordx4 v[34:37], v[8:9], off offset:704
	v_mfma_f32_16x16x32_bf16 v[2:5], v[30:33], v[42:45], v[2:5]
	global_load_dwordx4 v[30:33], v[78:79], off offset:640
	v_mfma_f32_16x16x32_bf16 v[2:5], v[38:41], v[46:49], v[2:5]
	global_load_dwordx4 v[38:41], v[78:79], off offset:704
	global_load_dwordx4 v[42:45], v[8:9], off offset:768
	global_load_dwordx4 v[46:49], v[8:9], off offset:832
	v_mfma_f32_16x16x32_bf16 v[2:5], v[50:53], v[54:57], v[2:5]
	global_load_dwordx4 v[50:53], v[78:79], off offset:768
	global_load_dwordx4 v[54:57], v[78:79], off offset:832
	v_mfma_f32_16x16x32_bf16 v[2:5], v[58:61], v[66:69], v[2:5]
	v_mfma_f32_16x16x32_bf16 v[2:5], v[62:65], v[70:73], v[2:5]
	global_load_dwordx4 v[58:61], v[8:9], off offset:896
	global_load_dwordx4 v[62:65], v[8:9], off offset:960
	s_waitcnt vmcnt(11)
	v_mfma_f32_16x16x32_bf16 v[2:5], v[18:21], v[14:17], v[2:5]
	global_load_dwordx4 v[14:17], v[78:79], off offset:896
	global_load_dwordx4 v[18:21], v[78:79], off offset:960
	s_waitcnt vmcnt(12)
	v_mfma_f32_16x16x32_bf16 v[2:5], v[74:77], v[22:25], v[2:5]
	global_load_dwordx4 v[22:25], v[8:9], off offset:1024
	global_load_dwordx4 v[66:69], v[8:9], off offset:1088
	s_waitcnt vmcnt(11)
	v_mfma_f32_16x16x32_bf16 v[2:5], v[26:29], v[30:33], v[2:5]
	global_load_dwordx4 v[26:29], v[78:79], off offset:1024
	global_load_dwordx4 v[30:33], v[78:79], off offset:1088
	s_waitcnt vmcnt(12)
	v_mfma_f32_16x16x32_bf16 v[2:5], v[34:37], v[38:41], v[2:5]
	global_load_dwordx4 v[34:37], v[8:9], off offset:1152
	global_load_dwordx4 v[38:41], v[8:9], off offset:1216
	s_waitcnt vmcnt(11)
	v_mfma_f32_16x16x32_bf16 v[2:5], v[42:45], v[50:53], v[2:5]
	s_waitcnt vmcnt(10)
	v_mfma_f32_16x16x32_bf16 v[2:5], v[46:49], v[54:57], v[2:5]
	global_load_dwordx4 v[42:45], v[78:79], off offset:1152
	global_load_dwordx4 v[46:49], v[78:79], off offset:1216
	s_waitcnt vmcnt(9)
	v_mfma_f32_16x16x32_bf16 v[2:5], v[58:61], v[14:17], v[2:5]
	global_load_dwordx4 v[14:17], v[8:9], off offset:1280
	global_load_dwordx4 v[50:53], v[8:9], off offset:1344
	s_waitcnt vmcnt(10)
	v_mfma_f32_16x16x32_bf16 v[2:5], v[62:65], v[18:21], v[2:5]
	global_load_dwordx4 v[18:21], v[78:79], off offset:1280
	global_load_dwordx4 v[54:57], v[8:9], off offset:1408
	s_waitcnt vmcnt(9)
	v_mfma_f32_16x16x32_bf16 v[2:5], v[22:25], v[26:29], v[2:5]
	global_load_dwordx4 v[22:25], v[78:79], off offset:1344
	global_load_dwordx4 v[26:29], v[78:79], off offset:1408
	s_waitcnt vmcnt(10)
	v_mfma_f32_16x16x32_bf16 v[2:5], v[66:69], v[30:33], v[2:5]
	s_waitcnt vmcnt(7)
	v_mfma_f32_16x16x32_bf16 v[2:5], v[34:37], v[42:45], v[2:5]
	global_load_dwordx4 v[30:33], v[8:9], off offset:1472
	global_load_dwordx4 v[34:37], v[78:79], off offset:1472
	s_waitcnt vmcnt(8)
	v_mfma_f32_16x16x32_bf16 v[2:5], v[38:41], v[46:49], v[2:5]
	global_load_dwordx4 v[38:41], v[8:9], off offset:1536
	global_load_dwordx4 v[42:45], v[8:9], off offset:1600
	s_waitcnt vmcnt(7)
	v_mfma_f32_16x16x32_bf16 v[2:5], v[14:17], v[18:21], v[2:5]
	global_load_dwordx4 v[14:17], v[78:79], off offset:1536
	global_load_dwordx4 v[18:21], v[8:9], off offset:1664
	s_waitcnt vmcnt(7)
	v_mfma_f32_16x16x32_bf16 v[2:5], v[50:53], v[22:25], v[2:5]
	global_load_dwordx4 v[22:25], v[78:79], off offset:1600
	s_waitcnt vmcnt(7)
	v_mfma_f32_16x16x32_bf16 v[2:5], v[54:57], v[26:29], v[2:5]
	global_load_dwordx4 v[26:29], v[78:79], off offset:1664
	s_waitcnt vmcnt(6)
	v_mfma_f32_16x16x32_bf16 v[2:5], v[30:33], v[34:37], v[2:5]
	global_load_dwordx4 v[30:33], v[8:9], off offset:1728
	global_load_dwordx4 v[34:37], v[78:79], off offset:1728
	s_waitcnt vmcnt(5)
	v_mfma_f32_16x16x32_bf16 v[2:5], v[38:41], v[14:17], v[2:5]
	global_load_dwordx4 v[14:17], v[8:9], off offset:1792
	global_load_dwordx4 v[38:41], v[8:9], off offset:1856
	s_waitcnt vmcnt(5)
	v_mfma_f32_16x16x32_bf16 v[2:5], v[42:45], v[22:25], v[2:5]
	global_load_dwordx4 v[22:25], v[78:79], off offset:1792
	s_waitcnt vmcnt(5)
	v_mfma_f32_16x16x32_bf16 v[2:5], v[18:21], v[26:29], v[2:5]
	global_load_dwordx4 v[18:21], v[78:79], off offset:1856
	s_waitcnt vmcnt(4)
	v_mfma_f32_16x16x32_bf16 v[2:5], v[30:33], v[34:37], v[2:5]
	global_load_dwordx4 v[26:29], v[8:9], off offset:1920
	global_load_dwordx4 v[30:33], v[8:9], off offset:1984
	s_waitcnt vmcnt(3)
	v_mfma_f32_16x16x32_bf16 v[2:5], v[14:17], v[22:25], v[2:5]
	global_load_dwordx4 v[14:17], v[78:79], off offset:1920
	s_waitcnt vmcnt(3)
	v_mfma_f32_16x16x32_bf16 v[2:5], v[38:41], v[18:21], v[2:5]
	global_load_dwordx4 v[18:21], v[78:79], off offset:1984
	s_waitcnt vmcnt(1)
	v_mfma_f32_16x16x32_bf16 v[2:5], v[26:29], v[14:17], v[2:5]
	s_waitcnt vmcnt(0)
	v_mfma_f32_16x16x32_bf16 v[2:5], v[30:33], v[18:21], v[2:5]
	s_and_saveexec_b64 s[28:29], vcc
	s_cbranch_execz .LBB0_507
	v_lshlrev_b64 v[14:15], 6, v[12:13]
	v_lshl_add_u64 v[26:27], s[30:31], 0, v[14:15]
	global_load_dwordx4 v[14:17], v[26:27], off offset:32
	global_load_dwordx4 v[18:21], v[26:27], off
	global_load_dwordx4 v[22:25], v[26:27], off offset:48
	s_nop 0
	global_load_dwordx4 v[26:29], v[26:27], off offset:16
	v_lshlrev_b64 v[12:13], 5, v[12:13]
	v_lshl_add_u64 v[12:13], v[10:11], 0, v[12:13]
	s_waitcnt vmcnt(3)
	v_mov_b32_e32 v30, v14
	s_waitcnt vmcnt(2)
	v_mov_b32_e32 v31, v18
	v_mov_b32_e32 v18, v15
	v_mov_b32_e32 v14, v16
	v_mov_b32_e32 v15, v20
	v_mov_b32_e32 v20, v17
	s_waitcnt vmcnt(1)
	v_mov_b32_e32 v16, v22
	s_waitcnt vmcnt(0)
	v_mov_b32_e32 v17, v26
	v_mov_b32_e32 v26, v23
	v_mov_b32_e32 v22, v24
	v_mov_b32_e32 v23, v28
	v_mov_b32_e32 v28, v25
	v_pk_add_f32 v[18:19], v[30:31], v[18:19]
	v_pk_add_f32 v[14:15], v[14:15], v[20:21]
	v_pk_add_f32 v[16:17], v[16:17], v[26:27]
	v_pk_add_f32 v[20:21], v[22:23], v[28:29]
	v_pk_add_f32 v[14:15], v[18:19], v[14:15]
	v_pk_add_f32 v[16:17], v[16:17], v[20:21]
	v_pk_add_f32 v[14:15], v[16:17], v[14:15]
	v_add_f32_e32 v14, v14, v15
	v_fmamk_f32 v14, v14, 0x3a800000, v225
	v_rsq_f32_e32 v14, v14
	s_nop 0
	v_pk_mul_f32 v[4:5], v[4:5], v[14:15] op_sel_hi:[1,0]
	v_pk_mul_f32 v[2:3], v[2:3], v[14:15] op_sel_hi:[1,0]
	global_store_dwordx4 v[12:13], v[2:5], off sc1
	s_branch .LBB0_507

.LBB0_514:
	ds_read2_b32 v[24:25], v13 offset1:8
	ds_read2_b32 v[26:27], v13 offset0:33 offset1:41
	ds_read2_b32 v[30:31], v13 offset0:66 offset1:74
	ds_read2_b32 v[32:33], v13 offset0:99 offset1:107
	ds_read2_b32 v[34:35], v13 offset0:132 offset1:140
	ds_read2_b32 v[36:37], v13 offset0:165 offset1:173
	ds_read2_b32 v[38:39], v13 offset0:198 offset1:206
	ds_read2_b32 v[40:41], v13 offset0:231 offset1:239
	s_waitcnt lgkmcnt(7)
	v_mov_b32_e32 v20, v24
	s_waitcnt lgkmcnt(6)
	v_mov_b32_e32 v21, v26
	s_waitcnt lgkmcnt(5)
	v_mov_b32_e32 v22, v30
	s_waitcnt lgkmcnt(4)
	v_mov_b32_e32 v23, v32
	s_waitcnt vmcnt(0)
	v_pk_mul_f32 v[20:21], v[6:7], v[20:21]
	v_pk_mul_f32 v[22:23], v[8:9], v[22:23]
	v_cvt_pk_bf16_f32 v20, v20, v21
	v_cvt_pk_bf16_f32 v21, v22, v23
	s_waitcnt lgkmcnt(3)
	v_mov_b32_e32 v22, v34
	s_waitcnt lgkmcnt(2)
	v_mov_b32_e32 v23, v36
	s_waitcnt lgkmcnt(1)
	v_mov_b32_e32 v42, v38
	s_waitcnt lgkmcnt(0)
	v_mov_b32_e32 v43, v40
	s_lshl_b32 s8, s6, 5
	s_lshl_b64 s[6:7], s[28:29], 1
	v_pk_mul_f32 v[22:23], v[2:3], v[22:23]
	v_pk_mul_f32 v[42:43], v[4:5], v[42:43]
	s_add_u32 s6, s37, s6
	v_cvt_pk_bf16_f32 v22, v22, v23
	v_cvt_pk_bf16_f32 v23, v42, v43
	v_or_b32_e32 v42, s8, v11
	s_addc_u32 s7, s34, s7
	v_lshlrev_b32_e32 v130, 1, v16
	v_ashrrev_i32_e32 v43, 31, v42
	v_lshl_add_u64 v[28:29], s[6:7], 0, v[130:131]
	v_lshlrev_b64 v[42:43], 11, v[42:43]
	v_lshl_add_u64 v[42:43], v[28:29], 0, v[42:43]
	v_mov_b32_e32 v26, v25
	v_mov_b32_e32 v32, v31
	global_store_dwordx4 v[42:43], v[20:23], off sc1
	v_mov_b32_e32 v36, v35
	v_mov_b32_e32 v40, v39
	v_pk_mul_f32 v[20:21], v[6:7], v[26:27]
	v_pk_mul_f32 v[22:23], v[8:9], v[32:33]
	v_cvt_pk_bf16_f32 v20, v20, v21
	v_cvt_pk_bf16_f32 v21, v22, v23
	v_pk_mul_f32 v[22:23], v[2:3], v[36:37]
	v_pk_mul_f32 v[24:25], v[4:5], v[40:41]
	v_cvt_pk_bf16_f32 v22, v22, v23
	v_cvt_pk_bf16_f32 v23, v24, v25
	v_or_b32_e32 v24, s8, v15
	v_ashrrev_i32_e32 v25, 31, v24
	v_lshlrev_b64 v[24:25], 11, v[24:25]
	v_lshl_add_u64 v[24:25], v[28:29], 0, v[24:25]
	ds_read2_b32 v[26:27], v13 offset0:16 offset1:24
	ds_read2_b32 v[30:31], v13 offset0:49 offset1:57
	global_store_dwordx4 v[24:25], v[20:23], off sc1
	ds_read2_b32 v[24:25], v13 offset0:82 offset1:90
	ds_read2_b32 v[32:33], v13 offset0:115 offset1:123
	ds_read2_b32 v[34:35], v13 offset0:148 offset1:156
	ds_read2_b32 v[36:37], v13 offset0:181 offset1:189
	ds_read2_b32 v[38:39], v13 offset0:214 offset1:222
	ds_read2_b32 v[40:41], v13 offset0:247 offset1:255
	s_waitcnt lgkmcnt(7)
	v_mov_b32_e32 v20, v26
	s_waitcnt lgkmcnt(6)
	v_mov_b32_e32 v21, v30
	s_waitcnt lgkmcnt(5)
	v_mov_b32_e32 v22, v24
	s_waitcnt lgkmcnt(4)
	v_mov_b32_e32 v23, v32
	v_pk_mul_f32 v[20:21], v[6:7], v[20:21]
	v_pk_mul_f32 v[22:23], v[8:9], v[22:23]
	v_cvt_pk_bf16_f32 v20, v20, v21
	v_cvt_pk_bf16_f32 v21, v22, v23
	s_waitcnt lgkmcnt(3)
	v_mov_b32_e32 v22, v34
	s_waitcnt lgkmcnt(2)
	v_mov_b32_e32 v23, v36
	v_mov_b32_e32 v30, v27
	v_mov_b32_e32 v32, v25
	v_mov_b32_e32 v36, v35
	v_pk_mul_f32 v[22:23], v[2:3], v[22:23]
	s_waitcnt lgkmcnt(1)
	v_mov_b32_e32 v42, v38
	s_waitcnt lgkmcnt(0)
	v_mov_b32_e32 v43, v40
	v_pk_mul_f32 v[6:7], v[6:7], v[30:31]
	v_pk_mul_f32 v[8:9], v[8:9], v[32:33]
	v_pk_mul_f32 v[2:3], v[2:3], v[36:37]
	v_mov_b32_e32 v40, v39
	v_pk_mul_f32 v[42:43], v[4:5], v[42:43]
	v_cvt_pk_bf16_f32 v6, v6, v7
	v_cvt_pk_bf16_f32 v7, v8, v9
	v_cvt_pk_bf16_f32 v8, v2, v3
	v_pk_mul_f32 v[2:3], v[4:5], v[40:41]
	v_cvt_pk_bf16_f32 v22, v22, v23
	v_cvt_pk_bf16_f32 v23, v42, v43
	v_or_b32_e32 v42, s8, v17
	v_cvt_pk_bf16_f32 v9, v2, v3
	v_or_b32_e32 v2, s8, v18
	v_ashrrev_i32_e32 v43, 31, v42
	v_ashrrev_i32_e32 v3, 31, v2
	v_lshlrev_b64 v[42:43], 11, v[42:43]
	v_lshlrev_b64 v[2:3], 11, v[2:3]
	v_lshl_add_u64 v[42:43], v[28:29], 0, v[42:43]
	v_lshl_add_u64 v[2:3], v[28:29], 0, v[2:3]
	global_store_dwordx4 v[42:43], v[20:23], off sc1
	global_store_dwordx4 v[2:3], v[6:9], off sc1
	s_waitcnt lgkmcnt(0)

.LBB0_521:
	s_lshl_b32 s8, s6, 1
	s_lshl_b32 s9, s44, 1
	v_or_b32_e32 v19, s8, v1
	v_or_b32_e32 v46, s9, v12
	s_add_i32 s10, s8, 4
	s_add_i32 s11, s9, 4
	s_add_i32 s46, s8, 8
	s_add_i32 s47, s9, 8
	s_add_i32 s48, s8, 12
	s_add_i32 s49, s9, 12
	s_add_i32 s50, s8, 16
	s_add_i32 s51, s9, 16
	s_add_i32 s52, s8, 20
	s_add_i32 s53, s9, 20
	s_add_i32 s54, s8, 24
	s_add_i32 s55, s9, 24
	s_add_i32 s8, s8, 28
	s_add_i32 s9, s9, 28
	v_add_u32_e32 v6, s28, v46
	v_or_b32_e32 v47, s10, v1
	v_or_b32_e32 v48, s11, v12
	v_or_b32_e32 v49, s46, v1
	v_or_b32_e32 v50, s47, v12
	v_or_b32_e32 v51, s48, v1
	v_or_b32_e32 v52, s49, v12
	v_or_b32_e32 v53, s50, v1
	v_or_b32_e32 v54, s51, v12
	v_or_b32_e32 v55, s52, v1
	v_or_b32_e32 v56, s53, v12
	v_or_b32_e32 v57, s54, v1
	v_or_b32_e32 v58, s55, v12
	v_or_b32_e32 v59, s8, v1
	v_or_b32_e32 v60, s9, v12
	v_add_u32_e32 v4, s29, v19
	v_ashrrev_i32_e32 v7, 31, v6
	v_add_u32_e32 v8, s29, v47
	v_add_u32_e32 v20, s28, v48
	v_add_u32_e32 v22, s29, v49
	v_add_u32_e32 v24, s28, v50
	v_add_u32_e32 v26, s29, v51
	v_add_u32_e32 v28, s28, v52
	v_add_u32_e32 v30, s29, v53
	v_add_u32_e32 v32, s28, v54
	v_add_u32_e32 v34, s29, v55
	v_add_u32_e32 v36, s28, v56
	v_add_u32_e32 v38, s29, v57
	v_add_u32_e32 v40, s28, v58
	v_add_u32_e32 v42, s29, v59
	v_add_u32_e32 v44, s28, v60
	v_ashrrev_i32_e32 v5, 31, v4
	v_lshlrev_b64 v[6:7], 12, v[6:7]
	v_ashrrev_i32_e32 v21, 31, v20
	v_ashrrev_i32_e32 v9, 31, v8
	v_ashrrev_i32_e32 v25, 31, v24
	v_ashrrev_i32_e32 v23, 31, v22
	v_ashrrev_i32_e32 v29, 31, v28
	v_ashrrev_i32_e32 v27, 31, v26
	v_ashrrev_i32_e32 v33, 31, v32
	v_ashrrev_i32_e32 v31, 31, v30
	v_ashrrev_i32_e32 v37, 31, v36
	v_ashrrev_i32_e32 v35, 31, v34
	v_ashrrev_i32_e32 v41, 31, v40
	v_ashrrev_i32_e32 v39, 31, v38
	v_ashrrev_i32_e32 v45, 31, v44
	v_ashrrev_i32_e32 v43, 31, v42
	v_lshlrev_b64 v[4:5], 12, v[4:5]
	v_lshl_add_u64 v[6:7], v[2:3], 0, v[6:7]
	v_lshlrev_b64 v[8:9], 12, v[8:9]
	v_lshlrev_b64 v[20:21], 12, v[20:21]
	v_lshlrev_b64 v[22:23], 12, v[22:23]
	v_lshlrev_b64 v[24:25], 12, v[24:25]
	v_lshlrev_b64 v[26:27], 12, v[26:27]
	v_lshlrev_b64 v[28:29], 12, v[28:29]
	v_lshlrev_b64 v[30:31], 12, v[30:31]
	v_lshlrev_b64 v[32:33], 12, v[32:33]
	v_lshlrev_b64 v[34:35], 12, v[34:35]
	v_lshlrev_b64 v[36:37], 12, v[36:37]
	v_lshlrev_b64 v[38:39], 12, v[38:39]
	v_lshlrev_b64 v[40:41], 12, v[40:41]
	v_lshlrev_b64 v[42:43], 12, v[42:43]
	v_lshlrev_b64 v[44:45], 12, v[44:45]
	v_lshl_add_u64 v[4:5], v[2:3], 0, v[4:5]
	v_lshl_add_u64 v[20:21], v[2:3], 0, v[20:21]
	v_lshl_add_u64 v[8:9], v[2:3], 0, v[8:9]
	v_lshl_add_u64 v[24:25], v[2:3], 0, v[24:25]
	v_lshl_add_u64 v[22:23], v[2:3], 0, v[22:23]
	v_lshl_add_u64 v[28:29], v[2:3], 0, v[28:29]
	v_lshl_add_u64 v[26:27], v[2:3], 0, v[26:27]
	v_lshl_add_u64 v[32:33], v[2:3], 0, v[32:33]
	v_lshl_add_u64 v[30:31], v[2:3], 0, v[30:31]
	v_lshl_add_u64 v[36:37], v[2:3], 0, v[36:37]
	v_lshl_add_u64 v[34:35], v[2:3], 0, v[34:35]
	v_lshl_add_u64 v[40:41], v[2:3], 0, v[40:41]
	v_lshl_add_u64 v[38:39], v[2:3], 0, v[38:39]
	v_lshl_add_u64 v[44:45], v[2:3], 0, v[44:45]
	v_lshl_add_u64 v[42:43], v[2:3], 0, v[42:43]
	global_load_dword v61, v[6:7], off
	global_load_dword v62, v[4:5], off
	global_load_dword v63, v[20:21], off
	global_load_dword v64, v[8:9], off
	global_load_dword v65, v[24:25], off
	global_load_dword v66, v[22:23], off
	global_load_dword v67, v[28:29], off
	global_load_dword v68, v[26:27], off
	global_load_dword v69, v[32:33], off
	global_load_dword v70, v[30:31], off
	global_load_dword v71, v[36:37], off
	global_load_dword v72, v[34:35], off
	global_load_dword v73, v[40:41], off
	global_load_dword v74, v[38:39], off
	global_load_dword v75, v[44:45], off
	global_load_dword v76, v[42:43], off
	s_add_i32 s44, s44, 16
	s_add_i32 s6, s6, 16
	s_add_i32 s45, s45, -16
	v_mad_u64_u32 v[4:5], s[8:9], v46, s93, v[14:15]
	s_cmp_lg_u32 s45, 0
	v_mad_u64_u32 v[6:7], s[8:9], v19, s93, v[14:15]
	v_mad_u64_u32 v[8:9], s[8:9], v48, s93, v[14:15]
	v_mad_u64_u32 v[20:21], s[8:9], v47, s93, v[14:15]
	v_mad_u64_u32 v[22:23], s[8:9], v50, s93, v[14:15]
	v_mad_u64_u32 v[24:25], s[8:9], v49, s93, v[14:15]
	v_mad_u64_u32 v[26:27], s[8:9], v52, s93, v[14:15]
	v_mad_u64_u32 v[28:29], s[8:9], v51, s93, v[14:15]
	v_mad_u64_u32 v[30:31], s[8:9], v54, s93, v[14:15]
	v_mad_u64_u32 v[32:33], s[8:9], v53, s93, v[14:15]
	v_mad_u64_u32 v[34:35], s[8:9], v56, s93, v[14:15]
	v_mad_u64_u32 v[36:37], s[8:9], v55, s93, v[14:15]
	v_mad_u64_u32 v[38:39], s[8:9], v58, s93, v[14:15]
	v_mad_u64_u32 v[40:41], s[8:9], v57, s93, v[14:15]
	v_mad_u64_u32 v[42:43], s[8:9], v60, s93, v[14:15]
	v_mad_u64_u32 v[44:45], s[8:9], v59, s93, v[14:15]
	s_waitcnt vmcnt(15)
	ds_write_b32 v4, v61
	s_waitcnt vmcnt(14)
	ds_write_b32 v6, v62
	s_waitcnt vmcnt(13)
	ds_write_b32 v8, v63
	s_waitcnt vmcnt(12)
	ds_write_b32 v20, v64
	s_waitcnt vmcnt(11)
	ds_write_b32 v22, v65
	s_waitcnt vmcnt(10)
	ds_write_b32 v24, v66
	s_waitcnt vmcnt(9)
	ds_write_b32 v26, v67
	s_waitcnt vmcnt(8)
	ds_write_b32 v28, v68
	s_waitcnt vmcnt(7)
	ds_write_b32 v30, v69
	s_waitcnt vmcnt(6)
	ds_write_b32 v32, v70
	s_waitcnt vmcnt(5)
	ds_write_b32 v34, v71
	s_waitcnt vmcnt(4)
	ds_write_b32 v36, v72
	s_waitcnt vmcnt(3)
	ds_write_b32 v38, v73
	s_waitcnt vmcnt(2)
	ds_write_b32 v40, v74
	s_waitcnt vmcnt(1)
	ds_write_b32 v42, v75
	s_waitcnt vmcnt(0)
	ds_write_b32 v44, v76
	s_cbranch_scc1 .LBB0_521
	s_lshl_b32 s6, s40, 5
	s_waitcnt lgkmcnt(0)
	s_mov_b32 s29, s35
	s_and_b32 s6, s6, 0x3e0
	s_lshl_b64 s[8:9], s[28:29], 1
	s_add_u32 s8, s37, s8
	ds_read2_b32 v[6:7], v13 offset0:33 offset1:41
	ds_read2_b32 v[8:9], v13 offset1:8
	ds_read2_b32 v[20:21], v13 offset0:66 offset1:74
	ds_read2_b32 v[22:23], v13 offset0:99 offset1:107
	ds_read2_b32 v[24:25], v13 offset0:132 offset1:140
	ds_read2_b32 v[26:27], v13 offset0:165 offset1:173
	ds_read2_b32 v[28:29], v13 offset0:198 offset1:206
	ds_read2_b32 v[30:31], v13 offset0:231 offset1:239
	s_addc_u32 s9, s34, s9
	v_lshlrev_b32_e32 v130, 1, v16
	v_lshl_add_u64 v[2:3], s[8:9], 0, v[130:131]
	s_mov_b64 s[8:9], 0x1300000
	v_lshl_add_u64 v[32:33], v[2:3], 0, s[8:9]
	s_waitcnt lgkmcnt(6)
	v_cvt_pk_bf16_f32 v2, v8, v6
	v_or_b32_e32 v6, s6, v11
	v_mul_u32_u24_e32 v130, 0x1600, v6
	s_waitcnt lgkmcnt(4)
	v_cvt_pk_bf16_f32 v3, v20, v22
	s_waitcnt lgkmcnt(2)
	v_cvt_pk_bf16_f32 v4, v24, v26
	s_waitcnt lgkmcnt(0)
	v_cvt_pk_bf16_f32 v5, v28, v30
	v_lshl_add_u64 v[34:35], v[32:33], 0, v[130:131]
	global_store_dwordx4 v[34:35], v[2:5], off sc1
	v_or_b32_e32 v6, s6, v15
	v_mul_u32_u24_e32 v130, 0x1600, v6
	v_cvt_pk_bf16_f32 v2, v9, v7
	v_cvt_pk_bf16_f32 v3, v21, v23
	v_cvt_pk_bf16_f32 v4, v25, v27
	v_cvt_pk_bf16_f32 v5, v29, v31
	ds_read2_b32 v[8:9], v13 offset0:16 offset1:24
	ds_read2_b32 v[20:21], v13 offset0:49 offset1:57
	ds_read2_b32 v[22:23], v13 offset0:82 offset1:90
	ds_read2_b32 v[24:25], v13 offset0:115 offset1:123
	ds_read2_b32 v[26:27], v13 offset0:148 offset1:156
	ds_read2_b32 v[28:29], v13 offset0:181 offset1:189
	ds_read2_b32 v[30:31], v13 offset0:214 offset1:222
	ds_read2_b32 v[34:35], v13 offset0:247 offset1:255
	v_lshl_add_u64 v[6:7], v[32:33], 0, v[130:131]
	global_store_dwordx4 v[6:7], v[2:5], off sc1
	v_or_b32_e32 v6, s6, v17
	v_mul_u32_u24_e32 v130, 0x1600, v6
	s_waitcnt lgkmcnt(6)
	v_cvt_pk_bf16_f32 v2, v8, v20
	s_waitcnt lgkmcnt(4)
	v_cvt_pk_bf16_f32 v3, v22, v24
	s_waitcnt lgkmcnt(2)
	v_cvt_pk_bf16_f32 v4, v26, v28
	s_waitcnt lgkmcnt(0)
	v_cvt_pk_bf16_f32 v5, v30, v34
	v_lshl_add_u64 v[6:7], v[32:33], 0, v[130:131]
	global_store_dwordx4 v[6:7], v[2:5], off sc1
	v_or_b32_e32 v6, s6, v18
	v_mul_u32_u24_e32 v130, 0x1600, v6
	v_cvt_pk_bf16_f32 v2, v9, v21
	v_cvt_pk_bf16_f32 v3, v23, v25
	v_cvt_pk_bf16_f32 v4, v27, v29
	v_cvt_pk_bf16_f32 v5, v31, v35
	v_lshl_add_u64 v[6:7], v[32:33], 0, v[130:131]
	global_store_dwordx4 v[6:7], v[2:5], off sc1
	s_waitcnt lgkmcnt(0)
	s_mov_b64 s[28:29], 0

.LBB0_529:
	ds_read2_b32 v[24:25], v13 offset1:8
	ds_read2_b32 v[26:27], v13 offset0:33 offset1:41
	ds_read2_b32 v[30:31], v13 offset0:66 offset1:74
	ds_read2_b32 v[32:33], v13 offset0:99 offset1:107
	s_lshl_b32 s7, s7, 1
	s_add_u32 s8, s37, s7
	ds_read2_b32 v[34:35], v13 offset0:132 offset1:140
	ds_read2_b32 v[36:37], v13 offset0:165 offset1:173
	ds_read2_b32 v[38:39], v13 offset0:198 offset1:206
	ds_read2_b32 v[40:41], v13 offset0:231 offset1:239
	s_addc_u32 s9, s34, 0
	v_lshlrev_b32_e32 v130, 1, v16
	v_lshl_add_u64 v[20:21], s[8:9], 0, v[130:131]
	s_mov_b64 s[8:9], 0x800000
	v_lshl_add_u64 v[28:29], v[20:21], 0, s[8:9]
	s_waitcnt lgkmcnt(7)
	v_mov_b32_e32 v20, v24
	s_waitcnt lgkmcnt(6)
	v_mov_b32_e32 v21, v26
	s_waitcnt lgkmcnt(5)
	v_mov_b32_e32 v22, v30
	s_waitcnt lgkmcnt(4)
	v_mov_b32_e32 v23, v32
	s_waitcnt vmcnt(0)
	v_pk_mul_f32 v[20:21], v[6:7], v[20:21]
	v_pk_mul_f32 v[22:23], v[8:9], v[22:23]
	v_cvt_pk_bf16_f32 v20, v20, v21
	v_cvt_pk_bf16_f32 v21, v22, v23
	s_waitcnt lgkmcnt(3)
	v_mov_b32_e32 v22, v34
	s_waitcnt lgkmcnt(2)
	v_mov_b32_e32 v23, v36
	s_waitcnt lgkmcnt(1)
	v_mov_b32_e32 v42, v38
	s_waitcnt lgkmcnt(0)
	v_mov_b32_e32 v43, v40
	v_or_b32_e32 v19, s6, v11
	v_pk_mul_f32 v[22:23], v[2:3], v[22:23]
	v_pk_mul_f32 v[42:43], v[4:5], v[42:43]
	v_lshlrev_b32_e32 v130, 11, v19
	v_cvt_pk_bf16_f32 v22, v22, v23
	v_cvt_pk_bf16_f32 v23, v42, v43
	v_lshl_add_u64 v[42:43], v[28:29], 0, v[130:131]
	v_mov_b32_e32 v26, v25
	v_mov_b32_e32 v32, v31
	global_store_dwordx4 v[42:43], v[20:23], off sc1
	v_mov_b32_e32 v36, v35
	v_mov_b32_e32 v40, v39
	v_pk_mul_f32 v[20:21], v[6:7], v[26:27]
	v_pk_mul_f32 v[22:23], v[8:9], v[32:33]
	v_or_b32_e32 v19, s6, v15
	v_cvt_pk_bf16_f32 v20, v20, v21
	v_cvt_pk_bf16_f32 v21, v22, v23
	v_pk_mul_f32 v[22:23], v[2:3], v[36:37]
	v_pk_mul_f32 v[24:25], v[4:5], v[40:41]
	v_lshlrev_b32_e32 v130, 11, v19
	v_cvt_pk_bf16_f32 v22, v22, v23
	v_cvt_pk_bf16_f32 v23, v24, v25
	v_lshl_add_u64 v[30:31], v[28:29], 0, v[130:131]
	ds_read2_b32 v[24:25], v13 offset0:16 offset1:24
	ds_read2_b32 v[26:27], v13 offset0:49 offset1:57
	global_store_dwordx4 v[30:31], v[20:23], off sc1
	ds_read2_b32 v[30:31], v13 offset0:82 offset1:90
	ds_read2_b32 v[32:33], v13 offset0:115 offset1:123
	ds_read2_b32 v[34:35], v13 offset0:148 offset1:156
	ds_read2_b32 v[36:37], v13 offset0:181 offset1:189
	ds_read2_b32 v[38:39], v13 offset0:214 offset1:222
	ds_read2_b32 v[40:41], v13 offset0:247 offset1:255
	s_waitcnt lgkmcnt(7)
	v_mov_b32_e32 v20, v24
	s_waitcnt lgkmcnt(6)
	v_mov_b32_e32 v21, v26
	s_waitcnt lgkmcnt(5)
	v_mov_b32_e32 v22, v30
	s_waitcnt lgkmcnt(4)
	v_mov_b32_e32 v23, v32
	v_pk_mul_f32 v[20:21], v[6:7], v[20:21]
	v_pk_mul_f32 v[22:23], v[8:9], v[22:23]
	v_cvt_pk_bf16_f32 v20, v20, v21
	v_cvt_pk_bf16_f32 v21, v22, v23
	s_waitcnt lgkmcnt(3)
	v_mov_b32_e32 v22, v34
	s_waitcnt lgkmcnt(2)
	v_mov_b32_e32 v23, v36
	v_mov_b32_e32 v26, v25
	v_mov_b32_e32 v32, v31
	v_mov_b32_e32 v36, v35
	v_pk_mul_f32 v[22:23], v[2:3], v[22:23]
	s_waitcnt lgkmcnt(0)
	v_mov_b32_e32 v43, v40
	v_pk_mul_f32 v[6:7], v[6:7], v[26:27]
	v_pk_mul_f32 v[8:9], v[8:9], v[32:33]
	v_pk_mul_f32 v[2:3], v[2:3], v[36:37]
	v_mov_b32_e32 v40, v39
	v_mov_b32_e32 v42, v38
	v_or_b32_e32 v19, s6, v17
	v_cvt_pk_bf16_f32 v6, v6, v7
	v_cvt_pk_bf16_f32 v7, v8, v9
	v_cvt_pk_bf16_f32 v8, v2, v3
	v_pk_mul_f32 v[2:3], v[4:5], v[40:41]
	v_pk_mul_f32 v[42:43], v[4:5], v[42:43]
	v_lshlrev_b32_e32 v130, 11, v19
	v_cvt_pk_bf16_f32 v9, v2, v3
	v_or_b32_e32 v2, s6, v18
	v_cvt_pk_bf16_f32 v22, v22, v23
	v_cvt_pk_bf16_f32 v23, v42, v43
	v_lshl_add_u64 v[42:43], v[28:29], 0, v[130:131]
	v_lshlrev_b32_e32 v130, 11, v2
	v_lshl_add_u64 v[2:3], v[28:29], 0, v[130:131]
	global_store_dwordx4 v[42:43], v[20:23], off sc1
	global_store_dwordx4 v[2:3], v[6:9], off sc1
	s_waitcnt lgkmcnt(0)

.LBB0_533:
	s_lshl_b32 s8, s6, 1
	s_lshl_b32 s9, s29, 1
	v_or_b32_e32 v19, s8, v1
	v_or_b32_e32 v46, s9, v12
	s_add_i32 s10, s8, 4
	s_add_i32 s11, s9, 4
	s_add_i32 s43, s8, 8
	s_add_i32 s44, s9, 8
	s_add_i32 s45, s8, 12
	s_add_i32 s46, s9, 12
	s_add_i32 s47, s8, 16
	s_add_i32 s48, s9, 16
	s_add_i32 s49, s8, 20
	s_add_i32 s50, s9, 20
	s_add_i32 s51, s8, 24
	s_add_i32 s52, s9, 24
	s_add_i32 s8, s8, 28
	s_add_i32 s9, s9, 28
	v_add_u32_e32 v6, s28, v46
	v_or_b32_e32 v47, s10, v1
	v_or_b32_e32 v48, s11, v12
	v_or_b32_e32 v49, s43, v1
	v_or_b32_e32 v50, s44, v12
	v_or_b32_e32 v51, s45, v1
	v_or_b32_e32 v52, s46, v12
	v_or_b32_e32 v53, s47, v1
	v_or_b32_e32 v54, s48, v12
	v_or_b32_e32 v55, s49, v1
	v_or_b32_e32 v56, s50, v12
	v_or_b32_e32 v57, s51, v1
	v_or_b32_e32 v58, s52, v12
	v_or_b32_e32 v59, s8, v1
	v_or_b32_e32 v60, s9, v12
	v_add_u32_e32 v4, s7, v19
	v_ashrrev_i32_e32 v7, 31, v6
	v_add_u32_e32 v8, s7, v47
	v_add_u32_e32 v20, s28, v48
	v_add_u32_e32 v22, s7, v49
	v_add_u32_e32 v24, s28, v50
	v_add_u32_e32 v26, s7, v51
	v_add_u32_e32 v28, s28, v52
	v_add_u32_e32 v30, s7, v53
	v_add_u32_e32 v32, s28, v54
	v_add_u32_e32 v34, s7, v55
	v_add_u32_e32 v36, s28, v56
	v_add_u32_e32 v38, s7, v57
	v_add_u32_e32 v40, s28, v58
	v_add_u32_e32 v42, s7, v59
	v_add_u32_e32 v44, s28, v60
	v_ashrrev_i32_e32 v5, 31, v4
	v_lshlrev_b64 v[6:7], 12, v[6:7]
	v_ashrrev_i32_e32 v21, 31, v20
	v_ashrrev_i32_e32 v9, 31, v8
	v_ashrrev_i32_e32 v25, 31, v24
	v_ashrrev_i32_e32 v23, 31, v22
	v_ashrrev_i32_e32 v29, 31, v28
	v_ashrrev_i32_e32 v27, 31, v26
	v_ashrrev_i32_e32 v33, 31, v32
	v_ashrrev_i32_e32 v31, 31, v30
	v_ashrrev_i32_e32 v37, 31, v36
	v_ashrrev_i32_e32 v35, 31, v34
	v_ashrrev_i32_e32 v41, 31, v40
	v_ashrrev_i32_e32 v39, 31, v38
	v_ashrrev_i32_e32 v45, 31, v44
	v_ashrrev_i32_e32 v43, 31, v42
	v_lshlrev_b64 v[4:5], 12, v[4:5]
	v_lshl_add_u64 v[6:7], v[2:3], 0, v[6:7]
	v_lshlrev_b64 v[8:9], 12, v[8:9]
	v_lshlrev_b64 v[20:21], 12, v[20:21]
	v_lshlrev_b64 v[22:23], 12, v[22:23]
	v_lshlrev_b64 v[24:25], 12, v[24:25]
	v_lshlrev_b64 v[26:27], 12, v[26:27]
	v_lshlrev_b64 v[28:29], 12, v[28:29]
	v_lshlrev_b64 v[30:31], 12, v[30:31]
	v_lshlrev_b64 v[32:33], 12, v[32:33]
	v_lshlrev_b64 v[34:35], 12, v[34:35]
	v_lshlrev_b64 v[36:37], 12, v[36:37]
	v_lshlrev_b64 v[38:39], 12, v[38:39]
	v_lshlrev_b64 v[40:41], 12, v[40:41]
	v_lshlrev_b64 v[42:43], 12, v[42:43]
	v_lshlrev_b64 v[44:45], 12, v[44:45]
	v_lshl_add_u64 v[4:5], v[2:3], 0, v[4:5]
	v_lshl_add_u64 v[20:21], v[2:3], 0, v[20:21]
	v_lshl_add_u64 v[8:9], v[2:3], 0, v[8:9]
	v_lshl_add_u64 v[24:25], v[2:3], 0, v[24:25]
	v_lshl_add_u64 v[22:23], v[2:3], 0, v[22:23]
	v_lshl_add_u64 v[28:29], v[2:3], 0, v[28:29]
	v_lshl_add_u64 v[26:27], v[2:3], 0, v[26:27]
	v_lshl_add_u64 v[32:33], v[2:3], 0, v[32:33]
	v_lshl_add_u64 v[30:31], v[2:3], 0, v[30:31]
	v_lshl_add_u64 v[36:37], v[2:3], 0, v[36:37]
	v_lshl_add_u64 v[34:35], v[2:3], 0, v[34:35]
	v_lshl_add_u64 v[40:41], v[2:3], 0, v[40:41]
	v_lshl_add_u64 v[38:39], v[2:3], 0, v[38:39]
	v_lshl_add_u64 v[44:45], v[2:3], 0, v[44:45]
	v_lshl_add_u64 v[42:43], v[2:3], 0, v[42:43]
	global_load_dword v61, v[6:7], off
	global_load_dword v62, v[4:5], off
	global_load_dword v63, v[20:21], off
	global_load_dword v64, v[8:9], off
	global_load_dword v65, v[24:25], off
	global_load_dword v66, v[22:23], off
	global_load_dword v67, v[28:29], off
	global_load_dword v68, v[26:27], off
	global_load_dword v69, v[32:33], off
	global_load_dword v70, v[30:31], off
	global_load_dword v71, v[36:37], off
	global_load_dword v72, v[34:35], off
	global_load_dword v73, v[40:41], off
	global_load_dword v74, v[38:39], off
	global_load_dword v75, v[44:45], off
	global_load_dword v76, v[42:43], off
	s_add_i32 s29, s29, 16
	s_add_i32 s6, s6, 16
	s_add_i32 s41, s41, -16
	v_mad_u64_u32 v[4:5], s[8:9], v46, s93, v[14:15]
	s_cmp_lg_u32 s41, 0
	v_mad_u64_u32 v[6:7], s[8:9], v19, s93, v[14:15]
	v_mad_u64_u32 v[8:9], s[8:9], v48, s93, v[14:15]
	v_mad_u64_u32 v[20:21], s[8:9], v47, s93, v[14:15]
	v_mad_u64_u32 v[22:23], s[8:9], v50, s93, v[14:15]
	v_mad_u64_u32 v[24:25], s[8:9], v49, s93, v[14:15]
	v_mad_u64_u32 v[26:27], s[8:9], v52, s93, v[14:15]
	v_mad_u64_u32 v[28:29], s[8:9], v51, s93, v[14:15]
	v_mad_u64_u32 v[30:31], s[8:9], v54, s93, v[14:15]
	v_mad_u64_u32 v[32:33], s[8:9], v53, s93, v[14:15]
	v_mad_u64_u32 v[34:35], s[8:9], v56, s93, v[14:15]
	v_mad_u64_u32 v[36:37], s[8:9], v55, s93, v[14:15]
	v_mad_u64_u32 v[38:39], s[8:9], v58, s93, v[14:15]
	v_mad_u64_u32 v[40:41], s[8:9], v57, s93, v[14:15]
	v_mad_u64_u32 v[42:43], s[8:9], v60, s93, v[14:15]
	v_mad_u64_u32 v[44:45], s[8:9], v59, s93, v[14:15]
	s_waitcnt vmcnt(15)
	ds_write_b32 v4, v61
	s_waitcnt vmcnt(14)
	ds_write_b32 v6, v62
	s_waitcnt vmcnt(13)
	ds_write_b32 v8, v63
	s_waitcnt vmcnt(12)
	ds_write_b32 v20, v64
	s_waitcnt vmcnt(11)
	ds_write_b32 v22, v65
	s_waitcnt vmcnt(10)
	ds_write_b32 v24, v66
	s_waitcnt vmcnt(9)
	ds_write_b32 v26, v67
	s_waitcnt vmcnt(8)
	ds_write_b32 v28, v68
	s_waitcnt vmcnt(7)
	ds_write_b32 v30, v69
	s_waitcnt vmcnt(6)
	ds_write_b32 v32, v70
	s_waitcnt vmcnt(5)
	ds_write_b32 v34, v71
	s_waitcnt vmcnt(4)
	ds_write_b32 v36, v72
	s_waitcnt vmcnt(3)
	ds_write_b32 v38, v73
	s_waitcnt vmcnt(2)
	ds_write_b32 v40, v74
	s_waitcnt vmcnt(1)
	ds_write_b32 v42, v75
	s_waitcnt vmcnt(0)
	ds_write_b32 v44, v76
	s_cbranch_scc1 .LBB0_533
	s_lshl_b32 s6, s40, 5
	s_waitcnt lgkmcnt(0)
	s_mov_b32 s29, s35
	s_and_b32 s8, s6, 0x3e0
	s_lshl_b64 s[6:7], s[28:29], 1
	s_add_u32 s6, s37, s6
	ds_read2_b32 v[6:7], v13 offset0:33 offset1:41
	ds_read2_b32 v[8:9], v13 offset1:8
	ds_read2_b32 v[20:21], v13 offset0:66 offset1:74
	ds_read2_b32 v[22:23], v13 offset0:99 offset1:107
	ds_read2_b32 v[24:25], v13 offset0:132 offset1:140
	ds_read2_b32 v[26:27], v13 offset0:165 offset1:173
	ds_read2_b32 v[28:29], v13 offset0:198 offset1:206
	ds_read2_b32 v[30:31], v13 offset0:231 offset1:239
	s_addc_u32 s7, s34, s7
	v_lshlrev_b32_e32 v130, 1, v16
	v_lshl_add_u64 v[2:3], s[6:7], 0, v[130:131]
	s_mov_b64 s[6:7], 0x600000
	v_lshl_add_u64 v[32:33], v[2:3], 0, s[6:7]
	s_waitcnt lgkmcnt(6)
	v_cvt_pk_bf16_f32 v2, v8, v6
	v_or_b32_e32 v6, s8, v11
	v_lshlrev_b32_e32 v130, 11, v6
	s_waitcnt lgkmcnt(4)
	v_cvt_pk_bf16_f32 v3, v20, v22
	s_waitcnt lgkmcnt(2)
	v_cvt_pk_bf16_f32 v4, v24, v26
	s_waitcnt lgkmcnt(0)
	v_cvt_pk_bf16_f32 v5, v28, v30
	v_lshl_add_u64 v[34:35], v[32:33], 0, v[130:131]
	global_store_dwordx4 v[34:35], v[2:5], off sc1
	v_or_b32_e32 v6, s8, v15
	v_lshlrev_b32_e32 v130, 11, v6
	v_cvt_pk_bf16_f32 v2, v9, v7
	v_cvt_pk_bf16_f32 v3, v21, v23
	v_cvt_pk_bf16_f32 v4, v25, v27
	v_cvt_pk_bf16_f32 v5, v29, v31
	ds_read2_b32 v[8:9], v13 offset0:49 offset1:57
	ds_read2_b32 v[20:21], v13 offset0:16 offset1:24
	ds_read2_b32 v[22:23], v13 offset0:82 offset1:90
	ds_read2_b32 v[24:25], v13 offset0:115 offset1:123
	ds_read2_b32 v[26:27], v13 offset0:148 offset1:156
	ds_read2_b32 v[28:29], v13 offset0:181 offset1:189
	ds_read2_b32 v[30:31], v13 offset0:214 offset1:222
	ds_read2_b32 v[34:35], v13 offset0:247 offset1:255
	v_lshl_add_u64 v[6:7], v[32:33], 0, v[130:131]
	global_store_dwordx4 v[6:7], v[2:5], off sc1
	v_or_b32_e32 v6, s8, v17
	v_lshlrev_b32_e32 v130, 11, v6
	s_waitcnt lgkmcnt(6)
	v_cvt_pk_bf16_f32 v2, v20, v8
	s_waitcnt lgkmcnt(4)
	v_cvt_pk_bf16_f32 v3, v22, v24
	s_waitcnt lgkmcnt(2)
	v_cvt_pk_bf16_f32 v4, v26, v28
	s_waitcnt lgkmcnt(0)
	v_cvt_pk_bf16_f32 v5, v30, v34
	v_lshl_add_u64 v[6:7], v[32:33], 0, v[130:131]
	global_store_dwordx4 v[6:7], v[2:5], off sc1
	v_or_b32_e32 v6, s8, v18
	v_lshlrev_b32_e32 v130, 11, v6
	v_cvt_pk_bf16_f32 v2, v21, v9
	v_cvt_pk_bf16_f32 v3, v23, v25
	v_cvt_pk_bf16_f32 v4, v27, v29
	v_cvt_pk_bf16_f32 v5, v31, v35
	v_lshl_add_u64 v[6:7], v[32:33], 0, v[130:131]
	global_store_dwordx4 v[6:7], v[2:5], off sc1
	s_waitcnt lgkmcnt(0)

.LBB0_563:
	s_or_b64 exec, exec, s[40:41]
	v_lshlrev_b32_e32 v130, 4, v1
	s_waitcnt vmcnt(0)
	v_cvt_pk_bf16_f32 v12, v12, v11
	v_cvt_pk_bf16_f32 v11, v10, v9
	v_cvt_pk_bf16_f32 v10, v8, v5
	v_lshl_add_u64 v[4:5], s[78:79], 0, v[130:131]
	v_add_co_u32_e32 v4, vcc, 0x3420000, v4
	v_cvt_pk_bf16_f32 v13, v14, v13
	s_nop 0
	v_addc_co_u32_e32 v5, vcc, 0, v5, vcc
	global_store_dwordx4 v[4:5], v[10:13], off sc1

.LBB0_567:
	s_or_b64 exec, exec, s[40:41]
	v_lshl_add_u64 v[2:3], v[2:3], 1, s[78:79]
	v_bfe_u32 v4, v1, 16, 1
	s_movk_i32 s4, 0x7fff
	v_add_co_u32_e32 v2, vcc, 0x3400000, v2
	v_add3_u32 v1, v1, v4, s4
	s_nop 0
	v_addc_co_u32_e32 v3, vcc, 0, v3, vcc
	global_store_short_d16_hi v[2:3], v1, off sc1

.LBB0_571:
	s_mov_b32 s4, s36
	s_add_i32 s36, s36, s30
	s_cmpk_gt_i32 s36, 0x7fff
	s_cselect_b64 s[40:41], -1, 0
	s_cmp_lt_i32 s36, 0x8000
	s_cselect_b32 s4, s36, s4
	s_ashr_i32 s5, s4, 31
	s_lshl_b64 s[4:5], s[4:5], 12
	v_lshl_add_u64 v[14:15], v[34:35], 0, s[4:5]
	global_load_dwordx4 v[30:33], v[14:15], off
	global_load_dwordx4 v[26:29], v[14:15], off offset:1024
	global_load_dwordx4 v[22:25], v[14:15], off offset:2048
	s_nop 0
	global_load_dwordx4 v[14:17], v[14:15], off offset:3072
	s_waitcnt vmcnt(7)
	v_mul_f32_e32 v1, v19, v19
	v_cvt_pk_bf16_f32 v42, v18, v19
	v_fmac_f32_e32 v1, v18, v18
	v_mul_f32_e32 v18, v21, v21
	v_fmac_f32_e32 v18, v20, v20
	v_add_f32_e32 v1, v1, v18
	s_waitcnt vmcnt(6)
	v_cvt_pk_bf16_f32 v18, v10, v11
	v_mul_f32_e32 v11, v11, v11
	v_fmac_f32_e32 v11, v10, v10
	v_mul_f32_e32 v10, v13, v13
	v_fmac_f32_e32 v10, v12, v12
	v_add_f32_e32 v10, v11, v10
	v_add_f32_e32 v1, v1, v10
	s_waitcnt vmcnt(5)
	v_cvt_pk_bf16_f32 v10, v6, v7
	v_mul_f32_e32 v7, v7, v7
	v_fmac_f32_e32 v7, v6, v6
	v_mul_f32_e32 v6, v9, v9
	v_fmac_f32_e32 v6, v8, v8
	v_add_f32_e32 v6, v7, v6
	v_add_f32_e32 v1, v6, v1
	s_waitcnt vmcnt(4)
	v_cvt_pk_bf16_f32 v6, v2, v3
	v_mul_f32_e32 v3, v3, v3
	v_fmac_f32_e32 v3, v2, v2
	v_mul_f32_e32 v2, v5, v5
	v_fmac_f32_e32 v2, v4, v4
	v_add_f32_e32 v2, v3, v2
	v_add_f32_e32 v1, v2, v1
	v_lshl_add_u64 v[40:41], s[78:79], 0, v[38:39]
	s_nop 0
	v_add_f32_dpp v1, v1, v1 quad_perm:[1,0,3,2] row_mask:0xf bank_mask:0xf bound_ctrl:1
	s_brev_b32 s4, 32
	v_add_co_u32_e32 v40, vcc, s4, v40
	v_add_f32_dpp v1, v1, v1 quad_perm:[2,3,0,1] row_mask:0xf bank_mask:0xf bound_ctrl:1
	v_cvt_pk_bf16_f32 v43, v20, v21
	v_addc_co_u32_e32 v41, vcc, 0, v41, vcc
	v_add_f32_dpp v1, v1, v1 row_half_mirror row_mask:0xf bank_mask:0xf bound_ctrl:1
	v_cvt_pk_bf16_f32 v19, v12, v13
	v_cvt_pk_bf16_f32 v11, v8, v9
	v_add_f32_dpp v1, v1, v1 row_mirror row_mask:0xf bank_mask:0xf bound_ctrl:1
	v_cvt_pk_bf16_f32 v7, v4, v5
	global_store_dwordx2 v[40:41], v[42:43], off sc1
	v_add_f32_dpp v1, v1, v1 row_bcast:15 row_mask:0xa bank_mask:0xf
	global_store_dwordx2 v[40:41], v[18:19], off offset:512 sc1
	global_store_dwordx2 v[40:41], v[10:11], off offset:1024 sc1
	v_add_f32_dpp v1, v1, v1 row_bcast:31 row_mask:0xc bank_mask:0xf
	global_store_dwordx2 v[40:41], v[6:7], off offset:1536 sc1
	v_readlane_b32 s4, v1, 63
	s_and_saveexec_b64 s[46:47], s[42:43]
	s_cbranch_execz .LBB0_570
	v_mov_b32_e32 v1, s4
	v_cndmask_b32_e64 v130, 0, v1, s[44:45]
	v_lshl_add_u64 v[2:3], s[78:79], 0, v[36:37]
	v_mov_b32_e32 v132, v131
	v_mov_b32_e32 v133, v131
	global_store_dwordx4 v[2:3], v[130:133], off sc1
	s_branch .LBB0_570

.LBB0_605:
	s_mov_b64 s[28:29], exec
	s_nop 0
	s_waitcnt lgkmcnt(0)
	s_waitcnt vmcnt(0)
	v_mbcnt_lo_u32_b32 v1, s28, 0
	v_mbcnt_hi_u32_b32 v1, s29, v1
	v_cmp_eq_u32_e32 vcc, 0, v1
	s_and_saveexec_b64 s[30:31], vcc
	s_cbranch_execz .LBB0_607
	s_bcnt1_i32_b64 s4, s[28:29]
	v_mov_b32_e32 v3, s4
	v_readlane_b32 s4, v251, 14
	v_readlane_b32 s5, v251, 15
	s_nop 4
	global_atomic_add v3, v131, v3, s[4:5] sc0
